# GEMM K-loops: the priority dip between the two 16-MFMA halves of a block removed (priority 1 held through the 32-MFMA block)
# baseline (speedup 1.0000x reference)
;     __host__ __device__ bool next(int i, Unit& u) const { const bool ok = StaticOrder::next(i, u); u.pm = 0; u.pn = 0; return ok; }
; #define PG8_STAGE(bufoff, gbase, voff) do { _Pragma("unroll") for (int _i = 0; _i < 2; ++_i) \
;         __builtin_amdgcn_global_load_lds((const unsigned*)((const char*)(gbase) + (voff)[_i]), (PG8_LAS unsigned*)(lds + (bufoff) + ldsw + _i * 8192), 16, 0, 0); } while (0)
; #define PG8_LDA(dst, b, h) do { _Pragma("unroll") for (int m = 0; m < 4; ++m) _Pragma("unroll") for (int k = 0; k < 2; ++k) dst[m][k] = *(const PG8_LAS bf16x8*)(lds + PG8_SA(b, h) + aoff + m * 2048 + k * 1024); } while (0)
; #define PG8_LDB(dst, b, h) do { _Pragma("unroll") for (int n = 0; n < 2; ++n) _Pragma("unroll") for (int k = 0; k < 2; ++k) dst[n][k] = *(const PG8_LAS bf16x8*)(lds + PG8_SB(b, h) + boff + n * 2048 + k * 1024); } while (0)
; #define PG8_WAIT_V(n) asm volatile("s_waitcnt vmcnt(" #n ")" ::: "memory")
; #define PG8_WAIT_L(n) asm volatile("s_waitcnt lgkmcnt(" #n ")" ::: "memory")
; #define PG8_BAR __builtin_amdgcn_s_barrier()
; #define PG8_SCHED __builtin_amdgcn_sched_barrier(0)
; template <class Epi, class Sched, bool ALIGN_EPI = false, bool SP2 = false>
; __device__ __forceinline__ void gemm_phase(PG8_LAS unsigned char* lds, const Gemm g, const Sched& S, const Epi& E, const int wave_in) {
;     ...
;         const bool has_next = S.next(ui + 1, nxt);
;         const char* nA = has_next ? (const char*)g.A + (size_t)nxt.pm * tstepA : cA; const char* nB = has_next ? (const char*)g.Bt + (size_t)nxt.pn * tstepB : cB;
;         for (int t = 0; t < nt; t += 2) {
;             const bool last = (t == nt - 2);
;             const char* a1 = cA + (size_t)(t + 1) * kstep;
;             const char* a2 = last ? nA : cA + (size_t)(t + 2) * kstep; const char* b2 = last ? nB : cB + (size_t)(t + 2) * kstep;
;             const char* a3 = a2 + kstep; const char* b3 = b2 + kstep;
;             if (last && has_next) S.a_ready(nxt);
;             if constexpr (SP2) {
;             PG8_LDB(B0, 0, 0); PG8_LDB(B1, 0, 1); PG8_SCHED; PG8_LDA(At, 0, 0); PG8_STAGE(PG8_SA(1, 1), a1 + hstepA, voffA);
;             PG8_WAIT_V(8); PG8_WAIT_L(0); PG8_BAR; PG8_MMA(0, 0, At, B0); PG8_MMA(0, 1, At, B1); PG8_BAR; PG8_SCHED;
;             PG8_LDA(At, 0, 1); PG8_STAGE(PG8_SB(0, 0), b2, voffB); PG8_STAGE(PG8_SB(0, 1), b2 + hstepB, voffB); PG8_STAGE(PG8_SA(0, 0), a2, voffA);
.LBB0_157:
	s_ashr_i32 s15, s14, 31
	s_lshl_b64 s[16:17], s[14:15], 20
	s_add_u32 s16, s28, s16
	s_addc_u32 s17, s29, s17
	s_and_b64 s[18:19], s[2:3], exec
	s_cselect_b32 s5, s17, s23
	s_cselect_b32 s15, s16, s22
	s_ashr_i32 s13, s12, 31
	s_lshl_b64 s[18:19], s[12:13], 20
	s_add_u32 s18, s30, s18
	s_addc_u32 s19, s31, s19
	s_and_b64 s[26:27], s[2:3], exec
	s_cselect_b32 s13, s19, s25
	s_cselect_b32 s46, s18, s24
	s_add_u32 s22, s22, 0x80080
	s_addc_u32 s23, s23, 0
	s_add_u32 s47, s24, 0x100
	v_mov_b32_e32 v0, 0
	s_addc_u32 s48, s25, 0
	s_mov_b32 s49, -2
	ds_read_b128 v[144:147], v151
	ds_read_b128 v[154:157], v151 offset:1024
	ds_read_b128 v[158:161], v151 offset:2048
	ds_read_b128 v[162:165], v151 offset:3072
	ds_read_b128 v[166:169], v152
	ds_read_b128 v[170:173], v152 offset:1024
	ds_read_b128 v[174:177], v152 offset:2048
	ds_read_b128 v[178:181], v152 offset:3072
	s_add_u32 s24, s22, 0xfff80080
	s_addc_u32 s25, s23, -1
	s_cmp_eq_u32 s49, 28
	s_cselect_b32 s27, s5, s25
	s_cselect_b32 s26, s15, s24
	s_cselect_b32 s25, s13, s48
	s_cselect_b32 s24, s46, s47
	v_lshl_add_u64 v[214:215], s[22:23], 0, v[136:137]
	s_add_i32 m0, s21, 0xc000
	ds_read_b128 v[182:185], v153
	ds_read_b128 v[186:189], v153 offset:1024
	ds_read_b128 v[190:193], v153 offset:2048
	ds_read_b128 v[194:197], v153 offset:3072
	ds_read_b128 v[198:201], v153 offset:4096
	ds_read_b128 v[202:205], v153 offset:5120
	ds_read_b128 v[206:209], v153 offset:6144
	ds_read_b128 v[210:213], v153 offset:7168
	global_load_lds_dwordx4 v[214:215], off
	v_lshl_add_u64 v[214:215], s[22:23], 0, v[138:139]
	s_add_i32 m0, s21, 0xe000
	s_nop 0
	global_load_lds_dwordx4 v[214:215], off
	s_waitcnt vmcnt(8)
	s_waitcnt lgkmcnt(0)
	s_barrier
	s_setprio 1
	s_waitcnt lgkmcnt(0)
	v_mfma_f32_16x16x32_bf16 v[124:127], v[144:147], v[182:185], 0
	v_mfma_f32_16x16x32_bf16 v[120:123], v[158:161], v[182:185], 0
	v_mfma_f32_16x16x32_bf16 v[108:111], v[144:147], v[190:193], 0
	v_mfma_f32_16x16x32_bf16 v[104:107], v[158:161], v[190:193], 0
	v_mfma_f32_16x16x32_bf16 v[92:95], v[144:147], v[198:201], 0
	v_mfma_f32_16x16x32_bf16 v[88:91], v[158:161], v[198:201], 0
	v_mfma_f32_16x16x32_bf16 v[76:79], v[144:147], v[206:209], 0
	v_mfma_f32_16x16x32_bf16 v[72:75], v[158:161], v[206:209], 0
	v_mfma_f32_16x16x32_bf16 v[124:127], v[154:157], v[186:189], v[124:127]
	v_mfma_f32_16x16x32_bf16 v[120:123], v[162:165], v[186:189], v[120:123]
	v_mfma_f32_16x16x32_bf16 v[108:111], v[154:157], v[194:197], v[108:111]
	v_mfma_f32_16x16x32_bf16 v[104:107], v[162:165], v[194:197], v[104:107]
	v_mfma_f32_16x16x32_bf16 v[92:95], v[154:157], v[202:205], v[92:95]
	v_mfma_f32_16x16x32_bf16 v[88:91], v[162:165], v[202:205], v[88:91]
	v_mfma_f32_16x16x32_bf16 v[76:79], v[154:157], v[210:213], v[76:79]
	v_mfma_f32_16x16x32_bf16 v[72:75], v[162:165], v[210:213], v[72:75]
	v_mfma_f32_16x16x32_bf16 v[116:119], v[166:169], v[182:185], 0
	v_mfma_f32_16x16x32_bf16 v[112:115], v[174:177], v[182:185], 0
	v_mfma_f32_16x16x32_bf16 v[100:103], v[166:169], v[190:193], 0
	v_mfma_f32_16x16x32_bf16 v[96:99], v[174:177], v[190:193], 0
	v_mfma_f32_16x16x32_bf16 v[84:87], v[166:169], v[198:201], 0
	v_mfma_f32_16x16x32_bf16 v[80:83], v[174:177], v[198:201], 0
	v_mfma_f32_16x16x32_bf16 v[68:71], v[166:169], v[206:209], 0
	v_mfma_f32_16x16x32_bf16 v[64:67], v[174:177], v[206:209], 0
	v_mfma_f32_16x16x32_bf16 v[116:119], v[170:173], v[186:189], v[116:119]
	v_mfma_f32_16x16x32_bf16 v[112:115], v[178:181], v[186:189], v[112:115]
	v_mfma_f32_16x16x32_bf16 v[100:103], v[170:173], v[194:197], v[100:103]
	v_mfma_f32_16x16x32_bf16 v[96:99], v[178:181], v[194:197], v[96:99]
	v_mfma_f32_16x16x32_bf16 v[84:87], v[170:173], v[202:205], v[84:87]
	v_mfma_f32_16x16x32_bf16 v[80:83], v[178:181], v[202:205], v[80:83]
	v_mfma_f32_16x16x32_bf16 v[68:71], v[170:173], v[210:213], v[68:71]
	v_mfma_f32_16x16x32_bf16 v[64:67], v[178:181], v[210:213], v[64:67]
	s_setprio 0
	s_barrier
	s_add_i32 s50, s43, s34
	v_lshl_add_u64 v[214:215], s[24:25], 0, v[130:131]
	s_mov_b32 m0, s50
	ds_read_b128 v[182:185], v153 offset:16384
	ds_read_b128 v[186:189], v153 offset:17408
	ds_read_b128 v[190:193], v153 offset:18432
	ds_read_b128 v[194:197], v153 offset:19456
	ds_read_b128 v[198:201], v153 offset:20480
	ds_read_b128 v[202:205], v153 offset:21504
	ds_read_b128 v[206:209], v153 offset:22528
	ds_read_b128 v[210:213], v153 offset:23552
	global_load_lds_dwordx4 v[214:215], off
	s_add_i32 m0, s50, 0x2000
	s_add_u32 s50, s24, 0x80000
	v_lshl_add_u64 v[216:217], s[24:25], 0, v[134:135]
	s_addc_u32 s51, s25, 0
	s_add_i32 s52, s44, s34
	global_load_lds_dwordx4 v[216:217], off
	v_lshl_add_u64 v[218:219], s[50:51], 0, v[130:131]
	s_mov_b32 m0, s52
	v_lshl_add_u64 v[220:221], s[26:27], 0, v[132:133]
	global_load_lds_dwordx4 v[218:219], off
	v_lshl_add_u64 v[218:219], s[50:51], 0, v[134:135]
	s_add_i32 m0, s52, 0x2000
	s_nop 0
	global_load_lds_dwordx4 v[218:219], off
	v_lshl_add_u64 v[218:219], s[26:27], 0, v[128:129]
	s_mov_b32 m0, s21
	s_nop 0
	global_load_lds_dwordx4 v[218:219], off
	s_mov_b32 m0, s35
	s_nop 0
	global_load_lds_dwordx4 v[220:221], off
	s_waitcnt vmcnt(8)
	s_waitcnt lgkmcnt(0)
	s_barrier
; #define PG8_STAGE(bufoff, gbase, voff) do { _Pragma("unroll") for (int _i = 0; _i < 2; ++_i) \
;         __builtin_amdgcn_global_load_lds((const unsigned*)((const char*)(gbase) + (voff)[_i]), (PG8_LAS unsigned*)(lds + (bufoff) + ldsw + _i * 8192), 16, 0, 0); } while (0)
; #define PG8_LDA(dst, b, h) do { _Pragma("unroll") for (int m = 0; m < 4; ++m) _Pragma("unroll") for (int k = 0; k < 2; ++k) dst[m][k] = *(const PG8_LAS bf16x8*)(lds + PG8_SA(b, h) + aoff + m * 2048 + k * 1024); } while (0)
; #define PG8_LDB(dst, b, h) do { _Pragma("unroll") for (int n = 0; n < 2; ++n) _Pragma("unroll") for (int k = 0; k < 2; ++k) dst[n][k] = *(const PG8_LAS bf16x8*)(lds + PG8_SB(b, h) + boff + n * 2048 + k * 1024); } while (0)
; #define PG8_MMA(ai, bj, At, Bt) do { __builtin_amdgcn_s_setprio(1); _Pragma("unroll") for (int m = 0; m < 4; ++m) _Pragma("unroll") for (int n = 0; n < 2; ++n) _Pragma("unroll") for (int k = 0; k < 2; ++k) \
;         acc[ai][bj][m][n] = __builtin_amdgcn_mfma_f32_16x16x32_bf16(Bt[n][k], At[m][k], acc[ai][bj][m][n], 0, 0, 0); __builtin_amdgcn_s_setprio(0); } while (0)
; #define PG8_WAIT_V(n) asm volatile("s_waitcnt vmcnt(" #n ")" ::: "memory")
; #define PG8_WAIT_L(n) asm volatile("s_waitcnt lgkmcnt(" #n ")" ::: "memory")
; #define PG8_BAR __builtin_amdgcn_s_barrier()
; #define PG8_SCHED __builtin_amdgcn_sched_barrier(0)
; template <class Epi, class Sched, bool ALIGN_EPI = false, bool SP2 = false>
; __device__ __forceinline__ void gemm_phase(PG8_LAS unsigned char* lds, const Gemm g, const Sched& S, const Epi& E, const int wave_in) {
;     ...
;             PG8_WAIT_V(8); PG8_WAIT_L(0); PG8_BAR; PG8_MMA(1, 0, At, B0); PG8_MMA(1, 1, At, B1); PG8_BAR; PG8_SCHED;
;             PG8_LDB(B0, 1, 0); PG8_LDB(B1, 1, 1); PG8_SCHED; PG8_LDA(At, 1, 0); PG8_STAGE(PG8_SA(0, 1), a2 + hstepA, voffA);
;             PG8_WAIT_V(8); PG8_WAIT_L(0); PG8_BAR; PG8_MMA(0, 0, At, B0); PG8_MMA(0, 1, At, B1); PG8_BAR; PG8_SCHED;
	s_setprio 1
	s_waitcnt lgkmcnt(0)
	v_mfma_f32_16x16x32_bf16 v[60:63], v[144:147], v[182:185], 0
	v_mfma_f32_16x16x32_bf16 v[56:59], v[158:161], v[182:185], 0
	v_mfma_f32_16x16x32_bf16 v[44:47], v[144:147], v[190:193], 0
	v_mfma_f32_16x16x32_bf16 v[40:43], v[158:161], v[190:193], 0
	v_mfma_f32_16x16x32_bf16 v[28:31], v[144:147], v[198:201], 0
	v_mfma_f32_16x16x32_bf16 v[24:27], v[158:161], v[198:201], 0
	v_mfma_f32_16x16x32_bf16 v[12:15], v[144:147], v[206:209], 0
	v_mfma_f32_16x16x32_bf16 v[8:11], v[158:161], v[206:209], 0
	v_mfma_f32_16x16x32_bf16 v[60:63], v[154:157], v[186:189], v[60:63]
	v_mfma_f32_16x16x32_bf16 v[56:59], v[162:165], v[186:189], v[56:59]
	v_mfma_f32_16x16x32_bf16 v[44:47], v[154:157], v[194:197], v[44:47]
	v_mfma_f32_16x16x32_bf16 v[40:43], v[162:165], v[194:197], v[40:43]
	v_mfma_f32_16x16x32_bf16 v[28:31], v[154:157], v[202:205], v[28:31]
	v_mfma_f32_16x16x32_bf16 v[24:27], v[162:165], v[202:205], v[24:27]
	v_mfma_f32_16x16x32_bf16 v[12:15], v[154:157], v[210:213], v[12:15]
	v_mfma_f32_16x16x32_bf16 v[8:11], v[162:165], v[210:213], v[8:11]
	v_mfma_f32_16x16x32_bf16 v[52:55], v[166:169], v[182:185], 0
	v_mfma_f32_16x16x32_bf16 v[48:51], v[174:177], v[182:185], 0
	v_mfma_f32_16x16x32_bf16 v[36:39], v[166:169], v[190:193], 0
	v_mfma_f32_16x16x32_bf16 v[32:35], v[174:177], v[190:193], 0
	v_mfma_f32_16x16x32_bf16 v[20:23], v[166:169], v[198:201], 0
	v_mfma_f32_16x16x32_bf16 v[16:19], v[174:177], v[198:201], 0
	v_mfma_f32_16x16x32_bf16 v[4:7], v[166:169], v[206:209], 0
	v_mfma_f32_16x16x32_bf16 v[0:3], v[174:177], v[206:209], 0
	v_mfma_f32_16x16x32_bf16 v[52:55], v[170:173], v[186:189], v[52:55]
	v_mfma_f32_16x16x32_bf16 v[48:51], v[178:181], v[186:189], v[48:51]
	v_mfma_f32_16x16x32_bf16 v[36:39], v[170:173], v[194:197], v[36:39]
	v_mfma_f32_16x16x32_bf16 v[32:35], v[178:181], v[194:197], v[32:35]
	v_mfma_f32_16x16x32_bf16 v[20:23], v[170:173], v[202:205], v[20:23]
	v_mfma_f32_16x16x32_bf16 v[16:19], v[178:181], v[202:205], v[16:19]
	v_mfma_f32_16x16x32_bf16 v[4:7], v[170:173], v[210:213], v[4:7]
	v_mfma_f32_16x16x32_bf16 v[0:3], v[178:181], v[210:213], v[0:3]
	s_setprio 0
	s_barrier
	s_add_i32 s50, 0, 0x18000
	s_add_i32 s51, 0, 0x1c000
	v_add_u32_e32 v162, s50, v149
	v_add_u32_e32 v178, s51, v149
	ds_read_b128 v[144:147], v162
	ds_read_b128 v[154:157], v162 offset:1024
	ds_read_b128 v[158:161], v162 offset:2048
	ds_read_b128 v[162:165], v162 offset:3072
	ds_read_b128 v[166:169], v178
	ds_read_b128 v[170:173], v178 offset:1024
	ds_read_b128 v[174:177], v178 offset:2048
	ds_read_b128 v[178:181], v178 offset:3072
	s_add_u32 s26, s26, 0x80000
	s_addc_u32 s27, s27, 0
	s_mov_b32 m0, s36
	v_lshl_add_u64 v[222:223], s[26:27], 0, v[128:129]
	ds_read_b128 v[182:185], v153 offset:32768
	ds_read_b128 v[186:189], v153 offset:33792
	ds_read_b128 v[190:193], v153 offset:34816
	ds_read_b128 v[194:197], v153 offset:35840
	ds_read_b128 v[198:201], v153 offset:36864
	ds_read_b128 v[202:205], v153 offset:37888
	ds_read_b128 v[206:209], v153 offset:38912
	ds_read_b128 v[210:213], v153 offset:39936
	global_load_lds_dwordx4 v[222:223], off
	v_lshl_add_u64 v[222:223], s[26:27], 0, v[132:133]
	s_mov_b32 m0, s37
	s_nop 0
	global_load_lds_dwordx4 v[222:223], off
	s_waitcnt vmcnt(8)
	s_waitcnt lgkmcnt(0)
	s_barrier
	s_setprio 1
	s_waitcnt lgkmcnt(0)
	v_mfma_f32_16x16x32_bf16 v[124:127], v[144:147], v[182:185], v[124:127]
	v_mfma_f32_16x16x32_bf16 v[120:123], v[158:161], v[182:185], v[120:123]
	v_mfma_f32_16x16x32_bf16 v[108:111], v[144:147], v[190:193], v[108:111]
	v_mfma_f32_16x16x32_bf16 v[104:107], v[158:161], v[190:193], v[104:107]
	v_mfma_f32_16x16x32_bf16 v[92:95], v[144:147], v[198:201], v[92:95]
	v_mfma_f32_16x16x32_bf16 v[88:91], v[158:161], v[198:201], v[88:91]
	v_mfma_f32_16x16x32_bf16 v[76:79], v[144:147], v[206:209], v[76:79]
	v_mfma_f32_16x16x32_bf16 v[72:75], v[158:161], v[206:209], v[72:75]
	v_mfma_f32_16x16x32_bf16 v[124:127], v[154:157], v[186:189], v[124:127]
	v_mfma_f32_16x16x32_bf16 v[120:123], v[162:165], v[186:189], v[120:123]
	v_mfma_f32_16x16x32_bf16 v[108:111], v[154:157], v[194:197], v[108:111]
	v_mfma_f32_16x16x32_bf16 v[104:107], v[162:165], v[194:197], v[104:107]
	v_mfma_f32_16x16x32_bf16 v[92:95], v[154:157], v[202:205], v[92:95]
	v_mfma_f32_16x16x32_bf16 v[88:91], v[162:165], v[202:205], v[88:91]
	v_mfma_f32_16x16x32_bf16 v[76:79], v[154:157], v[210:213], v[76:79]
	v_mfma_f32_16x16x32_bf16 v[72:75], v[162:165], v[210:213], v[72:75]
	v_mfma_f32_16x16x32_bf16 v[116:119], v[166:169], v[182:185], v[116:119]
	v_mfma_f32_16x16x32_bf16 v[112:115], v[174:177], v[182:185], v[112:115]
	v_mfma_f32_16x16x32_bf16 v[100:103], v[166:169], v[190:193], v[100:103]
	v_mfma_f32_16x16x32_bf16 v[96:99], v[174:177], v[190:193], v[96:99]
	v_mfma_f32_16x16x32_bf16 v[84:87], v[166:169], v[198:201], v[84:87]
	v_mfma_f32_16x16x32_bf16 v[80:83], v[174:177], v[198:201], v[80:83]
	v_mfma_f32_16x16x32_bf16 v[68:71], v[166:169], v[206:209], v[68:71]
	v_mfma_f32_16x16x32_bf16 v[64:67], v[174:177], v[206:209], v[64:67]
	v_mfma_f32_16x16x32_bf16 v[116:119], v[170:173], v[186:189], v[116:119]
	v_mfma_f32_16x16x32_bf16 v[112:115], v[178:181], v[186:189], v[112:115]
	v_mfma_f32_16x16x32_bf16 v[100:103], v[170:173], v[194:197], v[100:103]
	v_mfma_f32_16x16x32_bf16 v[96:99], v[178:181], v[194:197], v[96:99]
	v_mfma_f32_16x16x32_bf16 v[84:87], v[170:173], v[202:205], v[84:87]
	v_mfma_f32_16x16x32_bf16 v[80:83], v[178:181], v[202:205], v[80:83]
	v_mfma_f32_16x16x32_bf16 v[68:71], v[170:173], v[210:213], v[68:71]
	v_mfma_f32_16x16x32_bf16 v[64:67], v[178:181], v[210:213], v[64:67]
	s_setprio 0
	s_barrier
; #define PG8_STAGE(bufoff, gbase, voff) do { _Pragma("unroll") for (int _i = 0; _i < 2; ++_i) \
;         __builtin_amdgcn_global_load_lds((const unsigned*)((const char*)(gbase) + (voff)[_i]), (PG8_LAS unsigned*)(lds + (bufoff) + ldsw + _i * 8192), 16, 0, 0); } while (0)
; #define PG8_LDA(dst, b, h) do { _Pragma("unroll") for (int m = 0; m < 4; ++m) _Pragma("unroll") for (int k = 0; k < 2; ++k) dst[m][k] = *(const PG8_LAS bf16x8*)(lds + PG8_SA(b, h) + aoff + m * 2048 + k * 1024); } while (0)
; #define PG8_LDB(dst, b, h) do { _Pragma("unroll") for (int n = 0; n < 2; ++n) _Pragma("unroll") for (int k = 0; k < 2; ++k) dst[n][k] = *(const PG8_LAS bf16x8*)(lds + PG8_SB(b, h) + boff + n * 2048 + k * 1024); } while (0)
; #define PG8_MMA(ai, bj, At, Bt) do { __builtin_amdgcn_s_setprio(1); _Pragma("unroll") for (int m = 0; m < 4; ++m) _Pragma("unroll") for (int n = 0; n < 2; ++n) _Pragma("unroll") for (int k = 0; k < 2; ++k) \
;         acc[ai][bj][m][n] = __builtin_amdgcn_mfma_f32_16x16x32_bf16(Bt[n][k], At[m][k], acc[ai][bj][m][n], 0, 0, 0); __builtin_amdgcn_s_setprio(0); } while (0)
; #define PG8_BAR __builtin_amdgcn_s_barrier()
; template <class Epi, class Sched, bool ALIGN_EPI = false, bool SP2 = false>
; __device__ __forceinline__ void gemm_phase(PG8_LAS unsigned char* lds, const Gemm g, const Sched& S, const Epi& E, const int wave_in) {
;     ...
;             PG8_LDB(B0, 0, 0); PG8_LDB(B1, 0, 1); PG8_SCHED; PG8_LDA(At, 0, 0); PG8_STAGE(PG8_SA(1, 1), a1 + hstepA, voffA);
;             PG8_WAIT_V(8); PG8_WAIT_L(0); PG8_BAR; PG8_MMA(0, 0, At, B0); PG8_MMA(0, 1, At, B1); PG8_BAR; PG8_SCHED;
;             PG8_LDA(At, 0, 1); PG8_STAGE(PG8_SB(0, 0), b2, voffB); PG8_STAGE(PG8_SB(0, 1), b2 + hstepB, voffB); PG8_STAGE(PG8_SA(0, 0), a2, voffA);
;             PG8_WAIT_V(8); PG8_WAIT_L(0); PG8_BAR; PG8_MMA(1, 0, At, B0); PG8_MMA(1, 1, At, B1); PG8_BAR; PG8_SCHED;
;             PG8_LDB(B0, 1, 0); PG8_LDB(B1, 1, 1); PG8_SCHED; PG8_LDA(At, 1, 0); PG8_STAGE(PG8_SA(0, 1), a2 + hstepA, voffA);
;             PG8_WAIT_V(8); PG8_WAIT_L(0); PG8_BAR; PG8_MMA(0, 0, At, B0); PG8_MMA(0, 1, At, B1); PG8_BAR; PG8_SCHED;
;             PG8_LDA(At, 1, 1); PG8_STAGE(PG8_SB(1, 0), b3, voffB); PG8_STAGE(PG8_SB(1, 1), b3 + hstepB, voffB); PG8_STAGE(PG8_SA(1, 0), a3, voffA);
;             PG8_WAIT_V(8); PG8_WAIT_L(0); PG8_BAR; PG8_MMA(1, 0, At, B0); PG8_MMA(1, 1, At, B1); PG8_BAR; PG8_SCHED;
	s_add_i32 s26, s50, s34
	v_lshl_add_u64 v[214:215], v[214:215], 0, s[8:9]
	s_mov_b32 m0, s26
	ds_read_b128 v[182:185], v153 offset:49152
	ds_read_b128 v[186:189], v153 offset:50176
	ds_read_b128 v[190:193], v153 offset:51200
	ds_read_b128 v[194:197], v153 offset:52224
	ds_read_b128 v[198:201], v153 offset:53248
	ds_read_b128 v[202:205], v153 offset:54272
	ds_read_b128 v[206:209], v153 offset:55296
	ds_read_b128 v[210:213], v153 offset:56320
	global_load_lds_dwordx4 v[214:215], off
	s_add_i32 m0, s26, 0x2000
	s_add_u32 s24, s24, 0x80080
	v_lshl_add_u64 v[214:215], v[216:217], 0, s[8:9]
	s_addc_u32 s25, s25, 0
	s_add_i32 s26, s51, s34
	global_load_lds_dwordx4 v[214:215], off
	v_lshl_add_u64 v[214:215], s[24:25], 0, v[130:131]
	s_mov_b32 m0, s26
	s_nop 0
	global_load_lds_dwordx4 v[214:215], off
	v_lshl_add_u64 v[214:215], s[24:25], 0, v[134:135]
	s_add_i32 m0, s26, 0x2000
	s_nop 0
	global_load_lds_dwordx4 v[214:215], off
	v_lshl_add_u64 v[214:215], v[218:219], 0, s[8:9]
	s_mov_b32 m0, s39
	s_nop 0
	global_load_lds_dwordx4 v[214:215], off
	v_lshl_add_u64 v[214:215], v[220:221], 0, s[8:9]
	s_mov_b32 m0, s40
	s_nop 0
	global_load_lds_dwordx4 v[214:215], off
	s_waitcnt vmcnt(8)
	s_waitcnt lgkmcnt(0)
	s_barrier
	s_setprio 1
	s_waitcnt lgkmcnt(0)
	v_mfma_f32_16x16x32_bf16 v[60:63], v[144:147], v[182:185], v[60:63]
	v_mfma_f32_16x16x32_bf16 v[56:59], v[158:161], v[182:185], v[56:59]
	v_mfma_f32_16x16x32_bf16 v[44:47], v[144:147], v[190:193], v[44:47]
	v_mfma_f32_16x16x32_bf16 v[40:43], v[158:161], v[190:193], v[40:43]
	v_mfma_f32_16x16x32_bf16 v[28:31], v[144:147], v[198:201], v[28:31]
	v_mfma_f32_16x16x32_bf16 v[24:27], v[158:161], v[198:201], v[24:27]
	v_mfma_f32_16x16x32_bf16 v[12:15], v[144:147], v[206:209], v[12:15]
	v_mfma_f32_16x16x32_bf16 v[8:11], v[158:161], v[206:209], v[8:11]
	v_mfma_f32_16x16x32_bf16 v[60:63], v[154:157], v[186:189], v[60:63]
	v_mfma_f32_16x16x32_bf16 v[56:59], v[162:165], v[186:189], v[56:59]
	v_mfma_f32_16x16x32_bf16 v[44:47], v[154:157], v[194:197], v[44:47]
	v_mfma_f32_16x16x32_bf16 v[40:43], v[162:165], v[194:197], v[40:43]
	v_mfma_f32_16x16x32_bf16 v[28:31], v[154:157], v[202:205], v[28:31]
	v_mfma_f32_16x16x32_bf16 v[24:27], v[162:165], v[202:205], v[24:27]
	v_mfma_f32_16x16x32_bf16 v[12:15], v[154:157], v[210:213], v[12:15]
	v_mfma_f32_16x16x32_bf16 v[8:11], v[162:165], v[210:213], v[8:11]
	v_mfma_f32_16x16x32_bf16 v[52:55], v[166:169], v[182:185], v[52:55]
	v_mfma_f32_16x16x32_bf16 v[48:51], v[174:177], v[182:185], v[48:51]
	v_mfma_f32_16x16x32_bf16 v[36:39], v[166:169], v[190:193], v[36:39]
	v_mfma_f32_16x16x32_bf16 v[32:35], v[174:177], v[190:193], v[32:35]
	v_mfma_f32_16x16x32_bf16 v[20:23], v[166:169], v[198:201], v[20:23]
	v_mfma_f32_16x16x32_bf16 v[16:19], v[174:177], v[198:201], v[16:19]
	v_mfma_f32_16x16x32_bf16 v[4:7], v[166:169], v[206:209], v[4:7]
	v_mfma_f32_16x16x32_bf16 v[0:3], v[174:177], v[206:209], v[0:3]
	v_mfma_f32_16x16x32_bf16 v[52:55], v[170:173], v[186:189], v[52:55]
	v_mfma_f32_16x16x32_bf16 v[48:51], v[178:181], v[186:189], v[48:51]
	v_mfma_f32_16x16x32_bf16 v[36:39], v[170:173], v[194:197], v[36:39]
	v_mfma_f32_16x16x32_bf16 v[32:35], v[178:181], v[194:197], v[32:35]
	v_mfma_f32_16x16x32_bf16 v[20:23], v[170:173], v[202:205], v[20:23]
	v_mfma_f32_16x16x32_bf16 v[16:19], v[178:181], v[202:205], v[16:19]
	v_mfma_f32_16x16x32_bf16 v[4:7], v[170:173], v[210:213], v[4:7]
	v_mfma_f32_16x16x32_bf16 v[0:3], v[178:181], v[210:213], v[0:3]
	s_setprio 0
	s_barrier
	s_add_i32 s49, s49, 2
	s_add_u32 s22, s22, 0x100
	s_addc_u32 s23, s23, 0
	s_add_u32 s47, s47, 0x100
	s_addc_u32 s48, s48, 0
	s_cmp_gt_u32 s49, 29
	s_cbranch_scc0 .LBB0_158
	s_branch .Lkx_2
.LBB0_158:
	ds_read_b128 v[144:147], v151
	ds_read_b128 v[154:157], v151 offset:1024
	ds_read_b128 v[158:161], v151 offset:2048
	ds_read_b128 v[162:165], v151 offset:3072
	ds_read_b128 v[166:169], v152
	ds_read_b128 v[170:173], v152 offset:1024
	ds_read_b128 v[174:177], v152 offset:2048
	ds_read_b128 v[178:181], v152 offset:3072
	s_add_u32 s24, s22, 0xfff80080
	s_addc_u32 s25, s23, -1
	s_cmp_eq_u32 s49, 28
	s_cselect_b32 s27, s5, s25
	s_cselect_b32 s26, s15, s24
	s_cselect_b32 s25, s13, s48
	s_cselect_b32 s24, s46, s47
	v_lshl_add_u64 v[214:215], s[22:23], 0, v[136:137]
	s_add_i32 m0, s21, 0xc000
	ds_read_b128 v[182:185], v153
	ds_read_b128 v[186:189], v153 offset:1024
	ds_read_b128 v[190:193], v153 offset:2048
	ds_read_b128 v[194:197], v153 offset:3072
	ds_read_b128 v[198:201], v153 offset:4096
	ds_read_b128 v[202:205], v153 offset:5120
	ds_read_b128 v[206:209], v153 offset:6144
	ds_read_b128 v[210:213], v153 offset:7168
	global_load_lds_dwordx4 v[214:215], off
	v_lshl_add_u64 v[214:215], s[22:23], 0, v[138:139]
	s_add_i32 m0, s21, 0xe000
	s_nop 0
	global_load_lds_dwordx4 v[214:215], off
	s_waitcnt vmcnt(8)
	s_waitcnt lgkmcnt(0)
	s_barrier
; #define PG8_STAGE(bufoff, gbase, voff) do { _Pragma("unroll") for (int _i = 0; _i < 2; ++_i) \
;         __builtin_amdgcn_global_load_lds((const unsigned*)((const char*)(gbase) + (voff)[_i]), (PG8_LAS unsigned*)(lds + (bufoff) + ldsw + _i * 8192), 16, 0, 0); } while (0)
; #define PG8_LDA(dst, b, h) do { _Pragma("unroll") for (int m = 0; m < 4; ++m) _Pragma("unroll") for (int k = 0; k < 2; ++k) dst[m][k] = *(const PG8_LAS bf16x8*)(lds + PG8_SA(b, h) + aoff + m * 2048 + k * 1024); } while (0)
; #define PG8_LDB(dst, b, h) do { _Pragma("unroll") for (int n = 0; n < 2; ++n) _Pragma("unroll") for (int k = 0; k < 2; ++k) dst[n][k] = *(const PG8_LAS bf16x8*)(lds + PG8_SB(b, h) + boff + n * 2048 + k * 1024); } while (0)
; #define PG8_MMA(ai, bj, At, Bt) do { __builtin_amdgcn_s_setprio(1); _Pragma("unroll") for (int m = 0; m < 4; ++m) _Pragma("unroll") for (int n = 0; n < 2; ++n) _Pragma("unroll") for (int k = 0; k < 2; ++k) \
;         acc[ai][bj][m][n] = __builtin_amdgcn_mfma_f32_16x16x32_bf16(Bt[n][k], At[m][k], acc[ai][bj][m][n], 0, 0, 0); __builtin_amdgcn_s_setprio(0); } while (0)
; #define PG8_WAIT_V(n) asm volatile("s_waitcnt vmcnt(" #n ")" ::: "memory")
; #define PG8_WAIT_L(n) asm volatile("s_waitcnt lgkmcnt(" #n ")" ::: "memory")
; #define PG8_BAR __builtin_amdgcn_s_barrier()
; #define PG8_SCHED __builtin_amdgcn_sched_barrier(0)
; template <class Epi, class Sched, bool ALIGN_EPI = false, bool SP2 = false>
; __device__ __forceinline__ void gemm_phase(PG8_LAS unsigned char* lds, const Gemm g, const Sched& S, const Epi& E, const int wave_in) {
;     ...
;             PG8_WAIT_V(8); PG8_WAIT_L(0); PG8_BAR; PG8_MMA(0, 0, At, B0); PG8_MMA(0, 1, At, B1); PG8_BAR; PG8_SCHED;
;             PG8_LDA(At, 0, 1); PG8_STAGE(PG8_SB(0, 0), b2, voffB); PG8_STAGE(PG8_SB(0, 1), b2 + hstepB, voffB); PG8_STAGE(PG8_SA(0, 0), a2, voffA);
;             PG8_WAIT_V(8); PG8_WAIT_L(0); PG8_BAR; PG8_MMA(1, 0, At, B0); PG8_MMA(1, 1, At, B1); PG8_BAR; PG8_SCHED;
;             PG8_LDB(B0, 1, 0); PG8_LDB(B1, 1, 1); PG8_SCHED; PG8_LDA(At, 1, 0); PG8_STAGE(PG8_SA(0, 1), a2 + hstepA, voffA);
;             PG8_WAIT_V(8); PG8_WAIT_L(0); PG8_BAR; PG8_MMA(0, 0, At, B0); PG8_MMA(0, 1, At, B1); PG8_BAR; PG8_SCHED;
	s_setprio 1
	s_waitcnt lgkmcnt(0)
	v_mfma_f32_16x16x32_bf16 v[124:127], v[144:147], v[182:185], v[124:127]
	v_mfma_f32_16x16x32_bf16 v[120:123], v[158:161], v[182:185], v[120:123]
	v_mfma_f32_16x16x32_bf16 v[108:111], v[144:147], v[190:193], v[108:111]
	v_mfma_f32_16x16x32_bf16 v[104:107], v[158:161], v[190:193], v[104:107]
	v_mfma_f32_16x16x32_bf16 v[92:95], v[144:147], v[198:201], v[92:95]
	v_mfma_f32_16x16x32_bf16 v[88:91], v[158:161], v[198:201], v[88:91]
	v_mfma_f32_16x16x32_bf16 v[76:79], v[144:147], v[206:209], v[76:79]
	v_mfma_f32_16x16x32_bf16 v[72:75], v[158:161], v[206:209], v[72:75]
	v_mfma_f32_16x16x32_bf16 v[124:127], v[154:157], v[186:189], v[124:127]
	v_mfma_f32_16x16x32_bf16 v[120:123], v[162:165], v[186:189], v[120:123]
	v_mfma_f32_16x16x32_bf16 v[108:111], v[154:157], v[194:197], v[108:111]
	v_mfma_f32_16x16x32_bf16 v[104:107], v[162:165], v[194:197], v[104:107]
	v_mfma_f32_16x16x32_bf16 v[92:95], v[154:157], v[202:205], v[92:95]
	v_mfma_f32_16x16x32_bf16 v[88:91], v[162:165], v[202:205], v[88:91]
	v_mfma_f32_16x16x32_bf16 v[76:79], v[154:157], v[210:213], v[76:79]
	v_mfma_f32_16x16x32_bf16 v[72:75], v[162:165], v[210:213], v[72:75]
	v_mfma_f32_16x16x32_bf16 v[116:119], v[166:169], v[182:185], v[116:119]
	v_mfma_f32_16x16x32_bf16 v[112:115], v[174:177], v[182:185], v[112:115]
	v_mfma_f32_16x16x32_bf16 v[100:103], v[166:169], v[190:193], v[100:103]
	v_mfma_f32_16x16x32_bf16 v[96:99], v[174:177], v[190:193], v[96:99]
	v_mfma_f32_16x16x32_bf16 v[84:87], v[166:169], v[198:201], v[84:87]
	v_mfma_f32_16x16x32_bf16 v[80:83], v[174:177], v[198:201], v[80:83]
	v_mfma_f32_16x16x32_bf16 v[68:71], v[166:169], v[206:209], v[68:71]
	v_mfma_f32_16x16x32_bf16 v[64:67], v[174:177], v[206:209], v[64:67]
	v_mfma_f32_16x16x32_bf16 v[116:119], v[170:173], v[186:189], v[116:119]
	v_mfma_f32_16x16x32_bf16 v[112:115], v[178:181], v[186:189], v[112:115]
	v_mfma_f32_16x16x32_bf16 v[100:103], v[170:173], v[194:197], v[100:103]
	v_mfma_f32_16x16x32_bf16 v[96:99], v[178:181], v[194:197], v[96:99]
	v_mfma_f32_16x16x32_bf16 v[84:87], v[170:173], v[202:205], v[84:87]
	v_mfma_f32_16x16x32_bf16 v[80:83], v[178:181], v[202:205], v[80:83]
	v_mfma_f32_16x16x32_bf16 v[68:71], v[170:173], v[210:213], v[68:71]
	v_mfma_f32_16x16x32_bf16 v[64:67], v[178:181], v[210:213], v[64:67]
	s_setprio 0
	s_barrier
	s_add_i32 s50, s43, s34
	v_lshl_add_u64 v[214:215], s[24:25], 0, v[130:131]
	s_mov_b32 m0, s50
	ds_read_b128 v[182:185], v153 offset:16384
	ds_read_b128 v[186:189], v153 offset:17408
	ds_read_b128 v[190:193], v153 offset:18432
	ds_read_b128 v[194:197], v153 offset:19456
	ds_read_b128 v[198:201], v153 offset:20480
	ds_read_b128 v[202:205], v153 offset:21504
	ds_read_b128 v[206:209], v153 offset:22528
	ds_read_b128 v[210:213], v153 offset:23552
	global_load_lds_dwordx4 v[214:215], off
	s_add_i32 m0, s50, 0x2000
	s_add_u32 s50, s24, 0x80000
	v_lshl_add_u64 v[216:217], s[24:25], 0, v[134:135]
	s_addc_u32 s51, s25, 0
	s_add_i32 s52, s44, s34
	global_load_lds_dwordx4 v[216:217], off
	v_lshl_add_u64 v[218:219], s[50:51], 0, v[130:131]
	s_mov_b32 m0, s52
	v_lshl_add_u64 v[220:221], s[26:27], 0, v[132:133]
	global_load_lds_dwordx4 v[218:219], off
	v_lshl_add_u64 v[218:219], s[50:51], 0, v[134:135]
	s_add_i32 m0, s52, 0x2000
	s_nop 0
	global_load_lds_dwordx4 v[218:219], off
	v_lshl_add_u64 v[218:219], s[26:27], 0, v[128:129]
	s_mov_b32 m0, s21
	s_nop 0
	global_load_lds_dwordx4 v[218:219], off
	s_mov_b32 m0, s35
	s_nop 0
	global_load_lds_dwordx4 v[220:221], off
	s_waitcnt vmcnt(8)
	s_waitcnt lgkmcnt(0)
	s_barrier
	s_setprio 1
	s_waitcnt lgkmcnt(0)
	v_mfma_f32_16x16x32_bf16 v[60:63], v[144:147], v[182:185], v[60:63]
	v_mfma_f32_16x16x32_bf16 v[56:59], v[158:161], v[182:185], v[56:59]
	v_mfma_f32_16x16x32_bf16 v[44:47], v[144:147], v[190:193], v[44:47]
	v_mfma_f32_16x16x32_bf16 v[40:43], v[158:161], v[190:193], v[40:43]
	v_mfma_f32_16x16x32_bf16 v[28:31], v[144:147], v[198:201], v[28:31]
	v_mfma_f32_16x16x32_bf16 v[24:27], v[158:161], v[198:201], v[24:27]
	v_mfma_f32_16x16x32_bf16 v[12:15], v[144:147], v[206:209], v[12:15]
	v_mfma_f32_16x16x32_bf16 v[8:11], v[158:161], v[206:209], v[8:11]
	v_mfma_f32_16x16x32_bf16 v[60:63], v[154:157], v[186:189], v[60:63]
	v_mfma_f32_16x16x32_bf16 v[56:59], v[162:165], v[186:189], v[56:59]
	v_mfma_f32_16x16x32_bf16 v[44:47], v[154:157], v[194:197], v[44:47]
	v_mfma_f32_16x16x32_bf16 v[40:43], v[162:165], v[194:197], v[40:43]
	v_mfma_f32_16x16x32_bf16 v[28:31], v[154:157], v[202:205], v[28:31]
	v_mfma_f32_16x16x32_bf16 v[24:27], v[162:165], v[202:205], v[24:27]
	v_mfma_f32_16x16x32_bf16 v[12:15], v[154:157], v[210:213], v[12:15]
	v_mfma_f32_16x16x32_bf16 v[8:11], v[162:165], v[210:213], v[8:11]
	v_mfma_f32_16x16x32_bf16 v[52:55], v[166:169], v[182:185], v[52:55]
	v_mfma_f32_16x16x32_bf16 v[48:51], v[174:177], v[182:185], v[48:51]
	v_mfma_f32_16x16x32_bf16 v[36:39], v[166:169], v[190:193], v[36:39]
	v_mfma_f32_16x16x32_bf16 v[32:35], v[174:177], v[190:193], v[32:35]
	v_mfma_f32_16x16x32_bf16 v[20:23], v[166:169], v[198:201], v[20:23]
	v_mfma_f32_16x16x32_bf16 v[16:19], v[174:177], v[198:201], v[16:19]
	v_mfma_f32_16x16x32_bf16 v[4:7], v[166:169], v[206:209], v[4:7]
	v_mfma_f32_16x16x32_bf16 v[0:3], v[174:177], v[206:209], v[0:3]
	v_mfma_f32_16x16x32_bf16 v[52:55], v[170:173], v[186:189], v[52:55]
	v_mfma_f32_16x16x32_bf16 v[48:51], v[178:181], v[186:189], v[48:51]
	v_mfma_f32_16x16x32_bf16 v[36:39], v[170:173], v[194:197], v[36:39]
	v_mfma_f32_16x16x32_bf16 v[32:35], v[178:181], v[194:197], v[32:35]
	v_mfma_f32_16x16x32_bf16 v[20:23], v[170:173], v[202:205], v[20:23]
	v_mfma_f32_16x16x32_bf16 v[16:19], v[178:181], v[202:205], v[16:19]
	v_mfma_f32_16x16x32_bf16 v[4:7], v[170:173], v[210:213], v[4:7]
	v_mfma_f32_16x16x32_bf16 v[0:3], v[178:181], v[210:213], v[0:3]
	s_setprio 0
	s_barrier
; #define PG8_STAGE(bufoff, gbase, voff) do { _Pragma("unroll") for (int _i = 0; _i < 2; ++_i) \
;         __builtin_amdgcn_global_load_lds((const unsigned*)((const char*)(gbase) + (voff)[_i]), (PG8_LAS unsigned*)(lds + (bufoff) + ldsw + _i * 8192), 16, 0, 0); } while (0)
; #define PG8_LDA(dst, b, h) do { _Pragma("unroll") for (int m = 0; m < 4; ++m) _Pragma("unroll") for (int k = 0; k < 2; ++k) dst[m][k] = *(const PG8_LAS bf16x8*)(lds + PG8_SA(b, h) + aoff + m * 2048 + k * 1024); } while (0)
; #define PG8_LDB(dst, b, h) do { _Pragma("unroll") for (int n = 0; n < 2; ++n) _Pragma("unroll") for (int k = 0; k < 2; ++k) dst[n][k] = *(const PG8_LAS bf16x8*)(lds + PG8_SB(b, h) + boff + n * 2048 + k * 1024); } while (0)
; #define PG8_MMA(ai, bj, At, Bt) do { __builtin_amdgcn_s_setprio(1); _Pragma("unroll") for (int m = 0; m < 4; ++m) _Pragma("unroll") for (int n = 0; n < 2; ++n) _Pragma("unroll") for (int k = 0; k < 2; ++k) \
;         acc[ai][bj][m][n] = __builtin_amdgcn_mfma_f32_16x16x32_bf16(Bt[n][k], At[m][k], acc[ai][bj][m][n], 0, 0, 0); __builtin_amdgcn_s_setprio(0); } while (0)
; #define PG8_WAIT_V(n) asm volatile("s_waitcnt vmcnt(" #n ")" ::: "memory")
; #define PG8_WAIT_L(n) asm volatile("s_waitcnt lgkmcnt(" #n ")" ::: "memory")
; #define PG8_BAR __builtin_amdgcn_s_barrier()
; #define PG8_SCHED __builtin_amdgcn_sched_barrier(0)
; template <class Epi, class Sched, bool ALIGN_EPI = false, bool SP2 = false>
; __device__ __forceinline__ void gemm_phase(PG8_LAS unsigned char* lds, const Gemm g, const Sched& S, const Epi& E, const int wave_in) {
;     ...
;             PG8_LDB(B0, 1, 0); PG8_LDB(B1, 1, 1); PG8_SCHED; PG8_LDA(At, 1, 0); PG8_STAGE(PG8_SA(0, 1), a2 + hstepA, voffA);
;             PG8_WAIT_V(8); PG8_WAIT_L(0); PG8_BAR; PG8_MMA(0, 0, At, B0); PG8_MMA(0, 1, At, B1); PG8_BAR; PG8_SCHED;
	s_add_i32 s50, 0, 0x18000
	s_add_i32 s51, 0, 0x1c000
	v_add_u32_e32 v162, s50, v149
	v_add_u32_e32 v178, s51, v149
	ds_read_b128 v[144:147], v162
	ds_read_b128 v[154:157], v162 offset:1024
	ds_read_b128 v[158:161], v162 offset:2048
	ds_read_b128 v[162:165], v162 offset:3072
	ds_read_b128 v[166:169], v178
	ds_read_b128 v[170:173], v178 offset:1024
	ds_read_b128 v[174:177], v178 offset:2048
	ds_read_b128 v[178:181], v178 offset:3072
	s_add_u32 s26, s26, 0x80000
	s_addc_u32 s27, s27, 0
	s_mov_b32 m0, s36
	v_lshl_add_u64 v[222:223], s[26:27], 0, v[128:129]
	ds_read_b128 v[182:185], v153 offset:32768
	ds_read_b128 v[186:189], v153 offset:33792
	ds_read_b128 v[190:193], v153 offset:34816
	ds_read_b128 v[194:197], v153 offset:35840
	ds_read_b128 v[198:201], v153 offset:36864
	ds_read_b128 v[202:205], v153 offset:37888
	ds_read_b128 v[206:209], v153 offset:38912
	ds_read_b128 v[210:213], v153 offset:39936
	global_load_lds_dwordx4 v[222:223], off
	v_lshl_add_u64 v[222:223], s[26:27], 0, v[132:133]
	s_mov_b32 m0, s37
	s_nop 0
	global_load_lds_dwordx4 v[222:223], off
	s_waitcnt vmcnt(8)
	s_waitcnt lgkmcnt(0)
	s_barrier
	s_setprio 1
	s_waitcnt lgkmcnt(0)
	v_mfma_f32_16x16x32_bf16 v[124:127], v[144:147], v[182:185], v[124:127]
	v_mfma_f32_16x16x32_bf16 v[120:123], v[158:161], v[182:185], v[120:123]
	v_mfma_f32_16x16x32_bf16 v[108:111], v[144:147], v[190:193], v[108:111]
	v_mfma_f32_16x16x32_bf16 v[104:107], v[158:161], v[190:193], v[104:107]
	v_mfma_f32_16x16x32_bf16 v[92:95], v[144:147], v[198:201], v[92:95]
	v_mfma_f32_16x16x32_bf16 v[88:91], v[158:161], v[198:201], v[88:91]
	v_mfma_f32_16x16x32_bf16 v[76:79], v[144:147], v[206:209], v[76:79]
	v_mfma_f32_16x16x32_bf16 v[72:75], v[158:161], v[206:209], v[72:75]
	v_mfma_f32_16x16x32_bf16 v[124:127], v[154:157], v[186:189], v[124:127]
	v_mfma_f32_16x16x32_bf16 v[120:123], v[162:165], v[186:189], v[120:123]
	v_mfma_f32_16x16x32_bf16 v[108:111], v[154:157], v[194:197], v[108:111]
	v_mfma_f32_16x16x32_bf16 v[104:107], v[162:165], v[194:197], v[104:107]
	v_mfma_f32_16x16x32_bf16 v[92:95], v[154:157], v[202:205], v[92:95]
	v_mfma_f32_16x16x32_bf16 v[88:91], v[162:165], v[202:205], v[88:91]
	v_mfma_f32_16x16x32_bf16 v[76:79], v[154:157], v[210:213], v[76:79]
	v_mfma_f32_16x16x32_bf16 v[72:75], v[162:165], v[210:213], v[72:75]
	v_mfma_f32_16x16x32_bf16 v[116:119], v[166:169], v[182:185], v[116:119]
	v_mfma_f32_16x16x32_bf16 v[112:115], v[174:177], v[182:185], v[112:115]
	v_mfma_f32_16x16x32_bf16 v[100:103], v[166:169], v[190:193], v[100:103]
	v_mfma_f32_16x16x32_bf16 v[96:99], v[174:177], v[190:193], v[96:99]
	v_mfma_f32_16x16x32_bf16 v[84:87], v[166:169], v[198:201], v[84:87]
	v_mfma_f32_16x16x32_bf16 v[80:83], v[174:177], v[198:201], v[80:83]
	v_mfma_f32_16x16x32_bf16 v[68:71], v[166:169], v[206:209], v[68:71]
	v_mfma_f32_16x16x32_bf16 v[64:67], v[174:177], v[206:209], v[64:67]
	v_mfma_f32_16x16x32_bf16 v[116:119], v[170:173], v[186:189], v[116:119]
	v_mfma_f32_16x16x32_bf16 v[112:115], v[178:181], v[186:189], v[112:115]
	v_mfma_f32_16x16x32_bf16 v[100:103], v[170:173], v[194:197], v[100:103]
	v_mfma_f32_16x16x32_bf16 v[96:99], v[178:181], v[194:197], v[96:99]
	v_mfma_f32_16x16x32_bf16 v[84:87], v[170:173], v[202:205], v[84:87]
	v_mfma_f32_16x16x32_bf16 v[80:83], v[178:181], v[202:205], v[80:83]
	v_mfma_f32_16x16x32_bf16 v[68:71], v[170:173], v[210:213], v[68:71]
	v_mfma_f32_16x16x32_bf16 v[64:67], v[178:181], v[210:213], v[64:67]
	s_setprio 0
	s_barrier
; #define PG8_STAGE(bufoff, gbase, voff) do { _Pragma("unroll") for (int _i = 0; _i < 2; ++_i) \
;         __builtin_amdgcn_global_load_lds((const unsigned*)((const char*)(gbase) + (voff)[_i]), (PG8_LAS unsigned*)(lds + (bufoff) + ldsw + _i * 8192), 16, 0, 0); } while (0)
; #define PG8_LDA(dst, b, h) do { _Pragma("unroll") for (int m = 0; m < 4; ++m) _Pragma("unroll") for (int k = 0; k < 2; ++k) dst[m][k] = *(const PG8_LAS bf16x8*)(lds + PG8_SA(b, h) + aoff + m * 2048 + k * 1024); } while (0)
; #define PG8_MMA(ai, bj, At, Bt) do { __builtin_amdgcn_s_setprio(1); _Pragma("unroll") for (int m = 0; m < 4; ++m) _Pragma("unroll") for (int n = 0; n < 2; ++n) _Pragma("unroll") for (int k = 0; k < 2; ++k) \
;         acc[ai][bj][m][n] = __builtin_amdgcn_mfma_f32_16x16x32_bf16(Bt[n][k], At[m][k], acc[ai][bj][m][n], 0, 0, 0); __builtin_amdgcn_s_setprio(0); } while (0)
; #define PG8_WAIT_V(n) asm volatile("s_waitcnt vmcnt(" #n ")" ::: "memory")
; #define PG8_WAIT_L(n) asm volatile("s_waitcnt lgkmcnt(" #n ")" ::: "memory")
; #define PG8_BAR __builtin_amdgcn_s_barrier()
; #define PG8_SCHED __builtin_amdgcn_sched_barrier(0)
; template <class Epi, class Sched, bool ALIGN_EPI = false, bool SP2 = false>
; __device__ __forceinline__ void gemm_phase(PG8_LAS unsigned char* lds, const Gemm g, const Sched& S, const Epi& E, const int wave_in) {
;     ...
;         for (int t = 0; t < nt; t += 2) {
;             const bool last = (t == nt - 2);
;     ...
;             PG8_LDA(At, 1, 1); PG8_STAGE(PG8_SB(1, 0), b3, voffB); PG8_STAGE(PG8_SB(1, 1), b3 + hstepB, voffB); PG8_STAGE(PG8_SA(1, 0), a3, voffA);
;             PG8_WAIT_V(8); PG8_WAIT_L(0); PG8_BAR; PG8_MMA(1, 0, At, B0); PG8_MMA(1, 1, At, B1); PG8_BAR; PG8_SCHED;
	s_add_i32 s26, s50, s34
	v_lshl_add_u64 v[214:215], v[214:215], 0, s[8:9]
	s_mov_b32 m0, s26
	ds_read_b128 v[182:185], v153 offset:49152
	ds_read_b128 v[186:189], v153 offset:50176
	ds_read_b128 v[190:193], v153 offset:51200
	ds_read_b128 v[194:197], v153 offset:52224
	ds_read_b128 v[198:201], v153 offset:53248
	ds_read_b128 v[202:205], v153 offset:54272
	ds_read_b128 v[206:209], v153 offset:55296
	ds_read_b128 v[210:213], v153 offset:56320
	global_load_lds_dwordx4 v[214:215], off
	s_add_i32 m0, s26, 0x2000
	s_add_u32 s24, s24, 0x80080
	v_lshl_add_u64 v[214:215], v[216:217], 0, s[8:9]
	s_addc_u32 s25, s25, 0
	s_add_i32 s26, s51, s34
	global_load_lds_dwordx4 v[214:215], off
	v_lshl_add_u64 v[214:215], s[24:25], 0, v[130:131]
	s_mov_b32 m0, s26
	s_nop 0
	global_load_lds_dwordx4 v[214:215], off
	v_lshl_add_u64 v[214:215], s[24:25], 0, v[134:135]
	s_add_i32 m0, s26, 0x2000
	s_nop 0
	global_load_lds_dwordx4 v[214:215], off
	v_lshl_add_u64 v[214:215], v[218:219], 0, s[8:9]
	s_mov_b32 m0, s39
	s_nop 0
	global_load_lds_dwordx4 v[214:215], off
	v_lshl_add_u64 v[214:215], v[220:221], 0, s[8:9]
	s_mov_b32 m0, s40
	s_nop 0
	global_load_lds_dwordx4 v[214:215], off
	s_waitcnt vmcnt(8)
	s_waitcnt lgkmcnt(0)
	s_barrier
	s_setprio 1
	s_waitcnt lgkmcnt(0)
	v_mfma_f32_16x16x32_bf16 v[60:63], v[144:147], v[182:185], v[60:63]
	v_mfma_f32_16x16x32_bf16 v[56:59], v[158:161], v[182:185], v[56:59]
	v_mfma_f32_16x16x32_bf16 v[44:47], v[144:147], v[190:193], v[44:47]
	v_mfma_f32_16x16x32_bf16 v[40:43], v[158:161], v[190:193], v[40:43]
	v_mfma_f32_16x16x32_bf16 v[28:31], v[144:147], v[198:201], v[28:31]
	v_mfma_f32_16x16x32_bf16 v[24:27], v[158:161], v[198:201], v[24:27]
	v_mfma_f32_16x16x32_bf16 v[12:15], v[144:147], v[206:209], v[12:15]
	v_mfma_f32_16x16x32_bf16 v[8:11], v[158:161], v[206:209], v[8:11]
	v_mfma_f32_16x16x32_bf16 v[60:63], v[154:157], v[186:189], v[60:63]
	v_mfma_f32_16x16x32_bf16 v[56:59], v[162:165], v[186:189], v[56:59]
	v_mfma_f32_16x16x32_bf16 v[44:47], v[154:157], v[194:197], v[44:47]
	v_mfma_f32_16x16x32_bf16 v[40:43], v[162:165], v[194:197], v[40:43]
	v_mfma_f32_16x16x32_bf16 v[28:31], v[154:157], v[202:205], v[28:31]
	v_mfma_f32_16x16x32_bf16 v[24:27], v[162:165], v[202:205], v[24:27]
	v_mfma_f32_16x16x32_bf16 v[12:15], v[154:157], v[210:213], v[12:15]
	v_mfma_f32_16x16x32_bf16 v[8:11], v[162:165], v[210:213], v[8:11]
	v_mfma_f32_16x16x32_bf16 v[52:55], v[166:169], v[182:185], v[52:55]
	v_mfma_f32_16x16x32_bf16 v[48:51], v[174:177], v[182:185], v[48:51]
	v_mfma_f32_16x16x32_bf16 v[36:39], v[166:169], v[190:193], v[36:39]
	v_mfma_f32_16x16x32_bf16 v[32:35], v[174:177], v[190:193], v[32:35]
	v_mfma_f32_16x16x32_bf16 v[20:23], v[166:169], v[198:201], v[20:23]
	v_mfma_f32_16x16x32_bf16 v[16:19], v[174:177], v[198:201], v[16:19]
	v_mfma_f32_16x16x32_bf16 v[4:7], v[166:169], v[206:209], v[4:7]
	v_mfma_f32_16x16x32_bf16 v[0:3], v[174:177], v[206:209], v[0:3]
	v_mfma_f32_16x16x32_bf16 v[52:55], v[170:173], v[186:189], v[52:55]
	v_mfma_f32_16x16x32_bf16 v[48:51], v[178:181], v[186:189], v[48:51]
	v_mfma_f32_16x16x32_bf16 v[36:39], v[170:173], v[194:197], v[36:39]
	v_mfma_f32_16x16x32_bf16 v[32:35], v[178:181], v[194:197], v[32:35]
	v_mfma_f32_16x16x32_bf16 v[20:23], v[170:173], v[202:205], v[20:23]
	v_mfma_f32_16x16x32_bf16 v[16:19], v[178:181], v[202:205], v[16:19]
	v_mfma_f32_16x16x32_bf16 v[4:7], v[170:173], v[210:213], v[4:7]
	v_mfma_f32_16x16x32_bf16 v[0:3], v[178:181], v[210:213], v[0:3]
	s_setprio 0
	s_barrier
	s_add_i32 s49, s49, 2
	s_add_u32 s22, s22, 0x100
	s_addc_u32 s23, s23, 0
	s_add_u32 s47, s47, 0x100
	s_addc_u32 s48, s48, 0
	s_cmp_gt_u32 s49, 29
	s_cbranch_scc0 .LBB0_158

;     __host__ __device__ bool next(int i, Unit& u) const { const bool ok = StaticOrder::next(i, u); u.pm = 0; u.pn = 0; return ok; }
; #define PG8_STAGE(bufoff, gbase, voff) do { _Pragma("unroll") for (int _i = 0; _i < 2; ++_i) \
;         __builtin_amdgcn_global_load_lds((const unsigned*)((const char*)(gbase) + (voff)[_i]), (PG8_LAS unsigned*)(lds + (bufoff) + ldsw + _i * 8192), 16, 0, 0); } while (0)
; #define PG8_LDA(dst, b, h) do { _Pragma("unroll") for (int m = 0; m < 4; ++m) _Pragma("unroll") for (int k = 0; k < 2; ++k) dst[m][k] = *(const PG8_LAS bf16x8*)(lds + PG8_SA(b, h) + aoff + m * 2048 + k * 1024); } while (0)
; #define PG8_LDB(dst, b, h) do { _Pragma("unroll") for (int n = 0; n < 2; ++n) _Pragma("unroll") for (int k = 0; k < 2; ++k) dst[n][k] = *(const PG8_LAS bf16x8*)(lds + PG8_SB(b, h) + boff + n * 2048 + k * 1024); } while (0)
; #define PG8_WAIT_V(n) asm volatile("s_waitcnt vmcnt(" #n ")" ::: "memory")
; #define PG8_WAIT_L(n) asm volatile("s_waitcnt lgkmcnt(" #n ")" ::: "memory")
; #define PG8_BAR __builtin_amdgcn_s_barrier()
; #define PG8_SCHED __builtin_amdgcn_sched_barrier(0)
; template <class Epi, class Sched, bool ALIGN_EPI = false, bool SP2 = false>
; __device__ __forceinline__ void gemm_phase(PG8_LAS unsigned char* lds, const Gemm g, const Sched& S, const Epi& E, const int wave_in) {
;     ...
;         const bool has_next = S.next(ui + 1, nxt);
;         const char* nA = has_next ? (const char*)g.A + (size_t)nxt.pm * tstepA : cA; const char* nB = has_next ? (const char*)g.Bt + (size_t)nxt.pn * tstepB : cB;
;         for (int t = 0; t < nt; t += 2) {
;             const bool last = (t == nt - 2);
;             const char* a1 = cA + (size_t)(t + 1) * kstep;
;             const char* a2 = last ? nA : cA + (size_t)(t + 2) * kstep; const char* b2 = last ? nB : cB + (size_t)(t + 2) * kstep;
;             const char* a3 = a2 + kstep; const char* b3 = b2 + kstep;
;             if (last && has_next) S.a_ready(nxt);
;             if constexpr (SP2) {
;             PG8_LDB(B0, 0, 0); PG8_LDB(B1, 0, 1); PG8_SCHED; PG8_LDA(At, 0, 0); PG8_STAGE(PG8_SA(1, 1), a1 + hstepA, voffA);
;             PG8_WAIT_V(8); PG8_WAIT_L(0); PG8_BAR; PG8_MMA(0, 0, At, B0); PG8_MMA(0, 1, At, B1); PG8_BAR; PG8_SCHED;
;             PG8_LDA(At, 0, 1); PG8_STAGE(PG8_SB(0, 0), b2, voffB); PG8_STAGE(PG8_SB(0, 1), b2 + hstepB, voffB); PG8_STAGE(PG8_SA(0, 0), a2, voffA);
.LBB0_352:
	s_ashr_i32 s15, s14, 31
	s_lshl_b64 s[18:19], s[14:15], 20
	s_add_u32 s18, s30, s18
	s_addc_u32 s19, s31, s19
	s_and_b64 s[4:5], s[4:5], exec
	s_cselect_b32 s15, s19, s25
	s_cselect_b32 s21, s18, s24
	s_add_u32 s51, s24, 0x100
	v_mov_b32_e32 v0, 0
	s_addc_u32 s52, s25, 0
	s_mov_b32 s53, -2
	ds_read_b128 v[128:131], v168
	ds_read_b128 v[132:135], v168 offset:1024
	ds_read_b128 v[136:139], v168 offset:2048
	ds_read_b128 v[140:143], v168 offset:3072
	ds_read_b128 v[162:165], v169
	ds_read_b128 v[172:175], v169 offset:1024
	ds_read_b128 v[176:179], v169 offset:2048
	ds_read_b128 v[180:183], v169 offset:3072
	s_add_u32 s4, s22, 0x100
	s_addc_u32 s5, s23, 0
	s_cmp_eq_u32 s53, 28
	s_cselect_b32 s27, s17, s5
	s_cselect_b32 s26, s16, s4
	s_cselect_b32 s25, s15, s52
	s_cselect_b32 s24, s21, s51
	v_lshl_add_u64 v[216:217], s[22:23], 0, v[154:155]
	s_add_i32 m0, s37, 0xc000
	ds_read_b128 v[184:187], v170
	ds_read_b128 v[188:191], v170 offset:1024
	ds_read_b128 v[192:195], v170 offset:2048
	ds_read_b128 v[196:199], v170 offset:3072
	ds_read_b128 v[200:203], v170 offset:4096
	ds_read_b128 v[204:207], v170 offset:5120
	ds_read_b128 v[208:211], v170 offset:6144
	ds_read_b128 v[212:215], v170 offset:7168
	global_load_lds_dwordx4 v[216:217], off
	v_lshl_add_u64 v[216:217], s[22:23], 0, v[156:157]
	s_add_i32 m0, s37, 0xe000
	s_nop 0
	global_load_lds_dwordx4 v[216:217], off
	s_waitcnt vmcnt(8)
	s_waitcnt lgkmcnt(0)
	s_barrier
	s_setprio 1
	s_waitcnt lgkmcnt(0)
	v_mfma_f32_16x16x32_bf16 v[124:127], v[128:131], v[184:187], 0
	v_mfma_f32_16x16x32_bf16 v[120:123], v[136:139], v[184:187], 0
	v_mfma_f32_16x16x32_bf16 v[116:119], v[128:131], v[192:195], 0
	v_mfma_f32_16x16x32_bf16 v[112:115], v[136:139], v[192:195], 0
	v_mfma_f32_16x16x32_bf16 v[92:95], v[128:131], v[200:203], 0
	v_mfma_f32_16x16x32_bf16 v[88:91], v[136:139], v[200:203], 0
	v_mfma_f32_16x16x32_bf16 v[84:87], v[128:131], v[208:211], 0
	v_mfma_f32_16x16x32_bf16 v[76:79], v[136:139], v[208:211], 0
	v_mfma_f32_16x16x32_bf16 v[124:127], v[132:135], v[188:191], v[124:127]
	v_mfma_f32_16x16x32_bf16 v[120:123], v[140:143], v[188:191], v[120:123]
	v_mfma_f32_16x16x32_bf16 v[116:119], v[132:135], v[196:199], v[116:119]
	v_mfma_f32_16x16x32_bf16 v[112:115], v[140:143], v[196:199], v[112:115]
	v_mfma_f32_16x16x32_bf16 v[92:95], v[132:135], v[204:207], v[92:95]
	v_mfma_f32_16x16x32_bf16 v[88:91], v[140:143], v[204:207], v[88:91]
	v_mfma_f32_16x16x32_bf16 v[84:87], v[132:135], v[212:215], v[84:87]
	v_mfma_f32_16x16x32_bf16 v[76:79], v[140:143], v[212:215], v[76:79]
	v_mfma_f32_16x16x32_bf16 v[108:111], v[162:165], v[184:187], 0
	v_mfma_f32_16x16x32_bf16 v[104:107], v[176:179], v[184:187], 0
	v_mfma_f32_16x16x32_bf16 v[100:103], v[162:165], v[192:195], 0
	v_mfma_f32_16x16x32_bf16 v[96:99], v[176:179], v[192:195], 0
	v_mfma_f32_16x16x32_bf16 v[80:83], v[162:165], v[200:203], 0
	v_mfma_f32_16x16x32_bf16 v[72:75], v[176:179], v[200:203], 0
	v_mfma_f32_16x16x32_bf16 v[68:71], v[162:165], v[208:211], 0
	v_mfma_f32_16x16x32_bf16 v[64:67], v[176:179], v[208:211], 0
	v_mfma_f32_16x16x32_bf16 v[108:111], v[172:175], v[188:191], v[108:111]
	v_mfma_f32_16x16x32_bf16 v[104:107], v[180:183], v[188:191], v[104:107]
	v_mfma_f32_16x16x32_bf16 v[100:103], v[172:175], v[196:199], v[100:103]
	v_mfma_f32_16x16x32_bf16 v[96:99], v[180:183], v[196:199], v[96:99]
	v_mfma_f32_16x16x32_bf16 v[80:83], v[172:175], v[204:207], v[80:83]
	v_mfma_f32_16x16x32_bf16 v[72:75], v[180:183], v[204:207], v[72:75]
	v_mfma_f32_16x16x32_bf16 v[68:71], v[172:175], v[212:215], v[68:71]
	v_mfma_f32_16x16x32_bf16 v[64:67], v[180:183], v[212:215], v[64:67]
	s_setprio 0
	s_barrier
	s_add_i32 s22, s47, s34
	v_lshl_add_u64 v[216:217], s[24:25], 0, v[148:149]
	s_mov_b32 m0, s22
	ds_read_b128 v[184:187], v170 offset:16384
	ds_read_b128 v[188:191], v170 offset:17408
	ds_read_b128 v[192:195], v170 offset:18432
	ds_read_b128 v[196:199], v170 offset:19456
	ds_read_b128 v[200:203], v170 offset:20480
	ds_read_b128 v[204:207], v170 offset:21504
	ds_read_b128 v[208:211], v170 offset:22528
	ds_read_b128 v[212:215], v170 offset:23552
	global_load_lds_dwordx4 v[216:217], off
	s_add_i32 m0, s22, 0x2000
	s_add_u32 s22, s24, 0x80000
	v_lshl_add_u64 v[218:219], s[24:25], 0, v[144:145]
	s_addc_u32 s23, s25, 0
	s_add_i32 s54, s48, s34
	global_load_lds_dwordx4 v[218:219], off
	v_lshl_add_u64 v[220:221], s[22:23], 0, v[148:149]
	s_mov_b32 m0, s54
	v_lshl_add_u64 v[222:223], s[26:27], 0, v[146:147]
	global_load_lds_dwordx4 v[220:221], off
	v_lshl_add_u64 v[220:221], s[22:23], 0, v[144:145]
	s_add_i32 m0, s54, 0x2000
	s_nop 0
	global_load_lds_dwordx4 v[220:221], off
	v_lshl_add_u64 v[220:221], s[26:27], 0, v[150:151]
	s_mov_b32 m0, s37
	s_nop 0
	global_load_lds_dwordx4 v[220:221], off
	s_mov_b32 m0, s38
	s_nop 0
	global_load_lds_dwordx4 v[222:223], off
	s_waitcnt vmcnt(8)
	s_waitcnt lgkmcnt(0)
	s_barrier
; #define PG8_STAGE(bufoff, gbase, voff) do { _Pragma("unroll") for (int _i = 0; _i < 2; ++_i) \
;         __builtin_amdgcn_global_load_lds((const unsigned*)((const char*)(gbase) + (voff)[_i]), (PG8_LAS unsigned*)(lds + (bufoff) + ldsw + _i * 8192), 16, 0, 0); } while (0)
; #define PG8_LDA(dst, b, h) do { _Pragma("unroll") for (int m = 0; m < 4; ++m) _Pragma("unroll") for (int k = 0; k < 2; ++k) dst[m][k] = *(const PG8_LAS bf16x8*)(lds + PG8_SA(b, h) + aoff + m * 2048 + k * 1024); } while (0)
; #define PG8_LDB(dst, b, h) do { _Pragma("unroll") for (int n = 0; n < 2; ++n) _Pragma("unroll") for (int k = 0; k < 2; ++k) dst[n][k] = *(const PG8_LAS bf16x8*)(lds + PG8_SB(b, h) + boff + n * 2048 + k * 1024); } while (0)
; #define PG8_MMA(ai, bj, At, Bt) do { __builtin_amdgcn_s_setprio(1); _Pragma("unroll") for (int m = 0; m < 4; ++m) _Pragma("unroll") for (int n = 0; n < 2; ++n) _Pragma("unroll") for (int k = 0; k < 2; ++k) \
;         acc[ai][bj][m][n] = __builtin_amdgcn_mfma_f32_16x16x32_bf16(Bt[n][k], At[m][k], acc[ai][bj][m][n], 0, 0, 0); __builtin_amdgcn_s_setprio(0); } while (0)
; #define PG8_WAIT_V(n) asm volatile("s_waitcnt vmcnt(" #n ")" ::: "memory")
; #define PG8_WAIT_L(n) asm volatile("s_waitcnt lgkmcnt(" #n ")" ::: "memory")
; #define PG8_BAR __builtin_amdgcn_s_barrier()
; #define PG8_SCHED __builtin_amdgcn_sched_barrier(0)
; template <class Epi, class Sched, bool ALIGN_EPI = false, bool SP2 = false>
; __device__ __forceinline__ void gemm_phase(PG8_LAS unsigned char* lds, const Gemm g, const Sched& S, const Epi& E, const int wave_in) {
;     ...
;             PG8_WAIT_V(8); PG8_WAIT_L(0); PG8_BAR; PG8_MMA(1, 0, At, B0); PG8_MMA(1, 1, At, B1); PG8_BAR; PG8_SCHED;
;             PG8_LDB(B0, 1, 0); PG8_LDB(B1, 1, 1); PG8_SCHED; PG8_LDA(At, 1, 0); PG8_STAGE(PG8_SA(0, 1), a2 + hstepA, voffA);
;             PG8_WAIT_V(8); PG8_WAIT_L(0); PG8_BAR; PG8_MMA(0, 0, At, B0); PG8_MMA(0, 1, At, B1); PG8_BAR; PG8_SCHED;
	s_setprio 1
	s_waitcnt lgkmcnt(0)
	v_mfma_f32_16x16x32_bf16 v[60:63], v[128:131], v[184:187], 0
	v_mfma_f32_16x16x32_bf16 v[56:59], v[136:139], v[184:187], 0
	v_mfma_f32_16x16x32_bf16 v[52:55], v[128:131], v[192:195], 0
	v_mfma_f32_16x16x32_bf16 v[44:47], v[136:139], v[192:195], 0
	v_mfma_f32_16x16x32_bf16 v[36:39], v[128:131], v[200:203], 0
	v_mfma_f32_16x16x32_bf16 v[28:31], v[136:139], v[200:203], 0
	v_mfma_f32_16x16x32_bf16 v[20:23], v[128:131], v[208:211], 0
	v_mfma_f32_16x16x32_bf16 v[12:15], v[136:139], v[208:211], 0
	v_mfma_f32_16x16x32_bf16 v[60:63], v[132:135], v[188:191], v[60:63]
	v_mfma_f32_16x16x32_bf16 v[56:59], v[140:143], v[188:191], v[56:59]
	v_mfma_f32_16x16x32_bf16 v[52:55], v[132:135], v[196:199], v[52:55]
	v_mfma_f32_16x16x32_bf16 v[44:47], v[140:143], v[196:199], v[44:47]
	v_mfma_f32_16x16x32_bf16 v[36:39], v[132:135], v[204:207], v[36:39]
	v_mfma_f32_16x16x32_bf16 v[28:31], v[140:143], v[204:207], v[28:31]
	v_mfma_f32_16x16x32_bf16 v[20:23], v[132:135], v[212:215], v[20:23]
	v_mfma_f32_16x16x32_bf16 v[12:15], v[140:143], v[212:215], v[12:15]
	v_mfma_f32_16x16x32_bf16 v[48:51], v[162:165], v[184:187], 0
	v_mfma_f32_16x16x32_bf16 v[40:43], v[176:179], v[184:187], 0
	v_mfma_f32_16x16x32_bf16 v[32:35], v[162:165], v[192:195], 0
	v_mfma_f32_16x16x32_bf16 v[24:27], v[176:179], v[192:195], 0
	v_mfma_f32_16x16x32_bf16 v[16:19], v[162:165], v[200:203], 0
	v_mfma_f32_16x16x32_bf16 v[8:11], v[176:179], v[200:203], 0
	v_mfma_f32_16x16x32_bf16 v[4:7], v[162:165], v[208:211], 0
	v_mfma_f32_16x16x32_bf16 v[0:3], v[176:179], v[208:211], 0
	v_mfma_f32_16x16x32_bf16 v[48:51], v[172:175], v[188:191], v[48:51]
	v_mfma_f32_16x16x32_bf16 v[40:43], v[180:183], v[188:191], v[40:43]
	v_mfma_f32_16x16x32_bf16 v[32:35], v[172:175], v[196:199], v[32:35]
	v_mfma_f32_16x16x32_bf16 v[24:27], v[180:183], v[196:199], v[24:27]
	v_mfma_f32_16x16x32_bf16 v[16:19], v[172:175], v[204:207], v[16:19]
	v_mfma_f32_16x16x32_bf16 v[8:11], v[180:183], v[204:207], v[8:11]
	v_mfma_f32_16x16x32_bf16 v[4:7], v[172:175], v[212:215], v[4:7]
	v_mfma_f32_16x16x32_bf16 v[0:3], v[180:183], v[212:215], v[0:3]
	s_setprio 0
	s_barrier
	s_add_i32 s54, 0, 0x18000
	s_add_i32 s55, 0, 0x1c000
	v_add_u32_e32 v140, s54, v166
	v_add_u32_e32 v171, s55, v166
	ds_read_b128 v[128:131], v140
	ds_read_b128 v[132:135], v140 offset:1024
	ds_read_b128 v[136:139], v140 offset:2048
	ds_read_b128 v[140:143], v140 offset:3072
	ds_read_b128 v[162:165], v171
	ds_read_b128 v[172:175], v171 offset:1024
	ds_read_b128 v[176:179], v171 offset:2048
	ds_read_b128 v[180:183], v171 offset:3072
	s_add_u32 s22, s26, 0x280000
	s_addc_u32 s23, s27, 0
	s_mov_b32 m0, s39
	v_lshl_add_u64 v[224:225], s[22:23], 0, v[150:151]
	ds_read_b128 v[184:187], v170 offset:32768
	ds_read_b128 v[188:191], v170 offset:33792
	ds_read_b128 v[192:195], v170 offset:34816
	ds_read_b128 v[196:199], v170 offset:35840
	ds_read_b128 v[200:203], v170 offset:36864
	ds_read_b128 v[204:207], v170 offset:37888
	ds_read_b128 v[208:211], v170 offset:38912
	ds_read_b128 v[212:215], v170 offset:39936
	global_load_lds_dwordx4 v[224:225], off
	v_lshl_add_u64 v[224:225], s[22:23], 0, v[146:147]
	s_mov_b32 m0, s40
	s_nop 0
	global_load_lds_dwordx4 v[224:225], off
	s_waitcnt vmcnt(8)
	s_waitcnt lgkmcnt(0)
	s_barrier
	s_setprio 1
	s_waitcnt lgkmcnt(0)
	v_mfma_f32_16x16x32_bf16 v[124:127], v[128:131], v[184:187], v[124:127]
	v_mfma_f32_16x16x32_bf16 v[120:123], v[136:139], v[184:187], v[120:123]
	v_mfma_f32_16x16x32_bf16 v[116:119], v[128:131], v[192:195], v[116:119]
	v_mfma_f32_16x16x32_bf16 v[112:115], v[136:139], v[192:195], v[112:115]
	v_mfma_f32_16x16x32_bf16 v[92:95], v[128:131], v[200:203], v[92:95]
	v_mfma_f32_16x16x32_bf16 v[88:91], v[136:139], v[200:203], v[88:91]
	v_mfma_f32_16x16x32_bf16 v[84:87], v[128:131], v[208:211], v[84:87]
	v_mfma_f32_16x16x32_bf16 v[76:79], v[136:139], v[208:211], v[76:79]
	v_mfma_f32_16x16x32_bf16 v[124:127], v[132:135], v[188:191], v[124:127]
	v_mfma_f32_16x16x32_bf16 v[120:123], v[140:143], v[188:191], v[120:123]
	v_mfma_f32_16x16x32_bf16 v[116:119], v[132:135], v[196:199], v[116:119]
	v_mfma_f32_16x16x32_bf16 v[112:115], v[140:143], v[196:199], v[112:115]
	v_mfma_f32_16x16x32_bf16 v[92:95], v[132:135], v[204:207], v[92:95]
	v_mfma_f32_16x16x32_bf16 v[88:91], v[140:143], v[204:207], v[88:91]
	v_mfma_f32_16x16x32_bf16 v[84:87], v[132:135], v[212:215], v[84:87]
	v_mfma_f32_16x16x32_bf16 v[76:79], v[140:143], v[212:215], v[76:79]
	v_mfma_f32_16x16x32_bf16 v[108:111], v[162:165], v[184:187], v[108:111]
	v_mfma_f32_16x16x32_bf16 v[104:107], v[176:179], v[184:187], v[104:107]
	v_mfma_f32_16x16x32_bf16 v[100:103], v[162:165], v[192:195], v[100:103]
	v_mfma_f32_16x16x32_bf16 v[96:99], v[176:179], v[192:195], v[96:99]
	v_mfma_f32_16x16x32_bf16 v[80:83], v[162:165], v[200:203], v[80:83]
	v_mfma_f32_16x16x32_bf16 v[72:75], v[176:179], v[200:203], v[72:75]
	v_mfma_f32_16x16x32_bf16 v[68:71], v[162:165], v[208:211], v[68:71]
	v_mfma_f32_16x16x32_bf16 v[64:67], v[176:179], v[208:211], v[64:67]
	v_mfma_f32_16x16x32_bf16 v[108:111], v[172:175], v[188:191], v[108:111]
	v_mfma_f32_16x16x32_bf16 v[104:107], v[180:183], v[188:191], v[104:107]
	v_mfma_f32_16x16x32_bf16 v[100:103], v[172:175], v[196:199], v[100:103]
	v_mfma_f32_16x16x32_bf16 v[96:99], v[180:183], v[196:199], v[96:99]
	v_mfma_f32_16x16x32_bf16 v[80:83], v[172:175], v[204:207], v[80:83]
	v_mfma_f32_16x16x32_bf16 v[72:75], v[180:183], v[204:207], v[72:75]
	v_mfma_f32_16x16x32_bf16 v[68:71], v[172:175], v[212:215], v[68:71]
	v_mfma_f32_16x16x32_bf16 v[64:67], v[180:183], v[212:215], v[64:67]
	s_setprio 0
	s_barrier
; #define PG8_STAGE(bufoff, gbase, voff) do { _Pragma("unroll") for (int _i = 0; _i < 2; ++_i) \
;         __builtin_amdgcn_global_load_lds((const unsigned*)((const char*)(gbase) + (voff)[_i]), (PG8_LAS unsigned*)(lds + (bufoff) + ldsw + _i * 8192), 16, 0, 0); } while (0)
; #define PG8_LDA(dst, b, h) do { _Pragma("unroll") for (int m = 0; m < 4; ++m) _Pragma("unroll") for (int k = 0; k < 2; ++k) dst[m][k] = *(const PG8_LAS bf16x8*)(lds + PG8_SA(b, h) + aoff + m * 2048 + k * 1024); } while (0)
; #define PG8_WAIT_V(n) asm volatile("s_waitcnt vmcnt(" #n ")" ::: "memory")
; #define PG8_WAIT_L(n) asm volatile("s_waitcnt lgkmcnt(" #n ")" ::: "memory")
; #define PG8_BAR __builtin_amdgcn_s_barrier()
; template <class Epi, class Sched, bool ALIGN_EPI = false, bool SP2 = false>
; __device__ __forceinline__ void gemm_phase(PG8_LAS unsigned char* lds, const Gemm g, const Sched& S, const Epi& E, const int wave_in) {
;     ...
;         for (int t = 0; t < nt; t += 2) {
;             const bool last = (t == nt - 2);
;             const char* a1 = cA + (size_t)(t + 1) * kstep;
;             const char* a2 = last ? nA : cA + (size_t)(t + 2) * kstep; const char* b2 = last ? nB : cB + (size_t)(t + 2) * kstep;
;             const char* a3 = a2 + kstep; const char* b3 = b2 + kstep;
;             if (last && has_next) S.a_ready(nxt);
;             if constexpr (SP2) {
;             PG8_LDB(B0, 0, 0); PG8_LDB(B1, 0, 1); PG8_SCHED; PG8_LDA(At, 0, 0); PG8_STAGE(PG8_SA(1, 1), a1 + hstepA, voffA);
;             PG8_WAIT_V(8); PG8_WAIT_L(0); PG8_BAR; PG8_MMA(0, 0, At, B0); PG8_MMA(0, 1, At, B1); PG8_BAR; PG8_SCHED;
;             PG8_LDA(At, 0, 1); PG8_STAGE(PG8_SB(0, 0), b2, voffB); PG8_STAGE(PG8_SB(0, 1), b2 + hstepB, voffB); PG8_STAGE(PG8_SA(0, 0), a2, voffA);
;             PG8_WAIT_V(8); PG8_WAIT_L(0); PG8_BAR; PG8_MMA(1, 0, At, B0); PG8_MMA(1, 1, At, B1); PG8_BAR; PG8_SCHED;
;             PG8_LDB(B0, 1, 0); PG8_LDB(B1, 1, 1); PG8_SCHED; PG8_LDA(At, 1, 0); PG8_STAGE(PG8_SA(0, 1), a2 + hstepA, voffA);
;             PG8_WAIT_V(8); PG8_WAIT_L(0); PG8_BAR; PG8_MMA(0, 0, At, B0); PG8_MMA(0, 1, At, B1); PG8_BAR; PG8_SCHED;
;             PG8_LDA(At, 1, 1); PG8_STAGE(PG8_SB(1, 0), b3, voffB); PG8_STAGE(PG8_SB(1, 1), b3 + hstepB, voffB); PG8_STAGE(PG8_SA(1, 0), a3, voffA);
;             PG8_WAIT_V(8); PG8_WAIT_L(0); PG8_BAR; PG8_MMA(1, 0, At, B0); PG8_MMA(1, 1, At, B1); PG8_BAR; PG8_SCHED;
	s_add_i32 s22, s54, s34
	v_lshl_add_u64 v[216:217], v[216:217], 0, s[10:11]
	s_mov_b32 m0, s22
	ds_read_b128 v[184:187], v170 offset:49152
	ds_read_b128 v[188:191], v170 offset:50176
	ds_read_b128 v[192:195], v170 offset:51200
	ds_read_b128 v[196:199], v170 offset:52224
	ds_read_b128 v[200:203], v170 offset:53248
	ds_read_b128 v[204:207], v170 offset:54272
	ds_read_b128 v[208:211], v170 offset:55296
	ds_read_b128 v[212:215], v170 offset:56320
	global_load_lds_dwordx4 v[216:217], off
	s_add_i32 m0, s22, 0x2000
	s_add_u32 s22, s24, 0x80080
	v_lshl_add_u64 v[216:217], v[218:219], 0, s[10:11]
	s_addc_u32 s23, s25, 0
	s_add_i32 s24, s55, s34
	global_load_lds_dwordx4 v[216:217], off
	v_lshl_add_u64 v[216:217], s[22:23], 0, v[148:149]
	s_mov_b32 m0, s24
	s_nop 0
	global_load_lds_dwordx4 v[216:217], off
	v_lshl_add_u64 v[216:217], s[22:23], 0, v[144:145]
	s_add_i32 m0, s24, 0x2000
	s_nop 0
	global_load_lds_dwordx4 v[216:217], off
	v_lshl_add_u64 v[216:217], v[220:221], 0, s[10:11]
	s_mov_b32 m0, s44
	s_nop 0
	global_load_lds_dwordx4 v[216:217], off
	v_lshl_add_u64 v[216:217], v[222:223], 0, s[10:11]
	s_mov_b32 m0, s45
	s_nop 0
	global_load_lds_dwordx4 v[216:217], off
	s_waitcnt vmcnt(8)
	s_waitcnt lgkmcnt(0)
	s_barrier
	s_setprio 1
	s_waitcnt lgkmcnt(0)
	v_mfma_f32_16x16x32_bf16 v[60:63], v[128:131], v[184:187], v[60:63]
	v_mfma_f32_16x16x32_bf16 v[56:59], v[136:139], v[184:187], v[56:59]
	v_mfma_f32_16x16x32_bf16 v[52:55], v[128:131], v[192:195], v[52:55]
	v_mfma_f32_16x16x32_bf16 v[44:47], v[136:139], v[192:195], v[44:47]
	v_mfma_f32_16x16x32_bf16 v[36:39], v[128:131], v[200:203], v[36:39]
	v_mfma_f32_16x16x32_bf16 v[28:31], v[136:139], v[200:203], v[28:31]
	v_mfma_f32_16x16x32_bf16 v[20:23], v[128:131], v[208:211], v[20:23]
	v_mfma_f32_16x16x32_bf16 v[12:15], v[136:139], v[208:211], v[12:15]
	v_mfma_f32_16x16x32_bf16 v[60:63], v[132:135], v[188:191], v[60:63]
	v_mfma_f32_16x16x32_bf16 v[56:59], v[140:143], v[188:191], v[56:59]
	v_mfma_f32_16x16x32_bf16 v[52:55], v[132:135], v[196:199], v[52:55]
	v_mfma_f32_16x16x32_bf16 v[44:47], v[140:143], v[196:199], v[44:47]
	v_mfma_f32_16x16x32_bf16 v[36:39], v[132:135], v[204:207], v[36:39]
	v_mfma_f32_16x16x32_bf16 v[28:31], v[140:143], v[204:207], v[28:31]
	v_mfma_f32_16x16x32_bf16 v[20:23], v[132:135], v[212:215], v[20:23]
	v_mfma_f32_16x16x32_bf16 v[12:15], v[140:143], v[212:215], v[12:15]
	v_mfma_f32_16x16x32_bf16 v[48:51], v[162:165], v[184:187], v[48:51]
	v_mfma_f32_16x16x32_bf16 v[40:43], v[176:179], v[184:187], v[40:43]
	v_mfma_f32_16x16x32_bf16 v[32:35], v[162:165], v[192:195], v[32:35]
	v_mfma_f32_16x16x32_bf16 v[24:27], v[176:179], v[192:195], v[24:27]
	v_mfma_f32_16x16x32_bf16 v[16:19], v[162:165], v[200:203], v[16:19]
	v_mfma_f32_16x16x32_bf16 v[8:11], v[176:179], v[200:203], v[8:11]
	v_mfma_f32_16x16x32_bf16 v[4:7], v[162:165], v[208:211], v[4:7]
	v_mfma_f32_16x16x32_bf16 v[0:3], v[176:179], v[208:211], v[0:3]
	v_mfma_f32_16x16x32_bf16 v[48:51], v[172:175], v[188:191], v[48:51]
	v_mfma_f32_16x16x32_bf16 v[40:43], v[180:183], v[188:191], v[40:43]
	v_mfma_f32_16x16x32_bf16 v[32:35], v[172:175], v[196:199], v[32:35]
	v_mfma_f32_16x16x32_bf16 v[24:27], v[180:183], v[196:199], v[24:27]
	v_mfma_f32_16x16x32_bf16 v[16:19], v[172:175], v[204:207], v[16:19]
	v_mfma_f32_16x16x32_bf16 v[8:11], v[180:183], v[204:207], v[8:11]
	v_mfma_f32_16x16x32_bf16 v[4:7], v[172:175], v[212:215], v[4:7]
	v_mfma_f32_16x16x32_bf16 v[0:3], v[180:183], v[212:215], v[0:3]
	s_setprio 0
	s_barrier
	s_add_i32 s53, s53, 2
	s_add_u32 s51, s51, 0x100
	s_addc_u32 s52, s52, 0
	s_cmp_gt_u32 s53, 29
	s_mov_b64 s[22:23], s[4:5]
	s_cbranch_scc0 .LBB0_353
	s_branch .Lkx_4
.LBB0_353:
	ds_read_b128 v[128:131], v168
	ds_read_b128 v[132:135], v168 offset:1024
	ds_read_b128 v[136:139], v168 offset:2048
	ds_read_b128 v[140:143], v168 offset:3072
	ds_read_b128 v[162:165], v169
	ds_read_b128 v[172:175], v169 offset:1024
	ds_read_b128 v[176:179], v169 offset:2048
	ds_read_b128 v[180:183], v169 offset:3072
	s_add_u32 s4, s22, 0x100
	s_addc_u32 s5, s23, 0
	s_cmp_eq_u32 s53, 28
	s_cselect_b32 s27, s17, s5
	s_cselect_b32 s26, s16, s4
	s_cselect_b32 s25, s15, s52
	s_cselect_b32 s24, s21, s51
	v_lshl_add_u64 v[216:217], s[22:23], 0, v[154:155]
	s_add_i32 m0, s37, 0xc000
	ds_read_b128 v[184:187], v170
	ds_read_b128 v[188:191], v170 offset:1024
	ds_read_b128 v[192:195], v170 offset:2048
	ds_read_b128 v[196:199], v170 offset:3072
	ds_read_b128 v[200:203], v170 offset:4096
	ds_read_b128 v[204:207], v170 offset:5120
	ds_read_b128 v[208:211], v170 offset:6144
	ds_read_b128 v[212:215], v170 offset:7168
	global_load_lds_dwordx4 v[216:217], off
	v_lshl_add_u64 v[216:217], s[22:23], 0, v[156:157]
	s_add_i32 m0, s37, 0xe000
	s_nop 0
	global_load_lds_dwordx4 v[216:217], off
	s_waitcnt vmcnt(8)
	s_waitcnt lgkmcnt(0)
	s_barrier
; #define PG8_STAGE(bufoff, gbase, voff) do { _Pragma("unroll") for (int _i = 0; _i < 2; ++_i) \
;         __builtin_amdgcn_global_load_lds((const unsigned*)((const char*)(gbase) + (voff)[_i]), (PG8_LAS unsigned*)(lds + (bufoff) + ldsw + _i * 8192), 16, 0, 0); } while (0)
; #define PG8_LDA(dst, b, h) do { _Pragma("unroll") for (int m = 0; m < 4; ++m) _Pragma("unroll") for (int k = 0; k < 2; ++k) dst[m][k] = *(const PG8_LAS bf16x8*)(lds + PG8_SA(b, h) + aoff + m * 2048 + k * 1024); } while (0)
; #define PG8_MMA(ai, bj, At, Bt) do { __builtin_amdgcn_s_setprio(1); _Pragma("unroll") for (int m = 0; m < 4; ++m) _Pragma("unroll") for (int n = 0; n < 2; ++n) _Pragma("unroll") for (int k = 0; k < 2; ++k) \
;         acc[ai][bj][m][n] = __builtin_amdgcn_mfma_f32_16x16x32_bf16(Bt[n][k], At[m][k], acc[ai][bj][m][n], 0, 0, 0); __builtin_amdgcn_s_setprio(0); } while (0)
; #define PG8_WAIT_V(n) asm volatile("s_waitcnt vmcnt(" #n ")" ::: "memory")
; #define PG8_WAIT_L(n) asm volatile("s_waitcnt lgkmcnt(" #n ")" ::: "memory")
; #define PG8_BAR __builtin_amdgcn_s_barrier()
; #define PG8_SCHED __builtin_amdgcn_sched_barrier(0)
; template <class Epi, class Sched, bool ALIGN_EPI = false, bool SP2 = false>
; __device__ __forceinline__ void gemm_phase(PG8_LAS unsigned char* lds, const Gemm g, const Sched& S, const Epi& E, const int wave_in) {
;     ...
;             PG8_WAIT_V(8); PG8_WAIT_L(0); PG8_BAR; PG8_MMA(0, 0, At, B0); PG8_MMA(0, 1, At, B1); PG8_BAR; PG8_SCHED;
;             PG8_LDA(At, 0, 1); PG8_STAGE(PG8_SB(0, 0), b2, voffB); PG8_STAGE(PG8_SB(0, 1), b2 + hstepB, voffB); PG8_STAGE(PG8_SA(0, 0), a2, voffA);
;             PG8_WAIT_V(8); PG8_WAIT_L(0); PG8_BAR; PG8_MMA(1, 0, At, B0); PG8_MMA(1, 1, At, B1); PG8_BAR; PG8_SCHED;
	s_setprio 1
	s_waitcnt lgkmcnt(0)
	v_mfma_f32_16x16x32_bf16 v[124:127], v[128:131], v[184:187], v[124:127]
	v_mfma_f32_16x16x32_bf16 v[120:123], v[136:139], v[184:187], v[120:123]
	v_mfma_f32_16x16x32_bf16 v[116:119], v[128:131], v[192:195], v[116:119]
	v_mfma_f32_16x16x32_bf16 v[112:115], v[136:139], v[192:195], v[112:115]
	v_mfma_f32_16x16x32_bf16 v[92:95], v[128:131], v[200:203], v[92:95]
	v_mfma_f32_16x16x32_bf16 v[88:91], v[136:139], v[200:203], v[88:91]
	v_mfma_f32_16x16x32_bf16 v[84:87], v[128:131], v[208:211], v[84:87]
	v_mfma_f32_16x16x32_bf16 v[76:79], v[136:139], v[208:211], v[76:79]
	v_mfma_f32_16x16x32_bf16 v[124:127], v[132:135], v[188:191], v[124:127]
	v_mfma_f32_16x16x32_bf16 v[120:123], v[140:143], v[188:191], v[120:123]
	v_mfma_f32_16x16x32_bf16 v[116:119], v[132:135], v[196:199], v[116:119]
	v_mfma_f32_16x16x32_bf16 v[112:115], v[140:143], v[196:199], v[112:115]
	v_mfma_f32_16x16x32_bf16 v[92:95], v[132:135], v[204:207], v[92:95]
	v_mfma_f32_16x16x32_bf16 v[88:91], v[140:143], v[204:207], v[88:91]
	v_mfma_f32_16x16x32_bf16 v[84:87], v[132:135], v[212:215], v[84:87]
	v_mfma_f32_16x16x32_bf16 v[76:79], v[140:143], v[212:215], v[76:79]
	v_mfma_f32_16x16x32_bf16 v[108:111], v[162:165], v[184:187], v[108:111]
	v_mfma_f32_16x16x32_bf16 v[104:107], v[176:179], v[184:187], v[104:107]
	v_mfma_f32_16x16x32_bf16 v[100:103], v[162:165], v[192:195], v[100:103]
	v_mfma_f32_16x16x32_bf16 v[96:99], v[176:179], v[192:195], v[96:99]
	v_mfma_f32_16x16x32_bf16 v[80:83], v[162:165], v[200:203], v[80:83]
	v_mfma_f32_16x16x32_bf16 v[72:75], v[176:179], v[200:203], v[72:75]
	v_mfma_f32_16x16x32_bf16 v[68:71], v[162:165], v[208:211], v[68:71]
	v_mfma_f32_16x16x32_bf16 v[64:67], v[176:179], v[208:211], v[64:67]
	v_mfma_f32_16x16x32_bf16 v[108:111], v[172:175], v[188:191], v[108:111]
	v_mfma_f32_16x16x32_bf16 v[104:107], v[180:183], v[188:191], v[104:107]
	v_mfma_f32_16x16x32_bf16 v[100:103], v[172:175], v[196:199], v[100:103]
	v_mfma_f32_16x16x32_bf16 v[96:99], v[180:183], v[196:199], v[96:99]
	v_mfma_f32_16x16x32_bf16 v[80:83], v[172:175], v[204:207], v[80:83]
	v_mfma_f32_16x16x32_bf16 v[72:75], v[180:183], v[204:207], v[72:75]
	v_mfma_f32_16x16x32_bf16 v[68:71], v[172:175], v[212:215], v[68:71]
	v_mfma_f32_16x16x32_bf16 v[64:67], v[180:183], v[212:215], v[64:67]
	s_setprio 0
	s_barrier
	s_add_i32 s22, s47, s34
	v_lshl_add_u64 v[216:217], s[24:25], 0, v[148:149]
	s_mov_b32 m0, s22
	ds_read_b128 v[184:187], v170 offset:16384
	ds_read_b128 v[188:191], v170 offset:17408
	ds_read_b128 v[192:195], v170 offset:18432
	ds_read_b128 v[196:199], v170 offset:19456
	ds_read_b128 v[200:203], v170 offset:20480
	ds_read_b128 v[204:207], v170 offset:21504
	ds_read_b128 v[208:211], v170 offset:22528
	ds_read_b128 v[212:215], v170 offset:23552
	global_load_lds_dwordx4 v[216:217], off
	s_add_i32 m0, s22, 0x2000
	s_add_u32 s22, s24, 0x80000
	v_lshl_add_u64 v[218:219], s[24:25], 0, v[144:145]
	s_addc_u32 s23, s25, 0
	s_add_i32 s54, s48, s34
	global_load_lds_dwordx4 v[218:219], off
	v_lshl_add_u64 v[220:221], s[22:23], 0, v[148:149]
	s_mov_b32 m0, s54
	v_lshl_add_u64 v[222:223], s[26:27], 0, v[146:147]
	global_load_lds_dwordx4 v[220:221], off
	v_lshl_add_u64 v[220:221], s[22:23], 0, v[144:145]
	s_add_i32 m0, s54, 0x2000
	s_nop 0
	global_load_lds_dwordx4 v[220:221], off
	v_lshl_add_u64 v[220:221], s[26:27], 0, v[150:151]
	s_mov_b32 m0, s37
	s_nop 0
	global_load_lds_dwordx4 v[220:221], off
	s_mov_b32 m0, s38
	s_nop 0
	global_load_lds_dwordx4 v[222:223], off
	s_waitcnt vmcnt(8)
	s_waitcnt lgkmcnt(0)
	s_barrier
	s_setprio 1
	s_waitcnt lgkmcnt(0)
	v_mfma_f32_16x16x32_bf16 v[60:63], v[128:131], v[184:187], v[60:63]
	v_mfma_f32_16x16x32_bf16 v[56:59], v[136:139], v[184:187], v[56:59]
	v_mfma_f32_16x16x32_bf16 v[52:55], v[128:131], v[192:195], v[52:55]
	v_mfma_f32_16x16x32_bf16 v[44:47], v[136:139], v[192:195], v[44:47]
	v_mfma_f32_16x16x32_bf16 v[36:39], v[128:131], v[200:203], v[36:39]
	v_mfma_f32_16x16x32_bf16 v[28:31], v[136:139], v[200:203], v[28:31]
	v_mfma_f32_16x16x32_bf16 v[20:23], v[128:131], v[208:211], v[20:23]
	v_mfma_f32_16x16x32_bf16 v[12:15], v[136:139], v[208:211], v[12:15]
	v_mfma_f32_16x16x32_bf16 v[60:63], v[132:135], v[188:191], v[60:63]
	v_mfma_f32_16x16x32_bf16 v[56:59], v[140:143], v[188:191], v[56:59]
	v_mfma_f32_16x16x32_bf16 v[52:55], v[132:135], v[196:199], v[52:55]
	v_mfma_f32_16x16x32_bf16 v[44:47], v[140:143], v[196:199], v[44:47]
	v_mfma_f32_16x16x32_bf16 v[36:39], v[132:135], v[204:207], v[36:39]
	v_mfma_f32_16x16x32_bf16 v[28:31], v[140:143], v[204:207], v[28:31]
	v_mfma_f32_16x16x32_bf16 v[20:23], v[132:135], v[212:215], v[20:23]
	v_mfma_f32_16x16x32_bf16 v[12:15], v[140:143], v[212:215], v[12:15]
	v_mfma_f32_16x16x32_bf16 v[48:51], v[162:165], v[184:187], v[48:51]
	v_mfma_f32_16x16x32_bf16 v[40:43], v[176:179], v[184:187], v[40:43]
	v_mfma_f32_16x16x32_bf16 v[32:35], v[162:165], v[192:195], v[32:35]
	v_mfma_f32_16x16x32_bf16 v[24:27], v[176:179], v[192:195], v[24:27]
	v_mfma_f32_16x16x32_bf16 v[16:19], v[162:165], v[200:203], v[16:19]
	v_mfma_f32_16x16x32_bf16 v[8:11], v[176:179], v[200:203], v[8:11]
	v_mfma_f32_16x16x32_bf16 v[4:7], v[162:165], v[208:211], v[4:7]
	v_mfma_f32_16x16x32_bf16 v[0:3], v[176:179], v[208:211], v[0:3]
	v_mfma_f32_16x16x32_bf16 v[48:51], v[172:175], v[188:191], v[48:51]
	v_mfma_f32_16x16x32_bf16 v[40:43], v[180:183], v[188:191], v[40:43]
	v_mfma_f32_16x16x32_bf16 v[32:35], v[172:175], v[196:199], v[32:35]
	v_mfma_f32_16x16x32_bf16 v[24:27], v[180:183], v[196:199], v[24:27]
	v_mfma_f32_16x16x32_bf16 v[16:19], v[172:175], v[204:207], v[16:19]
	v_mfma_f32_16x16x32_bf16 v[8:11], v[180:183], v[204:207], v[8:11]
	v_mfma_f32_16x16x32_bf16 v[4:7], v[172:175], v[212:215], v[4:7]
	v_mfma_f32_16x16x32_bf16 v[0:3], v[180:183], v[212:215], v[0:3]
	s_setprio 0
	s_barrier
; #define PG8_STAGE(bufoff, gbase, voff) do { _Pragma("unroll") for (int _i = 0; _i < 2; ++_i) \
;         __builtin_amdgcn_global_load_lds((const unsigned*)((const char*)(gbase) + (voff)[_i]), (PG8_LAS unsigned*)(lds + (bufoff) + ldsw + _i * 8192), 16, 0, 0); } while (0)
; #define PG8_LDA(dst, b, h) do { _Pragma("unroll") for (int m = 0; m < 4; ++m) _Pragma("unroll") for (int k = 0; k < 2; ++k) dst[m][k] = *(const PG8_LAS bf16x8*)(lds + PG8_SA(b, h) + aoff + m * 2048 + k * 1024); } while (0)
; #define PG8_LDB(dst, b, h) do { _Pragma("unroll") for (int n = 0; n < 2; ++n) _Pragma("unroll") for (int k = 0; k < 2; ++k) dst[n][k] = *(const PG8_LAS bf16x8*)(lds + PG8_SB(b, h) + boff + n * 2048 + k * 1024); } while (0)
; #define PG8_MMA(ai, bj, At, Bt) do { __builtin_amdgcn_s_setprio(1); _Pragma("unroll") for (int m = 0; m < 4; ++m) _Pragma("unroll") for (int n = 0; n < 2; ++n) _Pragma("unroll") for (int k = 0; k < 2; ++k) \
;         acc[ai][bj][m][n] = __builtin_amdgcn_mfma_f32_16x16x32_bf16(Bt[n][k], At[m][k], acc[ai][bj][m][n], 0, 0, 0); __builtin_amdgcn_s_setprio(0); } while (0)
; #define PG8_WAIT_V(n) asm volatile("s_waitcnt vmcnt(" #n ")" ::: "memory")
; #define PG8_WAIT_L(n) asm volatile("s_waitcnt lgkmcnt(" #n ")" ::: "memory")
; #define PG8_BAR __builtin_amdgcn_s_barrier()
; #define PG8_SCHED __builtin_amdgcn_sched_barrier(0)
; template <class Epi, class Sched, bool ALIGN_EPI = false, bool SP2 = false>
; __device__ __forceinline__ void gemm_phase(PG8_LAS unsigned char* lds, const Gemm g, const Sched& S, const Epi& E, const int wave_in) {
;     ...
;             PG8_LDB(B0, 1, 0); PG8_LDB(B1, 1, 1); PG8_SCHED; PG8_LDA(At, 1, 0); PG8_STAGE(PG8_SA(0, 1), a2 + hstepA, voffA);
;             PG8_WAIT_V(8); PG8_WAIT_L(0); PG8_BAR; PG8_MMA(0, 0, At, B0); PG8_MMA(0, 1, At, B1); PG8_BAR; PG8_SCHED;
	s_add_i32 s54, 0, 0x18000
	s_add_i32 s55, 0, 0x1c000
	v_add_u32_e32 v140, s54, v166
	v_add_u32_e32 v171, s55, v166
	ds_read_b128 v[128:131], v140
	ds_read_b128 v[132:135], v140 offset:1024
	ds_read_b128 v[136:139], v140 offset:2048
	ds_read_b128 v[140:143], v140 offset:3072
	ds_read_b128 v[162:165], v171
	ds_read_b128 v[172:175], v171 offset:1024
	ds_read_b128 v[176:179], v171 offset:2048
	ds_read_b128 v[180:183], v171 offset:3072
	s_add_u32 s22, s26, 0x280000
	s_addc_u32 s23, s27, 0
	s_mov_b32 m0, s39
	v_lshl_add_u64 v[224:225], s[22:23], 0, v[150:151]
	ds_read_b128 v[184:187], v170 offset:32768
	ds_read_b128 v[188:191], v170 offset:33792
	ds_read_b128 v[192:195], v170 offset:34816
	ds_read_b128 v[196:199], v170 offset:35840
	ds_read_b128 v[200:203], v170 offset:36864
	ds_read_b128 v[204:207], v170 offset:37888
	ds_read_b128 v[208:211], v170 offset:38912
	ds_read_b128 v[212:215], v170 offset:39936
	global_load_lds_dwordx4 v[224:225], off
	v_lshl_add_u64 v[224:225], s[22:23], 0, v[146:147]
	s_mov_b32 m0, s40
	s_nop 0
	global_load_lds_dwordx4 v[224:225], off
	s_waitcnt vmcnt(8)
	s_waitcnt lgkmcnt(0)
	s_barrier
	s_setprio 1
	s_waitcnt lgkmcnt(0)
	v_mfma_f32_16x16x32_bf16 v[124:127], v[128:131], v[184:187], v[124:127]
	v_mfma_f32_16x16x32_bf16 v[120:123], v[136:139], v[184:187], v[120:123]
	v_mfma_f32_16x16x32_bf16 v[116:119], v[128:131], v[192:195], v[116:119]
	v_mfma_f32_16x16x32_bf16 v[112:115], v[136:139], v[192:195], v[112:115]
	v_mfma_f32_16x16x32_bf16 v[92:95], v[128:131], v[200:203], v[92:95]
	v_mfma_f32_16x16x32_bf16 v[88:91], v[136:139], v[200:203], v[88:91]
	v_mfma_f32_16x16x32_bf16 v[84:87], v[128:131], v[208:211], v[84:87]
	v_mfma_f32_16x16x32_bf16 v[76:79], v[136:139], v[208:211], v[76:79]
	v_mfma_f32_16x16x32_bf16 v[124:127], v[132:135], v[188:191], v[124:127]
	v_mfma_f32_16x16x32_bf16 v[120:123], v[140:143], v[188:191], v[120:123]
	v_mfma_f32_16x16x32_bf16 v[116:119], v[132:135], v[196:199], v[116:119]
	v_mfma_f32_16x16x32_bf16 v[112:115], v[140:143], v[196:199], v[112:115]
	v_mfma_f32_16x16x32_bf16 v[92:95], v[132:135], v[204:207], v[92:95]
	v_mfma_f32_16x16x32_bf16 v[88:91], v[140:143], v[204:207], v[88:91]
	v_mfma_f32_16x16x32_bf16 v[84:87], v[132:135], v[212:215], v[84:87]
	v_mfma_f32_16x16x32_bf16 v[76:79], v[140:143], v[212:215], v[76:79]
	v_mfma_f32_16x16x32_bf16 v[108:111], v[162:165], v[184:187], v[108:111]
	v_mfma_f32_16x16x32_bf16 v[104:107], v[176:179], v[184:187], v[104:107]
	v_mfma_f32_16x16x32_bf16 v[100:103], v[162:165], v[192:195], v[100:103]
	v_mfma_f32_16x16x32_bf16 v[96:99], v[176:179], v[192:195], v[96:99]
	v_mfma_f32_16x16x32_bf16 v[80:83], v[162:165], v[200:203], v[80:83]
	v_mfma_f32_16x16x32_bf16 v[72:75], v[176:179], v[200:203], v[72:75]
	v_mfma_f32_16x16x32_bf16 v[68:71], v[162:165], v[208:211], v[68:71]
	v_mfma_f32_16x16x32_bf16 v[64:67], v[176:179], v[208:211], v[64:67]
	v_mfma_f32_16x16x32_bf16 v[108:111], v[172:175], v[188:191], v[108:111]
	v_mfma_f32_16x16x32_bf16 v[104:107], v[180:183], v[188:191], v[104:107]
	v_mfma_f32_16x16x32_bf16 v[100:103], v[172:175], v[196:199], v[100:103]
	v_mfma_f32_16x16x32_bf16 v[96:99], v[180:183], v[196:199], v[96:99]
	v_mfma_f32_16x16x32_bf16 v[80:83], v[172:175], v[204:207], v[80:83]
	v_mfma_f32_16x16x32_bf16 v[72:75], v[180:183], v[204:207], v[72:75]
	v_mfma_f32_16x16x32_bf16 v[68:71], v[172:175], v[212:215], v[68:71]
	v_mfma_f32_16x16x32_bf16 v[64:67], v[180:183], v[212:215], v[64:67]
	s_setprio 0
	s_barrier
; #define PG8_STAGE(bufoff, gbase, voff) do { _Pragma("unroll") for (int _i = 0; _i < 2; ++_i) \
;         __builtin_amdgcn_global_load_lds((const unsigned*)((const char*)(gbase) + (voff)[_i]), (PG8_LAS unsigned*)(lds + (bufoff) + ldsw + _i * 8192), 16, 0, 0); } while (0)
; #define PG8_LDA(dst, b, h) do { _Pragma("unroll") for (int m = 0; m < 4; ++m) _Pragma("unroll") for (int k = 0; k < 2; ++k) dst[m][k] = *(const PG8_LAS bf16x8*)(lds + PG8_SA(b, h) + aoff + m * 2048 + k * 1024); } while (0)
; #define PG8_MMA(ai, bj, At, Bt) do { __builtin_amdgcn_s_setprio(1); _Pragma("unroll") for (int m = 0; m < 4; ++m) _Pragma("unroll") for (int n = 0; n < 2; ++n) _Pragma("unroll") for (int k = 0; k < 2; ++k) \
;         acc[ai][bj][m][n] = __builtin_amdgcn_mfma_f32_16x16x32_bf16(Bt[n][k], At[m][k], acc[ai][bj][m][n], 0, 0, 0); __builtin_amdgcn_s_setprio(0); } while (0)
; #define PG8_WAIT_V(n) asm volatile("s_waitcnt vmcnt(" #n ")" ::: "memory")
; #define PG8_WAIT_L(n) asm volatile("s_waitcnt lgkmcnt(" #n ")" ::: "memory")
; #define PG8_BAR __builtin_amdgcn_s_barrier()
; #define PG8_SCHED __builtin_amdgcn_sched_barrier(0)
; template <class Epi, class Sched, bool ALIGN_EPI = false, bool SP2 = false>
; __device__ __forceinline__ void gemm_phase(PG8_LAS unsigned char* lds, const Gemm g, const Sched& S, const Epi& E, const int wave_in) {
;     ...
;         for (int t = 0; t < nt; t += 2) {
;     ...
;             PG8_LDA(At, 1, 1); PG8_STAGE(PG8_SB(1, 0), b3, voffB); PG8_STAGE(PG8_SB(1, 1), b3 + hstepB, voffB); PG8_STAGE(PG8_SA(1, 0), a3, voffA);
;             PG8_WAIT_V(8); PG8_WAIT_L(0); PG8_BAR; PG8_MMA(1, 0, At, B0); PG8_MMA(1, 1, At, B1); PG8_BAR; PG8_SCHED;
	s_add_i32 s22, s54, s34
	v_lshl_add_u64 v[216:217], v[216:217], 0, s[10:11]
	s_mov_b32 m0, s22
	ds_read_b128 v[184:187], v170 offset:49152
	ds_read_b128 v[188:191], v170 offset:50176
	ds_read_b128 v[192:195], v170 offset:51200
	ds_read_b128 v[196:199], v170 offset:52224
	ds_read_b128 v[200:203], v170 offset:53248
	ds_read_b128 v[204:207], v170 offset:54272
	ds_read_b128 v[208:211], v170 offset:55296
	ds_read_b128 v[212:215], v170 offset:56320
	global_load_lds_dwordx4 v[216:217], off
	s_add_i32 m0, s22, 0x2000
	s_add_u32 s22, s24, 0x80080
	v_lshl_add_u64 v[216:217], v[218:219], 0, s[10:11]
	s_addc_u32 s23, s25, 0
	s_add_i32 s24, s55, s34
	global_load_lds_dwordx4 v[216:217], off
	v_lshl_add_u64 v[216:217], s[22:23], 0, v[148:149]
	s_mov_b32 m0, s24
	s_nop 0
	global_load_lds_dwordx4 v[216:217], off
	v_lshl_add_u64 v[216:217], s[22:23], 0, v[144:145]
	s_add_i32 m0, s24, 0x2000
	s_nop 0
	global_load_lds_dwordx4 v[216:217], off
	v_lshl_add_u64 v[216:217], v[220:221], 0, s[10:11]
	s_mov_b32 m0, s44
	s_nop 0
	global_load_lds_dwordx4 v[216:217], off
	v_lshl_add_u64 v[216:217], v[222:223], 0, s[10:11]
	s_mov_b32 m0, s45
	s_nop 0
	global_load_lds_dwordx4 v[216:217], off
	s_waitcnt vmcnt(8)
	s_waitcnt lgkmcnt(0)
	s_barrier
	s_setprio 1
	s_waitcnt lgkmcnt(0)
	v_mfma_f32_16x16x32_bf16 v[60:63], v[128:131], v[184:187], v[60:63]
	v_mfma_f32_16x16x32_bf16 v[56:59], v[136:139], v[184:187], v[56:59]
	v_mfma_f32_16x16x32_bf16 v[52:55], v[128:131], v[192:195], v[52:55]
	v_mfma_f32_16x16x32_bf16 v[44:47], v[136:139], v[192:195], v[44:47]
	v_mfma_f32_16x16x32_bf16 v[36:39], v[128:131], v[200:203], v[36:39]
	v_mfma_f32_16x16x32_bf16 v[28:31], v[136:139], v[200:203], v[28:31]
	v_mfma_f32_16x16x32_bf16 v[20:23], v[128:131], v[208:211], v[20:23]
	v_mfma_f32_16x16x32_bf16 v[12:15], v[136:139], v[208:211], v[12:15]
	v_mfma_f32_16x16x32_bf16 v[60:63], v[132:135], v[188:191], v[60:63]
	v_mfma_f32_16x16x32_bf16 v[56:59], v[140:143], v[188:191], v[56:59]
	v_mfma_f32_16x16x32_bf16 v[52:55], v[132:135], v[196:199], v[52:55]
	v_mfma_f32_16x16x32_bf16 v[44:47], v[140:143], v[196:199], v[44:47]
	v_mfma_f32_16x16x32_bf16 v[36:39], v[132:135], v[204:207], v[36:39]
	v_mfma_f32_16x16x32_bf16 v[28:31], v[140:143], v[204:207], v[28:31]
	v_mfma_f32_16x16x32_bf16 v[20:23], v[132:135], v[212:215], v[20:23]
	v_mfma_f32_16x16x32_bf16 v[12:15], v[140:143], v[212:215], v[12:15]
	v_mfma_f32_16x16x32_bf16 v[48:51], v[162:165], v[184:187], v[48:51]
	v_mfma_f32_16x16x32_bf16 v[40:43], v[176:179], v[184:187], v[40:43]
	v_mfma_f32_16x16x32_bf16 v[32:35], v[162:165], v[192:195], v[32:35]
	v_mfma_f32_16x16x32_bf16 v[24:27], v[176:179], v[192:195], v[24:27]
	v_mfma_f32_16x16x32_bf16 v[16:19], v[162:165], v[200:203], v[16:19]
	v_mfma_f32_16x16x32_bf16 v[8:11], v[176:179], v[200:203], v[8:11]
	v_mfma_f32_16x16x32_bf16 v[4:7], v[162:165], v[208:211], v[4:7]
	v_mfma_f32_16x16x32_bf16 v[0:3], v[176:179], v[208:211], v[0:3]
	v_mfma_f32_16x16x32_bf16 v[48:51], v[172:175], v[188:191], v[48:51]
	v_mfma_f32_16x16x32_bf16 v[40:43], v[180:183], v[188:191], v[40:43]
	v_mfma_f32_16x16x32_bf16 v[32:35], v[172:175], v[196:199], v[32:35]
	v_mfma_f32_16x16x32_bf16 v[24:27], v[180:183], v[196:199], v[24:27]
	v_mfma_f32_16x16x32_bf16 v[16:19], v[172:175], v[204:207], v[16:19]
	v_mfma_f32_16x16x32_bf16 v[8:11], v[180:183], v[204:207], v[8:11]
	v_mfma_f32_16x16x32_bf16 v[4:7], v[172:175], v[212:215], v[4:7]
	v_mfma_f32_16x16x32_bf16 v[0:3], v[180:183], v[212:215], v[0:3]
	s_setprio 0
	s_barrier
	s_add_i32 s53, s53, 2
	s_add_u32 s51, s51, 0x100
	s_addc_u32 s52, s52, 0
	s_cmp_gt_u32 s53, 29
	s_mov_b64 s[22:23], s[4:5]
	s_cbranch_scc0 .LBB0_353

;     __host__ __device__ bool next(int i, Unit& u) const { const bool ok = StaticOrder::next(i, u); u.pm = 0; u.pn = 0; return ok; }
; #define PG8_STAGE(bufoff, gbase, voff) do { _Pragma("unroll") for (int _i = 0; _i < 2; ++_i) \
;         __builtin_amdgcn_global_load_lds((const unsigned*)((const char*)(gbase) + (voff)[_i]), (PG8_LAS unsigned*)(lds + (bufoff) + ldsw + _i * 8192), 16, 0, 0); } while (0)
; #define PG8_LDA(dst, b, h) do { _Pragma("unroll") for (int m = 0; m < 4; ++m) _Pragma("unroll") for (int k = 0; k < 2; ++k) dst[m][k] = *(const PG8_LAS bf16x8*)(lds + PG8_SA(b, h) + aoff + m * 2048 + k * 1024); } while (0)
; #define PG8_LDB(dst, b, h) do { _Pragma("unroll") for (int n = 0; n < 2; ++n) _Pragma("unroll") for (int k = 0; k < 2; ++k) dst[n][k] = *(const PG8_LAS bf16x8*)(lds + PG8_SB(b, h) + boff + n * 2048 + k * 1024); } while (0)
; #define PG8_WAIT_V(n) asm volatile("s_waitcnt vmcnt(" #n ")" ::: "memory")
; #define PG8_WAIT_L(n) asm volatile("s_waitcnt lgkmcnt(" #n ")" ::: "memory")
; #define PG8_BAR __builtin_amdgcn_s_barrier()
; #define PG8_SCHED __builtin_amdgcn_sched_barrier(0)
; template <class Epi, class Sched, bool ALIGN_EPI = false, bool SP2 = false>
; __device__ __forceinline__ void gemm_phase(PG8_LAS unsigned char* lds, const Gemm g, const Sched& S, const Epi& E, const int wave_in) {
;     ...
;         const bool has_next = S.next(ui + 1, nxt);
;         const char* nA = has_next ? (const char*)g.A + (size_t)nxt.pm * tstepA : cA; const char* nB = has_next ? (const char*)g.Bt + (size_t)nxt.pn * tstepB : cB;
;         for (int t = 0; t < nt; t += 2) {
;             const bool last = (t == nt - 2);
;             const char* a1 = cA + (size_t)(t + 1) * kstep;
;             const char* a2 = last ? nA : cA + (size_t)(t + 2) * kstep; const char* b2 = last ? nB : cB + (size_t)(t + 2) * kstep;
;             const char* a3 = a2 + kstep; const char* b3 = b2 + kstep;
;             if (last && has_next) S.a_ready(nxt);
;             if constexpr (SP2) {
;             PG8_LDB(B0, 0, 0); PG8_LDB(B1, 0, 1); PG8_SCHED; PG8_LDA(At, 0, 0); PG8_STAGE(PG8_SA(1, 1), a1 + hstepA, voffA);
;             PG8_WAIT_V(8); PG8_WAIT_L(0); PG8_BAR; PG8_MMA(0, 0, At, B0); PG8_MMA(0, 1, At, B1); PG8_BAR; PG8_SCHED;
;             PG8_LDA(At, 0, 1); PG8_STAGE(PG8_SB(0, 0), b2, voffB); PG8_STAGE(PG8_SB(0, 1), b2 + hstepB, voffB); PG8_STAGE(PG8_SA(0, 0), a2, voffA);
.LBB0_478:
	s_ashr_i32 s41, s40, 31
	s_lshl_b64 s[42:43], s[40:41], 20
	s_add_u32 s42, s52, s42
	s_addc_u32 s43, s53, s43
	s_and_b64 s[44:45], s[10:11], exec
	s_cselect_b32 s1, s43, s47
	s_cselect_b32 s13, s42, s46
	s_ashr_i32 s39, s38, 31
	s_lshl_b64 s[44:45], s[38:39], 20
	s_add_u32 s44, s54, s44
	s_addc_u32 s45, s55, s45
	s_and_b64 s[50:51], s[10:11], exec
	s_cselect_b32 s39, s45, s49
	s_cselect_b32 s41, s44, s48
	s_add_u32 s46, s46, 0x80080
	s_addc_u32 s47, s47, 0
	s_add_u32 s72, s48, 0x100
	v_mov_b32_e32 v0, 0
	s_addc_u32 s73, s49, 0
	s_mov_b32 s74, -2
	ds_read_b128 v[44:47], v189
	ds_read_b128 v[48:51], v189 offset:1024
	ds_read_b128 v[52:55], v189 offset:2048
	ds_read_b128 v[56:59], v189 offset:3072
	ds_read_b128 v[60:63], v197
	ds_read_b128 v[64:67], v197 offset:1024
	ds_read_b128 v[80:83], v197 offset:2048
	ds_read_b128 v[84:87], v197 offset:3072
	s_add_u32 s48, s46, 0xfff80080
	s_addc_u32 s49, s47, -1
	s_cmp_eq_u32 s74, 28
	s_cselect_b32 s51, s1, s49
	s_cselect_b32 s50, s13, s48
	s_cselect_b32 s49, s39, s73
	s_cselect_b32 s48, s41, s72
	v_lshl_add_u64 v[224:225], s[46:47], 0, v[206:207]
	s_add_i32 m0, s57, 0xc000
	ds_read_b128 v[88:91], v199
	ds_read_b128 v[92:95], v199 offset:1024
	ds_read_b128 v[96:99], v199 offset:2048
	ds_read_b128 v[100:103], v199 offset:3072
	ds_read_b128 v[176:179], v199 offset:4096
	ds_read_b128 v[212:215], v199 offset:5120
	ds_read_b128 v[216:219], v199 offset:6144
	ds_read_b128 v[220:223], v199 offset:7168
	global_load_lds_dwordx4 v[224:225], off
	v_lshl_add_u64 v[224:225], s[46:47], 0, v[208:209]
	s_add_i32 m0, s57, 0xe000
	s_nop 0
	global_load_lds_dwordx4 v[224:225], off
	s_waitcnt vmcnt(8)
	s_waitcnt lgkmcnt(0)
	s_barrier
	s_setprio 1
	s_waitcnt lgkmcnt(0)
	v_mfma_f32_16x16x32_bf16 v[172:175], v[44:47], v[88:91], 0
	v_mfma_f32_16x16x32_bf16 v[164:167], v[52:55], v[88:91], 0
	v_mfma_f32_16x16x32_bf16 v[156:159], v[44:47], v[96:99], 0
	v_mfma_f32_16x16x32_bf16 v[148:151], v[52:55], v[96:99], 0
	v_mfma_f32_16x16x32_bf16 v[140:143], v[44:47], v[176:179], 0
	v_mfma_f32_16x16x32_bf16 v[132:135], v[52:55], v[176:179], 0
	v_mfma_f32_16x16x32_bf16 v[124:127], v[44:47], v[216:219], 0
	v_mfma_f32_16x16x32_bf16 v[120:123], v[52:55], v[216:219], 0
	v_mfma_f32_16x16x32_bf16 v[172:175], v[48:51], v[92:95], v[172:175]
	v_mfma_f32_16x16x32_bf16 v[164:167], v[56:59], v[92:95], v[164:167]
	v_mfma_f32_16x16x32_bf16 v[156:159], v[48:51], v[100:103], v[156:159]
	v_mfma_f32_16x16x32_bf16 v[148:151], v[56:59], v[100:103], v[148:151]
	v_mfma_f32_16x16x32_bf16 v[140:143], v[48:51], v[212:215], v[140:143]
	v_mfma_f32_16x16x32_bf16 v[132:135], v[56:59], v[212:215], v[132:135]
	v_mfma_f32_16x16x32_bf16 v[124:127], v[48:51], v[220:223], v[124:127]
	v_mfma_f32_16x16x32_bf16 v[120:123], v[56:59], v[220:223], v[120:123]
	v_mfma_f32_16x16x32_bf16 v[168:171], v[60:63], v[88:91], 0
	v_mfma_f32_16x16x32_bf16 v[88:91], v[80:83], v[88:91], 0
	v_mfma_f32_16x16x32_bf16 v[168:171], v[64:67], v[92:95], v[168:171]
	v_mfma_f32_16x16x32_bf16 v[88:91], v[84:87], v[92:95], v[88:91]
	v_mfma_f32_16x16x32_bf16 v[92:95], v[60:63], v[96:99], 0
	v_mfma_f32_16x16x32_bf16 v[96:99], v[80:83], v[96:99], 0
	v_mfma_f32_16x16x32_bf16 v[128:131], v[80:83], v[176:179], 0
	v_mfma_f32_16x16x32_bf16 v[116:119], v[60:63], v[216:219], 0
	v_mfma_f32_16x16x32_bf16 v[112:115], v[80:83], v[216:219], 0
	v_mfma_f32_16x16x32_bf16 v[92:95], v[64:67], v[100:103], v[92:95]
	v_mfma_f32_16x16x32_bf16 v[96:99], v[84:87], v[100:103], v[96:99]
	v_mfma_f32_16x16x32_bf16 v[100:103], v[60:63], v[176:179], 0
	v_mfma_f32_16x16x32_bf16 v[128:131], v[84:87], v[212:215], v[128:131]
	v_mfma_f32_16x16x32_bf16 v[116:119], v[64:67], v[220:223], v[116:119]
	v_mfma_f32_16x16x32_bf16 v[112:115], v[84:87], v[220:223], v[112:115]
	v_mfma_f32_16x16x32_bf16 v[100:103], v[64:67], v[212:215], v[100:103]
	s_setprio 0
	s_barrier
	s_add_i32 s75, s68, s56
	v_lshl_add_u64 v[232:233], s[48:49], 0, v[182:183]
	s_mov_b32 m0, s75
	ds_read_b128 v[136:139], v199 offset:16384
	ds_read_b128 v[144:147], v199 offset:17408
	ds_read_b128 v[152:155], v199 offset:18432
	ds_read_b128 v[160:163], v199 offset:19456
	ds_read_b128 v[176:179], v199 offset:20480
	ds_read_b128 v[212:215], v199 offset:21504
	ds_read_b128 v[216:219], v199 offset:22528
	ds_read_b128 v[220:223], v199 offset:23552
	global_load_lds_dwordx4 v[232:233], off
	s_add_i32 m0, s75, 0x2000
	s_add_u32 s76, s48, 0x80000
	v_lshl_add_u64 v[234:235], s[48:49], 0, v[186:187]
	s_addc_u32 s77, s49, 0
	s_add_i32 s75, s69, s56
	global_load_lds_dwordx4 v[234:235], off
	v_lshl_add_u64 v[224:225], s[76:77], 0, v[182:183]
	s_mov_b32 m0, s75
	v_lshl_add_u64 v[236:237], s[50:51], 0, v[180:181]
	global_load_lds_dwordx4 v[224:225], off
	v_lshl_add_u64 v[224:225], s[76:77], 0, v[186:187]
	s_add_i32 m0, s75, 0x2000
	v_lshl_add_u64 v[238:239], s[50:51], 0, v[184:185]
	global_load_lds_dwordx4 v[224:225], off
	s_mov_b32 m0, s57
	s_nop 0
	global_load_lds_dwordx4 v[236:237], off
	s_mov_b32 m0, s58
	s_nop 0
	global_load_lds_dwordx4 v[238:239], off
	s_waitcnt vmcnt(8)
	s_waitcnt lgkmcnt(0)
	s_barrier
; #define PG8_STAGE(bufoff, gbase, voff) do { _Pragma("unroll") for (int _i = 0; _i < 2; ++_i) \
;         __builtin_amdgcn_global_load_lds((const unsigned*)((const char*)(gbase) + (voff)[_i]), (PG8_LAS unsigned*)(lds + (bufoff) + ldsw + _i * 8192), 16, 0, 0); } while (0)
; #define PG8_LDA(dst, b, h) do { _Pragma("unroll") for (int m = 0; m < 4; ++m) _Pragma("unroll") for (int k = 0; k < 2; ++k) dst[m][k] = *(const PG8_LAS bf16x8*)(lds + PG8_SA(b, h) + aoff + m * 2048 + k * 1024); } while (0)
; #define PG8_LDB(dst, b, h) do { _Pragma("unroll") for (int n = 0; n < 2; ++n) _Pragma("unroll") for (int k = 0; k < 2; ++k) dst[n][k] = *(const PG8_LAS bf16x8*)(lds + PG8_SB(b, h) + boff + n * 2048 + k * 1024); } while (0)
; #define PG8_MMA(ai, bj, At, Bt) do { __builtin_amdgcn_s_setprio(1); _Pragma("unroll") for (int m = 0; m < 4; ++m) _Pragma("unroll") for (int n = 0; n < 2; ++n) _Pragma("unroll") for (int k = 0; k < 2; ++k) \
;         acc[ai][bj][m][n] = __builtin_amdgcn_mfma_f32_16x16x32_bf16(Bt[n][k], At[m][k], acc[ai][bj][m][n], 0, 0, 0); __builtin_amdgcn_s_setprio(0); } while (0)
; #define PG8_WAIT_V(n) asm volatile("s_waitcnt vmcnt(" #n ")" ::: "memory")
; #define PG8_WAIT_L(n) asm volatile("s_waitcnt lgkmcnt(" #n ")" ::: "memory")
; #define PG8_BAR __builtin_amdgcn_s_barrier()
; #define PG8_SCHED __builtin_amdgcn_sched_barrier(0)
; template <class Epi, class Sched, bool ALIGN_EPI = false, bool SP2 = false>
; __device__ __forceinline__ void gemm_phase(PG8_LAS unsigned char* lds, const Gemm g, const Sched& S, const Epi& E, const int wave_in) {
;     ...
;             PG8_WAIT_V(8); PG8_WAIT_L(0); PG8_BAR; PG8_MMA(1, 0, At, B0); PG8_MMA(1, 1, At, B1); PG8_BAR; PG8_SCHED;
;             PG8_LDB(B0, 1, 0); PG8_LDB(B1, 1, 1); PG8_SCHED; PG8_LDA(At, 1, 0); PG8_STAGE(PG8_SA(0, 1), a2 + hstepA, voffA);
;             PG8_WAIT_V(8); PG8_WAIT_L(0); PG8_BAR; PG8_MMA(0, 0, At, B0); PG8_MMA(0, 1, At, B1); PG8_BAR; PG8_SCHED;
	s_setprio 1
	s_waitcnt lgkmcnt(0)
	v_mfma_f32_16x16x32_bf16 v[108:111], v[44:47], v[136:139], 0
	v_mfma_f32_16x16x32_bf16 v[76:79], v[52:55], v[136:139], 0
	v_mfma_f32_16x16x32_bf16 v[68:71], v[44:47], v[152:155], 0
	v_mfma_f32_16x16x32_bf16 v[36:39], v[52:55], v[152:155], 0
	v_mfma_f32_16x16x32_bf16 v[28:31], v[44:47], v[176:179], 0
	v_mfma_f32_16x16x32_bf16 v[20:23], v[52:55], v[176:179], 0
	v_mfma_f32_16x16x32_bf16 v[12:15], v[44:47], v[216:219], 0
	v_mfma_f32_16x16x32_bf16 v[8:11], v[52:55], v[216:219], 0
	v_mfma_f32_16x16x32_bf16 v[108:111], v[48:51], v[144:147], v[108:111]
	v_mfma_f32_16x16x32_bf16 v[76:79], v[56:59], v[144:147], v[76:79]
	v_mfma_f32_16x16x32_bf16 v[68:71], v[48:51], v[160:163], v[68:71]
	v_mfma_f32_16x16x32_bf16 v[36:39], v[56:59], v[160:163], v[36:39]
	v_mfma_f32_16x16x32_bf16 v[28:31], v[48:51], v[212:215], v[28:31]
	v_mfma_f32_16x16x32_bf16 v[20:23], v[56:59], v[212:215], v[20:23]
	v_mfma_f32_16x16x32_bf16 v[12:15], v[48:51], v[220:223], v[12:15]
	v_mfma_f32_16x16x32_bf16 v[8:11], v[56:59], v[220:223], v[8:11]
	v_mfma_f32_16x16x32_bf16 v[40:43], v[60:63], v[152:155], 0
	v_mfma_f32_16x16x32_bf16 v[32:35], v[80:83], v[152:155], 0
	v_mfma_f32_16x16x32_bf16 v[24:27], v[60:63], v[176:179], 0
	v_mfma_f32_16x16x32_bf16 v[16:19], v[80:83], v[176:179], 0
	v_mfma_f32_16x16x32_bf16 v[4:7], v[60:63], v[216:219], 0
	v_mfma_f32_16x16x32_bf16 v[0:3], v[80:83], v[216:219], 0
	v_mfma_f32_16x16x32_bf16 v[44:47], v[60:63], v[136:139], 0
	v_mfma_f32_16x16x32_bf16 v[48:51], v[80:83], v[136:139], 0
	v_mfma_f32_16x16x32_bf16 v[40:43], v[64:67], v[160:163], v[40:43]
	v_mfma_f32_16x16x32_bf16 v[32:35], v[84:87], v[160:163], v[32:35]
	v_mfma_f32_16x16x32_bf16 v[24:27], v[64:67], v[212:215], v[24:27]
	v_mfma_f32_16x16x32_bf16 v[16:19], v[84:87], v[212:215], v[16:19]
	v_mfma_f32_16x16x32_bf16 v[4:7], v[64:67], v[220:223], v[4:7]
	v_mfma_f32_16x16x32_bf16 v[0:3], v[84:87], v[220:223], v[0:3]
	v_mfma_f32_16x16x32_bf16 v[44:47], v[64:67], v[144:147], v[44:47]
	v_mfma_f32_16x16x32_bf16 v[48:51], v[84:87], v[144:147], v[48:51]
	s_setprio 0
	s_barrier
	s_add_i32 s75, 0, 0x18000
	s_add_i32 s76, 0, 0x1c000
	v_add_u32_e32 v64, s75, v195
	v_add_u32_e32 v72, s76, v195
	ds_read_b128 v[52:55], v64
	ds_read_b128 v[56:59], v64 offset:1024
	ds_read_b128 v[60:63], v64 offset:2048
	ds_read_b128 v[64:67], v64 offset:3072
	ds_read_b128 v[80:83], v72
	ds_read_b128 v[84:87], v72 offset:1024
	ds_read_b128 v[176:179], v72 offset:2048
	ds_read_b128 v[212:215], v72 offset:3072
	s_add_u32 s50, s50, 0x80000
	s_addc_u32 s51, s51, 0
	s_mov_b32 m0, s59
	v_lshl_add_u64 v[152:153], s[50:51], 0, v[180:181]
	ds_read_b128 v[72:75], v199 offset:32768
	ds_read_b128 v[104:107], v199 offset:33792
	ds_read_b128 v[136:139], v199 offset:34816
	ds_read_b128 v[144:147], v199 offset:35840
	ds_read_b128 v[216:219], v199 offset:36864
	ds_read_b128 v[220:223], v199 offset:37888
	ds_read_b128 v[224:227], v199 offset:38912
	ds_read_b128 v[228:231], v199 offset:39936
	global_load_lds_dwordx4 v[152:153], off
	v_lshl_add_u64 v[152:153], s[50:51], 0, v[184:185]
	s_mov_b32 m0, s60
	s_nop 0
	global_load_lds_dwordx4 v[152:153], off
	s_waitcnt vmcnt(8)
	s_waitcnt lgkmcnt(0)
	s_barrier
	s_setprio 1
	s_waitcnt lgkmcnt(0)
	v_mfma_f32_16x16x32_bf16 v[152:155], v[52:55], v[72:75], v[172:175]
	v_mfma_f32_16x16x32_bf16 v[172:175], v[56:59], v[104:107], v[152:155]
	v_mfma_f32_16x16x32_bf16 v[152:155], v[60:63], v[72:75], v[164:167]
	v_mfma_f32_16x16x32_bf16 v[164:167], v[64:67], v[104:107], v[152:155]
	v_mfma_f32_16x16x32_bf16 v[152:155], v[52:55], v[136:139], v[156:159]
	v_mfma_f32_16x16x32_bf16 v[148:151], v[60:63], v[136:139], v[148:151]
	v_mfma_f32_16x16x32_bf16 v[140:143], v[52:55], v[216:219], v[140:143]
	v_mfma_f32_16x16x32_bf16 v[132:135], v[60:63], v[216:219], v[132:135]
	v_mfma_f32_16x16x32_bf16 v[124:127], v[52:55], v[224:227], v[124:127]
	v_mfma_f32_16x16x32_bf16 v[120:123], v[60:63], v[224:227], v[120:123]
	v_mfma_f32_16x16x32_bf16 v[156:159], v[56:59], v[144:147], v[152:155]
	v_mfma_f32_16x16x32_bf16 v[148:151], v[64:67], v[144:147], v[148:151]
	v_mfma_f32_16x16x32_bf16 v[140:143], v[56:59], v[220:223], v[140:143]
	v_mfma_f32_16x16x32_bf16 v[132:135], v[64:67], v[220:223], v[132:135]
	v_mfma_f32_16x16x32_bf16 v[124:127], v[56:59], v[228:231], v[124:127]
	v_mfma_f32_16x16x32_bf16 v[120:123], v[64:67], v[228:231], v[120:123]
	v_mfma_f32_16x16x32_bf16 v[152:155], v[80:83], v[72:75], v[168:171]
	v_mfma_f32_16x16x32_bf16 v[72:75], v[176:179], v[72:75], v[88:91]
	v_mfma_f32_16x16x32_bf16 v[160:163], v[212:215], v[104:107], v[72:75]
	v_mfma_f32_16x16x32_bf16 v[72:75], v[80:83], v[136:139], v[92:95]
	v_mfma_f32_16x16x32_bf16 v[168:171], v[84:87], v[104:107], v[152:155]
	v_mfma_f32_16x16x32_bf16 v[152:155], v[84:87], v[144:147], v[72:75]
	v_mfma_f32_16x16x32_bf16 v[72:75], v[176:179], v[136:139], v[96:99]
	v_mfma_f32_16x16x32_bf16 v[144:147], v[212:215], v[144:147], v[72:75]
	v_mfma_f32_16x16x32_bf16 v[72:75], v[80:83], v[216:219], v[100:103]
	v_mfma_f32_16x16x32_bf16 v[136:139], v[84:87], v[220:223], v[72:75]
	v_mfma_f32_16x16x32_bf16 v[72:75], v[176:179], v[216:219], v[128:131]
	v_mfma_f32_16x16x32_bf16 v[128:131], v[212:215], v[220:223], v[72:75]
	v_mfma_f32_16x16x32_bf16 v[72:75], v[80:83], v[224:227], v[116:119]
	v_mfma_f32_16x16x32_bf16 v[116:119], v[84:87], v[228:231], v[72:75]
	v_mfma_f32_16x16x32_bf16 v[72:75], v[176:179], v[224:227], v[112:115]
	v_mfma_f32_16x16x32_bf16 v[112:115], v[212:215], v[228:231], v[72:75]
	s_setprio 0
	s_barrier
; #define PG8_STAGE(bufoff, gbase, voff) do { _Pragma("unroll") for (int _i = 0; _i < 2; ++_i) \
;         __builtin_amdgcn_global_load_lds((const unsigned*)((const char*)(gbase) + (voff)[_i]), (PG8_LAS unsigned*)(lds + (bufoff) + ldsw + _i * 8192), 16, 0, 0); } while (0)
; #define PG8_LDA(dst, b, h) do { _Pragma("unroll") for (int m = 0; m < 4; ++m) _Pragma("unroll") for (int k = 0; k < 2; ++k) dst[m][k] = *(const PG8_LAS bf16x8*)(lds + PG8_SA(b, h) + aoff + m * 2048 + k * 1024); } while (0)
; #define PG8_WAIT_V(n) asm volatile("s_waitcnt vmcnt(" #n ")" ::: "memory")
; #define PG8_WAIT_L(n) asm volatile("s_waitcnt lgkmcnt(" #n ")" ::: "memory")
; #define PG8_BAR __builtin_amdgcn_s_barrier()
; template <class Epi, class Sched, bool ALIGN_EPI = false, bool SP2 = false>
; __device__ __forceinline__ void gemm_phase(PG8_LAS unsigned char* lds, const Gemm g, const Sched& S, const Epi& E, const int wave_in) {
;     ...
;         for (int t = 0; t < nt; t += 2) {
;             const bool last = (t == nt - 2);
;             const char* a1 = cA + (size_t)(t + 1) * kstep;
;             const char* a2 = last ? nA : cA + (size_t)(t + 2) * kstep; const char* b2 = last ? nB : cB + (size_t)(t + 2) * kstep;
;             const char* a3 = a2 + kstep; const char* b3 = b2 + kstep;
;             if (last && has_next) S.a_ready(nxt);
;             if constexpr (SP2) {
;             PG8_LDB(B0, 0, 0); PG8_LDB(B1, 0, 1); PG8_SCHED; PG8_LDA(At, 0, 0); PG8_STAGE(PG8_SA(1, 1), a1 + hstepA, voffA);
;             PG8_WAIT_V(8); PG8_WAIT_L(0); PG8_BAR; PG8_MMA(0, 0, At, B0); PG8_MMA(0, 1, At, B1); PG8_BAR; PG8_SCHED;
;             PG8_LDA(At, 0, 1); PG8_STAGE(PG8_SB(0, 0), b2, voffB); PG8_STAGE(PG8_SB(0, 1), b2 + hstepB, voffB); PG8_STAGE(PG8_SA(0, 0), a2, voffA);
;             PG8_WAIT_V(8); PG8_WAIT_L(0); PG8_BAR; PG8_MMA(1, 0, At, B0); PG8_MMA(1, 1, At, B1); PG8_BAR; PG8_SCHED;
;             PG8_LDB(B0, 1, 0); PG8_LDB(B1, 1, 1); PG8_SCHED; PG8_LDA(At, 1, 0); PG8_STAGE(PG8_SA(0, 1), a2 + hstepA, voffA);
;             PG8_WAIT_V(8); PG8_WAIT_L(0); PG8_BAR; PG8_MMA(0, 0, At, B0); PG8_MMA(0, 1, At, B1); PG8_BAR; PG8_SCHED;
;             PG8_LDA(At, 1, 1); PG8_STAGE(PG8_SB(1, 0), b3, voffB); PG8_STAGE(PG8_SB(1, 1), b3 + hstepB, voffB); PG8_STAGE(PG8_SA(1, 0), a3, voffA);
;             PG8_WAIT_V(8); PG8_WAIT_L(0); PG8_BAR; PG8_MMA(1, 0, At, B0); PG8_MMA(1, 1, At, B1); PG8_BAR; PG8_SCHED;
	s_add_i32 s50, s75, s56
	v_lshl_add_u64 v[104:105], v[232:233], 0, s[22:23]
	s_mov_b32 m0, s50
	s_nop 1
	ds_read_b128 v[72:75], v199 offset:49152
	ds_read_b128 v[88:91], v199 offset:50176
	ds_read_b128 v[92:95], v199 offset:51200
	ds_read_b128 v[96:99], v199 offset:52224
	ds_read_b128 v[100:103], v199 offset:53248
	ds_read_b128 v[216:219], v199 offset:54272
	ds_read_b128 v[220:223], v199 offset:55296
	ds_read_b128 v[224:227], v199 offset:56320
	global_load_lds_dwordx4 v[104:105], off
	s_add_i32 m0, s50, 0x2000
	s_add_u32 s48, s48, 0x80080
	v_lshl_add_u64 v[104:105], v[234:235], 0, s[22:23]
	s_addc_u32 s49, s49, 0
	s_add_i32 s50, s76, s56
	global_load_lds_dwordx4 v[104:105], off
	v_lshl_add_u64 v[104:105], s[48:49], 0, v[182:183]
	s_mov_b32 m0, s50
	s_nop 0
	global_load_lds_dwordx4 v[104:105], off
	v_lshl_add_u64 v[104:105], s[48:49], 0, v[186:187]
	s_add_i32 m0, s50, 0x2000
	s_nop 0
	global_load_lds_dwordx4 v[104:105], off
	v_lshl_add_u64 v[104:105], v[236:237], 0, s[22:23]
	s_mov_b32 m0, s63
	s_nop 0
	global_load_lds_dwordx4 v[104:105], off
	v_lshl_add_u64 v[104:105], v[238:239], 0, s[22:23]
	s_mov_b32 m0, s64
	s_nop 0
	global_load_lds_dwordx4 v[104:105], off
	s_waitcnt vmcnt(8)
	s_waitcnt lgkmcnt(0)
	s_barrier
	s_setprio 1
	s_waitcnt lgkmcnt(0)
	v_mfma_f32_16x16x32_bf16 v[104:107], v[52:55], v[72:75], v[108:111]
	v_mfma_f32_16x16x32_bf16 v[76:79], v[60:63], v[72:75], v[76:79]
	v_mfma_f32_16x16x32_bf16 v[68:71], v[52:55], v[92:95], v[68:71]
	v_mfma_f32_16x16x32_bf16 v[36:39], v[60:63], v[92:95], v[36:39]
	v_mfma_f32_16x16x32_bf16 v[28:31], v[52:55], v[100:103], v[28:31]
	v_mfma_f32_16x16x32_bf16 v[20:23], v[60:63], v[100:103], v[20:23]
	v_mfma_f32_16x16x32_bf16 v[12:15], v[52:55], v[220:223], v[12:15]
	v_mfma_f32_16x16x32_bf16 v[8:11], v[60:63], v[220:223], v[8:11]
	v_mfma_f32_16x16x32_bf16 v[108:111], v[56:59], v[88:91], v[104:107]
	v_mfma_f32_16x16x32_bf16 v[76:79], v[64:67], v[88:91], v[76:79]
	v_mfma_f32_16x16x32_bf16 v[68:71], v[56:59], v[96:99], v[68:71]
	v_mfma_f32_16x16x32_bf16 v[36:39], v[64:67], v[96:99], v[36:39]
	v_mfma_f32_16x16x32_bf16 v[28:31], v[56:59], v[216:219], v[28:31]
	v_mfma_f32_16x16x32_bf16 v[20:23], v[64:67], v[216:219], v[20:23]
	v_mfma_f32_16x16x32_bf16 v[12:15], v[56:59], v[224:227], v[12:15]
	v_mfma_f32_16x16x32_bf16 v[8:11], v[64:67], v[224:227], v[8:11]
	v_mfma_f32_16x16x32_bf16 v[44:47], v[80:83], v[72:75], v[44:47]
	v_mfma_f32_16x16x32_bf16 v[104:107], v[84:87], v[88:91], v[44:47]
	v_mfma_f32_16x16x32_bf16 v[44:47], v[176:179], v[72:75], v[48:51]
	v_mfma_f32_16x16x32_bf16 v[40:43], v[80:83], v[92:95], v[40:43]
	v_mfma_f32_16x16x32_bf16 v[32:35], v[176:179], v[92:95], v[32:35]
	v_mfma_f32_16x16x32_bf16 v[24:27], v[80:83], v[100:103], v[24:27]
	v_mfma_f32_16x16x32_bf16 v[16:19], v[176:179], v[100:103], v[16:19]
	v_mfma_f32_16x16x32_bf16 v[4:7], v[80:83], v[220:223], v[4:7]
	v_mfma_f32_16x16x32_bf16 v[0:3], v[176:179], v[220:223], v[0:3]
	v_mfma_f32_16x16x32_bf16 v[72:75], v[212:215], v[88:91], v[44:47]
	v_mfma_f32_16x16x32_bf16 v[40:43], v[84:87], v[96:99], v[40:43]
	v_mfma_f32_16x16x32_bf16 v[32:35], v[212:215], v[96:99], v[32:35]
	v_mfma_f32_16x16x32_bf16 v[24:27], v[84:87], v[216:219], v[24:27]
	v_mfma_f32_16x16x32_bf16 v[16:19], v[212:215], v[216:219], v[16:19]
	v_mfma_f32_16x16x32_bf16 v[4:7], v[84:87], v[224:227], v[4:7]
	v_mfma_f32_16x16x32_bf16 v[0:3], v[212:215], v[224:227], v[0:3]
	s_setprio 0
	s_barrier
	s_add_i32 s74, s74, 2
	s_add_u32 s46, s46, 0x100
	s_addc_u32 s47, s47, 0
	s_add_u32 s72, s72, 0x100
	s_addc_u32 s73, s73, 0
	s_cmp_gt_u32 s74, 29
	s_cbranch_scc0 .LBB0_479
	s_branch .Lkx_6
.LBB0_479:
	ds_read_b128 v[44:47], v189
	ds_read_b128 v[48:51], v189 offset:1024
	ds_read_b128 v[52:55], v189 offset:2048
	ds_read_b128 v[56:59], v189 offset:3072
	ds_read_b128 v[60:63], v197
	ds_read_b128 v[64:67], v197 offset:1024
	ds_read_b128 v[80:83], v197 offset:2048
	ds_read_b128 v[84:87], v197 offset:3072
	s_add_u32 s48, s46, 0xfff80080
	s_addc_u32 s49, s47, -1
	s_cmp_eq_u32 s74, 28
	s_cselect_b32 s51, s1, s49
	s_cselect_b32 s50, s13, s48
	s_cselect_b32 s49, s39, s73
	s_cselect_b32 s48, s41, s72
	v_lshl_add_u64 v[224:225], s[46:47], 0, v[206:207]
	s_add_i32 m0, s57, 0xc000
	ds_read_b128 v[88:91], v199
	ds_read_b128 v[92:95], v199 offset:1024
	ds_read_b128 v[96:99], v199 offset:2048
	ds_read_b128 v[100:103], v199 offset:3072
	ds_read_b128 v[176:179], v199 offset:4096
	ds_read_b128 v[212:215], v199 offset:5120
	ds_read_b128 v[216:219], v199 offset:6144
	ds_read_b128 v[220:223], v199 offset:7168
	global_load_lds_dwordx4 v[224:225], off
	v_lshl_add_u64 v[224:225], s[46:47], 0, v[208:209]
	s_add_i32 m0, s57, 0xe000
	s_nop 0
	global_load_lds_dwordx4 v[224:225], off
	s_waitcnt vmcnt(8)
	s_waitcnt lgkmcnt(0)
	s_barrier
; #define PG8_STAGE(bufoff, gbase, voff) do { _Pragma("unroll") for (int _i = 0; _i < 2; ++_i) \
;         __builtin_amdgcn_global_load_lds((const unsigned*)((const char*)(gbase) + (voff)[_i]), (PG8_LAS unsigned*)(lds + (bufoff) + ldsw + _i * 8192), 16, 0, 0); } while (0)
; #define PG8_LDA(dst, b, h) do { _Pragma("unroll") for (int m = 0; m < 4; ++m) _Pragma("unroll") for (int k = 0; k < 2; ++k) dst[m][k] = *(const PG8_LAS bf16x8*)(lds + PG8_SA(b, h) + aoff + m * 2048 + k * 1024); } while (0)
; #define PG8_MMA(ai, bj, At, Bt) do { __builtin_amdgcn_s_setprio(1); _Pragma("unroll") for (int m = 0; m < 4; ++m) _Pragma("unroll") for (int n = 0; n < 2; ++n) _Pragma("unroll") for (int k = 0; k < 2; ++k) \
;         acc[ai][bj][m][n] = __builtin_amdgcn_mfma_f32_16x16x32_bf16(Bt[n][k], At[m][k], acc[ai][bj][m][n], 0, 0, 0); __builtin_amdgcn_s_setprio(0); } while (0)
; #define PG8_WAIT_V(n) asm volatile("s_waitcnt vmcnt(" #n ")" ::: "memory")
; #define PG8_WAIT_L(n) asm volatile("s_waitcnt lgkmcnt(" #n ")" ::: "memory")
; #define PG8_BAR __builtin_amdgcn_s_barrier()
; #define PG8_SCHED __builtin_amdgcn_sched_barrier(0)
; template <class Epi, class Sched, bool ALIGN_EPI = false, bool SP2 = false>
; __device__ __forceinline__ void gemm_phase(PG8_LAS unsigned char* lds, const Gemm g, const Sched& S, const Epi& E, const int wave_in) {
;     ...
;             PG8_WAIT_V(8); PG8_WAIT_L(0); PG8_BAR; PG8_MMA(0, 0, At, B0); PG8_MMA(0, 1, At, B1); PG8_BAR; PG8_SCHED;
;             PG8_LDA(At, 0, 1); PG8_STAGE(PG8_SB(0, 0), b2, voffB); PG8_STAGE(PG8_SB(0, 1), b2 + hstepB, voffB); PG8_STAGE(PG8_SA(0, 0), a2, voffA);
;             PG8_WAIT_V(8); PG8_WAIT_L(0); PG8_BAR; PG8_MMA(1, 0, At, B0); PG8_MMA(1, 1, At, B1); PG8_BAR; PG8_SCHED;
	s_setprio 1
	s_waitcnt lgkmcnt(0)
	v_mfma_f32_16x16x32_bf16 v[172:175], v[44:47], v[88:91], v[172:175]
	v_mfma_f32_16x16x32_bf16 v[164:167], v[52:55], v[88:91], v[164:167]
	v_mfma_f32_16x16x32_bf16 v[156:159], v[44:47], v[96:99], v[156:159]
	v_mfma_f32_16x16x32_bf16 v[148:151], v[52:55], v[96:99], v[148:151]
	v_mfma_f32_16x16x32_bf16 v[140:143], v[44:47], v[176:179], v[140:143]
	v_mfma_f32_16x16x32_bf16 v[132:135], v[52:55], v[176:179], v[132:135]
	v_mfma_f32_16x16x32_bf16 v[124:127], v[44:47], v[216:219], v[124:127]
	v_mfma_f32_16x16x32_bf16 v[120:123], v[52:55], v[216:219], v[120:123]
	v_mfma_f32_16x16x32_bf16 v[172:175], v[48:51], v[92:95], v[172:175]
	v_mfma_f32_16x16x32_bf16 v[164:167], v[56:59], v[92:95], v[164:167]
	v_mfma_f32_16x16x32_bf16 v[156:159], v[48:51], v[100:103], v[156:159]
	v_mfma_f32_16x16x32_bf16 v[148:151], v[56:59], v[100:103], v[148:151]
	v_mfma_f32_16x16x32_bf16 v[140:143], v[48:51], v[212:215], v[140:143]
	v_mfma_f32_16x16x32_bf16 v[132:135], v[56:59], v[212:215], v[132:135]
	v_mfma_f32_16x16x32_bf16 v[124:127], v[48:51], v[220:223], v[124:127]
	v_mfma_f32_16x16x32_bf16 v[120:123], v[56:59], v[220:223], v[120:123]
	v_mfma_f32_16x16x32_bf16 v[168:171], v[60:63], v[88:91], v[168:171]
	v_mfma_f32_16x16x32_bf16 v[88:91], v[80:83], v[88:91], v[160:163]
	v_mfma_f32_16x16x32_bf16 v[168:171], v[64:67], v[92:95], v[168:171]
	v_mfma_f32_16x16x32_bf16 v[88:91], v[84:87], v[92:95], v[88:91]
	v_mfma_f32_16x16x32_bf16 v[92:95], v[60:63], v[96:99], v[152:155]
	v_mfma_f32_16x16x32_bf16 v[96:99], v[80:83], v[96:99], v[144:147]
	v_mfma_f32_16x16x32_bf16 v[128:131], v[80:83], v[176:179], v[128:131]
	v_mfma_f32_16x16x32_bf16 v[116:119], v[60:63], v[216:219], v[116:119]
	v_mfma_f32_16x16x32_bf16 v[112:115], v[80:83], v[216:219], v[112:115]
	v_mfma_f32_16x16x32_bf16 v[92:95], v[64:67], v[100:103], v[92:95]
	v_mfma_f32_16x16x32_bf16 v[96:99], v[84:87], v[100:103], v[96:99]
	v_mfma_f32_16x16x32_bf16 v[100:103], v[60:63], v[176:179], v[136:139]
	v_mfma_f32_16x16x32_bf16 v[128:131], v[84:87], v[212:215], v[128:131]
	v_mfma_f32_16x16x32_bf16 v[116:119], v[64:67], v[220:223], v[116:119]
	v_mfma_f32_16x16x32_bf16 v[112:115], v[84:87], v[220:223], v[112:115]
	v_mfma_f32_16x16x32_bf16 v[100:103], v[64:67], v[212:215], v[100:103]
	s_setprio 0
	s_barrier
	s_add_i32 s75, s68, s56
	v_lshl_add_u64 v[232:233], s[48:49], 0, v[182:183]
	s_mov_b32 m0, s75
	ds_read_b128 v[136:139], v199 offset:16384
	ds_read_b128 v[144:147], v199 offset:17408
	ds_read_b128 v[152:155], v199 offset:18432
	ds_read_b128 v[160:163], v199 offset:19456
	ds_read_b128 v[176:179], v199 offset:20480
	ds_read_b128 v[212:215], v199 offset:21504
	ds_read_b128 v[216:219], v199 offset:22528
	ds_read_b128 v[220:223], v199 offset:23552
	global_load_lds_dwordx4 v[232:233], off
	s_add_i32 m0, s75, 0x2000
	s_add_u32 s76, s48, 0x80000
	v_lshl_add_u64 v[234:235], s[48:49], 0, v[186:187]
	s_addc_u32 s77, s49, 0
	s_add_i32 s75, s69, s56
	global_load_lds_dwordx4 v[234:235], off
	v_lshl_add_u64 v[224:225], s[76:77], 0, v[182:183]
	s_mov_b32 m0, s75
	v_lshl_add_u64 v[236:237], s[50:51], 0, v[180:181]
	global_load_lds_dwordx4 v[224:225], off
	v_lshl_add_u64 v[224:225], s[76:77], 0, v[186:187]
	s_add_i32 m0, s75, 0x2000
	v_lshl_add_u64 v[238:239], s[50:51], 0, v[184:185]
	global_load_lds_dwordx4 v[224:225], off
	s_mov_b32 m0, s57
	s_nop 0
	global_load_lds_dwordx4 v[236:237], off
	s_mov_b32 m0, s58
	s_nop 0
	global_load_lds_dwordx4 v[238:239], off
	s_waitcnt vmcnt(8)
	s_waitcnt lgkmcnt(0)
	s_barrier
	s_setprio 1
	s_waitcnt lgkmcnt(0)
	v_mfma_f32_16x16x32_bf16 v[108:111], v[44:47], v[136:139], v[108:111]
	v_mfma_f32_16x16x32_bf16 v[76:79], v[52:55], v[136:139], v[76:79]
	v_mfma_f32_16x16x32_bf16 v[68:71], v[44:47], v[152:155], v[68:71]
	v_mfma_f32_16x16x32_bf16 v[36:39], v[52:55], v[152:155], v[36:39]
	v_mfma_f32_16x16x32_bf16 v[28:31], v[44:47], v[176:179], v[28:31]
	v_mfma_f32_16x16x32_bf16 v[20:23], v[52:55], v[176:179], v[20:23]
	v_mfma_f32_16x16x32_bf16 v[12:15], v[44:47], v[216:219], v[12:15]
	v_mfma_f32_16x16x32_bf16 v[8:11], v[52:55], v[216:219], v[8:11]
	v_mfma_f32_16x16x32_bf16 v[108:111], v[48:51], v[144:147], v[108:111]
	v_mfma_f32_16x16x32_bf16 v[76:79], v[56:59], v[144:147], v[76:79]
	v_mfma_f32_16x16x32_bf16 v[68:71], v[48:51], v[160:163], v[68:71]
	v_mfma_f32_16x16x32_bf16 v[36:39], v[56:59], v[160:163], v[36:39]
	v_mfma_f32_16x16x32_bf16 v[28:31], v[48:51], v[212:215], v[28:31]
	v_mfma_f32_16x16x32_bf16 v[20:23], v[56:59], v[212:215], v[20:23]
	v_mfma_f32_16x16x32_bf16 v[12:15], v[48:51], v[220:223], v[12:15]
	v_mfma_f32_16x16x32_bf16 v[8:11], v[56:59], v[220:223], v[8:11]
	v_mfma_f32_16x16x32_bf16 v[40:43], v[60:63], v[152:155], v[40:43]
	v_mfma_f32_16x16x32_bf16 v[32:35], v[80:83], v[152:155], v[32:35]
	v_mfma_f32_16x16x32_bf16 v[24:27], v[60:63], v[176:179], v[24:27]
	v_mfma_f32_16x16x32_bf16 v[16:19], v[80:83], v[176:179], v[16:19]
	v_mfma_f32_16x16x32_bf16 v[4:7], v[60:63], v[216:219], v[4:7]
	v_mfma_f32_16x16x32_bf16 v[0:3], v[80:83], v[216:219], v[0:3]
	v_mfma_f32_16x16x32_bf16 v[44:47], v[60:63], v[136:139], v[104:107]
	v_mfma_f32_16x16x32_bf16 v[48:51], v[80:83], v[136:139], v[72:75]
	v_mfma_f32_16x16x32_bf16 v[40:43], v[64:67], v[160:163], v[40:43]
	v_mfma_f32_16x16x32_bf16 v[32:35], v[84:87], v[160:163], v[32:35]
	v_mfma_f32_16x16x32_bf16 v[24:27], v[64:67], v[212:215], v[24:27]
	v_mfma_f32_16x16x32_bf16 v[16:19], v[84:87], v[212:215], v[16:19]
	v_mfma_f32_16x16x32_bf16 v[4:7], v[64:67], v[220:223], v[4:7]
	v_mfma_f32_16x16x32_bf16 v[0:3], v[84:87], v[220:223], v[0:3]
	v_mfma_f32_16x16x32_bf16 v[44:47], v[64:67], v[144:147], v[44:47]
	v_mfma_f32_16x16x32_bf16 v[48:51], v[84:87], v[144:147], v[48:51]
	s_setprio 0
	s_barrier
; #define PG8_STAGE(bufoff, gbase, voff) do { _Pragma("unroll") for (int _i = 0; _i < 2; ++_i) \
;         __builtin_amdgcn_global_load_lds((const unsigned*)((const char*)(gbase) + (voff)[_i]), (PG8_LAS unsigned*)(lds + (bufoff) + ldsw + _i * 8192), 16, 0, 0); } while (0)
; #define PG8_LDA(dst, b, h) do { _Pragma("unroll") for (int m = 0; m < 4; ++m) _Pragma("unroll") for (int k = 0; k < 2; ++k) dst[m][k] = *(const PG8_LAS bf16x8*)(lds + PG8_SA(b, h) + aoff + m * 2048 + k * 1024); } while (0)
; #define PG8_LDB(dst, b, h) do { _Pragma("unroll") for (int n = 0; n < 2; ++n) _Pragma("unroll") for (int k = 0; k < 2; ++k) dst[n][k] = *(const PG8_LAS bf16x8*)(lds + PG8_SB(b, h) + boff + n * 2048 + k * 1024); } while (0)
; #define PG8_MMA(ai, bj, At, Bt) do { __builtin_amdgcn_s_setprio(1); _Pragma("unroll") for (int m = 0; m < 4; ++m) _Pragma("unroll") for (int n = 0; n < 2; ++n) _Pragma("unroll") for (int k = 0; k < 2; ++k) \
;         acc[ai][bj][m][n] = __builtin_amdgcn_mfma_f32_16x16x32_bf16(Bt[n][k], At[m][k], acc[ai][bj][m][n], 0, 0, 0); __builtin_amdgcn_s_setprio(0); } while (0)
; #define PG8_WAIT_V(n) asm volatile("s_waitcnt vmcnt(" #n ")" ::: "memory")
; #define PG8_WAIT_L(n) asm volatile("s_waitcnt lgkmcnt(" #n ")" ::: "memory")
; #define PG8_BAR __builtin_amdgcn_s_barrier()
; #define PG8_SCHED __builtin_amdgcn_sched_barrier(0)
; template <class Epi, class Sched, bool ALIGN_EPI = false, bool SP2 = false>
; __device__ __forceinline__ void gemm_phase(PG8_LAS unsigned char* lds, const Gemm g, const Sched& S, const Epi& E, const int wave_in) {
;     ...
;             PG8_LDB(B0, 1, 0); PG8_LDB(B1, 1, 1); PG8_SCHED; PG8_LDA(At, 1, 0); PG8_STAGE(PG8_SA(0, 1), a2 + hstepA, voffA);
;             PG8_WAIT_V(8); PG8_WAIT_L(0); PG8_BAR; PG8_MMA(0, 0, At, B0); PG8_MMA(0, 1, At, B1); PG8_BAR; PG8_SCHED;
;             PG8_LDA(At, 1, 1); PG8_STAGE(PG8_SB(1, 0), b3, voffB); PG8_STAGE(PG8_SB(1, 1), b3 + hstepB, voffB); PG8_STAGE(PG8_SA(1, 0), a3, voffA);
;             PG8_WAIT_V(8); PG8_WAIT_L(0); PG8_BAR; PG8_MMA(1, 0, At, B0); PG8_MMA(1, 1, At, B1); PG8_BAR; PG8_SCHED;
	s_add_i32 s75, 0, 0x18000
	s_add_i32 s76, 0, 0x1c000
	v_add_u32_e32 v64, s75, v195
	v_add_u32_e32 v72, s76, v195
	ds_read_b128 v[52:55], v64
	ds_read_b128 v[56:59], v64 offset:1024
	ds_read_b128 v[60:63], v64 offset:2048
	ds_read_b128 v[64:67], v64 offset:3072
	ds_read_b128 v[80:83], v72
	ds_read_b128 v[84:87], v72 offset:1024
	ds_read_b128 v[176:179], v72 offset:2048
	ds_read_b128 v[212:215], v72 offset:3072
	s_add_u32 s50, s50, 0x80000
	s_addc_u32 s51, s51, 0
	s_mov_b32 m0, s59
	v_lshl_add_u64 v[152:153], s[50:51], 0, v[180:181]
	ds_read_b128 v[72:75], v199 offset:32768
	ds_read_b128 v[104:107], v199 offset:33792
	ds_read_b128 v[136:139], v199 offset:34816
	ds_read_b128 v[144:147], v199 offset:35840
	ds_read_b128 v[216:219], v199 offset:36864
	ds_read_b128 v[220:223], v199 offset:37888
	ds_read_b128 v[224:227], v199 offset:38912
	ds_read_b128 v[228:231], v199 offset:39936
	global_load_lds_dwordx4 v[152:153], off
	v_lshl_add_u64 v[152:153], s[50:51], 0, v[184:185]
	s_mov_b32 m0, s60
	s_nop 0
	global_load_lds_dwordx4 v[152:153], off
	s_waitcnt vmcnt(8)
	s_waitcnt lgkmcnt(0)
	s_barrier
	s_setprio 1
	s_waitcnt lgkmcnt(0)
	v_mfma_f32_16x16x32_bf16 v[152:155], v[52:55], v[72:75], v[172:175]
	v_mfma_f32_16x16x32_bf16 v[172:175], v[56:59], v[104:107], v[152:155]
	v_mfma_f32_16x16x32_bf16 v[152:155], v[60:63], v[72:75], v[164:167]
	v_mfma_f32_16x16x32_bf16 v[164:167], v[64:67], v[104:107], v[152:155]
	v_mfma_f32_16x16x32_bf16 v[152:155], v[52:55], v[136:139], v[156:159]
	v_mfma_f32_16x16x32_bf16 v[148:151], v[60:63], v[136:139], v[148:151]
	v_mfma_f32_16x16x32_bf16 v[140:143], v[52:55], v[216:219], v[140:143]
	v_mfma_f32_16x16x32_bf16 v[132:135], v[60:63], v[216:219], v[132:135]
	v_mfma_f32_16x16x32_bf16 v[124:127], v[52:55], v[224:227], v[124:127]
	v_mfma_f32_16x16x32_bf16 v[120:123], v[60:63], v[224:227], v[120:123]
	v_mfma_f32_16x16x32_bf16 v[156:159], v[56:59], v[144:147], v[152:155]
	v_mfma_f32_16x16x32_bf16 v[148:151], v[64:67], v[144:147], v[148:151]
	v_mfma_f32_16x16x32_bf16 v[140:143], v[56:59], v[220:223], v[140:143]
	v_mfma_f32_16x16x32_bf16 v[132:135], v[64:67], v[220:223], v[132:135]
	v_mfma_f32_16x16x32_bf16 v[124:127], v[56:59], v[228:231], v[124:127]
	v_mfma_f32_16x16x32_bf16 v[120:123], v[64:67], v[228:231], v[120:123]
	v_mfma_f32_16x16x32_bf16 v[152:155], v[80:83], v[72:75], v[168:171]
	v_mfma_f32_16x16x32_bf16 v[72:75], v[176:179], v[72:75], v[88:91]
	v_mfma_f32_16x16x32_bf16 v[160:163], v[212:215], v[104:107], v[72:75]
	v_mfma_f32_16x16x32_bf16 v[72:75], v[80:83], v[136:139], v[92:95]
	v_mfma_f32_16x16x32_bf16 v[168:171], v[84:87], v[104:107], v[152:155]
	v_mfma_f32_16x16x32_bf16 v[152:155], v[84:87], v[144:147], v[72:75]
	v_mfma_f32_16x16x32_bf16 v[72:75], v[176:179], v[136:139], v[96:99]
	v_mfma_f32_16x16x32_bf16 v[144:147], v[212:215], v[144:147], v[72:75]
	v_mfma_f32_16x16x32_bf16 v[72:75], v[80:83], v[216:219], v[100:103]
	v_mfma_f32_16x16x32_bf16 v[136:139], v[84:87], v[220:223], v[72:75]
	v_mfma_f32_16x16x32_bf16 v[72:75], v[176:179], v[216:219], v[128:131]
	v_mfma_f32_16x16x32_bf16 v[128:131], v[212:215], v[220:223], v[72:75]
	v_mfma_f32_16x16x32_bf16 v[72:75], v[80:83], v[224:227], v[116:119]
	v_mfma_f32_16x16x32_bf16 v[116:119], v[84:87], v[228:231], v[72:75]
	v_mfma_f32_16x16x32_bf16 v[72:75], v[176:179], v[224:227], v[112:115]
	v_mfma_f32_16x16x32_bf16 v[112:115], v[212:215], v[228:231], v[72:75]
	s_setprio 0
	s_barrier
	s_add_i32 s50, s75, s56
	v_lshl_add_u64 v[104:105], v[232:233], 0, s[22:23]
	s_mov_b32 m0, s50
	s_nop 1
	ds_read_b128 v[72:75], v199 offset:49152
	ds_read_b128 v[88:91], v199 offset:50176
	ds_read_b128 v[92:95], v199 offset:51200
	ds_read_b128 v[96:99], v199 offset:52224
	ds_read_b128 v[100:103], v199 offset:53248
	ds_read_b128 v[216:219], v199 offset:54272
	ds_read_b128 v[220:223], v199 offset:55296
	ds_read_b128 v[224:227], v199 offset:56320
	global_load_lds_dwordx4 v[104:105], off
	s_add_i32 m0, s50, 0x2000
	s_add_u32 s48, s48, 0x80080
	v_lshl_add_u64 v[104:105], v[234:235], 0, s[22:23]
	s_addc_u32 s49, s49, 0
	s_add_i32 s50, s76, s56
	global_load_lds_dwordx4 v[104:105], off
	v_lshl_add_u64 v[104:105], s[48:49], 0, v[182:183]
	s_mov_b32 m0, s50
	s_nop 0
	global_load_lds_dwordx4 v[104:105], off
	v_lshl_add_u64 v[104:105], s[48:49], 0, v[186:187]
	s_add_i32 m0, s50, 0x2000
	s_nop 0
	global_load_lds_dwordx4 v[104:105], off
	v_lshl_add_u64 v[104:105], v[236:237], 0, s[22:23]
	s_mov_b32 m0, s63
	s_nop 0
	global_load_lds_dwordx4 v[104:105], off
	v_lshl_add_u64 v[104:105], v[238:239], 0, s[22:23]
	s_mov_b32 m0, s64
	s_nop 0
	global_load_lds_dwordx4 v[104:105], off
	s_waitcnt vmcnt(8)
	s_waitcnt lgkmcnt(0)
	s_barrier
	s_setprio 1
	s_waitcnt lgkmcnt(0)
	v_mfma_f32_16x16x32_bf16 v[104:107], v[52:55], v[72:75], v[108:111]
	v_mfma_f32_16x16x32_bf16 v[76:79], v[60:63], v[72:75], v[76:79]
	v_mfma_f32_16x16x32_bf16 v[68:71], v[52:55], v[92:95], v[68:71]
	v_mfma_f32_16x16x32_bf16 v[36:39], v[60:63], v[92:95], v[36:39]
	v_mfma_f32_16x16x32_bf16 v[28:31], v[52:55], v[100:103], v[28:31]
	v_mfma_f32_16x16x32_bf16 v[20:23], v[60:63], v[100:103], v[20:23]
	v_mfma_f32_16x16x32_bf16 v[12:15], v[52:55], v[220:223], v[12:15]
	v_mfma_f32_16x16x32_bf16 v[8:11], v[60:63], v[220:223], v[8:11]
	v_mfma_f32_16x16x32_bf16 v[108:111], v[56:59], v[88:91], v[104:107]
	v_mfma_f32_16x16x32_bf16 v[76:79], v[64:67], v[88:91], v[76:79]
	v_mfma_f32_16x16x32_bf16 v[68:71], v[56:59], v[96:99], v[68:71]
	v_mfma_f32_16x16x32_bf16 v[36:39], v[64:67], v[96:99], v[36:39]
	v_mfma_f32_16x16x32_bf16 v[28:31], v[56:59], v[216:219], v[28:31]
	v_mfma_f32_16x16x32_bf16 v[20:23], v[64:67], v[216:219], v[20:23]
	v_mfma_f32_16x16x32_bf16 v[12:15], v[56:59], v[224:227], v[12:15]
	v_mfma_f32_16x16x32_bf16 v[8:11], v[64:67], v[224:227], v[8:11]
	v_mfma_f32_16x16x32_bf16 v[44:47], v[80:83], v[72:75], v[44:47]
	v_mfma_f32_16x16x32_bf16 v[104:107], v[84:87], v[88:91], v[44:47]
	v_mfma_f32_16x16x32_bf16 v[44:47], v[176:179], v[72:75], v[48:51]
	v_mfma_f32_16x16x32_bf16 v[40:43], v[80:83], v[92:95], v[40:43]
	v_mfma_f32_16x16x32_bf16 v[32:35], v[176:179], v[92:95], v[32:35]
	v_mfma_f32_16x16x32_bf16 v[24:27], v[80:83], v[100:103], v[24:27]
	v_mfma_f32_16x16x32_bf16 v[16:19], v[176:179], v[100:103], v[16:19]
	v_mfma_f32_16x16x32_bf16 v[4:7], v[80:83], v[220:223], v[4:7]
	v_mfma_f32_16x16x32_bf16 v[0:3], v[176:179], v[220:223], v[0:3]
	v_mfma_f32_16x16x32_bf16 v[72:75], v[212:215], v[88:91], v[44:47]
	v_mfma_f32_16x16x32_bf16 v[40:43], v[84:87], v[96:99], v[40:43]
	v_mfma_f32_16x16x32_bf16 v[32:35], v[212:215], v[96:99], v[32:35]
	v_mfma_f32_16x16x32_bf16 v[24:27], v[84:87], v[216:219], v[24:27]
	v_mfma_f32_16x16x32_bf16 v[16:19], v[212:215], v[216:219], v[16:19]
	v_mfma_f32_16x16x32_bf16 v[4:7], v[84:87], v[224:227], v[4:7]
	v_mfma_f32_16x16x32_bf16 v[0:3], v[212:215], v[224:227], v[0:3]
	s_setprio 0
	s_barrier
	s_add_i32 s74, s74, 2
	s_add_u32 s46, s46, 0x100
	s_addc_u32 s47, s47, 0
	s_add_u32 s72, s72, 0x100
	s_addc_u32 s73, s73, 0
	s_cmp_gt_u32 s74, 29
	s_cbranch_scc0 .LBB0_479

; #define PG8_STAGE(bufoff, gbase, voff) do { _Pragma("unroll") for (int _i = 0; _i < 2; ++_i) \
;         __builtin_amdgcn_global_load_lds((const unsigned*)((const char*)(gbase) + (voff)[_i]), (PG8_LAS unsigned*)(lds + (bufoff) + ldsw + _i * 8192), 16, 0, 0); } while (0)
; #define PG8_LDA(dst, b, h) do { _Pragma("unroll") for (int m = 0; m < 4; ++m) _Pragma("unroll") for (int k = 0; k < 2; ++k) dst[m][k] = *(const PG8_LAS bf16x8*)(lds + PG8_SA(b, h) + aoff + m * 2048 + k * 1024); } while (0)
; #define PG8_LDB(dst, b, h) do { _Pragma("unroll") for (int n = 0; n < 2; ++n) _Pragma("unroll") for (int k = 0; k < 2; ++k) dst[n][k] = *(const PG8_LAS bf16x8*)(lds + PG8_SB(b, h) + boff + n * 2048 + k * 1024); } while (0)
; #define PG8_MMA(ai, bj, At, Bt) do { __builtin_amdgcn_s_setprio(1); _Pragma("unroll") for (int m = 0; m < 4; ++m) _Pragma("unroll") for (int n = 0; n < 2; ++n) _Pragma("unroll") for (int k = 0; k < 2; ++k) \
;         acc[ai][bj][m][n] = __builtin_amdgcn_mfma_f32_16x16x32_bf16(Bt[n][k], At[m][k], acc[ai][bj][m][n], 0, 0, 0); __builtin_amdgcn_s_setprio(0); } while (0)
; #define PG8_WAIT_V(n) asm volatile("s_waitcnt vmcnt(" #n ")" ::: "memory")
; #define PG8_WAIT_L(n) asm volatile("s_waitcnt lgkmcnt(" #n ")" ::: "memory")
; #define PG8_BAR __builtin_amdgcn_s_barrier()
; template <class Epi, class Sched, bool ALIGN_EPI = false, bool SP2 = false>
; __device__ __forceinline__ void gemm_phase(PG8_LAS unsigned char* lds, const Gemm g, const Sched& S, const Epi& E, const int wave_in) {
;     ...
;         for (int t = 0; t < nt; t += 2) {
;             const bool last = (t == nt - 2);
;             const char* a1 = cA + (size_t)(t + 1) * kstep;
;             const char* a2 = last ? nA : cA + (size_t)(t + 2) * kstep; const char* b2 = last ? nB : cB + (size_t)(t + 2) * kstep;
;             const char* a3 = a2 + kstep; const char* b3 = b2 + kstep;
;             if (last && has_next) S.a_ready(nxt);
;             if constexpr (SP2) {
;             PG8_LDB(B0, 0, 0); PG8_LDB(B1, 0, 1); PG8_SCHED; PG8_LDA(At, 0, 0); PG8_STAGE(PG8_SA(1, 1), a1 + hstepA, voffA);
;             PG8_WAIT_V(8); PG8_WAIT_L(0); PG8_BAR; PG8_MMA(0, 0, At, B0); PG8_MMA(0, 1, At, B1); PG8_BAR; PG8_SCHED;
;             PG8_LDA(At, 0, 1); PG8_STAGE(PG8_SB(0, 0), b2, voffB); PG8_STAGE(PG8_SB(0, 1), b2 + hstepB, voffB); PG8_STAGE(PG8_SA(0, 0), a2, voffA);
.LBB0_634:
	s_add_u32 s17, s20, 0x100
	v_mov_b32_e32 v0, 0
	s_addc_u32 s52, s21, 0
	s_mov_b32 s53, -2
	ds_read_b128 v[64:67], v230
	ds_read_b128 v[68:71], v230 offset:1024
	ds_read_b128 v[72:75], v230 offset:2048
	ds_read_b128 v[76:79], v230 offset:3072
	ds_read_b128 v[144:147], v231
	ds_read_b128 v[148:151], v231 offset:1024
	ds_read_b128 v[170:173], v231 offset:2048
	ds_read_b128 v[174:177], v231 offset:3072
	s_add_u32 s20, s18, 0x100
	s_addc_u32 s21, s19, 0
	s_cmpk_eq_i32 s53, 0x52
	s_cselect_b32 s25, s5, s21
	s_cselect_b32 s24, s4, s20
	s_cselect_b32 s23, s15, s52
	s_cselect_b32 s22, s14, s17
	v_lshl_add_u64 v[210:211], s[18:19], 0, v[162:163]
	s_add_i32 m0, s35, 0xc000
	ds_read_b128 v[178:181], v232
	ds_read_b128 v[182:185], v232 offset:1024
	ds_read_b128 v[186:189], v232 offset:2048
	ds_read_b128 v[190:193], v232 offset:3072
	ds_read_b128 v[194:197], v232 offset:4096
	ds_read_b128 v[198:201], v232 offset:5120
	ds_read_b128 v[202:205], v232 offset:6144
	ds_read_b128 v[206:209], v232 offset:7168
	global_load_lds_dwordx4 v[210:211], off
	v_lshl_add_u64 v[210:211], s[18:19], 0, v[164:165]
	s_add_i32 m0, s35, 0xe000
	s_nop 0
	global_load_lds_dwordx4 v[210:211], off
	s_waitcnt vmcnt(8)
	s_waitcnt lgkmcnt(0)
	s_barrier
	s_setprio 1
	s_waitcnt lgkmcnt(0)
	v_mfma_f32_16x16x32_bf16 v[140:143], v[64:67], v[178:181], 0
	v_mfma_f32_16x16x32_bf16 v[136:139], v[72:75], v[178:181], 0
	v_mfma_f32_16x16x32_bf16 v[128:131], v[64:67], v[186:189], 0
	v_mfma_f32_16x16x32_bf16 v[120:123], v[72:75], v[186:189], 0
	v_mfma_f32_16x16x32_bf16 v[116:119], v[64:67], v[194:197], 0
	v_mfma_f32_16x16x32_bf16 v[112:115], v[72:75], v[194:197], 0
	v_mfma_f32_16x16x32_bf16 v[100:103], v[64:67], v[202:205], 0
	v_mfma_f32_16x16x32_bf16 v[96:99], v[72:75], v[202:205], 0
	v_mfma_f32_16x16x32_bf16 v[140:143], v[68:71], v[182:185], v[140:143]
	v_mfma_f32_16x16x32_bf16 v[136:139], v[76:79], v[182:185], v[136:139]
	v_mfma_f32_16x16x32_bf16 v[128:131], v[68:71], v[190:193], v[128:131]
	v_mfma_f32_16x16x32_bf16 v[120:123], v[76:79], v[190:193], v[120:123]
	v_mfma_f32_16x16x32_bf16 v[116:119], v[68:71], v[198:201], v[116:119]
	v_mfma_f32_16x16x32_bf16 v[112:115], v[76:79], v[198:201], v[112:115]
	v_mfma_f32_16x16x32_bf16 v[100:103], v[68:71], v[206:209], v[100:103]
	v_mfma_f32_16x16x32_bf16 v[96:99], v[76:79], v[206:209], v[96:99]
	v_mfma_f32_16x16x32_bf16 v[132:135], v[144:147], v[178:181], 0
	v_mfma_f32_16x16x32_bf16 v[124:127], v[170:173], v[178:181], 0
	v_mfma_f32_16x16x32_bf16 v[108:111], v[144:147], v[186:189], 0
	v_mfma_f32_16x16x32_bf16 v[104:107], v[170:173], v[186:189], 0
	v_mfma_f32_16x16x32_bf16 v[92:95], v[144:147], v[194:197], 0
	v_mfma_f32_16x16x32_bf16 v[88:91], v[170:173], v[194:197], 0
	v_mfma_f32_16x16x32_bf16 v[84:87], v[144:147], v[202:205], 0
	v_mfma_f32_16x16x32_bf16 v[80:83], v[170:173], v[202:205], 0
	v_mfma_f32_16x16x32_bf16 v[132:135], v[148:151], v[182:185], v[132:135]
	v_mfma_f32_16x16x32_bf16 v[124:127], v[174:177], v[182:185], v[124:127]
	v_mfma_f32_16x16x32_bf16 v[108:111], v[148:151], v[190:193], v[108:111]
	v_mfma_f32_16x16x32_bf16 v[104:107], v[174:177], v[190:193], v[104:107]
	v_mfma_f32_16x16x32_bf16 v[92:95], v[148:151], v[198:201], v[92:95]
	v_mfma_f32_16x16x32_bf16 v[88:91], v[174:177], v[198:201], v[88:91]
	v_mfma_f32_16x16x32_bf16 v[84:87], v[148:151], v[206:209], v[84:87]
	v_mfma_f32_16x16x32_bf16 v[80:83], v[174:177], v[206:209], v[80:83]
	s_setprio 0
	s_barrier
	s_add_i32 s18, s45, s30
	v_lshl_add_u64 v[210:211], s[22:23], 0, v[156:157]
	s_mov_b32 m0, s18
	ds_read_b128 v[178:181], v232 offset:16384
	ds_read_b128 v[182:185], v232 offset:17408
	ds_read_b128 v[186:189], v232 offset:18432
	ds_read_b128 v[190:193], v232 offset:19456
	ds_read_b128 v[194:197], v232 offset:20480
	ds_read_b128 v[198:201], v232 offset:21504
	ds_read_b128 v[202:205], v232 offset:22528
	ds_read_b128 v[206:209], v232 offset:23552
	global_load_lds_dwordx4 v[210:211], off
	s_add_i32 m0, s18, 0x2000
	s_add_u32 s18, s22, 0x158000
	v_lshl_add_u64 v[212:213], s[22:23], 0, v[152:153]
	s_addc_u32 s19, s23, 0
	s_add_i32 s54, s46, s30
	global_load_lds_dwordx4 v[212:213], off
	v_lshl_add_u64 v[214:215], s[18:19], 0, v[156:157]
	s_mov_b32 m0, s54
	v_lshl_add_u64 v[216:217], s[24:25], 0, v[154:155]
	global_load_lds_dwordx4 v[214:215], off
	v_lshl_add_u64 v[214:215], s[18:19], 0, v[152:153]
	s_add_i32 m0, s54, 0x2000
	s_nop 0
	global_load_lds_dwordx4 v[214:215], off
	v_lshl_add_u64 v[214:215], s[24:25], 0, v[158:159]
	s_mov_b32 m0, s35
	s_nop 0
	global_load_lds_dwordx4 v[214:215], off
	s_mov_b32 m0, s36
	s_nop 0
	global_load_lds_dwordx4 v[216:217], off
	s_waitcnt vmcnt(8)
	s_waitcnt lgkmcnt(0)
	s_barrier
; #define PG8_STAGE(bufoff, gbase, voff) do { _Pragma("unroll") for (int _i = 0; _i < 2; ++_i) \
;         __builtin_amdgcn_global_load_lds((const unsigned*)((const char*)(gbase) + (voff)[_i]), (PG8_LAS unsigned*)(lds + (bufoff) + ldsw + _i * 8192), 16, 0, 0); } while (0)
; #define PG8_LDA(dst, b, h) do { _Pragma("unroll") for (int m = 0; m < 4; ++m) _Pragma("unroll") for (int k = 0; k < 2; ++k) dst[m][k] = *(const PG8_LAS bf16x8*)(lds + PG8_SA(b, h) + aoff + m * 2048 + k * 1024); } while (0)
; #define PG8_LDB(dst, b, h) do { _Pragma("unroll") for (int n = 0; n < 2; ++n) _Pragma("unroll") for (int k = 0; k < 2; ++k) dst[n][k] = *(const PG8_LAS bf16x8*)(lds + PG8_SB(b, h) + boff + n * 2048 + k * 1024); } while (0)
; #define PG8_MMA(ai, bj, At, Bt) do { __builtin_amdgcn_s_setprio(1); _Pragma("unroll") for (int m = 0; m < 4; ++m) _Pragma("unroll") for (int n = 0; n < 2; ++n) _Pragma("unroll") for (int k = 0; k < 2; ++k) \
;         acc[ai][bj][m][n] = __builtin_amdgcn_mfma_f32_16x16x32_bf16(Bt[n][k], At[m][k], acc[ai][bj][m][n], 0, 0, 0); __builtin_amdgcn_s_setprio(0); } while (0)
; #define PG8_WAIT_V(n) asm volatile("s_waitcnt vmcnt(" #n ")" ::: "memory")
; #define PG8_WAIT_L(n) asm volatile("s_waitcnt lgkmcnt(" #n ")" ::: "memory")
; #define PG8_BAR __builtin_amdgcn_s_barrier()
; #define PG8_SCHED __builtin_amdgcn_sched_barrier(0)
; template <class Epi, class Sched, bool ALIGN_EPI = false, bool SP2 = false>
; __device__ __forceinline__ void gemm_phase(PG8_LAS unsigned char* lds, const Gemm g, const Sched& S, const Epi& E, const int wave_in) {
;     ...
;             PG8_WAIT_V(8); PG8_WAIT_L(0); PG8_BAR; PG8_MMA(1, 0, At, B0); PG8_MMA(1, 1, At, B1); PG8_BAR; PG8_SCHED;
;             PG8_LDB(B0, 1, 0); PG8_LDB(B1, 1, 1); PG8_SCHED; PG8_LDA(At, 1, 0); PG8_STAGE(PG8_SA(0, 1), a2 + hstepA, voffA);
;             PG8_WAIT_V(8); PG8_WAIT_L(0); PG8_BAR; PG8_MMA(0, 0, At, B0); PG8_MMA(0, 1, At, B1); PG8_BAR; PG8_SCHED;
	s_setprio 1
	s_waitcnt lgkmcnt(0)
	v_mfma_f32_16x16x32_bf16 v[60:63], v[64:67], v[178:181], 0
	v_mfma_f32_16x16x32_bf16 v[56:59], v[72:75], v[178:181], 0
	v_mfma_f32_16x16x32_bf16 v[48:51], v[64:67], v[186:189], 0
	v_mfma_f32_16x16x32_bf16 v[40:43], v[72:75], v[186:189], 0
	v_mfma_f32_16x16x32_bf16 v[32:35], v[64:67], v[194:197], 0
	v_mfma_f32_16x16x32_bf16 v[24:27], v[72:75], v[194:197], 0
	v_mfma_f32_16x16x32_bf16 v[16:19], v[64:67], v[202:205], 0
	v_mfma_f32_16x16x32_bf16 v[8:11], v[72:75], v[202:205], 0
	v_mfma_f32_16x16x32_bf16 v[60:63], v[68:71], v[182:185], v[60:63]
	v_mfma_f32_16x16x32_bf16 v[56:59], v[76:79], v[182:185], v[56:59]
	v_mfma_f32_16x16x32_bf16 v[48:51], v[68:71], v[190:193], v[48:51]
	v_mfma_f32_16x16x32_bf16 v[40:43], v[76:79], v[190:193], v[40:43]
	v_mfma_f32_16x16x32_bf16 v[32:35], v[68:71], v[198:201], v[32:35]
	v_mfma_f32_16x16x32_bf16 v[24:27], v[76:79], v[198:201], v[24:27]
	v_mfma_f32_16x16x32_bf16 v[16:19], v[68:71], v[206:209], v[16:19]
	v_mfma_f32_16x16x32_bf16 v[8:11], v[76:79], v[206:209], v[8:11]
	v_mfma_f32_16x16x32_bf16 v[52:55], v[144:147], v[178:181], 0
	v_mfma_f32_16x16x32_bf16 v[44:47], v[170:173], v[178:181], 0
	v_mfma_f32_16x16x32_bf16 v[36:39], v[144:147], v[186:189], 0
	v_mfma_f32_16x16x32_bf16 v[28:31], v[170:173], v[186:189], 0
	v_mfma_f32_16x16x32_bf16 v[20:23], v[144:147], v[194:197], 0
	v_mfma_f32_16x16x32_bf16 v[12:15], v[170:173], v[194:197], 0
	v_mfma_f32_16x16x32_bf16 v[4:7], v[144:147], v[202:205], 0
	v_mfma_f32_16x16x32_bf16 v[0:3], v[170:173], v[202:205], 0
	v_mfma_f32_16x16x32_bf16 v[52:55], v[148:151], v[182:185], v[52:55]
	v_mfma_f32_16x16x32_bf16 v[44:47], v[174:177], v[182:185], v[44:47]
	v_mfma_f32_16x16x32_bf16 v[36:39], v[148:151], v[190:193], v[36:39]
	v_mfma_f32_16x16x32_bf16 v[28:31], v[174:177], v[190:193], v[28:31]
	v_mfma_f32_16x16x32_bf16 v[20:23], v[148:151], v[198:201], v[20:23]
	v_mfma_f32_16x16x32_bf16 v[12:15], v[174:177], v[198:201], v[12:15]
	v_mfma_f32_16x16x32_bf16 v[4:7], v[148:151], v[206:209], v[4:7]
	v_mfma_f32_16x16x32_bf16 v[0:3], v[174:177], v[206:209], v[0:3]
	s_setprio 0
	s_barrier
	s_add_i32 s54, 0, 0x18000
	s_add_i32 s55, 0, 0x1c000
	v_add_u32_e32 v76, s54, v228
	v_add_u32_e32 v174, s55, v228
	ds_read_b128 v[64:67], v76
	ds_read_b128 v[68:71], v76 offset:1024
	ds_read_b128 v[72:75], v76 offset:2048
	ds_read_b128 v[76:79], v76 offset:3072
	ds_read_b128 v[144:147], v174
	ds_read_b128 v[148:151], v174 offset:1024
	ds_read_b128 v[170:173], v174 offset:2048
	ds_read_b128 v[174:177], v174 offset:3072
	s_add_u32 s18, s24, 0x158000
	s_addc_u32 s19, s25, 0
	s_mov_b32 m0, s37
	v_lshl_add_u64 v[218:219], s[18:19], 0, v[158:159]
	ds_read_b128 v[178:181], v232 offset:32768
	ds_read_b128 v[182:185], v232 offset:33792
	ds_read_b128 v[186:189], v232 offset:34816
	ds_read_b128 v[190:193], v232 offset:35840
	ds_read_b128 v[194:197], v232 offset:36864
	ds_read_b128 v[198:201], v232 offset:37888
	ds_read_b128 v[202:205], v232 offset:38912
	ds_read_b128 v[206:209], v232 offset:39936
	global_load_lds_dwordx4 v[218:219], off
	v_lshl_add_u64 v[218:219], s[18:19], 0, v[154:155]
	s_mov_b32 m0, s38
	s_nop 0
	global_load_lds_dwordx4 v[218:219], off
	s_waitcnt vmcnt(8)
	s_waitcnt lgkmcnt(0)
	s_barrier
	s_setprio 1
	s_waitcnt lgkmcnt(0)
	v_mfma_f32_16x16x32_bf16 v[140:143], v[64:67], v[178:181], v[140:143]
	v_mfma_f32_16x16x32_bf16 v[136:139], v[72:75], v[178:181], v[136:139]
	v_mfma_f32_16x16x32_bf16 v[128:131], v[64:67], v[186:189], v[128:131]
	v_mfma_f32_16x16x32_bf16 v[120:123], v[72:75], v[186:189], v[120:123]
	v_mfma_f32_16x16x32_bf16 v[116:119], v[64:67], v[194:197], v[116:119]
	v_mfma_f32_16x16x32_bf16 v[112:115], v[72:75], v[194:197], v[112:115]
	v_mfma_f32_16x16x32_bf16 v[100:103], v[64:67], v[202:205], v[100:103]
	v_mfma_f32_16x16x32_bf16 v[96:99], v[72:75], v[202:205], v[96:99]
	v_mfma_f32_16x16x32_bf16 v[140:143], v[68:71], v[182:185], v[140:143]
	v_mfma_f32_16x16x32_bf16 v[136:139], v[76:79], v[182:185], v[136:139]
	v_mfma_f32_16x16x32_bf16 v[128:131], v[68:71], v[190:193], v[128:131]
	v_mfma_f32_16x16x32_bf16 v[120:123], v[76:79], v[190:193], v[120:123]
	v_mfma_f32_16x16x32_bf16 v[116:119], v[68:71], v[198:201], v[116:119]
	v_mfma_f32_16x16x32_bf16 v[112:115], v[76:79], v[198:201], v[112:115]
	v_mfma_f32_16x16x32_bf16 v[100:103], v[68:71], v[206:209], v[100:103]
	v_mfma_f32_16x16x32_bf16 v[96:99], v[76:79], v[206:209], v[96:99]
	v_mfma_f32_16x16x32_bf16 v[132:135], v[144:147], v[178:181], v[132:135]
	v_mfma_f32_16x16x32_bf16 v[124:127], v[170:173], v[178:181], v[124:127]
	v_mfma_f32_16x16x32_bf16 v[108:111], v[144:147], v[186:189], v[108:111]
	v_mfma_f32_16x16x32_bf16 v[104:107], v[170:173], v[186:189], v[104:107]
	v_mfma_f32_16x16x32_bf16 v[92:95], v[144:147], v[194:197], v[92:95]
	v_mfma_f32_16x16x32_bf16 v[88:91], v[170:173], v[194:197], v[88:91]
	v_mfma_f32_16x16x32_bf16 v[84:87], v[144:147], v[202:205], v[84:87]
	v_mfma_f32_16x16x32_bf16 v[80:83], v[170:173], v[202:205], v[80:83]
	v_mfma_f32_16x16x32_bf16 v[132:135], v[148:151], v[182:185], v[132:135]
	v_mfma_f32_16x16x32_bf16 v[124:127], v[174:177], v[182:185], v[124:127]
	v_mfma_f32_16x16x32_bf16 v[108:111], v[148:151], v[190:193], v[108:111]
	v_mfma_f32_16x16x32_bf16 v[104:107], v[174:177], v[190:193], v[104:107]
	v_mfma_f32_16x16x32_bf16 v[92:95], v[148:151], v[198:201], v[92:95]
	v_mfma_f32_16x16x32_bf16 v[88:91], v[174:177], v[198:201], v[88:91]
	v_mfma_f32_16x16x32_bf16 v[84:87], v[148:151], v[206:209], v[84:87]
	v_mfma_f32_16x16x32_bf16 v[80:83], v[174:177], v[206:209], v[80:83]
	s_setprio 0
	s_barrier
; #define PG8_STAGE(bufoff, gbase, voff) do { _Pragma("unroll") for (int _i = 0; _i < 2; ++_i) \
;         __builtin_amdgcn_global_load_lds((const unsigned*)((const char*)(gbase) + (voff)[_i]), (PG8_LAS unsigned*)(lds + (bufoff) + ldsw + _i * 8192), 16, 0, 0); } while (0)
; #define PG8_LDA(dst, b, h) do { _Pragma("unroll") for (int m = 0; m < 4; ++m) _Pragma("unroll") for (int k = 0; k < 2; ++k) dst[m][k] = *(const PG8_LAS bf16x8*)(lds + PG8_SA(b, h) + aoff + m * 2048 + k * 1024); } while (0)
; #define PG8_LDB(dst, b, h) do { _Pragma("unroll") for (int n = 0; n < 2; ++n) _Pragma("unroll") for (int k = 0; k < 2; ++k) dst[n][k] = *(const PG8_LAS bf16x8*)(lds + PG8_SB(b, h) + boff + n * 2048 + k * 1024); } while (0)
; #define PG8_MMA(ai, bj, At, Bt) do { __builtin_amdgcn_s_setprio(1); _Pragma("unroll") for (int m = 0; m < 4; ++m) _Pragma("unroll") for (int n = 0; n < 2; ++n) _Pragma("unroll") for (int k = 0; k < 2; ++k) \
;         acc[ai][bj][m][n] = __builtin_amdgcn_mfma_f32_16x16x32_bf16(Bt[n][k], At[m][k], acc[ai][bj][m][n], 0, 0, 0); __builtin_amdgcn_s_setprio(0); } while (0)
; #define PG8_WAIT_V(n) asm volatile("s_waitcnt vmcnt(" #n ")" ::: "memory")
; #define PG8_WAIT_L(n) asm volatile("s_waitcnt lgkmcnt(" #n ")" ::: "memory")
; #define PG8_BAR __builtin_amdgcn_s_barrier()
; template <class Epi, class Sched, bool ALIGN_EPI = false, bool SP2 = false>
; __device__ __forceinline__ void gemm_phase(PG8_LAS unsigned char* lds, const Gemm g, const Sched& S, const Epi& E, const int wave_in) {
;     ...
;         for (int t = 0; t < nt; t += 2) {
;             const bool last = (t == nt - 2);
;             const char* a1 = cA + (size_t)(t + 1) * kstep;
;             const char* a2 = last ? nA : cA + (size_t)(t + 2) * kstep; const char* b2 = last ? nB : cB + (size_t)(t + 2) * kstep;
;             const char* a3 = a2 + kstep; const char* b3 = b2 + kstep;
;             if (last && has_next) S.a_ready(nxt);
;             if constexpr (SP2) {
;             PG8_LDB(B0, 0, 0); PG8_LDB(B1, 0, 1); PG8_SCHED; PG8_LDA(At, 0, 0); PG8_STAGE(PG8_SA(1, 1), a1 + hstepA, voffA);
;     ...
;             PG8_LDA(At, 1, 1); PG8_STAGE(PG8_SB(1, 0), b3, voffB); PG8_STAGE(PG8_SB(1, 1), b3 + hstepB, voffB); PG8_STAGE(PG8_SA(1, 0), a3, voffA);
;             PG8_WAIT_V(8); PG8_WAIT_L(0); PG8_BAR; PG8_MMA(1, 0, At, B0); PG8_MMA(1, 1, At, B1); PG8_BAR; PG8_SCHED;
	s_add_i32 s18, s54, s30
	v_lshl_add_u64 v[210:211], v[210:211], 0, s[6:7]
	s_mov_b32 m0, s18
	ds_read_b128 v[178:181], v232 offset:49152
	ds_read_b128 v[182:185], v232 offset:50176
	ds_read_b128 v[186:189], v232 offset:51200
	ds_read_b128 v[190:193], v232 offset:52224
	ds_read_b128 v[194:197], v232 offset:53248
	ds_read_b128 v[198:201], v232 offset:54272
	ds_read_b128 v[202:205], v232 offset:55296
	ds_read_b128 v[206:209], v232 offset:56320
	global_load_lds_dwordx4 v[210:211], off
	s_add_i32 m0, s18, 0x2000
	s_add_u32 s18, s22, 0x158080
	v_lshl_add_u64 v[210:211], v[212:213], 0, s[6:7]
	s_addc_u32 s19, s23, 0
	s_add_i32 s22, s55, s30
	global_load_lds_dwordx4 v[210:211], off
	v_lshl_add_u64 v[210:211], s[18:19], 0, v[156:157]
	s_mov_b32 m0, s22
	s_nop 0
	global_load_lds_dwordx4 v[210:211], off
	v_lshl_add_u64 v[210:211], s[18:19], 0, v[152:153]
	s_add_i32 m0, s22, 0x2000
	s_nop 0
	global_load_lds_dwordx4 v[210:211], off
	v_lshl_add_u64 v[210:211], v[214:215], 0, s[6:7]
	s_mov_b32 m0, s42
	s_nop 0
	global_load_lds_dwordx4 v[210:211], off
	v_lshl_add_u64 v[210:211], v[216:217], 0, s[6:7]
	s_mov_b32 m0, s43
	s_nop 0
	global_load_lds_dwordx4 v[210:211], off
	s_waitcnt vmcnt(8)
	s_waitcnt lgkmcnt(0)
	s_barrier
	s_setprio 1
	s_waitcnt lgkmcnt(0)
	v_mfma_f32_16x16x32_bf16 v[60:63], v[64:67], v[178:181], v[60:63]
	v_mfma_f32_16x16x32_bf16 v[56:59], v[72:75], v[178:181], v[56:59]
	v_mfma_f32_16x16x32_bf16 v[48:51], v[64:67], v[186:189], v[48:51]
	v_mfma_f32_16x16x32_bf16 v[40:43], v[72:75], v[186:189], v[40:43]
	v_mfma_f32_16x16x32_bf16 v[32:35], v[64:67], v[194:197], v[32:35]
	v_mfma_f32_16x16x32_bf16 v[24:27], v[72:75], v[194:197], v[24:27]
	v_mfma_f32_16x16x32_bf16 v[16:19], v[64:67], v[202:205], v[16:19]
	v_mfma_f32_16x16x32_bf16 v[8:11], v[72:75], v[202:205], v[8:11]
	v_mfma_f32_16x16x32_bf16 v[60:63], v[68:71], v[182:185], v[60:63]
	v_mfma_f32_16x16x32_bf16 v[56:59], v[76:79], v[182:185], v[56:59]
	v_mfma_f32_16x16x32_bf16 v[48:51], v[68:71], v[190:193], v[48:51]
	v_mfma_f32_16x16x32_bf16 v[40:43], v[76:79], v[190:193], v[40:43]
	v_mfma_f32_16x16x32_bf16 v[32:35], v[68:71], v[198:201], v[32:35]
	v_mfma_f32_16x16x32_bf16 v[24:27], v[76:79], v[198:201], v[24:27]
	v_mfma_f32_16x16x32_bf16 v[16:19], v[68:71], v[206:209], v[16:19]
	v_mfma_f32_16x16x32_bf16 v[8:11], v[76:79], v[206:209], v[8:11]
	v_mfma_f32_16x16x32_bf16 v[52:55], v[144:147], v[178:181], v[52:55]
	v_mfma_f32_16x16x32_bf16 v[44:47], v[170:173], v[178:181], v[44:47]
	v_mfma_f32_16x16x32_bf16 v[36:39], v[144:147], v[186:189], v[36:39]
	v_mfma_f32_16x16x32_bf16 v[28:31], v[170:173], v[186:189], v[28:31]
	v_mfma_f32_16x16x32_bf16 v[20:23], v[144:147], v[194:197], v[20:23]
	v_mfma_f32_16x16x32_bf16 v[12:15], v[170:173], v[194:197], v[12:15]
	v_mfma_f32_16x16x32_bf16 v[4:7], v[144:147], v[202:205], v[4:7]
	v_mfma_f32_16x16x32_bf16 v[0:3], v[170:173], v[202:205], v[0:3]
	v_mfma_f32_16x16x32_bf16 v[52:55], v[148:151], v[182:185], v[52:55]
	v_mfma_f32_16x16x32_bf16 v[44:47], v[174:177], v[182:185], v[44:47]
	v_mfma_f32_16x16x32_bf16 v[36:39], v[148:151], v[190:193], v[36:39]
	v_mfma_f32_16x16x32_bf16 v[28:31], v[174:177], v[190:193], v[28:31]
	v_mfma_f32_16x16x32_bf16 v[20:23], v[148:151], v[198:201], v[20:23]
	v_mfma_f32_16x16x32_bf16 v[12:15], v[174:177], v[198:201], v[12:15]
	v_mfma_f32_16x16x32_bf16 v[4:7], v[148:151], v[206:209], v[4:7]
	v_mfma_f32_16x16x32_bf16 v[0:3], v[174:177], v[206:209], v[0:3]
	s_setprio 0
	s_barrier
	s_add_i32 s53, s53, 2
	s_add_u32 s17, s17, 0x100
	s_addc_u32 s52, s52, 0
	s_cmpk_gt_u32 s53, 0x53
	s_mov_b64 s[18:19], s[20:21]
	s_cbranch_scc0 .LBB0_635
	s_branch .Lkx_8
.LBB0_635:
	ds_read_b128 v[64:67], v230
	ds_read_b128 v[68:71], v230 offset:1024
	ds_read_b128 v[72:75], v230 offset:2048
	ds_read_b128 v[76:79], v230 offset:3072
	ds_read_b128 v[144:147], v231
	ds_read_b128 v[148:151], v231 offset:1024
	ds_read_b128 v[170:173], v231 offset:2048
	ds_read_b128 v[174:177], v231 offset:3072
	s_add_u32 s20, s18, 0x100
	s_addc_u32 s21, s19, 0
	s_cmpk_eq_i32 s53, 0x52
	s_cselect_b32 s25, s5, s21
	s_cselect_b32 s24, s4, s20
	s_cselect_b32 s23, s15, s52
	s_cselect_b32 s22, s14, s17
	v_lshl_add_u64 v[210:211], s[18:19], 0, v[162:163]
	s_add_i32 m0, s35, 0xc000
	ds_read_b128 v[178:181], v232
	ds_read_b128 v[182:185], v232 offset:1024
	ds_read_b128 v[186:189], v232 offset:2048
	ds_read_b128 v[190:193], v232 offset:3072
	ds_read_b128 v[194:197], v232 offset:4096
	ds_read_b128 v[198:201], v232 offset:5120
	ds_read_b128 v[202:205], v232 offset:6144
	ds_read_b128 v[206:209], v232 offset:7168
	global_load_lds_dwordx4 v[210:211], off
	v_lshl_add_u64 v[210:211], s[18:19], 0, v[164:165]
	s_add_i32 m0, s35, 0xe000
	s_nop 0
	global_load_lds_dwordx4 v[210:211], off
	s_waitcnt vmcnt(8)
	s_waitcnt lgkmcnt(0)
	s_barrier
; #define PG8_STAGE(bufoff, gbase, voff) do { _Pragma("unroll") for (int _i = 0; _i < 2; ++_i) \
;         __builtin_amdgcn_global_load_lds((const unsigned*)((const char*)(gbase) + (voff)[_i]), (PG8_LAS unsigned*)(lds + (bufoff) + ldsw + _i * 8192), 16, 0, 0); } while (0)
; #define PG8_LDA(dst, b, h) do { _Pragma("unroll") for (int m = 0; m < 4; ++m) _Pragma("unroll") for (int k = 0; k < 2; ++k) dst[m][k] = *(const PG8_LAS bf16x8*)(lds + PG8_SA(b, h) + aoff + m * 2048 + k * 1024); } while (0)
; #define PG8_MMA(ai, bj, At, Bt) do { __builtin_amdgcn_s_setprio(1); _Pragma("unroll") for (int m = 0; m < 4; ++m) _Pragma("unroll") for (int n = 0; n < 2; ++n) _Pragma("unroll") for (int k = 0; k < 2; ++k) \
;         acc[ai][bj][m][n] = __builtin_amdgcn_mfma_f32_16x16x32_bf16(Bt[n][k], At[m][k], acc[ai][bj][m][n], 0, 0, 0); __builtin_amdgcn_s_setprio(0); } while (0)
; #define PG8_WAIT_V(n) asm volatile("s_waitcnt vmcnt(" #n ")" ::: "memory")
; #define PG8_WAIT_L(n) asm volatile("s_waitcnt lgkmcnt(" #n ")" ::: "memory")
; #define PG8_BAR __builtin_amdgcn_s_barrier()
; #define PG8_SCHED __builtin_amdgcn_sched_barrier(0)
; template <class Epi, class Sched, bool ALIGN_EPI = false, bool SP2 = false>
; __device__ __forceinline__ void gemm_phase(PG8_LAS unsigned char* lds, const Gemm g, const Sched& S, const Epi& E, const int wave_in) {
;     ...
;             PG8_WAIT_V(8); PG8_WAIT_L(0); PG8_BAR; PG8_MMA(0, 0, At, B0); PG8_MMA(0, 1, At, B1); PG8_BAR; PG8_SCHED;
;             PG8_LDA(At, 0, 1); PG8_STAGE(PG8_SB(0, 0), b2, voffB); PG8_STAGE(PG8_SB(0, 1), b2 + hstepB, voffB); PG8_STAGE(PG8_SA(0, 0), a2, voffA);
;             PG8_WAIT_V(8); PG8_WAIT_L(0); PG8_BAR; PG8_MMA(1, 0, At, B0); PG8_MMA(1, 1, At, B1); PG8_BAR; PG8_SCHED;
	s_setprio 1
	s_waitcnt lgkmcnt(0)
	v_mfma_f32_16x16x32_bf16 v[140:143], v[64:67], v[178:181], v[140:143]
	v_mfma_f32_16x16x32_bf16 v[136:139], v[72:75], v[178:181], v[136:139]
	v_mfma_f32_16x16x32_bf16 v[128:131], v[64:67], v[186:189], v[128:131]
	v_mfma_f32_16x16x32_bf16 v[120:123], v[72:75], v[186:189], v[120:123]
	v_mfma_f32_16x16x32_bf16 v[116:119], v[64:67], v[194:197], v[116:119]
	v_mfma_f32_16x16x32_bf16 v[112:115], v[72:75], v[194:197], v[112:115]
	v_mfma_f32_16x16x32_bf16 v[100:103], v[64:67], v[202:205], v[100:103]
	v_mfma_f32_16x16x32_bf16 v[96:99], v[72:75], v[202:205], v[96:99]
	v_mfma_f32_16x16x32_bf16 v[140:143], v[68:71], v[182:185], v[140:143]
	v_mfma_f32_16x16x32_bf16 v[136:139], v[76:79], v[182:185], v[136:139]
	v_mfma_f32_16x16x32_bf16 v[128:131], v[68:71], v[190:193], v[128:131]
	v_mfma_f32_16x16x32_bf16 v[120:123], v[76:79], v[190:193], v[120:123]
	v_mfma_f32_16x16x32_bf16 v[116:119], v[68:71], v[198:201], v[116:119]
	v_mfma_f32_16x16x32_bf16 v[112:115], v[76:79], v[198:201], v[112:115]
	v_mfma_f32_16x16x32_bf16 v[100:103], v[68:71], v[206:209], v[100:103]
	v_mfma_f32_16x16x32_bf16 v[96:99], v[76:79], v[206:209], v[96:99]
	v_mfma_f32_16x16x32_bf16 v[132:135], v[144:147], v[178:181], v[132:135]
	v_mfma_f32_16x16x32_bf16 v[124:127], v[170:173], v[178:181], v[124:127]
	v_mfma_f32_16x16x32_bf16 v[108:111], v[144:147], v[186:189], v[108:111]
	v_mfma_f32_16x16x32_bf16 v[104:107], v[170:173], v[186:189], v[104:107]
	v_mfma_f32_16x16x32_bf16 v[92:95], v[144:147], v[194:197], v[92:95]
	v_mfma_f32_16x16x32_bf16 v[88:91], v[170:173], v[194:197], v[88:91]
	v_mfma_f32_16x16x32_bf16 v[84:87], v[144:147], v[202:205], v[84:87]
	v_mfma_f32_16x16x32_bf16 v[80:83], v[170:173], v[202:205], v[80:83]
	v_mfma_f32_16x16x32_bf16 v[132:135], v[148:151], v[182:185], v[132:135]
	v_mfma_f32_16x16x32_bf16 v[124:127], v[174:177], v[182:185], v[124:127]
	v_mfma_f32_16x16x32_bf16 v[108:111], v[148:151], v[190:193], v[108:111]
	v_mfma_f32_16x16x32_bf16 v[104:107], v[174:177], v[190:193], v[104:107]
	v_mfma_f32_16x16x32_bf16 v[92:95], v[148:151], v[198:201], v[92:95]
	v_mfma_f32_16x16x32_bf16 v[88:91], v[174:177], v[198:201], v[88:91]
	v_mfma_f32_16x16x32_bf16 v[84:87], v[148:151], v[206:209], v[84:87]
	v_mfma_f32_16x16x32_bf16 v[80:83], v[174:177], v[206:209], v[80:83]
	s_setprio 0
	s_barrier
	s_add_i32 s18, s45, s30
	v_lshl_add_u64 v[210:211], s[22:23], 0, v[156:157]
	s_mov_b32 m0, s18
	ds_read_b128 v[178:181], v232 offset:16384
	ds_read_b128 v[182:185], v232 offset:17408
	ds_read_b128 v[186:189], v232 offset:18432
	ds_read_b128 v[190:193], v232 offset:19456
	ds_read_b128 v[194:197], v232 offset:20480
	ds_read_b128 v[198:201], v232 offset:21504
	ds_read_b128 v[202:205], v232 offset:22528
	ds_read_b128 v[206:209], v232 offset:23552
	global_load_lds_dwordx4 v[210:211], off
	s_add_i32 m0, s18, 0x2000
	s_add_u32 s18, s22, 0x158000
	v_lshl_add_u64 v[212:213], s[22:23], 0, v[152:153]
	s_addc_u32 s19, s23, 0
	s_add_i32 s54, s46, s30
	global_load_lds_dwordx4 v[212:213], off
	v_lshl_add_u64 v[214:215], s[18:19], 0, v[156:157]
	s_mov_b32 m0, s54
	v_lshl_add_u64 v[216:217], s[24:25], 0, v[154:155]
	global_load_lds_dwordx4 v[214:215], off
	v_lshl_add_u64 v[214:215], s[18:19], 0, v[152:153]
	s_add_i32 m0, s54, 0x2000
	s_nop 0
	global_load_lds_dwordx4 v[214:215], off
	v_lshl_add_u64 v[214:215], s[24:25], 0, v[158:159]
	s_mov_b32 m0, s35
	s_nop 0
	global_load_lds_dwordx4 v[214:215], off
	s_mov_b32 m0, s36
	s_nop 0
	global_load_lds_dwordx4 v[216:217], off
	s_waitcnt vmcnt(8)
	s_waitcnt lgkmcnt(0)
	s_barrier
	s_setprio 1
	s_waitcnt lgkmcnt(0)
	v_mfma_f32_16x16x32_bf16 v[60:63], v[64:67], v[178:181], v[60:63]
	v_mfma_f32_16x16x32_bf16 v[56:59], v[72:75], v[178:181], v[56:59]
	v_mfma_f32_16x16x32_bf16 v[48:51], v[64:67], v[186:189], v[48:51]
	v_mfma_f32_16x16x32_bf16 v[40:43], v[72:75], v[186:189], v[40:43]
	v_mfma_f32_16x16x32_bf16 v[32:35], v[64:67], v[194:197], v[32:35]
	v_mfma_f32_16x16x32_bf16 v[24:27], v[72:75], v[194:197], v[24:27]
	v_mfma_f32_16x16x32_bf16 v[16:19], v[64:67], v[202:205], v[16:19]
	v_mfma_f32_16x16x32_bf16 v[8:11], v[72:75], v[202:205], v[8:11]
	v_mfma_f32_16x16x32_bf16 v[60:63], v[68:71], v[182:185], v[60:63]
	v_mfma_f32_16x16x32_bf16 v[56:59], v[76:79], v[182:185], v[56:59]
	v_mfma_f32_16x16x32_bf16 v[48:51], v[68:71], v[190:193], v[48:51]
	v_mfma_f32_16x16x32_bf16 v[40:43], v[76:79], v[190:193], v[40:43]
	v_mfma_f32_16x16x32_bf16 v[32:35], v[68:71], v[198:201], v[32:35]
	v_mfma_f32_16x16x32_bf16 v[24:27], v[76:79], v[198:201], v[24:27]
	v_mfma_f32_16x16x32_bf16 v[16:19], v[68:71], v[206:209], v[16:19]
	v_mfma_f32_16x16x32_bf16 v[8:11], v[76:79], v[206:209], v[8:11]
	v_mfma_f32_16x16x32_bf16 v[52:55], v[144:147], v[178:181], v[52:55]
	v_mfma_f32_16x16x32_bf16 v[44:47], v[170:173], v[178:181], v[44:47]
	v_mfma_f32_16x16x32_bf16 v[36:39], v[144:147], v[186:189], v[36:39]
	v_mfma_f32_16x16x32_bf16 v[28:31], v[170:173], v[186:189], v[28:31]
	v_mfma_f32_16x16x32_bf16 v[20:23], v[144:147], v[194:197], v[20:23]
	v_mfma_f32_16x16x32_bf16 v[12:15], v[170:173], v[194:197], v[12:15]
	v_mfma_f32_16x16x32_bf16 v[4:7], v[144:147], v[202:205], v[4:7]
	v_mfma_f32_16x16x32_bf16 v[0:3], v[170:173], v[202:205], v[0:3]
	v_mfma_f32_16x16x32_bf16 v[52:55], v[148:151], v[182:185], v[52:55]
	v_mfma_f32_16x16x32_bf16 v[44:47], v[174:177], v[182:185], v[44:47]
	v_mfma_f32_16x16x32_bf16 v[36:39], v[148:151], v[190:193], v[36:39]
	v_mfma_f32_16x16x32_bf16 v[28:31], v[174:177], v[190:193], v[28:31]
	v_mfma_f32_16x16x32_bf16 v[20:23], v[148:151], v[198:201], v[20:23]
	v_mfma_f32_16x16x32_bf16 v[12:15], v[174:177], v[198:201], v[12:15]
	v_mfma_f32_16x16x32_bf16 v[4:7], v[148:151], v[206:209], v[4:7]
	v_mfma_f32_16x16x32_bf16 v[0:3], v[174:177], v[206:209], v[0:3]
	s_setprio 0
	s_barrier
; #define PG8_STAGE(bufoff, gbase, voff) do { _Pragma("unroll") for (int _i = 0; _i < 2; ++_i) \
;         __builtin_amdgcn_global_load_lds((const unsigned*)((const char*)(gbase) + (voff)[_i]), (PG8_LAS unsigned*)(lds + (bufoff) + ldsw + _i * 8192), 16, 0, 0); } while (0)
; #define PG8_LDA(dst, b, h) do { _Pragma("unroll") for (int m = 0; m < 4; ++m) _Pragma("unroll") for (int k = 0; k < 2; ++k) dst[m][k] = *(const PG8_LAS bf16x8*)(lds + PG8_SA(b, h) + aoff + m * 2048 + k * 1024); } while (0)
; #define PG8_LDB(dst, b, h) do { _Pragma("unroll") for (int n = 0; n < 2; ++n) _Pragma("unroll") for (int k = 0; k < 2; ++k) dst[n][k] = *(const PG8_LAS bf16x8*)(lds + PG8_SB(b, h) + boff + n * 2048 + k * 1024); } while (0)
; #define PG8_MMA(ai, bj, At, Bt) do { __builtin_amdgcn_s_setprio(1); _Pragma("unroll") for (int m = 0; m < 4; ++m) _Pragma("unroll") for (int n = 0; n < 2; ++n) _Pragma("unroll") for (int k = 0; k < 2; ++k) \
;         acc[ai][bj][m][n] = __builtin_amdgcn_mfma_f32_16x16x32_bf16(Bt[n][k], At[m][k], acc[ai][bj][m][n], 0, 0, 0); __builtin_amdgcn_s_setprio(0); } while (0)
; #define PG8_WAIT_V(n) asm volatile("s_waitcnt vmcnt(" #n ")" ::: "memory")
; #define PG8_WAIT_L(n) asm volatile("s_waitcnt lgkmcnt(" #n ")" ::: "memory")
; #define PG8_BAR __builtin_amdgcn_s_barrier()
; #define PG8_SCHED __builtin_amdgcn_sched_barrier(0)
; template <class Epi, class Sched, bool ALIGN_EPI = false, bool SP2 = false>
; __device__ __forceinline__ void gemm_phase(PG8_LAS unsigned char* lds, const Gemm g, const Sched& S, const Epi& E, const int wave_in) {
;     ...
;             PG8_LDB(B0, 1, 0); PG8_LDB(B1, 1, 1); PG8_SCHED; PG8_LDA(At, 1, 0); PG8_STAGE(PG8_SA(0, 1), a2 + hstepA, voffA);
;             PG8_WAIT_V(8); PG8_WAIT_L(0); PG8_BAR; PG8_MMA(0, 0, At, B0); PG8_MMA(0, 1, At, B1); PG8_BAR; PG8_SCHED;
;             PG8_LDA(At, 1, 1); PG8_STAGE(PG8_SB(1, 0), b3, voffB); PG8_STAGE(PG8_SB(1, 1), b3 + hstepB, voffB); PG8_STAGE(PG8_SA(1, 0), a3, voffA);
;             PG8_WAIT_V(8); PG8_WAIT_L(0); PG8_BAR; PG8_MMA(1, 0, At, B0); PG8_MMA(1, 1, At, B1); PG8_BAR; PG8_SCHED;
	s_add_i32 s54, 0, 0x18000
	s_add_i32 s55, 0, 0x1c000
	v_add_u32_e32 v76, s54, v228
	v_add_u32_e32 v174, s55, v228
	ds_read_b128 v[64:67], v76
	ds_read_b128 v[68:71], v76 offset:1024
	ds_read_b128 v[72:75], v76 offset:2048
	ds_read_b128 v[76:79], v76 offset:3072
	ds_read_b128 v[144:147], v174
	ds_read_b128 v[148:151], v174 offset:1024
	ds_read_b128 v[170:173], v174 offset:2048
	ds_read_b128 v[174:177], v174 offset:3072
	s_add_u32 s18, s24, 0x158000
	s_addc_u32 s19, s25, 0
	s_mov_b32 m0, s37
	v_lshl_add_u64 v[218:219], s[18:19], 0, v[158:159]
	ds_read_b128 v[178:181], v232 offset:32768
	ds_read_b128 v[182:185], v232 offset:33792
	ds_read_b128 v[186:189], v232 offset:34816
	ds_read_b128 v[190:193], v232 offset:35840
	ds_read_b128 v[194:197], v232 offset:36864
	ds_read_b128 v[198:201], v232 offset:37888
	ds_read_b128 v[202:205], v232 offset:38912
	ds_read_b128 v[206:209], v232 offset:39936
	global_load_lds_dwordx4 v[218:219], off
	v_lshl_add_u64 v[218:219], s[18:19], 0, v[154:155]
	s_mov_b32 m0, s38
	s_nop 0
	global_load_lds_dwordx4 v[218:219], off
	s_waitcnt vmcnt(8)
	s_waitcnt lgkmcnt(0)
	s_barrier
	s_setprio 1
	s_waitcnt lgkmcnt(0)
	v_mfma_f32_16x16x32_bf16 v[140:143], v[64:67], v[178:181], v[140:143]
	v_mfma_f32_16x16x32_bf16 v[136:139], v[72:75], v[178:181], v[136:139]
	v_mfma_f32_16x16x32_bf16 v[128:131], v[64:67], v[186:189], v[128:131]
	v_mfma_f32_16x16x32_bf16 v[120:123], v[72:75], v[186:189], v[120:123]
	v_mfma_f32_16x16x32_bf16 v[116:119], v[64:67], v[194:197], v[116:119]
	v_mfma_f32_16x16x32_bf16 v[112:115], v[72:75], v[194:197], v[112:115]
	v_mfma_f32_16x16x32_bf16 v[100:103], v[64:67], v[202:205], v[100:103]
	v_mfma_f32_16x16x32_bf16 v[96:99], v[72:75], v[202:205], v[96:99]
	v_mfma_f32_16x16x32_bf16 v[140:143], v[68:71], v[182:185], v[140:143]
	v_mfma_f32_16x16x32_bf16 v[136:139], v[76:79], v[182:185], v[136:139]
	v_mfma_f32_16x16x32_bf16 v[128:131], v[68:71], v[190:193], v[128:131]
	v_mfma_f32_16x16x32_bf16 v[120:123], v[76:79], v[190:193], v[120:123]
	v_mfma_f32_16x16x32_bf16 v[116:119], v[68:71], v[198:201], v[116:119]
	v_mfma_f32_16x16x32_bf16 v[112:115], v[76:79], v[198:201], v[112:115]
	v_mfma_f32_16x16x32_bf16 v[100:103], v[68:71], v[206:209], v[100:103]
	v_mfma_f32_16x16x32_bf16 v[96:99], v[76:79], v[206:209], v[96:99]
	v_mfma_f32_16x16x32_bf16 v[132:135], v[144:147], v[178:181], v[132:135]
	v_mfma_f32_16x16x32_bf16 v[124:127], v[170:173], v[178:181], v[124:127]
	v_mfma_f32_16x16x32_bf16 v[108:111], v[144:147], v[186:189], v[108:111]
	v_mfma_f32_16x16x32_bf16 v[104:107], v[170:173], v[186:189], v[104:107]
	v_mfma_f32_16x16x32_bf16 v[92:95], v[144:147], v[194:197], v[92:95]
	v_mfma_f32_16x16x32_bf16 v[88:91], v[170:173], v[194:197], v[88:91]
	v_mfma_f32_16x16x32_bf16 v[84:87], v[144:147], v[202:205], v[84:87]
	v_mfma_f32_16x16x32_bf16 v[80:83], v[170:173], v[202:205], v[80:83]
	v_mfma_f32_16x16x32_bf16 v[132:135], v[148:151], v[182:185], v[132:135]
	v_mfma_f32_16x16x32_bf16 v[124:127], v[174:177], v[182:185], v[124:127]
	v_mfma_f32_16x16x32_bf16 v[108:111], v[148:151], v[190:193], v[108:111]
	v_mfma_f32_16x16x32_bf16 v[104:107], v[174:177], v[190:193], v[104:107]
	v_mfma_f32_16x16x32_bf16 v[92:95], v[148:151], v[198:201], v[92:95]
	v_mfma_f32_16x16x32_bf16 v[88:91], v[174:177], v[198:201], v[88:91]
	v_mfma_f32_16x16x32_bf16 v[84:87], v[148:151], v[206:209], v[84:87]
	v_mfma_f32_16x16x32_bf16 v[80:83], v[174:177], v[206:209], v[80:83]
	s_setprio 0
	s_barrier
	s_add_i32 s18, s54, s30
	v_lshl_add_u64 v[210:211], v[210:211], 0, s[6:7]
	s_mov_b32 m0, s18
	ds_read_b128 v[178:181], v232 offset:49152
	ds_read_b128 v[182:185], v232 offset:50176
	ds_read_b128 v[186:189], v232 offset:51200
	ds_read_b128 v[190:193], v232 offset:52224
	ds_read_b128 v[194:197], v232 offset:53248
	ds_read_b128 v[198:201], v232 offset:54272
	ds_read_b128 v[202:205], v232 offset:55296
	ds_read_b128 v[206:209], v232 offset:56320
	global_load_lds_dwordx4 v[210:211], off
	s_add_i32 m0, s18, 0x2000
	s_add_u32 s18, s22, 0x158080
	v_lshl_add_u64 v[210:211], v[212:213], 0, s[6:7]
	s_addc_u32 s19, s23, 0
	s_add_i32 s22, s55, s30
	global_load_lds_dwordx4 v[210:211], off
	v_lshl_add_u64 v[210:211], s[18:19], 0, v[156:157]
	s_mov_b32 m0, s22
	s_nop 0
	global_load_lds_dwordx4 v[210:211], off
	v_lshl_add_u64 v[210:211], s[18:19], 0, v[152:153]
	s_add_i32 m0, s22, 0x2000
	s_nop 0
	global_load_lds_dwordx4 v[210:211], off
	v_lshl_add_u64 v[210:211], v[214:215], 0, s[6:7]
	s_mov_b32 m0, s42
	s_nop 0
	global_load_lds_dwordx4 v[210:211], off
	v_lshl_add_u64 v[210:211], v[216:217], 0, s[6:7]
	s_mov_b32 m0, s43
	s_nop 0
	global_load_lds_dwordx4 v[210:211], off
	s_waitcnt vmcnt(8)
	s_waitcnt lgkmcnt(0)
	s_barrier
	s_setprio 1
	s_waitcnt lgkmcnt(0)
	v_mfma_f32_16x16x32_bf16 v[60:63], v[64:67], v[178:181], v[60:63]
	v_mfma_f32_16x16x32_bf16 v[56:59], v[72:75], v[178:181], v[56:59]
	v_mfma_f32_16x16x32_bf16 v[48:51], v[64:67], v[186:189], v[48:51]
	v_mfma_f32_16x16x32_bf16 v[40:43], v[72:75], v[186:189], v[40:43]
	v_mfma_f32_16x16x32_bf16 v[32:35], v[64:67], v[194:197], v[32:35]
	v_mfma_f32_16x16x32_bf16 v[24:27], v[72:75], v[194:197], v[24:27]
	v_mfma_f32_16x16x32_bf16 v[16:19], v[64:67], v[202:205], v[16:19]
	v_mfma_f32_16x16x32_bf16 v[8:11], v[72:75], v[202:205], v[8:11]
	v_mfma_f32_16x16x32_bf16 v[60:63], v[68:71], v[182:185], v[60:63]
	v_mfma_f32_16x16x32_bf16 v[56:59], v[76:79], v[182:185], v[56:59]
	v_mfma_f32_16x16x32_bf16 v[48:51], v[68:71], v[190:193], v[48:51]
	v_mfma_f32_16x16x32_bf16 v[40:43], v[76:79], v[190:193], v[40:43]
	v_mfma_f32_16x16x32_bf16 v[32:35], v[68:71], v[198:201], v[32:35]
	v_mfma_f32_16x16x32_bf16 v[24:27], v[76:79], v[198:201], v[24:27]
	v_mfma_f32_16x16x32_bf16 v[16:19], v[68:71], v[206:209], v[16:19]
	v_mfma_f32_16x16x32_bf16 v[8:11], v[76:79], v[206:209], v[8:11]
	v_mfma_f32_16x16x32_bf16 v[52:55], v[144:147], v[178:181], v[52:55]
	v_mfma_f32_16x16x32_bf16 v[44:47], v[170:173], v[178:181], v[44:47]
	v_mfma_f32_16x16x32_bf16 v[36:39], v[144:147], v[186:189], v[36:39]
	v_mfma_f32_16x16x32_bf16 v[28:31], v[170:173], v[186:189], v[28:31]
	v_mfma_f32_16x16x32_bf16 v[20:23], v[144:147], v[194:197], v[20:23]
	v_mfma_f32_16x16x32_bf16 v[12:15], v[170:173], v[194:197], v[12:15]
	v_mfma_f32_16x16x32_bf16 v[4:7], v[144:147], v[202:205], v[4:7]
	v_mfma_f32_16x16x32_bf16 v[0:3], v[170:173], v[202:205], v[0:3]
	v_mfma_f32_16x16x32_bf16 v[52:55], v[148:151], v[182:185], v[52:55]
	v_mfma_f32_16x16x32_bf16 v[44:47], v[174:177], v[182:185], v[44:47]
	v_mfma_f32_16x16x32_bf16 v[36:39], v[148:151], v[190:193], v[36:39]
	v_mfma_f32_16x16x32_bf16 v[28:31], v[174:177], v[190:193], v[28:31]
	v_mfma_f32_16x16x32_bf16 v[20:23], v[148:151], v[198:201], v[20:23]
	v_mfma_f32_16x16x32_bf16 v[12:15], v[174:177], v[198:201], v[12:15]
	v_mfma_f32_16x16x32_bf16 v[4:7], v[148:151], v[206:209], v[4:7]
	v_mfma_f32_16x16x32_bf16 v[0:3], v[174:177], v[206:209], v[0:3]
	s_setprio 0
	s_barrier
	s_add_i32 s53, s53, 2
	s_add_u32 s17, s17, 0x100
	s_addc_u32 s52, s52, 0
	s_cmpk_gt_u32 s53, 0x53
	s_mov_b64 s[18:19], s[20:21]
	s_cbranch_scc0 .LBB0_635

;     __host__ __device__ bool next(int i, Unit& u) const { const bool ok = StaticOrder::next(i, u); u.pm = 0; u.pn = 0; return ok; }
; #define PG8_STAGE(bufoff, gbase, voff) do { _Pragma("unroll") for (int _i = 0; _i < 2; ++_i) \
;         __builtin_amdgcn_global_load_lds((const unsigned*)((const char*)(gbase) + (voff)[_i]), (PG8_LAS unsigned*)(lds + (bufoff) + ldsw + _i * 8192), 16, 0, 0); } while (0)
; #define PG8_LDA(dst, b, h) do { _Pragma("unroll") for (int m = 0; m < 4; ++m) _Pragma("unroll") for (int k = 0; k < 2; ++k) dst[m][k] = *(const PG8_LAS bf16x8*)(lds + PG8_SA(b, h) + aoff + m * 2048 + k * 1024); } while (0)
; #define PG8_LDB(dst, b, h) do { _Pragma("unroll") for (int n = 0; n < 2; ++n) _Pragma("unroll") for (int k = 0; k < 2; ++k) dst[n][k] = *(const PG8_LAS bf16x8*)(lds + PG8_SB(b, h) + boff + n * 2048 + k * 1024); } while (0)
; #define PG8_WAIT_V(n) asm volatile("s_waitcnt vmcnt(" #n ")" ::: "memory")
; #define PG8_WAIT_L(n) asm volatile("s_waitcnt lgkmcnt(" #n ")" ::: "memory")
; #define PG8_BAR __builtin_amdgcn_s_barrier()
; #define PG8_SCHED __builtin_amdgcn_sched_barrier(0)
; template <class Epi, class Sched, bool ALIGN_EPI = false, bool SP2 = false>
; __device__ __forceinline__ void gemm_phase(PG8_LAS unsigned char* lds, const Gemm g, const Sched& S, const Epi& E, const int wave_in) {
;     ...
;         const bool has_next = S.next(ui + 1, nxt);
;         const char* nA = has_next ? (const char*)g.A + (size_t)nxt.pm * tstepA : cA; const char* nB = has_next ? (const char*)g.Bt + (size_t)nxt.pn * tstepB : cB;
;         for (int t = 0; t < nt; t += 2) {
;             const bool last = (t == nt - 2);
;             const char* a1 = cA + (size_t)(t + 1) * kstep;
;             const char* a2 = last ? nA : cA + (size_t)(t + 2) * kstep; const char* b2 = last ? nB : cB + (size_t)(t + 2) * kstep;
;             const char* a3 = a2 + kstep; const char* b3 = b2 + kstep;
;             if (last && has_next) S.a_ready(nxt);
;             if constexpr (SP2) {
;             PG8_LDB(B0, 0, 0); PG8_LDB(B1, 0, 1); PG8_SCHED; PG8_LDA(At, 0, 0); PG8_STAGE(PG8_SA(1, 1), a1 + hstepA, voffA);
;             PG8_WAIT_V(8); PG8_WAIT_L(0); PG8_BAR; PG8_MMA(0, 0, At, B0); PG8_MMA(0, 1, At, B1); PG8_BAR; PG8_SCHED;
;             PG8_LDA(At, 0, 1); PG8_STAGE(PG8_SB(0, 0), b2, voffB); PG8_STAGE(PG8_SB(0, 1), b2 + hstepB, voffB); PG8_STAGE(PG8_SA(0, 0), a2, voffA);
.LBB0_1092:
	s_ashr_i32 s15, s14, 31
	s_lshl_b64 s[18:19], s[14:15], 21
	s_add_u32 s18, s30, s18
	s_addc_u32 s19, s31, s19
	s_and_b64 s[4:5], s[4:5], exec
	s_cselect_b32 s15, s19, s25
	s_cselect_b32 s21, s18, s24
	s_add_u32 s53, s24, 0x100
	v_mov_b32_e32 v0, 0
	s_addc_u32 s54, s25, 0
	s_mov_b32 s55, -2
	ds_read_b128 v[128:131], v214
	ds_read_b128 v[132:135], v214 offset:1024
	ds_read_b128 v[136:139], v214 offset:2048
	ds_read_b128 v[140:143], v214 offset:3072
	ds_read_b128 v[162:165], v215
	ds_read_b128 v[166:169], v215 offset:1024
	ds_read_b128 v[170:173], v215 offset:2048
	ds_read_b128 v[174:177], v215 offset:3072
	s_add_u32 s4, s22, 0x100
	s_addc_u32 s5, s23, 0
	s_cmp_eq_u32 s55, 60
	s_cselect_b32 s27, s17, s5
	s_cselect_b32 s26, s16, s4
	s_cselect_b32 s25, s15, s54
	s_cselect_b32 s24, s21, s53
	v_lshl_add_u64 v[210:211], s[22:23], 0, v[154:155]
	s_add_i32 m0, s37, 0xc000
	ds_read_b128 v[178:181], v216
	ds_read_b128 v[182:185], v216 offset:1024
	ds_read_b128 v[186:189], v216 offset:2048
	ds_read_b128 v[190:193], v216 offset:3072
	ds_read_b128 v[194:197], v216 offset:4096
	ds_read_b128 v[198:201], v216 offset:5120
	ds_read_b128 v[202:205], v216 offset:6144
	ds_read_b128 v[206:209], v216 offset:7168
	global_load_lds_dwordx4 v[210:211], off
	v_lshl_add_u64 v[210:211], s[22:23], 0, v[156:157]
	s_add_i32 m0, s37, 0xe000
	s_nop 0
	global_load_lds_dwordx4 v[210:211], off
	s_waitcnt vmcnt(8)
	s_waitcnt lgkmcnt(0)
	s_barrier
	s_setprio 1
	s_waitcnt lgkmcnt(0)
	v_mfma_f32_16x16x32_bf16 v[124:127], v[128:131], v[178:181], 0
	v_mfma_f32_16x16x32_bf16 v[120:123], v[136:139], v[178:181], 0
	v_mfma_f32_16x16x32_bf16 v[112:115], v[128:131], v[186:189], 0
	v_mfma_f32_16x16x32_bf16 v[104:107], v[136:139], v[186:189], 0
	v_mfma_f32_16x16x32_bf16 v[100:103], v[128:131], v[194:197], 0
	v_mfma_f32_16x16x32_bf16 v[96:99], v[136:139], v[194:197], 0
	v_mfma_f32_16x16x32_bf16 v[76:79], v[128:131], v[202:205], 0
	v_mfma_f32_16x16x32_bf16 v[72:75], v[136:139], v[202:205], 0
	v_mfma_f32_16x16x32_bf16 v[124:127], v[132:135], v[182:185], v[124:127]
	v_mfma_f32_16x16x32_bf16 v[120:123], v[140:143], v[182:185], v[120:123]
	v_mfma_f32_16x16x32_bf16 v[112:115], v[132:135], v[190:193], v[112:115]
	v_mfma_f32_16x16x32_bf16 v[104:107], v[140:143], v[190:193], v[104:107]
	v_mfma_f32_16x16x32_bf16 v[100:103], v[132:135], v[198:201], v[100:103]
	v_mfma_f32_16x16x32_bf16 v[96:99], v[140:143], v[198:201], v[96:99]
	v_mfma_f32_16x16x32_bf16 v[76:79], v[132:135], v[206:209], v[76:79]
	v_mfma_f32_16x16x32_bf16 v[72:75], v[140:143], v[206:209], v[72:75]
	v_mfma_f32_16x16x32_bf16 v[116:119], v[162:165], v[178:181], 0
	v_mfma_f32_16x16x32_bf16 v[108:111], v[170:173], v[178:181], 0
	v_mfma_f32_16x16x32_bf16 v[92:95], v[162:165], v[186:189], 0
	v_mfma_f32_16x16x32_bf16 v[88:91], v[170:173], v[186:189], 0
	v_mfma_f32_16x16x32_bf16 v[84:87], v[162:165], v[194:197], 0
	v_mfma_f32_16x16x32_bf16 v[80:83], v[170:173], v[194:197], 0
	v_mfma_f32_16x16x32_bf16 v[68:71], v[162:165], v[202:205], 0
	v_mfma_f32_16x16x32_bf16 v[64:67], v[170:173], v[202:205], 0
	v_mfma_f32_16x16x32_bf16 v[116:119], v[166:169], v[182:185], v[116:119]
	v_mfma_f32_16x16x32_bf16 v[108:111], v[174:177], v[182:185], v[108:111]
	v_mfma_f32_16x16x32_bf16 v[92:95], v[166:169], v[190:193], v[92:95]
	v_mfma_f32_16x16x32_bf16 v[88:91], v[174:177], v[190:193], v[88:91]
	v_mfma_f32_16x16x32_bf16 v[84:87], v[166:169], v[198:201], v[84:87]
	v_mfma_f32_16x16x32_bf16 v[80:83], v[174:177], v[198:201], v[80:83]
	v_mfma_f32_16x16x32_bf16 v[68:71], v[166:169], v[206:209], v[68:71]
	v_mfma_f32_16x16x32_bf16 v[64:67], v[174:177], v[206:209], v[64:67]
	s_setprio 0
	s_barrier
	s_add_i32 s22, s47, s34
	v_lshl_add_u64 v[210:211], s[24:25], 0, v[148:149]
	s_mov_b32 m0, s22
	ds_read_b128 v[178:181], v216 offset:16384
	ds_read_b128 v[182:185], v216 offset:17408
	ds_read_b128 v[186:189], v216 offset:18432
	ds_read_b128 v[190:193], v216 offset:19456
	ds_read_b128 v[194:197], v216 offset:20480
	ds_read_b128 v[198:201], v216 offset:21504
	ds_read_b128 v[202:205], v216 offset:22528
	ds_read_b128 v[206:209], v216 offset:23552
	global_load_lds_dwordx4 v[210:211], off
	s_add_i32 m0, s22, 0x2000
	s_add_u32 s22, s24, 0x100000
	v_lshl_add_u64 v[218:219], s[24:25], 0, v[144:145]
	s_addc_u32 s23, s25, 0
	s_add_i32 s56, s48, s34
	global_load_lds_dwordx4 v[218:219], off
	v_lshl_add_u64 v[220:221], s[22:23], 0, v[148:149]
	s_mov_b32 m0, s56
	v_lshl_add_u64 v[222:223], s[26:27], 0, v[146:147]
	global_load_lds_dwordx4 v[220:221], off
	v_lshl_add_u64 v[220:221], s[22:23], 0, v[144:145]
	s_add_i32 m0, s56, 0x2000
	s_nop 0
	global_load_lds_dwordx4 v[220:221], off
	v_lshl_add_u64 v[220:221], s[26:27], 0, v[150:151]
	s_mov_b32 m0, s37
	s_nop 0
	global_load_lds_dwordx4 v[220:221], off
	s_mov_b32 m0, s38
	s_nop 0
	global_load_lds_dwordx4 v[222:223], off
	s_waitcnt vmcnt(8)
	s_waitcnt lgkmcnt(0)
	s_barrier
; #define PG8_STAGE(bufoff, gbase, voff) do { _Pragma("unroll") for (int _i = 0; _i < 2; ++_i) \
;         __builtin_amdgcn_global_load_lds((const unsigned*)((const char*)(gbase) + (voff)[_i]), (PG8_LAS unsigned*)(lds + (bufoff) + ldsw + _i * 8192), 16, 0, 0); } while (0)
; #define PG8_LDA(dst, b, h) do { _Pragma("unroll") for (int m = 0; m < 4; ++m) _Pragma("unroll") for (int k = 0; k < 2; ++k) dst[m][k] = *(const PG8_LAS bf16x8*)(lds + PG8_SA(b, h) + aoff + m * 2048 + k * 1024); } while (0)
; #define PG8_LDB(dst, b, h) do { _Pragma("unroll") for (int n = 0; n < 2; ++n) _Pragma("unroll") for (int k = 0; k < 2; ++k) dst[n][k] = *(const PG8_LAS bf16x8*)(lds + PG8_SB(b, h) + boff + n * 2048 + k * 1024); } while (0)
; #define PG8_MMA(ai, bj, At, Bt) do { __builtin_amdgcn_s_setprio(1); _Pragma("unroll") for (int m = 0; m < 4; ++m) _Pragma("unroll") for (int n = 0; n < 2; ++n) _Pragma("unroll") for (int k = 0; k < 2; ++k) \
;         acc[ai][bj][m][n] = __builtin_amdgcn_mfma_f32_16x16x32_bf16(Bt[n][k], At[m][k], acc[ai][bj][m][n], 0, 0, 0); __builtin_amdgcn_s_setprio(0); } while (0)
; #define PG8_WAIT_V(n) asm volatile("s_waitcnt vmcnt(" #n ")" ::: "memory")
; #define PG8_WAIT_L(n) asm volatile("s_waitcnt lgkmcnt(" #n ")" ::: "memory")
; #define PG8_BAR __builtin_amdgcn_s_barrier()
; #define PG8_SCHED __builtin_amdgcn_sched_barrier(0)
; template <class Epi, class Sched, bool ALIGN_EPI = false, bool SP2 = false>
; __device__ __forceinline__ void gemm_phase(PG8_LAS unsigned char* lds, const Gemm g, const Sched& S, const Epi& E, const int wave_in) {
;     ...
;             PG8_WAIT_V(8); PG8_WAIT_L(0); PG8_BAR; PG8_MMA(1, 0, At, B0); PG8_MMA(1, 1, At, B1); PG8_BAR; PG8_SCHED;
;             PG8_LDB(B0, 1, 0); PG8_LDB(B1, 1, 1); PG8_SCHED; PG8_LDA(At, 1, 0); PG8_STAGE(PG8_SA(0, 1), a2 + hstepA, voffA);
;             PG8_WAIT_V(8); PG8_WAIT_L(0); PG8_BAR; PG8_MMA(0, 0, At, B0); PG8_MMA(0, 1, At, B1); PG8_BAR; PG8_SCHED;
	s_setprio 1
	s_waitcnt lgkmcnt(0)
	v_mfma_f32_16x16x32_bf16 v[60:63], v[128:131], v[178:181], 0
	v_mfma_f32_16x16x32_bf16 v[56:59], v[136:139], v[178:181], 0
	v_mfma_f32_16x16x32_bf16 v[48:51], v[128:131], v[186:189], 0
	v_mfma_f32_16x16x32_bf16 v[40:43], v[136:139], v[186:189], 0
	v_mfma_f32_16x16x32_bf16 v[32:35], v[128:131], v[194:197], 0
	v_mfma_f32_16x16x32_bf16 v[24:27], v[136:139], v[194:197], 0
	v_mfma_f32_16x16x32_bf16 v[16:19], v[128:131], v[202:205], 0
	v_mfma_f32_16x16x32_bf16 v[8:11], v[136:139], v[202:205], 0
	v_mfma_f32_16x16x32_bf16 v[60:63], v[132:135], v[182:185], v[60:63]
	v_mfma_f32_16x16x32_bf16 v[56:59], v[140:143], v[182:185], v[56:59]
	v_mfma_f32_16x16x32_bf16 v[48:51], v[132:135], v[190:193], v[48:51]
	v_mfma_f32_16x16x32_bf16 v[40:43], v[140:143], v[190:193], v[40:43]
	v_mfma_f32_16x16x32_bf16 v[32:35], v[132:135], v[198:201], v[32:35]
	v_mfma_f32_16x16x32_bf16 v[24:27], v[140:143], v[198:201], v[24:27]
	v_mfma_f32_16x16x32_bf16 v[16:19], v[132:135], v[206:209], v[16:19]
	v_mfma_f32_16x16x32_bf16 v[8:11], v[140:143], v[206:209], v[8:11]
	v_mfma_f32_16x16x32_bf16 v[52:55], v[162:165], v[178:181], 0
	v_mfma_f32_16x16x32_bf16 v[44:47], v[170:173], v[178:181], 0
	v_mfma_f32_16x16x32_bf16 v[36:39], v[162:165], v[186:189], 0
	v_mfma_f32_16x16x32_bf16 v[28:31], v[170:173], v[186:189], 0
	v_mfma_f32_16x16x32_bf16 v[20:23], v[162:165], v[194:197], 0
	v_mfma_f32_16x16x32_bf16 v[12:15], v[170:173], v[194:197], 0
	v_mfma_f32_16x16x32_bf16 v[4:7], v[162:165], v[202:205], 0
	v_mfma_f32_16x16x32_bf16 v[0:3], v[170:173], v[202:205], 0
	v_mfma_f32_16x16x32_bf16 v[52:55], v[166:169], v[182:185], v[52:55]
	v_mfma_f32_16x16x32_bf16 v[44:47], v[174:177], v[182:185], v[44:47]
	v_mfma_f32_16x16x32_bf16 v[36:39], v[166:169], v[190:193], v[36:39]
	v_mfma_f32_16x16x32_bf16 v[28:31], v[174:177], v[190:193], v[28:31]
	v_mfma_f32_16x16x32_bf16 v[20:23], v[166:169], v[198:201], v[20:23]
	v_mfma_f32_16x16x32_bf16 v[12:15], v[174:177], v[198:201], v[12:15]
	v_mfma_f32_16x16x32_bf16 v[4:7], v[166:169], v[206:209], v[4:7]
	v_mfma_f32_16x16x32_bf16 v[0:3], v[174:177], v[206:209], v[0:3]
	s_setprio 0
	s_barrier
	s_add_i32 s56, 0, 0x18000
	s_add_i32 s57, 0, 0x1c000
	v_add_u32_e32 v140, s56, v212
	v_add_u32_e32 v174, s57, v212
	ds_read_b128 v[128:131], v140
	ds_read_b128 v[132:135], v140 offset:1024
	ds_read_b128 v[136:139], v140 offset:2048
	ds_read_b128 v[140:143], v140 offset:3072
	ds_read_b128 v[162:165], v174
	ds_read_b128 v[166:169], v174 offset:1024
	ds_read_b128 v[170:173], v174 offset:2048
	ds_read_b128 v[174:177], v174 offset:3072
	s_add_u32 s22, s26, 0x310000
	s_addc_u32 s23, s27, 0
	s_mov_b32 m0, s39
	v_lshl_add_u64 v[224:225], s[22:23], 0, v[150:151]
	ds_read_b128 v[178:181], v216 offset:32768
	ds_read_b128 v[182:185], v216 offset:33792
	ds_read_b128 v[186:189], v216 offset:34816
	ds_read_b128 v[190:193], v216 offset:35840
	ds_read_b128 v[194:197], v216 offset:36864
	ds_read_b128 v[198:201], v216 offset:37888
	ds_read_b128 v[202:205], v216 offset:38912
	ds_read_b128 v[206:209], v216 offset:39936
	global_load_lds_dwordx4 v[224:225], off
	v_lshl_add_u64 v[224:225], s[22:23], 0, v[146:147]
	s_mov_b32 m0, s40
	s_nop 0
	global_load_lds_dwordx4 v[224:225], off
	s_waitcnt vmcnt(8)
	s_waitcnt lgkmcnt(0)
	s_barrier
	s_setprio 1
	s_waitcnt lgkmcnt(0)
	v_mfma_f32_16x16x32_bf16 v[124:127], v[128:131], v[178:181], v[124:127]
	v_mfma_f32_16x16x32_bf16 v[120:123], v[136:139], v[178:181], v[120:123]
	v_mfma_f32_16x16x32_bf16 v[112:115], v[128:131], v[186:189], v[112:115]
	v_mfma_f32_16x16x32_bf16 v[104:107], v[136:139], v[186:189], v[104:107]
	v_mfma_f32_16x16x32_bf16 v[100:103], v[128:131], v[194:197], v[100:103]
	v_mfma_f32_16x16x32_bf16 v[96:99], v[136:139], v[194:197], v[96:99]
	v_mfma_f32_16x16x32_bf16 v[76:79], v[128:131], v[202:205], v[76:79]
	v_mfma_f32_16x16x32_bf16 v[72:75], v[136:139], v[202:205], v[72:75]
	v_mfma_f32_16x16x32_bf16 v[124:127], v[132:135], v[182:185], v[124:127]
	v_mfma_f32_16x16x32_bf16 v[120:123], v[140:143], v[182:185], v[120:123]
	v_mfma_f32_16x16x32_bf16 v[112:115], v[132:135], v[190:193], v[112:115]
	v_mfma_f32_16x16x32_bf16 v[104:107], v[140:143], v[190:193], v[104:107]
	v_mfma_f32_16x16x32_bf16 v[100:103], v[132:135], v[198:201], v[100:103]
	v_mfma_f32_16x16x32_bf16 v[96:99], v[140:143], v[198:201], v[96:99]
	v_mfma_f32_16x16x32_bf16 v[76:79], v[132:135], v[206:209], v[76:79]
	v_mfma_f32_16x16x32_bf16 v[72:75], v[140:143], v[206:209], v[72:75]
	v_mfma_f32_16x16x32_bf16 v[116:119], v[162:165], v[178:181], v[116:119]
	v_mfma_f32_16x16x32_bf16 v[108:111], v[170:173], v[178:181], v[108:111]
	v_mfma_f32_16x16x32_bf16 v[92:95], v[162:165], v[186:189], v[92:95]
	v_mfma_f32_16x16x32_bf16 v[88:91], v[170:173], v[186:189], v[88:91]
	v_mfma_f32_16x16x32_bf16 v[84:87], v[162:165], v[194:197], v[84:87]
	v_mfma_f32_16x16x32_bf16 v[80:83], v[170:173], v[194:197], v[80:83]
	v_mfma_f32_16x16x32_bf16 v[68:71], v[162:165], v[202:205], v[68:71]
	v_mfma_f32_16x16x32_bf16 v[64:67], v[170:173], v[202:205], v[64:67]
	v_mfma_f32_16x16x32_bf16 v[116:119], v[166:169], v[182:185], v[116:119]
	v_mfma_f32_16x16x32_bf16 v[108:111], v[174:177], v[182:185], v[108:111]
	v_mfma_f32_16x16x32_bf16 v[92:95], v[166:169], v[190:193], v[92:95]
	v_mfma_f32_16x16x32_bf16 v[88:91], v[174:177], v[190:193], v[88:91]
	v_mfma_f32_16x16x32_bf16 v[84:87], v[166:169], v[198:201], v[84:87]
	v_mfma_f32_16x16x32_bf16 v[80:83], v[174:177], v[198:201], v[80:83]
	v_mfma_f32_16x16x32_bf16 v[68:71], v[166:169], v[206:209], v[68:71]
	v_mfma_f32_16x16x32_bf16 v[64:67], v[174:177], v[206:209], v[64:67]
	s_setprio 0
	s_barrier
; #define PG8_STAGE(bufoff, gbase, voff) do { _Pragma("unroll") for (int _i = 0; _i < 2; ++_i) \
;         __builtin_amdgcn_global_load_lds((const unsigned*)((const char*)(gbase) + (voff)[_i]), (PG8_LAS unsigned*)(lds + (bufoff) + ldsw + _i * 8192), 16, 0, 0); } while (0)
; #define PG8_LDA(dst, b, h) do { _Pragma("unroll") for (int m = 0; m < 4; ++m) _Pragma("unroll") for (int k = 0; k < 2; ++k) dst[m][k] = *(const PG8_LAS bf16x8*)(lds + PG8_SA(b, h) + aoff + m * 2048 + k * 1024); } while (0)
; #define PG8_LDB(dst, b, h) do { _Pragma("unroll") for (int n = 0; n < 2; ++n) _Pragma("unroll") for (int k = 0; k < 2; ++k) dst[n][k] = *(const PG8_LAS bf16x8*)(lds + PG8_SB(b, h) + boff + n * 2048 + k * 1024); } while (0)
; #define PG8_MMA(ai, bj, At, Bt) do { __builtin_amdgcn_s_setprio(1); _Pragma("unroll") for (int m = 0; m < 4; ++m) _Pragma("unroll") for (int n = 0; n < 2; ++n) _Pragma("unroll") for (int k = 0; k < 2; ++k) \
;         acc[ai][bj][m][n] = __builtin_amdgcn_mfma_f32_16x16x32_bf16(Bt[n][k], At[m][k], acc[ai][bj][m][n], 0, 0, 0); __builtin_amdgcn_s_setprio(0); } while (0)
; #define PG8_WAIT_V(n) asm volatile("s_waitcnt vmcnt(" #n ")" ::: "memory")
; #define PG8_WAIT_L(n) asm volatile("s_waitcnt lgkmcnt(" #n ")" ::: "memory")
; #define PG8_BAR __builtin_amdgcn_s_barrier()
; template <class Epi, class Sched, bool ALIGN_EPI = false, bool SP2 = false>
; __device__ __forceinline__ void gemm_phase(PG8_LAS unsigned char* lds, const Gemm g, const Sched& S, const Epi& E, const int wave_in) {
;     ...
;         for (int t = 0; t < nt; t += 2) {
;             const bool last = (t == nt - 2);
;             const char* a1 = cA + (size_t)(t + 1) * kstep;
;             const char* a2 = last ? nA : cA + (size_t)(t + 2) * kstep; const char* b2 = last ? nB : cB + (size_t)(t + 2) * kstep;
;             const char* a3 = a2 + kstep; const char* b3 = b2 + kstep;
;             if (last && has_next) S.a_ready(nxt);
;             if constexpr (SP2) {
;             PG8_LDB(B0, 0, 0); PG8_LDB(B1, 0, 1); PG8_SCHED; PG8_LDA(At, 0, 0); PG8_STAGE(PG8_SA(1, 1), a1 + hstepA, voffA);
;     ...
;             PG8_LDA(At, 1, 1); PG8_STAGE(PG8_SB(1, 0), b3, voffB); PG8_STAGE(PG8_SB(1, 1), b3 + hstepB, voffB); PG8_STAGE(PG8_SA(1, 0), a3, voffA);
;             PG8_WAIT_V(8); PG8_WAIT_L(0); PG8_BAR; PG8_MMA(1, 0, At, B0); PG8_MMA(1, 1, At, B1); PG8_BAR; PG8_SCHED;
	s_add_i32 s22, s56, s34
	v_lshl_add_u64 v[210:211], v[210:211], 0, s[6:7]
	s_mov_b32 m0, s22
	ds_read_b128 v[178:181], v216 offset:49152
	ds_read_b128 v[182:185], v216 offset:50176
	ds_read_b128 v[186:189], v216 offset:51200
	ds_read_b128 v[190:193], v216 offset:52224
	ds_read_b128 v[194:197], v216 offset:53248
	ds_read_b128 v[198:201], v216 offset:54272
	ds_read_b128 v[202:205], v216 offset:55296
	ds_read_b128 v[206:209], v216 offset:56320
	global_load_lds_dwordx4 v[210:211], off
	s_add_i32 m0, s22, 0x2000
	s_add_u32 s22, s24, 0x100080
	v_lshl_add_u64 v[210:211], v[218:219], 0, s[6:7]
	s_addc_u32 s23, s25, 0
	s_add_i32 s24, s57, s34
	global_load_lds_dwordx4 v[210:211], off
	v_lshl_add_u64 v[210:211], s[22:23], 0, v[148:149]
	s_mov_b32 m0, s24
	s_nop 0
	global_load_lds_dwordx4 v[210:211], off
	v_lshl_add_u64 v[210:211], s[22:23], 0, v[144:145]
	s_add_i32 m0, s24, 0x2000
	s_nop 0
	global_load_lds_dwordx4 v[210:211], off
	v_lshl_add_u64 v[210:211], v[220:221], 0, s[6:7]
	s_mov_b32 m0, s44
	s_nop 0
	global_load_lds_dwordx4 v[210:211], off
	v_lshl_add_u64 v[210:211], v[222:223], 0, s[6:7]
	s_mov_b32 m0, s45
	s_nop 0
	global_load_lds_dwordx4 v[210:211], off
	s_waitcnt vmcnt(8)
	s_waitcnt lgkmcnt(0)
	s_barrier
	s_setprio 1
	s_waitcnt lgkmcnt(0)
	v_mfma_f32_16x16x32_bf16 v[60:63], v[128:131], v[178:181], v[60:63]
	v_mfma_f32_16x16x32_bf16 v[56:59], v[136:139], v[178:181], v[56:59]
	v_mfma_f32_16x16x32_bf16 v[48:51], v[128:131], v[186:189], v[48:51]
	v_mfma_f32_16x16x32_bf16 v[40:43], v[136:139], v[186:189], v[40:43]
	v_mfma_f32_16x16x32_bf16 v[32:35], v[128:131], v[194:197], v[32:35]
	v_mfma_f32_16x16x32_bf16 v[24:27], v[136:139], v[194:197], v[24:27]
	v_mfma_f32_16x16x32_bf16 v[16:19], v[128:131], v[202:205], v[16:19]
	v_mfma_f32_16x16x32_bf16 v[8:11], v[136:139], v[202:205], v[8:11]
	v_mfma_f32_16x16x32_bf16 v[60:63], v[132:135], v[182:185], v[60:63]
	v_mfma_f32_16x16x32_bf16 v[56:59], v[140:143], v[182:185], v[56:59]
	v_mfma_f32_16x16x32_bf16 v[48:51], v[132:135], v[190:193], v[48:51]
	v_mfma_f32_16x16x32_bf16 v[40:43], v[140:143], v[190:193], v[40:43]
	v_mfma_f32_16x16x32_bf16 v[32:35], v[132:135], v[198:201], v[32:35]
	v_mfma_f32_16x16x32_bf16 v[24:27], v[140:143], v[198:201], v[24:27]
	v_mfma_f32_16x16x32_bf16 v[16:19], v[132:135], v[206:209], v[16:19]
	v_mfma_f32_16x16x32_bf16 v[8:11], v[140:143], v[206:209], v[8:11]
	v_mfma_f32_16x16x32_bf16 v[52:55], v[162:165], v[178:181], v[52:55]
	v_mfma_f32_16x16x32_bf16 v[44:47], v[170:173], v[178:181], v[44:47]
	v_mfma_f32_16x16x32_bf16 v[36:39], v[162:165], v[186:189], v[36:39]
	v_mfma_f32_16x16x32_bf16 v[28:31], v[170:173], v[186:189], v[28:31]
	v_mfma_f32_16x16x32_bf16 v[20:23], v[162:165], v[194:197], v[20:23]
	v_mfma_f32_16x16x32_bf16 v[12:15], v[170:173], v[194:197], v[12:15]
	v_mfma_f32_16x16x32_bf16 v[4:7], v[162:165], v[202:205], v[4:7]
	v_mfma_f32_16x16x32_bf16 v[0:3], v[170:173], v[202:205], v[0:3]
	v_mfma_f32_16x16x32_bf16 v[52:55], v[166:169], v[182:185], v[52:55]
	v_mfma_f32_16x16x32_bf16 v[44:47], v[174:177], v[182:185], v[44:47]
	v_mfma_f32_16x16x32_bf16 v[36:39], v[166:169], v[190:193], v[36:39]
	v_mfma_f32_16x16x32_bf16 v[28:31], v[174:177], v[190:193], v[28:31]
	v_mfma_f32_16x16x32_bf16 v[20:23], v[166:169], v[198:201], v[20:23]
	v_mfma_f32_16x16x32_bf16 v[12:15], v[174:177], v[198:201], v[12:15]
	v_mfma_f32_16x16x32_bf16 v[4:7], v[166:169], v[206:209], v[4:7]
	v_mfma_f32_16x16x32_bf16 v[0:3], v[174:177], v[206:209], v[0:3]
	s_setprio 0
	s_barrier
	s_add_i32 s55, s55, 2
	s_add_u32 s53, s53, 0x100
	s_addc_u32 s54, s54, 0
	s_cmp_gt_u32 s55, 61
	s_mov_b64 s[22:23], s[4:5]
	s_cbranch_scc0 .LBB0_1093
	s_branch .Lkx_12
.LBB0_1093:
	ds_read_b128 v[128:131], v214
	ds_read_b128 v[132:135], v214 offset:1024
	ds_read_b128 v[136:139], v214 offset:2048
	ds_read_b128 v[140:143], v214 offset:3072
	ds_read_b128 v[162:165], v215
	ds_read_b128 v[166:169], v215 offset:1024
	ds_read_b128 v[170:173], v215 offset:2048
	ds_read_b128 v[174:177], v215 offset:3072
	s_add_u32 s4, s22, 0x100
	s_addc_u32 s5, s23, 0
	s_cmp_eq_u32 s55, 60
	s_cselect_b32 s27, s17, s5
	s_cselect_b32 s26, s16, s4
	s_cselect_b32 s25, s15, s54
	s_cselect_b32 s24, s21, s53
	v_lshl_add_u64 v[210:211], s[22:23], 0, v[154:155]
	s_add_i32 m0, s37, 0xc000
	ds_read_b128 v[178:181], v216
	ds_read_b128 v[182:185], v216 offset:1024
	ds_read_b128 v[186:189], v216 offset:2048
	ds_read_b128 v[190:193], v216 offset:3072
	ds_read_b128 v[194:197], v216 offset:4096
	ds_read_b128 v[198:201], v216 offset:5120
	ds_read_b128 v[202:205], v216 offset:6144
	ds_read_b128 v[206:209], v216 offset:7168
	global_load_lds_dwordx4 v[210:211], off
	v_lshl_add_u64 v[210:211], s[22:23], 0, v[156:157]
	s_add_i32 m0, s37, 0xe000
	s_nop 0
	global_load_lds_dwordx4 v[210:211], off
	s_waitcnt vmcnt(8)
	s_waitcnt lgkmcnt(0)
	s_barrier
; #define PG8_STAGE(bufoff, gbase, voff) do { _Pragma("unroll") for (int _i = 0; _i < 2; ++_i) \
;         __builtin_amdgcn_global_load_lds((const unsigned*)((const char*)(gbase) + (voff)[_i]), (PG8_LAS unsigned*)(lds + (bufoff) + ldsw + _i * 8192), 16, 0, 0); } while (0)
; #define PG8_LDA(dst, b, h) do { _Pragma("unroll") for (int m = 0; m < 4; ++m) _Pragma("unroll") for (int k = 0; k < 2; ++k) dst[m][k] = *(const PG8_LAS bf16x8*)(lds + PG8_SA(b, h) + aoff + m * 2048 + k * 1024); } while (0)
; #define PG8_MMA(ai, bj, At, Bt) do { __builtin_amdgcn_s_setprio(1); _Pragma("unroll") for (int m = 0; m < 4; ++m) _Pragma("unroll") for (int n = 0; n < 2; ++n) _Pragma("unroll") for (int k = 0; k < 2; ++k) \
;         acc[ai][bj][m][n] = __builtin_amdgcn_mfma_f32_16x16x32_bf16(Bt[n][k], At[m][k], acc[ai][bj][m][n], 0, 0, 0); __builtin_amdgcn_s_setprio(0); } while (0)
; #define PG8_WAIT_V(n) asm volatile("s_waitcnt vmcnt(" #n ")" ::: "memory")
; #define PG8_WAIT_L(n) asm volatile("s_waitcnt lgkmcnt(" #n ")" ::: "memory")
; #define PG8_BAR __builtin_amdgcn_s_barrier()
; #define PG8_SCHED __builtin_amdgcn_sched_barrier(0)
; template <class Epi, class Sched, bool ALIGN_EPI = false, bool SP2 = false>
; __device__ __forceinline__ void gemm_phase(PG8_LAS unsigned char* lds, const Gemm g, const Sched& S, const Epi& E, const int wave_in) {
;     ...
;             PG8_WAIT_V(8); PG8_WAIT_L(0); PG8_BAR; PG8_MMA(0, 0, At, B0); PG8_MMA(0, 1, At, B1); PG8_BAR; PG8_SCHED;
;             PG8_LDA(At, 0, 1); PG8_STAGE(PG8_SB(0, 0), b2, voffB); PG8_STAGE(PG8_SB(0, 1), b2 + hstepB, voffB); PG8_STAGE(PG8_SA(0, 0), a2, voffA);
;             PG8_WAIT_V(8); PG8_WAIT_L(0); PG8_BAR; PG8_MMA(1, 0, At, B0); PG8_MMA(1, 1, At, B1); PG8_BAR; PG8_SCHED;
	s_setprio 1
	s_waitcnt lgkmcnt(0)
	v_mfma_f32_16x16x32_bf16 v[124:127], v[128:131], v[178:181], v[124:127]
	v_mfma_f32_16x16x32_bf16 v[120:123], v[136:139], v[178:181], v[120:123]
	v_mfma_f32_16x16x32_bf16 v[112:115], v[128:131], v[186:189], v[112:115]
	v_mfma_f32_16x16x32_bf16 v[104:107], v[136:139], v[186:189], v[104:107]
	v_mfma_f32_16x16x32_bf16 v[100:103], v[128:131], v[194:197], v[100:103]
	v_mfma_f32_16x16x32_bf16 v[96:99], v[136:139], v[194:197], v[96:99]
	v_mfma_f32_16x16x32_bf16 v[76:79], v[128:131], v[202:205], v[76:79]
	v_mfma_f32_16x16x32_bf16 v[72:75], v[136:139], v[202:205], v[72:75]
	v_mfma_f32_16x16x32_bf16 v[124:127], v[132:135], v[182:185], v[124:127]
	v_mfma_f32_16x16x32_bf16 v[120:123], v[140:143], v[182:185], v[120:123]
	v_mfma_f32_16x16x32_bf16 v[112:115], v[132:135], v[190:193], v[112:115]
	v_mfma_f32_16x16x32_bf16 v[104:107], v[140:143], v[190:193], v[104:107]
	v_mfma_f32_16x16x32_bf16 v[100:103], v[132:135], v[198:201], v[100:103]
	v_mfma_f32_16x16x32_bf16 v[96:99], v[140:143], v[198:201], v[96:99]
	v_mfma_f32_16x16x32_bf16 v[76:79], v[132:135], v[206:209], v[76:79]
	v_mfma_f32_16x16x32_bf16 v[72:75], v[140:143], v[206:209], v[72:75]
	v_mfma_f32_16x16x32_bf16 v[116:119], v[162:165], v[178:181], v[116:119]
	v_mfma_f32_16x16x32_bf16 v[108:111], v[170:173], v[178:181], v[108:111]
	v_mfma_f32_16x16x32_bf16 v[92:95], v[162:165], v[186:189], v[92:95]
	v_mfma_f32_16x16x32_bf16 v[88:91], v[170:173], v[186:189], v[88:91]
	v_mfma_f32_16x16x32_bf16 v[84:87], v[162:165], v[194:197], v[84:87]
	v_mfma_f32_16x16x32_bf16 v[80:83], v[170:173], v[194:197], v[80:83]
	v_mfma_f32_16x16x32_bf16 v[68:71], v[162:165], v[202:205], v[68:71]
	v_mfma_f32_16x16x32_bf16 v[64:67], v[170:173], v[202:205], v[64:67]
	v_mfma_f32_16x16x32_bf16 v[116:119], v[166:169], v[182:185], v[116:119]
	v_mfma_f32_16x16x32_bf16 v[108:111], v[174:177], v[182:185], v[108:111]
	v_mfma_f32_16x16x32_bf16 v[92:95], v[166:169], v[190:193], v[92:95]
	v_mfma_f32_16x16x32_bf16 v[88:91], v[174:177], v[190:193], v[88:91]
	v_mfma_f32_16x16x32_bf16 v[84:87], v[166:169], v[198:201], v[84:87]
	v_mfma_f32_16x16x32_bf16 v[80:83], v[174:177], v[198:201], v[80:83]
	v_mfma_f32_16x16x32_bf16 v[68:71], v[166:169], v[206:209], v[68:71]
	v_mfma_f32_16x16x32_bf16 v[64:67], v[174:177], v[206:209], v[64:67]
	s_setprio 0
	s_barrier
	s_add_i32 s22, s47, s34
	v_lshl_add_u64 v[210:211], s[24:25], 0, v[148:149]
	s_mov_b32 m0, s22
	ds_read_b128 v[178:181], v216 offset:16384
	ds_read_b128 v[182:185], v216 offset:17408
	ds_read_b128 v[186:189], v216 offset:18432
	ds_read_b128 v[190:193], v216 offset:19456
	ds_read_b128 v[194:197], v216 offset:20480
	ds_read_b128 v[198:201], v216 offset:21504
	ds_read_b128 v[202:205], v216 offset:22528
	ds_read_b128 v[206:209], v216 offset:23552
	global_load_lds_dwordx4 v[210:211], off
	s_add_i32 m0, s22, 0x2000
	s_add_u32 s22, s24, 0x100000
	v_lshl_add_u64 v[218:219], s[24:25], 0, v[144:145]
	s_addc_u32 s23, s25, 0
	s_add_i32 s56, s48, s34
	global_load_lds_dwordx4 v[218:219], off
	v_lshl_add_u64 v[220:221], s[22:23], 0, v[148:149]
	s_mov_b32 m0, s56
	v_lshl_add_u64 v[222:223], s[26:27], 0, v[146:147]
	global_load_lds_dwordx4 v[220:221], off
	v_lshl_add_u64 v[220:221], s[22:23], 0, v[144:145]
	s_add_i32 m0, s56, 0x2000
	s_nop 0
	global_load_lds_dwordx4 v[220:221], off
	v_lshl_add_u64 v[220:221], s[26:27], 0, v[150:151]
	s_mov_b32 m0, s37
	s_nop 0
	global_load_lds_dwordx4 v[220:221], off
	s_mov_b32 m0, s38
	s_nop 0
	global_load_lds_dwordx4 v[222:223], off
	s_waitcnt vmcnt(8)
	s_waitcnt lgkmcnt(0)
	s_barrier
	s_setprio 1
	s_waitcnt lgkmcnt(0)
	v_mfma_f32_16x16x32_bf16 v[60:63], v[128:131], v[178:181], v[60:63]
	v_mfma_f32_16x16x32_bf16 v[56:59], v[136:139], v[178:181], v[56:59]
	v_mfma_f32_16x16x32_bf16 v[48:51], v[128:131], v[186:189], v[48:51]
	v_mfma_f32_16x16x32_bf16 v[40:43], v[136:139], v[186:189], v[40:43]
	v_mfma_f32_16x16x32_bf16 v[32:35], v[128:131], v[194:197], v[32:35]
	v_mfma_f32_16x16x32_bf16 v[24:27], v[136:139], v[194:197], v[24:27]
	v_mfma_f32_16x16x32_bf16 v[16:19], v[128:131], v[202:205], v[16:19]
	v_mfma_f32_16x16x32_bf16 v[8:11], v[136:139], v[202:205], v[8:11]
	v_mfma_f32_16x16x32_bf16 v[60:63], v[132:135], v[182:185], v[60:63]
	v_mfma_f32_16x16x32_bf16 v[56:59], v[140:143], v[182:185], v[56:59]
	v_mfma_f32_16x16x32_bf16 v[48:51], v[132:135], v[190:193], v[48:51]
	v_mfma_f32_16x16x32_bf16 v[40:43], v[140:143], v[190:193], v[40:43]
	v_mfma_f32_16x16x32_bf16 v[32:35], v[132:135], v[198:201], v[32:35]
	v_mfma_f32_16x16x32_bf16 v[24:27], v[140:143], v[198:201], v[24:27]
	v_mfma_f32_16x16x32_bf16 v[16:19], v[132:135], v[206:209], v[16:19]
	v_mfma_f32_16x16x32_bf16 v[8:11], v[140:143], v[206:209], v[8:11]
	v_mfma_f32_16x16x32_bf16 v[52:55], v[162:165], v[178:181], v[52:55]
	v_mfma_f32_16x16x32_bf16 v[44:47], v[170:173], v[178:181], v[44:47]
	v_mfma_f32_16x16x32_bf16 v[36:39], v[162:165], v[186:189], v[36:39]
	v_mfma_f32_16x16x32_bf16 v[28:31], v[170:173], v[186:189], v[28:31]
	v_mfma_f32_16x16x32_bf16 v[20:23], v[162:165], v[194:197], v[20:23]
	v_mfma_f32_16x16x32_bf16 v[12:15], v[170:173], v[194:197], v[12:15]
	v_mfma_f32_16x16x32_bf16 v[4:7], v[162:165], v[202:205], v[4:7]
	v_mfma_f32_16x16x32_bf16 v[0:3], v[170:173], v[202:205], v[0:3]
	v_mfma_f32_16x16x32_bf16 v[52:55], v[166:169], v[182:185], v[52:55]
	v_mfma_f32_16x16x32_bf16 v[44:47], v[174:177], v[182:185], v[44:47]
	v_mfma_f32_16x16x32_bf16 v[36:39], v[166:169], v[190:193], v[36:39]
	v_mfma_f32_16x16x32_bf16 v[28:31], v[174:177], v[190:193], v[28:31]
	v_mfma_f32_16x16x32_bf16 v[20:23], v[166:169], v[198:201], v[20:23]
	v_mfma_f32_16x16x32_bf16 v[12:15], v[174:177], v[198:201], v[12:15]
	v_mfma_f32_16x16x32_bf16 v[4:7], v[166:169], v[206:209], v[4:7]
	v_mfma_f32_16x16x32_bf16 v[0:3], v[174:177], v[206:209], v[0:3]
	s_setprio 0
	s_barrier
; #define PG8_STAGE(bufoff, gbase, voff) do { _Pragma("unroll") for (int _i = 0; _i < 2; ++_i) \
;         __builtin_amdgcn_global_load_lds((const unsigned*)((const char*)(gbase) + (voff)[_i]), (PG8_LAS unsigned*)(lds + (bufoff) + ldsw + _i * 8192), 16, 0, 0); } while (0)
; #define PG8_LDA(dst, b, h) do { _Pragma("unroll") for (int m = 0; m < 4; ++m) _Pragma("unroll") for (int k = 0; k < 2; ++k) dst[m][k] = *(const PG8_LAS bf16x8*)(lds + PG8_SA(b, h) + aoff + m * 2048 + k * 1024); } while (0)
; #define PG8_LDB(dst, b, h) do { _Pragma("unroll") for (int n = 0; n < 2; ++n) _Pragma("unroll") for (int k = 0; k < 2; ++k) dst[n][k] = *(const PG8_LAS bf16x8*)(lds + PG8_SB(b, h) + boff + n * 2048 + k * 1024); } while (0)
; #define PG8_MMA(ai, bj, At, Bt) do { __builtin_amdgcn_s_setprio(1); _Pragma("unroll") for (int m = 0; m < 4; ++m) _Pragma("unroll") for (int n = 0; n < 2; ++n) _Pragma("unroll") for (int k = 0; k < 2; ++k) \
;         acc[ai][bj][m][n] = __builtin_amdgcn_mfma_f32_16x16x32_bf16(Bt[n][k], At[m][k], acc[ai][bj][m][n], 0, 0, 0); __builtin_amdgcn_s_setprio(0); } while (0)
; #define PG8_WAIT_V(n) asm volatile("s_waitcnt vmcnt(" #n ")" ::: "memory")
; #define PG8_WAIT_L(n) asm volatile("s_waitcnt lgkmcnt(" #n ")" ::: "memory")
; #define PG8_BAR __builtin_amdgcn_s_barrier()
; #define PG8_SCHED __builtin_amdgcn_sched_barrier(0)
; template <class Epi, class Sched, bool ALIGN_EPI = false, bool SP2 = false>
; __device__ __forceinline__ void gemm_phase(PG8_LAS unsigned char* lds, const Gemm g, const Sched& S, const Epi& E, const int wave_in) {
;     ...
;             PG8_LDB(B0, 1, 0); PG8_LDB(B1, 1, 1); PG8_SCHED; PG8_LDA(At, 1, 0); PG8_STAGE(PG8_SA(0, 1), a2 + hstepA, voffA);
;             PG8_WAIT_V(8); PG8_WAIT_L(0); PG8_BAR; PG8_MMA(0, 0, At, B0); PG8_MMA(0, 1, At, B1); PG8_BAR; PG8_SCHED;
	s_add_i32 s56, 0, 0x18000
	s_add_i32 s57, 0, 0x1c000
	v_add_u32_e32 v140, s56, v212
	v_add_u32_e32 v174, s57, v212
	ds_read_b128 v[128:131], v140
	ds_read_b128 v[132:135], v140 offset:1024
	ds_read_b128 v[136:139], v140 offset:2048
	ds_read_b128 v[140:143], v140 offset:3072
	ds_read_b128 v[162:165], v174
	ds_read_b128 v[166:169], v174 offset:1024
	ds_read_b128 v[170:173], v174 offset:2048
	ds_read_b128 v[174:177], v174 offset:3072
	s_add_u32 s22, s26, 0x310000
	s_addc_u32 s23, s27, 0
	s_mov_b32 m0, s39
	v_lshl_add_u64 v[224:225], s[22:23], 0, v[150:151]
	ds_read_b128 v[178:181], v216 offset:32768
	ds_read_b128 v[182:185], v216 offset:33792
	ds_read_b128 v[186:189], v216 offset:34816
	ds_read_b128 v[190:193], v216 offset:35840
	ds_read_b128 v[194:197], v216 offset:36864
	ds_read_b128 v[198:201], v216 offset:37888
	ds_read_b128 v[202:205], v216 offset:38912
	ds_read_b128 v[206:209], v216 offset:39936
	global_load_lds_dwordx4 v[224:225], off
	v_lshl_add_u64 v[224:225], s[22:23], 0, v[146:147]
	s_mov_b32 m0, s40
	s_nop 0
	global_load_lds_dwordx4 v[224:225], off
	s_waitcnt vmcnt(8)
	s_waitcnt lgkmcnt(0)
	s_barrier
	s_setprio 1
	s_waitcnt lgkmcnt(0)
	v_mfma_f32_16x16x32_bf16 v[124:127], v[128:131], v[178:181], v[124:127]
	v_mfma_f32_16x16x32_bf16 v[120:123], v[136:139], v[178:181], v[120:123]
	v_mfma_f32_16x16x32_bf16 v[112:115], v[128:131], v[186:189], v[112:115]
	v_mfma_f32_16x16x32_bf16 v[104:107], v[136:139], v[186:189], v[104:107]
	v_mfma_f32_16x16x32_bf16 v[100:103], v[128:131], v[194:197], v[100:103]
	v_mfma_f32_16x16x32_bf16 v[96:99], v[136:139], v[194:197], v[96:99]
	v_mfma_f32_16x16x32_bf16 v[76:79], v[128:131], v[202:205], v[76:79]
	v_mfma_f32_16x16x32_bf16 v[72:75], v[136:139], v[202:205], v[72:75]
	v_mfma_f32_16x16x32_bf16 v[124:127], v[132:135], v[182:185], v[124:127]
	v_mfma_f32_16x16x32_bf16 v[120:123], v[140:143], v[182:185], v[120:123]
	v_mfma_f32_16x16x32_bf16 v[112:115], v[132:135], v[190:193], v[112:115]
	v_mfma_f32_16x16x32_bf16 v[104:107], v[140:143], v[190:193], v[104:107]
	v_mfma_f32_16x16x32_bf16 v[100:103], v[132:135], v[198:201], v[100:103]
	v_mfma_f32_16x16x32_bf16 v[96:99], v[140:143], v[198:201], v[96:99]
	v_mfma_f32_16x16x32_bf16 v[76:79], v[132:135], v[206:209], v[76:79]
	v_mfma_f32_16x16x32_bf16 v[72:75], v[140:143], v[206:209], v[72:75]
	v_mfma_f32_16x16x32_bf16 v[116:119], v[162:165], v[178:181], v[116:119]
	v_mfma_f32_16x16x32_bf16 v[108:111], v[170:173], v[178:181], v[108:111]
	v_mfma_f32_16x16x32_bf16 v[92:95], v[162:165], v[186:189], v[92:95]
	v_mfma_f32_16x16x32_bf16 v[88:91], v[170:173], v[186:189], v[88:91]
	v_mfma_f32_16x16x32_bf16 v[84:87], v[162:165], v[194:197], v[84:87]
	v_mfma_f32_16x16x32_bf16 v[80:83], v[170:173], v[194:197], v[80:83]
	v_mfma_f32_16x16x32_bf16 v[68:71], v[162:165], v[202:205], v[68:71]
	v_mfma_f32_16x16x32_bf16 v[64:67], v[170:173], v[202:205], v[64:67]
	v_mfma_f32_16x16x32_bf16 v[116:119], v[166:169], v[182:185], v[116:119]
	v_mfma_f32_16x16x32_bf16 v[108:111], v[174:177], v[182:185], v[108:111]
	v_mfma_f32_16x16x32_bf16 v[92:95], v[166:169], v[190:193], v[92:95]
	v_mfma_f32_16x16x32_bf16 v[88:91], v[174:177], v[190:193], v[88:91]
	v_mfma_f32_16x16x32_bf16 v[84:87], v[166:169], v[198:201], v[84:87]
	v_mfma_f32_16x16x32_bf16 v[80:83], v[174:177], v[198:201], v[80:83]
	v_mfma_f32_16x16x32_bf16 v[68:71], v[166:169], v[206:209], v[68:71]
	v_mfma_f32_16x16x32_bf16 v[64:67], v[174:177], v[206:209], v[64:67]
	s_setprio 0
	s_barrier
; #define PG8_STAGE(bufoff, gbase, voff) do { _Pragma("unroll") for (int _i = 0; _i < 2; ++_i) \
;         __builtin_amdgcn_global_load_lds((const unsigned*)((const char*)(gbase) + (voff)[_i]), (PG8_LAS unsigned*)(lds + (bufoff) + ldsw + _i * 8192), 16, 0, 0); } while (0)
; #define PG8_LDA(dst, b, h) do { _Pragma("unroll") for (int m = 0; m < 4; ++m) _Pragma("unroll") for (int k = 0; k < 2; ++k) dst[m][k] = *(const PG8_LAS bf16x8*)(lds + PG8_SA(b, h) + aoff + m * 2048 + k * 1024); } while (0)
; #define PG8_MMA(ai, bj, At, Bt) do { __builtin_amdgcn_s_setprio(1); _Pragma("unroll") for (int m = 0; m < 4; ++m) _Pragma("unroll") for (int n = 0; n < 2; ++n) _Pragma("unroll") for (int k = 0; k < 2; ++k) \
;         acc[ai][bj][m][n] = __builtin_amdgcn_mfma_f32_16x16x32_bf16(Bt[n][k], At[m][k], acc[ai][bj][m][n], 0, 0, 0); __builtin_amdgcn_s_setprio(0); } while (0)
; #define PG8_WAIT_V(n) asm volatile("s_waitcnt vmcnt(" #n ")" ::: "memory")
; #define PG8_WAIT_L(n) asm volatile("s_waitcnt lgkmcnt(" #n ")" ::: "memory")
; #define PG8_BAR __builtin_amdgcn_s_barrier()
; #define PG8_SCHED __builtin_amdgcn_sched_barrier(0)
; template <class Epi, class Sched, bool ALIGN_EPI = false, bool SP2 = false>
; __device__ __forceinline__ void gemm_phase(PG8_LAS unsigned char* lds, const Gemm g, const Sched& S, const Epi& E, const int wave_in) {
;     ...
;         for (int t = 0; t < nt; t += 2) {
;     ...
;             PG8_LDA(At, 1, 1); PG8_STAGE(PG8_SB(1, 0), b3, voffB); PG8_STAGE(PG8_SB(1, 1), b3 + hstepB, voffB); PG8_STAGE(PG8_SA(1, 0), a3, voffA);
;             PG8_WAIT_V(8); PG8_WAIT_L(0); PG8_BAR; PG8_MMA(1, 0, At, B0); PG8_MMA(1, 1, At, B1); PG8_BAR; PG8_SCHED;
	s_add_i32 s22, s56, s34
	v_lshl_add_u64 v[210:211], v[210:211], 0, s[6:7]
	s_mov_b32 m0, s22
	ds_read_b128 v[178:181], v216 offset:49152
	ds_read_b128 v[182:185], v216 offset:50176
	ds_read_b128 v[186:189], v216 offset:51200
	ds_read_b128 v[190:193], v216 offset:52224
	ds_read_b128 v[194:197], v216 offset:53248
	ds_read_b128 v[198:201], v216 offset:54272
	ds_read_b128 v[202:205], v216 offset:55296
	ds_read_b128 v[206:209], v216 offset:56320
	global_load_lds_dwordx4 v[210:211], off
	s_add_i32 m0, s22, 0x2000
	s_add_u32 s22, s24, 0x100080
	v_lshl_add_u64 v[210:211], v[218:219], 0, s[6:7]
	s_addc_u32 s23, s25, 0
	s_add_i32 s24, s57, s34
	global_load_lds_dwordx4 v[210:211], off
	v_lshl_add_u64 v[210:211], s[22:23], 0, v[148:149]
	s_mov_b32 m0, s24
	s_nop 0
	global_load_lds_dwordx4 v[210:211], off
	v_lshl_add_u64 v[210:211], s[22:23], 0, v[144:145]
	s_add_i32 m0, s24, 0x2000
	s_nop 0
	global_load_lds_dwordx4 v[210:211], off
	v_lshl_add_u64 v[210:211], v[220:221], 0, s[6:7]
	s_mov_b32 m0, s44
	s_nop 0
	global_load_lds_dwordx4 v[210:211], off
	v_lshl_add_u64 v[210:211], v[222:223], 0, s[6:7]
	s_mov_b32 m0, s45
	s_nop 0
	global_load_lds_dwordx4 v[210:211], off
	s_waitcnt vmcnt(8)
	s_waitcnt lgkmcnt(0)
	s_barrier
	s_setprio 1
	s_waitcnt lgkmcnt(0)
	v_mfma_f32_16x16x32_bf16 v[60:63], v[128:131], v[178:181], v[60:63]
	v_mfma_f32_16x16x32_bf16 v[56:59], v[136:139], v[178:181], v[56:59]
	v_mfma_f32_16x16x32_bf16 v[48:51], v[128:131], v[186:189], v[48:51]
	v_mfma_f32_16x16x32_bf16 v[40:43], v[136:139], v[186:189], v[40:43]
	v_mfma_f32_16x16x32_bf16 v[32:35], v[128:131], v[194:197], v[32:35]
	v_mfma_f32_16x16x32_bf16 v[24:27], v[136:139], v[194:197], v[24:27]
	v_mfma_f32_16x16x32_bf16 v[16:19], v[128:131], v[202:205], v[16:19]
	v_mfma_f32_16x16x32_bf16 v[8:11], v[136:139], v[202:205], v[8:11]
	v_mfma_f32_16x16x32_bf16 v[60:63], v[132:135], v[182:185], v[60:63]
	v_mfma_f32_16x16x32_bf16 v[56:59], v[140:143], v[182:185], v[56:59]
	v_mfma_f32_16x16x32_bf16 v[48:51], v[132:135], v[190:193], v[48:51]
	v_mfma_f32_16x16x32_bf16 v[40:43], v[140:143], v[190:193], v[40:43]
	v_mfma_f32_16x16x32_bf16 v[32:35], v[132:135], v[198:201], v[32:35]
	v_mfma_f32_16x16x32_bf16 v[24:27], v[140:143], v[198:201], v[24:27]
	v_mfma_f32_16x16x32_bf16 v[16:19], v[132:135], v[206:209], v[16:19]
	v_mfma_f32_16x16x32_bf16 v[8:11], v[140:143], v[206:209], v[8:11]
	v_mfma_f32_16x16x32_bf16 v[52:55], v[162:165], v[178:181], v[52:55]
	v_mfma_f32_16x16x32_bf16 v[44:47], v[170:173], v[178:181], v[44:47]
	v_mfma_f32_16x16x32_bf16 v[36:39], v[162:165], v[186:189], v[36:39]
	v_mfma_f32_16x16x32_bf16 v[28:31], v[170:173], v[186:189], v[28:31]
	v_mfma_f32_16x16x32_bf16 v[20:23], v[162:165], v[194:197], v[20:23]
	v_mfma_f32_16x16x32_bf16 v[12:15], v[170:173], v[194:197], v[12:15]
	v_mfma_f32_16x16x32_bf16 v[4:7], v[162:165], v[202:205], v[4:7]
	v_mfma_f32_16x16x32_bf16 v[0:3], v[170:173], v[202:205], v[0:3]
	v_mfma_f32_16x16x32_bf16 v[52:55], v[166:169], v[182:185], v[52:55]
	v_mfma_f32_16x16x32_bf16 v[44:47], v[174:177], v[182:185], v[44:47]
	v_mfma_f32_16x16x32_bf16 v[36:39], v[166:169], v[190:193], v[36:39]
	v_mfma_f32_16x16x32_bf16 v[28:31], v[174:177], v[190:193], v[28:31]
	v_mfma_f32_16x16x32_bf16 v[20:23], v[166:169], v[198:201], v[20:23]
	v_mfma_f32_16x16x32_bf16 v[12:15], v[174:177], v[198:201], v[12:15]
	v_mfma_f32_16x16x32_bf16 v[4:7], v[166:169], v[206:209], v[4:7]
	v_mfma_f32_16x16x32_bf16 v[0:3], v[174:177], v[206:209], v[0:3]
	s_setprio 0
	s_barrier
	s_add_i32 s55, s55, 2
	s_add_u32 s53, s53, 0x100
	s_addc_u32 s54, s54, 0
	s_cmp_gt_u32 s55, 61
	s_mov_b64 s[22:23], s[4:5]
	s_cbranch_scc0 .LBB0_1093

; #define PG8_STAGE(bufoff, gbase, voff) do { _Pragma("unroll") for (int _i = 0; _i < 2; ++_i) \
;         __builtin_amdgcn_global_load_lds((const unsigned*)((const char*)(gbase) + (voff)[_i]), (PG8_LAS unsigned*)(lds + (bufoff) + ldsw + _i * 8192), 16, 0, 0); } while (0)
; #define PG8_LDA(dst, b, h) do { _Pragma("unroll") for (int m = 0; m < 4; ++m) _Pragma("unroll") for (int k = 0; k < 2; ++k) dst[m][k] = *(const PG8_LAS bf16x8*)(lds + PG8_SA(b, h) + aoff + m * 2048 + k * 1024); } while (0)
; #define PG8_LDB(dst, b, h) do { _Pragma("unroll") for (int n = 0; n < 2; ++n) _Pragma("unroll") for (int k = 0; k < 2; ++k) dst[n][k] = *(const PG8_LAS bf16x8*)(lds + PG8_SB(b, h) + boff + n * 2048 + k * 1024); } while (0)
; #define PG8_MMA(ai, bj, At, Bt) do { __builtin_amdgcn_s_setprio(1); _Pragma("unroll") for (int m = 0; m < 4; ++m) _Pragma("unroll") for (int n = 0; n < 2; ++n) _Pragma("unroll") for (int k = 0; k < 2; ++k) \
;         acc[ai][bj][m][n] = __builtin_amdgcn_mfma_f32_16x16x32_bf16(Bt[n][k], At[m][k], acc[ai][bj][m][n], 0, 0, 0); __builtin_amdgcn_s_setprio(0); } while (0)
; #define PG8_WAIT_V(n) asm volatile("s_waitcnt vmcnt(" #n ")" ::: "memory")
; #define PG8_WAIT_L(n) asm volatile("s_waitcnt lgkmcnt(" #n ")" ::: "memory")
; #define PG8_BAR __builtin_amdgcn_s_barrier()
; template <class Epi, class Sched, bool ALIGN_EPI = false, bool SP2 = false>
; __device__ __forceinline__ void gemm_phase(PG8_LAS unsigned char* lds, const Gemm g, const Sched& S, const Epi& E, const int wave_in) {
;     ...
;         for (int t = 0; t < nt; t += 2) {
;             const bool last = (t == nt - 2);
;             const char* a1 = cA + (size_t)(t + 1) * kstep;
;             const char* a2 = last ? nA : cA + (size_t)(t + 2) * kstep; const char* b2 = last ? nB : cB + (size_t)(t + 2) * kstep;
;             const char* a3 = a2 + kstep; const char* b3 = b2 + kstep;
;             if (last && has_next) S.a_ready(nxt);
;             if constexpr (SP2) {
;             PG8_LDB(B0, 0, 0); PG8_LDB(B1, 0, 1); PG8_SCHED; PG8_LDA(At, 0, 0); PG8_STAGE(PG8_SA(1, 1), a1 + hstepA, voffA);
;             PG8_WAIT_V(8); PG8_WAIT_L(0); PG8_BAR; PG8_MMA(0, 0, At, B0); PG8_MMA(0, 1, At, B1); PG8_BAR; PG8_SCHED;
;             PG8_LDA(At, 0, 1); PG8_STAGE(PG8_SB(0, 0), b2, voffB); PG8_STAGE(PG8_SB(0, 1), b2 + hstepB, voffB); PG8_STAGE(PG8_SA(0, 0), a2, voffA);
.LBB0_1374:
	s_add_u32 s17, s20, 0x100
	v_mov_b32_e32 v0, 0
	s_addc_u32 s53, s21, 0
	s_mov_b32 s54, -2
	ds_read_b128 v[128:131], v214
	ds_read_b128 v[132:135], v214 offset:1024
	ds_read_b128 v[136:139], v214 offset:2048
	ds_read_b128 v[140:143], v214 offset:3072
	ds_read_b128 v[162:165], v215
	ds_read_b128 v[166:169], v215 offset:1024
	ds_read_b128 v[170:173], v215 offset:2048
	ds_read_b128 v[174:177], v215 offset:3072
	s_add_u32 s20, s18, 0x100
	s_addc_u32 s21, s19, 0
	s_cmpk_eq_i32 s54, 0x52
	s_cselect_b32 s25, s5, s21
	s_cselect_b32 s24, s4, s20
	s_cselect_b32 s23, s15, s53
	s_cselect_b32 s22, s14, s17
	v_lshl_add_u64 v[210:211], s[18:19], 0, v[154:155]
	s_add_i32 m0, s35, 0xc000
	ds_read_b128 v[178:181], v216
	ds_read_b128 v[182:185], v216 offset:1024
	ds_read_b128 v[186:189], v216 offset:2048
	ds_read_b128 v[190:193], v216 offset:3072
	ds_read_b128 v[194:197], v216 offset:4096
	ds_read_b128 v[198:201], v216 offset:5120
	ds_read_b128 v[202:205], v216 offset:6144
	ds_read_b128 v[206:209], v216 offset:7168
	global_load_lds_dwordx4 v[210:211], off
	v_lshl_add_u64 v[210:211], s[18:19], 0, v[156:157]
	s_add_i32 m0, s35, 0xe000
	s_nop 0
	global_load_lds_dwordx4 v[210:211], off
	s_waitcnt vmcnt(8)
	s_waitcnt lgkmcnt(0)
	s_barrier
	s_setprio 1
	s_waitcnt lgkmcnt(0)
	v_mfma_f32_16x16x32_bf16 v[124:127], v[128:131], v[178:181], 0
	v_mfma_f32_16x16x32_bf16 v[120:123], v[136:139], v[178:181], 0
	v_mfma_f32_16x16x32_bf16 v[112:115], v[128:131], v[186:189], 0
	v_mfma_f32_16x16x32_bf16 v[104:107], v[136:139], v[186:189], 0
	v_mfma_f32_16x16x32_bf16 v[100:103], v[128:131], v[194:197], 0
	v_mfma_f32_16x16x32_bf16 v[96:99], v[136:139], v[194:197], 0
	v_mfma_f32_16x16x32_bf16 v[76:79], v[128:131], v[202:205], 0
	v_mfma_f32_16x16x32_bf16 v[72:75], v[136:139], v[202:205], 0
	v_mfma_f32_16x16x32_bf16 v[124:127], v[132:135], v[182:185], v[124:127]
	v_mfma_f32_16x16x32_bf16 v[120:123], v[140:143], v[182:185], v[120:123]
	v_mfma_f32_16x16x32_bf16 v[112:115], v[132:135], v[190:193], v[112:115]
	v_mfma_f32_16x16x32_bf16 v[104:107], v[140:143], v[190:193], v[104:107]
	v_mfma_f32_16x16x32_bf16 v[100:103], v[132:135], v[198:201], v[100:103]
	v_mfma_f32_16x16x32_bf16 v[96:99], v[140:143], v[198:201], v[96:99]
	v_mfma_f32_16x16x32_bf16 v[76:79], v[132:135], v[206:209], v[76:79]
	v_mfma_f32_16x16x32_bf16 v[72:75], v[140:143], v[206:209], v[72:75]
	v_mfma_f32_16x16x32_bf16 v[116:119], v[162:165], v[178:181], 0
	v_mfma_f32_16x16x32_bf16 v[108:111], v[170:173], v[178:181], 0
	v_mfma_f32_16x16x32_bf16 v[92:95], v[162:165], v[186:189], 0
	v_mfma_f32_16x16x32_bf16 v[88:91], v[170:173], v[186:189], 0
	v_mfma_f32_16x16x32_bf16 v[84:87], v[162:165], v[194:197], 0
	v_mfma_f32_16x16x32_bf16 v[80:83], v[170:173], v[194:197], 0
	v_mfma_f32_16x16x32_bf16 v[68:71], v[162:165], v[202:205], 0
	v_mfma_f32_16x16x32_bf16 v[64:67], v[170:173], v[202:205], 0
	v_mfma_f32_16x16x32_bf16 v[116:119], v[166:169], v[182:185], v[116:119]
	v_mfma_f32_16x16x32_bf16 v[108:111], v[174:177], v[182:185], v[108:111]
	v_mfma_f32_16x16x32_bf16 v[92:95], v[166:169], v[190:193], v[92:95]
	v_mfma_f32_16x16x32_bf16 v[88:91], v[174:177], v[190:193], v[88:91]
	v_mfma_f32_16x16x32_bf16 v[84:87], v[166:169], v[198:201], v[84:87]
	v_mfma_f32_16x16x32_bf16 v[80:83], v[174:177], v[198:201], v[80:83]
	v_mfma_f32_16x16x32_bf16 v[68:71], v[166:169], v[206:209], v[68:71]
	v_mfma_f32_16x16x32_bf16 v[64:67], v[174:177], v[206:209], v[64:67]
	s_setprio 0
	s_barrier
	s_add_i32 s18, s45, s30
	v_lshl_add_u64 v[210:211], s[22:23], 0, v[148:149]
	s_mov_b32 m0, s18
	ds_read_b128 v[178:181], v216 offset:16384
	ds_read_b128 v[182:185], v216 offset:17408
	ds_read_b128 v[186:189], v216 offset:18432
	ds_read_b128 v[190:193], v216 offset:19456
	ds_read_b128 v[194:197], v216 offset:20480
	ds_read_b128 v[198:201], v216 offset:21504
	ds_read_b128 v[202:205], v216 offset:22528
	ds_read_b128 v[206:209], v216 offset:23552
	global_load_lds_dwordx4 v[210:211], off
	s_add_i32 m0, s18, 0x2000
	s_add_u32 s18, s22, 0x158000
	v_lshl_add_u64 v[218:219], s[22:23], 0, v[144:145]
	s_addc_u32 s19, s23, 0
	s_add_i32 s55, s46, s30
	global_load_lds_dwordx4 v[218:219], off
	v_lshl_add_u64 v[220:221], s[18:19], 0, v[148:149]
	s_mov_b32 m0, s55
	v_lshl_add_u64 v[222:223], s[24:25], 0, v[146:147]
	global_load_lds_dwordx4 v[220:221], off
	v_lshl_add_u64 v[220:221], s[18:19], 0, v[144:145]
	s_add_i32 m0, s55, 0x2000
	s_nop 0
	global_load_lds_dwordx4 v[220:221], off
	v_lshl_add_u64 v[220:221], s[24:25], 0, v[150:151]
	s_mov_b32 m0, s35
	s_nop 0
	global_load_lds_dwordx4 v[220:221], off
	s_mov_b32 m0, s36
	s_nop 0
	global_load_lds_dwordx4 v[222:223], off
	s_waitcnt vmcnt(8)
	s_waitcnt lgkmcnt(0)
	s_barrier
; #define PG8_STAGE(bufoff, gbase, voff) do { _Pragma("unroll") for (int _i = 0; _i < 2; ++_i) \
;         __builtin_amdgcn_global_load_lds((const unsigned*)((const char*)(gbase) + (voff)[_i]), (PG8_LAS unsigned*)(lds + (bufoff) + ldsw + _i * 8192), 16, 0, 0); } while (0)
; #define PG8_LDA(dst, b, h) do { _Pragma("unroll") for (int m = 0; m < 4; ++m) _Pragma("unroll") for (int k = 0; k < 2; ++k) dst[m][k] = *(const PG8_LAS bf16x8*)(lds + PG8_SA(b, h) + aoff + m * 2048 + k * 1024); } while (0)
; #define PG8_LDB(dst, b, h) do { _Pragma("unroll") for (int n = 0; n < 2; ++n) _Pragma("unroll") for (int k = 0; k < 2; ++k) dst[n][k] = *(const PG8_LAS bf16x8*)(lds + PG8_SB(b, h) + boff + n * 2048 + k * 1024); } while (0)
; #define PG8_MMA(ai, bj, At, Bt) do { __builtin_amdgcn_s_setprio(1); _Pragma("unroll") for (int m = 0; m < 4; ++m) _Pragma("unroll") for (int n = 0; n < 2; ++n) _Pragma("unroll") for (int k = 0; k < 2; ++k) \
;         acc[ai][bj][m][n] = __builtin_amdgcn_mfma_f32_16x16x32_bf16(Bt[n][k], At[m][k], acc[ai][bj][m][n], 0, 0, 0); __builtin_amdgcn_s_setprio(0); } while (0)
; #define PG8_WAIT_V(n) asm volatile("s_waitcnt vmcnt(" #n ")" ::: "memory")
; #define PG8_WAIT_L(n) asm volatile("s_waitcnt lgkmcnt(" #n ")" ::: "memory")
; #define PG8_BAR __builtin_amdgcn_s_barrier()
; #define PG8_SCHED __builtin_amdgcn_sched_barrier(0)
; template <class Epi, class Sched, bool ALIGN_EPI = false, bool SP2 = false>
; __device__ __forceinline__ void gemm_phase(PG8_LAS unsigned char* lds, const Gemm g, const Sched& S, const Epi& E, const int wave_in) {
;     ...
;             PG8_WAIT_V(8); PG8_WAIT_L(0); PG8_BAR; PG8_MMA(1, 0, At, B0); PG8_MMA(1, 1, At, B1); PG8_BAR; PG8_SCHED;
;             PG8_LDB(B0, 1, 0); PG8_LDB(B1, 1, 1); PG8_SCHED; PG8_LDA(At, 1, 0); PG8_STAGE(PG8_SA(0, 1), a2 + hstepA, voffA);
;             PG8_WAIT_V(8); PG8_WAIT_L(0); PG8_BAR; PG8_MMA(0, 0, At, B0); PG8_MMA(0, 1, At, B1); PG8_BAR; PG8_SCHED;
	s_setprio 1
	s_waitcnt lgkmcnt(0)
	v_mfma_f32_16x16x32_bf16 v[60:63], v[128:131], v[178:181], 0
	v_mfma_f32_16x16x32_bf16 v[56:59], v[136:139], v[178:181], 0
	v_mfma_f32_16x16x32_bf16 v[48:51], v[128:131], v[186:189], 0
	v_mfma_f32_16x16x32_bf16 v[40:43], v[136:139], v[186:189], 0
	v_mfma_f32_16x16x32_bf16 v[32:35], v[128:131], v[194:197], 0
	v_mfma_f32_16x16x32_bf16 v[24:27], v[136:139], v[194:197], 0
	v_mfma_f32_16x16x32_bf16 v[16:19], v[128:131], v[202:205], 0
	v_mfma_f32_16x16x32_bf16 v[8:11], v[136:139], v[202:205], 0
	v_mfma_f32_16x16x32_bf16 v[60:63], v[132:135], v[182:185], v[60:63]
	v_mfma_f32_16x16x32_bf16 v[56:59], v[140:143], v[182:185], v[56:59]
	v_mfma_f32_16x16x32_bf16 v[48:51], v[132:135], v[190:193], v[48:51]
	v_mfma_f32_16x16x32_bf16 v[40:43], v[140:143], v[190:193], v[40:43]
	v_mfma_f32_16x16x32_bf16 v[32:35], v[132:135], v[198:201], v[32:35]
	v_mfma_f32_16x16x32_bf16 v[24:27], v[140:143], v[198:201], v[24:27]
	v_mfma_f32_16x16x32_bf16 v[16:19], v[132:135], v[206:209], v[16:19]
	v_mfma_f32_16x16x32_bf16 v[8:11], v[140:143], v[206:209], v[8:11]
	v_mfma_f32_16x16x32_bf16 v[52:55], v[162:165], v[178:181], 0
	v_mfma_f32_16x16x32_bf16 v[44:47], v[170:173], v[178:181], 0
	v_mfma_f32_16x16x32_bf16 v[36:39], v[162:165], v[186:189], 0
	v_mfma_f32_16x16x32_bf16 v[28:31], v[170:173], v[186:189], 0
	v_mfma_f32_16x16x32_bf16 v[20:23], v[162:165], v[194:197], 0
	v_mfma_f32_16x16x32_bf16 v[12:15], v[170:173], v[194:197], 0
	v_mfma_f32_16x16x32_bf16 v[4:7], v[162:165], v[202:205], 0
	v_mfma_f32_16x16x32_bf16 v[0:3], v[170:173], v[202:205], 0
	v_mfma_f32_16x16x32_bf16 v[52:55], v[166:169], v[182:185], v[52:55]
	v_mfma_f32_16x16x32_bf16 v[44:47], v[174:177], v[182:185], v[44:47]
	v_mfma_f32_16x16x32_bf16 v[36:39], v[166:169], v[190:193], v[36:39]
	v_mfma_f32_16x16x32_bf16 v[28:31], v[174:177], v[190:193], v[28:31]
	v_mfma_f32_16x16x32_bf16 v[20:23], v[166:169], v[198:201], v[20:23]
	v_mfma_f32_16x16x32_bf16 v[12:15], v[174:177], v[198:201], v[12:15]
	v_mfma_f32_16x16x32_bf16 v[4:7], v[166:169], v[206:209], v[4:7]
	v_mfma_f32_16x16x32_bf16 v[0:3], v[174:177], v[206:209], v[0:3]
	s_setprio 0
	s_barrier
	s_add_i32 s55, 0, 0x18000
	s_add_i32 s56, 0, 0x1c000
	v_add_u32_e32 v140, s55, v212
	v_add_u32_e32 v174, s56, v212
	ds_read_b128 v[128:131], v140
	ds_read_b128 v[132:135], v140 offset:1024
	ds_read_b128 v[136:139], v140 offset:2048
	ds_read_b128 v[140:143], v140 offset:3072
	ds_read_b128 v[162:165], v174
	ds_read_b128 v[166:169], v174 offset:1024
	ds_read_b128 v[170:173], v174 offset:2048
	ds_read_b128 v[174:177], v174 offset:3072
	s_add_u32 s18, s24, 0x158000
	s_addc_u32 s19, s25, 0
	s_mov_b32 m0, s37
	v_lshl_add_u64 v[224:225], s[18:19], 0, v[150:151]
	ds_read_b128 v[178:181], v216 offset:32768
	ds_read_b128 v[182:185], v216 offset:33792
	ds_read_b128 v[186:189], v216 offset:34816
	ds_read_b128 v[190:193], v216 offset:35840
	ds_read_b128 v[194:197], v216 offset:36864
	ds_read_b128 v[198:201], v216 offset:37888
	ds_read_b128 v[202:205], v216 offset:38912
	ds_read_b128 v[206:209], v216 offset:39936
	global_load_lds_dwordx4 v[224:225], off
	v_lshl_add_u64 v[224:225], s[18:19], 0, v[146:147]
	s_mov_b32 m0, s38
	s_nop 0
	global_load_lds_dwordx4 v[224:225], off
	s_waitcnt vmcnt(8)
	s_waitcnt lgkmcnt(0)
	s_barrier
	s_setprio 1
	s_waitcnt lgkmcnt(0)
	v_mfma_f32_16x16x32_bf16 v[124:127], v[128:131], v[178:181], v[124:127]
	v_mfma_f32_16x16x32_bf16 v[120:123], v[136:139], v[178:181], v[120:123]
	v_mfma_f32_16x16x32_bf16 v[112:115], v[128:131], v[186:189], v[112:115]
	v_mfma_f32_16x16x32_bf16 v[104:107], v[136:139], v[186:189], v[104:107]
	v_mfma_f32_16x16x32_bf16 v[100:103], v[128:131], v[194:197], v[100:103]
	v_mfma_f32_16x16x32_bf16 v[96:99], v[136:139], v[194:197], v[96:99]
	v_mfma_f32_16x16x32_bf16 v[76:79], v[128:131], v[202:205], v[76:79]
	v_mfma_f32_16x16x32_bf16 v[72:75], v[136:139], v[202:205], v[72:75]
	v_mfma_f32_16x16x32_bf16 v[124:127], v[132:135], v[182:185], v[124:127]
	v_mfma_f32_16x16x32_bf16 v[120:123], v[140:143], v[182:185], v[120:123]
	v_mfma_f32_16x16x32_bf16 v[112:115], v[132:135], v[190:193], v[112:115]
	v_mfma_f32_16x16x32_bf16 v[104:107], v[140:143], v[190:193], v[104:107]
	v_mfma_f32_16x16x32_bf16 v[100:103], v[132:135], v[198:201], v[100:103]
	v_mfma_f32_16x16x32_bf16 v[96:99], v[140:143], v[198:201], v[96:99]
	v_mfma_f32_16x16x32_bf16 v[76:79], v[132:135], v[206:209], v[76:79]
	v_mfma_f32_16x16x32_bf16 v[72:75], v[140:143], v[206:209], v[72:75]
	v_mfma_f32_16x16x32_bf16 v[116:119], v[162:165], v[178:181], v[116:119]
	v_mfma_f32_16x16x32_bf16 v[108:111], v[170:173], v[178:181], v[108:111]
	v_mfma_f32_16x16x32_bf16 v[92:95], v[162:165], v[186:189], v[92:95]
	v_mfma_f32_16x16x32_bf16 v[88:91], v[170:173], v[186:189], v[88:91]
	v_mfma_f32_16x16x32_bf16 v[84:87], v[162:165], v[194:197], v[84:87]
	v_mfma_f32_16x16x32_bf16 v[80:83], v[170:173], v[194:197], v[80:83]
	v_mfma_f32_16x16x32_bf16 v[68:71], v[162:165], v[202:205], v[68:71]
	v_mfma_f32_16x16x32_bf16 v[64:67], v[170:173], v[202:205], v[64:67]
	v_mfma_f32_16x16x32_bf16 v[116:119], v[166:169], v[182:185], v[116:119]
	v_mfma_f32_16x16x32_bf16 v[108:111], v[174:177], v[182:185], v[108:111]
	v_mfma_f32_16x16x32_bf16 v[92:95], v[166:169], v[190:193], v[92:95]
	v_mfma_f32_16x16x32_bf16 v[88:91], v[174:177], v[190:193], v[88:91]
	v_mfma_f32_16x16x32_bf16 v[84:87], v[166:169], v[198:201], v[84:87]
	v_mfma_f32_16x16x32_bf16 v[80:83], v[174:177], v[198:201], v[80:83]
	v_mfma_f32_16x16x32_bf16 v[68:71], v[166:169], v[206:209], v[68:71]
	v_mfma_f32_16x16x32_bf16 v[64:67], v[174:177], v[206:209], v[64:67]
	s_setprio 0
	s_barrier
; #define PG8_STAGE(bufoff, gbase, voff) do { _Pragma("unroll") for (int _i = 0; _i < 2; ++_i) \
;         __builtin_amdgcn_global_load_lds((const unsigned*)((const char*)(gbase) + (voff)[_i]), (PG8_LAS unsigned*)(lds + (bufoff) + ldsw + _i * 8192), 16, 0, 0); } while (0)
; #define PG8_LDA(dst, b, h) do { _Pragma("unroll") for (int m = 0; m < 4; ++m) _Pragma("unroll") for (int k = 0; k < 2; ++k) dst[m][k] = *(const PG8_LAS bf16x8*)(lds + PG8_SA(b, h) + aoff + m * 2048 + k * 1024); } while (0)
; #define PG8_LDB(dst, b, h) do { _Pragma("unroll") for (int n = 0; n < 2; ++n) _Pragma("unroll") for (int k = 0; k < 2; ++k) dst[n][k] = *(const PG8_LAS bf16x8*)(lds + PG8_SB(b, h) + boff + n * 2048 + k * 1024); } while (0)
; #define PG8_MMA(ai, bj, At, Bt) do { __builtin_amdgcn_s_setprio(1); _Pragma("unroll") for (int m = 0; m < 4; ++m) _Pragma("unroll") for (int n = 0; n < 2; ++n) _Pragma("unroll") for (int k = 0; k < 2; ++k) \
;         acc[ai][bj][m][n] = __builtin_amdgcn_mfma_f32_16x16x32_bf16(Bt[n][k], At[m][k], acc[ai][bj][m][n], 0, 0, 0); __builtin_amdgcn_s_setprio(0); } while (0)
; #define PG8_WAIT_V(n) asm volatile("s_waitcnt vmcnt(" #n ")" ::: "memory")
; #define PG8_WAIT_L(n) asm volatile("s_waitcnt lgkmcnt(" #n ")" ::: "memory")
; #define PG8_BAR __builtin_amdgcn_s_barrier()
; template <class Epi, class Sched, bool ALIGN_EPI = false, bool SP2 = false>
; __device__ __forceinline__ void gemm_phase(PG8_LAS unsigned char* lds, const Gemm g, const Sched& S, const Epi& E, const int wave_in) {
;     ...
;         for (int t = 0; t < nt; t += 2) {
;             const bool last = (t == nt - 2);
;             const char* a1 = cA + (size_t)(t + 1) * kstep;
;             const char* a2 = last ? nA : cA + (size_t)(t + 2) * kstep; const char* b2 = last ? nB : cB + (size_t)(t + 2) * kstep;
;             const char* a3 = a2 + kstep; const char* b3 = b2 + kstep;
;             if (last && has_next) S.a_ready(nxt);
;             if constexpr (SP2) {
;             PG8_LDB(B0, 0, 0); PG8_LDB(B1, 0, 1); PG8_SCHED; PG8_LDA(At, 0, 0); PG8_STAGE(PG8_SA(1, 1), a1 + hstepA, voffA);
;     ...
;             PG8_LDA(At, 1, 1); PG8_STAGE(PG8_SB(1, 0), b3, voffB); PG8_STAGE(PG8_SB(1, 1), b3 + hstepB, voffB); PG8_STAGE(PG8_SA(1, 0), a3, voffA);
;             PG8_WAIT_V(8); PG8_WAIT_L(0); PG8_BAR; PG8_MMA(1, 0, At, B0); PG8_MMA(1, 1, At, B1); PG8_BAR; PG8_SCHED;
	s_add_i32 s18, s55, s30
	v_lshl_add_u64 v[210:211], v[210:211], 0, s[6:7]
	s_mov_b32 m0, s18
	ds_read_b128 v[178:181], v216 offset:49152
	ds_read_b128 v[182:185], v216 offset:50176
	ds_read_b128 v[186:189], v216 offset:51200
	ds_read_b128 v[190:193], v216 offset:52224
	ds_read_b128 v[194:197], v216 offset:53248
	ds_read_b128 v[198:201], v216 offset:54272
	ds_read_b128 v[202:205], v216 offset:55296
	ds_read_b128 v[206:209], v216 offset:56320
	global_load_lds_dwordx4 v[210:211], off
	s_add_i32 m0, s18, 0x2000
	s_add_u32 s18, s22, 0x158080
	v_lshl_add_u64 v[210:211], v[218:219], 0, s[6:7]
	s_addc_u32 s19, s23, 0
	s_add_i32 s22, s56, s30
	global_load_lds_dwordx4 v[210:211], off
	v_lshl_add_u64 v[210:211], s[18:19], 0, v[148:149]
	s_mov_b32 m0, s22
	s_nop 0
	global_load_lds_dwordx4 v[210:211], off
	v_lshl_add_u64 v[210:211], s[18:19], 0, v[144:145]
	s_add_i32 m0, s22, 0x2000
	s_nop 0
	global_load_lds_dwordx4 v[210:211], off
	v_lshl_add_u64 v[210:211], v[220:221], 0, s[6:7]
	s_mov_b32 m0, s42
	s_nop 0
	global_load_lds_dwordx4 v[210:211], off
	v_lshl_add_u64 v[210:211], v[222:223], 0, s[6:7]
	s_mov_b32 m0, s43
	s_nop 0
	global_load_lds_dwordx4 v[210:211], off
	s_waitcnt vmcnt(8)
	s_waitcnt lgkmcnt(0)
	s_barrier
	s_setprio 1
	s_waitcnt lgkmcnt(0)
	v_mfma_f32_16x16x32_bf16 v[60:63], v[128:131], v[178:181], v[60:63]
	v_mfma_f32_16x16x32_bf16 v[56:59], v[136:139], v[178:181], v[56:59]
	v_mfma_f32_16x16x32_bf16 v[48:51], v[128:131], v[186:189], v[48:51]
	v_mfma_f32_16x16x32_bf16 v[40:43], v[136:139], v[186:189], v[40:43]
	v_mfma_f32_16x16x32_bf16 v[32:35], v[128:131], v[194:197], v[32:35]
	v_mfma_f32_16x16x32_bf16 v[24:27], v[136:139], v[194:197], v[24:27]
	v_mfma_f32_16x16x32_bf16 v[16:19], v[128:131], v[202:205], v[16:19]
	v_mfma_f32_16x16x32_bf16 v[8:11], v[136:139], v[202:205], v[8:11]
	v_mfma_f32_16x16x32_bf16 v[60:63], v[132:135], v[182:185], v[60:63]
	v_mfma_f32_16x16x32_bf16 v[56:59], v[140:143], v[182:185], v[56:59]
	v_mfma_f32_16x16x32_bf16 v[48:51], v[132:135], v[190:193], v[48:51]
	v_mfma_f32_16x16x32_bf16 v[40:43], v[140:143], v[190:193], v[40:43]
	v_mfma_f32_16x16x32_bf16 v[32:35], v[132:135], v[198:201], v[32:35]
	v_mfma_f32_16x16x32_bf16 v[24:27], v[140:143], v[198:201], v[24:27]
	v_mfma_f32_16x16x32_bf16 v[16:19], v[132:135], v[206:209], v[16:19]
	v_mfma_f32_16x16x32_bf16 v[8:11], v[140:143], v[206:209], v[8:11]
	v_mfma_f32_16x16x32_bf16 v[52:55], v[162:165], v[178:181], v[52:55]
	v_mfma_f32_16x16x32_bf16 v[44:47], v[170:173], v[178:181], v[44:47]
	v_mfma_f32_16x16x32_bf16 v[36:39], v[162:165], v[186:189], v[36:39]
	v_mfma_f32_16x16x32_bf16 v[28:31], v[170:173], v[186:189], v[28:31]
	v_mfma_f32_16x16x32_bf16 v[20:23], v[162:165], v[194:197], v[20:23]
	v_mfma_f32_16x16x32_bf16 v[12:15], v[170:173], v[194:197], v[12:15]
	v_mfma_f32_16x16x32_bf16 v[4:7], v[162:165], v[202:205], v[4:7]
	v_mfma_f32_16x16x32_bf16 v[0:3], v[170:173], v[202:205], v[0:3]
	v_mfma_f32_16x16x32_bf16 v[52:55], v[166:169], v[182:185], v[52:55]
	v_mfma_f32_16x16x32_bf16 v[44:47], v[174:177], v[182:185], v[44:47]
	v_mfma_f32_16x16x32_bf16 v[36:39], v[166:169], v[190:193], v[36:39]
	v_mfma_f32_16x16x32_bf16 v[28:31], v[174:177], v[190:193], v[28:31]
	v_mfma_f32_16x16x32_bf16 v[20:23], v[166:169], v[198:201], v[20:23]
	v_mfma_f32_16x16x32_bf16 v[12:15], v[174:177], v[198:201], v[12:15]
	v_mfma_f32_16x16x32_bf16 v[4:7], v[166:169], v[206:209], v[4:7]
	v_mfma_f32_16x16x32_bf16 v[0:3], v[174:177], v[206:209], v[0:3]
	s_setprio 0
	s_barrier
	s_add_i32 s54, s54, 2
	s_add_u32 s17, s17, 0x100
	s_addc_u32 s53, s53, 0
	s_cmpk_gt_u32 s54, 0x53
	s_mov_b64 s[18:19], s[20:21]
	s_cbranch_scc0 .LBB0_1375
	s_branch .Lkx_16
.LBB0_1375:
	ds_read_b128 v[128:131], v214
	ds_read_b128 v[132:135], v214 offset:1024
	ds_read_b128 v[136:139], v214 offset:2048
	ds_read_b128 v[140:143], v214 offset:3072
	ds_read_b128 v[162:165], v215
	ds_read_b128 v[166:169], v215 offset:1024
	ds_read_b128 v[170:173], v215 offset:2048
	ds_read_b128 v[174:177], v215 offset:3072
	s_add_u32 s20, s18, 0x100
	s_addc_u32 s21, s19, 0
	s_cmpk_eq_i32 s54, 0x52
	s_cselect_b32 s25, s5, s21
	s_cselect_b32 s24, s4, s20
	s_cselect_b32 s23, s15, s53
	s_cselect_b32 s22, s14, s17
	v_lshl_add_u64 v[210:211], s[18:19], 0, v[154:155]
	s_add_i32 m0, s35, 0xc000
	ds_read_b128 v[178:181], v216
	ds_read_b128 v[182:185], v216 offset:1024
	ds_read_b128 v[186:189], v216 offset:2048
	ds_read_b128 v[190:193], v216 offset:3072
	ds_read_b128 v[194:197], v216 offset:4096
	ds_read_b128 v[198:201], v216 offset:5120
	ds_read_b128 v[202:205], v216 offset:6144
	ds_read_b128 v[206:209], v216 offset:7168
	global_load_lds_dwordx4 v[210:211], off
	v_lshl_add_u64 v[210:211], s[18:19], 0, v[156:157]
	s_add_i32 m0, s35, 0xe000
	s_nop 0
	global_load_lds_dwordx4 v[210:211], off
	s_waitcnt vmcnt(8)
	s_waitcnt lgkmcnt(0)
	s_barrier
; #define PG8_STAGE(bufoff, gbase, voff) do { _Pragma("unroll") for (int _i = 0; _i < 2; ++_i) \
;         __builtin_amdgcn_global_load_lds((const unsigned*)((const char*)(gbase) + (voff)[_i]), (PG8_LAS unsigned*)(lds + (bufoff) + ldsw + _i * 8192), 16, 0, 0); } while (0)
; #define PG8_LDA(dst, b, h) do { _Pragma("unroll") for (int m = 0; m < 4; ++m) _Pragma("unroll") for (int k = 0; k < 2; ++k) dst[m][k] = *(const PG8_LAS bf16x8*)(lds + PG8_SA(b, h) + aoff + m * 2048 + k * 1024); } while (0)
; #define PG8_LDB(dst, b, h) do { _Pragma("unroll") for (int n = 0; n < 2; ++n) _Pragma("unroll") for (int k = 0; k < 2; ++k) dst[n][k] = *(const PG8_LAS bf16x8*)(lds + PG8_SB(b, h) + boff + n * 2048 + k * 1024); } while (0)
; #define PG8_MMA(ai, bj, At, Bt) do { __builtin_amdgcn_s_setprio(1); _Pragma("unroll") for (int m = 0; m < 4; ++m) _Pragma("unroll") for (int n = 0; n < 2; ++n) _Pragma("unroll") for (int k = 0; k < 2; ++k) \
;         acc[ai][bj][m][n] = __builtin_amdgcn_mfma_f32_16x16x32_bf16(Bt[n][k], At[m][k], acc[ai][bj][m][n], 0, 0, 0); __builtin_amdgcn_s_setprio(0); } while (0)
; #define PG8_WAIT_V(n) asm volatile("s_waitcnt vmcnt(" #n ")" ::: "memory")
; #define PG8_WAIT_L(n) asm volatile("s_waitcnt lgkmcnt(" #n ")" ::: "memory")
; #define PG8_BAR __builtin_amdgcn_s_barrier()
; #define PG8_SCHED __builtin_amdgcn_sched_barrier(0)
; template <class Epi, class Sched, bool ALIGN_EPI = false, bool SP2 = false>
; __device__ __forceinline__ void gemm_phase(PG8_LAS unsigned char* lds, const Gemm g, const Sched& S, const Epi& E, const int wave_in) {
;     ...
;             PG8_LDB(B0, 0, 0); PG8_LDB(B1, 0, 1); PG8_SCHED; PG8_LDA(At, 0, 0); PG8_STAGE(PG8_SA(1, 1), a1 + hstepA, voffA);
;             PG8_WAIT_V(8); PG8_WAIT_L(0); PG8_BAR; PG8_MMA(0, 0, At, B0); PG8_MMA(0, 1, At, B1); PG8_BAR; PG8_SCHED;
;             PG8_LDA(At, 0, 1); PG8_STAGE(PG8_SB(0, 0), b2, voffB); PG8_STAGE(PG8_SB(0, 1), b2 + hstepB, voffB); PG8_STAGE(PG8_SA(0, 0), a2, voffA);
;             PG8_WAIT_V(8); PG8_WAIT_L(0); PG8_BAR; PG8_MMA(1, 0, At, B0); PG8_MMA(1, 1, At, B1); PG8_BAR; PG8_SCHED;
	s_setprio 1
	s_waitcnt lgkmcnt(0)
	v_mfma_f32_16x16x32_bf16 v[124:127], v[128:131], v[178:181], v[124:127]
	v_mfma_f32_16x16x32_bf16 v[120:123], v[136:139], v[178:181], v[120:123]
	v_mfma_f32_16x16x32_bf16 v[112:115], v[128:131], v[186:189], v[112:115]
	v_mfma_f32_16x16x32_bf16 v[104:107], v[136:139], v[186:189], v[104:107]
	v_mfma_f32_16x16x32_bf16 v[100:103], v[128:131], v[194:197], v[100:103]
	v_mfma_f32_16x16x32_bf16 v[96:99], v[136:139], v[194:197], v[96:99]
	v_mfma_f32_16x16x32_bf16 v[76:79], v[128:131], v[202:205], v[76:79]
	v_mfma_f32_16x16x32_bf16 v[72:75], v[136:139], v[202:205], v[72:75]
	v_mfma_f32_16x16x32_bf16 v[124:127], v[132:135], v[182:185], v[124:127]
	v_mfma_f32_16x16x32_bf16 v[120:123], v[140:143], v[182:185], v[120:123]
	v_mfma_f32_16x16x32_bf16 v[112:115], v[132:135], v[190:193], v[112:115]
	v_mfma_f32_16x16x32_bf16 v[104:107], v[140:143], v[190:193], v[104:107]
	v_mfma_f32_16x16x32_bf16 v[100:103], v[132:135], v[198:201], v[100:103]
	v_mfma_f32_16x16x32_bf16 v[96:99], v[140:143], v[198:201], v[96:99]
	v_mfma_f32_16x16x32_bf16 v[76:79], v[132:135], v[206:209], v[76:79]
	v_mfma_f32_16x16x32_bf16 v[72:75], v[140:143], v[206:209], v[72:75]
	v_mfma_f32_16x16x32_bf16 v[116:119], v[162:165], v[178:181], v[116:119]
	v_mfma_f32_16x16x32_bf16 v[108:111], v[170:173], v[178:181], v[108:111]
	v_mfma_f32_16x16x32_bf16 v[92:95], v[162:165], v[186:189], v[92:95]
	v_mfma_f32_16x16x32_bf16 v[88:91], v[170:173], v[186:189], v[88:91]
	v_mfma_f32_16x16x32_bf16 v[84:87], v[162:165], v[194:197], v[84:87]
	v_mfma_f32_16x16x32_bf16 v[80:83], v[170:173], v[194:197], v[80:83]
	v_mfma_f32_16x16x32_bf16 v[68:71], v[162:165], v[202:205], v[68:71]
	v_mfma_f32_16x16x32_bf16 v[64:67], v[170:173], v[202:205], v[64:67]
	v_mfma_f32_16x16x32_bf16 v[116:119], v[166:169], v[182:185], v[116:119]
	v_mfma_f32_16x16x32_bf16 v[108:111], v[174:177], v[182:185], v[108:111]
	v_mfma_f32_16x16x32_bf16 v[92:95], v[166:169], v[190:193], v[92:95]
	v_mfma_f32_16x16x32_bf16 v[88:91], v[174:177], v[190:193], v[88:91]
	v_mfma_f32_16x16x32_bf16 v[84:87], v[166:169], v[198:201], v[84:87]
	v_mfma_f32_16x16x32_bf16 v[80:83], v[174:177], v[198:201], v[80:83]
	v_mfma_f32_16x16x32_bf16 v[68:71], v[166:169], v[206:209], v[68:71]
	v_mfma_f32_16x16x32_bf16 v[64:67], v[174:177], v[206:209], v[64:67]
	s_setprio 0
	s_barrier
	s_add_i32 s18, s45, s30
	v_lshl_add_u64 v[210:211], s[22:23], 0, v[148:149]
	s_mov_b32 m0, s18
	ds_read_b128 v[178:181], v216 offset:16384
	ds_read_b128 v[182:185], v216 offset:17408
	ds_read_b128 v[186:189], v216 offset:18432
	ds_read_b128 v[190:193], v216 offset:19456
	ds_read_b128 v[194:197], v216 offset:20480
	ds_read_b128 v[198:201], v216 offset:21504
	ds_read_b128 v[202:205], v216 offset:22528
	ds_read_b128 v[206:209], v216 offset:23552
	global_load_lds_dwordx4 v[210:211], off
	s_add_i32 m0, s18, 0x2000
	s_add_u32 s18, s22, 0x158000
	v_lshl_add_u64 v[218:219], s[22:23], 0, v[144:145]
	s_addc_u32 s19, s23, 0
	s_add_i32 s55, s46, s30
	global_load_lds_dwordx4 v[218:219], off
	v_lshl_add_u64 v[220:221], s[18:19], 0, v[148:149]
	s_mov_b32 m0, s55
	v_lshl_add_u64 v[222:223], s[24:25], 0, v[146:147]
	global_load_lds_dwordx4 v[220:221], off
	v_lshl_add_u64 v[220:221], s[18:19], 0, v[144:145]
	s_add_i32 m0, s55, 0x2000
	s_nop 0
	global_load_lds_dwordx4 v[220:221], off
	v_lshl_add_u64 v[220:221], s[24:25], 0, v[150:151]
	s_mov_b32 m0, s35
	s_nop 0
	global_load_lds_dwordx4 v[220:221], off
	s_mov_b32 m0, s36
	s_nop 0
	global_load_lds_dwordx4 v[222:223], off
	s_waitcnt vmcnt(8)
	s_waitcnt lgkmcnt(0)
	s_barrier
	s_setprio 1
	s_waitcnt lgkmcnt(0)
	v_mfma_f32_16x16x32_bf16 v[60:63], v[128:131], v[178:181], v[60:63]
	v_mfma_f32_16x16x32_bf16 v[56:59], v[136:139], v[178:181], v[56:59]
	v_mfma_f32_16x16x32_bf16 v[48:51], v[128:131], v[186:189], v[48:51]
	v_mfma_f32_16x16x32_bf16 v[40:43], v[136:139], v[186:189], v[40:43]
	v_mfma_f32_16x16x32_bf16 v[32:35], v[128:131], v[194:197], v[32:35]
	v_mfma_f32_16x16x32_bf16 v[24:27], v[136:139], v[194:197], v[24:27]
	v_mfma_f32_16x16x32_bf16 v[16:19], v[128:131], v[202:205], v[16:19]
	v_mfma_f32_16x16x32_bf16 v[8:11], v[136:139], v[202:205], v[8:11]
	v_mfma_f32_16x16x32_bf16 v[60:63], v[132:135], v[182:185], v[60:63]
	v_mfma_f32_16x16x32_bf16 v[56:59], v[140:143], v[182:185], v[56:59]
	v_mfma_f32_16x16x32_bf16 v[48:51], v[132:135], v[190:193], v[48:51]
	v_mfma_f32_16x16x32_bf16 v[40:43], v[140:143], v[190:193], v[40:43]
	v_mfma_f32_16x16x32_bf16 v[32:35], v[132:135], v[198:201], v[32:35]
	v_mfma_f32_16x16x32_bf16 v[24:27], v[140:143], v[198:201], v[24:27]
	v_mfma_f32_16x16x32_bf16 v[16:19], v[132:135], v[206:209], v[16:19]
	v_mfma_f32_16x16x32_bf16 v[8:11], v[140:143], v[206:209], v[8:11]
	v_mfma_f32_16x16x32_bf16 v[52:55], v[162:165], v[178:181], v[52:55]
	v_mfma_f32_16x16x32_bf16 v[44:47], v[170:173], v[178:181], v[44:47]
	v_mfma_f32_16x16x32_bf16 v[36:39], v[162:165], v[186:189], v[36:39]
	v_mfma_f32_16x16x32_bf16 v[28:31], v[170:173], v[186:189], v[28:31]
	v_mfma_f32_16x16x32_bf16 v[20:23], v[162:165], v[194:197], v[20:23]
	v_mfma_f32_16x16x32_bf16 v[12:15], v[170:173], v[194:197], v[12:15]
	v_mfma_f32_16x16x32_bf16 v[4:7], v[162:165], v[202:205], v[4:7]
	v_mfma_f32_16x16x32_bf16 v[0:3], v[170:173], v[202:205], v[0:3]
	v_mfma_f32_16x16x32_bf16 v[52:55], v[166:169], v[182:185], v[52:55]
	v_mfma_f32_16x16x32_bf16 v[44:47], v[174:177], v[182:185], v[44:47]
	v_mfma_f32_16x16x32_bf16 v[36:39], v[166:169], v[190:193], v[36:39]
	v_mfma_f32_16x16x32_bf16 v[28:31], v[174:177], v[190:193], v[28:31]
	v_mfma_f32_16x16x32_bf16 v[20:23], v[166:169], v[198:201], v[20:23]
	v_mfma_f32_16x16x32_bf16 v[12:15], v[174:177], v[198:201], v[12:15]
	v_mfma_f32_16x16x32_bf16 v[4:7], v[166:169], v[206:209], v[4:7]
	v_mfma_f32_16x16x32_bf16 v[0:3], v[174:177], v[206:209], v[0:3]
	s_setprio 0
	s_barrier
; #define PG8_STAGE(bufoff, gbase, voff) do { _Pragma("unroll") for (int _i = 0; _i < 2; ++_i) \
;         __builtin_amdgcn_global_load_lds((const unsigned*)((const char*)(gbase) + (voff)[_i]), (PG8_LAS unsigned*)(lds + (bufoff) + ldsw + _i * 8192), 16, 0, 0); } while (0)
; #define PG8_LDA(dst, b, h) do { _Pragma("unroll") for (int m = 0; m < 4; ++m) _Pragma("unroll") for (int k = 0; k < 2; ++k) dst[m][k] = *(const PG8_LAS bf16x8*)(lds + PG8_SA(b, h) + aoff + m * 2048 + k * 1024); } while (0)
; #define PG8_LDB(dst, b, h) do { _Pragma("unroll") for (int n = 0; n < 2; ++n) _Pragma("unroll") for (int k = 0; k < 2; ++k) dst[n][k] = *(const PG8_LAS bf16x8*)(lds + PG8_SB(b, h) + boff + n * 2048 + k * 1024); } while (0)
; #define PG8_MMA(ai, bj, At, Bt) do { __builtin_amdgcn_s_setprio(1); _Pragma("unroll") for (int m = 0; m < 4; ++m) _Pragma("unroll") for (int n = 0; n < 2; ++n) _Pragma("unroll") for (int k = 0; k < 2; ++k) \
;         acc[ai][bj][m][n] = __builtin_amdgcn_mfma_f32_16x16x32_bf16(Bt[n][k], At[m][k], acc[ai][bj][m][n], 0, 0, 0); __builtin_amdgcn_s_setprio(0); } while (0)
; #define PG8_WAIT_V(n) asm volatile("s_waitcnt vmcnt(" #n ")" ::: "memory")
; #define PG8_WAIT_L(n) asm volatile("s_waitcnt lgkmcnt(" #n ")" ::: "memory")
; #define PG8_BAR __builtin_amdgcn_s_barrier()
; #define PG8_SCHED __builtin_amdgcn_sched_barrier(0)
; template <class Epi, class Sched, bool ALIGN_EPI = false, bool SP2 = false>
; __device__ __forceinline__ void gemm_phase(PG8_LAS unsigned char* lds, const Gemm g, const Sched& S, const Epi& E, const int wave_in) {
;     ...
;             PG8_LDB(B0, 1, 0); PG8_LDB(B1, 1, 1); PG8_SCHED; PG8_LDA(At, 1, 0); PG8_STAGE(PG8_SA(0, 1), a2 + hstepA, voffA);
;             PG8_WAIT_V(8); PG8_WAIT_L(0); PG8_BAR; PG8_MMA(0, 0, At, B0); PG8_MMA(0, 1, At, B1); PG8_BAR; PG8_SCHED;
	s_add_i32 s55, 0, 0x18000
	s_add_i32 s56, 0, 0x1c000
	v_add_u32_e32 v140, s55, v212
	v_add_u32_e32 v174, s56, v212
	ds_read_b128 v[128:131], v140
	ds_read_b128 v[132:135], v140 offset:1024
	ds_read_b128 v[136:139], v140 offset:2048
	ds_read_b128 v[140:143], v140 offset:3072
	ds_read_b128 v[162:165], v174
	ds_read_b128 v[166:169], v174 offset:1024
	ds_read_b128 v[170:173], v174 offset:2048
	ds_read_b128 v[174:177], v174 offset:3072
	s_add_u32 s18, s24, 0x158000
	s_addc_u32 s19, s25, 0
	s_mov_b32 m0, s37
	v_lshl_add_u64 v[224:225], s[18:19], 0, v[150:151]
	ds_read_b128 v[178:181], v216 offset:32768
	ds_read_b128 v[182:185], v216 offset:33792
	ds_read_b128 v[186:189], v216 offset:34816
	ds_read_b128 v[190:193], v216 offset:35840
	ds_read_b128 v[194:197], v216 offset:36864
	ds_read_b128 v[198:201], v216 offset:37888
	ds_read_b128 v[202:205], v216 offset:38912
	ds_read_b128 v[206:209], v216 offset:39936
	global_load_lds_dwordx4 v[224:225], off
	v_lshl_add_u64 v[224:225], s[18:19], 0, v[146:147]
	s_mov_b32 m0, s38
	s_nop 0
	global_load_lds_dwordx4 v[224:225], off
	s_waitcnt vmcnt(8)
	s_waitcnt lgkmcnt(0)
	s_barrier
	s_setprio 1
	s_waitcnt lgkmcnt(0)
	v_mfma_f32_16x16x32_bf16 v[124:127], v[128:131], v[178:181], v[124:127]
	v_mfma_f32_16x16x32_bf16 v[120:123], v[136:139], v[178:181], v[120:123]
	v_mfma_f32_16x16x32_bf16 v[112:115], v[128:131], v[186:189], v[112:115]
	v_mfma_f32_16x16x32_bf16 v[104:107], v[136:139], v[186:189], v[104:107]
	v_mfma_f32_16x16x32_bf16 v[100:103], v[128:131], v[194:197], v[100:103]
	v_mfma_f32_16x16x32_bf16 v[96:99], v[136:139], v[194:197], v[96:99]
	v_mfma_f32_16x16x32_bf16 v[76:79], v[128:131], v[202:205], v[76:79]
	v_mfma_f32_16x16x32_bf16 v[72:75], v[136:139], v[202:205], v[72:75]
	v_mfma_f32_16x16x32_bf16 v[124:127], v[132:135], v[182:185], v[124:127]
	v_mfma_f32_16x16x32_bf16 v[120:123], v[140:143], v[182:185], v[120:123]
	v_mfma_f32_16x16x32_bf16 v[112:115], v[132:135], v[190:193], v[112:115]
	v_mfma_f32_16x16x32_bf16 v[104:107], v[140:143], v[190:193], v[104:107]
	v_mfma_f32_16x16x32_bf16 v[100:103], v[132:135], v[198:201], v[100:103]
	v_mfma_f32_16x16x32_bf16 v[96:99], v[140:143], v[198:201], v[96:99]
	v_mfma_f32_16x16x32_bf16 v[76:79], v[132:135], v[206:209], v[76:79]
	v_mfma_f32_16x16x32_bf16 v[72:75], v[140:143], v[206:209], v[72:75]
	v_mfma_f32_16x16x32_bf16 v[116:119], v[162:165], v[178:181], v[116:119]
	v_mfma_f32_16x16x32_bf16 v[108:111], v[170:173], v[178:181], v[108:111]
	v_mfma_f32_16x16x32_bf16 v[92:95], v[162:165], v[186:189], v[92:95]
	v_mfma_f32_16x16x32_bf16 v[88:91], v[170:173], v[186:189], v[88:91]
	v_mfma_f32_16x16x32_bf16 v[84:87], v[162:165], v[194:197], v[84:87]
	v_mfma_f32_16x16x32_bf16 v[80:83], v[170:173], v[194:197], v[80:83]
	v_mfma_f32_16x16x32_bf16 v[68:71], v[162:165], v[202:205], v[68:71]
	v_mfma_f32_16x16x32_bf16 v[64:67], v[170:173], v[202:205], v[64:67]
	v_mfma_f32_16x16x32_bf16 v[116:119], v[166:169], v[182:185], v[116:119]
	v_mfma_f32_16x16x32_bf16 v[108:111], v[174:177], v[182:185], v[108:111]
	v_mfma_f32_16x16x32_bf16 v[92:95], v[166:169], v[190:193], v[92:95]
	v_mfma_f32_16x16x32_bf16 v[88:91], v[174:177], v[190:193], v[88:91]
	v_mfma_f32_16x16x32_bf16 v[84:87], v[166:169], v[198:201], v[84:87]
	v_mfma_f32_16x16x32_bf16 v[80:83], v[174:177], v[198:201], v[80:83]
	v_mfma_f32_16x16x32_bf16 v[68:71], v[166:169], v[206:209], v[68:71]
	v_mfma_f32_16x16x32_bf16 v[64:67], v[174:177], v[206:209], v[64:67]
	s_setprio 0
	s_barrier
; #define PG8_STAGE(bufoff, gbase, voff) do { _Pragma("unroll") for (int _i = 0; _i < 2; ++_i) \
;         __builtin_amdgcn_global_load_lds((const unsigned*)((const char*)(gbase) + (voff)[_i]), (PG8_LAS unsigned*)(lds + (bufoff) + ldsw + _i * 8192), 16, 0, 0); } while (0)
; #define PG8_LDA(dst, b, h) do { _Pragma("unroll") for (int m = 0; m < 4; ++m) _Pragma("unroll") for (int k = 0; k < 2; ++k) dst[m][k] = *(const PG8_LAS bf16x8*)(lds + PG8_SA(b, h) + aoff + m * 2048 + k * 1024); } while (0)
; #define PG8_MMA(ai, bj, At, Bt) do { __builtin_amdgcn_s_setprio(1); _Pragma("unroll") for (int m = 0; m < 4; ++m) _Pragma("unroll") for (int n = 0; n < 2; ++n) _Pragma("unroll") for (int k = 0; k < 2; ++k) \
;         acc[ai][bj][m][n] = __builtin_amdgcn_mfma_f32_16x16x32_bf16(Bt[n][k], At[m][k], acc[ai][bj][m][n], 0, 0, 0); __builtin_amdgcn_s_setprio(0); } while (0)
; #define PG8_WAIT_V(n) asm volatile("s_waitcnt vmcnt(" #n ")" ::: "memory")
; #define PG8_WAIT_L(n) asm volatile("s_waitcnt lgkmcnt(" #n ")" ::: "memory")
; #define PG8_BAR __builtin_amdgcn_s_barrier()
; #define PG8_SCHED __builtin_amdgcn_sched_barrier(0)
; template <class Epi, class Sched, bool ALIGN_EPI = false, bool SP2 = false>
; __device__ __forceinline__ void gemm_phase(PG8_LAS unsigned char* lds, const Gemm g, const Sched& S, const Epi& E, const int wave_in) {
;     ...
;         for (int t = 0; t < nt; t += 2) {
;     ...
;             PG8_LDA(At, 1, 1); PG8_STAGE(PG8_SB(1, 0), b3, voffB); PG8_STAGE(PG8_SB(1, 1), b3 + hstepB, voffB); PG8_STAGE(PG8_SA(1, 0), a3, voffA);
;             PG8_WAIT_V(8); PG8_WAIT_L(0); PG8_BAR; PG8_MMA(1, 0, At, B0); PG8_MMA(1, 1, At, B1); PG8_BAR; PG8_SCHED;
	s_add_i32 s18, s55, s30
	v_lshl_add_u64 v[210:211], v[210:211], 0, s[6:7]
	s_mov_b32 m0, s18
	ds_read_b128 v[178:181], v216 offset:49152
	ds_read_b128 v[182:185], v216 offset:50176
	ds_read_b128 v[186:189], v216 offset:51200
	ds_read_b128 v[190:193], v216 offset:52224
	ds_read_b128 v[194:197], v216 offset:53248
	ds_read_b128 v[198:201], v216 offset:54272
	ds_read_b128 v[202:205], v216 offset:55296
	ds_read_b128 v[206:209], v216 offset:56320
	global_load_lds_dwordx4 v[210:211], off
	s_add_i32 m0, s18, 0x2000
	s_add_u32 s18, s22, 0x158080
	v_lshl_add_u64 v[210:211], v[218:219], 0, s[6:7]
	s_addc_u32 s19, s23, 0
	s_add_i32 s22, s56, s30
	global_load_lds_dwordx4 v[210:211], off
	v_lshl_add_u64 v[210:211], s[18:19], 0, v[148:149]
	s_mov_b32 m0, s22
	s_nop 0
	global_load_lds_dwordx4 v[210:211], off
	v_lshl_add_u64 v[210:211], s[18:19], 0, v[144:145]
	s_add_i32 m0, s22, 0x2000
	s_nop 0
	global_load_lds_dwordx4 v[210:211], off
	v_lshl_add_u64 v[210:211], v[220:221], 0, s[6:7]
	s_mov_b32 m0, s42
	s_nop 0
	global_load_lds_dwordx4 v[210:211], off
	v_lshl_add_u64 v[210:211], v[222:223], 0, s[6:7]
	s_mov_b32 m0, s43
	s_nop 0
	global_load_lds_dwordx4 v[210:211], off
	s_waitcnt vmcnt(8)
	s_waitcnt lgkmcnt(0)
	s_barrier
	s_setprio 1
	s_waitcnt lgkmcnt(0)
	v_mfma_f32_16x16x32_bf16 v[60:63], v[128:131], v[178:181], v[60:63]
	v_mfma_f32_16x16x32_bf16 v[56:59], v[136:139], v[178:181], v[56:59]
	v_mfma_f32_16x16x32_bf16 v[48:51], v[128:131], v[186:189], v[48:51]
	v_mfma_f32_16x16x32_bf16 v[40:43], v[136:139], v[186:189], v[40:43]
	v_mfma_f32_16x16x32_bf16 v[32:35], v[128:131], v[194:197], v[32:35]
	v_mfma_f32_16x16x32_bf16 v[24:27], v[136:139], v[194:197], v[24:27]
	v_mfma_f32_16x16x32_bf16 v[16:19], v[128:131], v[202:205], v[16:19]
	v_mfma_f32_16x16x32_bf16 v[8:11], v[136:139], v[202:205], v[8:11]
	v_mfma_f32_16x16x32_bf16 v[60:63], v[132:135], v[182:185], v[60:63]
	v_mfma_f32_16x16x32_bf16 v[56:59], v[140:143], v[182:185], v[56:59]
	v_mfma_f32_16x16x32_bf16 v[48:51], v[132:135], v[190:193], v[48:51]
	v_mfma_f32_16x16x32_bf16 v[40:43], v[140:143], v[190:193], v[40:43]
	v_mfma_f32_16x16x32_bf16 v[32:35], v[132:135], v[198:201], v[32:35]
	v_mfma_f32_16x16x32_bf16 v[24:27], v[140:143], v[198:201], v[24:27]
	v_mfma_f32_16x16x32_bf16 v[16:19], v[132:135], v[206:209], v[16:19]
	v_mfma_f32_16x16x32_bf16 v[8:11], v[140:143], v[206:209], v[8:11]
	v_mfma_f32_16x16x32_bf16 v[52:55], v[162:165], v[178:181], v[52:55]
	v_mfma_f32_16x16x32_bf16 v[44:47], v[170:173], v[178:181], v[44:47]
	v_mfma_f32_16x16x32_bf16 v[36:39], v[162:165], v[186:189], v[36:39]
	v_mfma_f32_16x16x32_bf16 v[28:31], v[170:173], v[186:189], v[28:31]
	v_mfma_f32_16x16x32_bf16 v[20:23], v[162:165], v[194:197], v[20:23]
	v_mfma_f32_16x16x32_bf16 v[12:15], v[170:173], v[194:197], v[12:15]
	v_mfma_f32_16x16x32_bf16 v[4:7], v[162:165], v[202:205], v[4:7]
	v_mfma_f32_16x16x32_bf16 v[0:3], v[170:173], v[202:205], v[0:3]
	v_mfma_f32_16x16x32_bf16 v[52:55], v[166:169], v[182:185], v[52:55]
	v_mfma_f32_16x16x32_bf16 v[44:47], v[174:177], v[182:185], v[44:47]
	v_mfma_f32_16x16x32_bf16 v[36:39], v[166:169], v[190:193], v[36:39]
	v_mfma_f32_16x16x32_bf16 v[28:31], v[174:177], v[190:193], v[28:31]
	v_mfma_f32_16x16x32_bf16 v[20:23], v[166:169], v[198:201], v[20:23]
	v_mfma_f32_16x16x32_bf16 v[12:15], v[174:177], v[198:201], v[12:15]
	v_mfma_f32_16x16x32_bf16 v[4:7], v[166:169], v[206:209], v[4:7]
	v_mfma_f32_16x16x32_bf16 v[0:3], v[174:177], v[206:209], v[0:3]
	s_setprio 0
	s_barrier
	s_add_i32 s54, s54, 2
	s_add_u32 s17, s17, 0x100
	s_addc_u32 s53, s53, 0
	s_cmpk_gt_u32 s54, 0x53
	s_mov_b64 s[18:19], s[20:21]
	s_cbranch_scc0 .LBB0_1375

;     __host__ __device__ bool next(int i, Unit& u) const { const bool ok = StaticOrder::next(i, u); u.pm = 0; u.pn = 0; return ok; }
; #define PG8_STAGE(bufoff, gbase, voff) do { _Pragma("unroll") for (int _i = 0; _i < 2; ++_i) \
;         __builtin_amdgcn_global_load_lds((const unsigned*)((const char*)(gbase) + (voff)[_i]), (PG8_LAS unsigned*)(lds + (bufoff) + ldsw + _i * 8192), 16, 0, 0); } while (0)
; #define PG8_LDA(dst, b, h) do { _Pragma("unroll") for (int m = 0; m < 4; ++m) _Pragma("unroll") for (int k = 0; k < 2; ++k) dst[m][k] = *(const PG8_LAS bf16x8*)(lds + PG8_SA(b, h) + aoff + m * 2048 + k * 1024); } while (0)
; #define PG8_LDB(dst, b, h) do { _Pragma("unroll") for (int n = 0; n < 2; ++n) _Pragma("unroll") for (int k = 0; k < 2; ++k) dst[n][k] = *(const PG8_LAS bf16x8*)(lds + PG8_SB(b, h) + boff + n * 2048 + k * 1024); } while (0)
; #define PG8_WAIT_V(n) asm volatile("s_waitcnt vmcnt(" #n ")" ::: "memory")
; #define PG8_WAIT_L(n) asm volatile("s_waitcnt lgkmcnt(" #n ")" ::: "memory")
; #define PG8_BAR __builtin_amdgcn_s_barrier()
; #define PG8_SCHED __builtin_amdgcn_sched_barrier(0)
; template <class Epi, class Sched, bool ALIGN_EPI = false, bool SP2 = false>
; __device__ __forceinline__ void gemm_phase(PG8_LAS unsigned char* lds, const Gemm g, const Sched& S, const Epi& E, const int wave_in) {
;     ...
;         const bool has_next = S.next(ui + 1, nxt);
;         const char* nA = has_next ? (const char*)g.A + (size_t)nxt.pm * tstepA : cA; const char* nB = has_next ? (const char*)g.Bt + (size_t)nxt.pn * tstepB : cB;
;         for (int t = 0; t < nt; t += 2) {
;             const bool last = (t == nt - 2);
;             const char* a1 = cA + (size_t)(t + 1) * kstep;
;             const char* a2 = last ? nA : cA + (size_t)(t + 2) * kstep; const char* b2 = last ? nB : cB + (size_t)(t + 2) * kstep;
;             const char* a3 = a2 + kstep; const char* b3 = b2 + kstep;
;             if (last && has_next) S.a_ready(nxt);
;             if constexpr (SP2) {
;             PG8_LDB(B0, 0, 0); PG8_LDB(B1, 0, 1); PG8_SCHED; PG8_LDA(At, 0, 0); PG8_STAGE(PG8_SA(1, 1), a1 + hstepA, voffA);
;             PG8_WAIT_V(8); PG8_WAIT_L(0); PG8_BAR; PG8_MMA(0, 0, At, B0); PG8_MMA(0, 1, At, B1); PG8_BAR; PG8_SCHED;
;             PG8_LDA(At, 0, 1); PG8_STAGE(PG8_SB(0, 0), b2, voffB); PG8_STAGE(PG8_SB(0, 1), b2 + hstepB, voffB); PG8_STAGE(PG8_SA(0, 0), a2, voffA);
.LBB0_1512:
	s_ashr_i32 s13, s12, 31
	s_lshl_b64 s[14:15], s[12:13], 20
	s_add_u32 s14, s26, s14
	s_addc_u32 s15, s27, s15
	s_and_b64 s[16:17], s[2:3], exec
	s_cselect_b32 s13, s15, s21
	s_cselect_b32 s46, s14, s20
	s_ashr_i32 s11, s10, 31
	s_lshl_b64 s[16:17], s[10:11], 20
	s_add_u32 s16, s28, s16
	s_addc_u32 s17, s29, s17
	s_and_b64 s[24:25], s[2:3], exec
	s_cselect_b32 s11, s17, s23
	s_cselect_b32 s47, s16, s22
	s_add_u32 s20, s20, 0x80080
	s_addc_u32 s21, s21, 0
	s_add_u32 s48, s22, 0x100
	v_mov_b32_e32 v0, 0
	s_addc_u32 s49, s23, 0
	s_mov_b32 s50, -2
	ds_read_b128 v[144:147], v151
	ds_read_b128 v[154:157], v151 offset:1024
	ds_read_b128 v[158:161], v151 offset:2048
	ds_read_b128 v[162:165], v151 offset:3072
	ds_read_b128 v[166:169], v152
	ds_read_b128 v[170:173], v152 offset:1024
	ds_read_b128 v[174:177], v152 offset:2048
	ds_read_b128 v[178:181], v152 offset:3072
	s_add_u32 s22, s20, 0xfff80080
	s_addc_u32 s23, s21, -1
	s_cmp_eq_u32 s50, 28
	s_cselect_b32 s25, s13, s23
	s_cselect_b32 s24, s46, s22
	s_cselect_b32 s23, s11, s49
	s_cselect_b32 s22, s47, s48
	v_lshl_add_u64 v[214:215], s[20:21], 0, v[136:137]
	s_add_i32 m0, s19, 0xc000
	ds_read_b128 v[182:185], v153
	ds_read_b128 v[186:189], v153 offset:1024
	ds_read_b128 v[190:193], v153 offset:2048
	ds_read_b128 v[194:197], v153 offset:3072
	ds_read_b128 v[198:201], v153 offset:4096
	ds_read_b128 v[202:205], v153 offset:5120
	ds_read_b128 v[206:209], v153 offset:6144
	ds_read_b128 v[210:213], v153 offset:7168
	global_load_lds_dwordx4 v[214:215], off
	v_lshl_add_u64 v[214:215], s[20:21], 0, v[138:139]
	s_add_i32 m0, s19, 0xe000
	s_nop 0
	global_load_lds_dwordx4 v[214:215], off
	s_waitcnt vmcnt(8)
	s_waitcnt lgkmcnt(0)
	s_barrier
	s_setprio 1
	s_waitcnt lgkmcnt(0)
	v_mfma_f32_16x16x32_bf16 v[124:127], v[144:147], v[182:185], 0
	v_mfma_f32_16x16x32_bf16 v[120:123], v[158:161], v[182:185], 0
	v_mfma_f32_16x16x32_bf16 v[116:119], v[144:147], v[190:193], 0
	v_mfma_f32_16x16x32_bf16 v[108:111], v[158:161], v[190:193], 0
	v_mfma_f32_16x16x32_bf16 v[100:103], v[144:147], v[198:201], 0
	v_mfma_f32_16x16x32_bf16 v[92:95], v[158:161], v[198:201], 0
	v_mfma_f32_16x16x32_bf16 v[84:87], v[144:147], v[206:209], 0
	v_mfma_f32_16x16x32_bf16 v[76:79], v[158:161], v[206:209], 0
	v_mfma_f32_16x16x32_bf16 v[124:127], v[154:157], v[186:189], v[124:127]
	v_mfma_f32_16x16x32_bf16 v[120:123], v[162:165], v[186:189], v[120:123]
	v_mfma_f32_16x16x32_bf16 v[116:119], v[154:157], v[194:197], v[116:119]
	v_mfma_f32_16x16x32_bf16 v[108:111], v[162:165], v[194:197], v[108:111]
	v_mfma_f32_16x16x32_bf16 v[100:103], v[154:157], v[202:205], v[100:103]
	v_mfma_f32_16x16x32_bf16 v[92:95], v[162:165], v[202:205], v[92:95]
	v_mfma_f32_16x16x32_bf16 v[84:87], v[154:157], v[210:213], v[84:87]
	v_mfma_f32_16x16x32_bf16 v[76:79], v[162:165], v[210:213], v[76:79]
	v_mfma_f32_16x16x32_bf16 v[112:115], v[166:169], v[182:185], 0
	v_mfma_f32_16x16x32_bf16 v[104:107], v[174:177], v[182:185], 0
	v_mfma_f32_16x16x32_bf16 v[96:99], v[166:169], v[190:193], 0
	v_mfma_f32_16x16x32_bf16 v[88:91], v[174:177], v[190:193], 0
	v_mfma_f32_16x16x32_bf16 v[80:83], v[166:169], v[198:201], 0
	v_mfma_f32_16x16x32_bf16 v[72:75], v[174:177], v[198:201], 0
	v_mfma_f32_16x16x32_bf16 v[68:71], v[166:169], v[206:209], 0
	v_mfma_f32_16x16x32_bf16 v[64:67], v[174:177], v[206:209], 0
	v_mfma_f32_16x16x32_bf16 v[112:115], v[170:173], v[186:189], v[112:115]
	v_mfma_f32_16x16x32_bf16 v[104:107], v[178:181], v[186:189], v[104:107]
	v_mfma_f32_16x16x32_bf16 v[96:99], v[170:173], v[194:197], v[96:99]
	v_mfma_f32_16x16x32_bf16 v[88:91], v[178:181], v[194:197], v[88:91]
	v_mfma_f32_16x16x32_bf16 v[80:83], v[170:173], v[202:205], v[80:83]
	v_mfma_f32_16x16x32_bf16 v[72:75], v[178:181], v[202:205], v[72:75]
	v_mfma_f32_16x16x32_bf16 v[68:71], v[170:173], v[210:213], v[68:71]
	v_mfma_f32_16x16x32_bf16 v[64:67], v[178:181], v[210:213], v[64:67]
	s_setprio 0
	s_barrier
	s_add_i32 s51, s42, s30
	v_lshl_add_u64 v[214:215], s[22:23], 0, v[132:133]
	s_mov_b32 m0, s51
	ds_read_b128 v[182:185], v153 offset:16384
	ds_read_b128 v[186:189], v153 offset:17408
	ds_read_b128 v[190:193], v153 offset:18432
	ds_read_b128 v[194:197], v153 offset:19456
	ds_read_b128 v[198:201], v153 offset:20480
	ds_read_b128 v[202:205], v153 offset:21504
	ds_read_b128 v[206:209], v153 offset:22528
	ds_read_b128 v[210:213], v153 offset:23552
	global_load_lds_dwordx4 v[214:215], off
	s_add_i32 m0, s51, 0x2000
	s_add_u32 s52, s22, 0x80000
	v_lshl_add_u64 v[216:217], s[22:23], 0, v[128:129]
	s_addc_u32 s53, s23, 0
	s_add_i32 s51, s43, s30
	global_load_lds_dwordx4 v[216:217], off
	v_lshl_add_u64 v[218:219], s[52:53], 0, v[132:133]
	s_mov_b32 m0, s51
	v_lshl_add_u64 v[220:221], s[24:25], 0, v[130:131]
	global_load_lds_dwordx4 v[218:219], off
	v_lshl_add_u64 v[218:219], s[52:53], 0, v[128:129]
	s_add_i32 m0, s51, 0x2000
	s_nop 0
	global_load_lds_dwordx4 v[218:219], off
	v_lshl_add_u64 v[218:219], s[24:25], 0, v[134:135]
	s_mov_b32 m0, s19
	s_nop 0
	global_load_lds_dwordx4 v[218:219], off
	s_mov_b32 m0, s35
	s_nop 0
	global_load_lds_dwordx4 v[220:221], off
	s_waitcnt vmcnt(8)
	s_waitcnt lgkmcnt(0)
	s_barrier
; #define PG8_STAGE(bufoff, gbase, voff) do { _Pragma("unroll") for (int _i = 0; _i < 2; ++_i) \
;         __builtin_amdgcn_global_load_lds((const unsigned*)((const char*)(gbase) + (voff)[_i]), (PG8_LAS unsigned*)(lds + (bufoff) + ldsw + _i * 8192), 16, 0, 0); } while (0)
; #define PG8_LDA(dst, b, h) do { _Pragma("unroll") for (int m = 0; m < 4; ++m) _Pragma("unroll") for (int k = 0; k < 2; ++k) dst[m][k] = *(const PG8_LAS bf16x8*)(lds + PG8_SA(b, h) + aoff + m * 2048 + k * 1024); } while (0)
; #define PG8_LDB(dst, b, h) do { _Pragma("unroll") for (int n = 0; n < 2; ++n) _Pragma("unroll") for (int k = 0; k < 2; ++k) dst[n][k] = *(const PG8_LAS bf16x8*)(lds + PG8_SB(b, h) + boff + n * 2048 + k * 1024); } while (0)
; #define PG8_MMA(ai, bj, At, Bt) do { __builtin_amdgcn_s_setprio(1); _Pragma("unroll") for (int m = 0; m < 4; ++m) _Pragma("unroll") for (int n = 0; n < 2; ++n) _Pragma("unroll") for (int k = 0; k < 2; ++k) \
;         acc[ai][bj][m][n] = __builtin_amdgcn_mfma_f32_16x16x32_bf16(Bt[n][k], At[m][k], acc[ai][bj][m][n], 0, 0, 0); __builtin_amdgcn_s_setprio(0); } while (0)
; #define PG8_WAIT_V(n) asm volatile("s_waitcnt vmcnt(" #n ")" ::: "memory")
; #define PG8_WAIT_L(n) asm volatile("s_waitcnt lgkmcnt(" #n ")" ::: "memory")
; #define PG8_BAR __builtin_amdgcn_s_barrier()
; #define PG8_SCHED __builtin_amdgcn_sched_barrier(0)
; template <class Epi, class Sched, bool ALIGN_EPI = false, bool SP2 = false>
; __device__ __forceinline__ void gemm_phase(PG8_LAS unsigned char* lds, const Gemm g, const Sched& S, const Epi& E, const int wave_in) {
;     ...
;             PG8_LDA(At, 0, 1); PG8_STAGE(PG8_SB(0, 0), b2, voffB); PG8_STAGE(PG8_SB(0, 1), b2 + hstepB, voffB); PG8_STAGE(PG8_SA(0, 0), a2, voffA);
;             PG8_WAIT_V(8); PG8_WAIT_L(0); PG8_BAR; PG8_MMA(1, 0, At, B0); PG8_MMA(1, 1, At, B1); PG8_BAR; PG8_SCHED;
;             PG8_LDB(B0, 1, 0); PG8_LDB(B1, 1, 1); PG8_SCHED; PG8_LDA(At, 1, 0); PG8_STAGE(PG8_SA(0, 1), a2 + hstepA, voffA);
;             PG8_WAIT_V(8); PG8_WAIT_L(0); PG8_BAR; PG8_MMA(0, 0, At, B0); PG8_MMA(0, 1, At, B1); PG8_BAR; PG8_SCHED;
	s_setprio 1
	s_waitcnt lgkmcnt(0)
	v_mfma_f32_16x16x32_bf16 v[60:63], v[144:147], v[182:185], 0
	v_mfma_f32_16x16x32_bf16 v[56:59], v[158:161], v[182:185], 0
	v_mfma_f32_16x16x32_bf16 v[52:55], v[144:147], v[190:193], 0
	v_mfma_f32_16x16x32_bf16 v[44:47], v[158:161], v[190:193], 0
	v_mfma_f32_16x16x32_bf16 v[36:39], v[144:147], v[198:201], 0
	v_mfma_f32_16x16x32_bf16 v[28:31], v[158:161], v[198:201], 0
	v_mfma_f32_16x16x32_bf16 v[20:23], v[144:147], v[206:209], 0
	v_mfma_f32_16x16x32_bf16 v[12:15], v[158:161], v[206:209], 0
	v_mfma_f32_16x16x32_bf16 v[60:63], v[154:157], v[186:189], v[60:63]
	v_mfma_f32_16x16x32_bf16 v[56:59], v[162:165], v[186:189], v[56:59]
	v_mfma_f32_16x16x32_bf16 v[52:55], v[154:157], v[194:197], v[52:55]
	v_mfma_f32_16x16x32_bf16 v[44:47], v[162:165], v[194:197], v[44:47]
	v_mfma_f32_16x16x32_bf16 v[36:39], v[154:157], v[202:205], v[36:39]
	v_mfma_f32_16x16x32_bf16 v[28:31], v[162:165], v[202:205], v[28:31]
	v_mfma_f32_16x16x32_bf16 v[20:23], v[154:157], v[210:213], v[20:23]
	v_mfma_f32_16x16x32_bf16 v[12:15], v[162:165], v[210:213], v[12:15]
	v_mfma_f32_16x16x32_bf16 v[48:51], v[166:169], v[182:185], 0
	v_mfma_f32_16x16x32_bf16 v[40:43], v[174:177], v[182:185], 0
	v_mfma_f32_16x16x32_bf16 v[32:35], v[166:169], v[190:193], 0
	v_mfma_f32_16x16x32_bf16 v[24:27], v[174:177], v[190:193], 0
	v_mfma_f32_16x16x32_bf16 v[16:19], v[166:169], v[198:201], 0
	v_mfma_f32_16x16x32_bf16 v[8:11], v[174:177], v[198:201], 0
	v_mfma_f32_16x16x32_bf16 v[4:7], v[166:169], v[206:209], 0
	v_mfma_f32_16x16x32_bf16 v[0:3], v[174:177], v[206:209], 0
	v_mfma_f32_16x16x32_bf16 v[48:51], v[170:173], v[186:189], v[48:51]
	v_mfma_f32_16x16x32_bf16 v[40:43], v[178:181], v[186:189], v[40:43]
	v_mfma_f32_16x16x32_bf16 v[32:35], v[170:173], v[194:197], v[32:35]
	v_mfma_f32_16x16x32_bf16 v[24:27], v[178:181], v[194:197], v[24:27]
	v_mfma_f32_16x16x32_bf16 v[16:19], v[170:173], v[202:205], v[16:19]
	v_mfma_f32_16x16x32_bf16 v[8:11], v[178:181], v[202:205], v[8:11]
	v_mfma_f32_16x16x32_bf16 v[4:7], v[170:173], v[210:213], v[4:7]
	v_mfma_f32_16x16x32_bf16 v[0:3], v[178:181], v[210:213], v[0:3]
	s_setprio 0
	s_barrier
	s_add_i32 s51, 0, 0x18000
	s_add_i32 s52, 0, 0x1c000
	v_add_u32_e32 v162, s51, v149
	v_add_u32_e32 v178, s52, v149
	ds_read_b128 v[144:147], v162
	ds_read_b128 v[154:157], v162 offset:1024
	ds_read_b128 v[158:161], v162 offset:2048
	ds_read_b128 v[162:165], v162 offset:3072
	ds_read_b128 v[166:169], v178
	ds_read_b128 v[170:173], v178 offset:1024
	ds_read_b128 v[174:177], v178 offset:2048
	ds_read_b128 v[178:181], v178 offset:3072
	s_add_u32 s24, s24, 0x80000
	s_addc_u32 s25, s25, 0
	s_mov_b32 m0, s36
	v_lshl_add_u64 v[222:223], s[24:25], 0, v[134:135]
	ds_read_b128 v[182:185], v153 offset:32768
	ds_read_b128 v[186:189], v153 offset:33792
	ds_read_b128 v[190:193], v153 offset:34816
	ds_read_b128 v[194:197], v153 offset:35840
	ds_read_b128 v[198:201], v153 offset:36864
	ds_read_b128 v[202:205], v153 offset:37888
	ds_read_b128 v[206:209], v153 offset:38912
	ds_read_b128 v[210:213], v153 offset:39936
	global_load_lds_dwordx4 v[222:223], off
	v_lshl_add_u64 v[222:223], s[24:25], 0, v[130:131]
	s_mov_b32 m0, s37
	s_nop 0
	global_load_lds_dwordx4 v[222:223], off
	s_waitcnt vmcnt(8)
	s_waitcnt lgkmcnt(0)
	s_barrier
	s_setprio 1
	s_waitcnt lgkmcnt(0)
	v_mfma_f32_16x16x32_bf16 v[124:127], v[144:147], v[182:185], v[124:127]
	v_mfma_f32_16x16x32_bf16 v[120:123], v[158:161], v[182:185], v[120:123]
	v_mfma_f32_16x16x32_bf16 v[116:119], v[144:147], v[190:193], v[116:119]
	v_mfma_f32_16x16x32_bf16 v[108:111], v[158:161], v[190:193], v[108:111]
	v_mfma_f32_16x16x32_bf16 v[100:103], v[144:147], v[198:201], v[100:103]
	v_mfma_f32_16x16x32_bf16 v[92:95], v[158:161], v[198:201], v[92:95]
	v_mfma_f32_16x16x32_bf16 v[84:87], v[144:147], v[206:209], v[84:87]
	v_mfma_f32_16x16x32_bf16 v[76:79], v[158:161], v[206:209], v[76:79]
	v_mfma_f32_16x16x32_bf16 v[124:127], v[154:157], v[186:189], v[124:127]
	v_mfma_f32_16x16x32_bf16 v[120:123], v[162:165], v[186:189], v[120:123]
	v_mfma_f32_16x16x32_bf16 v[116:119], v[154:157], v[194:197], v[116:119]
	v_mfma_f32_16x16x32_bf16 v[108:111], v[162:165], v[194:197], v[108:111]
	v_mfma_f32_16x16x32_bf16 v[100:103], v[154:157], v[202:205], v[100:103]
	v_mfma_f32_16x16x32_bf16 v[92:95], v[162:165], v[202:205], v[92:95]
	v_mfma_f32_16x16x32_bf16 v[84:87], v[154:157], v[210:213], v[84:87]
	v_mfma_f32_16x16x32_bf16 v[76:79], v[162:165], v[210:213], v[76:79]
	v_mfma_f32_16x16x32_bf16 v[112:115], v[166:169], v[182:185], v[112:115]
	v_mfma_f32_16x16x32_bf16 v[104:107], v[174:177], v[182:185], v[104:107]
	v_mfma_f32_16x16x32_bf16 v[96:99], v[166:169], v[190:193], v[96:99]
	v_mfma_f32_16x16x32_bf16 v[88:91], v[174:177], v[190:193], v[88:91]
	v_mfma_f32_16x16x32_bf16 v[80:83], v[166:169], v[198:201], v[80:83]
	v_mfma_f32_16x16x32_bf16 v[72:75], v[174:177], v[198:201], v[72:75]
	v_mfma_f32_16x16x32_bf16 v[68:71], v[166:169], v[206:209], v[68:71]
	v_mfma_f32_16x16x32_bf16 v[64:67], v[174:177], v[206:209], v[64:67]
	v_mfma_f32_16x16x32_bf16 v[112:115], v[170:173], v[186:189], v[112:115]
	v_mfma_f32_16x16x32_bf16 v[104:107], v[178:181], v[186:189], v[104:107]
	v_mfma_f32_16x16x32_bf16 v[96:99], v[170:173], v[194:197], v[96:99]
	v_mfma_f32_16x16x32_bf16 v[88:91], v[178:181], v[194:197], v[88:91]
	v_mfma_f32_16x16x32_bf16 v[80:83], v[170:173], v[202:205], v[80:83]
	v_mfma_f32_16x16x32_bf16 v[72:75], v[178:181], v[202:205], v[72:75]
	v_mfma_f32_16x16x32_bf16 v[68:71], v[170:173], v[210:213], v[68:71]
	v_mfma_f32_16x16x32_bf16 v[64:67], v[178:181], v[210:213], v[64:67]
	s_setprio 0
	s_barrier
; #define PG8_STAGE(bufoff, gbase, voff) do { _Pragma("unroll") for (int _i = 0; _i < 2; ++_i) \
;         __builtin_amdgcn_global_load_lds((const unsigned*)((const char*)(gbase) + (voff)[_i]), (PG8_LAS unsigned*)(lds + (bufoff) + ldsw + _i * 8192), 16, 0, 0); } while (0)
; #define PG8_LDA(dst, b, h) do { _Pragma("unroll") for (int m = 0; m < 4; ++m) _Pragma("unroll") for (int k = 0; k < 2; ++k) dst[m][k] = *(const PG8_LAS bf16x8*)(lds + PG8_SA(b, h) + aoff + m * 2048 + k * 1024); } while (0)
; #define PG8_LDB(dst, b, h) do { _Pragma("unroll") for (int n = 0; n < 2; ++n) _Pragma("unroll") for (int k = 0; k < 2; ++k) dst[n][k] = *(const PG8_LAS bf16x8*)(lds + PG8_SB(b, h) + boff + n * 2048 + k * 1024); } while (0)
; #define PG8_MMA(ai, bj, At, Bt) do { __builtin_amdgcn_s_setprio(1); _Pragma("unroll") for (int m = 0; m < 4; ++m) _Pragma("unroll") for (int n = 0; n < 2; ++n) _Pragma("unroll") for (int k = 0; k < 2; ++k) \
;         acc[ai][bj][m][n] = __builtin_amdgcn_mfma_f32_16x16x32_bf16(Bt[n][k], At[m][k], acc[ai][bj][m][n], 0, 0, 0); __builtin_amdgcn_s_setprio(0); } while (0)
; #define PG8_WAIT_V(n) asm volatile("s_waitcnt vmcnt(" #n ")" ::: "memory")
; #define PG8_WAIT_L(n) asm volatile("s_waitcnt lgkmcnt(" #n ")" ::: "memory")
; #define PG8_BAR __builtin_amdgcn_s_barrier()
; #define PG8_SCHED __builtin_amdgcn_sched_barrier(0)
; template <class Epi, class Sched, bool ALIGN_EPI = false, bool SP2 = false>
; __device__ __forceinline__ void gemm_phase(PG8_LAS unsigned char* lds, const Gemm g, const Sched& S, const Epi& E, const int wave_in) {
;     ...
;         for (int t = 0; t < nt; t += 2) {
;     ...
;             PG8_LDB(B0, 0, 0); PG8_LDB(B1, 0, 1); PG8_SCHED; PG8_LDA(At, 0, 0); PG8_STAGE(PG8_SA(1, 1), a1 + hstepA, voffA);
;             PG8_WAIT_V(8); PG8_WAIT_L(0); PG8_BAR; PG8_MMA(0, 0, At, B0); PG8_MMA(0, 1, At, B1); PG8_BAR; PG8_SCHED;
;     ...
;             PG8_LDA(At, 1, 1); PG8_STAGE(PG8_SB(1, 0), b3, voffB); PG8_STAGE(PG8_SB(1, 1), b3 + hstepB, voffB); PG8_STAGE(PG8_SA(1, 0), a3, voffA);
;             PG8_WAIT_V(8); PG8_WAIT_L(0); PG8_BAR; PG8_MMA(1, 0, At, B0); PG8_MMA(1, 1, At, B1); PG8_BAR; PG8_SCHED;
	s_add_i32 s24, s51, s30
	v_lshl_add_u64 v[214:215], v[214:215], 0, s[6:7]
	s_mov_b32 m0, s24
	ds_read_b128 v[182:185], v153 offset:49152
	ds_read_b128 v[186:189], v153 offset:50176
	ds_read_b128 v[190:193], v153 offset:51200
	ds_read_b128 v[194:197], v153 offset:52224
	ds_read_b128 v[198:201], v153 offset:53248
	ds_read_b128 v[202:205], v153 offset:54272
	ds_read_b128 v[206:209], v153 offset:55296
	ds_read_b128 v[210:213], v153 offset:56320
	global_load_lds_dwordx4 v[214:215], off
	s_add_i32 m0, s24, 0x2000
	s_add_u32 s22, s22, 0x80080
	v_lshl_add_u64 v[214:215], v[216:217], 0, s[6:7]
	s_addc_u32 s23, s23, 0
	s_add_i32 s24, s52, s30
	global_load_lds_dwordx4 v[214:215], off
	v_lshl_add_u64 v[214:215], s[22:23], 0, v[132:133]
	s_mov_b32 m0, s24
	s_nop 0
	global_load_lds_dwordx4 v[214:215], off
	v_lshl_add_u64 v[214:215], s[22:23], 0, v[128:129]
	s_add_i32 m0, s24, 0x2000
	s_nop 0
	global_load_lds_dwordx4 v[214:215], off
	v_lshl_add_u64 v[214:215], v[218:219], 0, s[6:7]
	s_mov_b32 m0, s39
	s_nop 0
	global_load_lds_dwordx4 v[214:215], off
	v_lshl_add_u64 v[214:215], v[220:221], 0, s[6:7]
	s_mov_b32 m0, s40
	s_nop 0
	global_load_lds_dwordx4 v[214:215], off
	s_waitcnt vmcnt(8)
	s_waitcnt lgkmcnt(0)
	s_barrier
	s_setprio 1
	s_waitcnt lgkmcnt(0)
	v_mfma_f32_16x16x32_bf16 v[60:63], v[144:147], v[182:185], v[60:63]
	v_mfma_f32_16x16x32_bf16 v[56:59], v[158:161], v[182:185], v[56:59]
	v_mfma_f32_16x16x32_bf16 v[52:55], v[144:147], v[190:193], v[52:55]
	v_mfma_f32_16x16x32_bf16 v[44:47], v[158:161], v[190:193], v[44:47]
	v_mfma_f32_16x16x32_bf16 v[36:39], v[144:147], v[198:201], v[36:39]
	v_mfma_f32_16x16x32_bf16 v[28:31], v[158:161], v[198:201], v[28:31]
	v_mfma_f32_16x16x32_bf16 v[20:23], v[144:147], v[206:209], v[20:23]
	v_mfma_f32_16x16x32_bf16 v[12:15], v[158:161], v[206:209], v[12:15]
	v_mfma_f32_16x16x32_bf16 v[60:63], v[154:157], v[186:189], v[60:63]
	v_mfma_f32_16x16x32_bf16 v[56:59], v[162:165], v[186:189], v[56:59]
	v_mfma_f32_16x16x32_bf16 v[52:55], v[154:157], v[194:197], v[52:55]
	v_mfma_f32_16x16x32_bf16 v[44:47], v[162:165], v[194:197], v[44:47]
	v_mfma_f32_16x16x32_bf16 v[36:39], v[154:157], v[202:205], v[36:39]
	v_mfma_f32_16x16x32_bf16 v[28:31], v[162:165], v[202:205], v[28:31]
	v_mfma_f32_16x16x32_bf16 v[20:23], v[154:157], v[210:213], v[20:23]
	v_mfma_f32_16x16x32_bf16 v[12:15], v[162:165], v[210:213], v[12:15]
	v_mfma_f32_16x16x32_bf16 v[48:51], v[166:169], v[182:185], v[48:51]
	v_mfma_f32_16x16x32_bf16 v[40:43], v[174:177], v[182:185], v[40:43]
	v_mfma_f32_16x16x32_bf16 v[32:35], v[166:169], v[190:193], v[32:35]
	v_mfma_f32_16x16x32_bf16 v[24:27], v[174:177], v[190:193], v[24:27]
	v_mfma_f32_16x16x32_bf16 v[16:19], v[166:169], v[198:201], v[16:19]
	v_mfma_f32_16x16x32_bf16 v[8:11], v[174:177], v[198:201], v[8:11]
	v_mfma_f32_16x16x32_bf16 v[4:7], v[166:169], v[206:209], v[4:7]
	v_mfma_f32_16x16x32_bf16 v[0:3], v[174:177], v[206:209], v[0:3]
	v_mfma_f32_16x16x32_bf16 v[48:51], v[170:173], v[186:189], v[48:51]
	v_mfma_f32_16x16x32_bf16 v[40:43], v[178:181], v[186:189], v[40:43]
	v_mfma_f32_16x16x32_bf16 v[32:35], v[170:173], v[194:197], v[32:35]
	v_mfma_f32_16x16x32_bf16 v[24:27], v[178:181], v[194:197], v[24:27]
	v_mfma_f32_16x16x32_bf16 v[16:19], v[170:173], v[202:205], v[16:19]
	v_mfma_f32_16x16x32_bf16 v[8:11], v[178:181], v[202:205], v[8:11]
	v_mfma_f32_16x16x32_bf16 v[4:7], v[170:173], v[210:213], v[4:7]
	v_mfma_f32_16x16x32_bf16 v[0:3], v[178:181], v[210:213], v[0:3]
	s_setprio 0
	s_barrier
	s_add_i32 s50, s50, 2
	s_add_u32 s20, s20, 0x100
	s_addc_u32 s21, s21, 0
	s_add_u32 s48, s48, 0x100
	s_addc_u32 s49, s49, 0
	s_cmp_gt_u32 s50, 29
	s_cbranch_scc0 .LBB0_1513
	s_branch .Lkx_18
.LBB0_1513:
	ds_read_b128 v[144:147], v151
	ds_read_b128 v[154:157], v151 offset:1024
	ds_read_b128 v[158:161], v151 offset:2048
	ds_read_b128 v[162:165], v151 offset:3072
	ds_read_b128 v[166:169], v152
	ds_read_b128 v[170:173], v152 offset:1024
	ds_read_b128 v[174:177], v152 offset:2048
	ds_read_b128 v[178:181], v152 offset:3072
	s_add_u32 s22, s20, 0xfff80080
	s_addc_u32 s23, s21, -1
	s_cmp_eq_u32 s50, 28
	s_cselect_b32 s25, s13, s23
	s_cselect_b32 s24, s46, s22
	s_cselect_b32 s23, s11, s49
	s_cselect_b32 s22, s47, s48
	v_lshl_add_u64 v[214:215], s[20:21], 0, v[136:137]
	s_add_i32 m0, s19, 0xc000
	ds_read_b128 v[182:185], v153
	ds_read_b128 v[186:189], v153 offset:1024
	ds_read_b128 v[190:193], v153 offset:2048
	ds_read_b128 v[194:197], v153 offset:3072
	ds_read_b128 v[198:201], v153 offset:4096
	ds_read_b128 v[202:205], v153 offset:5120
	ds_read_b128 v[206:209], v153 offset:6144
	ds_read_b128 v[210:213], v153 offset:7168
	global_load_lds_dwordx4 v[214:215], off
	v_lshl_add_u64 v[214:215], s[20:21], 0, v[138:139]
	s_add_i32 m0, s19, 0xe000
	s_nop 0
	global_load_lds_dwordx4 v[214:215], off
	s_waitcnt vmcnt(8)
	s_waitcnt lgkmcnt(0)
	s_barrier
; #define PG8_STAGE(bufoff, gbase, voff) do { _Pragma("unroll") for (int _i = 0; _i < 2; ++_i) \
;         __builtin_amdgcn_global_load_lds((const unsigned*)((const char*)(gbase) + (voff)[_i]), (PG8_LAS unsigned*)(lds + (bufoff) + ldsw + _i * 8192), 16, 0, 0); } while (0)
; #define PG8_LDA(dst, b, h) do { _Pragma("unroll") for (int m = 0; m < 4; ++m) _Pragma("unroll") for (int k = 0; k < 2; ++k) dst[m][k] = *(const PG8_LAS bf16x8*)(lds + PG8_SA(b, h) + aoff + m * 2048 + k * 1024); } while (0)
; #define PG8_MMA(ai, bj, At, Bt) do { __builtin_amdgcn_s_setprio(1); _Pragma("unroll") for (int m = 0; m < 4; ++m) _Pragma("unroll") for (int n = 0; n < 2; ++n) _Pragma("unroll") for (int k = 0; k < 2; ++k) \
;         acc[ai][bj][m][n] = __builtin_amdgcn_mfma_f32_16x16x32_bf16(Bt[n][k], At[m][k], acc[ai][bj][m][n], 0, 0, 0); __builtin_amdgcn_s_setprio(0); } while (0)
; #define PG8_WAIT_V(n) asm volatile("s_waitcnt vmcnt(" #n ")" ::: "memory")
; #define PG8_WAIT_L(n) asm volatile("s_waitcnt lgkmcnt(" #n ")" ::: "memory")
; #define PG8_BAR __builtin_amdgcn_s_barrier()
; #define PG8_SCHED __builtin_amdgcn_sched_barrier(0)
; template <class Epi, class Sched, bool ALIGN_EPI = false, bool SP2 = false>
; __device__ __forceinline__ void gemm_phase(PG8_LAS unsigned char* lds, const Gemm g, const Sched& S, const Epi& E, const int wave_in) {
;     ...
;             PG8_WAIT_V(8); PG8_WAIT_L(0); PG8_BAR; PG8_MMA(0, 0, At, B0); PG8_MMA(0, 1, At, B1); PG8_BAR; PG8_SCHED;
;             PG8_LDA(At, 0, 1); PG8_STAGE(PG8_SB(0, 0), b2, voffB); PG8_STAGE(PG8_SB(0, 1), b2 + hstepB, voffB); PG8_STAGE(PG8_SA(0, 0), a2, voffA);
;             PG8_WAIT_V(8); PG8_WAIT_L(0); PG8_BAR; PG8_MMA(1, 0, At, B0); PG8_MMA(1, 1, At, B1); PG8_BAR; PG8_SCHED;
	s_setprio 1
	s_waitcnt lgkmcnt(0)
	v_mfma_f32_16x16x32_bf16 v[124:127], v[144:147], v[182:185], v[124:127]
	v_mfma_f32_16x16x32_bf16 v[120:123], v[158:161], v[182:185], v[120:123]
	v_mfma_f32_16x16x32_bf16 v[116:119], v[144:147], v[190:193], v[116:119]
	v_mfma_f32_16x16x32_bf16 v[108:111], v[158:161], v[190:193], v[108:111]
	v_mfma_f32_16x16x32_bf16 v[100:103], v[144:147], v[198:201], v[100:103]
	v_mfma_f32_16x16x32_bf16 v[92:95], v[158:161], v[198:201], v[92:95]
	v_mfma_f32_16x16x32_bf16 v[84:87], v[144:147], v[206:209], v[84:87]
	v_mfma_f32_16x16x32_bf16 v[76:79], v[158:161], v[206:209], v[76:79]
	v_mfma_f32_16x16x32_bf16 v[124:127], v[154:157], v[186:189], v[124:127]
	v_mfma_f32_16x16x32_bf16 v[120:123], v[162:165], v[186:189], v[120:123]
	v_mfma_f32_16x16x32_bf16 v[116:119], v[154:157], v[194:197], v[116:119]
	v_mfma_f32_16x16x32_bf16 v[108:111], v[162:165], v[194:197], v[108:111]
	v_mfma_f32_16x16x32_bf16 v[100:103], v[154:157], v[202:205], v[100:103]
	v_mfma_f32_16x16x32_bf16 v[92:95], v[162:165], v[202:205], v[92:95]
	v_mfma_f32_16x16x32_bf16 v[84:87], v[154:157], v[210:213], v[84:87]
	v_mfma_f32_16x16x32_bf16 v[76:79], v[162:165], v[210:213], v[76:79]
	v_mfma_f32_16x16x32_bf16 v[112:115], v[166:169], v[182:185], v[112:115]
	v_mfma_f32_16x16x32_bf16 v[104:107], v[174:177], v[182:185], v[104:107]
	v_mfma_f32_16x16x32_bf16 v[96:99], v[166:169], v[190:193], v[96:99]
	v_mfma_f32_16x16x32_bf16 v[88:91], v[174:177], v[190:193], v[88:91]
	v_mfma_f32_16x16x32_bf16 v[80:83], v[166:169], v[198:201], v[80:83]
	v_mfma_f32_16x16x32_bf16 v[72:75], v[174:177], v[198:201], v[72:75]
	v_mfma_f32_16x16x32_bf16 v[68:71], v[166:169], v[206:209], v[68:71]
	v_mfma_f32_16x16x32_bf16 v[64:67], v[174:177], v[206:209], v[64:67]
	v_mfma_f32_16x16x32_bf16 v[112:115], v[170:173], v[186:189], v[112:115]
	v_mfma_f32_16x16x32_bf16 v[104:107], v[178:181], v[186:189], v[104:107]
	v_mfma_f32_16x16x32_bf16 v[96:99], v[170:173], v[194:197], v[96:99]
	v_mfma_f32_16x16x32_bf16 v[88:91], v[178:181], v[194:197], v[88:91]
	v_mfma_f32_16x16x32_bf16 v[80:83], v[170:173], v[202:205], v[80:83]
	v_mfma_f32_16x16x32_bf16 v[72:75], v[178:181], v[202:205], v[72:75]
	v_mfma_f32_16x16x32_bf16 v[68:71], v[170:173], v[210:213], v[68:71]
	v_mfma_f32_16x16x32_bf16 v[64:67], v[178:181], v[210:213], v[64:67]
	s_setprio 0
	s_barrier
	s_add_i32 s51, s42, s30
	v_lshl_add_u64 v[214:215], s[22:23], 0, v[132:133]
	s_mov_b32 m0, s51
	ds_read_b128 v[182:185], v153 offset:16384
	ds_read_b128 v[186:189], v153 offset:17408
	ds_read_b128 v[190:193], v153 offset:18432
	ds_read_b128 v[194:197], v153 offset:19456
	ds_read_b128 v[198:201], v153 offset:20480
	ds_read_b128 v[202:205], v153 offset:21504
	ds_read_b128 v[206:209], v153 offset:22528
	ds_read_b128 v[210:213], v153 offset:23552
	global_load_lds_dwordx4 v[214:215], off
	s_add_i32 m0, s51, 0x2000
	s_add_u32 s52, s22, 0x80000
	v_lshl_add_u64 v[216:217], s[22:23], 0, v[128:129]
	s_addc_u32 s53, s23, 0
	s_add_i32 s51, s43, s30
	global_load_lds_dwordx4 v[216:217], off
	v_lshl_add_u64 v[218:219], s[52:53], 0, v[132:133]
	s_mov_b32 m0, s51
	v_lshl_add_u64 v[220:221], s[24:25], 0, v[130:131]
	global_load_lds_dwordx4 v[218:219], off
	v_lshl_add_u64 v[218:219], s[52:53], 0, v[128:129]
	s_add_i32 m0, s51, 0x2000
	s_nop 0
	global_load_lds_dwordx4 v[218:219], off
	v_lshl_add_u64 v[218:219], s[24:25], 0, v[134:135]
	s_mov_b32 m0, s19
	s_nop 0
	global_load_lds_dwordx4 v[218:219], off
	s_mov_b32 m0, s35
	s_nop 0
	global_load_lds_dwordx4 v[220:221], off
	s_waitcnt vmcnt(8)
	s_waitcnt lgkmcnt(0)
	s_barrier
	s_setprio 1
	s_waitcnt lgkmcnt(0)
	v_mfma_f32_16x16x32_bf16 v[60:63], v[144:147], v[182:185], v[60:63]
	v_mfma_f32_16x16x32_bf16 v[56:59], v[158:161], v[182:185], v[56:59]
	v_mfma_f32_16x16x32_bf16 v[52:55], v[144:147], v[190:193], v[52:55]
	v_mfma_f32_16x16x32_bf16 v[44:47], v[158:161], v[190:193], v[44:47]
	v_mfma_f32_16x16x32_bf16 v[36:39], v[144:147], v[198:201], v[36:39]
	v_mfma_f32_16x16x32_bf16 v[28:31], v[158:161], v[198:201], v[28:31]
	v_mfma_f32_16x16x32_bf16 v[20:23], v[144:147], v[206:209], v[20:23]
	v_mfma_f32_16x16x32_bf16 v[12:15], v[158:161], v[206:209], v[12:15]
	v_mfma_f32_16x16x32_bf16 v[60:63], v[154:157], v[186:189], v[60:63]
	v_mfma_f32_16x16x32_bf16 v[56:59], v[162:165], v[186:189], v[56:59]
	v_mfma_f32_16x16x32_bf16 v[52:55], v[154:157], v[194:197], v[52:55]
	v_mfma_f32_16x16x32_bf16 v[44:47], v[162:165], v[194:197], v[44:47]
	v_mfma_f32_16x16x32_bf16 v[36:39], v[154:157], v[202:205], v[36:39]
	v_mfma_f32_16x16x32_bf16 v[28:31], v[162:165], v[202:205], v[28:31]
	v_mfma_f32_16x16x32_bf16 v[20:23], v[154:157], v[210:213], v[20:23]
	v_mfma_f32_16x16x32_bf16 v[12:15], v[162:165], v[210:213], v[12:15]
	v_mfma_f32_16x16x32_bf16 v[48:51], v[166:169], v[182:185], v[48:51]
	v_mfma_f32_16x16x32_bf16 v[40:43], v[174:177], v[182:185], v[40:43]
	v_mfma_f32_16x16x32_bf16 v[32:35], v[166:169], v[190:193], v[32:35]
	v_mfma_f32_16x16x32_bf16 v[24:27], v[174:177], v[190:193], v[24:27]
	v_mfma_f32_16x16x32_bf16 v[16:19], v[166:169], v[198:201], v[16:19]
	v_mfma_f32_16x16x32_bf16 v[8:11], v[174:177], v[198:201], v[8:11]
	v_mfma_f32_16x16x32_bf16 v[4:7], v[166:169], v[206:209], v[4:7]
	v_mfma_f32_16x16x32_bf16 v[0:3], v[174:177], v[206:209], v[0:3]
	v_mfma_f32_16x16x32_bf16 v[48:51], v[170:173], v[186:189], v[48:51]
	v_mfma_f32_16x16x32_bf16 v[40:43], v[178:181], v[186:189], v[40:43]
	v_mfma_f32_16x16x32_bf16 v[32:35], v[170:173], v[194:197], v[32:35]
	v_mfma_f32_16x16x32_bf16 v[24:27], v[178:181], v[194:197], v[24:27]
	v_mfma_f32_16x16x32_bf16 v[16:19], v[170:173], v[202:205], v[16:19]
	v_mfma_f32_16x16x32_bf16 v[8:11], v[178:181], v[202:205], v[8:11]
	v_mfma_f32_16x16x32_bf16 v[4:7], v[170:173], v[210:213], v[4:7]
	v_mfma_f32_16x16x32_bf16 v[0:3], v[178:181], v[210:213], v[0:3]
	s_setprio 0
	s_barrier
; #define PG8_STAGE(bufoff, gbase, voff) do { _Pragma("unroll") for (int _i = 0; _i < 2; ++_i) \
;         __builtin_amdgcn_global_load_lds((const unsigned*)((const char*)(gbase) + (voff)[_i]), (PG8_LAS unsigned*)(lds + (bufoff) + ldsw + _i * 8192), 16, 0, 0); } while (0)
; #define PG8_LDA(dst, b, h) do { _Pragma("unroll") for (int m = 0; m < 4; ++m) _Pragma("unroll") for (int k = 0; k < 2; ++k) dst[m][k] = *(const PG8_LAS bf16x8*)(lds + PG8_SA(b, h) + aoff + m * 2048 + k * 1024); } while (0)
; #define PG8_LDB(dst, b, h) do { _Pragma("unroll") for (int n = 0; n < 2; ++n) _Pragma("unroll") for (int k = 0; k < 2; ++k) dst[n][k] = *(const PG8_LAS bf16x8*)(lds + PG8_SB(b, h) + boff + n * 2048 + k * 1024); } while (0)
; #define PG8_MMA(ai, bj, At, Bt) do { __builtin_amdgcn_s_setprio(1); _Pragma("unroll") for (int m = 0; m < 4; ++m) _Pragma("unroll") for (int n = 0; n < 2; ++n) _Pragma("unroll") for (int k = 0; k < 2; ++k) \
;         acc[ai][bj][m][n] = __builtin_amdgcn_mfma_f32_16x16x32_bf16(Bt[n][k], At[m][k], acc[ai][bj][m][n], 0, 0, 0); __builtin_amdgcn_s_setprio(0); } while (0)
; #define PG8_WAIT_V(n) asm volatile("s_waitcnt vmcnt(" #n ")" ::: "memory")
; #define PG8_WAIT_L(n) asm volatile("s_waitcnt lgkmcnt(" #n ")" ::: "memory")
; #define PG8_BAR __builtin_amdgcn_s_barrier()
; #define PG8_SCHED __builtin_amdgcn_sched_barrier(0)
; template <class Epi, class Sched, bool ALIGN_EPI = false, bool SP2 = false>
; __device__ __forceinline__ void gemm_phase(PG8_LAS unsigned char* lds, const Gemm g, const Sched& S, const Epi& E, const int wave_in) {
;     ...
;             PG8_LDB(B0, 1, 0); PG8_LDB(B1, 1, 1); PG8_SCHED; PG8_LDA(At, 1, 0); PG8_STAGE(PG8_SA(0, 1), a2 + hstepA, voffA);
;             PG8_WAIT_V(8); PG8_WAIT_L(0); PG8_BAR; PG8_MMA(0, 0, At, B0); PG8_MMA(0, 1, At, B1); PG8_BAR; PG8_SCHED;
	s_add_i32 s51, 0, 0x18000
	s_add_i32 s52, 0, 0x1c000
	v_add_u32_e32 v162, s51, v149
	v_add_u32_e32 v178, s52, v149
	ds_read_b128 v[144:147], v162
	ds_read_b128 v[154:157], v162 offset:1024
	ds_read_b128 v[158:161], v162 offset:2048
	ds_read_b128 v[162:165], v162 offset:3072
	ds_read_b128 v[166:169], v178
	ds_read_b128 v[170:173], v178 offset:1024
	ds_read_b128 v[174:177], v178 offset:2048
	ds_read_b128 v[178:181], v178 offset:3072
	s_add_u32 s24, s24, 0x80000
	s_addc_u32 s25, s25, 0
	s_mov_b32 m0, s36
	v_lshl_add_u64 v[222:223], s[24:25], 0, v[134:135]
	ds_read_b128 v[182:185], v153 offset:32768
	ds_read_b128 v[186:189], v153 offset:33792
	ds_read_b128 v[190:193], v153 offset:34816
	ds_read_b128 v[194:197], v153 offset:35840
	ds_read_b128 v[198:201], v153 offset:36864
	ds_read_b128 v[202:205], v153 offset:37888
	ds_read_b128 v[206:209], v153 offset:38912
	ds_read_b128 v[210:213], v153 offset:39936
	global_load_lds_dwordx4 v[222:223], off
	v_lshl_add_u64 v[222:223], s[24:25], 0, v[130:131]
	s_mov_b32 m0, s37
	s_nop 0
	global_load_lds_dwordx4 v[222:223], off
	s_waitcnt vmcnt(8)
	s_waitcnt lgkmcnt(0)
	s_barrier
	s_setprio 1
	s_waitcnt lgkmcnt(0)
	v_mfma_f32_16x16x32_bf16 v[124:127], v[144:147], v[182:185], v[124:127]
	v_mfma_f32_16x16x32_bf16 v[120:123], v[158:161], v[182:185], v[120:123]
	v_mfma_f32_16x16x32_bf16 v[116:119], v[144:147], v[190:193], v[116:119]
	v_mfma_f32_16x16x32_bf16 v[108:111], v[158:161], v[190:193], v[108:111]
	v_mfma_f32_16x16x32_bf16 v[100:103], v[144:147], v[198:201], v[100:103]
	v_mfma_f32_16x16x32_bf16 v[92:95], v[158:161], v[198:201], v[92:95]
	v_mfma_f32_16x16x32_bf16 v[84:87], v[144:147], v[206:209], v[84:87]
	v_mfma_f32_16x16x32_bf16 v[76:79], v[158:161], v[206:209], v[76:79]
	v_mfma_f32_16x16x32_bf16 v[124:127], v[154:157], v[186:189], v[124:127]
	v_mfma_f32_16x16x32_bf16 v[120:123], v[162:165], v[186:189], v[120:123]
	v_mfma_f32_16x16x32_bf16 v[116:119], v[154:157], v[194:197], v[116:119]
	v_mfma_f32_16x16x32_bf16 v[108:111], v[162:165], v[194:197], v[108:111]
	v_mfma_f32_16x16x32_bf16 v[100:103], v[154:157], v[202:205], v[100:103]
	v_mfma_f32_16x16x32_bf16 v[92:95], v[162:165], v[202:205], v[92:95]
	v_mfma_f32_16x16x32_bf16 v[84:87], v[154:157], v[210:213], v[84:87]
	v_mfma_f32_16x16x32_bf16 v[76:79], v[162:165], v[210:213], v[76:79]
	v_mfma_f32_16x16x32_bf16 v[112:115], v[166:169], v[182:185], v[112:115]
	v_mfma_f32_16x16x32_bf16 v[104:107], v[174:177], v[182:185], v[104:107]
	v_mfma_f32_16x16x32_bf16 v[96:99], v[166:169], v[190:193], v[96:99]
	v_mfma_f32_16x16x32_bf16 v[88:91], v[174:177], v[190:193], v[88:91]
	v_mfma_f32_16x16x32_bf16 v[80:83], v[166:169], v[198:201], v[80:83]
	v_mfma_f32_16x16x32_bf16 v[72:75], v[174:177], v[198:201], v[72:75]
	v_mfma_f32_16x16x32_bf16 v[68:71], v[166:169], v[206:209], v[68:71]
	v_mfma_f32_16x16x32_bf16 v[64:67], v[174:177], v[206:209], v[64:67]
	v_mfma_f32_16x16x32_bf16 v[112:115], v[170:173], v[186:189], v[112:115]
	v_mfma_f32_16x16x32_bf16 v[104:107], v[178:181], v[186:189], v[104:107]
	v_mfma_f32_16x16x32_bf16 v[96:99], v[170:173], v[194:197], v[96:99]
	v_mfma_f32_16x16x32_bf16 v[88:91], v[178:181], v[194:197], v[88:91]
	v_mfma_f32_16x16x32_bf16 v[80:83], v[170:173], v[202:205], v[80:83]
	v_mfma_f32_16x16x32_bf16 v[72:75], v[178:181], v[202:205], v[72:75]
	v_mfma_f32_16x16x32_bf16 v[68:71], v[170:173], v[210:213], v[68:71]
	v_mfma_f32_16x16x32_bf16 v[64:67], v[178:181], v[210:213], v[64:67]
	s_setprio 0
	s_barrier
; #define PG8_STAGE(bufoff, gbase, voff) do { _Pragma("unroll") for (int _i = 0; _i < 2; ++_i) \
;         __builtin_amdgcn_global_load_lds((const unsigned*)((const char*)(gbase) + (voff)[_i]), (PG8_LAS unsigned*)(lds + (bufoff) + ldsw + _i * 8192), 16, 0, 0); } while (0)
; #define PG8_LDA(dst, b, h) do { _Pragma("unroll") for (int m = 0; m < 4; ++m) _Pragma("unroll") for (int k = 0; k < 2; ++k) dst[m][k] = *(const PG8_LAS bf16x8*)(lds + PG8_SA(b, h) + aoff + m * 2048 + k * 1024); } while (0)
; #define PG8_MMA(ai, bj, At, Bt) do { __builtin_amdgcn_s_setprio(1); _Pragma("unroll") for (int m = 0; m < 4; ++m) _Pragma("unroll") for (int n = 0; n < 2; ++n) _Pragma("unroll") for (int k = 0; k < 2; ++k) \
;         acc[ai][bj][m][n] = __builtin_amdgcn_mfma_f32_16x16x32_bf16(Bt[n][k], At[m][k], acc[ai][bj][m][n], 0, 0, 0); __builtin_amdgcn_s_setprio(0); } while (0)
; #define PG8_WAIT_V(n) asm volatile("s_waitcnt vmcnt(" #n ")" ::: "memory")
; #define PG8_WAIT_L(n) asm volatile("s_waitcnt lgkmcnt(" #n ")" ::: "memory")
; #define PG8_BAR __builtin_amdgcn_s_barrier()
; #define PG8_SCHED __builtin_amdgcn_sched_barrier(0)
; template <class Epi, class Sched, bool ALIGN_EPI = false, bool SP2 = false>
; __device__ __forceinline__ void gemm_phase(PG8_LAS unsigned char* lds, const Gemm g, const Sched& S, const Epi& E, const int wave_in) {
;     ...
;         for (int t = 0; t < nt; t += 2) {
;     ...
;             PG8_LDA(At, 1, 1); PG8_STAGE(PG8_SB(1, 0), b3, voffB); PG8_STAGE(PG8_SB(1, 1), b3 + hstepB, voffB); PG8_STAGE(PG8_SA(1, 0), a3, voffA);
;             PG8_WAIT_V(8); PG8_WAIT_L(0); PG8_BAR; PG8_MMA(1, 0, At, B0); PG8_MMA(1, 1, At, B1); PG8_BAR; PG8_SCHED;
	s_add_i32 s24, s51, s30
	v_lshl_add_u64 v[214:215], v[214:215], 0, s[6:7]
	s_mov_b32 m0, s24
	ds_read_b128 v[182:185], v153 offset:49152
	ds_read_b128 v[186:189], v153 offset:50176
	ds_read_b128 v[190:193], v153 offset:51200
	ds_read_b128 v[194:197], v153 offset:52224
	ds_read_b128 v[198:201], v153 offset:53248
	ds_read_b128 v[202:205], v153 offset:54272
	ds_read_b128 v[206:209], v153 offset:55296
	ds_read_b128 v[210:213], v153 offset:56320
	global_load_lds_dwordx4 v[214:215], off
	s_add_i32 m0, s24, 0x2000
	s_add_u32 s22, s22, 0x80080
	v_lshl_add_u64 v[214:215], v[216:217], 0, s[6:7]
	s_addc_u32 s23, s23, 0
	s_add_i32 s24, s52, s30
	global_load_lds_dwordx4 v[214:215], off
	v_lshl_add_u64 v[214:215], s[22:23], 0, v[132:133]
	s_mov_b32 m0, s24
	s_nop 0
	global_load_lds_dwordx4 v[214:215], off
	v_lshl_add_u64 v[214:215], s[22:23], 0, v[128:129]
	s_add_i32 m0, s24, 0x2000
	s_nop 0
	global_load_lds_dwordx4 v[214:215], off
	v_lshl_add_u64 v[214:215], v[218:219], 0, s[6:7]
	s_mov_b32 m0, s39
	s_nop 0
	global_load_lds_dwordx4 v[214:215], off
	v_lshl_add_u64 v[214:215], v[220:221], 0, s[6:7]
	s_mov_b32 m0, s40
	s_nop 0
	global_load_lds_dwordx4 v[214:215], off
	s_waitcnt vmcnt(8)
	s_waitcnt lgkmcnt(0)
	s_barrier
	s_setprio 1
	s_waitcnt lgkmcnt(0)
	v_mfma_f32_16x16x32_bf16 v[60:63], v[144:147], v[182:185], v[60:63]
	v_mfma_f32_16x16x32_bf16 v[56:59], v[158:161], v[182:185], v[56:59]
	v_mfma_f32_16x16x32_bf16 v[52:55], v[144:147], v[190:193], v[52:55]
	v_mfma_f32_16x16x32_bf16 v[44:47], v[158:161], v[190:193], v[44:47]
	v_mfma_f32_16x16x32_bf16 v[36:39], v[144:147], v[198:201], v[36:39]
	v_mfma_f32_16x16x32_bf16 v[28:31], v[158:161], v[198:201], v[28:31]
	v_mfma_f32_16x16x32_bf16 v[20:23], v[144:147], v[206:209], v[20:23]
	v_mfma_f32_16x16x32_bf16 v[12:15], v[158:161], v[206:209], v[12:15]
	v_mfma_f32_16x16x32_bf16 v[60:63], v[154:157], v[186:189], v[60:63]
	v_mfma_f32_16x16x32_bf16 v[56:59], v[162:165], v[186:189], v[56:59]
	v_mfma_f32_16x16x32_bf16 v[52:55], v[154:157], v[194:197], v[52:55]
	v_mfma_f32_16x16x32_bf16 v[44:47], v[162:165], v[194:197], v[44:47]
	v_mfma_f32_16x16x32_bf16 v[36:39], v[154:157], v[202:205], v[36:39]
	v_mfma_f32_16x16x32_bf16 v[28:31], v[162:165], v[202:205], v[28:31]
	v_mfma_f32_16x16x32_bf16 v[20:23], v[154:157], v[210:213], v[20:23]
	v_mfma_f32_16x16x32_bf16 v[12:15], v[162:165], v[210:213], v[12:15]
	v_mfma_f32_16x16x32_bf16 v[48:51], v[166:169], v[182:185], v[48:51]
	v_mfma_f32_16x16x32_bf16 v[40:43], v[174:177], v[182:185], v[40:43]
	v_mfma_f32_16x16x32_bf16 v[32:35], v[166:169], v[190:193], v[32:35]
	v_mfma_f32_16x16x32_bf16 v[24:27], v[174:177], v[190:193], v[24:27]
	v_mfma_f32_16x16x32_bf16 v[16:19], v[166:169], v[198:201], v[16:19]
	v_mfma_f32_16x16x32_bf16 v[8:11], v[174:177], v[198:201], v[8:11]
	v_mfma_f32_16x16x32_bf16 v[4:7], v[166:169], v[206:209], v[4:7]
	v_mfma_f32_16x16x32_bf16 v[0:3], v[174:177], v[206:209], v[0:3]
	v_mfma_f32_16x16x32_bf16 v[48:51], v[170:173], v[186:189], v[48:51]
	v_mfma_f32_16x16x32_bf16 v[40:43], v[178:181], v[186:189], v[40:43]
	v_mfma_f32_16x16x32_bf16 v[32:35], v[170:173], v[194:197], v[32:35]
	v_mfma_f32_16x16x32_bf16 v[24:27], v[178:181], v[194:197], v[24:27]
	v_mfma_f32_16x16x32_bf16 v[16:19], v[170:173], v[202:205], v[16:19]
	v_mfma_f32_16x16x32_bf16 v[8:11], v[178:181], v[202:205], v[8:11]
	v_mfma_f32_16x16x32_bf16 v[4:7], v[170:173], v[210:213], v[4:7]
	v_mfma_f32_16x16x32_bf16 v[0:3], v[178:181], v[210:213], v[0:3]
	s_setprio 0
	s_barrier
	s_add_i32 s50, s50, 2
	s_add_u32 s20, s20, 0x100
	s_addc_u32 s21, s21, 0
	s_add_u32 s48, s48, 0x100
	s_addc_u32 s49, s49, 0
	s_cmp_gt_u32 s50, 29
	s_cbranch_scc0 .LBB0_1513

;     __host__ __device__ bool next(int i, Unit& u) const { const bool ok = StaticOrder::next(i, u); u.pm = 0; u.pn = 0; return ok; }
; #define PG8_STAGE(bufoff, gbase, voff) do { _Pragma("unroll") for (int _i = 0; _i < 2; ++_i) \
;         __builtin_amdgcn_global_load_lds((const unsigned*)((const char*)(gbase) + (voff)[_i]), (PG8_LAS unsigned*)(lds + (bufoff) + ldsw + _i * 8192), 16, 0, 0); } while (0)
; #define PG8_LDA(dst, b, h) do { _Pragma("unroll") for (int m = 0; m < 4; ++m) _Pragma("unroll") for (int k = 0; k < 2; ++k) dst[m][k] = *(const PG8_LAS bf16x8*)(lds + PG8_SA(b, h) + aoff + m * 2048 + k * 1024); } while (0)
; #define PG8_LDB(dst, b, h) do { _Pragma("unroll") for (int n = 0; n < 2; ++n) _Pragma("unroll") for (int k = 0; k < 2; ++k) dst[n][k] = *(const PG8_LAS bf16x8*)(lds + PG8_SB(b, h) + boff + n * 2048 + k * 1024); } while (0)
; #define PG8_WAIT_V(n) asm volatile("s_waitcnt vmcnt(" #n ")" ::: "memory")
; #define PG8_WAIT_L(n) asm volatile("s_waitcnt lgkmcnt(" #n ")" ::: "memory")
; #define PG8_BAR __builtin_amdgcn_s_barrier()
; #define PG8_SCHED __builtin_amdgcn_sched_barrier(0)
; template <class Epi, class Sched, bool ALIGN_EPI = false, bool SP2 = false>
; __device__ __forceinline__ void gemm_phase(PG8_LAS unsigned char* lds, const Gemm g, const Sched& S, const Epi& E, const int wave_in) {
;     ...
;         const bool has_next = S.next(ui + 1, nxt);
;         const char* nA = has_next ? (const char*)g.A + (size_t)nxt.pm * tstepA : cA; const char* nB = has_next ? (const char*)g.Bt + (size_t)nxt.pn * tstepB : cB;
;         for (int t = 0; t < nt; t += 2) {
;             const bool last = (t == nt - 2);
;             const char* a1 = cA + (size_t)(t + 1) * kstep;
;             const char* a2 = last ? nA : cA + (size_t)(t + 2) * kstep; const char* b2 = last ? nB : cB + (size_t)(t + 2) * kstep;
;             const char* a3 = a2 + kstep; const char* b3 = b2 + kstep;
;             if (last && has_next) S.a_ready(nxt);
;             if constexpr (SP2) {
;             PG8_LDB(B0, 0, 0); PG8_LDB(B1, 0, 1); PG8_SCHED; PG8_LDA(At, 0, 0); PG8_STAGE(PG8_SA(1, 1), a1 + hstepA, voffA);
;             PG8_WAIT_V(8); PG8_WAIT_L(0); PG8_BAR; PG8_MMA(0, 0, At, B0); PG8_MMA(0, 1, At, B1); PG8_BAR; PG8_SCHED;
;             PG8_LDA(At, 0, 1); PG8_STAGE(PG8_SB(0, 0), b2, voffB); PG8_STAGE(PG8_SB(0, 1), b2 + hstepB, voffB); PG8_STAGE(PG8_SA(0, 0), a2, voffA);
.LBB0_1824:
	s_ashr_i32 s19, s18, 31
	s_lshl_b64 s[20:21], s[18:19], 20
	s_add_u32 s20, s34, s20
	s_addc_u32 s21, s35, s21
	s_and_b64 s[22:23], s[2:3], exec
	s_cselect_b32 s19, s21, s27
	s_cselect_b32 s25, s20, s26
	s_ashr_i32 s17, s16, 31
	s_lshl_b64 s[22:23], s[16:17], 20
	s_add_u32 s22, s36, s22
	s_addc_u32 s23, s37, s23
	s_and_b64 s[30:31], s[2:3], exec
	s_cselect_b32 s17, s23, s29
	s_cselect_b32 s58, s22, s28
	s_add_u32 s26, s26, 0x80080
	s_addc_u32 s27, s27, 0
	s_add_u32 s59, s28, 0x100
	v_mov_b32_e32 v0, 0
	s_addc_u32 s60, s29, 0
	s_mov_b32 s61, -2
	s_waitcnt vmcnt(0)
	ds_read_b128 v[128:131], v214
	ds_read_b128 v[132:135], v214 offset:1024
	ds_read_b128 v[136:139], v214 offset:2048
	ds_read_b128 v[140:143], v214 offset:3072
	ds_read_b128 v[162:165], v215
	ds_read_b128 v[166:169], v215 offset:1024
	ds_read_b128 v[170:173], v215 offset:2048
	ds_read_b128 v[174:177], v215 offset:3072
	s_add_u32 s28, s26, 0xfff80080
	s_addc_u32 s29, s27, -1
	s_cmp_eq_u32 s61, 28
	s_cselect_b32 s31, s19, s29
	s_cselect_b32 s30, s25, s28
	s_cselect_b32 s29, s17, s60
	s_cselect_b32 s28, s58, s59
	v_lshl_add_u64 v[210:211], s[26:27], 0, v[154:155]
	s_add_i32 m0, s41, 0xc000
	ds_read_b128 v[178:181], v216
	ds_read_b128 v[182:185], v216 offset:1024
	ds_read_b128 v[186:189], v216 offset:2048
	ds_read_b128 v[190:193], v216 offset:3072
	ds_read_b128 v[194:197], v216 offset:4096
	ds_read_b128 v[198:201], v216 offset:5120
	ds_read_b128 v[202:205], v216 offset:6144
	ds_read_b128 v[206:209], v216 offset:7168
	global_load_lds_dwordx4 v[210:211], off
	v_lshl_add_u64 v[210:211], s[26:27], 0, v[156:157]
	s_add_i32 m0, s41, 0xe000
	s_nop 0
	global_load_lds_dwordx4 v[210:211], off
	s_waitcnt vmcnt(8)
	s_waitcnt lgkmcnt(0)
	s_barrier
	s_setprio 1
	s_waitcnt lgkmcnt(0)
	v_mfma_f32_16x16x32_bf16 v[124:127], v[128:131], v[178:181], 0
	v_mfma_f32_16x16x32_bf16 v[120:123], v[136:139], v[178:181], 0
	v_mfma_f32_16x16x32_bf16 v[112:115], v[128:131], v[186:189], 0
	v_mfma_f32_16x16x32_bf16 v[104:107], v[136:139], v[186:189], 0
	v_mfma_f32_16x16x32_bf16 v[100:103], v[128:131], v[194:197], 0
	v_mfma_f32_16x16x32_bf16 v[96:99], v[136:139], v[194:197], 0
	v_mfma_f32_16x16x32_bf16 v[76:79], v[128:131], v[202:205], 0
	v_mfma_f32_16x16x32_bf16 v[72:75], v[136:139], v[202:205], 0
	v_mfma_f32_16x16x32_bf16 v[124:127], v[132:135], v[182:185], v[124:127]
	v_mfma_f32_16x16x32_bf16 v[120:123], v[140:143], v[182:185], v[120:123]
	v_mfma_f32_16x16x32_bf16 v[112:115], v[132:135], v[190:193], v[112:115]
	v_mfma_f32_16x16x32_bf16 v[104:107], v[140:143], v[190:193], v[104:107]
	v_mfma_f32_16x16x32_bf16 v[100:103], v[132:135], v[198:201], v[100:103]
	v_mfma_f32_16x16x32_bf16 v[96:99], v[140:143], v[198:201], v[96:99]
	v_mfma_f32_16x16x32_bf16 v[76:79], v[132:135], v[206:209], v[76:79]
	v_mfma_f32_16x16x32_bf16 v[72:75], v[140:143], v[206:209], v[72:75]
	v_mfma_f32_16x16x32_bf16 v[116:119], v[162:165], v[178:181], 0
	v_mfma_f32_16x16x32_bf16 v[108:111], v[170:173], v[178:181], 0
	v_mfma_f32_16x16x32_bf16 v[92:95], v[162:165], v[186:189], 0
	v_mfma_f32_16x16x32_bf16 v[88:91], v[170:173], v[186:189], 0
	v_mfma_f32_16x16x32_bf16 v[84:87], v[162:165], v[194:197], 0
	v_mfma_f32_16x16x32_bf16 v[80:83], v[170:173], v[194:197], 0
	v_mfma_f32_16x16x32_bf16 v[68:71], v[162:165], v[202:205], 0
	v_mfma_f32_16x16x32_bf16 v[64:67], v[170:173], v[202:205], 0
	v_mfma_f32_16x16x32_bf16 v[116:119], v[166:169], v[182:185], v[116:119]
	v_mfma_f32_16x16x32_bf16 v[108:111], v[174:177], v[182:185], v[108:111]
	v_mfma_f32_16x16x32_bf16 v[92:95], v[166:169], v[190:193], v[92:95]
	v_mfma_f32_16x16x32_bf16 v[88:91], v[174:177], v[190:193], v[88:91]
	v_mfma_f32_16x16x32_bf16 v[84:87], v[166:169], v[198:201], v[84:87]
	v_mfma_f32_16x16x32_bf16 v[80:83], v[174:177], v[198:201], v[80:83]
	v_mfma_f32_16x16x32_bf16 v[68:71], v[166:169], v[206:209], v[68:71]
	v_mfma_f32_16x16x32_bf16 v[64:67], v[174:177], v[206:209], v[64:67]
	s_setprio 0
	s_barrier
	s_add_i32 s62, s51, s38
	v_lshl_add_u64 v[210:211], s[28:29], 0, v[148:149]
	s_mov_b32 m0, s62
	ds_read_b128 v[178:181], v216 offset:16384
	ds_read_b128 v[182:185], v216 offset:17408
	ds_read_b128 v[186:189], v216 offset:18432
	ds_read_b128 v[190:193], v216 offset:19456
	ds_read_b128 v[194:197], v216 offset:20480
	ds_read_b128 v[198:201], v216 offset:21504
	ds_read_b128 v[202:205], v216 offset:22528
	ds_read_b128 v[206:209], v216 offset:23552
	global_load_lds_dwordx4 v[210:211], off
	s_add_i32 m0, s62, 0x2000
	s_add_u32 s62, s28, 0x80000
	v_lshl_add_u64 v[218:219], s[28:29], 0, v[144:145]
	s_addc_u32 s63, s29, 0
	s_add_i32 s64, s52, s38
	global_load_lds_dwordx4 v[218:219], off
	v_lshl_add_u64 v[220:221], s[62:63], 0, v[148:149]
	s_mov_b32 m0, s64
	v_lshl_add_u64 v[222:223], s[30:31], 0, v[146:147]
	global_load_lds_dwordx4 v[220:221], off
	v_lshl_add_u64 v[220:221], s[62:63], 0, v[144:145]
	s_add_i32 m0, s64, 0x2000
	s_nop 0
	global_load_lds_dwordx4 v[220:221], off
	v_lshl_add_u64 v[220:221], s[30:31], 0, v[150:151]
	s_mov_b32 m0, s41
	s_nop 0
	global_load_lds_dwordx4 v[220:221], off
	s_mov_b32 m0, s42
	s_nop 0
	global_load_lds_dwordx4 v[222:223], off
	s_waitcnt vmcnt(8)
	s_waitcnt lgkmcnt(0)
	s_barrier
; #define PG8_STAGE(bufoff, gbase, voff) do { _Pragma("unroll") for (int _i = 0; _i < 2; ++_i) \
;         __builtin_amdgcn_global_load_lds((const unsigned*)((const char*)(gbase) + (voff)[_i]), (PG8_LAS unsigned*)(lds + (bufoff) + ldsw + _i * 8192), 16, 0, 0); } while (0)
; #define PG8_LDA(dst, b, h) do { _Pragma("unroll") for (int m = 0; m < 4; ++m) _Pragma("unroll") for (int k = 0; k < 2; ++k) dst[m][k] = *(const PG8_LAS bf16x8*)(lds + PG8_SA(b, h) + aoff + m * 2048 + k * 1024); } while (0)
; #define PG8_LDB(dst, b, h) do { _Pragma("unroll") for (int n = 0; n < 2; ++n) _Pragma("unroll") for (int k = 0; k < 2; ++k) dst[n][k] = *(const PG8_LAS bf16x8*)(lds + PG8_SB(b, h) + boff + n * 2048 + k * 1024); } while (0)
; #define PG8_MMA(ai, bj, At, Bt) do { __builtin_amdgcn_s_setprio(1); _Pragma("unroll") for (int m = 0; m < 4; ++m) _Pragma("unroll") for (int n = 0; n < 2; ++n) _Pragma("unroll") for (int k = 0; k < 2; ++k) \
;         acc[ai][bj][m][n] = __builtin_amdgcn_mfma_f32_16x16x32_bf16(Bt[n][k], At[m][k], acc[ai][bj][m][n], 0, 0, 0); __builtin_amdgcn_s_setprio(0); } while (0)
; #define PG8_WAIT_V(n) asm volatile("s_waitcnt vmcnt(" #n ")" ::: "memory")
; #define PG8_WAIT_L(n) asm volatile("s_waitcnt lgkmcnt(" #n ")" ::: "memory")
; #define PG8_BAR __builtin_amdgcn_s_barrier()
; #define PG8_SCHED __builtin_amdgcn_sched_barrier(0)
; template <class Epi, class Sched, bool ALIGN_EPI = false, bool SP2 = false>
; __device__ __forceinline__ void gemm_phase(PG8_LAS unsigned char* lds, const Gemm g, const Sched& S, const Epi& E, const int wave_in) {
;     ...
;             PG8_LDA(At, 0, 1); PG8_STAGE(PG8_SB(0, 0), b2, voffB); PG8_STAGE(PG8_SB(0, 1), b2 + hstepB, voffB); PG8_STAGE(PG8_SA(0, 0), a2, voffA);
;             PG8_WAIT_V(8); PG8_WAIT_L(0); PG8_BAR; PG8_MMA(1, 0, At, B0); PG8_MMA(1, 1, At, B1); PG8_BAR; PG8_SCHED;
;             PG8_LDB(B0, 1, 0); PG8_LDB(B1, 1, 1); PG8_SCHED; PG8_LDA(At, 1, 0); PG8_STAGE(PG8_SA(0, 1), a2 + hstepA, voffA);
;             PG8_WAIT_V(8); PG8_WAIT_L(0); PG8_BAR; PG8_MMA(0, 0, At, B0); PG8_MMA(0, 1, At, B1); PG8_BAR; PG8_SCHED;
	s_setprio 1
	s_waitcnt lgkmcnt(0)
	v_mfma_f32_16x16x32_bf16 v[60:63], v[128:131], v[178:181], 0
	v_mfma_f32_16x16x32_bf16 v[56:59], v[136:139], v[178:181], 0
	v_mfma_f32_16x16x32_bf16 v[48:51], v[128:131], v[186:189], 0
	v_mfma_f32_16x16x32_bf16 v[40:43], v[136:139], v[186:189], 0
	v_mfma_f32_16x16x32_bf16 v[32:35], v[128:131], v[194:197], 0
	v_mfma_f32_16x16x32_bf16 v[24:27], v[136:139], v[194:197], 0
	v_mfma_f32_16x16x32_bf16 v[16:19], v[128:131], v[202:205], 0
	v_mfma_f32_16x16x32_bf16 v[8:11], v[136:139], v[202:205], 0
	v_mfma_f32_16x16x32_bf16 v[60:63], v[132:135], v[182:185], v[60:63]
	v_mfma_f32_16x16x32_bf16 v[56:59], v[140:143], v[182:185], v[56:59]
	v_mfma_f32_16x16x32_bf16 v[48:51], v[132:135], v[190:193], v[48:51]
	v_mfma_f32_16x16x32_bf16 v[40:43], v[140:143], v[190:193], v[40:43]
	v_mfma_f32_16x16x32_bf16 v[32:35], v[132:135], v[198:201], v[32:35]
	v_mfma_f32_16x16x32_bf16 v[24:27], v[140:143], v[198:201], v[24:27]
	v_mfma_f32_16x16x32_bf16 v[16:19], v[132:135], v[206:209], v[16:19]
	v_mfma_f32_16x16x32_bf16 v[8:11], v[140:143], v[206:209], v[8:11]
	v_mfma_f32_16x16x32_bf16 v[52:55], v[162:165], v[178:181], 0
	v_mfma_f32_16x16x32_bf16 v[44:47], v[170:173], v[178:181], 0
	v_mfma_f32_16x16x32_bf16 v[36:39], v[162:165], v[186:189], 0
	v_mfma_f32_16x16x32_bf16 v[28:31], v[170:173], v[186:189], 0
	v_mfma_f32_16x16x32_bf16 v[20:23], v[162:165], v[194:197], 0
	v_mfma_f32_16x16x32_bf16 v[12:15], v[170:173], v[194:197], 0
	v_mfma_f32_16x16x32_bf16 v[4:7], v[162:165], v[202:205], 0
	v_mfma_f32_16x16x32_bf16 v[0:3], v[170:173], v[202:205], 0
	v_mfma_f32_16x16x32_bf16 v[52:55], v[166:169], v[182:185], v[52:55]
	v_mfma_f32_16x16x32_bf16 v[44:47], v[174:177], v[182:185], v[44:47]
	v_mfma_f32_16x16x32_bf16 v[36:39], v[166:169], v[190:193], v[36:39]
	v_mfma_f32_16x16x32_bf16 v[28:31], v[174:177], v[190:193], v[28:31]
	v_mfma_f32_16x16x32_bf16 v[20:23], v[166:169], v[198:201], v[20:23]
	v_mfma_f32_16x16x32_bf16 v[12:15], v[174:177], v[198:201], v[12:15]
	v_mfma_f32_16x16x32_bf16 v[4:7], v[166:169], v[206:209], v[4:7]
	v_mfma_f32_16x16x32_bf16 v[0:3], v[174:177], v[206:209], v[0:3]
	s_setprio 0
	s_barrier
	s_add_i32 s62, 0, 0x18000
	s_add_i32 s63, 0, 0x1c000
	v_add_u32_e32 v140, s62, v212
	v_add_u32_e32 v174, s63, v212
	ds_read_b128 v[128:131], v140
	ds_read_b128 v[132:135], v140 offset:1024
	ds_read_b128 v[136:139], v140 offset:2048
	ds_read_b128 v[140:143], v140 offset:3072
	ds_read_b128 v[162:165], v174
	ds_read_b128 v[166:169], v174 offset:1024
	ds_read_b128 v[170:173], v174 offset:2048
	ds_read_b128 v[174:177], v174 offset:3072
	s_add_u32 s30, s30, 0x80000
	s_addc_u32 s31, s31, 0
	s_mov_b32 m0, s43
	v_lshl_add_u64 v[224:225], s[30:31], 0, v[150:151]
	ds_read_b128 v[178:181], v216 offset:32768
	ds_read_b128 v[182:185], v216 offset:33792
	ds_read_b128 v[186:189], v216 offset:34816
	ds_read_b128 v[190:193], v216 offset:35840
	ds_read_b128 v[194:197], v216 offset:36864
	ds_read_b128 v[198:201], v216 offset:37888
	ds_read_b128 v[202:205], v216 offset:38912
	ds_read_b128 v[206:209], v216 offset:39936
	global_load_lds_dwordx4 v[224:225], off
	v_lshl_add_u64 v[224:225], s[30:31], 0, v[146:147]
	s_mov_b32 m0, s44
	s_nop 0
	global_load_lds_dwordx4 v[224:225], off
	s_waitcnt vmcnt(8)
	s_waitcnt lgkmcnt(0)
	s_barrier
	s_setprio 1
	s_waitcnt lgkmcnt(0)
	v_mfma_f32_16x16x32_bf16 v[124:127], v[128:131], v[178:181], v[124:127]
	v_mfma_f32_16x16x32_bf16 v[120:123], v[136:139], v[178:181], v[120:123]
	v_mfma_f32_16x16x32_bf16 v[112:115], v[128:131], v[186:189], v[112:115]
	v_mfma_f32_16x16x32_bf16 v[104:107], v[136:139], v[186:189], v[104:107]
	v_mfma_f32_16x16x32_bf16 v[100:103], v[128:131], v[194:197], v[100:103]
	v_mfma_f32_16x16x32_bf16 v[96:99], v[136:139], v[194:197], v[96:99]
	v_mfma_f32_16x16x32_bf16 v[76:79], v[128:131], v[202:205], v[76:79]
	v_mfma_f32_16x16x32_bf16 v[72:75], v[136:139], v[202:205], v[72:75]
	v_mfma_f32_16x16x32_bf16 v[124:127], v[132:135], v[182:185], v[124:127]
	v_mfma_f32_16x16x32_bf16 v[120:123], v[140:143], v[182:185], v[120:123]
	v_mfma_f32_16x16x32_bf16 v[112:115], v[132:135], v[190:193], v[112:115]
	v_mfma_f32_16x16x32_bf16 v[104:107], v[140:143], v[190:193], v[104:107]
	v_mfma_f32_16x16x32_bf16 v[100:103], v[132:135], v[198:201], v[100:103]
	v_mfma_f32_16x16x32_bf16 v[96:99], v[140:143], v[198:201], v[96:99]
	v_mfma_f32_16x16x32_bf16 v[76:79], v[132:135], v[206:209], v[76:79]
	v_mfma_f32_16x16x32_bf16 v[72:75], v[140:143], v[206:209], v[72:75]
	v_mfma_f32_16x16x32_bf16 v[116:119], v[162:165], v[178:181], v[116:119]
	v_mfma_f32_16x16x32_bf16 v[108:111], v[170:173], v[178:181], v[108:111]
	v_mfma_f32_16x16x32_bf16 v[92:95], v[162:165], v[186:189], v[92:95]
	v_mfma_f32_16x16x32_bf16 v[88:91], v[170:173], v[186:189], v[88:91]
	v_mfma_f32_16x16x32_bf16 v[84:87], v[162:165], v[194:197], v[84:87]
	v_mfma_f32_16x16x32_bf16 v[80:83], v[170:173], v[194:197], v[80:83]
	v_mfma_f32_16x16x32_bf16 v[68:71], v[162:165], v[202:205], v[68:71]
	v_mfma_f32_16x16x32_bf16 v[64:67], v[170:173], v[202:205], v[64:67]
	v_mfma_f32_16x16x32_bf16 v[116:119], v[166:169], v[182:185], v[116:119]
	v_mfma_f32_16x16x32_bf16 v[108:111], v[174:177], v[182:185], v[108:111]
	v_mfma_f32_16x16x32_bf16 v[92:95], v[166:169], v[190:193], v[92:95]
	v_mfma_f32_16x16x32_bf16 v[88:91], v[174:177], v[190:193], v[88:91]
	v_mfma_f32_16x16x32_bf16 v[84:87], v[166:169], v[198:201], v[84:87]
	v_mfma_f32_16x16x32_bf16 v[80:83], v[174:177], v[198:201], v[80:83]
	v_mfma_f32_16x16x32_bf16 v[68:71], v[166:169], v[206:209], v[68:71]
	v_mfma_f32_16x16x32_bf16 v[64:67], v[174:177], v[206:209], v[64:67]
	s_setprio 0
	s_barrier
; #define PG8_STAGE(bufoff, gbase, voff) do { _Pragma("unroll") for (int _i = 0; _i < 2; ++_i) \
;         __builtin_amdgcn_global_load_lds((const unsigned*)((const char*)(gbase) + (voff)[_i]), (PG8_LAS unsigned*)(lds + (bufoff) + ldsw + _i * 8192), 16, 0, 0); } while (0)
; #define PG8_LDA(dst, b, h) do { _Pragma("unroll") for (int m = 0; m < 4; ++m) _Pragma("unroll") for (int k = 0; k < 2; ++k) dst[m][k] = *(const PG8_LAS bf16x8*)(lds + PG8_SA(b, h) + aoff + m * 2048 + k * 1024); } while (0)
; #define PG8_LDB(dst, b, h) do { _Pragma("unroll") for (int n = 0; n < 2; ++n) _Pragma("unroll") for (int k = 0; k < 2; ++k) dst[n][k] = *(const PG8_LAS bf16x8*)(lds + PG8_SB(b, h) + boff + n * 2048 + k * 1024); } while (0)
; #define PG8_MMA(ai, bj, At, Bt) do { __builtin_amdgcn_s_setprio(1); _Pragma("unroll") for (int m = 0; m < 4; ++m) _Pragma("unroll") for (int n = 0; n < 2; ++n) _Pragma("unroll") for (int k = 0; k < 2; ++k) \
;         acc[ai][bj][m][n] = __builtin_amdgcn_mfma_f32_16x16x32_bf16(Bt[n][k], At[m][k], acc[ai][bj][m][n], 0, 0, 0); __builtin_amdgcn_s_setprio(0); } while (0)
; #define PG8_WAIT_V(n) asm volatile("s_waitcnt vmcnt(" #n ")" ::: "memory")
; #define PG8_WAIT_L(n) asm volatile("s_waitcnt lgkmcnt(" #n ")" ::: "memory")
; #define PG8_BAR __builtin_amdgcn_s_barrier()
; #define PG8_SCHED __builtin_amdgcn_sched_barrier(0)
; template <class Epi, class Sched, bool ALIGN_EPI = false, bool SP2 = false>
; __device__ __forceinline__ void gemm_phase(PG8_LAS unsigned char* lds, const Gemm g, const Sched& S, const Epi& E, const int wave_in) {
;     ...
;         for (int t = 0; t < nt; t += 2) {
;     ...
;             PG8_LDB(B0, 0, 0); PG8_LDB(B1, 0, 1); PG8_SCHED; PG8_LDA(At, 0, 0); PG8_STAGE(PG8_SA(1, 1), a1 + hstepA, voffA);
;             PG8_WAIT_V(8); PG8_WAIT_L(0); PG8_BAR; PG8_MMA(0, 0, At, B0); PG8_MMA(0, 1, At, B1); PG8_BAR; PG8_SCHED;
;     ...
;             PG8_LDA(At, 1, 1); PG8_STAGE(PG8_SB(1, 0), b3, voffB); PG8_STAGE(PG8_SB(1, 1), b3 + hstepB, voffB); PG8_STAGE(PG8_SA(1, 0), a3, voffA);
;             PG8_WAIT_V(8); PG8_WAIT_L(0); PG8_BAR; PG8_MMA(1, 0, At, B0); PG8_MMA(1, 1, At, B1); PG8_BAR; PG8_SCHED;
	s_add_i32 s30, s62, s38
	v_lshl_add_u64 v[210:211], v[210:211], 0, s[6:7]
	s_mov_b32 m0, s30
	ds_read_b128 v[178:181], v216 offset:49152
	ds_read_b128 v[182:185], v216 offset:50176
	ds_read_b128 v[186:189], v216 offset:51200
	ds_read_b128 v[190:193], v216 offset:52224
	ds_read_b128 v[194:197], v216 offset:53248
	ds_read_b128 v[198:201], v216 offset:54272
	ds_read_b128 v[202:205], v216 offset:55296
	ds_read_b128 v[206:209], v216 offset:56320
	global_load_lds_dwordx4 v[210:211], off
	s_add_i32 m0, s30, 0x2000
	s_add_u32 s28, s28, 0x80080
	v_lshl_add_u64 v[210:211], v[218:219], 0, s[6:7]
	s_addc_u32 s29, s29, 0
	s_add_i32 s30, s63, s38
	global_load_lds_dwordx4 v[210:211], off
	v_lshl_add_u64 v[210:211], s[28:29], 0, v[148:149]
	s_mov_b32 m0, s30
	s_nop 0
	global_load_lds_dwordx4 v[210:211], off
	v_lshl_add_u64 v[210:211], s[28:29], 0, v[144:145]
	s_add_i32 m0, s30, 0x2000
	s_nop 0
	global_load_lds_dwordx4 v[210:211], off
	v_lshl_add_u64 v[210:211], v[220:221], 0, s[6:7]
	s_mov_b32 m0, s48
	s_nop 0
	global_load_lds_dwordx4 v[210:211], off
	v_lshl_add_u64 v[210:211], v[222:223], 0, s[6:7]
	s_mov_b32 m0, s49
	s_nop 0
	global_load_lds_dwordx4 v[210:211], off
	s_waitcnt vmcnt(8)
	s_waitcnt lgkmcnt(0)
	s_barrier
	s_setprio 1
	s_waitcnt lgkmcnt(0)
	v_mfma_f32_16x16x32_bf16 v[60:63], v[128:131], v[178:181], v[60:63]
	v_mfma_f32_16x16x32_bf16 v[56:59], v[136:139], v[178:181], v[56:59]
	v_mfma_f32_16x16x32_bf16 v[48:51], v[128:131], v[186:189], v[48:51]
	v_mfma_f32_16x16x32_bf16 v[40:43], v[136:139], v[186:189], v[40:43]
	v_mfma_f32_16x16x32_bf16 v[32:35], v[128:131], v[194:197], v[32:35]
	v_mfma_f32_16x16x32_bf16 v[24:27], v[136:139], v[194:197], v[24:27]
	v_mfma_f32_16x16x32_bf16 v[16:19], v[128:131], v[202:205], v[16:19]
	v_mfma_f32_16x16x32_bf16 v[8:11], v[136:139], v[202:205], v[8:11]
	v_mfma_f32_16x16x32_bf16 v[60:63], v[132:135], v[182:185], v[60:63]
	v_mfma_f32_16x16x32_bf16 v[56:59], v[140:143], v[182:185], v[56:59]
	v_mfma_f32_16x16x32_bf16 v[48:51], v[132:135], v[190:193], v[48:51]
	v_mfma_f32_16x16x32_bf16 v[40:43], v[140:143], v[190:193], v[40:43]
	v_mfma_f32_16x16x32_bf16 v[32:35], v[132:135], v[198:201], v[32:35]
	v_mfma_f32_16x16x32_bf16 v[24:27], v[140:143], v[198:201], v[24:27]
	v_mfma_f32_16x16x32_bf16 v[16:19], v[132:135], v[206:209], v[16:19]
	v_mfma_f32_16x16x32_bf16 v[8:11], v[140:143], v[206:209], v[8:11]
	v_mfma_f32_16x16x32_bf16 v[52:55], v[162:165], v[178:181], v[52:55]
	v_mfma_f32_16x16x32_bf16 v[44:47], v[170:173], v[178:181], v[44:47]
	v_mfma_f32_16x16x32_bf16 v[36:39], v[162:165], v[186:189], v[36:39]
	v_mfma_f32_16x16x32_bf16 v[28:31], v[170:173], v[186:189], v[28:31]
	v_mfma_f32_16x16x32_bf16 v[20:23], v[162:165], v[194:197], v[20:23]
	v_mfma_f32_16x16x32_bf16 v[12:15], v[170:173], v[194:197], v[12:15]
	v_mfma_f32_16x16x32_bf16 v[4:7], v[162:165], v[202:205], v[4:7]
	v_mfma_f32_16x16x32_bf16 v[0:3], v[170:173], v[202:205], v[0:3]
	v_mfma_f32_16x16x32_bf16 v[52:55], v[166:169], v[182:185], v[52:55]
	v_mfma_f32_16x16x32_bf16 v[44:47], v[174:177], v[182:185], v[44:47]
	v_mfma_f32_16x16x32_bf16 v[36:39], v[166:169], v[190:193], v[36:39]
	v_mfma_f32_16x16x32_bf16 v[28:31], v[174:177], v[190:193], v[28:31]
	v_mfma_f32_16x16x32_bf16 v[20:23], v[166:169], v[198:201], v[20:23]
	v_mfma_f32_16x16x32_bf16 v[12:15], v[174:177], v[198:201], v[12:15]
	v_mfma_f32_16x16x32_bf16 v[4:7], v[166:169], v[206:209], v[4:7]
	v_mfma_f32_16x16x32_bf16 v[0:3], v[174:177], v[206:209], v[0:3]
	s_setprio 0
	s_barrier
	s_add_i32 s61, s61, 2
	s_add_u32 s26, s26, 0x100
	s_addc_u32 s27, s27, 0
	s_add_u32 s59, s59, 0x100
	s_addc_u32 s60, s60, 0
	s_cmp_gt_u32 s61, 29
	s_cbranch_scc0 .LBB0_1825
	s_branch .Lkx_20
.LBB0_1825:
	ds_read_b128 v[128:131], v214
	ds_read_b128 v[132:135], v214 offset:1024
	ds_read_b128 v[136:139], v214 offset:2048
	ds_read_b128 v[140:143], v214 offset:3072
	ds_read_b128 v[162:165], v215
	ds_read_b128 v[166:169], v215 offset:1024
	ds_read_b128 v[170:173], v215 offset:2048
	ds_read_b128 v[174:177], v215 offset:3072
	s_add_u32 s28, s26, 0xfff80080
	s_addc_u32 s29, s27, -1
	s_cmp_eq_u32 s61, 28
	s_cselect_b32 s31, s19, s29
	s_cselect_b32 s30, s25, s28
	s_cselect_b32 s29, s17, s60
	s_cselect_b32 s28, s58, s59
	v_lshl_add_u64 v[210:211], s[26:27], 0, v[154:155]
	s_add_i32 m0, s41, 0xc000
	ds_read_b128 v[178:181], v216
	ds_read_b128 v[182:185], v216 offset:1024
	ds_read_b128 v[186:189], v216 offset:2048
	ds_read_b128 v[190:193], v216 offset:3072
	ds_read_b128 v[194:197], v216 offset:4096
	ds_read_b128 v[198:201], v216 offset:5120
	ds_read_b128 v[202:205], v216 offset:6144
	ds_read_b128 v[206:209], v216 offset:7168
	global_load_lds_dwordx4 v[210:211], off
	v_lshl_add_u64 v[210:211], s[26:27], 0, v[156:157]
	s_add_i32 m0, s41, 0xe000
	s_nop 0
	global_load_lds_dwordx4 v[210:211], off
	s_waitcnt vmcnt(8)
	s_waitcnt lgkmcnt(0)
	s_barrier
; #define PG8_STAGE(bufoff, gbase, voff) do { _Pragma("unroll") for (int _i = 0; _i < 2; ++_i) \
;         __builtin_amdgcn_global_load_lds((const unsigned*)((const char*)(gbase) + (voff)[_i]), (PG8_LAS unsigned*)(lds + (bufoff) + ldsw + _i * 8192), 16, 0, 0); } while (0)
; #define PG8_LDA(dst, b, h) do { _Pragma("unroll") for (int m = 0; m < 4; ++m) _Pragma("unroll") for (int k = 0; k < 2; ++k) dst[m][k] = *(const PG8_LAS bf16x8*)(lds + PG8_SA(b, h) + aoff + m * 2048 + k * 1024); } while (0)
; #define PG8_MMA(ai, bj, At, Bt) do { __builtin_amdgcn_s_setprio(1); _Pragma("unroll") for (int m = 0; m < 4; ++m) _Pragma("unroll") for (int n = 0; n < 2; ++n) _Pragma("unroll") for (int k = 0; k < 2; ++k) \
;         acc[ai][bj][m][n] = __builtin_amdgcn_mfma_f32_16x16x32_bf16(Bt[n][k], At[m][k], acc[ai][bj][m][n], 0, 0, 0); __builtin_amdgcn_s_setprio(0); } while (0)
; #define PG8_WAIT_V(n) asm volatile("s_waitcnt vmcnt(" #n ")" ::: "memory")
; #define PG8_WAIT_L(n) asm volatile("s_waitcnt lgkmcnt(" #n ")" ::: "memory")
; #define PG8_BAR __builtin_amdgcn_s_barrier()
; #define PG8_SCHED __builtin_amdgcn_sched_barrier(0)
; template <class Epi, class Sched, bool ALIGN_EPI = false, bool SP2 = false>
; __device__ __forceinline__ void gemm_phase(PG8_LAS unsigned char* lds, const Gemm g, const Sched& S, const Epi& E, const int wave_in) {
;     ...
;             PG8_WAIT_V(8); PG8_WAIT_L(0); PG8_BAR; PG8_MMA(0, 0, At, B0); PG8_MMA(0, 1, At, B1); PG8_BAR; PG8_SCHED;
;             PG8_LDA(At, 0, 1); PG8_STAGE(PG8_SB(0, 0), b2, voffB); PG8_STAGE(PG8_SB(0, 1), b2 + hstepB, voffB); PG8_STAGE(PG8_SA(0, 0), a2, voffA);
;             PG8_WAIT_V(8); PG8_WAIT_L(0); PG8_BAR; PG8_MMA(1, 0, At, B0); PG8_MMA(1, 1, At, B1); PG8_BAR; PG8_SCHED;
	s_setprio 1
	s_waitcnt lgkmcnt(0)
	v_mfma_f32_16x16x32_bf16 v[124:127], v[128:131], v[178:181], v[124:127]
	v_mfma_f32_16x16x32_bf16 v[120:123], v[136:139], v[178:181], v[120:123]
	v_mfma_f32_16x16x32_bf16 v[112:115], v[128:131], v[186:189], v[112:115]
	v_mfma_f32_16x16x32_bf16 v[104:107], v[136:139], v[186:189], v[104:107]
	v_mfma_f32_16x16x32_bf16 v[100:103], v[128:131], v[194:197], v[100:103]
	v_mfma_f32_16x16x32_bf16 v[96:99], v[136:139], v[194:197], v[96:99]
	v_mfma_f32_16x16x32_bf16 v[76:79], v[128:131], v[202:205], v[76:79]
	v_mfma_f32_16x16x32_bf16 v[72:75], v[136:139], v[202:205], v[72:75]
	v_mfma_f32_16x16x32_bf16 v[124:127], v[132:135], v[182:185], v[124:127]
	v_mfma_f32_16x16x32_bf16 v[120:123], v[140:143], v[182:185], v[120:123]
	v_mfma_f32_16x16x32_bf16 v[112:115], v[132:135], v[190:193], v[112:115]
	v_mfma_f32_16x16x32_bf16 v[104:107], v[140:143], v[190:193], v[104:107]
	v_mfma_f32_16x16x32_bf16 v[100:103], v[132:135], v[198:201], v[100:103]
	v_mfma_f32_16x16x32_bf16 v[96:99], v[140:143], v[198:201], v[96:99]
	v_mfma_f32_16x16x32_bf16 v[76:79], v[132:135], v[206:209], v[76:79]
	v_mfma_f32_16x16x32_bf16 v[72:75], v[140:143], v[206:209], v[72:75]
	v_mfma_f32_16x16x32_bf16 v[116:119], v[162:165], v[178:181], v[116:119]
	v_mfma_f32_16x16x32_bf16 v[108:111], v[170:173], v[178:181], v[108:111]
	v_mfma_f32_16x16x32_bf16 v[92:95], v[162:165], v[186:189], v[92:95]
	v_mfma_f32_16x16x32_bf16 v[88:91], v[170:173], v[186:189], v[88:91]
	v_mfma_f32_16x16x32_bf16 v[84:87], v[162:165], v[194:197], v[84:87]
	v_mfma_f32_16x16x32_bf16 v[80:83], v[170:173], v[194:197], v[80:83]
	v_mfma_f32_16x16x32_bf16 v[68:71], v[162:165], v[202:205], v[68:71]
	v_mfma_f32_16x16x32_bf16 v[64:67], v[170:173], v[202:205], v[64:67]
	v_mfma_f32_16x16x32_bf16 v[116:119], v[166:169], v[182:185], v[116:119]
	v_mfma_f32_16x16x32_bf16 v[108:111], v[174:177], v[182:185], v[108:111]
	v_mfma_f32_16x16x32_bf16 v[92:95], v[166:169], v[190:193], v[92:95]
	v_mfma_f32_16x16x32_bf16 v[88:91], v[174:177], v[190:193], v[88:91]
	v_mfma_f32_16x16x32_bf16 v[84:87], v[166:169], v[198:201], v[84:87]
	v_mfma_f32_16x16x32_bf16 v[80:83], v[174:177], v[198:201], v[80:83]
	v_mfma_f32_16x16x32_bf16 v[68:71], v[166:169], v[206:209], v[68:71]
	v_mfma_f32_16x16x32_bf16 v[64:67], v[174:177], v[206:209], v[64:67]
	s_setprio 0
	s_barrier
	s_add_i32 s62, s51, s38
	v_lshl_add_u64 v[210:211], s[28:29], 0, v[148:149]
	s_mov_b32 m0, s62
	ds_read_b128 v[178:181], v216 offset:16384
	ds_read_b128 v[182:185], v216 offset:17408
	ds_read_b128 v[186:189], v216 offset:18432
	ds_read_b128 v[190:193], v216 offset:19456
	ds_read_b128 v[194:197], v216 offset:20480
	ds_read_b128 v[198:201], v216 offset:21504
	ds_read_b128 v[202:205], v216 offset:22528
	ds_read_b128 v[206:209], v216 offset:23552
	global_load_lds_dwordx4 v[210:211], off
	s_add_i32 m0, s62, 0x2000
	s_add_u32 s62, s28, 0x80000
	v_lshl_add_u64 v[218:219], s[28:29], 0, v[144:145]
	s_addc_u32 s63, s29, 0
	s_add_i32 s64, s52, s38
	global_load_lds_dwordx4 v[218:219], off
	v_lshl_add_u64 v[220:221], s[62:63], 0, v[148:149]
	s_mov_b32 m0, s64
	v_lshl_add_u64 v[222:223], s[30:31], 0, v[146:147]
	global_load_lds_dwordx4 v[220:221], off
	v_lshl_add_u64 v[220:221], s[62:63], 0, v[144:145]
	s_add_i32 m0, s64, 0x2000
	s_nop 0
	global_load_lds_dwordx4 v[220:221], off
	v_lshl_add_u64 v[220:221], s[30:31], 0, v[150:151]
	s_mov_b32 m0, s41
	s_nop 0
	global_load_lds_dwordx4 v[220:221], off
	s_mov_b32 m0, s42
	s_nop 0
	global_load_lds_dwordx4 v[222:223], off
	s_waitcnt vmcnt(8)
	s_waitcnt lgkmcnt(0)
	s_barrier
	s_setprio 1
	s_waitcnt lgkmcnt(0)
	v_mfma_f32_16x16x32_bf16 v[60:63], v[128:131], v[178:181], v[60:63]
	v_mfma_f32_16x16x32_bf16 v[56:59], v[136:139], v[178:181], v[56:59]
	v_mfma_f32_16x16x32_bf16 v[48:51], v[128:131], v[186:189], v[48:51]
	v_mfma_f32_16x16x32_bf16 v[40:43], v[136:139], v[186:189], v[40:43]
	v_mfma_f32_16x16x32_bf16 v[32:35], v[128:131], v[194:197], v[32:35]
	v_mfma_f32_16x16x32_bf16 v[24:27], v[136:139], v[194:197], v[24:27]
	v_mfma_f32_16x16x32_bf16 v[16:19], v[128:131], v[202:205], v[16:19]
	v_mfma_f32_16x16x32_bf16 v[8:11], v[136:139], v[202:205], v[8:11]
	v_mfma_f32_16x16x32_bf16 v[60:63], v[132:135], v[182:185], v[60:63]
	v_mfma_f32_16x16x32_bf16 v[56:59], v[140:143], v[182:185], v[56:59]
	v_mfma_f32_16x16x32_bf16 v[48:51], v[132:135], v[190:193], v[48:51]
	v_mfma_f32_16x16x32_bf16 v[40:43], v[140:143], v[190:193], v[40:43]
	v_mfma_f32_16x16x32_bf16 v[32:35], v[132:135], v[198:201], v[32:35]
	v_mfma_f32_16x16x32_bf16 v[24:27], v[140:143], v[198:201], v[24:27]
	v_mfma_f32_16x16x32_bf16 v[16:19], v[132:135], v[206:209], v[16:19]
	v_mfma_f32_16x16x32_bf16 v[8:11], v[140:143], v[206:209], v[8:11]
	v_mfma_f32_16x16x32_bf16 v[52:55], v[162:165], v[178:181], v[52:55]
	v_mfma_f32_16x16x32_bf16 v[44:47], v[170:173], v[178:181], v[44:47]
	v_mfma_f32_16x16x32_bf16 v[36:39], v[162:165], v[186:189], v[36:39]
	v_mfma_f32_16x16x32_bf16 v[28:31], v[170:173], v[186:189], v[28:31]
	v_mfma_f32_16x16x32_bf16 v[20:23], v[162:165], v[194:197], v[20:23]
	v_mfma_f32_16x16x32_bf16 v[12:15], v[170:173], v[194:197], v[12:15]
	v_mfma_f32_16x16x32_bf16 v[4:7], v[162:165], v[202:205], v[4:7]
	v_mfma_f32_16x16x32_bf16 v[0:3], v[170:173], v[202:205], v[0:3]
	v_mfma_f32_16x16x32_bf16 v[52:55], v[166:169], v[182:185], v[52:55]
	v_mfma_f32_16x16x32_bf16 v[44:47], v[174:177], v[182:185], v[44:47]
	v_mfma_f32_16x16x32_bf16 v[36:39], v[166:169], v[190:193], v[36:39]
	v_mfma_f32_16x16x32_bf16 v[28:31], v[174:177], v[190:193], v[28:31]
	v_mfma_f32_16x16x32_bf16 v[20:23], v[166:169], v[198:201], v[20:23]
	v_mfma_f32_16x16x32_bf16 v[12:15], v[174:177], v[198:201], v[12:15]
	v_mfma_f32_16x16x32_bf16 v[4:7], v[166:169], v[206:209], v[4:7]
	v_mfma_f32_16x16x32_bf16 v[0:3], v[174:177], v[206:209], v[0:3]
	s_setprio 0
	s_barrier
; #define PG8_STAGE(bufoff, gbase, voff) do { _Pragma("unroll") for (int _i = 0; _i < 2; ++_i) \
;         __builtin_amdgcn_global_load_lds((const unsigned*)((const char*)(gbase) + (voff)[_i]), (PG8_LAS unsigned*)(lds + (bufoff) + ldsw + _i * 8192), 16, 0, 0); } while (0)
; #define PG8_LDA(dst, b, h) do { _Pragma("unroll") for (int m = 0; m < 4; ++m) _Pragma("unroll") for (int k = 0; k < 2; ++k) dst[m][k] = *(const PG8_LAS bf16x8*)(lds + PG8_SA(b, h) + aoff + m * 2048 + k * 1024); } while (0)
; #define PG8_LDB(dst, b, h) do { _Pragma("unroll") for (int n = 0; n < 2; ++n) _Pragma("unroll") for (int k = 0; k < 2; ++k) dst[n][k] = *(const PG8_LAS bf16x8*)(lds + PG8_SB(b, h) + boff + n * 2048 + k * 1024); } while (0)
; #define PG8_MMA(ai, bj, At, Bt) do { __builtin_amdgcn_s_setprio(1); _Pragma("unroll") for (int m = 0; m < 4; ++m) _Pragma("unroll") for (int n = 0; n < 2; ++n) _Pragma("unroll") for (int k = 0; k < 2; ++k) \
;         acc[ai][bj][m][n] = __builtin_amdgcn_mfma_f32_16x16x32_bf16(Bt[n][k], At[m][k], acc[ai][bj][m][n], 0, 0, 0); __builtin_amdgcn_s_setprio(0); } while (0)
; #define PG8_WAIT_V(n) asm volatile("s_waitcnt vmcnt(" #n ")" ::: "memory")
; #define PG8_WAIT_L(n) asm volatile("s_waitcnt lgkmcnt(" #n ")" ::: "memory")
; #define PG8_BAR __builtin_amdgcn_s_barrier()
; #define PG8_SCHED __builtin_amdgcn_sched_barrier(0)
; template <class Epi, class Sched, bool ALIGN_EPI = false, bool SP2 = false>
; __device__ __forceinline__ void gemm_phase(PG8_LAS unsigned char* lds, const Gemm g, const Sched& S, const Epi& E, const int wave_in) {
;     ...
;             PG8_LDB(B0, 1, 0); PG8_LDB(B1, 1, 1); PG8_SCHED; PG8_LDA(At, 1, 0); PG8_STAGE(PG8_SA(0, 1), a2 + hstepA, voffA);
;             PG8_WAIT_V(8); PG8_WAIT_L(0); PG8_BAR; PG8_MMA(0, 0, At, B0); PG8_MMA(0, 1, At, B1); PG8_BAR; PG8_SCHED;
	s_add_i32 s62, 0, 0x18000
	s_add_i32 s63, 0, 0x1c000
	v_add_u32_e32 v140, s62, v212
	v_add_u32_e32 v174, s63, v212
	ds_read_b128 v[128:131], v140
	ds_read_b128 v[132:135], v140 offset:1024
	ds_read_b128 v[136:139], v140 offset:2048
	ds_read_b128 v[140:143], v140 offset:3072
	ds_read_b128 v[162:165], v174
	ds_read_b128 v[166:169], v174 offset:1024
	ds_read_b128 v[170:173], v174 offset:2048
	ds_read_b128 v[174:177], v174 offset:3072
	s_add_u32 s30, s30, 0x80000
	s_addc_u32 s31, s31, 0
	s_mov_b32 m0, s43
	v_lshl_add_u64 v[224:225], s[30:31], 0, v[150:151]
	ds_read_b128 v[178:181], v216 offset:32768
	ds_read_b128 v[182:185], v216 offset:33792
	ds_read_b128 v[186:189], v216 offset:34816
	ds_read_b128 v[190:193], v216 offset:35840
	ds_read_b128 v[194:197], v216 offset:36864
	ds_read_b128 v[198:201], v216 offset:37888
	ds_read_b128 v[202:205], v216 offset:38912
	ds_read_b128 v[206:209], v216 offset:39936
	global_load_lds_dwordx4 v[224:225], off
	v_lshl_add_u64 v[224:225], s[30:31], 0, v[146:147]
	s_mov_b32 m0, s44
	s_nop 0
	global_load_lds_dwordx4 v[224:225], off
	s_waitcnt vmcnt(8)
	s_waitcnt lgkmcnt(0)
	s_barrier
	s_setprio 1
	s_waitcnt lgkmcnt(0)
	v_mfma_f32_16x16x32_bf16 v[124:127], v[128:131], v[178:181], v[124:127]
	v_mfma_f32_16x16x32_bf16 v[120:123], v[136:139], v[178:181], v[120:123]
	v_mfma_f32_16x16x32_bf16 v[112:115], v[128:131], v[186:189], v[112:115]
	v_mfma_f32_16x16x32_bf16 v[104:107], v[136:139], v[186:189], v[104:107]
	v_mfma_f32_16x16x32_bf16 v[100:103], v[128:131], v[194:197], v[100:103]
	v_mfma_f32_16x16x32_bf16 v[96:99], v[136:139], v[194:197], v[96:99]
	v_mfma_f32_16x16x32_bf16 v[76:79], v[128:131], v[202:205], v[76:79]
	v_mfma_f32_16x16x32_bf16 v[72:75], v[136:139], v[202:205], v[72:75]
	v_mfma_f32_16x16x32_bf16 v[124:127], v[132:135], v[182:185], v[124:127]
	v_mfma_f32_16x16x32_bf16 v[120:123], v[140:143], v[182:185], v[120:123]
	v_mfma_f32_16x16x32_bf16 v[112:115], v[132:135], v[190:193], v[112:115]
	v_mfma_f32_16x16x32_bf16 v[104:107], v[140:143], v[190:193], v[104:107]
	v_mfma_f32_16x16x32_bf16 v[100:103], v[132:135], v[198:201], v[100:103]
	v_mfma_f32_16x16x32_bf16 v[96:99], v[140:143], v[198:201], v[96:99]
	v_mfma_f32_16x16x32_bf16 v[76:79], v[132:135], v[206:209], v[76:79]
	v_mfma_f32_16x16x32_bf16 v[72:75], v[140:143], v[206:209], v[72:75]
	v_mfma_f32_16x16x32_bf16 v[116:119], v[162:165], v[178:181], v[116:119]
	v_mfma_f32_16x16x32_bf16 v[108:111], v[170:173], v[178:181], v[108:111]
	v_mfma_f32_16x16x32_bf16 v[92:95], v[162:165], v[186:189], v[92:95]
	v_mfma_f32_16x16x32_bf16 v[88:91], v[170:173], v[186:189], v[88:91]
	v_mfma_f32_16x16x32_bf16 v[84:87], v[162:165], v[194:197], v[84:87]
	v_mfma_f32_16x16x32_bf16 v[80:83], v[170:173], v[194:197], v[80:83]
	v_mfma_f32_16x16x32_bf16 v[68:71], v[162:165], v[202:205], v[68:71]
	v_mfma_f32_16x16x32_bf16 v[64:67], v[170:173], v[202:205], v[64:67]
	v_mfma_f32_16x16x32_bf16 v[116:119], v[166:169], v[182:185], v[116:119]
	v_mfma_f32_16x16x32_bf16 v[108:111], v[174:177], v[182:185], v[108:111]
	v_mfma_f32_16x16x32_bf16 v[92:95], v[166:169], v[190:193], v[92:95]
	v_mfma_f32_16x16x32_bf16 v[88:91], v[174:177], v[190:193], v[88:91]
	v_mfma_f32_16x16x32_bf16 v[84:87], v[166:169], v[198:201], v[84:87]
	v_mfma_f32_16x16x32_bf16 v[80:83], v[174:177], v[198:201], v[80:83]
	v_mfma_f32_16x16x32_bf16 v[68:71], v[166:169], v[206:209], v[68:71]
	v_mfma_f32_16x16x32_bf16 v[64:67], v[174:177], v[206:209], v[64:67]
	s_setprio 0
	s_barrier
; #define PG8_STAGE(bufoff, gbase, voff) do { _Pragma("unroll") for (int _i = 0; _i < 2; ++_i) \
;         __builtin_amdgcn_global_load_lds((const unsigned*)((const char*)(gbase) + (voff)[_i]), (PG8_LAS unsigned*)(lds + (bufoff) + ldsw + _i * 8192), 16, 0, 0); } while (0)
; #define PG8_LDA(dst, b, h) do { _Pragma("unroll") for (int m = 0; m < 4; ++m) _Pragma("unroll") for (int k = 0; k < 2; ++k) dst[m][k] = *(const PG8_LAS bf16x8*)(lds + PG8_SA(b, h) + aoff + m * 2048 + k * 1024); } while (0)
; #define PG8_MMA(ai, bj, At, Bt) do { __builtin_amdgcn_s_setprio(1); _Pragma("unroll") for (int m = 0; m < 4; ++m) _Pragma("unroll") for (int n = 0; n < 2; ++n) _Pragma("unroll") for (int k = 0; k < 2; ++k) \
;         acc[ai][bj][m][n] = __builtin_amdgcn_mfma_f32_16x16x32_bf16(Bt[n][k], At[m][k], acc[ai][bj][m][n], 0, 0, 0); __builtin_amdgcn_s_setprio(0); } while (0)
; #define PG8_WAIT_V(n) asm volatile("s_waitcnt vmcnt(" #n ")" ::: "memory")
; #define PG8_WAIT_L(n) asm volatile("s_waitcnt lgkmcnt(" #n ")" ::: "memory")
; #define PG8_BAR __builtin_amdgcn_s_barrier()
; #define PG8_SCHED __builtin_amdgcn_sched_barrier(0)
; template <class Epi, class Sched, bool ALIGN_EPI = false, bool SP2 = false>
; __device__ __forceinline__ void gemm_phase(PG8_LAS unsigned char* lds, const Gemm g, const Sched& S, const Epi& E, const int wave_in) {
;     ...
;         for (int t = 0; t < nt; t += 2) {
;     ...
;             PG8_LDA(At, 1, 1); PG8_STAGE(PG8_SB(1, 0), b3, voffB); PG8_STAGE(PG8_SB(1, 1), b3 + hstepB, voffB); PG8_STAGE(PG8_SA(1, 0), a3, voffA);
;             PG8_WAIT_V(8); PG8_WAIT_L(0); PG8_BAR; PG8_MMA(1, 0, At, B0); PG8_MMA(1, 1, At, B1); PG8_BAR; PG8_SCHED;
	s_add_i32 s30, s62, s38
	v_lshl_add_u64 v[210:211], v[210:211], 0, s[6:7]
	s_mov_b32 m0, s30
	ds_read_b128 v[178:181], v216 offset:49152
	ds_read_b128 v[182:185], v216 offset:50176
	ds_read_b128 v[186:189], v216 offset:51200
	ds_read_b128 v[190:193], v216 offset:52224
	ds_read_b128 v[194:197], v216 offset:53248
	ds_read_b128 v[198:201], v216 offset:54272
	ds_read_b128 v[202:205], v216 offset:55296
	ds_read_b128 v[206:209], v216 offset:56320
	global_load_lds_dwordx4 v[210:211], off
	s_add_i32 m0, s30, 0x2000
	s_add_u32 s28, s28, 0x80080
	v_lshl_add_u64 v[210:211], v[218:219], 0, s[6:7]
	s_addc_u32 s29, s29, 0
	s_add_i32 s30, s63, s38
	global_load_lds_dwordx4 v[210:211], off
	v_lshl_add_u64 v[210:211], s[28:29], 0, v[148:149]
	s_mov_b32 m0, s30
	s_nop 0
	global_load_lds_dwordx4 v[210:211], off
	v_lshl_add_u64 v[210:211], s[28:29], 0, v[144:145]
	s_add_i32 m0, s30, 0x2000
	s_nop 0
	global_load_lds_dwordx4 v[210:211], off
	v_lshl_add_u64 v[210:211], v[220:221], 0, s[6:7]
	s_mov_b32 m0, s48
	s_nop 0
	global_load_lds_dwordx4 v[210:211], off
	v_lshl_add_u64 v[210:211], v[222:223], 0, s[6:7]
	s_mov_b32 m0, s49
	s_nop 0
	global_load_lds_dwordx4 v[210:211], off
	s_waitcnt vmcnt(8)
	s_waitcnt lgkmcnt(0)
	s_barrier
	s_setprio 1
	s_waitcnt lgkmcnt(0)
	v_mfma_f32_16x16x32_bf16 v[60:63], v[128:131], v[178:181], v[60:63]
	v_mfma_f32_16x16x32_bf16 v[56:59], v[136:139], v[178:181], v[56:59]
	v_mfma_f32_16x16x32_bf16 v[48:51], v[128:131], v[186:189], v[48:51]
	v_mfma_f32_16x16x32_bf16 v[40:43], v[136:139], v[186:189], v[40:43]
	v_mfma_f32_16x16x32_bf16 v[32:35], v[128:131], v[194:197], v[32:35]
	v_mfma_f32_16x16x32_bf16 v[24:27], v[136:139], v[194:197], v[24:27]
	v_mfma_f32_16x16x32_bf16 v[16:19], v[128:131], v[202:205], v[16:19]
	v_mfma_f32_16x16x32_bf16 v[8:11], v[136:139], v[202:205], v[8:11]
	v_mfma_f32_16x16x32_bf16 v[60:63], v[132:135], v[182:185], v[60:63]
	v_mfma_f32_16x16x32_bf16 v[56:59], v[140:143], v[182:185], v[56:59]
	v_mfma_f32_16x16x32_bf16 v[48:51], v[132:135], v[190:193], v[48:51]
	v_mfma_f32_16x16x32_bf16 v[40:43], v[140:143], v[190:193], v[40:43]
	v_mfma_f32_16x16x32_bf16 v[32:35], v[132:135], v[198:201], v[32:35]
	v_mfma_f32_16x16x32_bf16 v[24:27], v[140:143], v[198:201], v[24:27]
	v_mfma_f32_16x16x32_bf16 v[16:19], v[132:135], v[206:209], v[16:19]
	v_mfma_f32_16x16x32_bf16 v[8:11], v[140:143], v[206:209], v[8:11]
	v_mfma_f32_16x16x32_bf16 v[52:55], v[162:165], v[178:181], v[52:55]
	v_mfma_f32_16x16x32_bf16 v[44:47], v[170:173], v[178:181], v[44:47]
	v_mfma_f32_16x16x32_bf16 v[36:39], v[162:165], v[186:189], v[36:39]
	v_mfma_f32_16x16x32_bf16 v[28:31], v[170:173], v[186:189], v[28:31]
	v_mfma_f32_16x16x32_bf16 v[20:23], v[162:165], v[194:197], v[20:23]
	v_mfma_f32_16x16x32_bf16 v[12:15], v[170:173], v[194:197], v[12:15]
	v_mfma_f32_16x16x32_bf16 v[4:7], v[162:165], v[202:205], v[4:7]
	v_mfma_f32_16x16x32_bf16 v[0:3], v[170:173], v[202:205], v[0:3]
	v_mfma_f32_16x16x32_bf16 v[52:55], v[166:169], v[182:185], v[52:55]
	v_mfma_f32_16x16x32_bf16 v[44:47], v[174:177], v[182:185], v[44:47]
	v_mfma_f32_16x16x32_bf16 v[36:39], v[166:169], v[190:193], v[36:39]
	v_mfma_f32_16x16x32_bf16 v[28:31], v[174:177], v[190:193], v[28:31]
	v_mfma_f32_16x16x32_bf16 v[20:23], v[166:169], v[198:201], v[20:23]
	v_mfma_f32_16x16x32_bf16 v[12:15], v[174:177], v[198:201], v[12:15]
	v_mfma_f32_16x16x32_bf16 v[4:7], v[166:169], v[206:209], v[4:7]
	v_mfma_f32_16x16x32_bf16 v[0:3], v[174:177], v[206:209], v[0:3]
	s_setprio 0
	s_barrier
	s_add_i32 s61, s61, 2
	s_add_u32 s26, s26, 0x100
	s_addc_u32 s27, s27, 0
	s_add_u32 s59, s59, 0x100
	s_addc_u32 s60, s60, 0
	s_cmp_gt_u32 s61, 29
	s_cbranch_scc0 .LBB0_1825

;     __host__ __device__ bool next(int i, Unit& u) const { const bool ok = StaticOrder::next(i, u); u.pm = 0; u.pn = 0; return ok; }
; #define PG8_STAGE(bufoff, gbase, voff) do { _Pragma("unroll") for (int _i = 0; _i < 2; ++_i) \
;         __builtin_amdgcn_global_load_lds((const unsigned*)((const char*)(gbase) + (voff)[_i]), (PG8_LAS unsigned*)(lds + (bufoff) + ldsw + _i * 8192), 16, 0, 0); } while (0)
; #define PG8_LDA(dst, b, h) do { _Pragma("unroll") for (int m = 0; m < 4; ++m) _Pragma("unroll") for (int k = 0; k < 2; ++k) dst[m][k] = *(const PG8_LAS bf16x8*)(lds + PG8_SA(b, h) + aoff + m * 2048 + k * 1024); } while (0)
; #define PG8_LDB(dst, b, h) do { _Pragma("unroll") for (int n = 0; n < 2; ++n) _Pragma("unroll") for (int k = 0; k < 2; ++k) dst[n][k] = *(const PG8_LAS bf16x8*)(lds + PG8_SB(b, h) + boff + n * 2048 + k * 1024); } while (0)
; #define PG8_WAIT_V(n) asm volatile("s_waitcnt vmcnt(" #n ")" ::: "memory")
; #define PG8_WAIT_L(n) asm volatile("s_waitcnt lgkmcnt(" #n ")" ::: "memory")
; #define PG8_BAR __builtin_amdgcn_s_barrier()
; #define PG8_SCHED __builtin_amdgcn_sched_barrier(0)
; template <class Epi, class Sched, bool ALIGN_EPI = false, bool SP2 = false>
; __device__ __forceinline__ void gemm_phase(PG8_LAS unsigned char* lds, const Gemm g, const Sched& S, const Epi& E, const int wave_in) {
;     ...
;         const bool has_next = S.next(ui + 1, nxt);
;         const char* nA = has_next ? (const char*)g.A + (size_t)nxt.pm * tstepA : cA; const char* nB = has_next ? (const char*)g.Bt + (size_t)nxt.pn * tstepB : cB;
;         for (int t = 0; t < nt; t += 2) {
;             const bool last = (t == nt - 2);
;             const char* a1 = cA + (size_t)(t + 1) * kstep;
;             const char* a2 = last ? nA : cA + (size_t)(t + 2) * kstep; const char* b2 = last ? nB : cB + (size_t)(t + 2) * kstep;
;             const char* a3 = a2 + kstep; const char* b3 = b2 + kstep;
;             if (last && has_next) S.a_ready(nxt);
;             if constexpr (SP2) {
;             PG8_LDB(B0, 0, 0); PG8_LDB(B1, 0, 1); PG8_SCHED; PG8_LDA(At, 0, 0); PG8_STAGE(PG8_SA(1, 1), a1 + hstepA, voffA);
;             PG8_WAIT_V(8); PG8_WAIT_L(0); PG8_BAR; PG8_MMA(0, 0, At, B0); PG8_MMA(0, 1, At, B1); PG8_BAR; PG8_SCHED;
;             PG8_LDA(At, 0, 1); PG8_STAGE(PG8_SB(0, 0), b2, voffB); PG8_STAGE(PG8_SB(0, 1), b2 + hstepB, voffB); PG8_STAGE(PG8_SA(0, 0), a2, voffA);
.LBB0_1950:
	s_ashr_i32 s41, s40, 31
	s_lshl_b64 s[42:43], s[40:41], 20
	s_add_u32 s42, s52, s42
	s_addc_u32 s43, s53, s43
	s_and_b64 s[44:45], s[10:11], exec
	s_cselect_b32 s1, s43, s47
	s_cselect_b32 s13, s42, s46
	s_ashr_i32 s39, s38, 31
	s_lshl_b64 s[44:45], s[38:39], 20
	s_add_u32 s44, s54, s44
	s_addc_u32 s45, s55, s45
	s_and_b64 s[50:51], s[10:11], exec
	s_cselect_b32 s39, s45, s49
	s_cselect_b32 s41, s44, s48
	s_add_u32 s46, s46, 0x80080
	s_addc_u32 s47, s47, 0
	s_add_u32 s72, s48, 0x100
	v_mov_b32_e32 v0, 0
	s_addc_u32 s73, s49, 0
	s_mov_b32 s74, -2
	s_waitcnt vmcnt(0)
	ds_read_b128 v[44:47], v189
	ds_read_b128 v[48:51], v189 offset:1024
	ds_read_b128 v[52:55], v189 offset:2048
	ds_read_b128 v[56:59], v189 offset:3072
	ds_read_b128 v[60:63], v197
	ds_read_b128 v[64:67], v197 offset:1024
	ds_read_b128 v[80:83], v197 offset:2048
	ds_read_b128 v[84:87], v197 offset:3072
	s_add_u32 s48, s46, 0xfff80080
	s_addc_u32 s49, s47, -1
	s_cmp_eq_u32 s74, 28
	s_cselect_b32 s51, s1, s49
	s_cselect_b32 s50, s13, s48
	s_cselect_b32 s49, s39, s73
	s_cselect_b32 s48, s41, s72
	v_lshl_add_u64 v[224:225], s[46:47], 0, v[206:207]
	s_add_i32 m0, s57, 0xc000
	ds_read_b128 v[88:91], v199
	ds_read_b128 v[92:95], v199 offset:1024
	ds_read_b128 v[96:99], v199 offset:2048
	ds_read_b128 v[100:103], v199 offset:3072
	ds_read_b128 v[176:179], v199 offset:4096
	ds_read_b128 v[212:215], v199 offset:5120
	ds_read_b128 v[216:219], v199 offset:6144
	ds_read_b128 v[220:223], v199 offset:7168
	global_load_lds_dwordx4 v[224:225], off
	v_lshl_add_u64 v[224:225], s[46:47], 0, v[208:209]
	s_add_i32 m0, s57, 0xe000
	s_nop 0
	global_load_lds_dwordx4 v[224:225], off
	s_waitcnt vmcnt(8)
	s_waitcnt lgkmcnt(0)
	s_barrier
	s_setprio 1
	s_waitcnt lgkmcnt(0)
	v_mfma_f32_16x16x32_bf16 v[172:175], v[44:47], v[88:91], 0
	v_mfma_f32_16x16x32_bf16 v[164:167], v[52:55], v[88:91], 0
	v_mfma_f32_16x16x32_bf16 v[156:159], v[44:47], v[96:99], 0
	v_mfma_f32_16x16x32_bf16 v[148:151], v[52:55], v[96:99], 0
	v_mfma_f32_16x16x32_bf16 v[140:143], v[44:47], v[176:179], 0
	v_mfma_f32_16x16x32_bf16 v[132:135], v[52:55], v[176:179], 0
	v_mfma_f32_16x16x32_bf16 v[124:127], v[44:47], v[216:219], 0
	v_mfma_f32_16x16x32_bf16 v[120:123], v[52:55], v[216:219], 0
	v_mfma_f32_16x16x32_bf16 v[172:175], v[48:51], v[92:95], v[172:175]
	v_mfma_f32_16x16x32_bf16 v[164:167], v[56:59], v[92:95], v[164:167]
	v_mfma_f32_16x16x32_bf16 v[156:159], v[48:51], v[100:103], v[156:159]
	v_mfma_f32_16x16x32_bf16 v[148:151], v[56:59], v[100:103], v[148:151]
	v_mfma_f32_16x16x32_bf16 v[140:143], v[48:51], v[212:215], v[140:143]
	v_mfma_f32_16x16x32_bf16 v[132:135], v[56:59], v[212:215], v[132:135]
	v_mfma_f32_16x16x32_bf16 v[124:127], v[48:51], v[220:223], v[124:127]
	v_mfma_f32_16x16x32_bf16 v[120:123], v[56:59], v[220:223], v[120:123]
	v_mfma_f32_16x16x32_bf16 v[168:171], v[60:63], v[88:91], 0
	v_mfma_f32_16x16x32_bf16 v[88:91], v[80:83], v[88:91], 0
	v_mfma_f32_16x16x32_bf16 v[168:171], v[64:67], v[92:95], v[168:171]
	v_mfma_f32_16x16x32_bf16 v[88:91], v[84:87], v[92:95], v[88:91]
	v_mfma_f32_16x16x32_bf16 v[92:95], v[60:63], v[96:99], 0
	v_mfma_f32_16x16x32_bf16 v[96:99], v[80:83], v[96:99], 0
	v_mfma_f32_16x16x32_bf16 v[128:131], v[80:83], v[176:179], 0
	v_mfma_f32_16x16x32_bf16 v[116:119], v[60:63], v[216:219], 0
	v_mfma_f32_16x16x32_bf16 v[112:115], v[80:83], v[216:219], 0
	v_mfma_f32_16x16x32_bf16 v[92:95], v[64:67], v[100:103], v[92:95]
	v_mfma_f32_16x16x32_bf16 v[96:99], v[84:87], v[100:103], v[96:99]
	v_mfma_f32_16x16x32_bf16 v[100:103], v[60:63], v[176:179], 0
	v_mfma_f32_16x16x32_bf16 v[128:131], v[84:87], v[212:215], v[128:131]
	v_mfma_f32_16x16x32_bf16 v[116:119], v[64:67], v[220:223], v[116:119]
	v_mfma_f32_16x16x32_bf16 v[112:115], v[84:87], v[220:223], v[112:115]
	v_mfma_f32_16x16x32_bf16 v[100:103], v[64:67], v[212:215], v[100:103]
	s_setprio 0
	s_barrier
	s_add_i32 s75, s68, s56
	v_lshl_add_u64 v[232:233], s[48:49], 0, v[182:183]
	s_mov_b32 m0, s75
	ds_read_b128 v[136:139], v199 offset:16384
	ds_read_b128 v[144:147], v199 offset:17408
	ds_read_b128 v[152:155], v199 offset:18432
	ds_read_b128 v[160:163], v199 offset:19456
	ds_read_b128 v[176:179], v199 offset:20480
	ds_read_b128 v[212:215], v199 offset:21504
	ds_read_b128 v[216:219], v199 offset:22528
	ds_read_b128 v[220:223], v199 offset:23552
	global_load_lds_dwordx4 v[232:233], off
	s_add_i32 m0, s75, 0x2000
	s_add_u32 s76, s48, 0x80000
	v_lshl_add_u64 v[234:235], s[48:49], 0, v[186:187]
	s_addc_u32 s77, s49, 0
	s_add_i32 s75, s69, s56
	global_load_lds_dwordx4 v[234:235], off
	v_lshl_add_u64 v[224:225], s[76:77], 0, v[182:183]
	s_mov_b32 m0, s75
	v_lshl_add_u64 v[236:237], s[50:51], 0, v[180:181]
	global_load_lds_dwordx4 v[224:225], off
	v_lshl_add_u64 v[224:225], s[76:77], 0, v[186:187]
	s_add_i32 m0, s75, 0x2000
	v_lshl_add_u64 v[238:239], s[50:51], 0, v[184:185]
	global_load_lds_dwordx4 v[224:225], off
	s_mov_b32 m0, s57
	s_nop 0
	global_load_lds_dwordx4 v[236:237], off
	s_mov_b32 m0, s58
	s_nop 0
	global_load_lds_dwordx4 v[238:239], off
	s_waitcnt vmcnt(8)
	s_waitcnt lgkmcnt(0)
	s_barrier
; #define PG8_STAGE(bufoff, gbase, voff) do { _Pragma("unroll") for (int _i = 0; _i < 2; ++_i) \
;         __builtin_amdgcn_global_load_lds((const unsigned*)((const char*)(gbase) + (voff)[_i]), (PG8_LAS unsigned*)(lds + (bufoff) + ldsw + _i * 8192), 16, 0, 0); } while (0)
; #define PG8_LDA(dst, b, h) do { _Pragma("unroll") for (int m = 0; m < 4; ++m) _Pragma("unroll") for (int k = 0; k < 2; ++k) dst[m][k] = *(const PG8_LAS bf16x8*)(lds + PG8_SA(b, h) + aoff + m * 2048 + k * 1024); } while (0)
; #define PG8_LDB(dst, b, h) do { _Pragma("unroll") for (int n = 0; n < 2; ++n) _Pragma("unroll") for (int k = 0; k < 2; ++k) dst[n][k] = *(const PG8_LAS bf16x8*)(lds + PG8_SB(b, h) + boff + n * 2048 + k * 1024); } while (0)
; #define PG8_MMA(ai, bj, At, Bt) do { __builtin_amdgcn_s_setprio(1); _Pragma("unroll") for (int m = 0; m < 4; ++m) _Pragma("unroll") for (int n = 0; n < 2; ++n) _Pragma("unroll") for (int k = 0; k < 2; ++k) \
;         acc[ai][bj][m][n] = __builtin_amdgcn_mfma_f32_16x16x32_bf16(Bt[n][k], At[m][k], acc[ai][bj][m][n], 0, 0, 0); __builtin_amdgcn_s_setprio(0); } while (0)
; #define PG8_WAIT_V(n) asm volatile("s_waitcnt vmcnt(" #n ")" ::: "memory")
; #define PG8_WAIT_L(n) asm volatile("s_waitcnt lgkmcnt(" #n ")" ::: "memory")
; #define PG8_BAR __builtin_amdgcn_s_barrier()
; #define PG8_SCHED __builtin_amdgcn_sched_barrier(0)
; template <class Epi, class Sched, bool ALIGN_EPI = false, bool SP2 = false>
; __device__ __forceinline__ void gemm_phase(PG8_LAS unsigned char* lds, const Gemm g, const Sched& S, const Epi& E, const int wave_in) {
;     ...
;             PG8_LDA(At, 0, 1); PG8_STAGE(PG8_SB(0, 0), b2, voffB); PG8_STAGE(PG8_SB(0, 1), b2 + hstepB, voffB); PG8_STAGE(PG8_SA(0, 0), a2, voffA);
;             PG8_WAIT_V(8); PG8_WAIT_L(0); PG8_BAR; PG8_MMA(1, 0, At, B0); PG8_MMA(1, 1, At, B1); PG8_BAR; PG8_SCHED;
;             PG8_LDB(B0, 1, 0); PG8_LDB(B1, 1, 1); PG8_SCHED; PG8_LDA(At, 1, 0); PG8_STAGE(PG8_SA(0, 1), a2 + hstepA, voffA);
;             PG8_WAIT_V(8); PG8_WAIT_L(0); PG8_BAR; PG8_MMA(0, 0, At, B0); PG8_MMA(0, 1, At, B1); PG8_BAR; PG8_SCHED;
	s_setprio 1
	s_waitcnt lgkmcnt(0)
	v_mfma_f32_16x16x32_bf16 v[108:111], v[44:47], v[136:139], 0
	v_mfma_f32_16x16x32_bf16 v[76:79], v[52:55], v[136:139], 0
	v_mfma_f32_16x16x32_bf16 v[68:71], v[44:47], v[152:155], 0
	v_mfma_f32_16x16x32_bf16 v[36:39], v[52:55], v[152:155], 0
	v_mfma_f32_16x16x32_bf16 v[28:31], v[44:47], v[176:179], 0
	v_mfma_f32_16x16x32_bf16 v[20:23], v[52:55], v[176:179], 0
	v_mfma_f32_16x16x32_bf16 v[12:15], v[44:47], v[216:219], 0
	v_mfma_f32_16x16x32_bf16 v[8:11], v[52:55], v[216:219], 0
	v_mfma_f32_16x16x32_bf16 v[108:111], v[48:51], v[144:147], v[108:111]
	v_mfma_f32_16x16x32_bf16 v[76:79], v[56:59], v[144:147], v[76:79]
	v_mfma_f32_16x16x32_bf16 v[68:71], v[48:51], v[160:163], v[68:71]
	v_mfma_f32_16x16x32_bf16 v[36:39], v[56:59], v[160:163], v[36:39]
	v_mfma_f32_16x16x32_bf16 v[28:31], v[48:51], v[212:215], v[28:31]
	v_mfma_f32_16x16x32_bf16 v[20:23], v[56:59], v[212:215], v[20:23]
	v_mfma_f32_16x16x32_bf16 v[12:15], v[48:51], v[220:223], v[12:15]
	v_mfma_f32_16x16x32_bf16 v[8:11], v[56:59], v[220:223], v[8:11]
	v_mfma_f32_16x16x32_bf16 v[40:43], v[60:63], v[152:155], 0
	v_mfma_f32_16x16x32_bf16 v[32:35], v[80:83], v[152:155], 0
	v_mfma_f32_16x16x32_bf16 v[24:27], v[60:63], v[176:179], 0
	v_mfma_f32_16x16x32_bf16 v[16:19], v[80:83], v[176:179], 0
	v_mfma_f32_16x16x32_bf16 v[4:7], v[60:63], v[216:219], 0
	v_mfma_f32_16x16x32_bf16 v[0:3], v[80:83], v[216:219], 0
	v_mfma_f32_16x16x32_bf16 v[44:47], v[60:63], v[136:139], 0
	v_mfma_f32_16x16x32_bf16 v[48:51], v[80:83], v[136:139], 0
	v_mfma_f32_16x16x32_bf16 v[40:43], v[64:67], v[160:163], v[40:43]
	v_mfma_f32_16x16x32_bf16 v[32:35], v[84:87], v[160:163], v[32:35]
	v_mfma_f32_16x16x32_bf16 v[24:27], v[64:67], v[212:215], v[24:27]
	v_mfma_f32_16x16x32_bf16 v[16:19], v[84:87], v[212:215], v[16:19]
	v_mfma_f32_16x16x32_bf16 v[4:7], v[64:67], v[220:223], v[4:7]
	v_mfma_f32_16x16x32_bf16 v[0:3], v[84:87], v[220:223], v[0:3]
	v_mfma_f32_16x16x32_bf16 v[44:47], v[64:67], v[144:147], v[44:47]
	v_mfma_f32_16x16x32_bf16 v[48:51], v[84:87], v[144:147], v[48:51]
	s_setprio 0
	s_barrier
	s_add_i32 s75, 0, 0x18000
	s_add_i32 s76, 0, 0x1c000
	v_add_u32_e32 v64, s75, v195
	v_add_u32_e32 v72, s76, v195
	ds_read_b128 v[52:55], v64
	ds_read_b128 v[56:59], v64 offset:1024
	ds_read_b128 v[60:63], v64 offset:2048
	ds_read_b128 v[64:67], v64 offset:3072
	ds_read_b128 v[80:83], v72
	ds_read_b128 v[84:87], v72 offset:1024
	ds_read_b128 v[176:179], v72 offset:2048
	ds_read_b128 v[212:215], v72 offset:3072
	s_add_u32 s50, s50, 0x80000
	s_addc_u32 s51, s51, 0
	s_mov_b32 m0, s59
	v_lshl_add_u64 v[152:153], s[50:51], 0, v[180:181]
	ds_read_b128 v[72:75], v199 offset:32768
	ds_read_b128 v[104:107], v199 offset:33792
	ds_read_b128 v[136:139], v199 offset:34816
	ds_read_b128 v[144:147], v199 offset:35840
	ds_read_b128 v[216:219], v199 offset:36864
	ds_read_b128 v[220:223], v199 offset:37888
	ds_read_b128 v[224:227], v199 offset:38912
	ds_read_b128 v[228:231], v199 offset:39936
	global_load_lds_dwordx4 v[152:153], off
	v_lshl_add_u64 v[152:153], s[50:51], 0, v[184:185]
	s_mov_b32 m0, s60
	s_nop 0
	global_load_lds_dwordx4 v[152:153], off
	s_waitcnt vmcnt(8)
	s_waitcnt lgkmcnt(0)
	s_barrier
	s_setprio 1
	s_waitcnt lgkmcnt(0)
	v_mfma_f32_16x16x32_bf16 v[152:155], v[52:55], v[72:75], v[172:175]
	v_mfma_f32_16x16x32_bf16 v[172:175], v[56:59], v[104:107], v[152:155]
	v_mfma_f32_16x16x32_bf16 v[152:155], v[60:63], v[72:75], v[164:167]
	v_mfma_f32_16x16x32_bf16 v[164:167], v[64:67], v[104:107], v[152:155]
	v_mfma_f32_16x16x32_bf16 v[152:155], v[52:55], v[136:139], v[156:159]
	v_mfma_f32_16x16x32_bf16 v[148:151], v[60:63], v[136:139], v[148:151]
	v_mfma_f32_16x16x32_bf16 v[140:143], v[52:55], v[216:219], v[140:143]
	v_mfma_f32_16x16x32_bf16 v[132:135], v[60:63], v[216:219], v[132:135]
	v_mfma_f32_16x16x32_bf16 v[124:127], v[52:55], v[224:227], v[124:127]
	v_mfma_f32_16x16x32_bf16 v[120:123], v[60:63], v[224:227], v[120:123]
	v_mfma_f32_16x16x32_bf16 v[156:159], v[56:59], v[144:147], v[152:155]
	v_mfma_f32_16x16x32_bf16 v[148:151], v[64:67], v[144:147], v[148:151]
	v_mfma_f32_16x16x32_bf16 v[140:143], v[56:59], v[220:223], v[140:143]
	v_mfma_f32_16x16x32_bf16 v[132:135], v[64:67], v[220:223], v[132:135]
	v_mfma_f32_16x16x32_bf16 v[124:127], v[56:59], v[228:231], v[124:127]
	v_mfma_f32_16x16x32_bf16 v[120:123], v[64:67], v[228:231], v[120:123]
	v_mfma_f32_16x16x32_bf16 v[152:155], v[80:83], v[72:75], v[168:171]
	v_mfma_f32_16x16x32_bf16 v[72:75], v[176:179], v[72:75], v[88:91]
	v_mfma_f32_16x16x32_bf16 v[160:163], v[212:215], v[104:107], v[72:75]
	v_mfma_f32_16x16x32_bf16 v[72:75], v[80:83], v[136:139], v[92:95]
	v_mfma_f32_16x16x32_bf16 v[168:171], v[84:87], v[104:107], v[152:155]
	v_mfma_f32_16x16x32_bf16 v[152:155], v[84:87], v[144:147], v[72:75]
	v_mfma_f32_16x16x32_bf16 v[72:75], v[176:179], v[136:139], v[96:99]
	v_mfma_f32_16x16x32_bf16 v[144:147], v[212:215], v[144:147], v[72:75]
	v_mfma_f32_16x16x32_bf16 v[72:75], v[80:83], v[216:219], v[100:103]
	v_mfma_f32_16x16x32_bf16 v[136:139], v[84:87], v[220:223], v[72:75]
	v_mfma_f32_16x16x32_bf16 v[72:75], v[176:179], v[216:219], v[128:131]
	v_mfma_f32_16x16x32_bf16 v[128:131], v[212:215], v[220:223], v[72:75]
	v_mfma_f32_16x16x32_bf16 v[72:75], v[80:83], v[224:227], v[116:119]
	v_mfma_f32_16x16x32_bf16 v[116:119], v[84:87], v[228:231], v[72:75]
	v_mfma_f32_16x16x32_bf16 v[72:75], v[176:179], v[224:227], v[112:115]
	v_mfma_f32_16x16x32_bf16 v[112:115], v[212:215], v[228:231], v[72:75]
	s_setprio 0
	s_barrier
; #define PG8_STAGE(bufoff, gbase, voff) do { _Pragma("unroll") for (int _i = 0; _i < 2; ++_i) \
;         __builtin_amdgcn_global_load_lds((const unsigned*)((const char*)(gbase) + (voff)[_i]), (PG8_LAS unsigned*)(lds + (bufoff) + ldsw + _i * 8192), 16, 0, 0); } while (0)
; #define PG8_LDA(dst, b, h) do { _Pragma("unroll") for (int m = 0; m < 4; ++m) _Pragma("unroll") for (int k = 0; k < 2; ++k) dst[m][k] = *(const PG8_LAS bf16x8*)(lds + PG8_SA(b, h) + aoff + m * 2048 + k * 1024); } while (0)
; #define PG8_MMA(ai, bj, At, Bt) do { __builtin_amdgcn_s_setprio(1); _Pragma("unroll") for (int m = 0; m < 4; ++m) _Pragma("unroll") for (int n = 0; n < 2; ++n) _Pragma("unroll") for (int k = 0; k < 2; ++k) \
;         acc[ai][bj][m][n] = __builtin_amdgcn_mfma_f32_16x16x32_bf16(Bt[n][k], At[m][k], acc[ai][bj][m][n], 0, 0, 0); __builtin_amdgcn_s_setprio(0); } while (0)
; #define PG8_WAIT_V(n) asm volatile("s_waitcnt vmcnt(" #n ")" ::: "memory")
; #define PG8_WAIT_L(n) asm volatile("s_waitcnt lgkmcnt(" #n ")" ::: "memory")
; #define PG8_BAR __builtin_amdgcn_s_barrier()
; #define PG8_SCHED __builtin_amdgcn_sched_barrier(0)
; template <class Epi, class Sched, bool ALIGN_EPI = false, bool SP2 = false>
; __device__ __forceinline__ void gemm_phase(PG8_LAS unsigned char* lds, const Gemm g, const Sched& S, const Epi& E, const int wave_in) {
;     ...
;         for (int t = 0; t < nt; t += 2) {
;     ...
;             PG8_LDA(At, 1, 1); PG8_STAGE(PG8_SB(1, 0), b3, voffB); PG8_STAGE(PG8_SB(1, 1), b3 + hstepB, voffB); PG8_STAGE(PG8_SA(1, 0), a3, voffA);
;             PG8_WAIT_V(8); PG8_WAIT_L(0); PG8_BAR; PG8_MMA(1, 0, At, B0); PG8_MMA(1, 1, At, B1); PG8_BAR; PG8_SCHED;
	s_add_i32 s50, s75, s56
	v_lshl_add_u64 v[104:105], v[232:233], 0, s[22:23]
	s_mov_b32 m0, s50
	s_nop 1
	ds_read_b128 v[72:75], v199 offset:49152
	ds_read_b128 v[88:91], v199 offset:50176
	ds_read_b128 v[92:95], v199 offset:51200
	ds_read_b128 v[96:99], v199 offset:52224
	ds_read_b128 v[100:103], v199 offset:53248
	ds_read_b128 v[216:219], v199 offset:54272
	ds_read_b128 v[220:223], v199 offset:55296
	ds_read_b128 v[224:227], v199 offset:56320
	global_load_lds_dwordx4 v[104:105], off
	s_add_i32 m0, s50, 0x2000
	s_add_u32 s48, s48, 0x80080
	v_lshl_add_u64 v[104:105], v[234:235], 0, s[22:23]
	s_addc_u32 s49, s49, 0
	s_add_i32 s50, s76, s56
	global_load_lds_dwordx4 v[104:105], off
	v_lshl_add_u64 v[104:105], s[48:49], 0, v[182:183]
	s_mov_b32 m0, s50
	s_nop 0
	global_load_lds_dwordx4 v[104:105], off
	v_lshl_add_u64 v[104:105], s[48:49], 0, v[186:187]
	s_add_i32 m0, s50, 0x2000
	s_nop 0
	global_load_lds_dwordx4 v[104:105], off
	v_lshl_add_u64 v[104:105], v[236:237], 0, s[22:23]
	s_mov_b32 m0, s63
	s_nop 0
	global_load_lds_dwordx4 v[104:105], off
	v_lshl_add_u64 v[104:105], v[238:239], 0, s[22:23]
	s_mov_b32 m0, s64
	s_nop 0
	global_load_lds_dwordx4 v[104:105], off
	s_waitcnt vmcnt(8)
	s_waitcnt lgkmcnt(0)
	s_barrier
	s_setprio 1
	s_waitcnt lgkmcnt(0)
	v_mfma_f32_16x16x32_bf16 v[104:107], v[52:55], v[72:75], v[108:111]
	v_mfma_f32_16x16x32_bf16 v[76:79], v[60:63], v[72:75], v[76:79]
	v_mfma_f32_16x16x32_bf16 v[68:71], v[52:55], v[92:95], v[68:71]
	v_mfma_f32_16x16x32_bf16 v[36:39], v[60:63], v[92:95], v[36:39]
	v_mfma_f32_16x16x32_bf16 v[28:31], v[52:55], v[100:103], v[28:31]
	v_mfma_f32_16x16x32_bf16 v[20:23], v[60:63], v[100:103], v[20:23]
	v_mfma_f32_16x16x32_bf16 v[12:15], v[52:55], v[220:223], v[12:15]
	v_mfma_f32_16x16x32_bf16 v[8:11], v[60:63], v[220:223], v[8:11]
	v_mfma_f32_16x16x32_bf16 v[108:111], v[56:59], v[88:91], v[104:107]
	v_mfma_f32_16x16x32_bf16 v[76:79], v[64:67], v[88:91], v[76:79]
	v_mfma_f32_16x16x32_bf16 v[68:71], v[56:59], v[96:99], v[68:71]
	v_mfma_f32_16x16x32_bf16 v[36:39], v[64:67], v[96:99], v[36:39]
	v_mfma_f32_16x16x32_bf16 v[28:31], v[56:59], v[216:219], v[28:31]
	v_mfma_f32_16x16x32_bf16 v[20:23], v[64:67], v[216:219], v[20:23]
	v_mfma_f32_16x16x32_bf16 v[12:15], v[56:59], v[224:227], v[12:15]
	v_mfma_f32_16x16x32_bf16 v[8:11], v[64:67], v[224:227], v[8:11]
	v_mfma_f32_16x16x32_bf16 v[44:47], v[80:83], v[72:75], v[44:47]
	v_mfma_f32_16x16x32_bf16 v[104:107], v[84:87], v[88:91], v[44:47]
	v_mfma_f32_16x16x32_bf16 v[44:47], v[176:179], v[72:75], v[48:51]
	v_mfma_f32_16x16x32_bf16 v[40:43], v[80:83], v[92:95], v[40:43]
	v_mfma_f32_16x16x32_bf16 v[32:35], v[176:179], v[92:95], v[32:35]
	v_mfma_f32_16x16x32_bf16 v[24:27], v[80:83], v[100:103], v[24:27]
	v_mfma_f32_16x16x32_bf16 v[16:19], v[176:179], v[100:103], v[16:19]
	v_mfma_f32_16x16x32_bf16 v[4:7], v[80:83], v[220:223], v[4:7]
	v_mfma_f32_16x16x32_bf16 v[0:3], v[176:179], v[220:223], v[0:3]
	v_mfma_f32_16x16x32_bf16 v[72:75], v[212:215], v[88:91], v[44:47]
	v_mfma_f32_16x16x32_bf16 v[40:43], v[84:87], v[96:99], v[40:43]
	v_mfma_f32_16x16x32_bf16 v[32:35], v[212:215], v[96:99], v[32:35]
	v_mfma_f32_16x16x32_bf16 v[24:27], v[84:87], v[216:219], v[24:27]
	v_mfma_f32_16x16x32_bf16 v[16:19], v[212:215], v[216:219], v[16:19]
	v_mfma_f32_16x16x32_bf16 v[4:7], v[84:87], v[224:227], v[4:7]
	v_mfma_f32_16x16x32_bf16 v[0:3], v[212:215], v[224:227], v[0:3]
	s_setprio 0
	s_barrier
	s_add_i32 s74, s74, 2
	s_add_u32 s46, s46, 0x100
	s_addc_u32 s47, s47, 0
	s_add_u32 s72, s72, 0x100
	s_addc_u32 s73, s73, 0
	s_cmp_gt_u32 s74, 29
	s_cbranch_scc0 .LBB0_1951
	s_branch .Lkx_22

;     __host__ __device__ bool next(int i, Unit& u) const { const bool ok = StaticOrder::next(i, u); u.pm = 0; u.pn = 0; return ok; }
; #define PG8_STAGE(bufoff, gbase, voff) do { _Pragma("unroll") for (int _i = 0; _i < 2; ++_i) \
;         __builtin_amdgcn_global_load_lds((const unsigned*)((const char*)(gbase) + (voff)[_i]), (PG8_LAS unsigned*)(lds + (bufoff) + ldsw + _i * 8192), 16, 0, 0); } while (0)
; #define PG8_LDA(dst, b, h) do { _Pragma("unroll") for (int m = 0; m < 4; ++m) _Pragma("unroll") for (int k = 0; k < 2; ++k) dst[m][k] = *(const PG8_LAS bf16x8*)(lds + PG8_SA(b, h) + aoff + m * 2048 + k * 1024); } while (0)
; #define PG8_LDB(dst, b, h) do { _Pragma("unroll") for (int n = 0; n < 2; ++n) _Pragma("unroll") for (int k = 0; k < 2; ++k) dst[n][k] = *(const PG8_LAS bf16x8*)(lds + PG8_SB(b, h) + boff + n * 2048 + k * 1024); } while (0)
; #define PG8_WAIT_V(n) asm volatile("s_waitcnt vmcnt(" #n ")" ::: "memory")
; #define PG8_WAIT_L(n) asm volatile("s_waitcnt lgkmcnt(" #n ")" ::: "memory")
; #define PG8_BAR __builtin_amdgcn_s_barrier()
; #define PG8_SCHED __builtin_amdgcn_sched_barrier(0)
; template <class Epi, class Sched, bool ALIGN_EPI = false, bool SP2 = false>
; __device__ __forceinline__ void gemm_phase(PG8_LAS unsigned char* lds, const Gemm g, const Sched& S, const Epi& E, const int wave_in) {
;     ...
;         const bool has_next = S.next(ui + 1, nxt);
;         const char* nA = has_next ? (const char*)g.A + (size_t)nxt.pm * tstepA : cA; const char* nB = has_next ? (const char*)g.Bt + (size_t)nxt.pn * tstepB : cB;
;         for (int t = 0; t < nt; t += 2) {
;             const bool last = (t == nt - 2);
;             const char* a1 = cA + (size_t)(t + 1) * kstep;
;             const char* a2 = last ? nA : cA + (size_t)(t + 2) * kstep; const char* b2 = last ? nB : cB + (size_t)(t + 2) * kstep;
;             const char* a3 = a2 + kstep; const char* b3 = b2 + kstep;
;             if (last && has_next) S.a_ready(nxt);
;             if constexpr (SP2) {
;             PG8_LDB(B0, 0, 0); PG8_LDB(B1, 0, 1); PG8_SCHED; PG8_LDA(At, 0, 0); PG8_STAGE(PG8_SA(1, 1), a1 + hstepA, voffA);
;             PG8_WAIT_V(8); PG8_WAIT_L(0); PG8_BAR; PG8_MMA(0, 0, At, B0); PG8_MMA(0, 1, At, B1); PG8_BAR; PG8_SCHED;
;             PG8_LDA(At, 0, 1); PG8_STAGE(PG8_SB(0, 0), b2, voffB); PG8_STAGE(PG8_SB(0, 1), b2 + hstepB, voffB); PG8_STAGE(PG8_SA(0, 0), a2, voffA);
.LBB0_2106:
	s_add_u32 s21, s24, 0x100
	v_mov_b32_e32 v0, 0
	s_addc_u32 s58, s25, 0
	s_mov_b32 s59, -2
	s_waitcnt vmcnt(0)
	ds_read_b128 v[128:131], v214
	ds_read_b128 v[132:135], v214 offset:1024
	ds_read_b128 v[136:139], v214 offset:2048
	ds_read_b128 v[140:143], v214 offset:3072
	ds_read_b128 v[162:165], v215
	ds_read_b128 v[166:169], v215 offset:1024
	ds_read_b128 v[170:173], v215 offset:2048
	ds_read_b128 v[174:177], v215 offset:3072
	s_add_u32 s24, s22, 0x100
	s_addc_u32 s25, s23, 0
	s_cmpk_eq_i32 s59, 0x52
	s_cselect_b32 s29, s5, s25
	s_cselect_b32 s28, s4, s24
	s_cselect_b32 s27, s19, s58
	s_cselect_b32 s26, s18, s21
	v_lshl_add_u64 v[210:211], s[22:23], 0, v[154:155]
	s_add_i32 m0, s39, 0xc000
	ds_read_b128 v[178:181], v216
	ds_read_b128 v[182:185], v216 offset:1024
	ds_read_b128 v[186:189], v216 offset:2048
	ds_read_b128 v[190:193], v216 offset:3072
	ds_read_b128 v[194:197], v216 offset:4096
	ds_read_b128 v[198:201], v216 offset:5120
	ds_read_b128 v[202:205], v216 offset:6144
	ds_read_b128 v[206:209], v216 offset:7168
	global_load_lds_dwordx4 v[210:211], off
	v_lshl_add_u64 v[210:211], s[22:23], 0, v[156:157]
	s_add_i32 m0, s39, 0xe000
	s_nop 0
	global_load_lds_dwordx4 v[210:211], off
	s_waitcnt vmcnt(8)
	s_waitcnt lgkmcnt(0)
	s_barrier
	s_setprio 1
	s_waitcnt lgkmcnt(0)
	v_mfma_f32_16x16x32_bf16 v[124:127], v[128:131], v[178:181], 0
	v_mfma_f32_16x16x32_bf16 v[120:123], v[136:139], v[178:181], 0
	v_mfma_f32_16x16x32_bf16 v[112:115], v[128:131], v[186:189], 0
	v_mfma_f32_16x16x32_bf16 v[104:107], v[136:139], v[186:189], 0
	v_mfma_f32_16x16x32_bf16 v[100:103], v[128:131], v[194:197], 0
	v_mfma_f32_16x16x32_bf16 v[96:99], v[136:139], v[194:197], 0
	v_mfma_f32_16x16x32_bf16 v[76:79], v[128:131], v[202:205], 0
	v_mfma_f32_16x16x32_bf16 v[72:75], v[136:139], v[202:205], 0
	v_mfma_f32_16x16x32_bf16 v[124:127], v[132:135], v[182:185], v[124:127]
	v_mfma_f32_16x16x32_bf16 v[120:123], v[140:143], v[182:185], v[120:123]
	v_mfma_f32_16x16x32_bf16 v[112:115], v[132:135], v[190:193], v[112:115]
	v_mfma_f32_16x16x32_bf16 v[104:107], v[140:143], v[190:193], v[104:107]
	v_mfma_f32_16x16x32_bf16 v[100:103], v[132:135], v[198:201], v[100:103]
	v_mfma_f32_16x16x32_bf16 v[96:99], v[140:143], v[198:201], v[96:99]
	v_mfma_f32_16x16x32_bf16 v[76:79], v[132:135], v[206:209], v[76:79]
	v_mfma_f32_16x16x32_bf16 v[72:75], v[140:143], v[206:209], v[72:75]
	v_mfma_f32_16x16x32_bf16 v[116:119], v[162:165], v[178:181], 0
	v_mfma_f32_16x16x32_bf16 v[108:111], v[170:173], v[178:181], 0
	v_mfma_f32_16x16x32_bf16 v[92:95], v[162:165], v[186:189], 0
	v_mfma_f32_16x16x32_bf16 v[88:91], v[170:173], v[186:189], 0
	v_mfma_f32_16x16x32_bf16 v[84:87], v[162:165], v[194:197], 0
	v_mfma_f32_16x16x32_bf16 v[80:83], v[170:173], v[194:197], 0
	v_mfma_f32_16x16x32_bf16 v[68:71], v[162:165], v[202:205], 0
	v_mfma_f32_16x16x32_bf16 v[64:67], v[170:173], v[202:205], 0
	v_mfma_f32_16x16x32_bf16 v[116:119], v[166:169], v[182:185], v[116:119]
	v_mfma_f32_16x16x32_bf16 v[108:111], v[174:177], v[182:185], v[108:111]
	v_mfma_f32_16x16x32_bf16 v[92:95], v[166:169], v[190:193], v[92:95]
	v_mfma_f32_16x16x32_bf16 v[88:91], v[174:177], v[190:193], v[88:91]
	v_mfma_f32_16x16x32_bf16 v[84:87], v[166:169], v[198:201], v[84:87]
	v_mfma_f32_16x16x32_bf16 v[80:83], v[174:177], v[198:201], v[80:83]
	v_mfma_f32_16x16x32_bf16 v[68:71], v[166:169], v[206:209], v[68:71]
	v_mfma_f32_16x16x32_bf16 v[64:67], v[174:177], v[206:209], v[64:67]
	s_setprio 0
	s_barrier
	s_add_i32 s22, s49, s36
	v_lshl_add_u64 v[210:211], s[26:27], 0, v[148:149]
	s_mov_b32 m0, s22
	ds_read_b128 v[178:181], v216 offset:16384
	ds_read_b128 v[182:185], v216 offset:17408
	ds_read_b128 v[186:189], v216 offset:18432
	ds_read_b128 v[190:193], v216 offset:19456
	ds_read_b128 v[194:197], v216 offset:20480
	ds_read_b128 v[198:201], v216 offset:21504
	ds_read_b128 v[202:205], v216 offset:22528
	ds_read_b128 v[206:209], v216 offset:23552
	global_load_lds_dwordx4 v[210:211], off
	s_add_i32 m0, s22, 0x2000
	s_add_u32 s22, s26, 0x158000
	v_lshl_add_u64 v[218:219], s[26:27], 0, v[144:145]
	s_addc_u32 s23, s27, 0
	s_add_i32 s60, s50, s36
	global_load_lds_dwordx4 v[218:219], off
	v_lshl_add_u64 v[220:221], s[22:23], 0, v[148:149]
	s_mov_b32 m0, s60
	v_lshl_add_u64 v[222:223], s[28:29], 0, v[146:147]
	global_load_lds_dwordx4 v[220:221], off
	v_lshl_add_u64 v[220:221], s[22:23], 0, v[144:145]
	s_add_i32 m0, s60, 0x2000
	s_nop 0
	global_load_lds_dwordx4 v[220:221], off
	v_lshl_add_u64 v[220:221], s[28:29], 0, v[150:151]
	s_mov_b32 m0, s39
	s_nop 0
	global_load_lds_dwordx4 v[220:221], off
	s_mov_b32 m0, s40
	s_nop 0
	global_load_lds_dwordx4 v[222:223], off
	s_waitcnt vmcnt(8)
	s_waitcnt lgkmcnt(0)
	s_barrier
; #define PG8_STAGE(bufoff, gbase, voff) do { _Pragma("unroll") for (int _i = 0; _i < 2; ++_i) \
;         __builtin_amdgcn_global_load_lds((const unsigned*)((const char*)(gbase) + (voff)[_i]), (PG8_LAS unsigned*)(lds + (bufoff) + ldsw + _i * 8192), 16, 0, 0); } while (0)
; #define PG8_LDA(dst, b, h) do { _Pragma("unroll") for (int m = 0; m < 4; ++m) _Pragma("unroll") for (int k = 0; k < 2; ++k) dst[m][k] = *(const PG8_LAS bf16x8*)(lds + PG8_SA(b, h) + aoff + m * 2048 + k * 1024); } while (0)
; #define PG8_LDB(dst, b, h) do { _Pragma("unroll") for (int n = 0; n < 2; ++n) _Pragma("unroll") for (int k = 0; k < 2; ++k) dst[n][k] = *(const PG8_LAS bf16x8*)(lds + PG8_SB(b, h) + boff + n * 2048 + k * 1024); } while (0)
; #define PG8_MMA(ai, bj, At, Bt) do { __builtin_amdgcn_s_setprio(1); _Pragma("unroll") for (int m = 0; m < 4; ++m) _Pragma("unroll") for (int n = 0; n < 2; ++n) _Pragma("unroll") for (int k = 0; k < 2; ++k) \
;         acc[ai][bj][m][n] = __builtin_amdgcn_mfma_f32_16x16x32_bf16(Bt[n][k], At[m][k], acc[ai][bj][m][n], 0, 0, 0); __builtin_amdgcn_s_setprio(0); } while (0)
; #define PG8_WAIT_V(n) asm volatile("s_waitcnt vmcnt(" #n ")" ::: "memory")
; #define PG8_WAIT_L(n) asm volatile("s_waitcnt lgkmcnt(" #n ")" ::: "memory")
; #define PG8_BAR __builtin_amdgcn_s_barrier()
; #define PG8_SCHED __builtin_amdgcn_sched_barrier(0)
; template <class Epi, class Sched, bool ALIGN_EPI = false, bool SP2 = false>
; __device__ __forceinline__ void gemm_phase(PG8_LAS unsigned char* lds, const Gemm g, const Sched& S, const Epi& E, const int wave_in) {
;     ...
;             PG8_LDA(At, 0, 1); PG8_STAGE(PG8_SB(0, 0), b2, voffB); PG8_STAGE(PG8_SB(0, 1), b2 + hstepB, voffB); PG8_STAGE(PG8_SA(0, 0), a2, voffA);
;             PG8_WAIT_V(8); PG8_WAIT_L(0); PG8_BAR; PG8_MMA(1, 0, At, B0); PG8_MMA(1, 1, At, B1); PG8_BAR; PG8_SCHED;
;             PG8_LDB(B0, 1, 0); PG8_LDB(B1, 1, 1); PG8_SCHED; PG8_LDA(At, 1, 0); PG8_STAGE(PG8_SA(0, 1), a2 + hstepA, voffA);
;             PG8_WAIT_V(8); PG8_WAIT_L(0); PG8_BAR; PG8_MMA(0, 0, At, B0); PG8_MMA(0, 1, At, B1); PG8_BAR; PG8_SCHED;
	s_setprio 1
	s_waitcnt lgkmcnt(0)
	v_mfma_f32_16x16x32_bf16 v[60:63], v[128:131], v[178:181], 0
	v_mfma_f32_16x16x32_bf16 v[56:59], v[136:139], v[178:181], 0
	v_mfma_f32_16x16x32_bf16 v[48:51], v[128:131], v[186:189], 0
	v_mfma_f32_16x16x32_bf16 v[40:43], v[136:139], v[186:189], 0
	v_mfma_f32_16x16x32_bf16 v[32:35], v[128:131], v[194:197], 0
	v_mfma_f32_16x16x32_bf16 v[24:27], v[136:139], v[194:197], 0
	v_mfma_f32_16x16x32_bf16 v[16:19], v[128:131], v[202:205], 0
	v_mfma_f32_16x16x32_bf16 v[8:11], v[136:139], v[202:205], 0
	v_mfma_f32_16x16x32_bf16 v[60:63], v[132:135], v[182:185], v[60:63]
	v_mfma_f32_16x16x32_bf16 v[56:59], v[140:143], v[182:185], v[56:59]
	v_mfma_f32_16x16x32_bf16 v[48:51], v[132:135], v[190:193], v[48:51]
	v_mfma_f32_16x16x32_bf16 v[40:43], v[140:143], v[190:193], v[40:43]
	v_mfma_f32_16x16x32_bf16 v[32:35], v[132:135], v[198:201], v[32:35]
	v_mfma_f32_16x16x32_bf16 v[24:27], v[140:143], v[198:201], v[24:27]
	v_mfma_f32_16x16x32_bf16 v[16:19], v[132:135], v[206:209], v[16:19]
	v_mfma_f32_16x16x32_bf16 v[8:11], v[140:143], v[206:209], v[8:11]
	v_mfma_f32_16x16x32_bf16 v[52:55], v[162:165], v[178:181], 0
	v_mfma_f32_16x16x32_bf16 v[44:47], v[170:173], v[178:181], 0
	v_mfma_f32_16x16x32_bf16 v[36:39], v[162:165], v[186:189], 0
	v_mfma_f32_16x16x32_bf16 v[28:31], v[170:173], v[186:189], 0
	v_mfma_f32_16x16x32_bf16 v[20:23], v[162:165], v[194:197], 0
	v_mfma_f32_16x16x32_bf16 v[12:15], v[170:173], v[194:197], 0
	v_mfma_f32_16x16x32_bf16 v[4:7], v[162:165], v[202:205], 0
	v_mfma_f32_16x16x32_bf16 v[0:3], v[170:173], v[202:205], 0
	v_mfma_f32_16x16x32_bf16 v[52:55], v[166:169], v[182:185], v[52:55]
	v_mfma_f32_16x16x32_bf16 v[44:47], v[174:177], v[182:185], v[44:47]
	v_mfma_f32_16x16x32_bf16 v[36:39], v[166:169], v[190:193], v[36:39]
	v_mfma_f32_16x16x32_bf16 v[28:31], v[174:177], v[190:193], v[28:31]
	v_mfma_f32_16x16x32_bf16 v[20:23], v[166:169], v[198:201], v[20:23]
	v_mfma_f32_16x16x32_bf16 v[12:15], v[174:177], v[198:201], v[12:15]
	v_mfma_f32_16x16x32_bf16 v[4:7], v[166:169], v[206:209], v[4:7]
	v_mfma_f32_16x16x32_bf16 v[0:3], v[174:177], v[206:209], v[0:3]
	s_setprio 0
	s_barrier
	s_add_i32 s60, 0, 0x18000
	s_add_i32 s61, 0, 0x1c000
	v_add_u32_e32 v140, s60, v212
	v_add_u32_e32 v174, s61, v212
	ds_read_b128 v[128:131], v140
	ds_read_b128 v[132:135], v140 offset:1024
	ds_read_b128 v[136:139], v140 offset:2048
	ds_read_b128 v[140:143], v140 offset:3072
	ds_read_b128 v[162:165], v174
	ds_read_b128 v[166:169], v174 offset:1024
	ds_read_b128 v[170:173], v174 offset:2048
	ds_read_b128 v[174:177], v174 offset:3072
	s_add_u32 s22, s28, 0x158000
	s_addc_u32 s23, s29, 0
	s_mov_b32 m0, s41
	v_lshl_add_u64 v[224:225], s[22:23], 0, v[150:151]
	ds_read_b128 v[178:181], v216 offset:32768
	ds_read_b128 v[182:185], v216 offset:33792
	ds_read_b128 v[186:189], v216 offset:34816
	ds_read_b128 v[190:193], v216 offset:35840
	ds_read_b128 v[194:197], v216 offset:36864
	ds_read_b128 v[198:201], v216 offset:37888
	ds_read_b128 v[202:205], v216 offset:38912
	ds_read_b128 v[206:209], v216 offset:39936
	global_load_lds_dwordx4 v[224:225], off
	v_lshl_add_u64 v[224:225], s[22:23], 0, v[146:147]
	s_mov_b32 m0, s42
	s_nop 0
	global_load_lds_dwordx4 v[224:225], off
	s_waitcnt vmcnt(8)
	s_waitcnt lgkmcnt(0)
	s_barrier
	s_setprio 1
	s_waitcnt lgkmcnt(0)
	v_mfma_f32_16x16x32_bf16 v[124:127], v[128:131], v[178:181], v[124:127]
	v_mfma_f32_16x16x32_bf16 v[120:123], v[136:139], v[178:181], v[120:123]
	v_mfma_f32_16x16x32_bf16 v[112:115], v[128:131], v[186:189], v[112:115]
	v_mfma_f32_16x16x32_bf16 v[104:107], v[136:139], v[186:189], v[104:107]
	v_mfma_f32_16x16x32_bf16 v[100:103], v[128:131], v[194:197], v[100:103]
	v_mfma_f32_16x16x32_bf16 v[96:99], v[136:139], v[194:197], v[96:99]
	v_mfma_f32_16x16x32_bf16 v[76:79], v[128:131], v[202:205], v[76:79]
	v_mfma_f32_16x16x32_bf16 v[72:75], v[136:139], v[202:205], v[72:75]
	v_mfma_f32_16x16x32_bf16 v[124:127], v[132:135], v[182:185], v[124:127]
	v_mfma_f32_16x16x32_bf16 v[120:123], v[140:143], v[182:185], v[120:123]
	v_mfma_f32_16x16x32_bf16 v[112:115], v[132:135], v[190:193], v[112:115]
	v_mfma_f32_16x16x32_bf16 v[104:107], v[140:143], v[190:193], v[104:107]
	v_mfma_f32_16x16x32_bf16 v[100:103], v[132:135], v[198:201], v[100:103]
	v_mfma_f32_16x16x32_bf16 v[96:99], v[140:143], v[198:201], v[96:99]
	v_mfma_f32_16x16x32_bf16 v[76:79], v[132:135], v[206:209], v[76:79]
	v_mfma_f32_16x16x32_bf16 v[72:75], v[140:143], v[206:209], v[72:75]
	v_mfma_f32_16x16x32_bf16 v[116:119], v[162:165], v[178:181], v[116:119]
	v_mfma_f32_16x16x32_bf16 v[108:111], v[170:173], v[178:181], v[108:111]
	v_mfma_f32_16x16x32_bf16 v[92:95], v[162:165], v[186:189], v[92:95]
	v_mfma_f32_16x16x32_bf16 v[88:91], v[170:173], v[186:189], v[88:91]
	v_mfma_f32_16x16x32_bf16 v[84:87], v[162:165], v[194:197], v[84:87]
	v_mfma_f32_16x16x32_bf16 v[80:83], v[170:173], v[194:197], v[80:83]
	v_mfma_f32_16x16x32_bf16 v[68:71], v[162:165], v[202:205], v[68:71]
	v_mfma_f32_16x16x32_bf16 v[64:67], v[170:173], v[202:205], v[64:67]
	v_mfma_f32_16x16x32_bf16 v[116:119], v[166:169], v[182:185], v[116:119]
	v_mfma_f32_16x16x32_bf16 v[108:111], v[174:177], v[182:185], v[108:111]
	v_mfma_f32_16x16x32_bf16 v[92:95], v[166:169], v[190:193], v[92:95]
	v_mfma_f32_16x16x32_bf16 v[88:91], v[174:177], v[190:193], v[88:91]
	v_mfma_f32_16x16x32_bf16 v[84:87], v[166:169], v[198:201], v[84:87]
	v_mfma_f32_16x16x32_bf16 v[80:83], v[174:177], v[198:201], v[80:83]
	v_mfma_f32_16x16x32_bf16 v[68:71], v[166:169], v[206:209], v[68:71]
	v_mfma_f32_16x16x32_bf16 v[64:67], v[174:177], v[206:209], v[64:67]
	s_setprio 0
	s_barrier
; #define PG8_STAGE(bufoff, gbase, voff) do { _Pragma("unroll") for (int _i = 0; _i < 2; ++_i) \
;         __builtin_amdgcn_global_load_lds((const unsigned*)((const char*)(gbase) + (voff)[_i]), (PG8_LAS unsigned*)(lds + (bufoff) + ldsw + _i * 8192), 16, 0, 0); } while (0)
; #define PG8_LDA(dst, b, h) do { _Pragma("unroll") for (int m = 0; m < 4; ++m) _Pragma("unroll") for (int k = 0; k < 2; ++k) dst[m][k] = *(const PG8_LAS bf16x8*)(lds + PG8_SA(b, h) + aoff + m * 2048 + k * 1024); } while (0)
; #define PG8_LDB(dst, b, h) do { _Pragma("unroll") for (int n = 0; n < 2; ++n) _Pragma("unroll") for (int k = 0; k < 2; ++k) dst[n][k] = *(const PG8_LAS bf16x8*)(lds + PG8_SB(b, h) + boff + n * 2048 + k * 1024); } while (0)
; #define PG8_MMA(ai, bj, At, Bt) do { __builtin_amdgcn_s_setprio(1); _Pragma("unroll") for (int m = 0; m < 4; ++m) _Pragma("unroll") for (int n = 0; n < 2; ++n) _Pragma("unroll") for (int k = 0; k < 2; ++k) \
;         acc[ai][bj][m][n] = __builtin_amdgcn_mfma_f32_16x16x32_bf16(Bt[n][k], At[m][k], acc[ai][bj][m][n], 0, 0, 0); __builtin_amdgcn_s_setprio(0); } while (0)
; #define PG8_WAIT_V(n) asm volatile("s_waitcnt vmcnt(" #n ")" ::: "memory")
; #define PG8_WAIT_L(n) asm volatile("s_waitcnt lgkmcnt(" #n ")" ::: "memory")
; #define PG8_BAR __builtin_amdgcn_s_barrier()
; #define PG8_SCHED __builtin_amdgcn_sched_barrier(0)
; template <class Epi, class Sched, bool ALIGN_EPI = false, bool SP2 = false>
; __device__ __forceinline__ void gemm_phase(PG8_LAS unsigned char* lds, const Gemm g, const Sched& S, const Epi& E, const int wave_in) {
;     ...
;         for (int t = 0; t < nt; t += 2) {
;     ...
;             PG8_LDB(B0, 0, 0); PG8_LDB(B1, 0, 1); PG8_SCHED; PG8_LDA(At, 0, 0); PG8_STAGE(PG8_SA(1, 1), a1 + hstepA, voffA);
;             PG8_WAIT_V(8); PG8_WAIT_L(0); PG8_BAR; PG8_MMA(0, 0, At, B0); PG8_MMA(0, 1, At, B1); PG8_BAR; PG8_SCHED;
;     ...
;             PG8_LDA(At, 1, 1); PG8_STAGE(PG8_SB(1, 0), b3, voffB); PG8_STAGE(PG8_SB(1, 1), b3 + hstepB, voffB); PG8_STAGE(PG8_SA(1, 0), a3, voffA);
;             PG8_WAIT_V(8); PG8_WAIT_L(0); PG8_BAR; PG8_MMA(1, 0, At, B0); PG8_MMA(1, 1, At, B1); PG8_BAR; PG8_SCHED;
	s_add_i32 s22, s60, s36
	v_lshl_add_u64 v[210:211], v[210:211], 0, s[6:7]
	s_mov_b32 m0, s22
	ds_read_b128 v[178:181], v216 offset:49152
	ds_read_b128 v[182:185], v216 offset:50176
	ds_read_b128 v[186:189], v216 offset:51200
	ds_read_b128 v[190:193], v216 offset:52224
	ds_read_b128 v[194:197], v216 offset:53248
	ds_read_b128 v[198:201], v216 offset:54272
	ds_read_b128 v[202:205], v216 offset:55296
	ds_read_b128 v[206:209], v216 offset:56320
	global_load_lds_dwordx4 v[210:211], off
	s_add_i32 m0, s22, 0x2000
	s_add_u32 s22, s26, 0x158080
	v_lshl_add_u64 v[210:211], v[218:219], 0, s[6:7]
	s_addc_u32 s23, s27, 0
	s_add_i32 s26, s61, s36
	global_load_lds_dwordx4 v[210:211], off
	v_lshl_add_u64 v[210:211], s[22:23], 0, v[148:149]
	s_mov_b32 m0, s26
	s_nop 0
	global_load_lds_dwordx4 v[210:211], off
	v_lshl_add_u64 v[210:211], s[22:23], 0, v[144:145]
	s_add_i32 m0, s26, 0x2000
	s_nop 0
	global_load_lds_dwordx4 v[210:211], off
	v_lshl_add_u64 v[210:211], v[220:221], 0, s[6:7]
	s_mov_b32 m0, s46
	s_nop 0
	global_load_lds_dwordx4 v[210:211], off
	v_lshl_add_u64 v[210:211], v[222:223], 0, s[6:7]
	s_mov_b32 m0, s47
	s_nop 0
	global_load_lds_dwordx4 v[210:211], off
	s_waitcnt vmcnt(8)
	s_waitcnt lgkmcnt(0)
	s_barrier
	s_setprio 1
	s_waitcnt lgkmcnt(0)
	v_mfma_f32_16x16x32_bf16 v[60:63], v[128:131], v[178:181], v[60:63]
	v_mfma_f32_16x16x32_bf16 v[56:59], v[136:139], v[178:181], v[56:59]
	v_mfma_f32_16x16x32_bf16 v[48:51], v[128:131], v[186:189], v[48:51]
	v_mfma_f32_16x16x32_bf16 v[40:43], v[136:139], v[186:189], v[40:43]
	v_mfma_f32_16x16x32_bf16 v[32:35], v[128:131], v[194:197], v[32:35]
	v_mfma_f32_16x16x32_bf16 v[24:27], v[136:139], v[194:197], v[24:27]
	v_mfma_f32_16x16x32_bf16 v[16:19], v[128:131], v[202:205], v[16:19]
	v_mfma_f32_16x16x32_bf16 v[8:11], v[136:139], v[202:205], v[8:11]
	v_mfma_f32_16x16x32_bf16 v[60:63], v[132:135], v[182:185], v[60:63]
	v_mfma_f32_16x16x32_bf16 v[56:59], v[140:143], v[182:185], v[56:59]
	v_mfma_f32_16x16x32_bf16 v[48:51], v[132:135], v[190:193], v[48:51]
	v_mfma_f32_16x16x32_bf16 v[40:43], v[140:143], v[190:193], v[40:43]
	v_mfma_f32_16x16x32_bf16 v[32:35], v[132:135], v[198:201], v[32:35]
	v_mfma_f32_16x16x32_bf16 v[24:27], v[140:143], v[198:201], v[24:27]
	v_mfma_f32_16x16x32_bf16 v[16:19], v[132:135], v[206:209], v[16:19]
	v_mfma_f32_16x16x32_bf16 v[8:11], v[140:143], v[206:209], v[8:11]
	v_mfma_f32_16x16x32_bf16 v[52:55], v[162:165], v[178:181], v[52:55]
	v_mfma_f32_16x16x32_bf16 v[44:47], v[170:173], v[178:181], v[44:47]
	v_mfma_f32_16x16x32_bf16 v[36:39], v[162:165], v[186:189], v[36:39]
	v_mfma_f32_16x16x32_bf16 v[28:31], v[170:173], v[186:189], v[28:31]
	v_mfma_f32_16x16x32_bf16 v[20:23], v[162:165], v[194:197], v[20:23]
	v_mfma_f32_16x16x32_bf16 v[12:15], v[170:173], v[194:197], v[12:15]
	v_mfma_f32_16x16x32_bf16 v[4:7], v[162:165], v[202:205], v[4:7]
	v_mfma_f32_16x16x32_bf16 v[0:3], v[170:173], v[202:205], v[0:3]
	v_mfma_f32_16x16x32_bf16 v[52:55], v[166:169], v[182:185], v[52:55]
	v_mfma_f32_16x16x32_bf16 v[44:47], v[174:177], v[182:185], v[44:47]
	v_mfma_f32_16x16x32_bf16 v[36:39], v[166:169], v[190:193], v[36:39]
	v_mfma_f32_16x16x32_bf16 v[28:31], v[174:177], v[190:193], v[28:31]
	v_mfma_f32_16x16x32_bf16 v[20:23], v[166:169], v[198:201], v[20:23]
	v_mfma_f32_16x16x32_bf16 v[12:15], v[174:177], v[198:201], v[12:15]
	v_mfma_f32_16x16x32_bf16 v[4:7], v[166:169], v[206:209], v[4:7]
	v_mfma_f32_16x16x32_bf16 v[0:3], v[174:177], v[206:209], v[0:3]
	s_setprio 0
	s_barrier
	s_add_i32 s59, s59, 2
	s_add_u32 s21, s21, 0x100
	s_addc_u32 s58, s58, 0
	s_cmpk_gt_u32 s59, 0x53
	s_mov_b64 s[22:23], s[24:25]
	s_cbranch_scc0 .LBB0_2107
	s_branch .Lkx_24
.LBB0_2107:
	ds_read_b128 v[128:131], v214
	ds_read_b128 v[132:135], v214 offset:1024
	ds_read_b128 v[136:139], v214 offset:2048
	ds_read_b128 v[140:143], v214 offset:3072
	ds_read_b128 v[162:165], v215
	ds_read_b128 v[166:169], v215 offset:1024
	ds_read_b128 v[170:173], v215 offset:2048
	ds_read_b128 v[174:177], v215 offset:3072
	s_add_u32 s24, s22, 0x100
	s_addc_u32 s25, s23, 0
	s_cmpk_eq_i32 s59, 0x52
	s_cselect_b32 s29, s5, s25
	s_cselect_b32 s28, s4, s24
	s_cselect_b32 s27, s19, s58
	s_cselect_b32 s26, s18, s21
	v_lshl_add_u64 v[210:211], s[22:23], 0, v[154:155]
	s_add_i32 m0, s39, 0xc000
	ds_read_b128 v[178:181], v216
	ds_read_b128 v[182:185], v216 offset:1024
	ds_read_b128 v[186:189], v216 offset:2048
	ds_read_b128 v[190:193], v216 offset:3072
	ds_read_b128 v[194:197], v216 offset:4096
	ds_read_b128 v[198:201], v216 offset:5120
	ds_read_b128 v[202:205], v216 offset:6144
	ds_read_b128 v[206:209], v216 offset:7168
	global_load_lds_dwordx4 v[210:211], off
	v_lshl_add_u64 v[210:211], s[22:23], 0, v[156:157]
	s_add_i32 m0, s39, 0xe000
	s_nop 0
	global_load_lds_dwordx4 v[210:211], off
	s_waitcnt vmcnt(8)
	s_waitcnt lgkmcnt(0)
	s_barrier
; #define PG8_STAGE(bufoff, gbase, voff) do { _Pragma("unroll") for (int _i = 0; _i < 2; ++_i) \
;         __builtin_amdgcn_global_load_lds((const unsigned*)((const char*)(gbase) + (voff)[_i]), (PG8_LAS unsigned*)(lds + (bufoff) + ldsw + _i * 8192), 16, 0, 0); } while (0)
; #define PG8_LDA(dst, b, h) do { _Pragma("unroll") for (int m = 0; m < 4; ++m) _Pragma("unroll") for (int k = 0; k < 2; ++k) dst[m][k] = *(const PG8_LAS bf16x8*)(lds + PG8_SA(b, h) + aoff + m * 2048 + k * 1024); } while (0)
; #define PG8_MMA(ai, bj, At, Bt) do { __builtin_amdgcn_s_setprio(1); _Pragma("unroll") for (int m = 0; m < 4; ++m) _Pragma("unroll") for (int n = 0; n < 2; ++n) _Pragma("unroll") for (int k = 0; k < 2; ++k) \
;         acc[ai][bj][m][n] = __builtin_amdgcn_mfma_f32_16x16x32_bf16(Bt[n][k], At[m][k], acc[ai][bj][m][n], 0, 0, 0); __builtin_amdgcn_s_setprio(0); } while (0)
; #define PG8_WAIT_V(n) asm volatile("s_waitcnt vmcnt(" #n ")" ::: "memory")
; #define PG8_WAIT_L(n) asm volatile("s_waitcnt lgkmcnt(" #n ")" ::: "memory")
; #define PG8_BAR __builtin_amdgcn_s_barrier()
; #define PG8_SCHED __builtin_amdgcn_sched_barrier(0)
; template <class Epi, class Sched, bool ALIGN_EPI = false, bool SP2 = false>
; __device__ __forceinline__ void gemm_phase(PG8_LAS unsigned char* lds, const Gemm g, const Sched& S, const Epi& E, const int wave_in) {
;     ...
;             PG8_WAIT_V(8); PG8_WAIT_L(0); PG8_BAR; PG8_MMA(0, 0, At, B0); PG8_MMA(0, 1, At, B1); PG8_BAR; PG8_SCHED;
;             PG8_LDA(At, 0, 1); PG8_STAGE(PG8_SB(0, 0), b2, voffB); PG8_STAGE(PG8_SB(0, 1), b2 + hstepB, voffB); PG8_STAGE(PG8_SA(0, 0), a2, voffA);
;             PG8_WAIT_V(8); PG8_WAIT_L(0); PG8_BAR; PG8_MMA(1, 0, At, B0); PG8_MMA(1, 1, At, B1); PG8_BAR; PG8_SCHED;
	s_setprio 1
	s_waitcnt lgkmcnt(0)
	v_mfma_f32_16x16x32_bf16 v[124:127], v[128:131], v[178:181], v[124:127]
	v_mfma_f32_16x16x32_bf16 v[120:123], v[136:139], v[178:181], v[120:123]
	v_mfma_f32_16x16x32_bf16 v[112:115], v[128:131], v[186:189], v[112:115]
	v_mfma_f32_16x16x32_bf16 v[104:107], v[136:139], v[186:189], v[104:107]
	v_mfma_f32_16x16x32_bf16 v[100:103], v[128:131], v[194:197], v[100:103]
	v_mfma_f32_16x16x32_bf16 v[96:99], v[136:139], v[194:197], v[96:99]
	v_mfma_f32_16x16x32_bf16 v[76:79], v[128:131], v[202:205], v[76:79]
	v_mfma_f32_16x16x32_bf16 v[72:75], v[136:139], v[202:205], v[72:75]
	v_mfma_f32_16x16x32_bf16 v[124:127], v[132:135], v[182:185], v[124:127]
	v_mfma_f32_16x16x32_bf16 v[120:123], v[140:143], v[182:185], v[120:123]
	v_mfma_f32_16x16x32_bf16 v[112:115], v[132:135], v[190:193], v[112:115]
	v_mfma_f32_16x16x32_bf16 v[104:107], v[140:143], v[190:193], v[104:107]
	v_mfma_f32_16x16x32_bf16 v[100:103], v[132:135], v[198:201], v[100:103]
	v_mfma_f32_16x16x32_bf16 v[96:99], v[140:143], v[198:201], v[96:99]
	v_mfma_f32_16x16x32_bf16 v[76:79], v[132:135], v[206:209], v[76:79]
	v_mfma_f32_16x16x32_bf16 v[72:75], v[140:143], v[206:209], v[72:75]
	v_mfma_f32_16x16x32_bf16 v[116:119], v[162:165], v[178:181], v[116:119]
	v_mfma_f32_16x16x32_bf16 v[108:111], v[170:173], v[178:181], v[108:111]
	v_mfma_f32_16x16x32_bf16 v[92:95], v[162:165], v[186:189], v[92:95]
	v_mfma_f32_16x16x32_bf16 v[88:91], v[170:173], v[186:189], v[88:91]
	v_mfma_f32_16x16x32_bf16 v[84:87], v[162:165], v[194:197], v[84:87]
	v_mfma_f32_16x16x32_bf16 v[80:83], v[170:173], v[194:197], v[80:83]
	v_mfma_f32_16x16x32_bf16 v[68:71], v[162:165], v[202:205], v[68:71]
	v_mfma_f32_16x16x32_bf16 v[64:67], v[170:173], v[202:205], v[64:67]
	v_mfma_f32_16x16x32_bf16 v[116:119], v[166:169], v[182:185], v[116:119]
	v_mfma_f32_16x16x32_bf16 v[108:111], v[174:177], v[182:185], v[108:111]
	v_mfma_f32_16x16x32_bf16 v[92:95], v[166:169], v[190:193], v[92:95]
	v_mfma_f32_16x16x32_bf16 v[88:91], v[174:177], v[190:193], v[88:91]
	v_mfma_f32_16x16x32_bf16 v[84:87], v[166:169], v[198:201], v[84:87]
	v_mfma_f32_16x16x32_bf16 v[80:83], v[174:177], v[198:201], v[80:83]
	v_mfma_f32_16x16x32_bf16 v[68:71], v[166:169], v[206:209], v[68:71]
	v_mfma_f32_16x16x32_bf16 v[64:67], v[174:177], v[206:209], v[64:67]
	s_setprio 0
	s_barrier
	s_add_i32 s22, s49, s36
	v_lshl_add_u64 v[210:211], s[26:27], 0, v[148:149]
	s_mov_b32 m0, s22
	ds_read_b128 v[178:181], v216 offset:16384
	ds_read_b128 v[182:185], v216 offset:17408
	ds_read_b128 v[186:189], v216 offset:18432
	ds_read_b128 v[190:193], v216 offset:19456
	ds_read_b128 v[194:197], v216 offset:20480
	ds_read_b128 v[198:201], v216 offset:21504
	ds_read_b128 v[202:205], v216 offset:22528
	ds_read_b128 v[206:209], v216 offset:23552
	global_load_lds_dwordx4 v[210:211], off
	s_add_i32 m0, s22, 0x2000
	s_add_u32 s22, s26, 0x158000
	v_lshl_add_u64 v[218:219], s[26:27], 0, v[144:145]
	s_addc_u32 s23, s27, 0
	s_add_i32 s60, s50, s36
	global_load_lds_dwordx4 v[218:219], off
	v_lshl_add_u64 v[220:221], s[22:23], 0, v[148:149]
	s_mov_b32 m0, s60
	v_lshl_add_u64 v[222:223], s[28:29], 0, v[146:147]
	global_load_lds_dwordx4 v[220:221], off
	v_lshl_add_u64 v[220:221], s[22:23], 0, v[144:145]
	s_add_i32 m0, s60, 0x2000
	s_nop 0
	global_load_lds_dwordx4 v[220:221], off
	v_lshl_add_u64 v[220:221], s[28:29], 0, v[150:151]
	s_mov_b32 m0, s39
	s_nop 0
	global_load_lds_dwordx4 v[220:221], off
	s_mov_b32 m0, s40
	s_nop 0
	global_load_lds_dwordx4 v[222:223], off
	s_waitcnt vmcnt(8)
	s_waitcnt lgkmcnt(0)
	s_barrier
	s_setprio 1
	s_waitcnt lgkmcnt(0)
	v_mfma_f32_16x16x32_bf16 v[60:63], v[128:131], v[178:181], v[60:63]
	v_mfma_f32_16x16x32_bf16 v[56:59], v[136:139], v[178:181], v[56:59]
	v_mfma_f32_16x16x32_bf16 v[48:51], v[128:131], v[186:189], v[48:51]
	v_mfma_f32_16x16x32_bf16 v[40:43], v[136:139], v[186:189], v[40:43]
	v_mfma_f32_16x16x32_bf16 v[32:35], v[128:131], v[194:197], v[32:35]
	v_mfma_f32_16x16x32_bf16 v[24:27], v[136:139], v[194:197], v[24:27]
	v_mfma_f32_16x16x32_bf16 v[16:19], v[128:131], v[202:205], v[16:19]
	v_mfma_f32_16x16x32_bf16 v[8:11], v[136:139], v[202:205], v[8:11]
	v_mfma_f32_16x16x32_bf16 v[60:63], v[132:135], v[182:185], v[60:63]
	v_mfma_f32_16x16x32_bf16 v[56:59], v[140:143], v[182:185], v[56:59]
	v_mfma_f32_16x16x32_bf16 v[48:51], v[132:135], v[190:193], v[48:51]
	v_mfma_f32_16x16x32_bf16 v[40:43], v[140:143], v[190:193], v[40:43]
	v_mfma_f32_16x16x32_bf16 v[32:35], v[132:135], v[198:201], v[32:35]
	v_mfma_f32_16x16x32_bf16 v[24:27], v[140:143], v[198:201], v[24:27]
	v_mfma_f32_16x16x32_bf16 v[16:19], v[132:135], v[206:209], v[16:19]
	v_mfma_f32_16x16x32_bf16 v[8:11], v[140:143], v[206:209], v[8:11]
	v_mfma_f32_16x16x32_bf16 v[52:55], v[162:165], v[178:181], v[52:55]
	v_mfma_f32_16x16x32_bf16 v[44:47], v[170:173], v[178:181], v[44:47]
	v_mfma_f32_16x16x32_bf16 v[36:39], v[162:165], v[186:189], v[36:39]
	v_mfma_f32_16x16x32_bf16 v[28:31], v[170:173], v[186:189], v[28:31]
	v_mfma_f32_16x16x32_bf16 v[20:23], v[162:165], v[194:197], v[20:23]
	v_mfma_f32_16x16x32_bf16 v[12:15], v[170:173], v[194:197], v[12:15]
	v_mfma_f32_16x16x32_bf16 v[4:7], v[162:165], v[202:205], v[4:7]
	v_mfma_f32_16x16x32_bf16 v[0:3], v[170:173], v[202:205], v[0:3]
	v_mfma_f32_16x16x32_bf16 v[52:55], v[166:169], v[182:185], v[52:55]
	v_mfma_f32_16x16x32_bf16 v[44:47], v[174:177], v[182:185], v[44:47]
	v_mfma_f32_16x16x32_bf16 v[36:39], v[166:169], v[190:193], v[36:39]
	v_mfma_f32_16x16x32_bf16 v[28:31], v[174:177], v[190:193], v[28:31]
	v_mfma_f32_16x16x32_bf16 v[20:23], v[166:169], v[198:201], v[20:23]
	v_mfma_f32_16x16x32_bf16 v[12:15], v[174:177], v[198:201], v[12:15]
	v_mfma_f32_16x16x32_bf16 v[4:7], v[166:169], v[206:209], v[4:7]
	v_mfma_f32_16x16x32_bf16 v[0:3], v[174:177], v[206:209], v[0:3]
	s_setprio 0
	s_barrier
; #define PG8_STAGE(bufoff, gbase, voff) do { _Pragma("unroll") for (int _i = 0; _i < 2; ++_i) \
;         __builtin_amdgcn_global_load_lds((const unsigned*)((const char*)(gbase) + (voff)[_i]), (PG8_LAS unsigned*)(lds + (bufoff) + ldsw + _i * 8192), 16, 0, 0); } while (0)
; #define PG8_LDA(dst, b, h) do { _Pragma("unroll") for (int m = 0; m < 4; ++m) _Pragma("unroll") for (int k = 0; k < 2; ++k) dst[m][k] = *(const PG8_LAS bf16x8*)(lds + PG8_SA(b, h) + aoff + m * 2048 + k * 1024); } while (0)
; #define PG8_LDB(dst, b, h) do { _Pragma("unroll") for (int n = 0; n < 2; ++n) _Pragma("unroll") for (int k = 0; k < 2; ++k) dst[n][k] = *(const PG8_LAS bf16x8*)(lds + PG8_SB(b, h) + boff + n * 2048 + k * 1024); } while (0)
; #define PG8_MMA(ai, bj, At, Bt) do { __builtin_amdgcn_s_setprio(1); _Pragma("unroll") for (int m = 0; m < 4; ++m) _Pragma("unroll") for (int n = 0; n < 2; ++n) _Pragma("unroll") for (int k = 0; k < 2; ++k) \
;         acc[ai][bj][m][n] = __builtin_amdgcn_mfma_f32_16x16x32_bf16(Bt[n][k], At[m][k], acc[ai][bj][m][n], 0, 0, 0); __builtin_amdgcn_s_setprio(0); } while (0)
; #define PG8_WAIT_V(n) asm volatile("s_waitcnt vmcnt(" #n ")" ::: "memory")
; #define PG8_WAIT_L(n) asm volatile("s_waitcnt lgkmcnt(" #n ")" ::: "memory")
; #define PG8_BAR __builtin_amdgcn_s_barrier()
; #define PG8_SCHED __builtin_amdgcn_sched_barrier(0)
; template <class Epi, class Sched, bool ALIGN_EPI = false, bool SP2 = false>
; __device__ __forceinline__ void gemm_phase(PG8_LAS unsigned char* lds, const Gemm g, const Sched& S, const Epi& E, const int wave_in) {
;     ...
;             PG8_LDB(B0, 1, 0); PG8_LDB(B1, 1, 1); PG8_SCHED; PG8_LDA(At, 1, 0); PG8_STAGE(PG8_SA(0, 1), a2 + hstepA, voffA);
;             PG8_WAIT_V(8); PG8_WAIT_L(0); PG8_BAR; PG8_MMA(0, 0, At, B0); PG8_MMA(0, 1, At, B1); PG8_BAR; PG8_SCHED;
	s_add_i32 s60, 0, 0x18000
	s_add_i32 s61, 0, 0x1c000
	v_add_u32_e32 v140, s60, v212
	v_add_u32_e32 v174, s61, v212
	ds_read_b128 v[128:131], v140
	ds_read_b128 v[132:135], v140 offset:1024
	ds_read_b128 v[136:139], v140 offset:2048
	ds_read_b128 v[140:143], v140 offset:3072
	ds_read_b128 v[162:165], v174
	ds_read_b128 v[166:169], v174 offset:1024
	ds_read_b128 v[170:173], v174 offset:2048
	ds_read_b128 v[174:177], v174 offset:3072
	s_add_u32 s22, s28, 0x158000
	s_addc_u32 s23, s29, 0
	s_mov_b32 m0, s41
	v_lshl_add_u64 v[224:225], s[22:23], 0, v[150:151]
	ds_read_b128 v[178:181], v216 offset:32768
	ds_read_b128 v[182:185], v216 offset:33792
	ds_read_b128 v[186:189], v216 offset:34816
	ds_read_b128 v[190:193], v216 offset:35840
	ds_read_b128 v[194:197], v216 offset:36864
	ds_read_b128 v[198:201], v216 offset:37888
	ds_read_b128 v[202:205], v216 offset:38912
	ds_read_b128 v[206:209], v216 offset:39936
	global_load_lds_dwordx4 v[224:225], off
	v_lshl_add_u64 v[224:225], s[22:23], 0, v[146:147]
	s_mov_b32 m0, s42
	s_nop 0
	global_load_lds_dwordx4 v[224:225], off
	s_waitcnt vmcnt(8)
	s_waitcnt lgkmcnt(0)
	s_barrier
	s_setprio 1
	s_waitcnt lgkmcnt(0)
	v_mfma_f32_16x16x32_bf16 v[124:127], v[128:131], v[178:181], v[124:127]
	v_mfma_f32_16x16x32_bf16 v[120:123], v[136:139], v[178:181], v[120:123]
	v_mfma_f32_16x16x32_bf16 v[112:115], v[128:131], v[186:189], v[112:115]
	v_mfma_f32_16x16x32_bf16 v[104:107], v[136:139], v[186:189], v[104:107]
	v_mfma_f32_16x16x32_bf16 v[100:103], v[128:131], v[194:197], v[100:103]
	v_mfma_f32_16x16x32_bf16 v[96:99], v[136:139], v[194:197], v[96:99]
	v_mfma_f32_16x16x32_bf16 v[76:79], v[128:131], v[202:205], v[76:79]
	v_mfma_f32_16x16x32_bf16 v[72:75], v[136:139], v[202:205], v[72:75]
	v_mfma_f32_16x16x32_bf16 v[124:127], v[132:135], v[182:185], v[124:127]
	v_mfma_f32_16x16x32_bf16 v[120:123], v[140:143], v[182:185], v[120:123]
	v_mfma_f32_16x16x32_bf16 v[112:115], v[132:135], v[190:193], v[112:115]
	v_mfma_f32_16x16x32_bf16 v[104:107], v[140:143], v[190:193], v[104:107]
	v_mfma_f32_16x16x32_bf16 v[100:103], v[132:135], v[198:201], v[100:103]
	v_mfma_f32_16x16x32_bf16 v[96:99], v[140:143], v[198:201], v[96:99]
	v_mfma_f32_16x16x32_bf16 v[76:79], v[132:135], v[206:209], v[76:79]
	v_mfma_f32_16x16x32_bf16 v[72:75], v[140:143], v[206:209], v[72:75]
	v_mfma_f32_16x16x32_bf16 v[116:119], v[162:165], v[178:181], v[116:119]
	v_mfma_f32_16x16x32_bf16 v[108:111], v[170:173], v[178:181], v[108:111]
	v_mfma_f32_16x16x32_bf16 v[92:95], v[162:165], v[186:189], v[92:95]
	v_mfma_f32_16x16x32_bf16 v[88:91], v[170:173], v[186:189], v[88:91]
	v_mfma_f32_16x16x32_bf16 v[84:87], v[162:165], v[194:197], v[84:87]
	v_mfma_f32_16x16x32_bf16 v[80:83], v[170:173], v[194:197], v[80:83]
	v_mfma_f32_16x16x32_bf16 v[68:71], v[162:165], v[202:205], v[68:71]
	v_mfma_f32_16x16x32_bf16 v[64:67], v[170:173], v[202:205], v[64:67]
	v_mfma_f32_16x16x32_bf16 v[116:119], v[166:169], v[182:185], v[116:119]
	v_mfma_f32_16x16x32_bf16 v[108:111], v[174:177], v[182:185], v[108:111]
	v_mfma_f32_16x16x32_bf16 v[92:95], v[166:169], v[190:193], v[92:95]
	v_mfma_f32_16x16x32_bf16 v[88:91], v[174:177], v[190:193], v[88:91]
	v_mfma_f32_16x16x32_bf16 v[84:87], v[166:169], v[198:201], v[84:87]
	v_mfma_f32_16x16x32_bf16 v[80:83], v[174:177], v[198:201], v[80:83]
	v_mfma_f32_16x16x32_bf16 v[68:71], v[166:169], v[206:209], v[68:71]
	v_mfma_f32_16x16x32_bf16 v[64:67], v[174:177], v[206:209], v[64:67]
	s_setprio 0
	s_barrier
; #define PG8_STAGE(bufoff, gbase, voff) do { _Pragma("unroll") for (int _i = 0; _i < 2; ++_i) \
;         __builtin_amdgcn_global_load_lds((const unsigned*)((const char*)(gbase) + (voff)[_i]), (PG8_LAS unsigned*)(lds + (bufoff) + ldsw + _i * 8192), 16, 0, 0); } while (0)
; #define PG8_LDA(dst, b, h) do { _Pragma("unroll") for (int m = 0; m < 4; ++m) _Pragma("unroll") for (int k = 0; k < 2; ++k) dst[m][k] = *(const PG8_LAS bf16x8*)(lds + PG8_SA(b, h) + aoff + m * 2048 + k * 1024); } while (0)
; #define PG8_MMA(ai, bj, At, Bt) do { __builtin_amdgcn_s_setprio(1); _Pragma("unroll") for (int m = 0; m < 4; ++m) _Pragma("unroll") for (int n = 0; n < 2; ++n) _Pragma("unroll") for (int k = 0; k < 2; ++k) \
;         acc[ai][bj][m][n] = __builtin_amdgcn_mfma_f32_16x16x32_bf16(Bt[n][k], At[m][k], acc[ai][bj][m][n], 0, 0, 0); __builtin_amdgcn_s_setprio(0); } while (0)
; #define PG8_WAIT_V(n) asm volatile("s_waitcnt vmcnt(" #n ")" ::: "memory")
; #define PG8_WAIT_L(n) asm volatile("s_waitcnt lgkmcnt(" #n ")" ::: "memory")
; #define PG8_BAR __builtin_amdgcn_s_barrier()
; #define PG8_SCHED __builtin_amdgcn_sched_barrier(0)
; template <class Epi, class Sched, bool ALIGN_EPI = false, bool SP2 = false>
; __device__ __forceinline__ void gemm_phase(PG8_LAS unsigned char* lds, const Gemm g, const Sched& S, const Epi& E, const int wave_in) {
;     ...
;         for (int t = 0; t < nt; t += 2) {
;     ...
;             PG8_LDA(At, 1, 1); PG8_STAGE(PG8_SB(1, 0), b3, voffB); PG8_STAGE(PG8_SB(1, 1), b3 + hstepB, voffB); PG8_STAGE(PG8_SA(1, 0), a3, voffA);
;             PG8_WAIT_V(8); PG8_WAIT_L(0); PG8_BAR; PG8_MMA(1, 0, At, B0); PG8_MMA(1, 1, At, B1); PG8_BAR; PG8_SCHED;
	s_add_i32 s22, s60, s36
	v_lshl_add_u64 v[210:211], v[210:211], 0, s[6:7]
	s_mov_b32 m0, s22
	ds_read_b128 v[178:181], v216 offset:49152
	ds_read_b128 v[182:185], v216 offset:50176
	ds_read_b128 v[186:189], v216 offset:51200
	ds_read_b128 v[190:193], v216 offset:52224
	ds_read_b128 v[194:197], v216 offset:53248
	ds_read_b128 v[198:201], v216 offset:54272
	ds_read_b128 v[202:205], v216 offset:55296
	ds_read_b128 v[206:209], v216 offset:56320
	global_load_lds_dwordx4 v[210:211], off
	s_add_i32 m0, s22, 0x2000
	s_add_u32 s22, s26, 0x158080
	v_lshl_add_u64 v[210:211], v[218:219], 0, s[6:7]
	s_addc_u32 s23, s27, 0
	s_add_i32 s26, s61, s36
	global_load_lds_dwordx4 v[210:211], off
	v_lshl_add_u64 v[210:211], s[22:23], 0, v[148:149]
	s_mov_b32 m0, s26
	s_nop 0
	global_load_lds_dwordx4 v[210:211], off
	v_lshl_add_u64 v[210:211], s[22:23], 0, v[144:145]
	s_add_i32 m0, s26, 0x2000
	s_nop 0
	global_load_lds_dwordx4 v[210:211], off
	v_lshl_add_u64 v[210:211], v[220:221], 0, s[6:7]
	s_mov_b32 m0, s46
	s_nop 0
	global_load_lds_dwordx4 v[210:211], off
	v_lshl_add_u64 v[210:211], v[222:223], 0, s[6:7]
	s_mov_b32 m0, s47
	s_nop 0
	global_load_lds_dwordx4 v[210:211], off
	s_waitcnt vmcnt(8)
	s_waitcnt lgkmcnt(0)
	s_barrier
	s_setprio 1
	s_waitcnt lgkmcnt(0)
	v_mfma_f32_16x16x32_bf16 v[60:63], v[128:131], v[178:181], v[60:63]
	v_mfma_f32_16x16x32_bf16 v[56:59], v[136:139], v[178:181], v[56:59]
	v_mfma_f32_16x16x32_bf16 v[48:51], v[128:131], v[186:189], v[48:51]
	v_mfma_f32_16x16x32_bf16 v[40:43], v[136:139], v[186:189], v[40:43]
	v_mfma_f32_16x16x32_bf16 v[32:35], v[128:131], v[194:197], v[32:35]
	v_mfma_f32_16x16x32_bf16 v[24:27], v[136:139], v[194:197], v[24:27]
	v_mfma_f32_16x16x32_bf16 v[16:19], v[128:131], v[202:205], v[16:19]
	v_mfma_f32_16x16x32_bf16 v[8:11], v[136:139], v[202:205], v[8:11]
	v_mfma_f32_16x16x32_bf16 v[60:63], v[132:135], v[182:185], v[60:63]
	v_mfma_f32_16x16x32_bf16 v[56:59], v[140:143], v[182:185], v[56:59]
	v_mfma_f32_16x16x32_bf16 v[48:51], v[132:135], v[190:193], v[48:51]
	v_mfma_f32_16x16x32_bf16 v[40:43], v[140:143], v[190:193], v[40:43]
	v_mfma_f32_16x16x32_bf16 v[32:35], v[132:135], v[198:201], v[32:35]
	v_mfma_f32_16x16x32_bf16 v[24:27], v[140:143], v[198:201], v[24:27]
	v_mfma_f32_16x16x32_bf16 v[16:19], v[132:135], v[206:209], v[16:19]
	v_mfma_f32_16x16x32_bf16 v[8:11], v[140:143], v[206:209], v[8:11]
	v_mfma_f32_16x16x32_bf16 v[52:55], v[162:165], v[178:181], v[52:55]
	v_mfma_f32_16x16x32_bf16 v[44:47], v[170:173], v[178:181], v[44:47]
	v_mfma_f32_16x16x32_bf16 v[36:39], v[162:165], v[186:189], v[36:39]
	v_mfma_f32_16x16x32_bf16 v[28:31], v[170:173], v[186:189], v[28:31]
	v_mfma_f32_16x16x32_bf16 v[20:23], v[162:165], v[194:197], v[20:23]
	v_mfma_f32_16x16x32_bf16 v[12:15], v[170:173], v[194:197], v[12:15]
	v_mfma_f32_16x16x32_bf16 v[4:7], v[162:165], v[202:205], v[4:7]
	v_mfma_f32_16x16x32_bf16 v[0:3], v[170:173], v[202:205], v[0:3]
	v_mfma_f32_16x16x32_bf16 v[52:55], v[166:169], v[182:185], v[52:55]
	v_mfma_f32_16x16x32_bf16 v[44:47], v[174:177], v[182:185], v[44:47]
	v_mfma_f32_16x16x32_bf16 v[36:39], v[166:169], v[190:193], v[36:39]
	v_mfma_f32_16x16x32_bf16 v[28:31], v[174:177], v[190:193], v[28:31]
	v_mfma_f32_16x16x32_bf16 v[20:23], v[166:169], v[198:201], v[20:23]
	v_mfma_f32_16x16x32_bf16 v[12:15], v[174:177], v[198:201], v[12:15]
	v_mfma_f32_16x16x32_bf16 v[4:7], v[166:169], v[206:209], v[4:7]
	v_mfma_f32_16x16x32_bf16 v[0:3], v[174:177], v[206:209], v[0:3]
	s_setprio 0
	s_barrier
	s_add_i32 s59, s59, 2
	s_add_u32 s21, s21, 0x100
	s_addc_u32 s58, s58, 0
	s_cmpk_gt_u32 s59, 0x53
	s_mov_b64 s[22:23], s[24:25]
	s_cbranch_scc0 .LBB0_2107

;     __host__ __device__ bool next(int i, Unit& u) const { const bool ok = StaticOrder::next(i, u); u.pm = 0; u.pn = 0; return ok; }
; #define PG8_STAGE(bufoff, gbase, voff) do { _Pragma("unroll") for (int _i = 0; _i < 2; ++_i) \
;         __builtin_amdgcn_global_load_lds((const unsigned*)((const char*)(gbase) + (voff)[_i]), (PG8_LAS unsigned*)(lds + (bufoff) + ldsw + _i * 8192), 16, 0, 0); } while (0)
; #define PG8_LDA(dst, b, h) do { _Pragma("unroll") for (int m = 0; m < 4; ++m) _Pragma("unroll") for (int k = 0; k < 2; ++k) dst[m][k] = *(const PG8_LAS bf16x8*)(lds + PG8_SA(b, h) + aoff + m * 2048 + k * 1024); } while (0)
; #define PG8_LDB(dst, b, h) do { _Pragma("unroll") for (int n = 0; n < 2; ++n) _Pragma("unroll") for (int k = 0; k < 2; ++k) dst[n][k] = *(const PG8_LAS bf16x8*)(lds + PG8_SB(b, h) + boff + n * 2048 + k * 1024); } while (0)
; #define PG8_WAIT_V(n) asm volatile("s_waitcnt vmcnt(" #n ")" ::: "memory")
; #define PG8_WAIT_L(n) asm volatile("s_waitcnt lgkmcnt(" #n ")" ::: "memory")
; #define PG8_BAR __builtin_amdgcn_s_barrier()
; #define PG8_SCHED __builtin_amdgcn_sched_barrier(0)
; template <class Epi, class Sched, bool ALIGN_EPI = false, bool SP2 = false>
; __device__ __forceinline__ void gemm_phase(PG8_LAS unsigned char* lds, const Gemm g, const Sched& S, const Epi& E, const int wave_in) {
;     ...
;         const bool has_next = S.next(ui + 1, nxt);
;         const char* nA = has_next ? (const char*)g.A + (size_t)nxt.pm * tstepA : cA; const char* nB = has_next ? (const char*)g.Bt + (size_t)nxt.pn * tstepB : cB;
;         for (int t = 0; t < nt; t += 2) {
;             const bool last = (t == nt - 2);
;             const char* a1 = cA + (size_t)(t + 1) * kstep;
;             const char* a2 = last ? nA : cA + (size_t)(t + 2) * kstep; const char* b2 = last ? nB : cB + (size_t)(t + 2) * kstep;
;             const char* a3 = a2 + kstep; const char* b3 = b2 + kstep;
;             if (last && has_next) S.a_ready(nxt);
;             if constexpr (SP2) {
;             PG8_LDB(B0, 0, 0); PG8_LDB(B1, 0, 1); PG8_SCHED; PG8_LDA(At, 0, 0); PG8_STAGE(PG8_SA(1, 1), a1 + hstepA, voffA);
;             PG8_WAIT_V(8); PG8_WAIT_L(0); PG8_BAR; PG8_MMA(0, 0, At, B0); PG8_MMA(0, 1, At, B1); PG8_BAR; PG8_SCHED;
;             PG8_LDA(At, 0, 1); PG8_STAGE(PG8_SB(0, 0), b2, voffB); PG8_STAGE(PG8_SB(0, 1), b2 + hstepB, voffB); PG8_STAGE(PG8_SA(0, 0), a2, voffA);
.LBB0_2247:
	s_ashr_i32 s15, s14, 31
	s_lshl_b64 s[16:17], s[14:15], 20
	s_add_u32 s16, s28, s16
	s_addc_u32 s17, s29, s17
	s_and_b64 s[18:19], s[2:3], exec
	s_cselect_b32 s5, s17, s23
	s_cselect_b32 s15, s16, s22
	s_ashr_i32 s13, s12, 31
	s_lshl_b64 s[18:19], s[12:13], 20
	s_add_u32 s18, s30, s18
	s_addc_u32 s19, s31, s19
	s_and_b64 s[26:27], s[2:3], exec
	s_cselect_b32 s13, s19, s25
	s_cselect_b32 s47, s18, s24
	s_add_u32 s22, s22, 0x80080
	s_addc_u32 s23, s23, 0
	s_add_u32 s48, s24, 0x100
	v_mov_b32_e32 v0, 0
	s_addc_u32 s49, s25, 0
	s_mov_b32 s50, -2
	ds_read_b128 v[144:147], v151
	ds_read_b128 v[154:157], v151 offset:1024
	ds_read_b128 v[158:161], v151 offset:2048
	ds_read_b128 v[162:165], v151 offset:3072
	ds_read_b128 v[166:169], v152
	ds_read_b128 v[170:173], v152 offset:1024
	ds_read_b128 v[174:177], v152 offset:2048
	ds_read_b128 v[178:181], v152 offset:3072
	s_add_u32 s24, s22, 0xfff80080
	s_addc_u32 s25, s23, -1
	s_cmp_eq_u32 s50, 28
	s_cselect_b32 s27, s5, s25
	s_cselect_b32 s26, s15, s24
	s_cselect_b32 s25, s13, s49
	s_cselect_b32 s24, s47, s48
	v_lshl_add_u64 v[214:215], s[22:23], 0, v[136:137]
	s_add_i32 m0, s21, 0xc000
	ds_read_b128 v[182:185], v153
	ds_read_b128 v[186:189], v153 offset:1024
	ds_read_b128 v[190:193], v153 offset:2048
	ds_read_b128 v[194:197], v153 offset:3072
	ds_read_b128 v[198:201], v153 offset:4096
	ds_read_b128 v[202:205], v153 offset:5120
	ds_read_b128 v[206:209], v153 offset:6144
	ds_read_b128 v[210:213], v153 offset:7168
	global_load_lds_dwordx4 v[214:215], off
	v_lshl_add_u64 v[214:215], s[22:23], 0, v[138:139]
	s_add_i32 m0, s21, 0xe000
	s_nop 0
	global_load_lds_dwordx4 v[214:215], off
	s_waitcnt vmcnt(8)
	s_waitcnt lgkmcnt(0)
	s_barrier
	s_setprio 1
	s_waitcnt lgkmcnt(0)
	v_mfma_f32_16x16x32_bf16 v[124:127], v[144:147], v[182:185], 0
	v_mfma_f32_16x16x32_bf16 v[120:123], v[158:161], v[182:185], 0
	v_mfma_f32_16x16x32_bf16 v[108:111], v[144:147], v[190:193], 0
	v_mfma_f32_16x16x32_bf16 v[104:107], v[158:161], v[190:193], 0
	v_mfma_f32_16x16x32_bf16 v[92:95], v[144:147], v[198:201], 0
	v_mfma_f32_16x16x32_bf16 v[88:91], v[158:161], v[198:201], 0
	v_mfma_f32_16x16x32_bf16 v[76:79], v[144:147], v[206:209], 0
	v_mfma_f32_16x16x32_bf16 v[72:75], v[158:161], v[206:209], 0
	v_mfma_f32_16x16x32_bf16 v[124:127], v[154:157], v[186:189], v[124:127]
	v_mfma_f32_16x16x32_bf16 v[120:123], v[162:165], v[186:189], v[120:123]
	v_mfma_f32_16x16x32_bf16 v[108:111], v[154:157], v[194:197], v[108:111]
	v_mfma_f32_16x16x32_bf16 v[104:107], v[162:165], v[194:197], v[104:107]
	v_mfma_f32_16x16x32_bf16 v[92:95], v[154:157], v[202:205], v[92:95]
	v_mfma_f32_16x16x32_bf16 v[88:91], v[162:165], v[202:205], v[88:91]
	v_mfma_f32_16x16x32_bf16 v[76:79], v[154:157], v[210:213], v[76:79]
	v_mfma_f32_16x16x32_bf16 v[72:75], v[162:165], v[210:213], v[72:75]
	v_mfma_f32_16x16x32_bf16 v[116:119], v[166:169], v[182:185], 0
	v_mfma_f32_16x16x32_bf16 v[112:115], v[174:177], v[182:185], 0
	v_mfma_f32_16x16x32_bf16 v[100:103], v[166:169], v[190:193], 0
	v_mfma_f32_16x16x32_bf16 v[96:99], v[174:177], v[190:193], 0
	v_mfma_f32_16x16x32_bf16 v[84:87], v[166:169], v[198:201], 0
	v_mfma_f32_16x16x32_bf16 v[80:83], v[174:177], v[198:201], 0
	v_mfma_f32_16x16x32_bf16 v[68:71], v[166:169], v[206:209], 0
	v_mfma_f32_16x16x32_bf16 v[64:67], v[174:177], v[206:209], 0
	v_mfma_f32_16x16x32_bf16 v[116:119], v[170:173], v[186:189], v[116:119]
	v_mfma_f32_16x16x32_bf16 v[112:115], v[178:181], v[186:189], v[112:115]
	v_mfma_f32_16x16x32_bf16 v[100:103], v[170:173], v[194:197], v[100:103]
	v_mfma_f32_16x16x32_bf16 v[96:99], v[178:181], v[194:197], v[96:99]
	v_mfma_f32_16x16x32_bf16 v[84:87], v[170:173], v[202:205], v[84:87]
	v_mfma_f32_16x16x32_bf16 v[80:83], v[178:181], v[202:205], v[80:83]
	v_mfma_f32_16x16x32_bf16 v[68:71], v[170:173], v[210:213], v[68:71]
	v_mfma_f32_16x16x32_bf16 v[64:67], v[178:181], v[210:213], v[64:67]
	s_setprio 0
	s_barrier
	s_add_i32 s51, s44, s34
	v_lshl_add_u64 v[214:215], s[24:25], 0, v[130:131]
	s_mov_b32 m0, s51
	ds_read_b128 v[182:185], v153 offset:16384
	ds_read_b128 v[186:189], v153 offset:17408
	ds_read_b128 v[190:193], v153 offset:18432
	ds_read_b128 v[194:197], v153 offset:19456
	ds_read_b128 v[198:201], v153 offset:20480
	ds_read_b128 v[202:205], v153 offset:21504
	ds_read_b128 v[206:209], v153 offset:22528
	ds_read_b128 v[210:213], v153 offset:23552
	global_load_lds_dwordx4 v[214:215], off
	s_add_i32 m0, s51, 0x2000
	s_add_u32 s52, s24, 0x80000
	v_lshl_add_u64 v[216:217], s[24:25], 0, v[134:135]
	s_addc_u32 s53, s25, 0
	s_add_i32 s51, s45, s34
	global_load_lds_dwordx4 v[216:217], off
	v_lshl_add_u64 v[218:219], s[52:53], 0, v[130:131]
	s_mov_b32 m0, s51
	v_lshl_add_u64 v[220:221], s[26:27], 0, v[132:133]
	global_load_lds_dwordx4 v[218:219], off
	v_lshl_add_u64 v[218:219], s[52:53], 0, v[134:135]
	s_add_i32 m0, s51, 0x2000
	s_nop 0
	global_load_lds_dwordx4 v[218:219], off
	v_lshl_add_u64 v[218:219], s[26:27], 0, v[128:129]
	s_mov_b32 m0, s21
	s_nop 0
	global_load_lds_dwordx4 v[218:219], off
	s_mov_b32 m0, s35
	s_nop 0
	global_load_lds_dwordx4 v[220:221], off
	s_waitcnt vmcnt(8)
	s_waitcnt lgkmcnt(0)
	s_barrier
; #define PG8_STAGE(bufoff, gbase, voff) do { _Pragma("unroll") for (int _i = 0; _i < 2; ++_i) \
;         __builtin_amdgcn_global_load_lds((const unsigned*)((const char*)(gbase) + (voff)[_i]), (PG8_LAS unsigned*)(lds + (bufoff) + ldsw + _i * 8192), 16, 0, 0); } while (0)
; #define PG8_LDA(dst, b, h) do { _Pragma("unroll") for (int m = 0; m < 4; ++m) _Pragma("unroll") for (int k = 0; k < 2; ++k) dst[m][k] = *(const PG8_LAS bf16x8*)(lds + PG8_SA(b, h) + aoff + m * 2048 + k * 1024); } while (0)
; #define PG8_LDB(dst, b, h) do { _Pragma("unroll") for (int n = 0; n < 2; ++n) _Pragma("unroll") for (int k = 0; k < 2; ++k) dst[n][k] = *(const PG8_LAS bf16x8*)(lds + PG8_SB(b, h) + boff + n * 2048 + k * 1024); } while (0)
; #define PG8_MMA(ai, bj, At, Bt) do { __builtin_amdgcn_s_setprio(1); _Pragma("unroll") for (int m = 0; m < 4; ++m) _Pragma("unroll") for (int n = 0; n < 2; ++n) _Pragma("unroll") for (int k = 0; k < 2; ++k) \
;         acc[ai][bj][m][n] = __builtin_amdgcn_mfma_f32_16x16x32_bf16(Bt[n][k], At[m][k], acc[ai][bj][m][n], 0, 0, 0); __builtin_amdgcn_s_setprio(0); } while (0)
; #define PG8_WAIT_V(n) asm volatile("s_waitcnt vmcnt(" #n ")" ::: "memory")
; #define PG8_WAIT_L(n) asm volatile("s_waitcnt lgkmcnt(" #n ")" ::: "memory")
; #define PG8_BAR __builtin_amdgcn_s_barrier()
; #define PG8_SCHED __builtin_amdgcn_sched_barrier(0)
; template <class Epi, class Sched, bool ALIGN_EPI = false, bool SP2 = false>
; __device__ __forceinline__ void gemm_phase(PG8_LAS unsigned char* lds, const Gemm g, const Sched& S, const Epi& E, const int wave_in) {
;     ...
;             PG8_LDA(At, 0, 1); PG8_STAGE(PG8_SB(0, 0), b2, voffB); PG8_STAGE(PG8_SB(0, 1), b2 + hstepB, voffB); PG8_STAGE(PG8_SA(0, 0), a2, voffA);
;             PG8_WAIT_V(8); PG8_WAIT_L(0); PG8_BAR; PG8_MMA(1, 0, At, B0); PG8_MMA(1, 1, At, B1); PG8_BAR; PG8_SCHED;
;             PG8_LDB(B0, 1, 0); PG8_LDB(B1, 1, 1); PG8_SCHED; PG8_LDA(At, 1, 0); PG8_STAGE(PG8_SA(0, 1), a2 + hstepA, voffA);
;             PG8_WAIT_V(8); PG8_WAIT_L(0); PG8_BAR; PG8_MMA(0, 0, At, B0); PG8_MMA(0, 1, At, B1); PG8_BAR; PG8_SCHED;
	s_setprio 1
	s_waitcnt lgkmcnt(0)
	v_mfma_f32_16x16x32_bf16 v[60:63], v[144:147], v[182:185], 0
	v_mfma_f32_16x16x32_bf16 v[56:59], v[158:161], v[182:185], 0
	v_mfma_f32_16x16x32_bf16 v[44:47], v[144:147], v[190:193], 0
	v_mfma_f32_16x16x32_bf16 v[40:43], v[158:161], v[190:193], 0
	v_mfma_f32_16x16x32_bf16 v[28:31], v[144:147], v[198:201], 0
	v_mfma_f32_16x16x32_bf16 v[24:27], v[158:161], v[198:201], 0
	v_mfma_f32_16x16x32_bf16 v[12:15], v[144:147], v[206:209], 0
	v_mfma_f32_16x16x32_bf16 v[8:11], v[158:161], v[206:209], 0
	v_mfma_f32_16x16x32_bf16 v[60:63], v[154:157], v[186:189], v[60:63]
	v_mfma_f32_16x16x32_bf16 v[56:59], v[162:165], v[186:189], v[56:59]
	v_mfma_f32_16x16x32_bf16 v[44:47], v[154:157], v[194:197], v[44:47]
	v_mfma_f32_16x16x32_bf16 v[40:43], v[162:165], v[194:197], v[40:43]
	v_mfma_f32_16x16x32_bf16 v[28:31], v[154:157], v[202:205], v[28:31]
	v_mfma_f32_16x16x32_bf16 v[24:27], v[162:165], v[202:205], v[24:27]
	v_mfma_f32_16x16x32_bf16 v[12:15], v[154:157], v[210:213], v[12:15]
	v_mfma_f32_16x16x32_bf16 v[8:11], v[162:165], v[210:213], v[8:11]
	v_mfma_f32_16x16x32_bf16 v[52:55], v[166:169], v[182:185], 0
	v_mfma_f32_16x16x32_bf16 v[48:51], v[174:177], v[182:185], 0
	v_mfma_f32_16x16x32_bf16 v[36:39], v[166:169], v[190:193], 0
	v_mfma_f32_16x16x32_bf16 v[32:35], v[174:177], v[190:193], 0
	v_mfma_f32_16x16x32_bf16 v[20:23], v[166:169], v[198:201], 0
	v_mfma_f32_16x16x32_bf16 v[16:19], v[174:177], v[198:201], 0
	v_mfma_f32_16x16x32_bf16 v[4:7], v[166:169], v[206:209], 0
	v_mfma_f32_16x16x32_bf16 v[0:3], v[174:177], v[206:209], 0
	v_mfma_f32_16x16x32_bf16 v[52:55], v[170:173], v[186:189], v[52:55]
	v_mfma_f32_16x16x32_bf16 v[48:51], v[178:181], v[186:189], v[48:51]
	v_mfma_f32_16x16x32_bf16 v[36:39], v[170:173], v[194:197], v[36:39]
	v_mfma_f32_16x16x32_bf16 v[32:35], v[178:181], v[194:197], v[32:35]
	v_mfma_f32_16x16x32_bf16 v[20:23], v[170:173], v[202:205], v[20:23]
	v_mfma_f32_16x16x32_bf16 v[16:19], v[178:181], v[202:205], v[16:19]
	v_mfma_f32_16x16x32_bf16 v[4:7], v[170:173], v[210:213], v[4:7]
	v_mfma_f32_16x16x32_bf16 v[0:3], v[178:181], v[210:213], v[0:3]
	s_setprio 0
	s_barrier
	s_add_i32 s51, 0, 0x18000
	s_add_i32 s52, 0, 0x1c000
	v_add_u32_e32 v162, s51, v149
	v_add_u32_e32 v178, s52, v149
	ds_read_b128 v[144:147], v162
	ds_read_b128 v[154:157], v162 offset:1024
	ds_read_b128 v[158:161], v162 offset:2048
	ds_read_b128 v[162:165], v162 offset:3072
	ds_read_b128 v[166:169], v178
	ds_read_b128 v[170:173], v178 offset:1024
	ds_read_b128 v[174:177], v178 offset:2048
	ds_read_b128 v[178:181], v178 offset:3072
	s_add_u32 s26, s26, 0x80000
	s_addc_u32 s27, s27, 0
	s_mov_b32 m0, s36
	v_lshl_add_u64 v[222:223], s[26:27], 0, v[128:129]
	ds_read_b128 v[182:185], v153 offset:32768
	ds_read_b128 v[186:189], v153 offset:33792
	ds_read_b128 v[190:193], v153 offset:34816
	ds_read_b128 v[194:197], v153 offset:35840
	ds_read_b128 v[198:201], v153 offset:36864
	ds_read_b128 v[202:205], v153 offset:37888
	ds_read_b128 v[206:209], v153 offset:38912
	ds_read_b128 v[210:213], v153 offset:39936
	global_load_lds_dwordx4 v[222:223], off
	v_lshl_add_u64 v[222:223], s[26:27], 0, v[132:133]
	s_mov_b32 m0, s37
	s_nop 0
	global_load_lds_dwordx4 v[222:223], off
	s_waitcnt vmcnt(8)
	s_waitcnt lgkmcnt(0)
	s_barrier
	s_setprio 1
	s_waitcnt lgkmcnt(0)
	v_mfma_f32_16x16x32_bf16 v[124:127], v[144:147], v[182:185], v[124:127]
	v_mfma_f32_16x16x32_bf16 v[120:123], v[158:161], v[182:185], v[120:123]
	v_mfma_f32_16x16x32_bf16 v[108:111], v[144:147], v[190:193], v[108:111]
	v_mfma_f32_16x16x32_bf16 v[104:107], v[158:161], v[190:193], v[104:107]
	v_mfma_f32_16x16x32_bf16 v[92:95], v[144:147], v[198:201], v[92:95]
	v_mfma_f32_16x16x32_bf16 v[88:91], v[158:161], v[198:201], v[88:91]
	v_mfma_f32_16x16x32_bf16 v[76:79], v[144:147], v[206:209], v[76:79]
	v_mfma_f32_16x16x32_bf16 v[72:75], v[158:161], v[206:209], v[72:75]
	v_mfma_f32_16x16x32_bf16 v[124:127], v[154:157], v[186:189], v[124:127]
	v_mfma_f32_16x16x32_bf16 v[120:123], v[162:165], v[186:189], v[120:123]
	v_mfma_f32_16x16x32_bf16 v[108:111], v[154:157], v[194:197], v[108:111]
	v_mfma_f32_16x16x32_bf16 v[104:107], v[162:165], v[194:197], v[104:107]
	v_mfma_f32_16x16x32_bf16 v[92:95], v[154:157], v[202:205], v[92:95]
	v_mfma_f32_16x16x32_bf16 v[88:91], v[162:165], v[202:205], v[88:91]
	v_mfma_f32_16x16x32_bf16 v[76:79], v[154:157], v[210:213], v[76:79]
	v_mfma_f32_16x16x32_bf16 v[72:75], v[162:165], v[210:213], v[72:75]
	v_mfma_f32_16x16x32_bf16 v[116:119], v[166:169], v[182:185], v[116:119]
	v_mfma_f32_16x16x32_bf16 v[112:115], v[174:177], v[182:185], v[112:115]
	v_mfma_f32_16x16x32_bf16 v[100:103], v[166:169], v[190:193], v[100:103]
	v_mfma_f32_16x16x32_bf16 v[96:99], v[174:177], v[190:193], v[96:99]
	v_mfma_f32_16x16x32_bf16 v[84:87], v[166:169], v[198:201], v[84:87]
	v_mfma_f32_16x16x32_bf16 v[80:83], v[174:177], v[198:201], v[80:83]
	v_mfma_f32_16x16x32_bf16 v[68:71], v[166:169], v[206:209], v[68:71]
	v_mfma_f32_16x16x32_bf16 v[64:67], v[174:177], v[206:209], v[64:67]
	v_mfma_f32_16x16x32_bf16 v[116:119], v[170:173], v[186:189], v[116:119]
	v_mfma_f32_16x16x32_bf16 v[112:115], v[178:181], v[186:189], v[112:115]
	v_mfma_f32_16x16x32_bf16 v[100:103], v[170:173], v[194:197], v[100:103]
	v_mfma_f32_16x16x32_bf16 v[96:99], v[178:181], v[194:197], v[96:99]
	v_mfma_f32_16x16x32_bf16 v[84:87], v[170:173], v[202:205], v[84:87]
	v_mfma_f32_16x16x32_bf16 v[80:83], v[178:181], v[202:205], v[80:83]
	v_mfma_f32_16x16x32_bf16 v[68:71], v[170:173], v[210:213], v[68:71]
	v_mfma_f32_16x16x32_bf16 v[64:67], v[178:181], v[210:213], v[64:67]
	s_setprio 0
	s_barrier
; #define PG8_STAGE(bufoff, gbase, voff) do { _Pragma("unroll") for (int _i = 0; _i < 2; ++_i) \
;         __builtin_amdgcn_global_load_lds((const unsigned*)((const char*)(gbase) + (voff)[_i]), (PG8_LAS unsigned*)(lds + (bufoff) + ldsw + _i * 8192), 16, 0, 0); } while (0)
; #define PG8_LDA(dst, b, h) do { _Pragma("unroll") for (int m = 0; m < 4; ++m) _Pragma("unroll") for (int k = 0; k < 2; ++k) dst[m][k] = *(const PG8_LAS bf16x8*)(lds + PG8_SA(b, h) + aoff + m * 2048 + k * 1024); } while (0)
; #define PG8_WAIT_V(n) asm volatile("s_waitcnt vmcnt(" #n ")" ::: "memory")
; #define PG8_WAIT_L(n) asm volatile("s_waitcnt lgkmcnt(" #n ")" ::: "memory")
; #define PG8_BAR __builtin_amdgcn_s_barrier()
; template <class Epi, class Sched, bool ALIGN_EPI = false, bool SP2 = false>
; __device__ __forceinline__ void gemm_phase(PG8_LAS unsigned char* lds, const Gemm g, const Sched& S, const Epi& E, const int wave_in) {
;     ...
;         for (int t = 0; t < nt; t += 2) {
;             const bool last = (t == nt - 2);
;             const char* a1 = cA + (size_t)(t + 1) * kstep;
;             const char* a2 = last ? nA : cA + (size_t)(t + 2) * kstep; const char* b2 = last ? nB : cB + (size_t)(t + 2) * kstep;
;             const char* a3 = a2 + kstep; const char* b3 = b2 + kstep;
;             if (last && has_next) S.a_ready(nxt);
;             if constexpr (SP2) {
;             PG8_LDB(B0, 0, 0); PG8_LDB(B1, 0, 1); PG8_SCHED; PG8_LDA(At, 0, 0); PG8_STAGE(PG8_SA(1, 1), a1 + hstepA, voffA);
;             PG8_WAIT_V(8); PG8_WAIT_L(0); PG8_BAR; PG8_MMA(0, 0, At, B0); PG8_MMA(0, 1, At, B1); PG8_BAR; PG8_SCHED;
;             PG8_LDA(At, 0, 1); PG8_STAGE(PG8_SB(0, 0), b2, voffB); PG8_STAGE(PG8_SB(0, 1), b2 + hstepB, voffB); PG8_STAGE(PG8_SA(0, 0), a2, voffA);
;             PG8_WAIT_V(8); PG8_WAIT_L(0); PG8_BAR; PG8_MMA(1, 0, At, B0); PG8_MMA(1, 1, At, B1); PG8_BAR; PG8_SCHED;
;             PG8_LDB(B0, 1, 0); PG8_LDB(B1, 1, 1); PG8_SCHED; PG8_LDA(At, 1, 0); PG8_STAGE(PG8_SA(0, 1), a2 + hstepA, voffA);
;             PG8_WAIT_V(8); PG8_WAIT_L(0); PG8_BAR; PG8_MMA(0, 0, At, B0); PG8_MMA(0, 1, At, B1); PG8_BAR; PG8_SCHED;
;             PG8_LDA(At, 1, 1); PG8_STAGE(PG8_SB(1, 0), b3, voffB); PG8_STAGE(PG8_SB(1, 1), b3 + hstepB, voffB); PG8_STAGE(PG8_SA(1, 0), a3, voffA);
;             PG8_WAIT_V(8); PG8_WAIT_L(0); PG8_BAR; PG8_MMA(1, 0, At, B0); PG8_MMA(1, 1, At, B1); PG8_BAR; PG8_SCHED;
	s_add_i32 s26, s51, s34
	v_lshl_add_u64 v[214:215], v[214:215], 0, s[8:9]
	s_mov_b32 m0, s26
	ds_read_b128 v[182:185], v153 offset:49152
	ds_read_b128 v[186:189], v153 offset:50176
	ds_read_b128 v[190:193], v153 offset:51200
	ds_read_b128 v[194:197], v153 offset:52224
	ds_read_b128 v[198:201], v153 offset:53248
	ds_read_b128 v[202:205], v153 offset:54272
	ds_read_b128 v[206:209], v153 offset:55296
	ds_read_b128 v[210:213], v153 offset:56320
	global_load_lds_dwordx4 v[214:215], off
	s_add_i32 m0, s26, 0x2000
	s_add_u32 s24, s24, 0x80080
	v_lshl_add_u64 v[214:215], v[216:217], 0, s[8:9]
	s_addc_u32 s25, s25, 0
	s_add_i32 s26, s52, s34
	global_load_lds_dwordx4 v[214:215], off
	v_lshl_add_u64 v[214:215], s[24:25], 0, v[130:131]
	s_mov_b32 m0, s26
	s_nop 0
	global_load_lds_dwordx4 v[214:215], off
	v_lshl_add_u64 v[214:215], s[24:25], 0, v[134:135]
	s_add_i32 m0, s26, 0x2000
	s_nop 0
	global_load_lds_dwordx4 v[214:215], off
	v_lshl_add_u64 v[214:215], v[218:219], 0, s[8:9]
	s_mov_b32 m0, s39
	s_nop 0
	global_load_lds_dwordx4 v[214:215], off
	v_lshl_add_u64 v[214:215], v[220:221], 0, s[8:9]
	s_mov_b32 m0, s40
	s_nop 0
	global_load_lds_dwordx4 v[214:215], off
	s_waitcnt vmcnt(8)
	s_waitcnt lgkmcnt(0)
	s_barrier
	s_setprio 1
	s_waitcnt lgkmcnt(0)
	v_mfma_f32_16x16x32_bf16 v[60:63], v[144:147], v[182:185], v[60:63]
	v_mfma_f32_16x16x32_bf16 v[56:59], v[158:161], v[182:185], v[56:59]
	v_mfma_f32_16x16x32_bf16 v[44:47], v[144:147], v[190:193], v[44:47]
	v_mfma_f32_16x16x32_bf16 v[40:43], v[158:161], v[190:193], v[40:43]
	v_mfma_f32_16x16x32_bf16 v[28:31], v[144:147], v[198:201], v[28:31]
	v_mfma_f32_16x16x32_bf16 v[24:27], v[158:161], v[198:201], v[24:27]
	v_mfma_f32_16x16x32_bf16 v[12:15], v[144:147], v[206:209], v[12:15]
	v_mfma_f32_16x16x32_bf16 v[8:11], v[158:161], v[206:209], v[8:11]
	v_mfma_f32_16x16x32_bf16 v[60:63], v[154:157], v[186:189], v[60:63]
	v_mfma_f32_16x16x32_bf16 v[56:59], v[162:165], v[186:189], v[56:59]
	v_mfma_f32_16x16x32_bf16 v[44:47], v[154:157], v[194:197], v[44:47]
	v_mfma_f32_16x16x32_bf16 v[40:43], v[162:165], v[194:197], v[40:43]
	v_mfma_f32_16x16x32_bf16 v[28:31], v[154:157], v[202:205], v[28:31]
	v_mfma_f32_16x16x32_bf16 v[24:27], v[162:165], v[202:205], v[24:27]
	v_mfma_f32_16x16x32_bf16 v[12:15], v[154:157], v[210:213], v[12:15]
	v_mfma_f32_16x16x32_bf16 v[8:11], v[162:165], v[210:213], v[8:11]
	v_mfma_f32_16x16x32_bf16 v[52:55], v[166:169], v[182:185], v[52:55]
	v_mfma_f32_16x16x32_bf16 v[48:51], v[174:177], v[182:185], v[48:51]
	v_mfma_f32_16x16x32_bf16 v[36:39], v[166:169], v[190:193], v[36:39]
	v_mfma_f32_16x16x32_bf16 v[32:35], v[174:177], v[190:193], v[32:35]
	v_mfma_f32_16x16x32_bf16 v[20:23], v[166:169], v[198:201], v[20:23]
	v_mfma_f32_16x16x32_bf16 v[16:19], v[174:177], v[198:201], v[16:19]
	v_mfma_f32_16x16x32_bf16 v[4:7], v[166:169], v[206:209], v[4:7]
	v_mfma_f32_16x16x32_bf16 v[0:3], v[174:177], v[206:209], v[0:3]
	v_mfma_f32_16x16x32_bf16 v[52:55], v[170:173], v[186:189], v[52:55]
	v_mfma_f32_16x16x32_bf16 v[48:51], v[178:181], v[186:189], v[48:51]
	v_mfma_f32_16x16x32_bf16 v[36:39], v[170:173], v[194:197], v[36:39]
	v_mfma_f32_16x16x32_bf16 v[32:35], v[178:181], v[194:197], v[32:35]
	v_mfma_f32_16x16x32_bf16 v[20:23], v[170:173], v[202:205], v[20:23]
	v_mfma_f32_16x16x32_bf16 v[16:19], v[178:181], v[202:205], v[16:19]
	v_mfma_f32_16x16x32_bf16 v[4:7], v[170:173], v[210:213], v[4:7]
	v_mfma_f32_16x16x32_bf16 v[0:3], v[178:181], v[210:213], v[0:3]
	s_setprio 0
	s_barrier
	s_add_i32 s50, s50, 2
	s_add_u32 s22, s22, 0x100
	s_addc_u32 s23, s23, 0
	s_add_u32 s48, s48, 0x100
	s_addc_u32 s49, s49, 0
	s_cmp_gt_u32 s50, 29
	s_cbranch_scc0 .LBB0_2248
	s_branch .Lkx_26
.LBB0_2248:
	ds_read_b128 v[144:147], v151
	ds_read_b128 v[154:157], v151 offset:1024
	ds_read_b128 v[158:161], v151 offset:2048
	ds_read_b128 v[162:165], v151 offset:3072
	ds_read_b128 v[166:169], v152
	ds_read_b128 v[170:173], v152 offset:1024
	ds_read_b128 v[174:177], v152 offset:2048
	ds_read_b128 v[178:181], v152 offset:3072
	s_add_u32 s24, s22, 0xfff80080
	s_addc_u32 s25, s23, -1
	s_cmp_eq_u32 s50, 28
	s_cselect_b32 s27, s5, s25
	s_cselect_b32 s26, s15, s24
	s_cselect_b32 s25, s13, s49
	s_cselect_b32 s24, s47, s48
	v_lshl_add_u64 v[214:215], s[22:23], 0, v[136:137]
	s_add_i32 m0, s21, 0xc000
	ds_read_b128 v[182:185], v153
	ds_read_b128 v[186:189], v153 offset:1024
	ds_read_b128 v[190:193], v153 offset:2048
	ds_read_b128 v[194:197], v153 offset:3072
	ds_read_b128 v[198:201], v153 offset:4096
	ds_read_b128 v[202:205], v153 offset:5120
	ds_read_b128 v[206:209], v153 offset:6144
	ds_read_b128 v[210:213], v153 offset:7168
	global_load_lds_dwordx4 v[214:215], off
	v_lshl_add_u64 v[214:215], s[22:23], 0, v[138:139]
	s_add_i32 m0, s21, 0xe000
	s_nop 0
	global_load_lds_dwordx4 v[214:215], off
	s_waitcnt vmcnt(8)
	s_waitcnt lgkmcnt(0)
	s_barrier
; #define PG8_STAGE(bufoff, gbase, voff) do { _Pragma("unroll") for (int _i = 0; _i < 2; ++_i) \
;         __builtin_amdgcn_global_load_lds((const unsigned*)((const char*)(gbase) + (voff)[_i]), (PG8_LAS unsigned*)(lds + (bufoff) + ldsw + _i * 8192), 16, 0, 0); } while (0)
; #define PG8_LDA(dst, b, h) do { _Pragma("unroll") for (int m = 0; m < 4; ++m) _Pragma("unroll") for (int k = 0; k < 2; ++k) dst[m][k] = *(const PG8_LAS bf16x8*)(lds + PG8_SA(b, h) + aoff + m * 2048 + k * 1024); } while (0)
; #define PG8_LDB(dst, b, h) do { _Pragma("unroll") for (int n = 0; n < 2; ++n) _Pragma("unroll") for (int k = 0; k < 2; ++k) dst[n][k] = *(const PG8_LAS bf16x8*)(lds + PG8_SB(b, h) + boff + n * 2048 + k * 1024); } while (0)
; #define PG8_MMA(ai, bj, At, Bt) do { __builtin_amdgcn_s_setprio(1); _Pragma("unroll") for (int m = 0; m < 4; ++m) _Pragma("unroll") for (int n = 0; n < 2; ++n) _Pragma("unroll") for (int k = 0; k < 2; ++k) \
;         acc[ai][bj][m][n] = __builtin_amdgcn_mfma_f32_16x16x32_bf16(Bt[n][k], At[m][k], acc[ai][bj][m][n], 0, 0, 0); __builtin_amdgcn_s_setprio(0); } while (0)
; #define PG8_WAIT_V(n) asm volatile("s_waitcnt vmcnt(" #n ")" ::: "memory")
; #define PG8_WAIT_L(n) asm volatile("s_waitcnt lgkmcnt(" #n ")" ::: "memory")
; #define PG8_BAR __builtin_amdgcn_s_barrier()
; #define PG8_SCHED __builtin_amdgcn_sched_barrier(0)
; template <class Epi, class Sched, bool ALIGN_EPI = false, bool SP2 = false>
; __device__ __forceinline__ void gemm_phase(PG8_LAS unsigned char* lds, const Gemm g, const Sched& S, const Epi& E, const int wave_in) {
;     ...
;             PG8_LDB(B0, 0, 0); PG8_LDB(B1, 0, 1); PG8_SCHED; PG8_LDA(At, 0, 0); PG8_STAGE(PG8_SA(1, 1), a1 + hstepA, voffA);
;             PG8_WAIT_V(8); PG8_WAIT_L(0); PG8_BAR; PG8_MMA(0, 0, At, B0); PG8_MMA(0, 1, At, B1); PG8_BAR; PG8_SCHED;
;             PG8_LDA(At, 0, 1); PG8_STAGE(PG8_SB(0, 0), b2, voffB); PG8_STAGE(PG8_SB(0, 1), b2 + hstepB, voffB); PG8_STAGE(PG8_SA(0, 0), a2, voffA);
;             PG8_WAIT_V(8); PG8_WAIT_L(0); PG8_BAR; PG8_MMA(1, 0, At, B0); PG8_MMA(1, 1, At, B1); PG8_BAR; PG8_SCHED;
	s_setprio 1
	s_waitcnt lgkmcnt(0)
	v_mfma_f32_16x16x32_bf16 v[124:127], v[144:147], v[182:185], v[124:127]
	v_mfma_f32_16x16x32_bf16 v[120:123], v[158:161], v[182:185], v[120:123]
	v_mfma_f32_16x16x32_bf16 v[108:111], v[144:147], v[190:193], v[108:111]
	v_mfma_f32_16x16x32_bf16 v[104:107], v[158:161], v[190:193], v[104:107]
	v_mfma_f32_16x16x32_bf16 v[92:95], v[144:147], v[198:201], v[92:95]
	v_mfma_f32_16x16x32_bf16 v[88:91], v[158:161], v[198:201], v[88:91]
	v_mfma_f32_16x16x32_bf16 v[76:79], v[144:147], v[206:209], v[76:79]
	v_mfma_f32_16x16x32_bf16 v[72:75], v[158:161], v[206:209], v[72:75]
	v_mfma_f32_16x16x32_bf16 v[124:127], v[154:157], v[186:189], v[124:127]
	v_mfma_f32_16x16x32_bf16 v[120:123], v[162:165], v[186:189], v[120:123]
	v_mfma_f32_16x16x32_bf16 v[108:111], v[154:157], v[194:197], v[108:111]
	v_mfma_f32_16x16x32_bf16 v[104:107], v[162:165], v[194:197], v[104:107]
	v_mfma_f32_16x16x32_bf16 v[92:95], v[154:157], v[202:205], v[92:95]
	v_mfma_f32_16x16x32_bf16 v[88:91], v[162:165], v[202:205], v[88:91]
	v_mfma_f32_16x16x32_bf16 v[76:79], v[154:157], v[210:213], v[76:79]
	v_mfma_f32_16x16x32_bf16 v[72:75], v[162:165], v[210:213], v[72:75]
	v_mfma_f32_16x16x32_bf16 v[116:119], v[166:169], v[182:185], v[116:119]
	v_mfma_f32_16x16x32_bf16 v[112:115], v[174:177], v[182:185], v[112:115]
	v_mfma_f32_16x16x32_bf16 v[100:103], v[166:169], v[190:193], v[100:103]
	v_mfma_f32_16x16x32_bf16 v[96:99], v[174:177], v[190:193], v[96:99]
	v_mfma_f32_16x16x32_bf16 v[84:87], v[166:169], v[198:201], v[84:87]
	v_mfma_f32_16x16x32_bf16 v[80:83], v[174:177], v[198:201], v[80:83]
	v_mfma_f32_16x16x32_bf16 v[68:71], v[166:169], v[206:209], v[68:71]
	v_mfma_f32_16x16x32_bf16 v[64:67], v[174:177], v[206:209], v[64:67]
	v_mfma_f32_16x16x32_bf16 v[116:119], v[170:173], v[186:189], v[116:119]
	v_mfma_f32_16x16x32_bf16 v[112:115], v[178:181], v[186:189], v[112:115]
	v_mfma_f32_16x16x32_bf16 v[100:103], v[170:173], v[194:197], v[100:103]
	v_mfma_f32_16x16x32_bf16 v[96:99], v[178:181], v[194:197], v[96:99]
	v_mfma_f32_16x16x32_bf16 v[84:87], v[170:173], v[202:205], v[84:87]
	v_mfma_f32_16x16x32_bf16 v[80:83], v[178:181], v[202:205], v[80:83]
	v_mfma_f32_16x16x32_bf16 v[68:71], v[170:173], v[210:213], v[68:71]
	v_mfma_f32_16x16x32_bf16 v[64:67], v[178:181], v[210:213], v[64:67]
	s_setprio 0
	s_barrier
	s_add_i32 s51, s44, s34
	v_lshl_add_u64 v[214:215], s[24:25], 0, v[130:131]
	s_mov_b32 m0, s51
	ds_read_b128 v[182:185], v153 offset:16384
	ds_read_b128 v[186:189], v153 offset:17408
	ds_read_b128 v[190:193], v153 offset:18432
	ds_read_b128 v[194:197], v153 offset:19456
	ds_read_b128 v[198:201], v153 offset:20480
	ds_read_b128 v[202:205], v153 offset:21504
	ds_read_b128 v[206:209], v153 offset:22528
	ds_read_b128 v[210:213], v153 offset:23552
	global_load_lds_dwordx4 v[214:215], off
	s_add_i32 m0, s51, 0x2000
	s_add_u32 s52, s24, 0x80000
	v_lshl_add_u64 v[216:217], s[24:25], 0, v[134:135]
	s_addc_u32 s53, s25, 0
	s_add_i32 s51, s45, s34
	global_load_lds_dwordx4 v[216:217], off
	v_lshl_add_u64 v[218:219], s[52:53], 0, v[130:131]
	s_mov_b32 m0, s51
	v_lshl_add_u64 v[220:221], s[26:27], 0, v[132:133]
	global_load_lds_dwordx4 v[218:219], off
	v_lshl_add_u64 v[218:219], s[52:53], 0, v[134:135]
	s_add_i32 m0, s51, 0x2000
	s_nop 0
	global_load_lds_dwordx4 v[218:219], off
	v_lshl_add_u64 v[218:219], s[26:27], 0, v[128:129]
	s_mov_b32 m0, s21
	s_nop 0
	global_load_lds_dwordx4 v[218:219], off
	s_mov_b32 m0, s35
	s_nop 0
	global_load_lds_dwordx4 v[220:221], off
	s_waitcnt vmcnt(8)
	s_waitcnt lgkmcnt(0)
	s_barrier
	s_setprio 1
	s_waitcnt lgkmcnt(0)
	v_mfma_f32_16x16x32_bf16 v[60:63], v[144:147], v[182:185], v[60:63]
	v_mfma_f32_16x16x32_bf16 v[56:59], v[158:161], v[182:185], v[56:59]
	v_mfma_f32_16x16x32_bf16 v[44:47], v[144:147], v[190:193], v[44:47]
	v_mfma_f32_16x16x32_bf16 v[40:43], v[158:161], v[190:193], v[40:43]
	v_mfma_f32_16x16x32_bf16 v[28:31], v[144:147], v[198:201], v[28:31]
	v_mfma_f32_16x16x32_bf16 v[24:27], v[158:161], v[198:201], v[24:27]
	v_mfma_f32_16x16x32_bf16 v[12:15], v[144:147], v[206:209], v[12:15]
	v_mfma_f32_16x16x32_bf16 v[8:11], v[158:161], v[206:209], v[8:11]
	v_mfma_f32_16x16x32_bf16 v[60:63], v[154:157], v[186:189], v[60:63]
	v_mfma_f32_16x16x32_bf16 v[56:59], v[162:165], v[186:189], v[56:59]
	v_mfma_f32_16x16x32_bf16 v[44:47], v[154:157], v[194:197], v[44:47]
	v_mfma_f32_16x16x32_bf16 v[40:43], v[162:165], v[194:197], v[40:43]
	v_mfma_f32_16x16x32_bf16 v[28:31], v[154:157], v[202:205], v[28:31]
	v_mfma_f32_16x16x32_bf16 v[24:27], v[162:165], v[202:205], v[24:27]
	v_mfma_f32_16x16x32_bf16 v[12:15], v[154:157], v[210:213], v[12:15]
	v_mfma_f32_16x16x32_bf16 v[8:11], v[162:165], v[210:213], v[8:11]
	v_mfma_f32_16x16x32_bf16 v[52:55], v[166:169], v[182:185], v[52:55]
	v_mfma_f32_16x16x32_bf16 v[48:51], v[174:177], v[182:185], v[48:51]
	v_mfma_f32_16x16x32_bf16 v[36:39], v[166:169], v[190:193], v[36:39]
	v_mfma_f32_16x16x32_bf16 v[32:35], v[174:177], v[190:193], v[32:35]
	v_mfma_f32_16x16x32_bf16 v[20:23], v[166:169], v[198:201], v[20:23]
	v_mfma_f32_16x16x32_bf16 v[16:19], v[174:177], v[198:201], v[16:19]
	v_mfma_f32_16x16x32_bf16 v[4:7], v[166:169], v[206:209], v[4:7]
	v_mfma_f32_16x16x32_bf16 v[0:3], v[174:177], v[206:209], v[0:3]
	v_mfma_f32_16x16x32_bf16 v[52:55], v[170:173], v[186:189], v[52:55]
	v_mfma_f32_16x16x32_bf16 v[48:51], v[178:181], v[186:189], v[48:51]
	v_mfma_f32_16x16x32_bf16 v[36:39], v[170:173], v[194:197], v[36:39]
	v_mfma_f32_16x16x32_bf16 v[32:35], v[178:181], v[194:197], v[32:35]
	v_mfma_f32_16x16x32_bf16 v[20:23], v[170:173], v[202:205], v[20:23]
	v_mfma_f32_16x16x32_bf16 v[16:19], v[178:181], v[202:205], v[16:19]
	v_mfma_f32_16x16x32_bf16 v[4:7], v[170:173], v[210:213], v[4:7]
	v_mfma_f32_16x16x32_bf16 v[0:3], v[178:181], v[210:213], v[0:3]
	s_setprio 0
	s_barrier
; #define PG8_STAGE(bufoff, gbase, voff) do { _Pragma("unroll") for (int _i = 0; _i < 2; ++_i) \
;         __builtin_amdgcn_global_load_lds((const unsigned*)((const char*)(gbase) + (voff)[_i]), (PG8_LAS unsigned*)(lds + (bufoff) + ldsw + _i * 8192), 16, 0, 0); } while (0)
; #define PG8_LDA(dst, b, h) do { _Pragma("unroll") for (int m = 0; m < 4; ++m) _Pragma("unroll") for (int k = 0; k < 2; ++k) dst[m][k] = *(const PG8_LAS bf16x8*)(lds + PG8_SA(b, h) + aoff + m * 2048 + k * 1024); } while (0)
; #define PG8_LDB(dst, b, h) do { _Pragma("unroll") for (int n = 0; n < 2; ++n) _Pragma("unroll") for (int k = 0; k < 2; ++k) dst[n][k] = *(const PG8_LAS bf16x8*)(lds + PG8_SB(b, h) + boff + n * 2048 + k * 1024); } while (0)
; #define PG8_MMA(ai, bj, At, Bt) do { __builtin_amdgcn_s_setprio(1); _Pragma("unroll") for (int m = 0; m < 4; ++m) _Pragma("unroll") for (int n = 0; n < 2; ++n) _Pragma("unroll") for (int k = 0; k < 2; ++k) \
;         acc[ai][bj][m][n] = __builtin_amdgcn_mfma_f32_16x16x32_bf16(Bt[n][k], At[m][k], acc[ai][bj][m][n], 0, 0, 0); __builtin_amdgcn_s_setprio(0); } while (0)
; #define PG8_WAIT_V(n) asm volatile("s_waitcnt vmcnt(" #n ")" ::: "memory")
; #define PG8_WAIT_L(n) asm volatile("s_waitcnt lgkmcnt(" #n ")" ::: "memory")
; #define PG8_BAR __builtin_amdgcn_s_barrier()
; #define PG8_SCHED __builtin_amdgcn_sched_barrier(0)
; template <class Epi, class Sched, bool ALIGN_EPI = false, bool SP2 = false>
; __device__ __forceinline__ void gemm_phase(PG8_LAS unsigned char* lds, const Gemm g, const Sched& S, const Epi& E, const int wave_in) {
;     ...
;             PG8_LDB(B0, 1, 0); PG8_LDB(B1, 1, 1); PG8_SCHED; PG8_LDA(At, 1, 0); PG8_STAGE(PG8_SA(0, 1), a2 + hstepA, voffA);
;             PG8_WAIT_V(8); PG8_WAIT_L(0); PG8_BAR; PG8_MMA(0, 0, At, B0); PG8_MMA(0, 1, At, B1); PG8_BAR; PG8_SCHED;
	s_add_i32 s51, 0, 0x18000
	s_add_i32 s52, 0, 0x1c000
	v_add_u32_e32 v162, s51, v149
	v_add_u32_e32 v178, s52, v149
	ds_read_b128 v[144:147], v162
	ds_read_b128 v[154:157], v162 offset:1024
	ds_read_b128 v[158:161], v162 offset:2048
	ds_read_b128 v[162:165], v162 offset:3072
	ds_read_b128 v[166:169], v178
	ds_read_b128 v[170:173], v178 offset:1024
	ds_read_b128 v[174:177], v178 offset:2048
	ds_read_b128 v[178:181], v178 offset:3072
	s_add_u32 s26, s26, 0x80000
	s_addc_u32 s27, s27, 0
	s_mov_b32 m0, s36
	v_lshl_add_u64 v[222:223], s[26:27], 0, v[128:129]
	ds_read_b128 v[182:185], v153 offset:32768
	ds_read_b128 v[186:189], v153 offset:33792
	ds_read_b128 v[190:193], v153 offset:34816
	ds_read_b128 v[194:197], v153 offset:35840
	ds_read_b128 v[198:201], v153 offset:36864
	ds_read_b128 v[202:205], v153 offset:37888
	ds_read_b128 v[206:209], v153 offset:38912
	ds_read_b128 v[210:213], v153 offset:39936
	global_load_lds_dwordx4 v[222:223], off
	v_lshl_add_u64 v[222:223], s[26:27], 0, v[132:133]
	s_mov_b32 m0, s37
	s_nop 0
	global_load_lds_dwordx4 v[222:223], off
	s_waitcnt vmcnt(8)
	s_waitcnt lgkmcnt(0)
	s_barrier
	s_setprio 1
	s_waitcnt lgkmcnt(0)
	v_mfma_f32_16x16x32_bf16 v[124:127], v[144:147], v[182:185], v[124:127]
	v_mfma_f32_16x16x32_bf16 v[120:123], v[158:161], v[182:185], v[120:123]
	v_mfma_f32_16x16x32_bf16 v[108:111], v[144:147], v[190:193], v[108:111]
	v_mfma_f32_16x16x32_bf16 v[104:107], v[158:161], v[190:193], v[104:107]
	v_mfma_f32_16x16x32_bf16 v[92:95], v[144:147], v[198:201], v[92:95]
	v_mfma_f32_16x16x32_bf16 v[88:91], v[158:161], v[198:201], v[88:91]
	v_mfma_f32_16x16x32_bf16 v[76:79], v[144:147], v[206:209], v[76:79]
	v_mfma_f32_16x16x32_bf16 v[72:75], v[158:161], v[206:209], v[72:75]
	v_mfma_f32_16x16x32_bf16 v[124:127], v[154:157], v[186:189], v[124:127]
	v_mfma_f32_16x16x32_bf16 v[120:123], v[162:165], v[186:189], v[120:123]
	v_mfma_f32_16x16x32_bf16 v[108:111], v[154:157], v[194:197], v[108:111]
	v_mfma_f32_16x16x32_bf16 v[104:107], v[162:165], v[194:197], v[104:107]
	v_mfma_f32_16x16x32_bf16 v[92:95], v[154:157], v[202:205], v[92:95]
	v_mfma_f32_16x16x32_bf16 v[88:91], v[162:165], v[202:205], v[88:91]
	v_mfma_f32_16x16x32_bf16 v[76:79], v[154:157], v[210:213], v[76:79]
	v_mfma_f32_16x16x32_bf16 v[72:75], v[162:165], v[210:213], v[72:75]
	v_mfma_f32_16x16x32_bf16 v[116:119], v[166:169], v[182:185], v[116:119]
	v_mfma_f32_16x16x32_bf16 v[112:115], v[174:177], v[182:185], v[112:115]
	v_mfma_f32_16x16x32_bf16 v[100:103], v[166:169], v[190:193], v[100:103]
	v_mfma_f32_16x16x32_bf16 v[96:99], v[174:177], v[190:193], v[96:99]
	v_mfma_f32_16x16x32_bf16 v[84:87], v[166:169], v[198:201], v[84:87]
	v_mfma_f32_16x16x32_bf16 v[80:83], v[174:177], v[198:201], v[80:83]
	v_mfma_f32_16x16x32_bf16 v[68:71], v[166:169], v[206:209], v[68:71]
	v_mfma_f32_16x16x32_bf16 v[64:67], v[174:177], v[206:209], v[64:67]
	v_mfma_f32_16x16x32_bf16 v[116:119], v[170:173], v[186:189], v[116:119]
	v_mfma_f32_16x16x32_bf16 v[112:115], v[178:181], v[186:189], v[112:115]
	v_mfma_f32_16x16x32_bf16 v[100:103], v[170:173], v[194:197], v[100:103]
	v_mfma_f32_16x16x32_bf16 v[96:99], v[178:181], v[194:197], v[96:99]
	v_mfma_f32_16x16x32_bf16 v[84:87], v[170:173], v[202:205], v[84:87]
	v_mfma_f32_16x16x32_bf16 v[80:83], v[178:181], v[202:205], v[80:83]
	v_mfma_f32_16x16x32_bf16 v[68:71], v[170:173], v[210:213], v[68:71]
	v_mfma_f32_16x16x32_bf16 v[64:67], v[178:181], v[210:213], v[64:67]
	s_setprio 0
	s_barrier
; #define PG8_STAGE(bufoff, gbase, voff) do { _Pragma("unroll") for (int _i = 0; _i < 2; ++_i) \
;         __builtin_amdgcn_global_load_lds((const unsigned*)((const char*)(gbase) + (voff)[_i]), (PG8_LAS unsigned*)(lds + (bufoff) + ldsw + _i * 8192), 16, 0, 0); } while (0)
; #define PG8_LDA(dst, b, h) do { _Pragma("unroll") for (int m = 0; m < 4; ++m) _Pragma("unroll") for (int k = 0; k < 2; ++k) dst[m][k] = *(const PG8_LAS bf16x8*)(lds + PG8_SA(b, h) + aoff + m * 2048 + k * 1024); } while (0)
; #define PG8_MMA(ai, bj, At, Bt) do { __builtin_amdgcn_s_setprio(1); _Pragma("unroll") for (int m = 0; m < 4; ++m) _Pragma("unroll") for (int n = 0; n < 2; ++n) _Pragma("unroll") for (int k = 0; k < 2; ++k) \
;         acc[ai][bj][m][n] = __builtin_amdgcn_mfma_f32_16x16x32_bf16(Bt[n][k], At[m][k], acc[ai][bj][m][n], 0, 0, 0); __builtin_amdgcn_s_setprio(0); } while (0)
; #define PG8_WAIT_V(n) asm volatile("s_waitcnt vmcnt(" #n ")" ::: "memory")
; #define PG8_WAIT_L(n) asm volatile("s_waitcnt lgkmcnt(" #n ")" ::: "memory")
; #define PG8_BAR __builtin_amdgcn_s_barrier()
; #define PG8_SCHED __builtin_amdgcn_sched_barrier(0)
; template <class Epi, class Sched, bool ALIGN_EPI = false, bool SP2 = false>
; __device__ __forceinline__ void gemm_phase(PG8_LAS unsigned char* lds, const Gemm g, const Sched& S, const Epi& E, const int wave_in) {
;     ...
;         for (int t = 0; t < nt; t += 2) {
;             const bool last = (t == nt - 2);
;             const char* a1 = cA + (size_t)(t + 1) * kstep;
;             const char* a2 = last ? nA : cA + (size_t)(t + 2) * kstep; const char* b2 = last ? nB : cB + (size_t)(t + 2) * kstep;
;     ...
;             PG8_LDA(At, 1, 1); PG8_STAGE(PG8_SB(1, 0), b3, voffB); PG8_STAGE(PG8_SB(1, 1), b3 + hstepB, voffB); PG8_STAGE(PG8_SA(1, 0), a3, voffA);
;             PG8_WAIT_V(8); PG8_WAIT_L(0); PG8_BAR; PG8_MMA(1, 0, At, B0); PG8_MMA(1, 1, At, B1); PG8_BAR; PG8_SCHED;
	s_add_i32 s26, s51, s34
	v_lshl_add_u64 v[214:215], v[214:215], 0, s[8:9]
	s_mov_b32 m0, s26
	ds_read_b128 v[182:185], v153 offset:49152
	ds_read_b128 v[186:189], v153 offset:50176
	ds_read_b128 v[190:193], v153 offset:51200
	ds_read_b128 v[194:197], v153 offset:52224
	ds_read_b128 v[198:201], v153 offset:53248
	ds_read_b128 v[202:205], v153 offset:54272
	ds_read_b128 v[206:209], v153 offset:55296
	ds_read_b128 v[210:213], v153 offset:56320
	global_load_lds_dwordx4 v[214:215], off
	s_add_i32 m0, s26, 0x2000
	s_add_u32 s24, s24, 0x80080
	v_lshl_add_u64 v[214:215], v[216:217], 0, s[8:9]
	s_addc_u32 s25, s25, 0
	s_add_i32 s26, s52, s34
	global_load_lds_dwordx4 v[214:215], off
	v_lshl_add_u64 v[214:215], s[24:25], 0, v[130:131]
	s_mov_b32 m0, s26
	s_nop 0
	global_load_lds_dwordx4 v[214:215], off
	v_lshl_add_u64 v[214:215], s[24:25], 0, v[134:135]
	s_add_i32 m0, s26, 0x2000
	s_nop 0
	global_load_lds_dwordx4 v[214:215], off
	v_lshl_add_u64 v[214:215], v[218:219], 0, s[8:9]
	s_mov_b32 m0, s39
	s_nop 0
	global_load_lds_dwordx4 v[214:215], off
	v_lshl_add_u64 v[214:215], v[220:221], 0, s[8:9]
	s_mov_b32 m0, s40
	s_nop 0
	global_load_lds_dwordx4 v[214:215], off
	s_waitcnt vmcnt(8)
	s_waitcnt lgkmcnt(0)
	s_barrier
	s_setprio 1
	s_waitcnt lgkmcnt(0)
	v_mfma_f32_16x16x32_bf16 v[60:63], v[144:147], v[182:185], v[60:63]
	v_mfma_f32_16x16x32_bf16 v[56:59], v[158:161], v[182:185], v[56:59]
	v_mfma_f32_16x16x32_bf16 v[44:47], v[144:147], v[190:193], v[44:47]
	v_mfma_f32_16x16x32_bf16 v[40:43], v[158:161], v[190:193], v[40:43]
	v_mfma_f32_16x16x32_bf16 v[28:31], v[144:147], v[198:201], v[28:31]
	v_mfma_f32_16x16x32_bf16 v[24:27], v[158:161], v[198:201], v[24:27]
	v_mfma_f32_16x16x32_bf16 v[12:15], v[144:147], v[206:209], v[12:15]
	v_mfma_f32_16x16x32_bf16 v[8:11], v[158:161], v[206:209], v[8:11]
	v_mfma_f32_16x16x32_bf16 v[60:63], v[154:157], v[186:189], v[60:63]
	v_mfma_f32_16x16x32_bf16 v[56:59], v[162:165], v[186:189], v[56:59]
	v_mfma_f32_16x16x32_bf16 v[44:47], v[154:157], v[194:197], v[44:47]
	v_mfma_f32_16x16x32_bf16 v[40:43], v[162:165], v[194:197], v[40:43]
	v_mfma_f32_16x16x32_bf16 v[28:31], v[154:157], v[202:205], v[28:31]
	v_mfma_f32_16x16x32_bf16 v[24:27], v[162:165], v[202:205], v[24:27]
	v_mfma_f32_16x16x32_bf16 v[12:15], v[154:157], v[210:213], v[12:15]
	v_mfma_f32_16x16x32_bf16 v[8:11], v[162:165], v[210:213], v[8:11]
	v_mfma_f32_16x16x32_bf16 v[52:55], v[166:169], v[182:185], v[52:55]
	v_mfma_f32_16x16x32_bf16 v[48:51], v[174:177], v[182:185], v[48:51]
	v_mfma_f32_16x16x32_bf16 v[36:39], v[166:169], v[190:193], v[36:39]
	v_mfma_f32_16x16x32_bf16 v[32:35], v[174:177], v[190:193], v[32:35]
	v_mfma_f32_16x16x32_bf16 v[20:23], v[166:169], v[198:201], v[20:23]
	v_mfma_f32_16x16x32_bf16 v[16:19], v[174:177], v[198:201], v[16:19]
	v_mfma_f32_16x16x32_bf16 v[4:7], v[166:169], v[206:209], v[4:7]
	v_mfma_f32_16x16x32_bf16 v[0:3], v[174:177], v[206:209], v[0:3]
	v_mfma_f32_16x16x32_bf16 v[52:55], v[170:173], v[186:189], v[52:55]
	v_mfma_f32_16x16x32_bf16 v[48:51], v[178:181], v[186:189], v[48:51]
	v_mfma_f32_16x16x32_bf16 v[36:39], v[170:173], v[194:197], v[36:39]
	v_mfma_f32_16x16x32_bf16 v[32:35], v[178:181], v[194:197], v[32:35]
	v_mfma_f32_16x16x32_bf16 v[20:23], v[170:173], v[202:205], v[20:23]
	v_mfma_f32_16x16x32_bf16 v[16:19], v[178:181], v[202:205], v[16:19]
	v_mfma_f32_16x16x32_bf16 v[4:7], v[170:173], v[210:213], v[4:7]
	v_mfma_f32_16x16x32_bf16 v[0:3], v[178:181], v[210:213], v[0:3]
	s_setprio 0
	s_barrier
	s_add_i32 s50, s50, 2
	s_add_u32 s22, s22, 0x100
	s_addc_u32 s23, s23, 0
	s_add_u32 s48, s48, 0x100
	s_addc_u32 s49, s49, 0
	s_cmp_gt_u32 s50, 29
	s_cbranch_scc0 .LBB0_2248

;     __host__ __device__ bool next(int i, Unit& u) const { const bool ok = StaticOrder::next(i, u); u.pm = 0; u.pn = 0; return ok; }
; #define PG8_STAGE(bufoff, gbase, voff) do { _Pragma("unroll") for (int _i = 0; _i < 2; ++_i) \
;         __builtin_amdgcn_global_load_lds((const unsigned*)((const char*)(gbase) + (voff)[_i]), (PG8_LAS unsigned*)(lds + (bufoff) + ldsw + _i * 8192), 16, 0, 0); } while (0)
; #define PG8_LDA(dst, b, h) do { _Pragma("unroll") for (int m = 0; m < 4; ++m) _Pragma("unroll") for (int k = 0; k < 2; ++k) dst[m][k] = *(const PG8_LAS bf16x8*)(lds + PG8_SA(b, h) + aoff + m * 2048 + k * 1024); } while (0)
; #define PG8_LDB(dst, b, h) do { _Pragma("unroll") for (int n = 0; n < 2; ++n) _Pragma("unroll") for (int k = 0; k < 2; ++k) dst[n][k] = *(const PG8_LAS bf16x8*)(lds + PG8_SB(b, h) + boff + n * 2048 + k * 1024); } while (0)
; #define PG8_WAIT_V(n) asm volatile("s_waitcnt vmcnt(" #n ")" ::: "memory")
; #define PG8_BAR __builtin_amdgcn_s_barrier()
; template <class Epi, class Sched, bool ALIGN_EPI = false, bool SP2 = false>
; __device__ __forceinline__ void gemm_phase(PG8_LAS unsigned char* lds, const Gemm g, const Sched& S, const Epi& E, const int wave_in) {
;     ...
;         const bool has_next = S.next(ui + 1, nxt);
;         const char* nA = has_next ? (const char*)g.A + (size_t)nxt.pm * tstepA : cA; const char* nB = has_next ? (const char*)g.Bt + (size_t)nxt.pn * tstepB : cB;
;         for (int t = 0; t < nt; t += 2) {
;             const bool last = (t == nt - 2);
;             const char* a1 = cA + (size_t)(t + 1) * kstep;
;             const char* a2 = last ? nA : cA + (size_t)(t + 2) * kstep; const char* b2 = last ? nB : cB + (size_t)(t + 2) * kstep;
;             const char* a3 = a2 + kstep; const char* b3 = b2 + kstep;
;             if (last && has_next) S.a_ready(nxt);
;             if constexpr (SP2) {
;             PG8_LDB(B0, 0, 0); PG8_LDB(B1, 0, 1); PG8_SCHED; PG8_LDA(At, 0, 0); PG8_STAGE(PG8_SA(1, 1), a1 + hstepA, voffA);
;             PG8_WAIT_V(8); PG8_WAIT_L(0); PG8_BAR; PG8_MMA(0, 0, At, B0); PG8_MMA(0, 1, At, B1); PG8_BAR; PG8_SCHED;
;             PG8_LDA(At, 0, 1); PG8_STAGE(PG8_SB(0, 0), b2, voffB); PG8_STAGE(PG8_SB(0, 1), b2 + hstepB, voffB); PG8_STAGE(PG8_SA(0, 0), a2, voffA);
;             PG8_WAIT_V(8); PG8_WAIT_L(0); PG8_BAR; PG8_MMA(1, 0, At, B0); PG8_MMA(1, 1, At, B1); PG8_BAR; PG8_SCHED;
.LBB0_2450:
	s_ashr_i32 s19, s18, 31
	s_lshl_b64 s[22:23], s[18:19], 20
	s_add_u32 s22, s37, s22
	s_addc_u32 s23, s38, s23
	s_and_b64 s[4:5], s[4:5], exec
	s_cselect_b32 s19, s23, s29
	s_cselect_b32 s25, s22, s28
	s_add_u32 s58, s28, 0x100
	v_mov_b32_e32 v0, 0
	s_addc_u32 s59, s29, 0
	s_mov_b32 s60, -2
	s_waitcnt vmcnt(0)
	ds_read_b128 v[128:131], v170
	ds_read_b128 v[132:135], v170 offset:1024
	ds_read_b128 v[136:139], v170 offset:2048
	ds_read_b128 v[140:143], v170 offset:3072
	ds_read_b128 v[162:165], v171
	ds_read_b128 v[174:177], v171 offset:1024
	ds_read_b128 v[178:181], v171 offset:2048
	ds_read_b128 v[182:185], v171 offset:3072
	s_add_u32 s4, s26, 0x100
	s_addc_u32 s5, s27, 0
	s_cmp_eq_u32 s60, 28
	s_cselect_b32 s31, s21, s5
	s_cselect_b32 s30, s20, s4
	s_cselect_b32 s29, s19, s59
	s_cselect_b32 s28, s25, s58
	v_lshl_add_u64 v[166:167], s[26:27], 0, v[154:155]
	s_add_i32 m0, s40, 0xc000
	ds_read_b128 v[186:189], v172
	ds_read_b128 v[190:193], v172 offset:1024
	ds_read_b128 v[194:197], v172 offset:2048
	ds_read_b128 v[198:201], v172 offset:3072
	ds_read_b128 v[202:205], v172 offset:4096
	ds_read_b128 v[206:209], v172 offset:5120
	ds_read_b128 v[210:213], v172 offset:6144
	ds_read_b128 v[214:217], v172 offset:7168
	global_load_lds_dwordx4 v[166:167], off
	v_lshl_add_u64 v[166:167], s[26:27], 0, v[156:157]
	s_add_i32 m0, s40, 0xe000
	s_nop 0
	global_load_lds_dwordx4 v[166:167], off
	s_waitcnt vmcnt(8)
	s_waitcnt lgkmcnt(0)
	s_barrier
	s_setprio 1
	s_waitcnt lgkmcnt(0)
	v_mfma_f32_16x16x32_bf16 v[124:127], v[128:131], v[186:189], 0
	v_mfma_f32_16x16x32_bf16 v[120:123], v[136:139], v[186:189], 0
	v_mfma_f32_16x16x32_bf16 v[112:115], v[128:131], v[194:197], 0
	v_mfma_f32_16x16x32_bf16 v[104:107], v[136:139], v[194:197], 0
	v_mfma_f32_16x16x32_bf16 v[96:99], v[128:131], v[202:205], 0
	v_mfma_f32_16x16x32_bf16 v[88:91], v[136:139], v[202:205], 0
	v_mfma_f32_16x16x32_bf16 v[80:83], v[128:131], v[210:213], 0
	v_mfma_f32_16x16x32_bf16 v[72:75], v[136:139], v[210:213], 0
	v_mfma_f32_16x16x32_bf16 v[124:127], v[132:135], v[190:193], v[124:127]
	v_mfma_f32_16x16x32_bf16 v[120:123], v[140:143], v[190:193], v[120:123]
	v_mfma_f32_16x16x32_bf16 v[112:115], v[132:135], v[198:201], v[112:115]
	v_mfma_f32_16x16x32_bf16 v[104:107], v[140:143], v[198:201], v[104:107]
	v_mfma_f32_16x16x32_bf16 v[96:99], v[132:135], v[206:209], v[96:99]
	v_mfma_f32_16x16x32_bf16 v[88:91], v[140:143], v[206:209], v[88:91]
	v_mfma_f32_16x16x32_bf16 v[80:83], v[132:135], v[214:217], v[80:83]
	v_mfma_f32_16x16x32_bf16 v[72:75], v[140:143], v[214:217], v[72:75]
	v_mfma_f32_16x16x32_bf16 v[116:119], v[162:165], v[186:189], 0
	v_mfma_f32_16x16x32_bf16 v[108:111], v[178:181], v[186:189], 0
	v_mfma_f32_16x16x32_bf16 v[100:103], v[162:165], v[194:197], 0
	v_mfma_f32_16x16x32_bf16 v[92:95], v[178:181], v[194:197], 0
	v_mfma_f32_16x16x32_bf16 v[84:87], v[162:165], v[202:205], 0
	v_mfma_f32_16x16x32_bf16 v[76:79], v[178:181], v[202:205], 0
	v_mfma_f32_16x16x32_bf16 v[68:71], v[162:165], v[210:213], 0
	v_mfma_f32_16x16x32_bf16 v[64:67], v[178:181], v[210:213], 0
	v_mfma_f32_16x16x32_bf16 v[116:119], v[174:177], v[190:193], v[116:119]
	v_mfma_f32_16x16x32_bf16 v[108:111], v[182:185], v[190:193], v[108:111]
	v_mfma_f32_16x16x32_bf16 v[100:103], v[174:177], v[198:201], v[100:103]
	v_mfma_f32_16x16x32_bf16 v[92:95], v[182:185], v[198:201], v[92:95]
	v_mfma_f32_16x16x32_bf16 v[84:87], v[174:177], v[206:209], v[84:87]
	v_mfma_f32_16x16x32_bf16 v[76:79], v[182:185], v[206:209], v[76:79]
	v_mfma_f32_16x16x32_bf16 v[68:71], v[174:177], v[214:217], v[68:71]
	v_mfma_f32_16x16x32_bf16 v[64:67], v[182:185], v[214:217], v[64:67]
	s_setprio 0
	s_barrier
	s_add_i32 s26, s50, s39
	v_lshl_add_u64 v[166:167], s[28:29], 0, v[146:147]
	s_mov_b32 m0, s26
	ds_read_b128 v[186:189], v172 offset:16384
	ds_read_b128 v[190:193], v172 offset:17408
	ds_read_b128 v[194:197], v172 offset:18432
	ds_read_b128 v[198:201], v172 offset:19456
	ds_read_b128 v[202:205], v172 offset:20480
	ds_read_b128 v[206:209], v172 offset:21504
	ds_read_b128 v[210:213], v172 offset:22528
	ds_read_b128 v[214:217], v172 offset:23552
	global_load_lds_dwordx4 v[166:167], off
	s_add_i32 m0, s26, 0x2000
	s_add_u32 s26, s28, 0x80000
	v_lshl_add_u64 v[218:219], s[28:29], 0, v[150:151]
	s_addc_u32 s27, s29, 0
	s_add_i32 s61, s51, s39
	global_load_lds_dwordx4 v[218:219], off
	v_lshl_add_u64 v[220:221], s[26:27], 0, v[146:147]
	s_mov_b32 m0, s61
	v_lshl_add_u64 v[222:223], s[30:31], 0, v[148:149]
	global_load_lds_dwordx4 v[220:221], off
	v_lshl_add_u64 v[220:221], s[26:27], 0, v[150:151]
	s_add_i32 m0, s61, 0x2000
	s_nop 0
	global_load_lds_dwordx4 v[220:221], off
	v_lshl_add_u64 v[220:221], s[30:31], 0, v[144:145]
	s_mov_b32 m0, s40
	s_nop 0
	global_load_lds_dwordx4 v[220:221], off
	s_mov_b32 m0, s41
	s_nop 0
	global_load_lds_dwordx4 v[222:223], off
	s_waitcnt vmcnt(8)
	s_waitcnt lgkmcnt(0)
	s_barrier
; #define PG8_STAGE(bufoff, gbase, voff) do { _Pragma("unroll") for (int _i = 0; _i < 2; ++_i) \
;         __builtin_amdgcn_global_load_lds((const unsigned*)((const char*)(gbase) + (voff)[_i]), (PG8_LAS unsigned*)(lds + (bufoff) + ldsw + _i * 8192), 16, 0, 0); } while (0)
; #define PG8_LDA(dst, b, h) do { _Pragma("unroll") for (int m = 0; m < 4; ++m) _Pragma("unroll") for (int k = 0; k < 2; ++k) dst[m][k] = *(const PG8_LAS bf16x8*)(lds + PG8_SA(b, h) + aoff + m * 2048 + k * 1024); } while (0)
; #define PG8_LDB(dst, b, h) do { _Pragma("unroll") for (int n = 0; n < 2; ++n) _Pragma("unroll") for (int k = 0; k < 2; ++k) dst[n][k] = *(const PG8_LAS bf16x8*)(lds + PG8_SB(b, h) + boff + n * 2048 + k * 1024); } while (0)
; #define PG8_MMA(ai, bj, At, Bt) do { __builtin_amdgcn_s_setprio(1); _Pragma("unroll") for (int m = 0; m < 4; ++m) _Pragma("unroll") for (int n = 0; n < 2; ++n) _Pragma("unroll") for (int k = 0; k < 2; ++k) \
;         acc[ai][bj][m][n] = __builtin_amdgcn_mfma_f32_16x16x32_bf16(Bt[n][k], At[m][k], acc[ai][bj][m][n], 0, 0, 0); __builtin_amdgcn_s_setprio(0); } while (0)
; #define PG8_WAIT_V(n) asm volatile("s_waitcnt vmcnt(" #n ")" ::: "memory")
; #define PG8_WAIT_L(n) asm volatile("s_waitcnt lgkmcnt(" #n ")" ::: "memory")
; #define PG8_BAR __builtin_amdgcn_s_barrier()
; #define PG8_SCHED __builtin_amdgcn_sched_barrier(0)
; template <class Epi, class Sched, bool ALIGN_EPI = false, bool SP2 = false>
; __device__ __forceinline__ void gemm_phase(PG8_LAS unsigned char* lds, const Gemm g, const Sched& S, const Epi& E, const int wave_in) {
;     ...
;             PG8_LDA(At, 0, 1); PG8_STAGE(PG8_SB(0, 0), b2, voffB); PG8_STAGE(PG8_SB(0, 1), b2 + hstepB, voffB); PG8_STAGE(PG8_SA(0, 0), a2, voffA);
;             PG8_WAIT_V(8); PG8_WAIT_L(0); PG8_BAR; PG8_MMA(1, 0, At, B0); PG8_MMA(1, 1, At, B1); PG8_BAR; PG8_SCHED;
;             PG8_LDB(B0, 1, 0); PG8_LDB(B1, 1, 1); PG8_SCHED; PG8_LDA(At, 1, 0); PG8_STAGE(PG8_SA(0, 1), a2 + hstepA, voffA);
;             PG8_WAIT_V(8); PG8_WAIT_L(0); PG8_BAR; PG8_MMA(0, 0, At, B0); PG8_MMA(0, 1, At, B1); PG8_BAR; PG8_SCHED;
	s_setprio 1
	s_waitcnt lgkmcnt(0)
	v_mfma_f32_16x16x32_bf16 v[60:63], v[128:131], v[186:189], 0
	v_mfma_f32_16x16x32_bf16 v[56:59], v[136:139], v[186:189], 0
	v_mfma_f32_16x16x32_bf16 v[48:51], v[128:131], v[194:197], 0
	v_mfma_f32_16x16x32_bf16 v[40:43], v[136:139], v[194:197], 0
	v_mfma_f32_16x16x32_bf16 v[32:35], v[128:131], v[202:205], 0
	v_mfma_f32_16x16x32_bf16 v[24:27], v[136:139], v[202:205], 0
	v_mfma_f32_16x16x32_bf16 v[16:19], v[128:131], v[210:213], 0
	v_mfma_f32_16x16x32_bf16 v[8:11], v[136:139], v[210:213], 0
	v_mfma_f32_16x16x32_bf16 v[60:63], v[132:135], v[190:193], v[60:63]
	v_mfma_f32_16x16x32_bf16 v[56:59], v[140:143], v[190:193], v[56:59]
	v_mfma_f32_16x16x32_bf16 v[48:51], v[132:135], v[198:201], v[48:51]
	v_mfma_f32_16x16x32_bf16 v[40:43], v[140:143], v[198:201], v[40:43]
	v_mfma_f32_16x16x32_bf16 v[32:35], v[132:135], v[206:209], v[32:35]
	v_mfma_f32_16x16x32_bf16 v[24:27], v[140:143], v[206:209], v[24:27]
	v_mfma_f32_16x16x32_bf16 v[16:19], v[132:135], v[214:217], v[16:19]
	v_mfma_f32_16x16x32_bf16 v[8:11], v[140:143], v[214:217], v[8:11]
	v_mfma_f32_16x16x32_bf16 v[52:55], v[162:165], v[186:189], 0
	v_mfma_f32_16x16x32_bf16 v[44:47], v[178:181], v[186:189], 0
	v_mfma_f32_16x16x32_bf16 v[36:39], v[162:165], v[194:197], 0
	v_mfma_f32_16x16x32_bf16 v[28:31], v[178:181], v[194:197], 0
	v_mfma_f32_16x16x32_bf16 v[20:23], v[162:165], v[202:205], 0
	v_mfma_f32_16x16x32_bf16 v[12:15], v[178:181], v[202:205], 0
	v_mfma_f32_16x16x32_bf16 v[4:7], v[162:165], v[210:213], 0
	v_mfma_f32_16x16x32_bf16 v[0:3], v[178:181], v[210:213], 0
	v_mfma_f32_16x16x32_bf16 v[52:55], v[174:177], v[190:193], v[52:55]
	v_mfma_f32_16x16x32_bf16 v[44:47], v[182:185], v[190:193], v[44:47]
	v_mfma_f32_16x16x32_bf16 v[36:39], v[174:177], v[198:201], v[36:39]
	v_mfma_f32_16x16x32_bf16 v[28:31], v[182:185], v[198:201], v[28:31]
	v_mfma_f32_16x16x32_bf16 v[20:23], v[174:177], v[206:209], v[20:23]
	v_mfma_f32_16x16x32_bf16 v[12:15], v[182:185], v[206:209], v[12:15]
	v_mfma_f32_16x16x32_bf16 v[4:7], v[174:177], v[214:217], v[4:7]
	v_mfma_f32_16x16x32_bf16 v[0:3], v[182:185], v[214:217], v[0:3]
	s_setprio 0
	s_barrier
	s_add_i32 s61, 0, 0x18000
	s_add_i32 s62, 0, 0x1c000
	v_add_u32_e32 v140, s61, v168
	v_add_u32_e32 v173, s62, v168
	ds_read_b128 v[128:131], v140
	ds_read_b128 v[132:135], v140 offset:1024
	ds_read_b128 v[136:139], v140 offset:2048
	ds_read_b128 v[140:143], v140 offset:3072
	ds_read_b128 v[162:165], v173
	ds_read_b128 v[174:177], v173 offset:1024
	ds_read_b128 v[178:181], v173 offset:2048
	ds_read_b128 v[182:185], v173 offset:3072
	s_add_u32 s26, s30, 0x280000
	s_addc_u32 s27, s31, 0
	s_mov_b32 m0, s42
	v_lshl_add_u64 v[224:225], s[26:27], 0, v[144:145]
	ds_read_b128 v[186:189], v172 offset:32768
	ds_read_b128 v[190:193], v172 offset:33792
	ds_read_b128 v[194:197], v172 offset:34816
	ds_read_b128 v[198:201], v172 offset:35840
	ds_read_b128 v[202:205], v172 offset:36864
	ds_read_b128 v[206:209], v172 offset:37888
	ds_read_b128 v[210:213], v172 offset:38912
	ds_read_b128 v[214:217], v172 offset:39936
	global_load_lds_dwordx4 v[224:225], off
	v_lshl_add_u64 v[224:225], s[26:27], 0, v[148:149]
	s_mov_b32 m0, s43
	s_nop 0
	global_load_lds_dwordx4 v[224:225], off
	s_waitcnt vmcnt(8)
	s_waitcnt lgkmcnt(0)
	s_barrier
	s_setprio 1
	s_waitcnt lgkmcnt(0)
	v_mfma_f32_16x16x32_bf16 v[124:127], v[128:131], v[186:189], v[124:127]
	v_mfma_f32_16x16x32_bf16 v[120:123], v[136:139], v[186:189], v[120:123]
	v_mfma_f32_16x16x32_bf16 v[112:115], v[128:131], v[194:197], v[112:115]
	v_mfma_f32_16x16x32_bf16 v[104:107], v[136:139], v[194:197], v[104:107]
	v_mfma_f32_16x16x32_bf16 v[96:99], v[128:131], v[202:205], v[96:99]
	v_mfma_f32_16x16x32_bf16 v[88:91], v[136:139], v[202:205], v[88:91]
	v_mfma_f32_16x16x32_bf16 v[80:83], v[128:131], v[210:213], v[80:83]
	v_mfma_f32_16x16x32_bf16 v[72:75], v[136:139], v[210:213], v[72:75]
	v_mfma_f32_16x16x32_bf16 v[124:127], v[132:135], v[190:193], v[124:127]
	v_mfma_f32_16x16x32_bf16 v[120:123], v[140:143], v[190:193], v[120:123]
	v_mfma_f32_16x16x32_bf16 v[112:115], v[132:135], v[198:201], v[112:115]
	v_mfma_f32_16x16x32_bf16 v[104:107], v[140:143], v[198:201], v[104:107]
	v_mfma_f32_16x16x32_bf16 v[96:99], v[132:135], v[206:209], v[96:99]
	v_mfma_f32_16x16x32_bf16 v[88:91], v[140:143], v[206:209], v[88:91]
	v_mfma_f32_16x16x32_bf16 v[80:83], v[132:135], v[214:217], v[80:83]
	v_mfma_f32_16x16x32_bf16 v[72:75], v[140:143], v[214:217], v[72:75]
	v_mfma_f32_16x16x32_bf16 v[116:119], v[162:165], v[186:189], v[116:119]
	v_mfma_f32_16x16x32_bf16 v[108:111], v[178:181], v[186:189], v[108:111]
	v_mfma_f32_16x16x32_bf16 v[100:103], v[162:165], v[194:197], v[100:103]
	v_mfma_f32_16x16x32_bf16 v[92:95], v[178:181], v[194:197], v[92:95]
	v_mfma_f32_16x16x32_bf16 v[84:87], v[162:165], v[202:205], v[84:87]
	v_mfma_f32_16x16x32_bf16 v[76:79], v[178:181], v[202:205], v[76:79]
	v_mfma_f32_16x16x32_bf16 v[68:71], v[162:165], v[210:213], v[68:71]
	v_mfma_f32_16x16x32_bf16 v[64:67], v[178:181], v[210:213], v[64:67]
	v_mfma_f32_16x16x32_bf16 v[116:119], v[174:177], v[190:193], v[116:119]
	v_mfma_f32_16x16x32_bf16 v[108:111], v[182:185], v[190:193], v[108:111]
	v_mfma_f32_16x16x32_bf16 v[100:103], v[174:177], v[198:201], v[100:103]
	v_mfma_f32_16x16x32_bf16 v[92:95], v[182:185], v[198:201], v[92:95]
	v_mfma_f32_16x16x32_bf16 v[84:87], v[174:177], v[206:209], v[84:87]
	v_mfma_f32_16x16x32_bf16 v[76:79], v[182:185], v[206:209], v[76:79]
	v_mfma_f32_16x16x32_bf16 v[68:71], v[174:177], v[214:217], v[68:71]
	v_mfma_f32_16x16x32_bf16 v[64:67], v[182:185], v[214:217], v[64:67]
	s_setprio 0
	s_barrier
; #define PG8_STAGE(bufoff, gbase, voff) do { _Pragma("unroll") for (int _i = 0; _i < 2; ++_i) \
;         __builtin_amdgcn_global_load_lds((const unsigned*)((const char*)(gbase) + (voff)[_i]), (PG8_LAS unsigned*)(lds + (bufoff) + ldsw + _i * 8192), 16, 0, 0); } while (0)
; #define PG8_LDA(dst, b, h) do { _Pragma("unroll") for (int m = 0; m < 4; ++m) _Pragma("unroll") for (int k = 0; k < 2; ++k) dst[m][k] = *(const PG8_LAS bf16x8*)(lds + PG8_SA(b, h) + aoff + m * 2048 + k * 1024); } while (0)
; #define PG8_WAIT_V(n) asm volatile("s_waitcnt vmcnt(" #n ")" ::: "memory")
; #define PG8_WAIT_L(n) asm volatile("s_waitcnt lgkmcnt(" #n ")" ::: "memory")
; #define PG8_BAR __builtin_amdgcn_s_barrier()
; template <class Epi, class Sched, bool ALIGN_EPI = false, bool SP2 = false>
; __device__ __forceinline__ void gemm_phase(PG8_LAS unsigned char* lds, const Gemm g, const Sched& S, const Epi& E, const int wave_in) {
;     ...
;         for (int t = 0; t < nt; t += 2) {
;             const bool last = (t == nt - 2);
;             const char* a1 = cA + (size_t)(t + 1) * kstep;
;             const char* a2 = last ? nA : cA + (size_t)(t + 2) * kstep; const char* b2 = last ? nB : cB + (size_t)(t + 2) * kstep;
;             const char* a3 = a2 + kstep; const char* b3 = b2 + kstep;
;             if (last && has_next) S.a_ready(nxt);
;             if constexpr (SP2) {
;             PG8_LDB(B0, 0, 0); PG8_LDB(B1, 0, 1); PG8_SCHED; PG8_LDA(At, 0, 0); PG8_STAGE(PG8_SA(1, 1), a1 + hstepA, voffA);
;             PG8_WAIT_V(8); PG8_WAIT_L(0); PG8_BAR; PG8_MMA(0, 0, At, B0); PG8_MMA(0, 1, At, B1); PG8_BAR; PG8_SCHED;
;             PG8_LDA(At, 0, 1); PG8_STAGE(PG8_SB(0, 0), b2, voffB); PG8_STAGE(PG8_SB(0, 1), b2 + hstepB, voffB); PG8_STAGE(PG8_SA(0, 0), a2, voffA);
;             PG8_WAIT_V(8); PG8_WAIT_L(0); PG8_BAR; PG8_MMA(1, 0, At, B0); PG8_MMA(1, 1, At, B1); PG8_BAR; PG8_SCHED;
;             PG8_LDB(B0, 1, 0); PG8_LDB(B1, 1, 1); PG8_SCHED; PG8_LDA(At, 1, 0); PG8_STAGE(PG8_SA(0, 1), a2 + hstepA, voffA);
;             PG8_WAIT_V(8); PG8_WAIT_L(0); PG8_BAR; PG8_MMA(0, 0, At, B0); PG8_MMA(0, 1, At, B1); PG8_BAR; PG8_SCHED;
;             PG8_LDA(At, 1, 1); PG8_STAGE(PG8_SB(1, 0), b3, voffB); PG8_STAGE(PG8_SB(1, 1), b3 + hstepB, voffB); PG8_STAGE(PG8_SA(1, 0), a3, voffA);
;             PG8_WAIT_V(8); PG8_WAIT_L(0); PG8_BAR; PG8_MMA(1, 0, At, B0); PG8_MMA(1, 1, At, B1); PG8_BAR; PG8_SCHED;
	s_add_i32 s26, s61, s39
	v_lshl_add_u64 v[166:167], v[166:167], 0, s[8:9]
	s_mov_b32 m0, s26
	ds_read_b128 v[186:189], v172 offset:49152
	ds_read_b128 v[190:193], v172 offset:50176
	ds_read_b128 v[194:197], v172 offset:51200
	ds_read_b128 v[198:201], v172 offset:52224
	ds_read_b128 v[202:205], v172 offset:53248
	ds_read_b128 v[206:209], v172 offset:54272
	ds_read_b128 v[210:213], v172 offset:55296
	ds_read_b128 v[214:217], v172 offset:56320
	global_load_lds_dwordx4 v[166:167], off
	s_add_i32 m0, s26, 0x2000
	s_add_u32 s26, s28, 0x80080
	v_lshl_add_u64 v[166:167], v[218:219], 0, s[8:9]
	s_addc_u32 s27, s29, 0
	s_add_i32 s28, s62, s39
	global_load_lds_dwordx4 v[166:167], off
	v_lshl_add_u64 v[166:167], s[26:27], 0, v[146:147]
	s_mov_b32 m0, s28
	s_nop 0
	global_load_lds_dwordx4 v[166:167], off
	v_lshl_add_u64 v[166:167], s[26:27], 0, v[150:151]
	s_add_i32 m0, s28, 0x2000
	s_nop 0
	global_load_lds_dwordx4 v[166:167], off
	v_lshl_add_u64 v[166:167], v[220:221], 0, s[8:9]
	s_mov_b32 m0, s47
	s_nop 0
	global_load_lds_dwordx4 v[166:167], off
	v_lshl_add_u64 v[166:167], v[222:223], 0, s[8:9]
	s_mov_b32 m0, s48
	s_nop 0
	global_load_lds_dwordx4 v[166:167], off
	s_waitcnt vmcnt(8)
	s_waitcnt lgkmcnt(0)
	s_barrier
	s_setprio 1
	s_waitcnt lgkmcnt(0)
	v_mfma_f32_16x16x32_bf16 v[60:63], v[128:131], v[186:189], v[60:63]
	v_mfma_f32_16x16x32_bf16 v[56:59], v[136:139], v[186:189], v[56:59]
	v_mfma_f32_16x16x32_bf16 v[48:51], v[128:131], v[194:197], v[48:51]
	v_mfma_f32_16x16x32_bf16 v[40:43], v[136:139], v[194:197], v[40:43]
	v_mfma_f32_16x16x32_bf16 v[32:35], v[128:131], v[202:205], v[32:35]
	v_mfma_f32_16x16x32_bf16 v[24:27], v[136:139], v[202:205], v[24:27]
	v_mfma_f32_16x16x32_bf16 v[16:19], v[128:131], v[210:213], v[16:19]
	v_mfma_f32_16x16x32_bf16 v[8:11], v[136:139], v[210:213], v[8:11]
	v_mfma_f32_16x16x32_bf16 v[60:63], v[132:135], v[190:193], v[60:63]
	v_mfma_f32_16x16x32_bf16 v[56:59], v[140:143], v[190:193], v[56:59]
	v_mfma_f32_16x16x32_bf16 v[48:51], v[132:135], v[198:201], v[48:51]
	v_mfma_f32_16x16x32_bf16 v[40:43], v[140:143], v[198:201], v[40:43]
	v_mfma_f32_16x16x32_bf16 v[32:35], v[132:135], v[206:209], v[32:35]
	v_mfma_f32_16x16x32_bf16 v[24:27], v[140:143], v[206:209], v[24:27]
	v_mfma_f32_16x16x32_bf16 v[16:19], v[132:135], v[214:217], v[16:19]
	v_mfma_f32_16x16x32_bf16 v[8:11], v[140:143], v[214:217], v[8:11]
	v_mfma_f32_16x16x32_bf16 v[52:55], v[162:165], v[186:189], v[52:55]
	v_mfma_f32_16x16x32_bf16 v[44:47], v[178:181], v[186:189], v[44:47]
	v_mfma_f32_16x16x32_bf16 v[36:39], v[162:165], v[194:197], v[36:39]
	v_mfma_f32_16x16x32_bf16 v[28:31], v[178:181], v[194:197], v[28:31]
	v_mfma_f32_16x16x32_bf16 v[20:23], v[162:165], v[202:205], v[20:23]
	v_mfma_f32_16x16x32_bf16 v[12:15], v[178:181], v[202:205], v[12:15]
	v_mfma_f32_16x16x32_bf16 v[4:7], v[162:165], v[210:213], v[4:7]
	v_mfma_f32_16x16x32_bf16 v[0:3], v[178:181], v[210:213], v[0:3]
	v_mfma_f32_16x16x32_bf16 v[52:55], v[174:177], v[190:193], v[52:55]
	v_mfma_f32_16x16x32_bf16 v[44:47], v[182:185], v[190:193], v[44:47]
	v_mfma_f32_16x16x32_bf16 v[36:39], v[174:177], v[198:201], v[36:39]
	v_mfma_f32_16x16x32_bf16 v[28:31], v[182:185], v[198:201], v[28:31]
	v_mfma_f32_16x16x32_bf16 v[20:23], v[174:177], v[206:209], v[20:23]
	v_mfma_f32_16x16x32_bf16 v[12:15], v[182:185], v[206:209], v[12:15]
	v_mfma_f32_16x16x32_bf16 v[4:7], v[174:177], v[214:217], v[4:7]
	v_mfma_f32_16x16x32_bf16 v[0:3], v[182:185], v[214:217], v[0:3]
	s_setprio 0
	s_barrier
	s_add_i32 s60, s60, 2
	s_add_u32 s58, s58, 0x100
	s_addc_u32 s59, s59, 0
	s_cmp_gt_u32 s60, 29
	s_mov_b64 s[26:27], s[4:5]
	s_cbranch_scc0 .LBB0_2451
	s_branch .Lkx_28
.LBB0_2451:
	ds_read_b128 v[128:131], v170
	ds_read_b128 v[132:135], v170 offset:1024
	ds_read_b128 v[136:139], v170 offset:2048
	ds_read_b128 v[140:143], v170 offset:3072
	ds_read_b128 v[162:165], v171
	ds_read_b128 v[174:177], v171 offset:1024
	ds_read_b128 v[178:181], v171 offset:2048
	ds_read_b128 v[182:185], v171 offset:3072
	s_add_u32 s4, s26, 0x100
	s_addc_u32 s5, s27, 0
	s_cmp_eq_u32 s60, 28
	s_cselect_b32 s31, s21, s5
	s_cselect_b32 s30, s20, s4
	s_cselect_b32 s29, s19, s59
	s_cselect_b32 s28, s25, s58
	v_lshl_add_u64 v[166:167], s[26:27], 0, v[154:155]
	s_add_i32 m0, s40, 0xc000
	ds_read_b128 v[186:189], v172
	ds_read_b128 v[190:193], v172 offset:1024
	ds_read_b128 v[194:197], v172 offset:2048
	ds_read_b128 v[198:201], v172 offset:3072
	ds_read_b128 v[202:205], v172 offset:4096
	ds_read_b128 v[206:209], v172 offset:5120
	ds_read_b128 v[210:213], v172 offset:6144
	ds_read_b128 v[214:217], v172 offset:7168
	global_load_lds_dwordx4 v[166:167], off
	v_lshl_add_u64 v[166:167], s[26:27], 0, v[156:157]
	s_add_i32 m0, s40, 0xe000
	s_nop 0
	global_load_lds_dwordx4 v[166:167], off
	s_waitcnt vmcnt(8)
	s_waitcnt lgkmcnt(0)
	s_barrier
; #define PG8_STAGE(bufoff, gbase, voff) do { _Pragma("unroll") for (int _i = 0; _i < 2; ++_i) \
;         __builtin_amdgcn_global_load_lds((const unsigned*)((const char*)(gbase) + (voff)[_i]), (PG8_LAS unsigned*)(lds + (bufoff) + ldsw + _i * 8192), 16, 0, 0); } while (0)
; #define PG8_LDA(dst, b, h) do { _Pragma("unroll") for (int m = 0; m < 4; ++m) _Pragma("unroll") for (int k = 0; k < 2; ++k) dst[m][k] = *(const PG8_LAS bf16x8*)(lds + PG8_SA(b, h) + aoff + m * 2048 + k * 1024); } while (0)
; #define PG8_LDB(dst, b, h) do { _Pragma("unroll") for (int n = 0; n < 2; ++n) _Pragma("unroll") for (int k = 0; k < 2; ++k) dst[n][k] = *(const PG8_LAS bf16x8*)(lds + PG8_SB(b, h) + boff + n * 2048 + k * 1024); } while (0)
; #define PG8_MMA(ai, bj, At, Bt) do { __builtin_amdgcn_s_setprio(1); _Pragma("unroll") for (int m = 0; m < 4; ++m) _Pragma("unroll") for (int n = 0; n < 2; ++n) _Pragma("unroll") for (int k = 0; k < 2; ++k) \
;         acc[ai][bj][m][n] = __builtin_amdgcn_mfma_f32_16x16x32_bf16(Bt[n][k], At[m][k], acc[ai][bj][m][n], 0, 0, 0); __builtin_amdgcn_s_setprio(0); } while (0)
; #define PG8_WAIT_V(n) asm volatile("s_waitcnt vmcnt(" #n ")" ::: "memory")
; #define PG8_WAIT_L(n) asm volatile("s_waitcnt lgkmcnt(" #n ")" ::: "memory")
; #define PG8_BAR __builtin_amdgcn_s_barrier()
; #define PG8_SCHED __builtin_amdgcn_sched_barrier(0)
; template <class Epi, class Sched, bool ALIGN_EPI = false, bool SP2 = false>
; __device__ __forceinline__ void gemm_phase(PG8_LAS unsigned char* lds, const Gemm g, const Sched& S, const Epi& E, const int wave_in) {
;     ...
;             PG8_LDB(B0, 0, 0); PG8_LDB(B1, 0, 1); PG8_SCHED; PG8_LDA(At, 0, 0); PG8_STAGE(PG8_SA(1, 1), a1 + hstepA, voffA);
;             PG8_WAIT_V(8); PG8_WAIT_L(0); PG8_BAR; PG8_MMA(0, 0, At, B0); PG8_MMA(0, 1, At, B1); PG8_BAR; PG8_SCHED;
;             PG8_LDA(At, 0, 1); PG8_STAGE(PG8_SB(0, 0), b2, voffB); PG8_STAGE(PG8_SB(0, 1), b2 + hstepB, voffB); PG8_STAGE(PG8_SA(0, 0), a2, voffA);
;             PG8_WAIT_V(8); PG8_WAIT_L(0); PG8_BAR; PG8_MMA(1, 0, At, B0); PG8_MMA(1, 1, At, B1); PG8_BAR; PG8_SCHED;
	s_setprio 1
	s_waitcnt lgkmcnt(0)
	v_mfma_f32_16x16x32_bf16 v[124:127], v[128:131], v[186:189], v[124:127]
	v_mfma_f32_16x16x32_bf16 v[120:123], v[136:139], v[186:189], v[120:123]
	v_mfma_f32_16x16x32_bf16 v[112:115], v[128:131], v[194:197], v[112:115]
	v_mfma_f32_16x16x32_bf16 v[104:107], v[136:139], v[194:197], v[104:107]
	v_mfma_f32_16x16x32_bf16 v[96:99], v[128:131], v[202:205], v[96:99]
	v_mfma_f32_16x16x32_bf16 v[88:91], v[136:139], v[202:205], v[88:91]
	v_mfma_f32_16x16x32_bf16 v[80:83], v[128:131], v[210:213], v[80:83]
	v_mfma_f32_16x16x32_bf16 v[72:75], v[136:139], v[210:213], v[72:75]
	v_mfma_f32_16x16x32_bf16 v[124:127], v[132:135], v[190:193], v[124:127]
	v_mfma_f32_16x16x32_bf16 v[120:123], v[140:143], v[190:193], v[120:123]
	v_mfma_f32_16x16x32_bf16 v[112:115], v[132:135], v[198:201], v[112:115]
	v_mfma_f32_16x16x32_bf16 v[104:107], v[140:143], v[198:201], v[104:107]
	v_mfma_f32_16x16x32_bf16 v[96:99], v[132:135], v[206:209], v[96:99]
	v_mfma_f32_16x16x32_bf16 v[88:91], v[140:143], v[206:209], v[88:91]
	v_mfma_f32_16x16x32_bf16 v[80:83], v[132:135], v[214:217], v[80:83]
	v_mfma_f32_16x16x32_bf16 v[72:75], v[140:143], v[214:217], v[72:75]
	v_mfma_f32_16x16x32_bf16 v[116:119], v[162:165], v[186:189], v[116:119]
	v_mfma_f32_16x16x32_bf16 v[108:111], v[178:181], v[186:189], v[108:111]
	v_mfma_f32_16x16x32_bf16 v[100:103], v[162:165], v[194:197], v[100:103]
	v_mfma_f32_16x16x32_bf16 v[92:95], v[178:181], v[194:197], v[92:95]
	v_mfma_f32_16x16x32_bf16 v[84:87], v[162:165], v[202:205], v[84:87]
	v_mfma_f32_16x16x32_bf16 v[76:79], v[178:181], v[202:205], v[76:79]
	v_mfma_f32_16x16x32_bf16 v[68:71], v[162:165], v[210:213], v[68:71]
	v_mfma_f32_16x16x32_bf16 v[64:67], v[178:181], v[210:213], v[64:67]
	v_mfma_f32_16x16x32_bf16 v[116:119], v[174:177], v[190:193], v[116:119]
	v_mfma_f32_16x16x32_bf16 v[108:111], v[182:185], v[190:193], v[108:111]
	v_mfma_f32_16x16x32_bf16 v[100:103], v[174:177], v[198:201], v[100:103]
	v_mfma_f32_16x16x32_bf16 v[92:95], v[182:185], v[198:201], v[92:95]
	v_mfma_f32_16x16x32_bf16 v[84:87], v[174:177], v[206:209], v[84:87]
	v_mfma_f32_16x16x32_bf16 v[76:79], v[182:185], v[206:209], v[76:79]
	v_mfma_f32_16x16x32_bf16 v[68:71], v[174:177], v[214:217], v[68:71]
	v_mfma_f32_16x16x32_bf16 v[64:67], v[182:185], v[214:217], v[64:67]
	s_setprio 0
	s_barrier
	s_add_i32 s26, s50, s39
	v_lshl_add_u64 v[166:167], s[28:29], 0, v[146:147]
	s_mov_b32 m0, s26
	ds_read_b128 v[186:189], v172 offset:16384
	ds_read_b128 v[190:193], v172 offset:17408
	ds_read_b128 v[194:197], v172 offset:18432
	ds_read_b128 v[198:201], v172 offset:19456
	ds_read_b128 v[202:205], v172 offset:20480
	ds_read_b128 v[206:209], v172 offset:21504
	ds_read_b128 v[210:213], v172 offset:22528
	ds_read_b128 v[214:217], v172 offset:23552
	global_load_lds_dwordx4 v[166:167], off
	s_add_i32 m0, s26, 0x2000
	s_add_u32 s26, s28, 0x80000
	v_lshl_add_u64 v[218:219], s[28:29], 0, v[150:151]
	s_addc_u32 s27, s29, 0
	s_add_i32 s61, s51, s39
	global_load_lds_dwordx4 v[218:219], off
	v_lshl_add_u64 v[220:221], s[26:27], 0, v[146:147]
	s_mov_b32 m0, s61
	v_lshl_add_u64 v[222:223], s[30:31], 0, v[148:149]
	global_load_lds_dwordx4 v[220:221], off
	v_lshl_add_u64 v[220:221], s[26:27], 0, v[150:151]
	s_add_i32 m0, s61, 0x2000
	s_nop 0
	global_load_lds_dwordx4 v[220:221], off
	v_lshl_add_u64 v[220:221], s[30:31], 0, v[144:145]
	s_mov_b32 m0, s40
	s_nop 0
	global_load_lds_dwordx4 v[220:221], off
	s_mov_b32 m0, s41
	s_nop 0
	global_load_lds_dwordx4 v[222:223], off
	s_waitcnt vmcnt(8)
	s_waitcnt lgkmcnt(0)
	s_barrier
	s_setprio 1
	s_waitcnt lgkmcnt(0)
	v_mfma_f32_16x16x32_bf16 v[60:63], v[128:131], v[186:189], v[60:63]
	v_mfma_f32_16x16x32_bf16 v[56:59], v[136:139], v[186:189], v[56:59]
	v_mfma_f32_16x16x32_bf16 v[48:51], v[128:131], v[194:197], v[48:51]
	v_mfma_f32_16x16x32_bf16 v[40:43], v[136:139], v[194:197], v[40:43]
	v_mfma_f32_16x16x32_bf16 v[32:35], v[128:131], v[202:205], v[32:35]
	v_mfma_f32_16x16x32_bf16 v[24:27], v[136:139], v[202:205], v[24:27]
	v_mfma_f32_16x16x32_bf16 v[16:19], v[128:131], v[210:213], v[16:19]
	v_mfma_f32_16x16x32_bf16 v[8:11], v[136:139], v[210:213], v[8:11]
	v_mfma_f32_16x16x32_bf16 v[60:63], v[132:135], v[190:193], v[60:63]
	v_mfma_f32_16x16x32_bf16 v[56:59], v[140:143], v[190:193], v[56:59]
	v_mfma_f32_16x16x32_bf16 v[48:51], v[132:135], v[198:201], v[48:51]
	v_mfma_f32_16x16x32_bf16 v[40:43], v[140:143], v[198:201], v[40:43]
	v_mfma_f32_16x16x32_bf16 v[32:35], v[132:135], v[206:209], v[32:35]
	v_mfma_f32_16x16x32_bf16 v[24:27], v[140:143], v[206:209], v[24:27]
	v_mfma_f32_16x16x32_bf16 v[16:19], v[132:135], v[214:217], v[16:19]
	v_mfma_f32_16x16x32_bf16 v[8:11], v[140:143], v[214:217], v[8:11]
	v_mfma_f32_16x16x32_bf16 v[52:55], v[162:165], v[186:189], v[52:55]
	v_mfma_f32_16x16x32_bf16 v[44:47], v[178:181], v[186:189], v[44:47]
	v_mfma_f32_16x16x32_bf16 v[36:39], v[162:165], v[194:197], v[36:39]
	v_mfma_f32_16x16x32_bf16 v[28:31], v[178:181], v[194:197], v[28:31]
	v_mfma_f32_16x16x32_bf16 v[20:23], v[162:165], v[202:205], v[20:23]
	v_mfma_f32_16x16x32_bf16 v[12:15], v[178:181], v[202:205], v[12:15]
	v_mfma_f32_16x16x32_bf16 v[4:7], v[162:165], v[210:213], v[4:7]
	v_mfma_f32_16x16x32_bf16 v[0:3], v[178:181], v[210:213], v[0:3]
	v_mfma_f32_16x16x32_bf16 v[52:55], v[174:177], v[190:193], v[52:55]
	v_mfma_f32_16x16x32_bf16 v[44:47], v[182:185], v[190:193], v[44:47]
	v_mfma_f32_16x16x32_bf16 v[36:39], v[174:177], v[198:201], v[36:39]
	v_mfma_f32_16x16x32_bf16 v[28:31], v[182:185], v[198:201], v[28:31]
	v_mfma_f32_16x16x32_bf16 v[20:23], v[174:177], v[206:209], v[20:23]
	v_mfma_f32_16x16x32_bf16 v[12:15], v[182:185], v[206:209], v[12:15]
	v_mfma_f32_16x16x32_bf16 v[4:7], v[174:177], v[214:217], v[4:7]
	v_mfma_f32_16x16x32_bf16 v[0:3], v[182:185], v[214:217], v[0:3]
	s_setprio 0
	s_barrier
; #define PG8_STAGE(bufoff, gbase, voff) do { _Pragma("unroll") for (int _i = 0; _i < 2; ++_i) \
;         __builtin_amdgcn_global_load_lds((const unsigned*)((const char*)(gbase) + (voff)[_i]), (PG8_LAS unsigned*)(lds + (bufoff) + ldsw + _i * 8192), 16, 0, 0); } while (0)
; #define PG8_LDA(dst, b, h) do { _Pragma("unroll") for (int m = 0; m < 4; ++m) _Pragma("unroll") for (int k = 0; k < 2; ++k) dst[m][k] = *(const PG8_LAS bf16x8*)(lds + PG8_SA(b, h) + aoff + m * 2048 + k * 1024); } while (0)
; #define PG8_LDB(dst, b, h) do { _Pragma("unroll") for (int n = 0; n < 2; ++n) _Pragma("unroll") for (int k = 0; k < 2; ++k) dst[n][k] = *(const PG8_LAS bf16x8*)(lds + PG8_SB(b, h) + boff + n * 2048 + k * 1024); } while (0)
; #define PG8_MMA(ai, bj, At, Bt) do { __builtin_amdgcn_s_setprio(1); _Pragma("unroll") for (int m = 0; m < 4; ++m) _Pragma("unroll") for (int n = 0; n < 2; ++n) _Pragma("unroll") for (int k = 0; k < 2; ++k) \
;         acc[ai][bj][m][n] = __builtin_amdgcn_mfma_f32_16x16x32_bf16(Bt[n][k], At[m][k], acc[ai][bj][m][n], 0, 0, 0); __builtin_amdgcn_s_setprio(0); } while (0)
; #define PG8_WAIT_V(n) asm volatile("s_waitcnt vmcnt(" #n ")" ::: "memory")
; #define PG8_WAIT_L(n) asm volatile("s_waitcnt lgkmcnt(" #n ")" ::: "memory")
; #define PG8_BAR __builtin_amdgcn_s_barrier()
; #define PG8_SCHED __builtin_amdgcn_sched_barrier(0)
; template <class Epi, class Sched, bool ALIGN_EPI = false, bool SP2 = false>
; __device__ __forceinline__ void gemm_phase(PG8_LAS unsigned char* lds, const Gemm g, const Sched& S, const Epi& E, const int wave_in) {
;     ...
;             PG8_LDB(B0, 1, 0); PG8_LDB(B1, 1, 1); PG8_SCHED; PG8_LDA(At, 1, 0); PG8_STAGE(PG8_SA(0, 1), a2 + hstepA, voffA);
;             PG8_WAIT_V(8); PG8_WAIT_L(0); PG8_BAR; PG8_MMA(0, 0, At, B0); PG8_MMA(0, 1, At, B1); PG8_BAR; PG8_SCHED;
	s_add_i32 s61, 0, 0x18000
	s_add_i32 s62, 0, 0x1c000
	v_add_u32_e32 v140, s61, v168
	v_add_u32_e32 v173, s62, v168
	ds_read_b128 v[128:131], v140
	ds_read_b128 v[132:135], v140 offset:1024
	ds_read_b128 v[136:139], v140 offset:2048
	ds_read_b128 v[140:143], v140 offset:3072
	ds_read_b128 v[162:165], v173
	ds_read_b128 v[174:177], v173 offset:1024
	ds_read_b128 v[178:181], v173 offset:2048
	ds_read_b128 v[182:185], v173 offset:3072
	s_add_u32 s26, s30, 0x280000
	s_addc_u32 s27, s31, 0
	s_mov_b32 m0, s42
	v_lshl_add_u64 v[224:225], s[26:27], 0, v[144:145]
	ds_read_b128 v[186:189], v172 offset:32768
	ds_read_b128 v[190:193], v172 offset:33792
	ds_read_b128 v[194:197], v172 offset:34816
	ds_read_b128 v[198:201], v172 offset:35840
	ds_read_b128 v[202:205], v172 offset:36864
	ds_read_b128 v[206:209], v172 offset:37888
	ds_read_b128 v[210:213], v172 offset:38912
	ds_read_b128 v[214:217], v172 offset:39936
	global_load_lds_dwordx4 v[224:225], off
	v_lshl_add_u64 v[224:225], s[26:27], 0, v[148:149]
	s_mov_b32 m0, s43
	s_nop 0
	global_load_lds_dwordx4 v[224:225], off
	s_waitcnt vmcnt(8)
	s_waitcnt lgkmcnt(0)
	s_barrier
	s_setprio 1
	s_waitcnt lgkmcnt(0)
	v_mfma_f32_16x16x32_bf16 v[124:127], v[128:131], v[186:189], v[124:127]
	v_mfma_f32_16x16x32_bf16 v[120:123], v[136:139], v[186:189], v[120:123]
	v_mfma_f32_16x16x32_bf16 v[112:115], v[128:131], v[194:197], v[112:115]
	v_mfma_f32_16x16x32_bf16 v[104:107], v[136:139], v[194:197], v[104:107]
	v_mfma_f32_16x16x32_bf16 v[96:99], v[128:131], v[202:205], v[96:99]
	v_mfma_f32_16x16x32_bf16 v[88:91], v[136:139], v[202:205], v[88:91]
	v_mfma_f32_16x16x32_bf16 v[80:83], v[128:131], v[210:213], v[80:83]
	v_mfma_f32_16x16x32_bf16 v[72:75], v[136:139], v[210:213], v[72:75]
	v_mfma_f32_16x16x32_bf16 v[124:127], v[132:135], v[190:193], v[124:127]
	v_mfma_f32_16x16x32_bf16 v[120:123], v[140:143], v[190:193], v[120:123]
	v_mfma_f32_16x16x32_bf16 v[112:115], v[132:135], v[198:201], v[112:115]
	v_mfma_f32_16x16x32_bf16 v[104:107], v[140:143], v[198:201], v[104:107]
	v_mfma_f32_16x16x32_bf16 v[96:99], v[132:135], v[206:209], v[96:99]
	v_mfma_f32_16x16x32_bf16 v[88:91], v[140:143], v[206:209], v[88:91]
	v_mfma_f32_16x16x32_bf16 v[80:83], v[132:135], v[214:217], v[80:83]
	v_mfma_f32_16x16x32_bf16 v[72:75], v[140:143], v[214:217], v[72:75]
	v_mfma_f32_16x16x32_bf16 v[116:119], v[162:165], v[186:189], v[116:119]
	v_mfma_f32_16x16x32_bf16 v[108:111], v[178:181], v[186:189], v[108:111]
	v_mfma_f32_16x16x32_bf16 v[100:103], v[162:165], v[194:197], v[100:103]
	v_mfma_f32_16x16x32_bf16 v[92:95], v[178:181], v[194:197], v[92:95]
	v_mfma_f32_16x16x32_bf16 v[84:87], v[162:165], v[202:205], v[84:87]
	v_mfma_f32_16x16x32_bf16 v[76:79], v[178:181], v[202:205], v[76:79]
	v_mfma_f32_16x16x32_bf16 v[68:71], v[162:165], v[210:213], v[68:71]
	v_mfma_f32_16x16x32_bf16 v[64:67], v[178:181], v[210:213], v[64:67]
	v_mfma_f32_16x16x32_bf16 v[116:119], v[174:177], v[190:193], v[116:119]
	v_mfma_f32_16x16x32_bf16 v[108:111], v[182:185], v[190:193], v[108:111]
	v_mfma_f32_16x16x32_bf16 v[100:103], v[174:177], v[198:201], v[100:103]
	v_mfma_f32_16x16x32_bf16 v[92:95], v[182:185], v[198:201], v[92:95]
	v_mfma_f32_16x16x32_bf16 v[84:87], v[174:177], v[206:209], v[84:87]
	v_mfma_f32_16x16x32_bf16 v[76:79], v[182:185], v[206:209], v[76:79]
	v_mfma_f32_16x16x32_bf16 v[68:71], v[174:177], v[214:217], v[68:71]
	v_mfma_f32_16x16x32_bf16 v[64:67], v[182:185], v[214:217], v[64:67]
	s_setprio 0
	s_barrier
; #define PG8_STAGE(bufoff, gbase, voff) do { _Pragma("unroll") for (int _i = 0; _i < 2; ++_i) \
;         __builtin_amdgcn_global_load_lds((const unsigned*)((const char*)(gbase) + (voff)[_i]), (PG8_LAS unsigned*)(lds + (bufoff) + ldsw + _i * 8192), 16, 0, 0); } while (0)
; #define PG8_LDA(dst, b, h) do { _Pragma("unroll") for (int m = 0; m < 4; ++m) _Pragma("unroll") for (int k = 0; k < 2; ++k) dst[m][k] = *(const PG8_LAS bf16x8*)(lds + PG8_SA(b, h) + aoff + m * 2048 + k * 1024); } while (0)
; #define PG8_MMA(ai, bj, At, Bt) do { __builtin_amdgcn_s_setprio(1); _Pragma("unroll") for (int m = 0; m < 4; ++m) _Pragma("unroll") for (int n = 0; n < 2; ++n) _Pragma("unroll") for (int k = 0; k < 2; ++k) \
;         acc[ai][bj][m][n] = __builtin_amdgcn_mfma_f32_16x16x32_bf16(Bt[n][k], At[m][k], acc[ai][bj][m][n], 0, 0, 0); __builtin_amdgcn_s_setprio(0); } while (0)
; #define PG8_WAIT_V(n) asm volatile("s_waitcnt vmcnt(" #n ")" ::: "memory")
; #define PG8_WAIT_L(n) asm volatile("s_waitcnt lgkmcnt(" #n ")" ::: "memory")
; #define PG8_BAR __builtin_amdgcn_s_barrier()
; #define PG8_SCHED __builtin_amdgcn_sched_barrier(0)
; template <class Epi, class Sched, bool ALIGN_EPI = false, bool SP2 = false>
; __device__ __forceinline__ void gemm_phase(PG8_LAS unsigned char* lds, const Gemm g, const Sched& S, const Epi& E, const int wave_in) {
;     ...
;         for (int t = 0; t < nt; t += 2) {
;             const bool last = (t == nt - 2);
;             const char* a1 = cA + (size_t)(t + 1) * kstep;
;             const char* a2 = last ? nA : cA + (size_t)(t + 2) * kstep; const char* b2 = last ? nB : cB + (size_t)(t + 2) * kstep;
;     ...
;             PG8_LDA(At, 1, 1); PG8_STAGE(PG8_SB(1, 0), b3, voffB); PG8_STAGE(PG8_SB(1, 1), b3 + hstepB, voffB); PG8_STAGE(PG8_SA(1, 0), a3, voffA);
;             PG8_WAIT_V(8); PG8_WAIT_L(0); PG8_BAR; PG8_MMA(1, 0, At, B0); PG8_MMA(1, 1, At, B1); PG8_BAR; PG8_SCHED;
	s_add_i32 s26, s61, s39
	v_lshl_add_u64 v[166:167], v[166:167], 0, s[8:9]
	s_mov_b32 m0, s26
	ds_read_b128 v[186:189], v172 offset:49152
	ds_read_b128 v[190:193], v172 offset:50176
	ds_read_b128 v[194:197], v172 offset:51200
	ds_read_b128 v[198:201], v172 offset:52224
	ds_read_b128 v[202:205], v172 offset:53248
	ds_read_b128 v[206:209], v172 offset:54272
	ds_read_b128 v[210:213], v172 offset:55296
	ds_read_b128 v[214:217], v172 offset:56320
	global_load_lds_dwordx4 v[166:167], off
	s_add_i32 m0, s26, 0x2000
	s_add_u32 s26, s28, 0x80080
	v_lshl_add_u64 v[166:167], v[218:219], 0, s[8:9]
	s_addc_u32 s27, s29, 0
	s_add_i32 s28, s62, s39
	global_load_lds_dwordx4 v[166:167], off
	v_lshl_add_u64 v[166:167], s[26:27], 0, v[146:147]
	s_mov_b32 m0, s28
	s_nop 0
	global_load_lds_dwordx4 v[166:167], off
	v_lshl_add_u64 v[166:167], s[26:27], 0, v[150:151]
	s_add_i32 m0, s28, 0x2000
	s_nop 0
	global_load_lds_dwordx4 v[166:167], off
	v_lshl_add_u64 v[166:167], v[220:221], 0, s[8:9]
	s_mov_b32 m0, s47
	s_nop 0
	global_load_lds_dwordx4 v[166:167], off
	v_lshl_add_u64 v[166:167], v[222:223], 0, s[8:9]
	s_mov_b32 m0, s48
	s_nop 0
	global_load_lds_dwordx4 v[166:167], off
	s_waitcnt vmcnt(8)
	s_waitcnt lgkmcnt(0)
	s_barrier
	s_setprio 1
	s_waitcnt lgkmcnt(0)
	v_mfma_f32_16x16x32_bf16 v[60:63], v[128:131], v[186:189], v[60:63]
	v_mfma_f32_16x16x32_bf16 v[56:59], v[136:139], v[186:189], v[56:59]
	v_mfma_f32_16x16x32_bf16 v[48:51], v[128:131], v[194:197], v[48:51]
	v_mfma_f32_16x16x32_bf16 v[40:43], v[136:139], v[194:197], v[40:43]
	v_mfma_f32_16x16x32_bf16 v[32:35], v[128:131], v[202:205], v[32:35]
	v_mfma_f32_16x16x32_bf16 v[24:27], v[136:139], v[202:205], v[24:27]
	v_mfma_f32_16x16x32_bf16 v[16:19], v[128:131], v[210:213], v[16:19]
	v_mfma_f32_16x16x32_bf16 v[8:11], v[136:139], v[210:213], v[8:11]
	v_mfma_f32_16x16x32_bf16 v[60:63], v[132:135], v[190:193], v[60:63]
	v_mfma_f32_16x16x32_bf16 v[56:59], v[140:143], v[190:193], v[56:59]
	v_mfma_f32_16x16x32_bf16 v[48:51], v[132:135], v[198:201], v[48:51]
	v_mfma_f32_16x16x32_bf16 v[40:43], v[140:143], v[198:201], v[40:43]
	v_mfma_f32_16x16x32_bf16 v[32:35], v[132:135], v[206:209], v[32:35]
	v_mfma_f32_16x16x32_bf16 v[24:27], v[140:143], v[206:209], v[24:27]
	v_mfma_f32_16x16x32_bf16 v[16:19], v[132:135], v[214:217], v[16:19]
	v_mfma_f32_16x16x32_bf16 v[8:11], v[140:143], v[214:217], v[8:11]
	v_mfma_f32_16x16x32_bf16 v[52:55], v[162:165], v[186:189], v[52:55]
	v_mfma_f32_16x16x32_bf16 v[44:47], v[178:181], v[186:189], v[44:47]
	v_mfma_f32_16x16x32_bf16 v[36:39], v[162:165], v[194:197], v[36:39]
	v_mfma_f32_16x16x32_bf16 v[28:31], v[178:181], v[194:197], v[28:31]
	v_mfma_f32_16x16x32_bf16 v[20:23], v[162:165], v[202:205], v[20:23]
	v_mfma_f32_16x16x32_bf16 v[12:15], v[178:181], v[202:205], v[12:15]
	v_mfma_f32_16x16x32_bf16 v[4:7], v[162:165], v[210:213], v[4:7]
	v_mfma_f32_16x16x32_bf16 v[0:3], v[178:181], v[210:213], v[0:3]
	v_mfma_f32_16x16x32_bf16 v[52:55], v[174:177], v[190:193], v[52:55]
	v_mfma_f32_16x16x32_bf16 v[44:47], v[182:185], v[190:193], v[44:47]
	v_mfma_f32_16x16x32_bf16 v[36:39], v[174:177], v[198:201], v[36:39]
	v_mfma_f32_16x16x32_bf16 v[28:31], v[182:185], v[198:201], v[28:31]
	v_mfma_f32_16x16x32_bf16 v[20:23], v[174:177], v[206:209], v[20:23]
	v_mfma_f32_16x16x32_bf16 v[12:15], v[182:185], v[206:209], v[12:15]
	v_mfma_f32_16x16x32_bf16 v[4:7], v[174:177], v[214:217], v[4:7]
	v_mfma_f32_16x16x32_bf16 v[0:3], v[182:185], v[214:217], v[0:3]
	s_setprio 0
	s_barrier
	s_add_i32 s60, s60, 2
	s_add_u32 s58, s58, 0x100
	s_addc_u32 s59, s59, 0
	s_cmp_gt_u32 s60, 29
	s_mov_b64 s[26:27], s[4:5]
	s_cbranch_scc0 .LBB0_2451

;     __host__ __device__ bool next(int i, Unit& u) const { const bool ok = StaticOrder::next(i, u); u.pm = 0; u.pn = 0; return ok; }
; #define PG8_STAGE(bufoff, gbase, voff) do { _Pragma("unroll") for (int _i = 0; _i < 2; ++_i) \
;         __builtin_amdgcn_global_load_lds((const unsigned*)((const char*)(gbase) + (voff)[_i]), (PG8_LAS unsigned*)(lds + (bufoff) + ldsw + _i * 8192), 16, 0, 0); } while (0)
; #define PG8_LDA(dst, b, h) do { _Pragma("unroll") for (int m = 0; m < 4; ++m) _Pragma("unroll") for (int k = 0; k < 2; ++k) dst[m][k] = *(const PG8_LAS bf16x8*)(lds + PG8_SA(b, h) + aoff + m * 2048 + k * 1024); } while (0)
; #define PG8_LDB(dst, b, h) do { _Pragma("unroll") for (int n = 0; n < 2; ++n) _Pragma("unroll") for (int k = 0; k < 2; ++k) dst[n][k] = *(const PG8_LAS bf16x8*)(lds + PG8_SB(b, h) + boff + n * 2048 + k * 1024); } while (0)
; #define PG8_WAIT_V(n) asm volatile("s_waitcnt vmcnt(" #n ")" ::: "memory")
; #define PG8_BAR __builtin_amdgcn_s_barrier()
; template <class Epi, class Sched, bool ALIGN_EPI = false, bool SP2 = false>
; __device__ __forceinline__ void gemm_phase(PG8_LAS unsigned char* lds, const Gemm g, const Sched& S, const Epi& E, const int wave_in) {
;     ...
;         const bool has_next = S.next(ui + 1, nxt);
;         const char* nA = has_next ? (const char*)g.A + (size_t)nxt.pm * tstepA : cA; const char* nB = has_next ? (const char*)g.Bt + (size_t)nxt.pn * tstepB : cB;
;         for (int t = 0; t < nt; t += 2) {
;             const bool last = (t == nt - 2);
;             const char* a1 = cA + (size_t)(t + 1) * kstep;
;             const char* a2 = last ? nA : cA + (size_t)(t + 2) * kstep; const char* b2 = last ? nB : cB + (size_t)(t + 2) * kstep;
;             const char* a3 = a2 + kstep; const char* b3 = b2 + kstep;
;             if (last && has_next) S.a_ready(nxt);
;             if constexpr (SP2) {
;             PG8_LDB(B0, 0, 0); PG8_LDB(B1, 0, 1); PG8_SCHED; PG8_LDA(At, 0, 0); PG8_STAGE(PG8_SA(1, 1), a1 + hstepA, voffA);
;             PG8_WAIT_V(8); PG8_WAIT_L(0); PG8_BAR; PG8_MMA(0, 0, At, B0); PG8_MMA(0, 1, At, B1); PG8_BAR; PG8_SCHED;
;             PG8_LDA(At, 0, 1); PG8_STAGE(PG8_SB(0, 0), b2, voffB); PG8_STAGE(PG8_SB(0, 1), b2 + hstepB, voffB); PG8_STAGE(PG8_SA(0, 0), a2, voffA);
;             PG8_WAIT_V(8); PG8_WAIT_L(0); PG8_BAR; PG8_MMA(1, 0, At, B0); PG8_MMA(1, 1, At, B1); PG8_BAR; PG8_SCHED;
.LBB0_2576:
	s_ashr_i32 s39, s38, 31
	s_lshl_b64 s[40:41], s[38:39], 20
	s_add_u32 s40, s52, s40
	s_addc_u32 s41, s53, s41
	s_and_b64 s[42:43], s[8:9], exec
	s_cselect_b32 s11, s41, s47
	s_cselect_b32 s39, s40, s46
	s_ashr_i32 s37, s36, 31
	s_lshl_b64 s[42:43], s[36:37], 20
	s_add_u32 s42, s54, s42
	s_addc_u32 s43, s55, s43
	s_and_b64 s[50:51], s[8:9], exec
	s_cselect_b32 s37, s43, s49
	s_cselect_b32 s45, s42, s48
	s_add_u32 s46, s46, 0x80080
	s_addc_u32 s47, s47, 0
	s_add_u32 s72, s48, 0x100
	v_mov_b32_e32 v0, 0
	s_addc_u32 s73, s49, 0
	s_mov_b32 s75, -2
	s_waitcnt vmcnt(0)
	ds_read_b128 v[64:67], v189
	ds_read_b128 v[68:71], v189 offset:1024
	ds_read_b128 v[72:75], v189 offset:2048
	ds_read_b128 v[76:79], v189 offset:3072
	ds_read_b128 v[80:83], v197
	ds_read_b128 v[84:87], v197 offset:1024
	ds_read_b128 v[88:91], v197 offset:2048
	ds_read_b128 v[92:95], v197 offset:3072
	s_add_u32 s48, s46, 0xfff80080
	s_addc_u32 s49, s47, -1
	s_cmp_eq_u32 s75, 28
	s_cselect_b32 s51, s11, s49
	s_cselect_b32 s50, s39, s48
	s_cselect_b32 s49, s37, s73
	s_cselect_b32 s48, s45, s72
	v_lshl_add_u64 v[224:225], s[46:47], 0, v[206:207]
	s_add_i32 m0, s57, 0xc000
	ds_read_b128 v[96:99], v199
	ds_read_b128 v[100:103], v199 offset:1024
	ds_read_b128 v[104:107], v199 offset:2048
	ds_read_b128 v[108:111], v199 offset:3072
	ds_read_b128 v[176:179], v199 offset:4096
	ds_read_b128 v[212:215], v199 offset:5120
	ds_read_b128 v[216:219], v199 offset:6144
	ds_read_b128 v[220:223], v199 offset:7168
	global_load_lds_dwordx4 v[224:225], off
	v_lshl_add_u64 v[224:225], s[46:47], 0, v[208:209]
	s_add_i32 m0, s57, 0xe000
	s_nop 0
	global_load_lds_dwordx4 v[224:225], off
	s_waitcnt vmcnt(8)
	s_waitcnt lgkmcnt(0)
	s_barrier
	s_setprio 1
	s_waitcnt lgkmcnt(0)
	v_mfma_f32_16x16x32_bf16 v[172:175], v[64:67], v[96:99], 0
	v_mfma_f32_16x16x32_bf16 v[164:167], v[72:75], v[96:99], 0
	v_mfma_f32_16x16x32_bf16 v[156:159], v[64:67], v[104:107], 0
	v_mfma_f32_16x16x32_bf16 v[148:151], v[72:75], v[104:107], 0
	v_mfma_f32_16x16x32_bf16 v[140:143], v[64:67], v[176:179], 0
	v_mfma_f32_16x16x32_bf16 v[132:135], v[72:75], v[176:179], 0
	v_mfma_f32_16x16x32_bf16 v[124:127], v[64:67], v[216:219], 0
	v_mfma_f32_16x16x32_bf16 v[120:123], v[72:75], v[216:219], 0
	v_mfma_f32_16x16x32_bf16 v[172:175], v[68:71], v[100:103], v[172:175]
	v_mfma_f32_16x16x32_bf16 v[164:167], v[76:79], v[100:103], v[164:167]
	v_mfma_f32_16x16x32_bf16 v[156:159], v[68:71], v[108:111], v[156:159]
	v_mfma_f32_16x16x32_bf16 v[148:151], v[76:79], v[108:111], v[148:151]
	v_mfma_f32_16x16x32_bf16 v[140:143], v[68:71], v[212:215], v[140:143]
	v_mfma_f32_16x16x32_bf16 v[132:135], v[76:79], v[212:215], v[132:135]
	v_mfma_f32_16x16x32_bf16 v[124:127], v[68:71], v[220:223], v[124:127]
	v_mfma_f32_16x16x32_bf16 v[120:123], v[76:79], v[220:223], v[120:123]
	v_mfma_f32_16x16x32_bf16 v[168:171], v[80:83], v[96:99], 0
	v_mfma_f32_16x16x32_bf16 v[96:99], v[88:91], v[96:99], 0
	v_mfma_f32_16x16x32_bf16 v[168:171], v[84:87], v[100:103], v[168:171]
	v_mfma_f32_16x16x32_bf16 v[96:99], v[92:95], v[100:103], v[96:99]
	v_mfma_f32_16x16x32_bf16 v[100:103], v[80:83], v[104:107], 0
	v_mfma_f32_16x16x32_bf16 v[104:107], v[88:91], v[104:107], 0
	v_mfma_f32_16x16x32_bf16 v[128:131], v[88:91], v[176:179], 0
	v_mfma_f32_16x16x32_bf16 v[116:119], v[80:83], v[216:219], 0
	v_mfma_f32_16x16x32_bf16 v[112:115], v[88:91], v[216:219], 0
	v_mfma_f32_16x16x32_bf16 v[100:103], v[84:87], v[108:111], v[100:103]
	v_mfma_f32_16x16x32_bf16 v[104:107], v[92:95], v[108:111], v[104:107]
	v_mfma_f32_16x16x32_bf16 v[108:111], v[80:83], v[176:179], 0
	v_mfma_f32_16x16x32_bf16 v[128:131], v[92:95], v[212:215], v[128:131]
	v_mfma_f32_16x16x32_bf16 v[116:119], v[84:87], v[220:223], v[116:119]
	v_mfma_f32_16x16x32_bf16 v[112:115], v[92:95], v[220:223], v[112:115]
	v_mfma_f32_16x16x32_bf16 v[108:111], v[84:87], v[212:215], v[108:111]
	s_setprio 0
	s_barrier
	s_add_i32 s76, s69, s56
	v_lshl_add_u64 v[232:233], s[48:49], 0, v[182:183]
	s_mov_b32 m0, s76
	ds_read_b128 v[136:139], v199 offset:16384
	ds_read_b128 v[144:147], v199 offset:17408
	ds_read_b128 v[152:155], v199 offset:18432
	ds_read_b128 v[160:163], v199 offset:19456
	ds_read_b128 v[176:179], v199 offset:20480
	ds_read_b128 v[212:215], v199 offset:21504
	ds_read_b128 v[216:219], v199 offset:22528
	ds_read_b128 v[220:223], v199 offset:23552
	global_load_lds_dwordx4 v[232:233], off
	s_add_i32 m0, s76, 0x2000
	s_add_u32 s76, s48, 0x80000
	v_lshl_add_u64 v[234:235], s[48:49], 0, v[186:187]
	s_addc_u32 s77, s49, 0
	s_add_i32 s78, s70, s56
	global_load_lds_dwordx4 v[234:235], off
	v_lshl_add_u64 v[224:225], s[76:77], 0, v[182:183]
	s_mov_b32 m0, s78
	v_lshl_add_u64 v[236:237], s[50:51], 0, v[180:181]
	global_load_lds_dwordx4 v[224:225], off
	v_lshl_add_u64 v[224:225], s[76:77], 0, v[186:187]
	s_add_i32 m0, s78, 0x2000
	v_lshl_add_u64 v[238:239], s[50:51], 0, v[184:185]
	global_load_lds_dwordx4 v[224:225], off
	s_mov_b32 m0, s57
	s_nop 0
	global_load_lds_dwordx4 v[236:237], off
	s_mov_b32 m0, s58
	s_nop 0
	global_load_lds_dwordx4 v[238:239], off
	s_waitcnt vmcnt(8)
	s_waitcnt lgkmcnt(0)
	s_barrier
; #define PG8_STAGE(bufoff, gbase, voff) do { _Pragma("unroll") for (int _i = 0; _i < 2; ++_i) \
;         __builtin_amdgcn_global_load_lds((const unsigned*)((const char*)(gbase) + (voff)[_i]), (PG8_LAS unsigned*)(lds + (bufoff) + ldsw + _i * 8192), 16, 0, 0); } while (0)
; #define PG8_LDA(dst, b, h) do { _Pragma("unroll") for (int m = 0; m < 4; ++m) _Pragma("unroll") for (int k = 0; k < 2; ++k) dst[m][k] = *(const PG8_LAS bf16x8*)(lds + PG8_SA(b, h) + aoff + m * 2048 + k * 1024); } while (0)
; #define PG8_LDB(dst, b, h) do { _Pragma("unroll") for (int n = 0; n < 2; ++n) _Pragma("unroll") for (int k = 0; k < 2; ++k) dst[n][k] = *(const PG8_LAS bf16x8*)(lds + PG8_SB(b, h) + boff + n * 2048 + k * 1024); } while (0)
; #define PG8_MMA(ai, bj, At, Bt) do { __builtin_amdgcn_s_setprio(1); _Pragma("unroll") for (int m = 0; m < 4; ++m) _Pragma("unroll") for (int n = 0; n < 2; ++n) _Pragma("unroll") for (int k = 0; k < 2; ++k) \
;         acc[ai][bj][m][n] = __builtin_amdgcn_mfma_f32_16x16x32_bf16(Bt[n][k], At[m][k], acc[ai][bj][m][n], 0, 0, 0); __builtin_amdgcn_s_setprio(0); } while (0)
; #define PG8_WAIT_V(n) asm volatile("s_waitcnt vmcnt(" #n ")" ::: "memory")
; #define PG8_WAIT_L(n) asm volatile("s_waitcnt lgkmcnt(" #n ")" ::: "memory")
; #define PG8_BAR __builtin_amdgcn_s_barrier()
; #define PG8_SCHED __builtin_amdgcn_sched_barrier(0)
; template <class Epi, class Sched, bool ALIGN_EPI = false, bool SP2 = false>
; __device__ __forceinline__ void gemm_phase(PG8_LAS unsigned char* lds, const Gemm g, const Sched& S, const Epi& E, const int wave_in) {
;     ...
;             PG8_LDA(At, 0, 1); PG8_STAGE(PG8_SB(0, 0), b2, voffB); PG8_STAGE(PG8_SB(0, 1), b2 + hstepB, voffB); PG8_STAGE(PG8_SA(0, 0), a2, voffA);
;             PG8_WAIT_V(8); PG8_WAIT_L(0); PG8_BAR; PG8_MMA(1, 0, At, B0); PG8_MMA(1, 1, At, B1); PG8_BAR; PG8_SCHED;
;             PG8_LDB(B0, 1, 0); PG8_LDB(B1, 1, 1); PG8_SCHED; PG8_LDA(At, 1, 0); PG8_STAGE(PG8_SA(0, 1), a2 + hstepA, voffA);
;             PG8_WAIT_V(8); PG8_WAIT_L(0); PG8_BAR; PG8_MMA(0, 0, At, B0); PG8_MMA(0, 1, At, B1); PG8_BAR; PG8_SCHED;
	s_setprio 1
	s_waitcnt lgkmcnt(0)
	v_mfma_f32_16x16x32_bf16 v[60:63], v[64:67], v[136:139], 0
	v_mfma_f32_16x16x32_bf16 v[52:55], v[72:75], v[136:139], 0
	v_mfma_f32_16x16x32_bf16 v[44:47], v[64:67], v[152:155], 0
	v_mfma_f32_16x16x32_bf16 v[36:39], v[72:75], v[152:155], 0
	v_mfma_f32_16x16x32_bf16 v[28:31], v[64:67], v[176:179], 0
	v_mfma_f32_16x16x32_bf16 v[20:23], v[72:75], v[176:179], 0
	v_mfma_f32_16x16x32_bf16 v[12:15], v[64:67], v[216:219], 0
	v_mfma_f32_16x16x32_bf16 v[8:11], v[72:75], v[216:219], 0
	v_mfma_f32_16x16x32_bf16 v[60:63], v[68:71], v[144:147], v[60:63]
	v_mfma_f32_16x16x32_bf16 v[52:55], v[76:79], v[144:147], v[52:55]
	v_mfma_f32_16x16x32_bf16 v[44:47], v[68:71], v[160:163], v[44:47]
	v_mfma_f32_16x16x32_bf16 v[36:39], v[76:79], v[160:163], v[36:39]
	v_mfma_f32_16x16x32_bf16 v[28:31], v[68:71], v[212:215], v[28:31]
	v_mfma_f32_16x16x32_bf16 v[20:23], v[76:79], v[212:215], v[20:23]
	v_mfma_f32_16x16x32_bf16 v[12:15], v[68:71], v[220:223], v[12:15]
	v_mfma_f32_16x16x32_bf16 v[8:11], v[76:79], v[220:223], v[8:11]
	v_mfma_f32_16x16x32_bf16 v[56:59], v[80:83], v[136:139], 0
	v_mfma_f32_16x16x32_bf16 v[48:51], v[88:91], v[136:139], 0
	v_mfma_f32_16x16x32_bf16 v[40:43], v[80:83], v[152:155], 0
	v_mfma_f32_16x16x32_bf16 v[32:35], v[88:91], v[152:155], 0
	v_mfma_f32_16x16x32_bf16 v[24:27], v[80:83], v[176:179], 0
	v_mfma_f32_16x16x32_bf16 v[16:19], v[88:91], v[176:179], 0
	v_mfma_f32_16x16x32_bf16 v[4:7], v[80:83], v[216:219], 0
	v_mfma_f32_16x16x32_bf16 v[0:3], v[88:91], v[216:219], 0
	v_mfma_f32_16x16x32_bf16 v[56:59], v[84:87], v[144:147], v[56:59]
	v_mfma_f32_16x16x32_bf16 v[48:51], v[92:95], v[144:147], v[48:51]
	v_mfma_f32_16x16x32_bf16 v[40:43], v[84:87], v[160:163], v[40:43]
	v_mfma_f32_16x16x32_bf16 v[32:35], v[92:95], v[160:163], v[32:35]
	v_mfma_f32_16x16x32_bf16 v[24:27], v[84:87], v[212:215], v[24:27]
	v_mfma_f32_16x16x32_bf16 v[16:19], v[92:95], v[212:215], v[16:19]
	v_mfma_f32_16x16x32_bf16 v[4:7], v[84:87], v[220:223], v[4:7]
	v_mfma_f32_16x16x32_bf16 v[0:3], v[92:95], v[220:223], v[0:3]
	s_setprio 0
	s_barrier
	s_add_i32 s76, 0, 0x18000
	s_add_i32 s77, 0, 0x1c000
	v_add_u32_e32 v76, s76, v195
	v_add_u32_e32 v92, s77, v195
	ds_read_b128 v[64:67], v76
	ds_read_b128 v[68:71], v76 offset:1024
	ds_read_b128 v[72:75], v76 offset:2048
	ds_read_b128 v[76:79], v76 offset:3072
	ds_read_b128 v[80:83], v92
	ds_read_b128 v[84:87], v92 offset:1024
	ds_read_b128 v[88:91], v92 offset:2048
	ds_read_b128 v[92:95], v92 offset:3072
	s_add_u32 s50, s50, 0x80000
	s_addc_u32 s51, s51, 0
	s_mov_b32 m0, s59
	v_lshl_add_u64 v[152:153], s[50:51], 0, v[180:181]
	ds_read_b128 v[136:139], v199 offset:32768
	ds_read_b128 v[144:147], v199 offset:33792
	ds_read_b128 v[176:179], v199 offset:34816
	ds_read_b128 v[212:215], v199 offset:35840
	ds_read_b128 v[216:219], v199 offset:36864
	ds_read_b128 v[220:223], v199 offset:37888
	ds_read_b128 v[224:227], v199 offset:38912
	ds_read_b128 v[228:231], v199 offset:39936
	global_load_lds_dwordx4 v[152:153], off
	v_lshl_add_u64 v[152:153], s[50:51], 0, v[184:185]
	s_mov_b32 m0, s60
	s_nop 0
	global_load_lds_dwordx4 v[152:153], off
	s_waitcnt vmcnt(8)
	s_waitcnt lgkmcnt(0)
	s_barrier
	s_setprio 1
	s_waitcnt lgkmcnt(0)
	v_mfma_f32_16x16x32_bf16 v[152:155], v[64:67], v[136:139], v[172:175]
	v_mfma_f32_16x16x32_bf16 v[172:175], v[68:71], v[144:147], v[152:155]
	v_mfma_f32_16x16x32_bf16 v[152:155], v[72:75], v[136:139], v[164:167]
	v_mfma_f32_16x16x32_bf16 v[164:167], v[76:79], v[144:147], v[152:155]
	v_mfma_f32_16x16x32_bf16 v[152:155], v[64:67], v[176:179], v[156:159]
	v_mfma_f32_16x16x32_bf16 v[148:151], v[72:75], v[176:179], v[148:151]
	v_mfma_f32_16x16x32_bf16 v[140:143], v[64:67], v[216:219], v[140:143]
	v_mfma_f32_16x16x32_bf16 v[132:135], v[72:75], v[216:219], v[132:135]
	v_mfma_f32_16x16x32_bf16 v[124:127], v[64:67], v[224:227], v[124:127]
	v_mfma_f32_16x16x32_bf16 v[120:123], v[72:75], v[224:227], v[120:123]
	v_mfma_f32_16x16x32_bf16 v[156:159], v[68:71], v[212:215], v[152:155]
	v_mfma_f32_16x16x32_bf16 v[148:151], v[76:79], v[212:215], v[148:151]
	v_mfma_f32_16x16x32_bf16 v[140:143], v[68:71], v[220:223], v[140:143]
	v_mfma_f32_16x16x32_bf16 v[132:135], v[76:79], v[220:223], v[132:135]
	v_mfma_f32_16x16x32_bf16 v[124:127], v[68:71], v[228:231], v[124:127]
	v_mfma_f32_16x16x32_bf16 v[120:123], v[76:79], v[228:231], v[120:123]
	v_mfma_f32_16x16x32_bf16 v[96:99], v[88:91], v[136:139], v[96:99]
	v_mfma_f32_16x16x32_bf16 v[152:155], v[80:83], v[136:139], v[168:171]
	v_mfma_f32_16x16x32_bf16 v[160:163], v[92:95], v[144:147], v[96:99]
	v_mfma_f32_16x16x32_bf16 v[96:99], v[80:83], v[176:179], v[100:103]
	v_mfma_f32_16x16x32_bf16 v[168:171], v[84:87], v[144:147], v[152:155]
	v_mfma_f32_16x16x32_bf16 v[152:155], v[84:87], v[212:215], v[96:99]
	v_mfma_f32_16x16x32_bf16 v[96:99], v[88:91], v[176:179], v[104:107]
	v_mfma_f32_16x16x32_bf16 v[144:147], v[92:95], v[212:215], v[96:99]
	v_mfma_f32_16x16x32_bf16 v[96:99], v[80:83], v[216:219], v[108:111]
	v_mfma_f32_16x16x32_bf16 v[136:139], v[84:87], v[220:223], v[96:99]
	v_mfma_f32_16x16x32_bf16 v[96:99], v[88:91], v[216:219], v[128:131]
	v_mfma_f32_16x16x32_bf16 v[128:131], v[92:95], v[220:223], v[96:99]
	v_mfma_f32_16x16x32_bf16 v[96:99], v[80:83], v[224:227], v[116:119]
	v_mfma_f32_16x16x32_bf16 v[116:119], v[84:87], v[228:231], v[96:99]
	v_mfma_f32_16x16x32_bf16 v[96:99], v[88:91], v[224:227], v[112:115]
	v_mfma_f32_16x16x32_bf16 v[112:115], v[92:95], v[228:231], v[96:99]
	s_setprio 0
	s_barrier
; #define PG8_STAGE(bufoff, gbase, voff) do { _Pragma("unroll") for (int _i = 0; _i < 2; ++_i) \
;         __builtin_amdgcn_global_load_lds((const unsigned*)((const char*)(gbase) + (voff)[_i]), (PG8_LAS unsigned*)(lds + (bufoff) + ldsw + _i * 8192), 16, 0, 0); } while (0)
; #define PG8_LDA(dst, b, h) do { _Pragma("unroll") for (int m = 0; m < 4; ++m) _Pragma("unroll") for (int k = 0; k < 2; ++k) dst[m][k] = *(const PG8_LAS bf16x8*)(lds + PG8_SA(b, h) + aoff + m * 2048 + k * 1024); } while (0)
; #define PG8_WAIT_V(n) asm volatile("s_waitcnt vmcnt(" #n ")" ::: "memory")
; #define PG8_WAIT_L(n) asm volatile("s_waitcnt lgkmcnt(" #n ")" ::: "memory")
; #define PG8_BAR __builtin_amdgcn_s_barrier()
; template <class Epi, class Sched, bool ALIGN_EPI = false, bool SP2 = false>
; __device__ __forceinline__ void gemm_phase(PG8_LAS unsigned char* lds, const Gemm g, const Sched& S, const Epi& E, const int wave_in) {
;     ...
;         for (int t = 0; t < nt; t += 2) {
;             const bool last = (t == nt - 2);
;             const char* a1 = cA + (size_t)(t + 1) * kstep;
;             const char* a2 = last ? nA : cA + (size_t)(t + 2) * kstep; const char* b2 = last ? nB : cB + (size_t)(t + 2) * kstep;
;             const char* a3 = a2 + kstep; const char* b3 = b2 + kstep;
;             if (last && has_next) S.a_ready(nxt);
;             if constexpr (SP2) {
;             PG8_LDB(B0, 0, 0); PG8_LDB(B1, 0, 1); PG8_SCHED; PG8_LDA(At, 0, 0); PG8_STAGE(PG8_SA(1, 1), a1 + hstepA, voffA);
;             PG8_WAIT_V(8); PG8_WAIT_L(0); PG8_BAR; PG8_MMA(0, 0, At, B0); PG8_MMA(0, 1, At, B1); PG8_BAR; PG8_SCHED;
;             PG8_LDA(At, 0, 1); PG8_STAGE(PG8_SB(0, 0), b2, voffB); PG8_STAGE(PG8_SB(0, 1), b2 + hstepB, voffB); PG8_STAGE(PG8_SA(0, 0), a2, voffA);
;             PG8_WAIT_V(8); PG8_WAIT_L(0); PG8_BAR; PG8_MMA(1, 0, At, B0); PG8_MMA(1, 1, At, B1); PG8_BAR; PG8_SCHED;
;             PG8_LDB(B0, 1, 0); PG8_LDB(B1, 1, 1); PG8_SCHED; PG8_LDA(At, 1, 0); PG8_STAGE(PG8_SA(0, 1), a2 + hstepA, voffA);
;             PG8_WAIT_V(8); PG8_WAIT_L(0); PG8_BAR; PG8_MMA(0, 0, At, B0); PG8_MMA(0, 1, At, B1); PG8_BAR; PG8_SCHED;
;             PG8_LDA(At, 1, 1); PG8_STAGE(PG8_SB(1, 0), b3, voffB); PG8_STAGE(PG8_SB(1, 1), b3 + hstepB, voffB); PG8_STAGE(PG8_SA(1, 0), a3, voffA);
;             PG8_WAIT_V(8); PG8_WAIT_L(0); PG8_BAR; PG8_MMA(1, 0, At, B0); PG8_MMA(1, 1, At, B1); PG8_BAR; PG8_SCHED;
	s_add_i32 s50, s76, s56
	v_lshl_add_u64 v[224:225], v[232:233], 0, s[20:21]
	s_mov_b32 m0, s50
	s_nop 1
	ds_read_b128 v[96:99], v199 offset:49152
	ds_read_b128 v[100:103], v199 offset:50176
	ds_read_b128 v[104:107], v199 offset:51200
	ds_read_b128 v[108:111], v199 offset:52224
	ds_read_b128 v[176:179], v199 offset:53248
	ds_read_b128 v[212:215], v199 offset:54272
	ds_read_b128 v[216:219], v199 offset:55296
	ds_read_b128 v[220:223], v199 offset:56320
	global_load_lds_dwordx4 v[224:225], off
	s_add_i32 m0, s50, 0x2000
	s_add_u32 s48, s48, 0x80080
	v_lshl_add_u64 v[224:225], v[234:235], 0, s[20:21]
	s_addc_u32 s49, s49, 0
	s_add_i32 s50, s77, s56
	global_load_lds_dwordx4 v[224:225], off
	v_lshl_add_u64 v[224:225], s[48:49], 0, v[182:183]
	s_mov_b32 m0, s50
	s_nop 0
	global_load_lds_dwordx4 v[224:225], off
	v_lshl_add_u64 v[224:225], s[48:49], 0, v[186:187]
	s_add_i32 m0, s50, 0x2000
	s_nop 0
	global_load_lds_dwordx4 v[224:225], off
	v_lshl_add_u64 v[224:225], v[236:237], 0, s[20:21]
	s_mov_b32 m0, s63
	s_nop 0
	global_load_lds_dwordx4 v[224:225], off
	v_lshl_add_u64 v[224:225], v[238:239], 0, s[20:21]
	s_mov_b32 m0, s64
	s_nop 0
	global_load_lds_dwordx4 v[224:225], off
	s_waitcnt vmcnt(8)
	s_waitcnt lgkmcnt(0)
	s_barrier
	s_setprio 1
	s_waitcnt lgkmcnt(0)
	v_mfma_f32_16x16x32_bf16 v[60:63], v[64:67], v[96:99], v[60:63]
	v_mfma_f32_16x16x32_bf16 v[52:55], v[72:75], v[96:99], v[52:55]
	v_mfma_f32_16x16x32_bf16 v[44:47], v[64:67], v[104:107], v[44:47]
	v_mfma_f32_16x16x32_bf16 v[36:39], v[72:75], v[104:107], v[36:39]
	v_mfma_f32_16x16x32_bf16 v[28:31], v[64:67], v[176:179], v[28:31]
	v_mfma_f32_16x16x32_bf16 v[20:23], v[72:75], v[176:179], v[20:23]
	v_mfma_f32_16x16x32_bf16 v[12:15], v[64:67], v[216:219], v[12:15]
	v_mfma_f32_16x16x32_bf16 v[8:11], v[72:75], v[216:219], v[8:11]
	v_mfma_f32_16x16x32_bf16 v[60:63], v[68:71], v[100:103], v[60:63]
	v_mfma_f32_16x16x32_bf16 v[52:55], v[76:79], v[100:103], v[52:55]
	v_mfma_f32_16x16x32_bf16 v[44:47], v[68:71], v[108:111], v[44:47]
	v_mfma_f32_16x16x32_bf16 v[36:39], v[76:79], v[108:111], v[36:39]
	v_mfma_f32_16x16x32_bf16 v[28:31], v[68:71], v[212:215], v[28:31]
	v_mfma_f32_16x16x32_bf16 v[20:23], v[76:79], v[212:215], v[20:23]
	v_mfma_f32_16x16x32_bf16 v[12:15], v[68:71], v[220:223], v[12:15]
	v_mfma_f32_16x16x32_bf16 v[8:11], v[76:79], v[220:223], v[8:11]
	v_mfma_f32_16x16x32_bf16 v[56:59], v[80:83], v[96:99], v[56:59]
	v_mfma_f32_16x16x32_bf16 v[48:51], v[88:91], v[96:99], v[48:51]
	v_mfma_f32_16x16x32_bf16 v[40:43], v[80:83], v[104:107], v[40:43]
	v_mfma_f32_16x16x32_bf16 v[32:35], v[88:91], v[104:107], v[32:35]
	v_mfma_f32_16x16x32_bf16 v[24:27], v[80:83], v[176:179], v[24:27]
	v_mfma_f32_16x16x32_bf16 v[16:19], v[88:91], v[176:179], v[16:19]
	v_mfma_f32_16x16x32_bf16 v[4:7], v[80:83], v[216:219], v[4:7]
	v_mfma_f32_16x16x32_bf16 v[0:3], v[88:91], v[216:219], v[0:3]
	v_mfma_f32_16x16x32_bf16 v[56:59], v[84:87], v[100:103], v[56:59]
	v_mfma_f32_16x16x32_bf16 v[48:51], v[92:95], v[100:103], v[48:51]
	v_mfma_f32_16x16x32_bf16 v[40:43], v[84:87], v[108:111], v[40:43]
	v_mfma_f32_16x16x32_bf16 v[32:35], v[92:95], v[108:111], v[32:35]
	v_mfma_f32_16x16x32_bf16 v[24:27], v[84:87], v[212:215], v[24:27]
	v_mfma_f32_16x16x32_bf16 v[16:19], v[92:95], v[212:215], v[16:19]
	v_mfma_f32_16x16x32_bf16 v[4:7], v[84:87], v[220:223], v[4:7]
	v_mfma_f32_16x16x32_bf16 v[0:3], v[92:95], v[220:223], v[0:3]
	s_setprio 0
	s_barrier
	s_add_i32 s75, s75, 2
	s_add_u32 s46, s46, 0x100
	s_addc_u32 s47, s47, 0
	s_add_u32 s72, s72, 0x100
	s_addc_u32 s73, s73, 0
	s_cmp_gt_u32 s75, 29
	s_cbranch_scc0 .LBB0_2577
	s_branch .Lkx_30
.LBB0_2577:
	ds_read_b128 v[64:67], v189
	ds_read_b128 v[68:71], v189 offset:1024
	ds_read_b128 v[72:75], v189 offset:2048
	ds_read_b128 v[76:79], v189 offset:3072
	ds_read_b128 v[80:83], v197
	ds_read_b128 v[84:87], v197 offset:1024
	ds_read_b128 v[88:91], v197 offset:2048
	ds_read_b128 v[92:95], v197 offset:3072
	s_add_u32 s48, s46, 0xfff80080
	s_addc_u32 s49, s47, -1
	s_cmp_eq_u32 s75, 28
	s_cselect_b32 s51, s11, s49
	s_cselect_b32 s50, s39, s48
	s_cselect_b32 s49, s37, s73
	s_cselect_b32 s48, s45, s72
	v_lshl_add_u64 v[224:225], s[46:47], 0, v[206:207]
	s_add_i32 m0, s57, 0xc000
	ds_read_b128 v[96:99], v199
	ds_read_b128 v[100:103], v199 offset:1024
	ds_read_b128 v[104:107], v199 offset:2048
	ds_read_b128 v[108:111], v199 offset:3072
	ds_read_b128 v[176:179], v199 offset:4096
	ds_read_b128 v[212:215], v199 offset:5120
	ds_read_b128 v[216:219], v199 offset:6144
	ds_read_b128 v[220:223], v199 offset:7168
	global_load_lds_dwordx4 v[224:225], off
	v_lshl_add_u64 v[224:225], s[46:47], 0, v[208:209]
	s_add_i32 m0, s57, 0xe000
	s_nop 0
	global_load_lds_dwordx4 v[224:225], off
	s_waitcnt vmcnt(8)
	s_waitcnt lgkmcnt(0)
	s_barrier
; #define PG8_STAGE(bufoff, gbase, voff) do { _Pragma("unroll") for (int _i = 0; _i < 2; ++_i) \
;         __builtin_amdgcn_global_load_lds((const unsigned*)((const char*)(gbase) + (voff)[_i]), (PG8_LAS unsigned*)(lds + (bufoff) + ldsw + _i * 8192), 16, 0, 0); } while (0)
; #define PG8_LDA(dst, b, h) do { _Pragma("unroll") for (int m = 0; m < 4; ++m) _Pragma("unroll") for (int k = 0; k < 2; ++k) dst[m][k] = *(const PG8_LAS bf16x8*)(lds + PG8_SA(b, h) + aoff + m * 2048 + k * 1024); } while (0)
; #define PG8_LDB(dst, b, h) do { _Pragma("unroll") for (int n = 0; n < 2; ++n) _Pragma("unroll") for (int k = 0; k < 2; ++k) dst[n][k] = *(const PG8_LAS bf16x8*)(lds + PG8_SB(b, h) + boff + n * 2048 + k * 1024); } while (0)
; #define PG8_MMA(ai, bj, At, Bt) do { __builtin_amdgcn_s_setprio(1); _Pragma("unroll") for (int m = 0; m < 4; ++m) _Pragma("unroll") for (int n = 0; n < 2; ++n) _Pragma("unroll") for (int k = 0; k < 2; ++k) \
;         acc[ai][bj][m][n] = __builtin_amdgcn_mfma_f32_16x16x32_bf16(Bt[n][k], At[m][k], acc[ai][bj][m][n], 0, 0, 0); __builtin_amdgcn_s_setprio(0); } while (0)
; #define PG8_WAIT_V(n) asm volatile("s_waitcnt vmcnt(" #n ")" ::: "memory")
; #define PG8_WAIT_L(n) asm volatile("s_waitcnt lgkmcnt(" #n ")" ::: "memory")
; #define PG8_BAR __builtin_amdgcn_s_barrier()
; #define PG8_SCHED __builtin_amdgcn_sched_barrier(0)
; template <class Epi, class Sched, bool ALIGN_EPI = false, bool SP2 = false>
; __device__ __forceinline__ void gemm_phase(PG8_LAS unsigned char* lds, const Gemm g, const Sched& S, const Epi& E, const int wave_in) {
;     ...
;             PG8_LDB(B0, 0, 0); PG8_LDB(B1, 0, 1); PG8_SCHED; PG8_LDA(At, 0, 0); PG8_STAGE(PG8_SA(1, 1), a1 + hstepA, voffA);
;             PG8_WAIT_V(8); PG8_WAIT_L(0); PG8_BAR; PG8_MMA(0, 0, At, B0); PG8_MMA(0, 1, At, B1); PG8_BAR; PG8_SCHED;
;             PG8_LDA(At, 0, 1); PG8_STAGE(PG8_SB(0, 0), b2, voffB); PG8_STAGE(PG8_SB(0, 1), b2 + hstepB, voffB); PG8_STAGE(PG8_SA(0, 0), a2, voffA);
;             PG8_WAIT_V(8); PG8_WAIT_L(0); PG8_BAR; PG8_MMA(1, 0, At, B0); PG8_MMA(1, 1, At, B1); PG8_BAR; PG8_SCHED;
	s_setprio 1
	s_waitcnt lgkmcnt(0)
	v_mfma_f32_16x16x32_bf16 v[172:175], v[64:67], v[96:99], v[172:175]
	v_mfma_f32_16x16x32_bf16 v[164:167], v[72:75], v[96:99], v[164:167]
	v_mfma_f32_16x16x32_bf16 v[156:159], v[64:67], v[104:107], v[156:159]
	v_mfma_f32_16x16x32_bf16 v[148:151], v[72:75], v[104:107], v[148:151]
	v_mfma_f32_16x16x32_bf16 v[140:143], v[64:67], v[176:179], v[140:143]
	v_mfma_f32_16x16x32_bf16 v[132:135], v[72:75], v[176:179], v[132:135]
	v_mfma_f32_16x16x32_bf16 v[124:127], v[64:67], v[216:219], v[124:127]
	v_mfma_f32_16x16x32_bf16 v[120:123], v[72:75], v[216:219], v[120:123]
	v_mfma_f32_16x16x32_bf16 v[172:175], v[68:71], v[100:103], v[172:175]
	v_mfma_f32_16x16x32_bf16 v[164:167], v[76:79], v[100:103], v[164:167]
	v_mfma_f32_16x16x32_bf16 v[156:159], v[68:71], v[108:111], v[156:159]
	v_mfma_f32_16x16x32_bf16 v[148:151], v[76:79], v[108:111], v[148:151]
	v_mfma_f32_16x16x32_bf16 v[140:143], v[68:71], v[212:215], v[140:143]
	v_mfma_f32_16x16x32_bf16 v[132:135], v[76:79], v[212:215], v[132:135]
	v_mfma_f32_16x16x32_bf16 v[124:127], v[68:71], v[220:223], v[124:127]
	v_mfma_f32_16x16x32_bf16 v[120:123], v[76:79], v[220:223], v[120:123]
	v_mfma_f32_16x16x32_bf16 v[168:171], v[80:83], v[96:99], v[168:171]
	v_mfma_f32_16x16x32_bf16 v[96:99], v[88:91], v[96:99], v[160:163]
	v_mfma_f32_16x16x32_bf16 v[168:171], v[84:87], v[100:103], v[168:171]
	v_mfma_f32_16x16x32_bf16 v[96:99], v[92:95], v[100:103], v[96:99]
	v_mfma_f32_16x16x32_bf16 v[100:103], v[80:83], v[104:107], v[152:155]
	v_mfma_f32_16x16x32_bf16 v[104:107], v[88:91], v[104:107], v[144:147]
	v_mfma_f32_16x16x32_bf16 v[128:131], v[88:91], v[176:179], v[128:131]
	v_mfma_f32_16x16x32_bf16 v[116:119], v[80:83], v[216:219], v[116:119]
	v_mfma_f32_16x16x32_bf16 v[112:115], v[88:91], v[216:219], v[112:115]
	v_mfma_f32_16x16x32_bf16 v[100:103], v[84:87], v[108:111], v[100:103]
	v_mfma_f32_16x16x32_bf16 v[104:107], v[92:95], v[108:111], v[104:107]
	v_mfma_f32_16x16x32_bf16 v[108:111], v[80:83], v[176:179], v[136:139]
	v_mfma_f32_16x16x32_bf16 v[128:131], v[92:95], v[212:215], v[128:131]
	v_mfma_f32_16x16x32_bf16 v[116:119], v[84:87], v[220:223], v[116:119]
	v_mfma_f32_16x16x32_bf16 v[112:115], v[92:95], v[220:223], v[112:115]
	v_mfma_f32_16x16x32_bf16 v[108:111], v[84:87], v[212:215], v[108:111]
	s_setprio 0
	s_barrier
	s_add_i32 s76, s69, s56
	v_lshl_add_u64 v[232:233], s[48:49], 0, v[182:183]
	s_mov_b32 m0, s76
	ds_read_b128 v[136:139], v199 offset:16384
	ds_read_b128 v[144:147], v199 offset:17408
	ds_read_b128 v[152:155], v199 offset:18432
	ds_read_b128 v[160:163], v199 offset:19456
	ds_read_b128 v[176:179], v199 offset:20480
	ds_read_b128 v[212:215], v199 offset:21504
	ds_read_b128 v[216:219], v199 offset:22528
	ds_read_b128 v[220:223], v199 offset:23552
	global_load_lds_dwordx4 v[232:233], off
	s_add_i32 m0, s76, 0x2000
	s_add_u32 s76, s48, 0x80000
	v_lshl_add_u64 v[234:235], s[48:49], 0, v[186:187]
	s_addc_u32 s77, s49, 0
	s_add_i32 s78, s70, s56
	global_load_lds_dwordx4 v[234:235], off
	v_lshl_add_u64 v[224:225], s[76:77], 0, v[182:183]
	s_mov_b32 m0, s78
	v_lshl_add_u64 v[236:237], s[50:51], 0, v[180:181]
	global_load_lds_dwordx4 v[224:225], off
	v_lshl_add_u64 v[224:225], s[76:77], 0, v[186:187]
	s_add_i32 m0, s78, 0x2000
	v_lshl_add_u64 v[238:239], s[50:51], 0, v[184:185]
	global_load_lds_dwordx4 v[224:225], off
	s_mov_b32 m0, s57
	s_nop 0
	global_load_lds_dwordx4 v[236:237], off
	s_mov_b32 m0, s58
	s_nop 0
	global_load_lds_dwordx4 v[238:239], off
	s_waitcnt vmcnt(8)
	s_waitcnt lgkmcnt(0)
	s_barrier
	s_setprio 1
	s_waitcnt lgkmcnt(0)
	v_mfma_f32_16x16x32_bf16 v[60:63], v[64:67], v[136:139], v[60:63]
	v_mfma_f32_16x16x32_bf16 v[52:55], v[72:75], v[136:139], v[52:55]
	v_mfma_f32_16x16x32_bf16 v[44:47], v[64:67], v[152:155], v[44:47]
	v_mfma_f32_16x16x32_bf16 v[36:39], v[72:75], v[152:155], v[36:39]
	v_mfma_f32_16x16x32_bf16 v[28:31], v[64:67], v[176:179], v[28:31]
	v_mfma_f32_16x16x32_bf16 v[20:23], v[72:75], v[176:179], v[20:23]
	v_mfma_f32_16x16x32_bf16 v[12:15], v[64:67], v[216:219], v[12:15]
	v_mfma_f32_16x16x32_bf16 v[8:11], v[72:75], v[216:219], v[8:11]
	v_mfma_f32_16x16x32_bf16 v[60:63], v[68:71], v[144:147], v[60:63]
	v_mfma_f32_16x16x32_bf16 v[52:55], v[76:79], v[144:147], v[52:55]
	v_mfma_f32_16x16x32_bf16 v[44:47], v[68:71], v[160:163], v[44:47]
	v_mfma_f32_16x16x32_bf16 v[36:39], v[76:79], v[160:163], v[36:39]
	v_mfma_f32_16x16x32_bf16 v[28:31], v[68:71], v[212:215], v[28:31]
	v_mfma_f32_16x16x32_bf16 v[20:23], v[76:79], v[212:215], v[20:23]
	v_mfma_f32_16x16x32_bf16 v[12:15], v[68:71], v[220:223], v[12:15]
	v_mfma_f32_16x16x32_bf16 v[8:11], v[76:79], v[220:223], v[8:11]
	v_mfma_f32_16x16x32_bf16 v[56:59], v[80:83], v[136:139], v[56:59]
	v_mfma_f32_16x16x32_bf16 v[48:51], v[88:91], v[136:139], v[48:51]
	v_mfma_f32_16x16x32_bf16 v[40:43], v[80:83], v[152:155], v[40:43]
	v_mfma_f32_16x16x32_bf16 v[32:35], v[88:91], v[152:155], v[32:35]
	v_mfma_f32_16x16x32_bf16 v[24:27], v[80:83], v[176:179], v[24:27]
	v_mfma_f32_16x16x32_bf16 v[16:19], v[88:91], v[176:179], v[16:19]
	v_mfma_f32_16x16x32_bf16 v[4:7], v[80:83], v[216:219], v[4:7]
	v_mfma_f32_16x16x32_bf16 v[0:3], v[88:91], v[216:219], v[0:3]
	v_mfma_f32_16x16x32_bf16 v[56:59], v[84:87], v[144:147], v[56:59]
	v_mfma_f32_16x16x32_bf16 v[48:51], v[92:95], v[144:147], v[48:51]
	v_mfma_f32_16x16x32_bf16 v[40:43], v[84:87], v[160:163], v[40:43]
	v_mfma_f32_16x16x32_bf16 v[32:35], v[92:95], v[160:163], v[32:35]
	v_mfma_f32_16x16x32_bf16 v[24:27], v[84:87], v[212:215], v[24:27]
	v_mfma_f32_16x16x32_bf16 v[16:19], v[92:95], v[212:215], v[16:19]
	v_mfma_f32_16x16x32_bf16 v[4:7], v[84:87], v[220:223], v[4:7]
	v_mfma_f32_16x16x32_bf16 v[0:3], v[92:95], v[220:223], v[0:3]
	s_setprio 0
	s_barrier
; #define PG8_STAGE(bufoff, gbase, voff) do { _Pragma("unroll") for (int _i = 0; _i < 2; ++_i) \
;         __builtin_amdgcn_global_load_lds((const unsigned*)((const char*)(gbase) + (voff)[_i]), (PG8_LAS unsigned*)(lds + (bufoff) + ldsw + _i * 8192), 16, 0, 0); } while (0)
; #define PG8_LDA(dst, b, h) do { _Pragma("unroll") for (int m = 0; m < 4; ++m) _Pragma("unroll") for (int k = 0; k < 2; ++k) dst[m][k] = *(const PG8_LAS bf16x8*)(lds + PG8_SA(b, h) + aoff + m * 2048 + k * 1024); } while (0)
; #define PG8_LDB(dst, b, h) do { _Pragma("unroll") for (int n = 0; n < 2; ++n) _Pragma("unroll") for (int k = 0; k < 2; ++k) dst[n][k] = *(const PG8_LAS bf16x8*)(lds + PG8_SB(b, h) + boff + n * 2048 + k * 1024); } while (0)
; #define PG8_MMA(ai, bj, At, Bt) do { __builtin_amdgcn_s_setprio(1); _Pragma("unroll") for (int m = 0; m < 4; ++m) _Pragma("unroll") for (int n = 0; n < 2; ++n) _Pragma("unroll") for (int k = 0; k < 2; ++k) \
;         acc[ai][bj][m][n] = __builtin_amdgcn_mfma_f32_16x16x32_bf16(Bt[n][k], At[m][k], acc[ai][bj][m][n], 0, 0, 0); __builtin_amdgcn_s_setprio(0); } while (0)
; #define PG8_WAIT_V(n) asm volatile("s_waitcnt vmcnt(" #n ")" ::: "memory")
; #define PG8_WAIT_L(n) asm volatile("s_waitcnt lgkmcnt(" #n ")" ::: "memory")
; #define PG8_BAR __builtin_amdgcn_s_barrier()
; #define PG8_SCHED __builtin_amdgcn_sched_barrier(0)
; template <class Epi, class Sched, bool ALIGN_EPI = false, bool SP2 = false>
; __device__ __forceinline__ void gemm_phase(PG8_LAS unsigned char* lds, const Gemm g, const Sched& S, const Epi& E, const int wave_in) {
;     ...
;             PG8_LDB(B0, 1, 0); PG8_LDB(B1, 1, 1); PG8_SCHED; PG8_LDA(At, 1, 0); PG8_STAGE(PG8_SA(0, 1), a2 + hstepA, voffA);
;             PG8_WAIT_V(8); PG8_WAIT_L(0); PG8_BAR; PG8_MMA(0, 0, At, B0); PG8_MMA(0, 1, At, B1); PG8_BAR; PG8_SCHED;
;             PG8_LDA(At, 1, 1); PG8_STAGE(PG8_SB(1, 0), b3, voffB); PG8_STAGE(PG8_SB(1, 1), b3 + hstepB, voffB); PG8_STAGE(PG8_SA(1, 0), a3, voffA);
;             PG8_WAIT_V(8); PG8_WAIT_L(0); PG8_BAR; PG8_MMA(1, 0, At, B0); PG8_MMA(1, 1, At, B1); PG8_BAR; PG8_SCHED;
	s_add_i32 s76, 0, 0x18000
	s_add_i32 s77, 0, 0x1c000
	v_add_u32_e32 v76, s76, v195
	v_add_u32_e32 v92, s77, v195
	ds_read_b128 v[64:67], v76
	ds_read_b128 v[68:71], v76 offset:1024
	ds_read_b128 v[72:75], v76 offset:2048
	ds_read_b128 v[76:79], v76 offset:3072
	ds_read_b128 v[80:83], v92
	ds_read_b128 v[84:87], v92 offset:1024
	ds_read_b128 v[88:91], v92 offset:2048
	ds_read_b128 v[92:95], v92 offset:3072
	s_add_u32 s50, s50, 0x80000
	s_addc_u32 s51, s51, 0
	s_mov_b32 m0, s59
	v_lshl_add_u64 v[152:153], s[50:51], 0, v[180:181]
	ds_read_b128 v[136:139], v199 offset:32768
	ds_read_b128 v[144:147], v199 offset:33792
	ds_read_b128 v[176:179], v199 offset:34816
	ds_read_b128 v[212:215], v199 offset:35840
	ds_read_b128 v[216:219], v199 offset:36864
	ds_read_b128 v[220:223], v199 offset:37888
	ds_read_b128 v[224:227], v199 offset:38912
	ds_read_b128 v[228:231], v199 offset:39936
	global_load_lds_dwordx4 v[152:153], off
	v_lshl_add_u64 v[152:153], s[50:51], 0, v[184:185]
	s_mov_b32 m0, s60
	s_nop 0
	global_load_lds_dwordx4 v[152:153], off
	s_waitcnt vmcnt(8)
	s_waitcnt lgkmcnt(0)
	s_barrier
	s_setprio 1
	s_waitcnt lgkmcnt(0)
	v_mfma_f32_16x16x32_bf16 v[152:155], v[64:67], v[136:139], v[172:175]
	v_mfma_f32_16x16x32_bf16 v[172:175], v[68:71], v[144:147], v[152:155]
	v_mfma_f32_16x16x32_bf16 v[152:155], v[72:75], v[136:139], v[164:167]
	v_mfma_f32_16x16x32_bf16 v[164:167], v[76:79], v[144:147], v[152:155]
	v_mfma_f32_16x16x32_bf16 v[152:155], v[64:67], v[176:179], v[156:159]
	v_mfma_f32_16x16x32_bf16 v[148:151], v[72:75], v[176:179], v[148:151]
	v_mfma_f32_16x16x32_bf16 v[140:143], v[64:67], v[216:219], v[140:143]
	v_mfma_f32_16x16x32_bf16 v[132:135], v[72:75], v[216:219], v[132:135]
	v_mfma_f32_16x16x32_bf16 v[124:127], v[64:67], v[224:227], v[124:127]
	v_mfma_f32_16x16x32_bf16 v[120:123], v[72:75], v[224:227], v[120:123]
	v_mfma_f32_16x16x32_bf16 v[156:159], v[68:71], v[212:215], v[152:155]
	v_mfma_f32_16x16x32_bf16 v[148:151], v[76:79], v[212:215], v[148:151]
	v_mfma_f32_16x16x32_bf16 v[140:143], v[68:71], v[220:223], v[140:143]
	v_mfma_f32_16x16x32_bf16 v[132:135], v[76:79], v[220:223], v[132:135]
	v_mfma_f32_16x16x32_bf16 v[124:127], v[68:71], v[228:231], v[124:127]
	v_mfma_f32_16x16x32_bf16 v[120:123], v[76:79], v[228:231], v[120:123]
	v_mfma_f32_16x16x32_bf16 v[96:99], v[88:91], v[136:139], v[96:99]
	v_mfma_f32_16x16x32_bf16 v[152:155], v[80:83], v[136:139], v[168:171]
	v_mfma_f32_16x16x32_bf16 v[160:163], v[92:95], v[144:147], v[96:99]
	v_mfma_f32_16x16x32_bf16 v[96:99], v[80:83], v[176:179], v[100:103]
	v_mfma_f32_16x16x32_bf16 v[168:171], v[84:87], v[144:147], v[152:155]
	v_mfma_f32_16x16x32_bf16 v[152:155], v[84:87], v[212:215], v[96:99]
	v_mfma_f32_16x16x32_bf16 v[96:99], v[88:91], v[176:179], v[104:107]
	v_mfma_f32_16x16x32_bf16 v[144:147], v[92:95], v[212:215], v[96:99]
	v_mfma_f32_16x16x32_bf16 v[96:99], v[80:83], v[216:219], v[108:111]
	v_mfma_f32_16x16x32_bf16 v[136:139], v[84:87], v[220:223], v[96:99]
	v_mfma_f32_16x16x32_bf16 v[96:99], v[88:91], v[216:219], v[128:131]
	v_mfma_f32_16x16x32_bf16 v[128:131], v[92:95], v[220:223], v[96:99]
	v_mfma_f32_16x16x32_bf16 v[96:99], v[80:83], v[224:227], v[116:119]
	v_mfma_f32_16x16x32_bf16 v[116:119], v[84:87], v[228:231], v[96:99]
	v_mfma_f32_16x16x32_bf16 v[96:99], v[88:91], v[224:227], v[112:115]
	v_mfma_f32_16x16x32_bf16 v[112:115], v[92:95], v[228:231], v[96:99]
	s_setprio 0
	s_barrier
	s_add_i32 s50, s76, s56
	v_lshl_add_u64 v[224:225], v[232:233], 0, s[20:21]
	s_mov_b32 m0, s50
	s_nop 1
	ds_read_b128 v[96:99], v199 offset:49152
	ds_read_b128 v[100:103], v199 offset:50176
	ds_read_b128 v[104:107], v199 offset:51200
	ds_read_b128 v[108:111], v199 offset:52224
	ds_read_b128 v[176:179], v199 offset:53248
	ds_read_b128 v[212:215], v199 offset:54272
	ds_read_b128 v[216:219], v199 offset:55296
	ds_read_b128 v[220:223], v199 offset:56320
	global_load_lds_dwordx4 v[224:225], off
	s_add_i32 m0, s50, 0x2000
	s_add_u32 s48, s48, 0x80080
	v_lshl_add_u64 v[224:225], v[234:235], 0, s[20:21]
	s_addc_u32 s49, s49, 0
	s_add_i32 s50, s77, s56
	global_load_lds_dwordx4 v[224:225], off
	v_lshl_add_u64 v[224:225], s[48:49], 0, v[182:183]
	s_mov_b32 m0, s50
	s_nop 0
	global_load_lds_dwordx4 v[224:225], off
	v_lshl_add_u64 v[224:225], s[48:49], 0, v[186:187]
	s_add_i32 m0, s50, 0x2000
	s_nop 0
	global_load_lds_dwordx4 v[224:225], off
	v_lshl_add_u64 v[224:225], v[236:237], 0, s[20:21]
	s_mov_b32 m0, s63
	s_nop 0
	global_load_lds_dwordx4 v[224:225], off
	v_lshl_add_u64 v[224:225], v[238:239], 0, s[20:21]
	s_mov_b32 m0, s64
	s_nop 0
	global_load_lds_dwordx4 v[224:225], off
	s_waitcnt vmcnt(8)
	s_waitcnt lgkmcnt(0)
	s_barrier
	s_setprio 1
	s_waitcnt lgkmcnt(0)
	v_mfma_f32_16x16x32_bf16 v[60:63], v[64:67], v[96:99], v[60:63]
	v_mfma_f32_16x16x32_bf16 v[52:55], v[72:75], v[96:99], v[52:55]
	v_mfma_f32_16x16x32_bf16 v[44:47], v[64:67], v[104:107], v[44:47]
	v_mfma_f32_16x16x32_bf16 v[36:39], v[72:75], v[104:107], v[36:39]
	v_mfma_f32_16x16x32_bf16 v[28:31], v[64:67], v[176:179], v[28:31]
	v_mfma_f32_16x16x32_bf16 v[20:23], v[72:75], v[176:179], v[20:23]
	v_mfma_f32_16x16x32_bf16 v[12:15], v[64:67], v[216:219], v[12:15]
	v_mfma_f32_16x16x32_bf16 v[8:11], v[72:75], v[216:219], v[8:11]
	v_mfma_f32_16x16x32_bf16 v[60:63], v[68:71], v[100:103], v[60:63]
	v_mfma_f32_16x16x32_bf16 v[52:55], v[76:79], v[100:103], v[52:55]
	v_mfma_f32_16x16x32_bf16 v[44:47], v[68:71], v[108:111], v[44:47]
	v_mfma_f32_16x16x32_bf16 v[36:39], v[76:79], v[108:111], v[36:39]
	v_mfma_f32_16x16x32_bf16 v[28:31], v[68:71], v[212:215], v[28:31]
	v_mfma_f32_16x16x32_bf16 v[20:23], v[76:79], v[212:215], v[20:23]
	v_mfma_f32_16x16x32_bf16 v[12:15], v[68:71], v[220:223], v[12:15]
	v_mfma_f32_16x16x32_bf16 v[8:11], v[76:79], v[220:223], v[8:11]
	v_mfma_f32_16x16x32_bf16 v[56:59], v[80:83], v[96:99], v[56:59]
	v_mfma_f32_16x16x32_bf16 v[48:51], v[88:91], v[96:99], v[48:51]
	v_mfma_f32_16x16x32_bf16 v[40:43], v[80:83], v[104:107], v[40:43]
	v_mfma_f32_16x16x32_bf16 v[32:35], v[88:91], v[104:107], v[32:35]
	v_mfma_f32_16x16x32_bf16 v[24:27], v[80:83], v[176:179], v[24:27]
	v_mfma_f32_16x16x32_bf16 v[16:19], v[88:91], v[176:179], v[16:19]
	v_mfma_f32_16x16x32_bf16 v[4:7], v[80:83], v[216:219], v[4:7]
	v_mfma_f32_16x16x32_bf16 v[0:3], v[88:91], v[216:219], v[0:3]
	v_mfma_f32_16x16x32_bf16 v[56:59], v[84:87], v[100:103], v[56:59]
	v_mfma_f32_16x16x32_bf16 v[48:51], v[92:95], v[100:103], v[48:51]
	v_mfma_f32_16x16x32_bf16 v[40:43], v[84:87], v[108:111], v[40:43]
	v_mfma_f32_16x16x32_bf16 v[32:35], v[92:95], v[108:111], v[32:35]
	v_mfma_f32_16x16x32_bf16 v[24:27], v[84:87], v[212:215], v[24:27]
	v_mfma_f32_16x16x32_bf16 v[16:19], v[92:95], v[212:215], v[16:19]
	v_mfma_f32_16x16x32_bf16 v[4:7], v[84:87], v[220:223], v[4:7]
	v_mfma_f32_16x16x32_bf16 v[0:3], v[92:95], v[220:223], v[0:3]
	s_setprio 0
	s_barrier
	s_add_i32 s75, s75, 2
	s_add_u32 s46, s46, 0x100
	s_addc_u32 s47, s47, 0
	s_add_u32 s72, s72, 0x100
	s_addc_u32 s73, s73, 0
	s_cmp_gt_u32 s75, 29
	s_cbranch_scc0 .LBB0_2577

; #define PG8_STAGE(bufoff, gbase, voff) do { _Pragma("unroll") for (int _i = 0; _i < 2; ++_i) \
;         __builtin_amdgcn_global_load_lds((const unsigned*)((const char*)(gbase) + (voff)[_i]), (PG8_LAS unsigned*)(lds + (bufoff) + ldsw + _i * 8192), 16, 0, 0); } while (0)
; #define PG8_LDA(dst, b, h) do { _Pragma("unroll") for (int m = 0; m < 4; ++m) _Pragma("unroll") for (int k = 0; k < 2; ++k) dst[m][k] = *(const PG8_LAS bf16x8*)(lds + PG8_SA(b, h) + aoff + m * 2048 + k * 1024); } while (0)
; #define PG8_LDB(dst, b, h) do { _Pragma("unroll") for (int n = 0; n < 2; ++n) _Pragma("unroll") for (int k = 0; k < 2; ++k) dst[n][k] = *(const PG8_LAS bf16x8*)(lds + PG8_SB(b, h) + boff + n * 2048 + k * 1024); } while (0)
; #define PG8_MMA(ai, bj, At, Bt) do { __builtin_amdgcn_s_setprio(1); _Pragma("unroll") for (int m = 0; m < 4; ++m) _Pragma("unroll") for (int n = 0; n < 2; ++n) _Pragma("unroll") for (int k = 0; k < 2; ++k) \
;         acc[ai][bj][m][n] = __builtin_amdgcn_mfma_f32_16x16x32_bf16(Bt[n][k], At[m][k], acc[ai][bj][m][n], 0, 0, 0); __builtin_amdgcn_s_setprio(0); } while (0)
; #define PG8_WAIT_V(n) asm volatile("s_waitcnt vmcnt(" #n ")" ::: "memory")
; #define PG8_BAR __builtin_amdgcn_s_barrier()
; template <class Epi, class Sched, bool ALIGN_EPI = false, bool SP2 = false>
; __device__ __forceinline__ void gemm_phase(PG8_LAS unsigned char* lds, const Gemm g, const Sched& S, const Epi& E, const int wave_in) {
;     ...
;         for (int t = 0; t < nt; t += 2) {
;             const bool last = (t == nt - 2);
;             const char* a1 = cA + (size_t)(t + 1) * kstep;
;             const char* a2 = last ? nA : cA + (size_t)(t + 2) * kstep; const char* b2 = last ? nB : cB + (size_t)(t + 2) * kstep;
;             const char* a3 = a2 + kstep; const char* b3 = b2 + kstep;
;             if (last && has_next) S.a_ready(nxt);
;             if constexpr (SP2) {
;             PG8_LDB(B0, 0, 0); PG8_LDB(B1, 0, 1); PG8_SCHED; PG8_LDA(At, 0, 0); PG8_STAGE(PG8_SA(1, 1), a1 + hstepA, voffA);
;             PG8_WAIT_V(8); PG8_WAIT_L(0); PG8_BAR; PG8_MMA(0, 0, At, B0); PG8_MMA(0, 1, At, B1); PG8_BAR; PG8_SCHED;
;             PG8_LDA(At, 0, 1); PG8_STAGE(PG8_SB(0, 0), b2, voffB); PG8_STAGE(PG8_SB(0, 1), b2 + hstepB, voffB); PG8_STAGE(PG8_SA(0, 0), a2, voffA);
;             PG8_WAIT_V(8); PG8_WAIT_L(0); PG8_BAR; PG8_MMA(1, 0, At, B0); PG8_MMA(1, 1, At, B1); PG8_BAR; PG8_SCHED;
.LBB0_2740:
	s_add_u32 s25, s28, 0x100
	v_mov_b32_e32 v0, 0
	s_addc_u32 s65, s29, 0
	s_mov_b32 s66, -2
	s_waitcnt vmcnt(0)
	ds_read_b128 v[128:131], v170
	ds_read_b128 v[132:135], v170 offset:1024
	ds_read_b128 v[136:139], v170 offset:2048
	ds_read_b128 v[140:143], v170 offset:3072
	ds_read_b128 v[162:165], v171
	ds_read_b128 v[174:177], v171 offset:1024
	ds_read_b128 v[178:181], v171 offset:2048
	ds_read_b128 v[182:185], v171 offset:3072
	s_add_u32 s2, s26, 0x100
	s_addc_u32 s3, s27, 0
	s_cmpk_eq_i32 s66, 0x52
	s_cselect_b32 s31, s21, s3
	s_cselect_b32 s30, s20, s2
	s_cselect_b32 s29, s23, s65
	s_cselect_b32 s28, s22, s25
	v_lshl_add_u64 v[166:167], s[26:27], 0, v[154:155]
	s_add_i32 m0, s40, 0xc000
	ds_read_b128 v[186:189], v172
	ds_read_b128 v[190:193], v172 offset:1024
	ds_read_b128 v[194:197], v172 offset:2048
	ds_read_b128 v[198:201], v172 offset:3072
	ds_read_b128 v[202:205], v172 offset:4096
	ds_read_b128 v[206:209], v172 offset:5120
	ds_read_b128 v[210:213], v172 offset:6144
	ds_read_b128 v[214:217], v172 offset:7168
	global_load_lds_dwordx4 v[166:167], off
	v_lshl_add_u64 v[166:167], s[26:27], 0, v[156:157]
	s_add_i32 m0, s40, 0xe000
	s_nop 0
	global_load_lds_dwordx4 v[166:167], off
	s_waitcnt vmcnt(8)
	s_waitcnt lgkmcnt(0)
	s_barrier
	s_setprio 1
	s_waitcnt lgkmcnt(0)
	v_mfma_f32_16x16x32_bf16 v[124:127], v[128:131], v[186:189], 0
	v_mfma_f32_16x16x32_bf16 v[120:123], v[136:139], v[186:189], 0
	v_mfma_f32_16x16x32_bf16 v[104:107], v[128:131], v[194:197], 0
	v_mfma_f32_16x16x32_bf16 v[108:111], v[136:139], v[194:197], 0
	v_mfma_f32_16x16x32_bf16 v[88:91], v[128:131], v[202:205], 0
	v_mfma_f32_16x16x32_bf16 v[92:95], v[136:139], v[202:205], 0
	v_mfma_f32_16x16x32_bf16 v[72:75], v[128:131], v[210:213], 0
	v_mfma_f32_16x16x32_bf16 v[76:79], v[136:139], v[210:213], 0
	v_mfma_f32_16x16x32_bf16 v[124:127], v[132:135], v[190:193], v[124:127]
	v_mfma_f32_16x16x32_bf16 v[120:123], v[140:143], v[190:193], v[120:123]
	v_mfma_f32_16x16x32_bf16 v[104:107], v[132:135], v[198:201], v[104:107]
	v_mfma_f32_16x16x32_bf16 v[108:111], v[140:143], v[198:201], v[108:111]
	v_mfma_f32_16x16x32_bf16 v[88:91], v[132:135], v[206:209], v[88:91]
	v_mfma_f32_16x16x32_bf16 v[92:95], v[140:143], v[206:209], v[92:95]
	v_mfma_f32_16x16x32_bf16 v[72:75], v[132:135], v[214:217], v[72:75]
	v_mfma_f32_16x16x32_bf16 v[76:79], v[140:143], v[214:217], v[76:79]
	v_mfma_f32_16x16x32_bf16 v[112:115], v[162:165], v[186:189], 0
	v_mfma_f32_16x16x32_bf16 v[116:119], v[178:181], v[186:189], 0
	v_mfma_f32_16x16x32_bf16 v[96:99], v[162:165], v[194:197], 0
	v_mfma_f32_16x16x32_bf16 v[100:103], v[178:181], v[194:197], 0
	v_mfma_f32_16x16x32_bf16 v[80:83], v[162:165], v[202:205], 0
	v_mfma_f32_16x16x32_bf16 v[84:87], v[178:181], v[202:205], 0
	v_mfma_f32_16x16x32_bf16 v[64:67], v[162:165], v[210:213], 0
	v_mfma_f32_16x16x32_bf16 v[68:71], v[178:181], v[210:213], 0
	v_mfma_f32_16x16x32_bf16 v[112:115], v[174:177], v[190:193], v[112:115]
	v_mfma_f32_16x16x32_bf16 v[116:119], v[182:185], v[190:193], v[116:119]
	v_mfma_f32_16x16x32_bf16 v[96:99], v[174:177], v[198:201], v[96:99]
	v_mfma_f32_16x16x32_bf16 v[100:103], v[182:185], v[198:201], v[100:103]
	v_mfma_f32_16x16x32_bf16 v[80:83], v[174:177], v[206:209], v[80:83]
	v_mfma_f32_16x16x32_bf16 v[84:87], v[182:185], v[206:209], v[84:87]
	v_mfma_f32_16x16x32_bf16 v[64:67], v[174:177], v[214:217], v[64:67]
	v_mfma_f32_16x16x32_bf16 v[68:71], v[182:185], v[214:217], v[68:71]
	s_setprio 0
	s_barrier
	s_add_i32 s26, s50, s39
	v_lshl_add_u64 v[166:167], s[28:29], 0, v[146:147]
	s_mov_b32 m0, s26
	ds_read_b128 v[186:189], v172 offset:16384
	ds_read_b128 v[190:193], v172 offset:17408
	ds_read_b128 v[194:197], v172 offset:18432
	ds_read_b128 v[198:201], v172 offset:19456
	ds_read_b128 v[202:205], v172 offset:20480
	ds_read_b128 v[206:209], v172 offset:21504
	ds_read_b128 v[210:213], v172 offset:22528
	ds_read_b128 v[214:217], v172 offset:23552
	global_load_lds_dwordx4 v[166:167], off
	s_add_i32 m0, s26, 0x2000
	s_add_u32 s26, s28, 0x158000
	v_lshl_add_u64 v[218:219], s[28:29], 0, v[150:151]
	s_addc_u32 s27, s29, 0
	s_add_i32 s67, s51, s39
	global_load_lds_dwordx4 v[218:219], off
	v_lshl_add_u64 v[220:221], s[26:27], 0, v[146:147]
	s_mov_b32 m0, s67
	v_lshl_add_u64 v[222:223], s[30:31], 0, v[148:149]
	global_load_lds_dwordx4 v[220:221], off
	v_lshl_add_u64 v[220:221], s[26:27], 0, v[150:151]
	s_add_i32 m0, s67, 0x2000
	s_nop 0
	global_load_lds_dwordx4 v[220:221], off
	v_lshl_add_u64 v[220:221], s[30:31], 0, v[144:145]
	s_mov_b32 m0, s40
	s_nop 0
	global_load_lds_dwordx4 v[220:221], off
	s_mov_b32 m0, s41
	s_nop 0
	global_load_lds_dwordx4 v[222:223], off
	s_waitcnt vmcnt(8)
	s_waitcnt lgkmcnt(0)
	s_barrier
; #define PG8_STAGE(bufoff, gbase, voff) do { _Pragma("unroll") for (int _i = 0; _i < 2; ++_i) \
;         __builtin_amdgcn_global_load_lds((const unsigned*)((const char*)(gbase) + (voff)[_i]), (PG8_LAS unsigned*)(lds + (bufoff) + ldsw + _i * 8192), 16, 0, 0); } while (0)
; #define PG8_LDA(dst, b, h) do { _Pragma("unroll") for (int m = 0; m < 4; ++m) _Pragma("unroll") for (int k = 0; k < 2; ++k) dst[m][k] = *(const PG8_LAS bf16x8*)(lds + PG8_SA(b, h) + aoff + m * 2048 + k * 1024); } while (0)
; #define PG8_LDB(dst, b, h) do { _Pragma("unroll") for (int n = 0; n < 2; ++n) _Pragma("unroll") for (int k = 0; k < 2; ++k) dst[n][k] = *(const PG8_LAS bf16x8*)(lds + PG8_SB(b, h) + boff + n * 2048 + k * 1024); } while (0)
; #define PG8_MMA(ai, bj, At, Bt) do { __builtin_amdgcn_s_setprio(1); _Pragma("unroll") for (int m = 0; m < 4; ++m) _Pragma("unroll") for (int n = 0; n < 2; ++n) _Pragma("unroll") for (int k = 0; k < 2; ++k) \
;         acc[ai][bj][m][n] = __builtin_amdgcn_mfma_f32_16x16x32_bf16(Bt[n][k], At[m][k], acc[ai][bj][m][n], 0, 0, 0); __builtin_amdgcn_s_setprio(0); } while (0)
; #define PG8_WAIT_V(n) asm volatile("s_waitcnt vmcnt(" #n ")" ::: "memory")
; #define PG8_WAIT_L(n) asm volatile("s_waitcnt lgkmcnt(" #n ")" ::: "memory")
; #define PG8_BAR __builtin_amdgcn_s_barrier()
; #define PG8_SCHED __builtin_amdgcn_sched_barrier(0)
; template <class Epi, class Sched, bool ALIGN_EPI = false, bool SP2 = false>
; __device__ __forceinline__ void gemm_phase(PG8_LAS unsigned char* lds, const Gemm g, const Sched& S, const Epi& E, const int wave_in) {
;     ...
;             PG8_LDA(At, 0, 1); PG8_STAGE(PG8_SB(0, 0), b2, voffB); PG8_STAGE(PG8_SB(0, 1), b2 + hstepB, voffB); PG8_STAGE(PG8_SA(0, 0), a2, voffA);
;             PG8_WAIT_V(8); PG8_WAIT_L(0); PG8_BAR; PG8_MMA(1, 0, At, B0); PG8_MMA(1, 1, At, B1); PG8_BAR; PG8_SCHED;
;             PG8_LDB(B0, 1, 0); PG8_LDB(B1, 1, 1); PG8_SCHED; PG8_LDA(At, 1, 0); PG8_STAGE(PG8_SA(0, 1), a2 + hstepA, voffA);
;             PG8_WAIT_V(8); PG8_WAIT_L(0); PG8_BAR; PG8_MMA(0, 0, At, B0); PG8_MMA(0, 1, At, B1); PG8_BAR; PG8_SCHED;
	s_setprio 1
	s_waitcnt lgkmcnt(0)
	v_mfma_f32_16x16x32_bf16 v[60:63], v[128:131], v[186:189], 0
	v_mfma_f32_16x16x32_bf16 v[56:59], v[136:139], v[186:189], 0
	v_mfma_f32_16x16x32_bf16 v[40:43], v[128:131], v[194:197], 0
	v_mfma_f32_16x16x32_bf16 v[48:51], v[136:139], v[194:197], 0
	v_mfma_f32_16x16x32_bf16 v[24:27], v[128:131], v[202:205], 0
	v_mfma_f32_16x16x32_bf16 v[32:35], v[136:139], v[202:205], 0
	v_mfma_f32_16x16x32_bf16 v[8:11], v[128:131], v[210:213], 0
	v_mfma_f32_16x16x32_bf16 v[16:19], v[136:139], v[210:213], 0
	v_mfma_f32_16x16x32_bf16 v[60:63], v[132:135], v[190:193], v[60:63]
	v_mfma_f32_16x16x32_bf16 v[56:59], v[140:143], v[190:193], v[56:59]
	v_mfma_f32_16x16x32_bf16 v[40:43], v[132:135], v[198:201], v[40:43]
	v_mfma_f32_16x16x32_bf16 v[48:51], v[140:143], v[198:201], v[48:51]
	v_mfma_f32_16x16x32_bf16 v[24:27], v[132:135], v[206:209], v[24:27]
	v_mfma_f32_16x16x32_bf16 v[32:35], v[140:143], v[206:209], v[32:35]
	v_mfma_f32_16x16x32_bf16 v[8:11], v[132:135], v[214:217], v[8:11]
	v_mfma_f32_16x16x32_bf16 v[16:19], v[140:143], v[214:217], v[16:19]
	v_mfma_f32_16x16x32_bf16 v[44:47], v[162:165], v[186:189], 0
	v_mfma_f32_16x16x32_bf16 v[52:55], v[178:181], v[186:189], 0
	v_mfma_f32_16x16x32_bf16 v[28:31], v[162:165], v[194:197], 0
	v_mfma_f32_16x16x32_bf16 v[36:39], v[178:181], v[194:197], 0
	v_mfma_f32_16x16x32_bf16 v[12:15], v[162:165], v[202:205], 0
	v_mfma_f32_16x16x32_bf16 v[20:23], v[178:181], v[202:205], 0
	v_mfma_f32_16x16x32_bf16 v[4:7], v[162:165], v[210:213], 0
	v_mfma_f32_16x16x32_bf16 v[0:3], v[178:181], v[210:213], 0
	v_mfma_f32_16x16x32_bf16 v[44:47], v[174:177], v[190:193], v[44:47]
	v_mfma_f32_16x16x32_bf16 v[52:55], v[182:185], v[190:193], v[52:55]
	v_mfma_f32_16x16x32_bf16 v[28:31], v[174:177], v[198:201], v[28:31]
	v_mfma_f32_16x16x32_bf16 v[36:39], v[182:185], v[198:201], v[36:39]
	v_mfma_f32_16x16x32_bf16 v[12:15], v[174:177], v[206:209], v[12:15]
	v_mfma_f32_16x16x32_bf16 v[20:23], v[182:185], v[206:209], v[20:23]
	v_mfma_f32_16x16x32_bf16 v[4:7], v[174:177], v[214:217], v[4:7]
	v_mfma_f32_16x16x32_bf16 v[0:3], v[182:185], v[214:217], v[0:3]
	s_setprio 0
	s_barrier
	s_add_i32 s67, 0, 0x18000
	s_add_i32 s68, 0, 0x1c000
	v_add_u32_e32 v140, s67, v168
	v_add_u32_e32 v173, s68, v168
	ds_read_b128 v[128:131], v140
	ds_read_b128 v[132:135], v140 offset:1024
	ds_read_b128 v[136:139], v140 offset:2048
	ds_read_b128 v[140:143], v140 offset:3072
	ds_read_b128 v[162:165], v173
	ds_read_b128 v[174:177], v173 offset:1024
	ds_read_b128 v[178:181], v173 offset:2048
	ds_read_b128 v[182:185], v173 offset:3072
	s_add_u32 s26, s30, 0x158000
	s_addc_u32 s27, s31, 0
	s_mov_b32 m0, s42
	v_lshl_add_u64 v[224:225], s[26:27], 0, v[144:145]
	ds_read_b128 v[186:189], v172 offset:32768
	ds_read_b128 v[190:193], v172 offset:33792
	ds_read_b128 v[194:197], v172 offset:34816
	ds_read_b128 v[198:201], v172 offset:35840
	ds_read_b128 v[202:205], v172 offset:36864
	ds_read_b128 v[206:209], v172 offset:37888
	ds_read_b128 v[210:213], v172 offset:38912
	ds_read_b128 v[214:217], v172 offset:39936
	global_load_lds_dwordx4 v[224:225], off
	v_lshl_add_u64 v[224:225], s[26:27], 0, v[148:149]
	s_mov_b32 m0, s43
	s_nop 0
	global_load_lds_dwordx4 v[224:225], off
	s_waitcnt vmcnt(8)
	s_waitcnt lgkmcnt(0)
	s_barrier
	s_setprio 1
	s_waitcnt lgkmcnt(0)
	v_mfma_f32_16x16x32_bf16 v[124:127], v[128:131], v[186:189], v[124:127]
	v_mfma_f32_16x16x32_bf16 v[120:123], v[136:139], v[186:189], v[120:123]
	v_mfma_f32_16x16x32_bf16 v[104:107], v[128:131], v[194:197], v[104:107]
	v_mfma_f32_16x16x32_bf16 v[108:111], v[136:139], v[194:197], v[108:111]
	v_mfma_f32_16x16x32_bf16 v[88:91], v[128:131], v[202:205], v[88:91]
	v_mfma_f32_16x16x32_bf16 v[92:95], v[136:139], v[202:205], v[92:95]
	v_mfma_f32_16x16x32_bf16 v[72:75], v[128:131], v[210:213], v[72:75]
	v_mfma_f32_16x16x32_bf16 v[76:79], v[136:139], v[210:213], v[76:79]
	v_mfma_f32_16x16x32_bf16 v[124:127], v[132:135], v[190:193], v[124:127]
	v_mfma_f32_16x16x32_bf16 v[120:123], v[140:143], v[190:193], v[120:123]
	v_mfma_f32_16x16x32_bf16 v[104:107], v[132:135], v[198:201], v[104:107]
	v_mfma_f32_16x16x32_bf16 v[108:111], v[140:143], v[198:201], v[108:111]
	v_mfma_f32_16x16x32_bf16 v[88:91], v[132:135], v[206:209], v[88:91]
	v_mfma_f32_16x16x32_bf16 v[92:95], v[140:143], v[206:209], v[92:95]
	v_mfma_f32_16x16x32_bf16 v[72:75], v[132:135], v[214:217], v[72:75]
	v_mfma_f32_16x16x32_bf16 v[76:79], v[140:143], v[214:217], v[76:79]
	v_mfma_f32_16x16x32_bf16 v[112:115], v[162:165], v[186:189], v[112:115]
	v_mfma_f32_16x16x32_bf16 v[116:119], v[178:181], v[186:189], v[116:119]
	v_mfma_f32_16x16x32_bf16 v[96:99], v[162:165], v[194:197], v[96:99]
	v_mfma_f32_16x16x32_bf16 v[100:103], v[178:181], v[194:197], v[100:103]
	v_mfma_f32_16x16x32_bf16 v[80:83], v[162:165], v[202:205], v[80:83]
	v_mfma_f32_16x16x32_bf16 v[84:87], v[178:181], v[202:205], v[84:87]
	v_mfma_f32_16x16x32_bf16 v[64:67], v[162:165], v[210:213], v[64:67]
	v_mfma_f32_16x16x32_bf16 v[68:71], v[178:181], v[210:213], v[68:71]
	v_mfma_f32_16x16x32_bf16 v[112:115], v[174:177], v[190:193], v[112:115]
	v_mfma_f32_16x16x32_bf16 v[116:119], v[182:185], v[190:193], v[116:119]
	v_mfma_f32_16x16x32_bf16 v[96:99], v[174:177], v[198:201], v[96:99]
	v_mfma_f32_16x16x32_bf16 v[100:103], v[182:185], v[198:201], v[100:103]
	v_mfma_f32_16x16x32_bf16 v[80:83], v[174:177], v[206:209], v[80:83]
	v_mfma_f32_16x16x32_bf16 v[84:87], v[182:185], v[206:209], v[84:87]
	v_mfma_f32_16x16x32_bf16 v[64:67], v[174:177], v[214:217], v[64:67]
	v_mfma_f32_16x16x32_bf16 v[68:71], v[182:185], v[214:217], v[68:71]
	s_setprio 0
	s_barrier
; #define PG8_STAGE(bufoff, gbase, voff) do { _Pragma("unroll") for (int _i = 0; _i < 2; ++_i) \
;         __builtin_amdgcn_global_load_lds((const unsigned*)((const char*)(gbase) + (voff)[_i]), (PG8_LAS unsigned*)(lds + (bufoff) + ldsw + _i * 8192), 16, 0, 0); } while (0)
; #define PG8_LDA(dst, b, h) do { _Pragma("unroll") for (int m = 0; m < 4; ++m) _Pragma("unroll") for (int k = 0; k < 2; ++k) dst[m][k] = *(const PG8_LAS bf16x8*)(lds + PG8_SA(b, h) + aoff + m * 2048 + k * 1024); } while (0)
; #define PG8_WAIT_V(n) asm volatile("s_waitcnt vmcnt(" #n ")" ::: "memory")
; #define PG8_WAIT_L(n) asm volatile("s_waitcnt lgkmcnt(" #n ")" ::: "memory")
; #define PG8_BAR __builtin_amdgcn_s_barrier()
; template <class Epi, class Sched, bool ALIGN_EPI = false, bool SP2 = false>
; __device__ __forceinline__ void gemm_phase(PG8_LAS unsigned char* lds, const Gemm g, const Sched& S, const Epi& E, const int wave_in) {
;     ...
;         for (int t = 0; t < nt; t += 2) {
;             const bool last = (t == nt - 2);
;             const char* a1 = cA + (size_t)(t + 1) * kstep;
;             const char* a2 = last ? nA : cA + (size_t)(t + 2) * kstep; const char* b2 = last ? nB : cB + (size_t)(t + 2) * kstep;
;             const char* a3 = a2 + kstep; const char* b3 = b2 + kstep;
;             if (last && has_next) S.a_ready(nxt);
;             if constexpr (SP2) {
;             PG8_LDB(B0, 0, 0); PG8_LDB(B1, 0, 1); PG8_SCHED; PG8_LDA(At, 0, 0); PG8_STAGE(PG8_SA(1, 1), a1 + hstepA, voffA);
;             PG8_WAIT_V(8); PG8_WAIT_L(0); PG8_BAR; PG8_MMA(0, 0, At, B0); PG8_MMA(0, 1, At, B1); PG8_BAR; PG8_SCHED;
;             PG8_LDA(At, 0, 1); PG8_STAGE(PG8_SB(0, 0), b2, voffB); PG8_STAGE(PG8_SB(0, 1), b2 + hstepB, voffB); PG8_STAGE(PG8_SA(0, 0), a2, voffA);
;             PG8_WAIT_V(8); PG8_WAIT_L(0); PG8_BAR; PG8_MMA(1, 0, At, B0); PG8_MMA(1, 1, At, B1); PG8_BAR; PG8_SCHED;
;             PG8_LDB(B0, 1, 0); PG8_LDB(B1, 1, 1); PG8_SCHED; PG8_LDA(At, 1, 0); PG8_STAGE(PG8_SA(0, 1), a2 + hstepA, voffA);
;             PG8_WAIT_V(8); PG8_WAIT_L(0); PG8_BAR; PG8_MMA(0, 0, At, B0); PG8_MMA(0, 1, At, B1); PG8_BAR; PG8_SCHED;
;             PG8_LDA(At, 1, 1); PG8_STAGE(PG8_SB(1, 0), b3, voffB); PG8_STAGE(PG8_SB(1, 1), b3 + hstepB, voffB); PG8_STAGE(PG8_SA(1, 0), a3, voffA);
;             PG8_WAIT_V(8); PG8_WAIT_L(0); PG8_BAR; PG8_MMA(1, 0, At, B0); PG8_MMA(1, 1, At, B1); PG8_BAR; PG8_SCHED;
	s_add_i32 s26, s67, s39
	v_lshl_add_u64 v[166:167], v[166:167], 0, s[6:7]
	s_mov_b32 m0, s26
	ds_read_b128 v[186:189], v172 offset:49152
	ds_read_b128 v[190:193], v172 offset:50176
	ds_read_b128 v[194:197], v172 offset:51200
	ds_read_b128 v[198:201], v172 offset:52224
	ds_read_b128 v[202:205], v172 offset:53248
	ds_read_b128 v[206:209], v172 offset:54272
	ds_read_b128 v[210:213], v172 offset:55296
	ds_read_b128 v[214:217], v172 offset:56320
	global_load_lds_dwordx4 v[166:167], off
	s_add_i32 m0, s26, 0x2000
	s_add_u32 s26, s28, 0x158080
	v_lshl_add_u64 v[166:167], v[218:219], 0, s[6:7]
	s_addc_u32 s27, s29, 0
	s_add_i32 s28, s68, s39
	global_load_lds_dwordx4 v[166:167], off
	v_lshl_add_u64 v[166:167], s[26:27], 0, v[146:147]
	s_mov_b32 m0, s28
	s_nop 0
	global_load_lds_dwordx4 v[166:167], off
	v_lshl_add_u64 v[166:167], s[26:27], 0, v[150:151]
	s_add_i32 m0, s28, 0x2000
	s_nop 0
	global_load_lds_dwordx4 v[166:167], off
	v_lshl_add_u64 v[166:167], v[220:221], 0, s[6:7]
	s_mov_b32 m0, s48
	s_nop 0
	global_load_lds_dwordx4 v[166:167], off
	v_lshl_add_u64 v[166:167], v[222:223], 0, s[6:7]
	s_mov_b32 m0, s49
	s_nop 0
	global_load_lds_dwordx4 v[166:167], off
	s_waitcnt vmcnt(8)
	s_waitcnt lgkmcnt(0)
	s_barrier
	s_setprio 1
	s_waitcnt lgkmcnt(0)
	v_mfma_f32_16x16x32_bf16 v[60:63], v[128:131], v[186:189], v[60:63]
	v_mfma_f32_16x16x32_bf16 v[56:59], v[136:139], v[186:189], v[56:59]
	v_mfma_f32_16x16x32_bf16 v[40:43], v[128:131], v[194:197], v[40:43]
	v_mfma_f32_16x16x32_bf16 v[48:51], v[136:139], v[194:197], v[48:51]
	v_mfma_f32_16x16x32_bf16 v[24:27], v[128:131], v[202:205], v[24:27]
	v_mfma_f32_16x16x32_bf16 v[32:35], v[136:139], v[202:205], v[32:35]
	v_mfma_f32_16x16x32_bf16 v[8:11], v[128:131], v[210:213], v[8:11]
	v_mfma_f32_16x16x32_bf16 v[16:19], v[136:139], v[210:213], v[16:19]
	v_mfma_f32_16x16x32_bf16 v[60:63], v[132:135], v[190:193], v[60:63]
	v_mfma_f32_16x16x32_bf16 v[56:59], v[140:143], v[190:193], v[56:59]
	v_mfma_f32_16x16x32_bf16 v[40:43], v[132:135], v[198:201], v[40:43]
	v_mfma_f32_16x16x32_bf16 v[48:51], v[140:143], v[198:201], v[48:51]
	v_mfma_f32_16x16x32_bf16 v[24:27], v[132:135], v[206:209], v[24:27]
	v_mfma_f32_16x16x32_bf16 v[32:35], v[140:143], v[206:209], v[32:35]
	v_mfma_f32_16x16x32_bf16 v[8:11], v[132:135], v[214:217], v[8:11]
	v_mfma_f32_16x16x32_bf16 v[16:19], v[140:143], v[214:217], v[16:19]
	v_mfma_f32_16x16x32_bf16 v[44:47], v[162:165], v[186:189], v[44:47]
	v_mfma_f32_16x16x32_bf16 v[52:55], v[178:181], v[186:189], v[52:55]
	v_mfma_f32_16x16x32_bf16 v[28:31], v[162:165], v[194:197], v[28:31]
	v_mfma_f32_16x16x32_bf16 v[36:39], v[178:181], v[194:197], v[36:39]
	v_mfma_f32_16x16x32_bf16 v[12:15], v[162:165], v[202:205], v[12:15]
	v_mfma_f32_16x16x32_bf16 v[20:23], v[178:181], v[202:205], v[20:23]
	v_mfma_f32_16x16x32_bf16 v[4:7], v[162:165], v[210:213], v[4:7]
	v_mfma_f32_16x16x32_bf16 v[0:3], v[178:181], v[210:213], v[0:3]
	v_mfma_f32_16x16x32_bf16 v[44:47], v[174:177], v[190:193], v[44:47]
	v_mfma_f32_16x16x32_bf16 v[52:55], v[182:185], v[190:193], v[52:55]
	v_mfma_f32_16x16x32_bf16 v[28:31], v[174:177], v[198:201], v[28:31]
	v_mfma_f32_16x16x32_bf16 v[36:39], v[182:185], v[198:201], v[36:39]
	v_mfma_f32_16x16x32_bf16 v[12:15], v[174:177], v[206:209], v[12:15]
	v_mfma_f32_16x16x32_bf16 v[20:23], v[182:185], v[206:209], v[20:23]
	v_mfma_f32_16x16x32_bf16 v[4:7], v[174:177], v[214:217], v[4:7]
	v_mfma_f32_16x16x32_bf16 v[0:3], v[182:185], v[214:217], v[0:3]
	s_setprio 0
	s_barrier
	s_add_i32 s66, s66, 2
	s_add_u32 s25, s25, 0x100
	s_addc_u32 s65, s65, 0
	s_cmpk_gt_u32 s66, 0x53
	s_mov_b64 s[26:27], s[2:3]
	s_cbranch_scc0 .LBB0_2741
	s_branch .Lkx_32
.LBB0_2741:
	ds_read_b128 v[128:131], v170
	ds_read_b128 v[132:135], v170 offset:1024
	ds_read_b128 v[136:139], v170 offset:2048
	ds_read_b128 v[140:143], v170 offset:3072
	ds_read_b128 v[162:165], v171
	ds_read_b128 v[174:177], v171 offset:1024
	ds_read_b128 v[178:181], v171 offset:2048
	ds_read_b128 v[182:185], v171 offset:3072
	s_add_u32 s2, s26, 0x100
	s_addc_u32 s3, s27, 0
	s_cmpk_eq_i32 s66, 0x52
	s_cselect_b32 s31, s21, s3
	s_cselect_b32 s30, s20, s2
	s_cselect_b32 s29, s23, s65
	s_cselect_b32 s28, s22, s25
	v_lshl_add_u64 v[166:167], s[26:27], 0, v[154:155]
	s_add_i32 m0, s40, 0xc000
	ds_read_b128 v[186:189], v172
	ds_read_b128 v[190:193], v172 offset:1024
	ds_read_b128 v[194:197], v172 offset:2048
	ds_read_b128 v[198:201], v172 offset:3072
	ds_read_b128 v[202:205], v172 offset:4096
	ds_read_b128 v[206:209], v172 offset:5120
	ds_read_b128 v[210:213], v172 offset:6144
	ds_read_b128 v[214:217], v172 offset:7168
	global_load_lds_dwordx4 v[166:167], off
	v_lshl_add_u64 v[166:167], s[26:27], 0, v[156:157]
	s_add_i32 m0, s40, 0xe000
	s_nop 0
	global_load_lds_dwordx4 v[166:167], off
	s_waitcnt vmcnt(8)
	s_waitcnt lgkmcnt(0)
	s_barrier
; #define PG8_STAGE(bufoff, gbase, voff) do { _Pragma("unroll") for (int _i = 0; _i < 2; ++_i) \
;         __builtin_amdgcn_global_load_lds((const unsigned*)((const char*)(gbase) + (voff)[_i]), (PG8_LAS unsigned*)(lds + (bufoff) + ldsw + _i * 8192), 16, 0, 0); } while (0)
; #define PG8_LDA(dst, b, h) do { _Pragma("unroll") for (int m = 0; m < 4; ++m) _Pragma("unroll") for (int k = 0; k < 2; ++k) dst[m][k] = *(const PG8_LAS bf16x8*)(lds + PG8_SA(b, h) + aoff + m * 2048 + k * 1024); } while (0)
; #define PG8_LDB(dst, b, h) do { _Pragma("unroll") for (int n = 0; n < 2; ++n) _Pragma("unroll") for (int k = 0; k < 2; ++k) dst[n][k] = *(const PG8_LAS bf16x8*)(lds + PG8_SB(b, h) + boff + n * 2048 + k * 1024); } while (0)
; #define PG8_MMA(ai, bj, At, Bt) do { __builtin_amdgcn_s_setprio(1); _Pragma("unroll") for (int m = 0; m < 4; ++m) _Pragma("unroll") for (int n = 0; n < 2; ++n) _Pragma("unroll") for (int k = 0; k < 2; ++k) \
;         acc[ai][bj][m][n] = __builtin_amdgcn_mfma_f32_16x16x32_bf16(Bt[n][k], At[m][k], acc[ai][bj][m][n], 0, 0, 0); __builtin_amdgcn_s_setprio(0); } while (0)
; #define PG8_WAIT_V(n) asm volatile("s_waitcnt vmcnt(" #n ")" ::: "memory")
; #define PG8_WAIT_L(n) asm volatile("s_waitcnt lgkmcnt(" #n ")" ::: "memory")
; #define PG8_BAR __builtin_amdgcn_s_barrier()
; #define PG8_SCHED __builtin_amdgcn_sched_barrier(0)
; template <class Epi, class Sched, bool ALIGN_EPI = false, bool SP2 = false>
; __device__ __forceinline__ void gemm_phase(PG8_LAS unsigned char* lds, const Gemm g, const Sched& S, const Epi& E, const int wave_in) {
;     ...
;             PG8_LDB(B0, 0, 0); PG8_LDB(B1, 0, 1); PG8_SCHED; PG8_LDA(At, 0, 0); PG8_STAGE(PG8_SA(1, 1), a1 + hstepA, voffA);
;             PG8_WAIT_V(8); PG8_WAIT_L(0); PG8_BAR; PG8_MMA(0, 0, At, B0); PG8_MMA(0, 1, At, B1); PG8_BAR; PG8_SCHED;
;             PG8_LDA(At, 0, 1); PG8_STAGE(PG8_SB(0, 0), b2, voffB); PG8_STAGE(PG8_SB(0, 1), b2 + hstepB, voffB); PG8_STAGE(PG8_SA(0, 0), a2, voffA);
;             PG8_WAIT_V(8); PG8_WAIT_L(0); PG8_BAR; PG8_MMA(1, 0, At, B0); PG8_MMA(1, 1, At, B1); PG8_BAR; PG8_SCHED;
	s_setprio 1
	s_waitcnt lgkmcnt(0)
	v_mfma_f32_16x16x32_bf16 v[124:127], v[128:131], v[186:189], v[124:127]
	v_mfma_f32_16x16x32_bf16 v[120:123], v[136:139], v[186:189], v[120:123]
	v_mfma_f32_16x16x32_bf16 v[104:107], v[128:131], v[194:197], v[104:107]
	v_mfma_f32_16x16x32_bf16 v[108:111], v[136:139], v[194:197], v[108:111]
	v_mfma_f32_16x16x32_bf16 v[88:91], v[128:131], v[202:205], v[88:91]
	v_mfma_f32_16x16x32_bf16 v[92:95], v[136:139], v[202:205], v[92:95]
	v_mfma_f32_16x16x32_bf16 v[72:75], v[128:131], v[210:213], v[72:75]
	v_mfma_f32_16x16x32_bf16 v[76:79], v[136:139], v[210:213], v[76:79]
	v_mfma_f32_16x16x32_bf16 v[124:127], v[132:135], v[190:193], v[124:127]
	v_mfma_f32_16x16x32_bf16 v[120:123], v[140:143], v[190:193], v[120:123]
	v_mfma_f32_16x16x32_bf16 v[104:107], v[132:135], v[198:201], v[104:107]
	v_mfma_f32_16x16x32_bf16 v[108:111], v[140:143], v[198:201], v[108:111]
	v_mfma_f32_16x16x32_bf16 v[88:91], v[132:135], v[206:209], v[88:91]
	v_mfma_f32_16x16x32_bf16 v[92:95], v[140:143], v[206:209], v[92:95]
	v_mfma_f32_16x16x32_bf16 v[72:75], v[132:135], v[214:217], v[72:75]
	v_mfma_f32_16x16x32_bf16 v[76:79], v[140:143], v[214:217], v[76:79]
	v_mfma_f32_16x16x32_bf16 v[112:115], v[162:165], v[186:189], v[112:115]
	v_mfma_f32_16x16x32_bf16 v[116:119], v[178:181], v[186:189], v[116:119]
	v_mfma_f32_16x16x32_bf16 v[96:99], v[162:165], v[194:197], v[96:99]
	v_mfma_f32_16x16x32_bf16 v[100:103], v[178:181], v[194:197], v[100:103]
	v_mfma_f32_16x16x32_bf16 v[80:83], v[162:165], v[202:205], v[80:83]
	v_mfma_f32_16x16x32_bf16 v[84:87], v[178:181], v[202:205], v[84:87]
	v_mfma_f32_16x16x32_bf16 v[64:67], v[162:165], v[210:213], v[64:67]
	v_mfma_f32_16x16x32_bf16 v[68:71], v[178:181], v[210:213], v[68:71]
	v_mfma_f32_16x16x32_bf16 v[112:115], v[174:177], v[190:193], v[112:115]
	v_mfma_f32_16x16x32_bf16 v[116:119], v[182:185], v[190:193], v[116:119]
	v_mfma_f32_16x16x32_bf16 v[96:99], v[174:177], v[198:201], v[96:99]
	v_mfma_f32_16x16x32_bf16 v[100:103], v[182:185], v[198:201], v[100:103]
	v_mfma_f32_16x16x32_bf16 v[80:83], v[174:177], v[206:209], v[80:83]
	v_mfma_f32_16x16x32_bf16 v[84:87], v[182:185], v[206:209], v[84:87]
	v_mfma_f32_16x16x32_bf16 v[64:67], v[174:177], v[214:217], v[64:67]
	v_mfma_f32_16x16x32_bf16 v[68:71], v[182:185], v[214:217], v[68:71]
	s_setprio 0
	s_barrier
	s_add_i32 s26, s50, s39
	v_lshl_add_u64 v[166:167], s[28:29], 0, v[146:147]
	s_mov_b32 m0, s26
	ds_read_b128 v[186:189], v172 offset:16384
	ds_read_b128 v[190:193], v172 offset:17408
	ds_read_b128 v[194:197], v172 offset:18432
	ds_read_b128 v[198:201], v172 offset:19456
	ds_read_b128 v[202:205], v172 offset:20480
	ds_read_b128 v[206:209], v172 offset:21504
	ds_read_b128 v[210:213], v172 offset:22528
	ds_read_b128 v[214:217], v172 offset:23552
	global_load_lds_dwordx4 v[166:167], off
	s_add_i32 m0, s26, 0x2000
	s_add_u32 s26, s28, 0x158000
	v_lshl_add_u64 v[218:219], s[28:29], 0, v[150:151]
	s_addc_u32 s27, s29, 0
	s_add_i32 s67, s51, s39
	global_load_lds_dwordx4 v[218:219], off
	v_lshl_add_u64 v[220:221], s[26:27], 0, v[146:147]
	s_mov_b32 m0, s67
	v_lshl_add_u64 v[222:223], s[30:31], 0, v[148:149]
	global_load_lds_dwordx4 v[220:221], off
	v_lshl_add_u64 v[220:221], s[26:27], 0, v[150:151]
	s_add_i32 m0, s67, 0x2000
	s_nop 0
	global_load_lds_dwordx4 v[220:221], off
	v_lshl_add_u64 v[220:221], s[30:31], 0, v[144:145]
	s_mov_b32 m0, s40
	s_nop 0
	global_load_lds_dwordx4 v[220:221], off
	s_mov_b32 m0, s41
	s_nop 0
	global_load_lds_dwordx4 v[222:223], off
	s_waitcnt vmcnt(8)
	s_waitcnt lgkmcnt(0)
	s_barrier
	s_setprio 1
	s_waitcnt lgkmcnt(0)
	v_mfma_f32_16x16x32_bf16 v[60:63], v[128:131], v[186:189], v[60:63]
	v_mfma_f32_16x16x32_bf16 v[56:59], v[136:139], v[186:189], v[56:59]
	v_mfma_f32_16x16x32_bf16 v[40:43], v[128:131], v[194:197], v[40:43]
	v_mfma_f32_16x16x32_bf16 v[48:51], v[136:139], v[194:197], v[48:51]
	v_mfma_f32_16x16x32_bf16 v[24:27], v[128:131], v[202:205], v[24:27]
	v_mfma_f32_16x16x32_bf16 v[32:35], v[136:139], v[202:205], v[32:35]
	v_mfma_f32_16x16x32_bf16 v[8:11], v[128:131], v[210:213], v[8:11]
	v_mfma_f32_16x16x32_bf16 v[16:19], v[136:139], v[210:213], v[16:19]
	v_mfma_f32_16x16x32_bf16 v[60:63], v[132:135], v[190:193], v[60:63]
	v_mfma_f32_16x16x32_bf16 v[56:59], v[140:143], v[190:193], v[56:59]
	v_mfma_f32_16x16x32_bf16 v[40:43], v[132:135], v[198:201], v[40:43]
	v_mfma_f32_16x16x32_bf16 v[48:51], v[140:143], v[198:201], v[48:51]
	v_mfma_f32_16x16x32_bf16 v[24:27], v[132:135], v[206:209], v[24:27]
	v_mfma_f32_16x16x32_bf16 v[32:35], v[140:143], v[206:209], v[32:35]
	v_mfma_f32_16x16x32_bf16 v[8:11], v[132:135], v[214:217], v[8:11]
	v_mfma_f32_16x16x32_bf16 v[16:19], v[140:143], v[214:217], v[16:19]
	v_mfma_f32_16x16x32_bf16 v[44:47], v[162:165], v[186:189], v[44:47]
	v_mfma_f32_16x16x32_bf16 v[52:55], v[178:181], v[186:189], v[52:55]
	v_mfma_f32_16x16x32_bf16 v[28:31], v[162:165], v[194:197], v[28:31]
	v_mfma_f32_16x16x32_bf16 v[36:39], v[178:181], v[194:197], v[36:39]
	v_mfma_f32_16x16x32_bf16 v[12:15], v[162:165], v[202:205], v[12:15]
	v_mfma_f32_16x16x32_bf16 v[20:23], v[178:181], v[202:205], v[20:23]
	v_mfma_f32_16x16x32_bf16 v[4:7], v[162:165], v[210:213], v[4:7]
	v_mfma_f32_16x16x32_bf16 v[0:3], v[178:181], v[210:213], v[0:3]
	v_mfma_f32_16x16x32_bf16 v[44:47], v[174:177], v[190:193], v[44:47]
	v_mfma_f32_16x16x32_bf16 v[52:55], v[182:185], v[190:193], v[52:55]
	v_mfma_f32_16x16x32_bf16 v[28:31], v[174:177], v[198:201], v[28:31]
	v_mfma_f32_16x16x32_bf16 v[36:39], v[182:185], v[198:201], v[36:39]
	v_mfma_f32_16x16x32_bf16 v[12:15], v[174:177], v[206:209], v[12:15]
	v_mfma_f32_16x16x32_bf16 v[20:23], v[182:185], v[206:209], v[20:23]
	v_mfma_f32_16x16x32_bf16 v[4:7], v[174:177], v[214:217], v[4:7]
	v_mfma_f32_16x16x32_bf16 v[0:3], v[182:185], v[214:217], v[0:3]
	s_setprio 0
	s_barrier
; #define PG8_STAGE(bufoff, gbase, voff) do { _Pragma("unroll") for (int _i = 0; _i < 2; ++_i) \
;         __builtin_amdgcn_global_load_lds((const unsigned*)((const char*)(gbase) + (voff)[_i]), (PG8_LAS unsigned*)(lds + (bufoff) + ldsw + _i * 8192), 16, 0, 0); } while (0)
; #define PG8_LDA(dst, b, h) do { _Pragma("unroll") for (int m = 0; m < 4; ++m) _Pragma("unroll") for (int k = 0; k < 2; ++k) dst[m][k] = *(const PG8_LAS bf16x8*)(lds + PG8_SA(b, h) + aoff + m * 2048 + k * 1024); } while (0)
; #define PG8_LDB(dst, b, h) do { _Pragma("unroll") for (int n = 0; n < 2; ++n) _Pragma("unroll") for (int k = 0; k < 2; ++k) dst[n][k] = *(const PG8_LAS bf16x8*)(lds + PG8_SB(b, h) + boff + n * 2048 + k * 1024); } while (0)
; #define PG8_MMA(ai, bj, At, Bt) do { __builtin_amdgcn_s_setprio(1); _Pragma("unroll") for (int m = 0; m < 4; ++m) _Pragma("unroll") for (int n = 0; n < 2; ++n) _Pragma("unroll") for (int k = 0; k < 2; ++k) \
;         acc[ai][bj][m][n] = __builtin_amdgcn_mfma_f32_16x16x32_bf16(Bt[n][k], At[m][k], acc[ai][bj][m][n], 0, 0, 0); __builtin_amdgcn_s_setprio(0); } while (0)
; #define PG8_WAIT_V(n) asm volatile("s_waitcnt vmcnt(" #n ")" ::: "memory")
; #define PG8_WAIT_L(n) asm volatile("s_waitcnt lgkmcnt(" #n ")" ::: "memory")
; #define PG8_BAR __builtin_amdgcn_s_barrier()
; #define PG8_SCHED __builtin_amdgcn_sched_barrier(0)
; template <class Epi, class Sched, bool ALIGN_EPI = false, bool SP2 = false>
; __device__ __forceinline__ void gemm_phase(PG8_LAS unsigned char* lds, const Gemm g, const Sched& S, const Epi& E, const int wave_in) {
;     ...
;             PG8_LDB(B0, 1, 0); PG8_LDB(B1, 1, 1); PG8_SCHED; PG8_LDA(At, 1, 0); PG8_STAGE(PG8_SA(0, 1), a2 + hstepA, voffA);
;             PG8_WAIT_V(8); PG8_WAIT_L(0); PG8_BAR; PG8_MMA(0, 0, At, B0); PG8_MMA(0, 1, At, B1); PG8_BAR; PG8_SCHED;
	s_add_i32 s67, 0, 0x18000
	s_add_i32 s68, 0, 0x1c000
	v_add_u32_e32 v140, s67, v168
	v_add_u32_e32 v173, s68, v168
	ds_read_b128 v[128:131], v140
	ds_read_b128 v[132:135], v140 offset:1024
	ds_read_b128 v[136:139], v140 offset:2048
	ds_read_b128 v[140:143], v140 offset:3072
	ds_read_b128 v[162:165], v173
	ds_read_b128 v[174:177], v173 offset:1024
	ds_read_b128 v[178:181], v173 offset:2048
	ds_read_b128 v[182:185], v173 offset:3072
	s_add_u32 s26, s30, 0x158000
	s_addc_u32 s27, s31, 0
	s_mov_b32 m0, s42
	v_lshl_add_u64 v[224:225], s[26:27], 0, v[144:145]
	ds_read_b128 v[186:189], v172 offset:32768
	ds_read_b128 v[190:193], v172 offset:33792
	ds_read_b128 v[194:197], v172 offset:34816
	ds_read_b128 v[198:201], v172 offset:35840
	ds_read_b128 v[202:205], v172 offset:36864
	ds_read_b128 v[206:209], v172 offset:37888
	ds_read_b128 v[210:213], v172 offset:38912
	ds_read_b128 v[214:217], v172 offset:39936
	global_load_lds_dwordx4 v[224:225], off
	v_lshl_add_u64 v[224:225], s[26:27], 0, v[148:149]
	s_mov_b32 m0, s43
	s_nop 0
	global_load_lds_dwordx4 v[224:225], off
	s_waitcnt vmcnt(8)
	s_waitcnt lgkmcnt(0)
	s_barrier
	s_setprio 1
	s_waitcnt lgkmcnt(0)
	v_mfma_f32_16x16x32_bf16 v[124:127], v[128:131], v[186:189], v[124:127]
	v_mfma_f32_16x16x32_bf16 v[120:123], v[136:139], v[186:189], v[120:123]
	v_mfma_f32_16x16x32_bf16 v[104:107], v[128:131], v[194:197], v[104:107]
	v_mfma_f32_16x16x32_bf16 v[108:111], v[136:139], v[194:197], v[108:111]
	v_mfma_f32_16x16x32_bf16 v[88:91], v[128:131], v[202:205], v[88:91]
	v_mfma_f32_16x16x32_bf16 v[92:95], v[136:139], v[202:205], v[92:95]
	v_mfma_f32_16x16x32_bf16 v[72:75], v[128:131], v[210:213], v[72:75]
	v_mfma_f32_16x16x32_bf16 v[76:79], v[136:139], v[210:213], v[76:79]
	v_mfma_f32_16x16x32_bf16 v[124:127], v[132:135], v[190:193], v[124:127]
	v_mfma_f32_16x16x32_bf16 v[120:123], v[140:143], v[190:193], v[120:123]
	v_mfma_f32_16x16x32_bf16 v[104:107], v[132:135], v[198:201], v[104:107]
	v_mfma_f32_16x16x32_bf16 v[108:111], v[140:143], v[198:201], v[108:111]
	v_mfma_f32_16x16x32_bf16 v[88:91], v[132:135], v[206:209], v[88:91]
	v_mfma_f32_16x16x32_bf16 v[92:95], v[140:143], v[206:209], v[92:95]
	v_mfma_f32_16x16x32_bf16 v[72:75], v[132:135], v[214:217], v[72:75]
	v_mfma_f32_16x16x32_bf16 v[76:79], v[140:143], v[214:217], v[76:79]
	v_mfma_f32_16x16x32_bf16 v[112:115], v[162:165], v[186:189], v[112:115]
	v_mfma_f32_16x16x32_bf16 v[116:119], v[178:181], v[186:189], v[116:119]
	v_mfma_f32_16x16x32_bf16 v[96:99], v[162:165], v[194:197], v[96:99]
	v_mfma_f32_16x16x32_bf16 v[100:103], v[178:181], v[194:197], v[100:103]
	v_mfma_f32_16x16x32_bf16 v[80:83], v[162:165], v[202:205], v[80:83]
	v_mfma_f32_16x16x32_bf16 v[84:87], v[178:181], v[202:205], v[84:87]
	v_mfma_f32_16x16x32_bf16 v[64:67], v[162:165], v[210:213], v[64:67]
	v_mfma_f32_16x16x32_bf16 v[68:71], v[178:181], v[210:213], v[68:71]
	v_mfma_f32_16x16x32_bf16 v[112:115], v[174:177], v[190:193], v[112:115]
	v_mfma_f32_16x16x32_bf16 v[116:119], v[182:185], v[190:193], v[116:119]
	v_mfma_f32_16x16x32_bf16 v[96:99], v[174:177], v[198:201], v[96:99]
	v_mfma_f32_16x16x32_bf16 v[100:103], v[182:185], v[198:201], v[100:103]
	v_mfma_f32_16x16x32_bf16 v[80:83], v[174:177], v[206:209], v[80:83]
	v_mfma_f32_16x16x32_bf16 v[84:87], v[182:185], v[206:209], v[84:87]
	v_mfma_f32_16x16x32_bf16 v[64:67], v[174:177], v[214:217], v[64:67]
	v_mfma_f32_16x16x32_bf16 v[68:71], v[182:185], v[214:217], v[68:71]
	s_setprio 0
	s_barrier
; #define PG8_STAGE(bufoff, gbase, voff) do { _Pragma("unroll") for (int _i = 0; _i < 2; ++_i) \
;         __builtin_amdgcn_global_load_lds((const unsigned*)((const char*)(gbase) + (voff)[_i]), (PG8_LAS unsigned*)(lds + (bufoff) + ldsw + _i * 8192), 16, 0, 0); } while (0)
; #define PG8_LDA(dst, b, h) do { _Pragma("unroll") for (int m = 0; m < 4; ++m) _Pragma("unroll") for (int k = 0; k < 2; ++k) dst[m][k] = *(const PG8_LAS bf16x8*)(lds + PG8_SA(b, h) + aoff + m * 2048 + k * 1024); } while (0)
; #define PG8_MMA(ai, bj, At, Bt) do { __builtin_amdgcn_s_setprio(1); _Pragma("unroll") for (int m = 0; m < 4; ++m) _Pragma("unroll") for (int n = 0; n < 2; ++n) _Pragma("unroll") for (int k = 0; k < 2; ++k) \
;         acc[ai][bj][m][n] = __builtin_amdgcn_mfma_f32_16x16x32_bf16(Bt[n][k], At[m][k], acc[ai][bj][m][n], 0, 0, 0); __builtin_amdgcn_s_setprio(0); } while (0)
; #define PG8_WAIT_V(n) asm volatile("s_waitcnt vmcnt(" #n ")" ::: "memory")
; #define PG8_WAIT_L(n) asm volatile("s_waitcnt lgkmcnt(" #n ")" ::: "memory")
; #define PG8_BAR __builtin_amdgcn_s_barrier()
; #define PG8_SCHED __builtin_amdgcn_sched_barrier(0)
; template <class Epi, class Sched, bool ALIGN_EPI = false, bool SP2 = false>
; __device__ __forceinline__ void gemm_phase(PG8_LAS unsigned char* lds, const Gemm g, const Sched& S, const Epi& E, const int wave_in) {
;     ...
;         for (int t = 0; t < nt; t += 2) {
;             const bool last = (t == nt - 2);
;             const char* a1 = cA + (size_t)(t + 1) * kstep;
;             const char* a2 = last ? nA : cA + (size_t)(t + 2) * kstep; const char* b2 = last ? nB : cB + (size_t)(t + 2) * kstep;
;     ...
;             PG8_LDA(At, 1, 1); PG8_STAGE(PG8_SB(1, 0), b3, voffB); PG8_STAGE(PG8_SB(1, 1), b3 + hstepB, voffB); PG8_STAGE(PG8_SA(1, 0), a3, voffA);
;             PG8_WAIT_V(8); PG8_WAIT_L(0); PG8_BAR; PG8_MMA(1, 0, At, B0); PG8_MMA(1, 1, At, B1); PG8_BAR; PG8_SCHED;
	s_add_i32 s26, s67, s39
	v_lshl_add_u64 v[166:167], v[166:167], 0, s[6:7]
	s_mov_b32 m0, s26
	ds_read_b128 v[186:189], v172 offset:49152
	ds_read_b128 v[190:193], v172 offset:50176
	ds_read_b128 v[194:197], v172 offset:51200
	ds_read_b128 v[198:201], v172 offset:52224
	ds_read_b128 v[202:205], v172 offset:53248
	ds_read_b128 v[206:209], v172 offset:54272
	ds_read_b128 v[210:213], v172 offset:55296
	ds_read_b128 v[214:217], v172 offset:56320
	global_load_lds_dwordx4 v[166:167], off
	s_add_i32 m0, s26, 0x2000
	s_add_u32 s26, s28, 0x158080
	v_lshl_add_u64 v[166:167], v[218:219], 0, s[6:7]
	s_addc_u32 s27, s29, 0
	s_add_i32 s28, s68, s39
	global_load_lds_dwordx4 v[166:167], off
	v_lshl_add_u64 v[166:167], s[26:27], 0, v[146:147]
	s_mov_b32 m0, s28
	s_nop 0
	global_load_lds_dwordx4 v[166:167], off
	v_lshl_add_u64 v[166:167], s[26:27], 0, v[150:151]
	s_add_i32 m0, s28, 0x2000
	s_nop 0
	global_load_lds_dwordx4 v[166:167], off
	v_lshl_add_u64 v[166:167], v[220:221], 0, s[6:7]
	s_mov_b32 m0, s48
	s_nop 0
	global_load_lds_dwordx4 v[166:167], off
	v_lshl_add_u64 v[166:167], v[222:223], 0, s[6:7]
	s_mov_b32 m0, s49
	s_nop 0
	global_load_lds_dwordx4 v[166:167], off
	s_waitcnt vmcnt(8)
	s_waitcnt lgkmcnt(0)
	s_barrier
	s_setprio 1
	s_waitcnt lgkmcnt(0)
	v_mfma_f32_16x16x32_bf16 v[60:63], v[128:131], v[186:189], v[60:63]
	v_mfma_f32_16x16x32_bf16 v[56:59], v[136:139], v[186:189], v[56:59]
	v_mfma_f32_16x16x32_bf16 v[40:43], v[128:131], v[194:197], v[40:43]
	v_mfma_f32_16x16x32_bf16 v[48:51], v[136:139], v[194:197], v[48:51]
	v_mfma_f32_16x16x32_bf16 v[24:27], v[128:131], v[202:205], v[24:27]
	v_mfma_f32_16x16x32_bf16 v[32:35], v[136:139], v[202:205], v[32:35]
	v_mfma_f32_16x16x32_bf16 v[8:11], v[128:131], v[210:213], v[8:11]
	v_mfma_f32_16x16x32_bf16 v[16:19], v[136:139], v[210:213], v[16:19]
	v_mfma_f32_16x16x32_bf16 v[60:63], v[132:135], v[190:193], v[60:63]
	v_mfma_f32_16x16x32_bf16 v[56:59], v[140:143], v[190:193], v[56:59]
	v_mfma_f32_16x16x32_bf16 v[40:43], v[132:135], v[198:201], v[40:43]
	v_mfma_f32_16x16x32_bf16 v[48:51], v[140:143], v[198:201], v[48:51]
	v_mfma_f32_16x16x32_bf16 v[24:27], v[132:135], v[206:209], v[24:27]
	v_mfma_f32_16x16x32_bf16 v[32:35], v[140:143], v[206:209], v[32:35]
	v_mfma_f32_16x16x32_bf16 v[8:11], v[132:135], v[214:217], v[8:11]
	v_mfma_f32_16x16x32_bf16 v[16:19], v[140:143], v[214:217], v[16:19]
	v_mfma_f32_16x16x32_bf16 v[44:47], v[162:165], v[186:189], v[44:47]
	v_mfma_f32_16x16x32_bf16 v[52:55], v[178:181], v[186:189], v[52:55]
	v_mfma_f32_16x16x32_bf16 v[28:31], v[162:165], v[194:197], v[28:31]
	v_mfma_f32_16x16x32_bf16 v[36:39], v[178:181], v[194:197], v[36:39]
	v_mfma_f32_16x16x32_bf16 v[12:15], v[162:165], v[202:205], v[12:15]
	v_mfma_f32_16x16x32_bf16 v[20:23], v[178:181], v[202:205], v[20:23]
	v_mfma_f32_16x16x32_bf16 v[4:7], v[162:165], v[210:213], v[4:7]
	v_mfma_f32_16x16x32_bf16 v[0:3], v[178:181], v[210:213], v[0:3]
	v_mfma_f32_16x16x32_bf16 v[44:47], v[174:177], v[190:193], v[44:47]
	v_mfma_f32_16x16x32_bf16 v[52:55], v[182:185], v[190:193], v[52:55]
	v_mfma_f32_16x16x32_bf16 v[28:31], v[174:177], v[198:201], v[28:31]
	v_mfma_f32_16x16x32_bf16 v[36:39], v[182:185], v[198:201], v[36:39]
	v_mfma_f32_16x16x32_bf16 v[12:15], v[174:177], v[206:209], v[12:15]
	v_mfma_f32_16x16x32_bf16 v[20:23], v[182:185], v[206:209], v[20:23]
	v_mfma_f32_16x16x32_bf16 v[4:7], v[174:177], v[214:217], v[4:7]
	v_mfma_f32_16x16x32_bf16 v[0:3], v[182:185], v[214:217], v[0:3]
	s_setprio 0
	s_barrier
	s_add_i32 s66, s66, 2
	s_add_u32 s25, s25, 0x100
	s_addc_u32 s65, s65, 0
	s_cmpk_gt_u32 s66, 0x53
	s_mov_b64 s[26:27], s[2:3]
	s_cbranch_scc0 .LBB0_2741
